# all remaining flat memory ops converted to global (no lgkmcnt coupling)
# speedup vs baseline: 1.0259x; 1.0056x over previous
; #define LAS __attribute__((address_space(3)))
; __global__ void __launch_bounds__(512) mk_fwd(Params P) {
;     ...
;             const int L = (ph - 1) / 3, sub = (ph - 1) % 3, kind = L % 3;
;             const int NZ = (kind == 0) ? NZ0 : (kind == 1 ? NZ1 : NZ2);
;             const int memq_off = (kind == 0) ? 3072 : 4608;
;             if (sub == 0) {
;                 for (int jb = (L == 0 ? 0 : 1); jb < 2; ++jb) {
;                     pg8::Gemm g; EpiZ E;
;                     LAS float* part = (LAS float*)(lds + LDS_PART);
;                     if (jb == 0) { g = pg8::Gemm{MEMN, WKV, NB * NMEM, 4096, DM}; E = EpiZ{ws, part, 4096, 3, 0}; }
;                     else { bf16_t* wt = (bf16_t*)(ws + (L == 0 ? WS_WIN0 : L == 1 ? WS_WIN1 : L == 2 ? WS_WIN2 : WS_WIN3));
;                            g = pg8::Gemm{HB, wt, NTOK, NZ, DM}; E = EpiZ{ws, part, NZ, kind, L}; }
;                     pg8::StaticOrder S; S.init(g.M, g.N, G, (int)blockIdx.x);
;                     pg8::gemm_phase<EpiZ, pg8::StaticOrder, true, true>(lds, g, S, E, tid);
;                 }
;             } else if (sub == 1) {
;                 const int gate_off = memq_off + 512;
;                 const float* gx = (const float*)(ws + WS_GT) + 2080;
;                 const float gqm = gx[4 * L], gkm = gx[4 * L + 1], gmq = gx[4 * L + 2], gmk = gx[4 * L + 3];
;                 const float m2_mem = 11.3137085f * gmq * gmk * 1.01f * LOG2E;
;                 if (kind == 0) {
;                     const int j = L / 3;
;     ...
;                     for (int rep_ = 0; rep_ < 2; ++rep_)
;     ...
;                     for (int it = blockIdx.x; it < NTOK / 128; it += G)
;                         gmlp_item(lds, Z + (size_t)it * 128 * NZ0, BR + (size_t)it * 128 * DM, (const bf16_t*)(ws + WS_GT + 65536) + (size_t)j * 12 * 16384, P.a_b_s + j * 1536, P.a_ln_g + j * 1536, P.a_ln_b + j * 1536, tid);
;                 } else if (kind == 1) {
;                     for (int it = blockIdx.x; it < 1536; it += G) {
;                         const int c = it & 255, rr = it >> 8, bh = rr * 16 + (c & 7) * 2 + (c >> 7); int j = (c >> 3) & 15; if (rr & 1) j = 15 - j;
;                         const int b = bh / 12, hh = bh - b * 12;
;                         const bf16_t* Zb = Z + (size_t)b * SEQ * NZ1;
.LBB0_7:
	v_writelane_b32 v250, s4, 11
	v_writelane_b32 v250, s60, 12
	s_add_i32 s41, s60, -1
	s_mul_hi_i32 s0, s41, 0x55555556
	s_lshr_b32 s1, s0, 31
	s_add_i32 s6, s0, s1
	s_mul_i32 s0, s6, 3
	s_sub_i32 s74, s41, s0
	s_mul_hi_i32 s0, s6, 0x55555556
	s_lshr_b32 s1, s0, 31
	s_add_i32 s0, s0, s1
	s_mul_i32 s0, s0, 3
	s_sub_i32 s1, s6, s0
	v_writelane_b32 v250, s61, 13
	s_mov_b32 s4, s6
	s_cmp_lg_u32 s1, 0
	v_writelane_b32 v250, s4, 14
	s_cselect_b64 s[6:7], -1, 0
	s_cmp_lg_u32 s1, 1
	v_writelane_b32 v250, s5, 15
	s_cselect_b64 s[4:5], -1, 0
	s_cmp_eq_u32 s1, 1
	s_movk_i32 s0, 0x1d00
	s_cselect_b32 s8, s0, 0x1c00
	s_cmp_eq_u32 s1, 0
	s_cselect_b64 s[10:11], -1, 0
	v_writelane_b32 v250, s1, 16
	s_and_b64 s[0:1], s[10:11], exec
	s_cselect_b32 s67, 0x1600, s8
	s_add_u32 s0, s24, 0xad00000
	s_addc_u32 s1, s25, 0
	v_writelane_b32 v250, s0, 17
	s_mov_b64 s[12:13], -1
	s_mov_b64 s[72:73], 0
	v_writelane_b32 v250, s1, 18
	s_add_u32 s0, s24, 0xb100000
	s_addc_u32 s1, s25, 0
	v_writelane_b32 v250, s0, 19
	s_add_u32 s93, s24, 0x13100000
	s_mov_b64 s[8:9], 0
	v_writelane_b32 v250, s1, 20
	v_writelane_b32 v250, s24, 21
	s_addc_u32 s95, s25, 0
	s_cmp_lt_i32 s74, 1
	v_writelane_b32 v250, s25, 22
	s_movk_i32 s79, 0x60
	s_movk_i32 s80, 0x50
	s_movk_i32 s22, 0x70
	s_movk_i32 s24, 0x80
	s_movk_i32 s25, 0x90
	s_movk_i32 s75, 0xa0
	s_movk_i32 s76, 0xb0
	s_movk_i32 s77, 0xc0
	s_movk_i32 s78, 0xd0
	s_mov_b32 s40, 0x3e38aa3b
	s_mov_b32 s28, 0x3a2aaaab
	s_mov_b64 s[56:57], 0x100
	s_cbranch_scc1 .LBB0_105
	s_cmp_eq_u32 s74, 1
	s_mov_b64 s[8:9], -1
	s_cbranch_scc0 .LBB0_104
	s_and_b64 s[8:9], s[10:11], exec
	s_movk_i32 s8, 0x1200
	s_cselect_b32 s0, 0xc00, s8
	v_writelane_b32 v250, s0, 31
	s_nop 0
	v_readlane_b32 s0, v250, 21
	v_readlane_b32 s1, v250, 22
	s_add_u32 s30, s0, 0x1b100000
	v_readlane_b32 s8, v250, 14
	s_addc_u32 s31, s1, 0
	v_readlane_b32 s9, v250, 15
	s_lshl_b32 s8, s8, 2
	s_ashr_i32 s9, s8, 31
	s_lshl_b64 s[8:9], s[8:9], 2
	s_add_u32 s8, s0, s8
	s_addc_u32 s9, s1, s9
	v_mov_b32_e32 v0, s8
	v_add_co_u32_e32 v2, vcc, 0xb002000, v0
	v_mov_b32_e32 v0, s9
	s_waitcnt lgkmcnt(0)
	v_addc_co_u32_e32 v3, vcc, 0, v0, vcc
	s_waitcnt vmcnt(0)
	global_load_dwordx4 v[112:115], v[2:3], off offset:128
	s_mov_b64 s[8:9], -1
	s_and_b64 vcc, exec, s[6:7]
	s_cbranch_vccz .LBB0_76
	s_mov_b64 s[6:7], -1
	s_and_b64 vcc, exec, s[4:5]
	s_cbranch_vccz .LBB0_47
	v_readlane_b32 s4, v252, 4
	v_readlane_b32 s5, v252, 5
	s_andn2_b64 vcc, exec, s[4:5]
	s_cbranch_vccnz .LBB0_46
	v_readlane_b32 s8, v250, 21
	v_readlane_b32 s9, v250, 22
	v_readlane_b32 s0, v250, 14
	v_mov_b32_e32 v0, s8
	v_add_co_u32_e32 v2, vcc, 0xb002000, v0
	v_mov_b32_e32 v0, s9
	s_nop 0
	v_addc_co_u32_e32 v3, vcc, 0, v0, vcc
	global_load_dwordx3 v[2:4], v[2:3], off offset:192
	v_cvt_f32_i32_e32 v0, s0
	s_mov_b32 s4, 0x3fb8aa3b
	s_mov_b32 s5, 0xc2ce8ed0
	s_mov_b32 s6, 0x42b17218
	v_mul_f32_e32 v0, 0xbe99999a, v0
	v_mul_f32_e32 v5, 0x3fb8aa3b, v0
	v_fma_f32 v6, v0, s4, -v5
	v_rndne_f32_e32 v7, v5
	v_fmac_f32_e32 v6, 0x32a5705f, v0
	v_sub_f32_e32 v5, v5, v7
	v_add_f32_e32 v5, v5, v6
	v_exp_f32_e32 v5, v5
	v_cvt_i32_f32_e32 v6, v7
	v_cmp_ngt_f32_e32 vcc, s5, v0
	v_readlane_b32 s1, v250, 15
	v_ashrrev_i32_e32 v181, 31, v180
	v_ldexp_f32 v5, v5, v6
	v_cndmask_b32_e32 v5, 0, v5, vcc
	v_cmp_nlt_f32_e32 vcc, s6, v0
	v_lshrrev_b32_e32 v158, 5, v182
	s_mov_b64 s[0:1], 0xb00a000
	v_cndmask_b32_e32 v0, v208, v5, vcc
	v_fmamk_f32 v0, v0, 0xbf19999a, v203
	v_lshrrev_b32_e32 v9, 3, v182
	v_and_b32_e32 v9, 2, v9
	v_bfe_u32 v10, v180, 1, 1
	v_and_b32_e32 v8, 12, v180
	v_or_b32_e32 v11, v9, v10
	v_or_b32_e32 v12, 12, v11
	v_or_b32_e32 v13, v158, v8
	v_or_b32_e32 v15, 8, v11
	v_or_b32_e32 v17, 4, v11
	v_bitop3_b32 v16, v11, v13, 8 bitop3:0x36
	v_bitop3_b32 v18, v11, v13, 4 bitop3:0x36
	s_add_u32 s16, s8, 0x1b331800
	v_sub_f32_e32 v156, 1.0, v0
	v_and_b32_e32 v157, 31, v180
	v_lshrrev_b32_e32 v161, 4, v182
	v_bitop3_b32 v14, v11, v13, 12 bitop3:0x36
	s_addc_u32 s17, s9, 0
	v_and_b32_e32 v160, 15, v180
	v_lshlrev_b32_e32 v162, 2, v161
	v_lshlrev_b32_e32 v164, 8, v157
	v_ashrrev_i32_e32 v167, 4, v180
	s_waitcnt vmcnt(0) lgkmcnt(0)
	v_mul_f32_e32 v5, 0x3fb8aa3b, v3
	v_fma_f32 v6, v3, s4, -v5
	v_rndne_f32_e32 v7, v5
	v_fmac_f32_e32 v6, 0x32a5705f, v3
	v_sub_f32_e32 v5, v5, v7
	v_add_f32_e32 v5, v5, v6
	v_exp_f32_e32 v5, v5
	v_cvt_i32_f32_e32 v6, v7
	v_cmp_ngt_f32_e32 vcc, s5, v3
	v_ldexp_f32 v5, v5, v6
	s_nop 0
	v_cndmask_b32_e32 v5, 0, v5, vcc
	v_cmp_nlt_f32_e32 vcc, s6, v3
	s_nop 1
	v_cndmask_b32_e32 v3, v208, v5, vcc
	v_mul_f32_e32 v5, 0x3fb8aa3b, v4
	v_fma_f32 v6, v4, s4, -v5
	v_rndne_f32_e32 v7, v5
	v_fmac_f32_e32 v6, 0x32a5705f, v4
	v_sub_f32_e32 v5, v5, v7
	v_add_f32_e32 v5, v5, v6
	v_exp_f32_e32 v5, v5
	v_cvt_i32_f32_e32 v6, v7
	v_cmp_ngt_f32_e32 vcc, s5, v4
	s_movk_i32 s4, 0xff
	v_cmp_gt_i32_e64 s[4:5], s4, v180
	v_ldexp_f32 v5, v5, v6
	v_cndmask_b32_e32 v5, 0, v5, vcc
	v_cmp_nlt_f32_e32 vcc, s6, v4
	v_bfe_u32 v6, v180, 2, 2
	v_readlane_b32 s6, v251, 1
	v_cndmask_b32_e32 v4, v208, v5, vcc
	v_sub_f32_e32 v3, v3, v4
	v_add_f32_e32 v154, v0, v3
	v_mul_f32_e32 v3, 0x41000000, v112
	v_mul_f32_e32 v3, v3, v113
	v_fmac_f32_e32 v2, 0x3f8147ae, v3
	v_mul_f32_e32 v155, 0x3fb8aa3b, v2
	v_lshl_add_u64 v[2:3], v[180:181], 2, s[8:9]
	v_lshl_add_u64 v[132:133], v[2:3], 0, s[0:1]
	v_lshlrev_b32_e32 v3, 2, v158
	v_lshlrev_b32_e32 v2, 3, v180
	v_or_b32_e32 v5, 8, v3
	v_and_b32_e32 v2, 8, v2
	v_or_b32_e32 v7, v5, v6
	v_lshrrev_b32_e32 v5, 2, v5
	v_or_b32_e32 v3, v3, v6
	v_lshlrev_b32_e32 v4, 2, v180
	v_bitop3_b32 v12, v5, v12, v8 bitop3:0x36
	v_bitop3_b32 v15, v5, v15, v8 bitop3:0x36
	v_bitop3_b32 v17, v5, v17, v8 bitop3:0x36
	v_bitop3_b32 v5, v5, v11, v8 bitop3:0x36
	v_bitop3_b32 v8, v9, v13, v10 bitop3:0x36
	v_lshl_or_b32 v3, v3, 8, v2
	v_lshl_or_b32 v2, v7, 8, v2
	v_readlane_b32 s0, v250, 31
	v_add_u32_e32 v159, s33, v4
	v_lshlrev_b32_e32 v0, 3, v158
	v_and_or_b32 v163, v4, 12, v6
	v_lshl_or_b32 v4, v8, 4, v3
	v_lshl_add_u32 v5, v5, 4, v2
	v_lshl_or_b32 v6, v18, 4, v3
	v_lshl_add_u32 v7, v17, 4, v2
	v_lshl_or_b32 v8, v16, 4, v3
	v_lshl_add_u32 v9, v15, 4, v2
	s_lshl_b32 s18, s0, 1
	v_readlane_b32 s0, v252, 54
	v_lshl_or_b32 v165, v14, 4, v3
	v_lshl_add_u32 v166, v12, 4, v2
	v_lshl_add_u32 v168, v158, 4, s6
	v_lshlrev_b32_e32 v134, 1, v0
	v_add_u32_e32 v169, 0, v4
	v_add_u32_e32 v170, 0, v5
	v_add_u32_e32 v171, 0, v6
	v_add_u32_e32 v172, 0, v7
	v_add_u32_e32 v173, 0, v8
	v_add_u32_e32 v179, 0, v9
	s_mov_b32 s19, s0
	s_mov_b32 s26, s0
	v_readlane_b32 s1, v252, 55
	s_branch .LBB0_14
; #define LAS __attribute__((address_space(3)))
; template <int MODE>
; __device__ __forceinline__ void attn_item(LAS unsigned char* lds, const AttnArgs& a, const int tid) {
;     const int wave = __builtin_amdgcn_readfirstlane(tid >> 6), lane = tid & 63, r = lane & 31, h = lane >> 5;
;     constexpr int NKS = (MODE == 2) ? 4 : 8;
;     const int map = (MODE == 2) ? (wave >> 2) : 0;
;     const int qw0 = a.q0 + 32 * ((MODE == 2) ? (wave & 3) : wave);
;     const int tw = (MODE == 0) ? (a.ntiles - 1) : (MODE == 1 ? ((qw0 + 31) >> 6) : (qw0 >> 6));
;     __syncthreads();
;     if (MODE == 2) {
;         if (tid < 255) ((LAS float*)(lds + A_LUT))[tid] = a.lutsrc[tid] - a.m2;
;     }
;     bf16x8 qf[NKS];
;     { const bf16_t* qrow = a.Q + (size_t)(qw0 + r) * a.ldq + map * 64 + 8 * h;
; #pragma unroll
;       for (int ks = 0; ks < NKS; ++ks) qf[ks] = *(const bf16x8*)(qrow + 16 * ks); }
;     if (MODE == 1) {
;         LAS float* cl = (LAS float*)(lds + A_CS); LAS float* wtot = (LAS float*)(lds + A_LUT);
;         const int n = a.q0 + 256; const bool on = 8 * tid < n;
;         float v[8]; float run = 0.f;
;         const float* lp = a.c + 8 * tid;
;         f32x4 x0 = {0.f, 0.f, 0.f, 0.f}, x1 = x0; if (on) { x0 = *(const f32x4*)lp; x1 = *(const f32x4*)(lp + 4); }
; #pragma unroll
;         for (int e = 0; e < 8; ++e) { run += (e < 4) ? x0[e & 3] : x1[e & 3]; v[e] = run; }
;         float incl = run;
; #pragma unroll
;         for (int o = 1; o < 64; o <<= 1) { const float x = __shfl_up(incl, o); if (lane >= o) incl += x; }
;         if (lane == 63) wtot[wave] = incl;
;         __syncthreads();
;         float pre = incl - run;
;         for (int w = 0; w < wave; ++w) pre += wtot[w];
;         if (on) {
; #pragma unroll
;             for (int e = 0; e < 8; ++e) cl[8 * tid + e] = -(pre + v[e]) * LOG2E; }
;     }
;     unsigned kaddr[NKS];
;     { const unsigned X = ((r & 3u) << 2) | ((r >> 2) & 3u);
; #pragma unroll
;       for (int ks = 0; ks < NKS; ++ks) kaddr[ks] = 256u * r + 16u * ((unsigned)(2 * (map * 4 + ks) + h) ^ X); }
;     unsigned vaddr[4][2];
;     { const unsigned q = (lane & 15) >> 2, p = lane & 3, blk = (lane >> 4) & 1;
; #pragma unroll
;       for (int dt = 0; dt < 4; ++dt)
; #pragma unroll
;           for (int t2 = 0; t2 < 2; ++t2) vaddr[dt][t2] = 16384u + off_b(8 * t2 + 4 * h + q, 4 * dt + 2 * blk + (p >> 1)) + 8u * (p & 1); }
.LBB0_13:
	s_lshl_b64 s[6:7], s[6:7], 24
	s_add_u32 s6, s93, s6
	s_addc_u32 s7, s95, s7
	s_waitcnt lgkmcnt(0)
	s_barrier
	ds_read_b128 v[2:5], v181
	v_ashrrev_i32_e32 v81, 31, v80
	s_add_u32 s6, s6, s8
	s_addc_u32 s7, s7, s9
	v_lshlrev_b64 v[6:7], 12, v[80:81]
	v_lshl_add_u64 v[6:7], s[6:7], 0, v[6:7]
	v_lshlrev_b64 v[8:9], 1, v[14:15]
	v_lshl_add_u64 v[6:7], v[6:7], 0, v[8:9]
	v_add_u32_e32 v0, 32, v135
	s_waitcnt lgkmcnt(0)
	global_store_dwordx4 v[6:7], v[2:5], off
	v_add_u32_e32 v6, s27, v0
	v_ashrrev_i32_e32 v7, 31, v6
	v_lshl_add_u32 v2, v0, 8, v184
	ds_read_b128 v[2:5], v2
	v_lshlrev_b64 v[6:7], 12, v[6:7]
	v_lshl_add_u64 v[6:7], s[6:7], 0, v[6:7]
	v_lshl_add_u64 v[6:7], v[6:7], 0, v[8:9]
	v_add_u32_e32 v0, 64, v135
	s_waitcnt lgkmcnt(0)
	global_store_dwordx4 v[6:7], v[2:5], off
	v_add_u32_e32 v6, s27, v0
	v_ashrrev_i32_e32 v7, 31, v6
	v_lshl_add_u32 v2, v0, 8, v184
	ds_read_b128 v[2:5], v2
	v_lshlrev_b64 v[6:7], 12, v[6:7]
	v_lshl_add_u64 v[6:7], s[6:7], 0, v[6:7]
	v_lshl_add_u64 v[6:7], v[6:7], 0, v[8:9]
	v_add_u32_e32 v0, 0x60, v135
	s_waitcnt lgkmcnt(0)
	global_store_dwordx4 v[6:7], v[2:5], off
	v_add_u32_e32 v6, s27, v0
	v_ashrrev_i32_e32 v7, 31, v6
	v_lshl_add_u32 v2, v0, 8, v184
	ds_read_b128 v[2:5], v2
	v_lshlrev_b64 v[6:7], 12, v[6:7]
	v_lshl_add_u64 v[6:7], s[6:7], 0, v[6:7]
	s_add_i32 s26, s26, s64
	s_add_i32 s19, s19, s64
	v_lshl_add_u64 v[6:7], v[6:7], 0, v[8:9]
	s_cmpk_lt_i32 s26, 0xc00
	s_waitcnt lgkmcnt(0)
	global_store_dwordx4 v[6:7], v[2:5], off
	s_cbranch_scc0 .LBB0_46
.LBB0_14:
	s_ashr_i32 s6, s26, 5
	s_and_b32 s10, s6, -8
	s_and_b32 s6, s26, 7
	s_or_b32 s7, s10, s6
	s_mul_hi_i32 s6, s7, 0x2aaaaaab
	s_lshr_b32 s8, s6, 31
	s_ashr_i32 s6, s6, 1
	s_add_i32 s6, s6, s8
	s_mul_i32 s11, s6, -12
	s_add_i32 s11, s11, s7
	v_readfirstlane_b32 s28, v180
	s_barrier
	s_and_saveexec_b64 s[8:9], s[4:5]
	s_cbranch_execz .LBB0_16
	s_lshl_b32 s12, s11, 8
	s_ashr_i32 s13, s12, 31
	v_lshl_add_u64 v[2:3], s[12:13], 2, v[132:133]
	global_load_dword v0, v[2:3], off
	s_waitcnt vmcnt(0) lgkmcnt(0)
	v_sub_f32_e32 v0, v0, v155
	ds_write_b32 v159, v0
.LBB0_16:
	s_or_b64 exec, exec, s[8:9]
	s_bfe_u32 s7, s26, 0x50003
	s_and_b32 s55, s19, 7
	s_and_b32 s8, s26, 0x100
	s_xor_b32 s9, s7, 31
	s_cmp_eq_u32 s8, 0
	s_cselect_b32 s14, s7, s9
	s_ashr_i32 s7, s6, 31
	s_mul_i32 s9, s6, 0x3800000
	s_mul_hi_i32 s8, s6, 0x3800000
	s_add_u32 s36, s30, s9
	s_addc_u32 s37, s31, s8
	s_lshl_b32 s8, s11, 7
	s_ashr_i32 s9, s8, 31
	s_lshl_b64 s[8:9], s[8:9], 1
	s_add_u32 s12, s36, s8
	s_addc_u32 s13, s37, s9
	s_ashr_i32 s11, s28, 6
	s_and_b32 s34, s11, 3
	s_lshl_b32 s27, s14, 7
	s_lshl_b32 s38, s34, 5
	s_lshl_b32 s39, s14, 1
	s_or_b32 s14, s38, s27
	s_ashr_i32 s29, s28, 8
	v_or_b32_e32 v0, s14, v157
	s_lshr_b32 s43, s14, 6
	v_mul_u32_u24_e32 v0, 0x1c00, v0
	s_lshl_b32 s14, s29, 6
	v_lshl_add_u64 v[2:3], v[0:1], 1, s[12:13]
	s_ashr_i32 s15, s14, 31
	v_lshl_add_u64 v[2:3], s[14:15], 1, v[2:3]
	v_mov_b32_e32 v135, v1
	v_lshl_add_u64 v[2:3], v[2:3], 0, v[134:135]
	global_load_dwordx4 v[116:119], v[2:3], off
	global_load_dwordx4 v[120:123], v[2:3], off offset:32
	global_load_dwordx4 v[124:127], v[2:3], off offset:64
	global_load_dwordx4 v[128:131], v[2:3], off offset:96
	v_lshl_or_b32 v0, s11, 2, v161
	s_movk_i32 s14, 0x1c00
	v_bitop3_b32 v10, s34, v160, v162 bitop3:0x36
	v_mad_i64_i32 v[4:5], s[14:15], v0, s14, 0
	v_lshl_or_b32 v4, v10, 3, v4
	v_lshl_add_u64 v[4:5], v[4:5], 1, s[12:13]
	s_mov_b64 s[0:1], 0xc00
	s_lshl_b32 s11, s11, 10
	v_lshl_add_u64 v[6:7], v[4:5], 0, s[0:1]
	s_add_i32 s44, s11, 0
	s_mov_b32 m0, s44
	s_nop 0
	global_load_lds_dwordx4 v[6:7], off
	s_mov_b64 s[12:13], 0x70c00
	s_mov_b64 s[0:1], 0x1800
	v_lshl_add_u64 v[2:3], v[4:5], 0, s[12:13]
	s_add_i32 s45, s44, 0x2000
	s_mov_b32 m0, s45
	s_nop 0
	global_load_lds_dwordx4 v[2:3], off
	s_mov_b64 s[12:13], 0x71800
	v_lshl_add_u64 v[8:9], v[4:5], 0, s[0:1]
	s_add_i32 s46, s44, 0x4000
	s_mov_b32 m0, s46
	s_nop 0
	global_load_lds_dwordx4 v[8:9], off
	v_lshl_add_u64 v[2:3], v[4:5], 0, s[12:13]
	s_add_i32 s11, 0, 0x14000
	s_add_i32 s47, s44, 0x6000
	s_mov_b32 m0, s47
	s_nop 0
	global_load_lds_dwordx4 v[2:3], off
	v_mov_b32_e32 v2, s11
	s_lshl_b32 s11, s29, 3
	s_waitcnt vmcnt(0)
	s_waitcnt lgkmcnt(0)
	s_barrier
	s_add_i32 s10, s10, s55
	s_add_i32 s42, s39, 2
	s_add_i32 s48, s43, -2
	s_add_i32 s49, s44, 0x8000
	s_add_i32 s50, s44, 0xa000
	s_add_i32 s51, s44, 0xc000
	s_add_i32 s54, s44, 0xe000
	v_mov_b32_e32 v14, v1
	v_mov_b32_e32 v15, v1
	v_mov_b32_e32 v4, v1
	v_mov_b32_e32 v5, v1
	v_mov_b32_e32 v6, v1
	v_mov_b32_e32 v7, v1
	v_mov_b32_e32 v8, v1
	v_mov_b32_e32 v9, v1
	v_mov_b32_e32 v11, v1
	v_mov_b32_e32 v12, v1
	v_mov_b32_e32 v13, v1
	s_mov_b32 s35, 0
	v_mov_b32_e32 v181, 0
	s_waitcnt vmcnt(0)
	ds_read_b32 v136, v2
	v_or_b32_e32 v2, s11, v158
	v_bitop3_b32 v3, v2, v163, 6 bitop3:0x36
	v_lshl_add_u32 v16, v3, 4, v164
	v_bitop3_b32 v3, v2, v163, 4 bitop3:0x36
	v_bitop3_b32 v2, v2, v163, 2 bitop3:0x36
	v_lshl_add_u32 v18, v2, 4, v164
	v_bitop3_b32 v2, s11, v163, v158 bitop3:0x36
	v_lshl_add_u32 v19, v2, 4, v164
	v_or_b32_e32 v2, s27, v157
	v_or_b32_e32 v2, s38, v2
	v_lshlrev_b32_e32 v2, 2, v2
	s_movk_i32 s11, 0x3800
	v_lshl_add_u32 v17, v3, 4, v164
	v_sub_u32_e32 v135, v168, v2
	v_mad_i64_i32 v[2:3], s[12:13], v0, s11, 0
	s_mul_i32 s11, s6, 12
	s_sub_i32 s10, s10, s11
	s_lshl_b32 s10, s10, 7
	s_ashr_i32 s11, s10, 31
	s_lshl_b64 s[10:11], s[10:11], 1
	v_mad_i64_i32 v[2:3], s[12:13], s6, v209, v[2:3]
	s_add_u32 s10, s16, s10
	v_lshl_or_b32 v2, v10, 4, v2
	s_addc_u32 s11, s17, s11
	v_lshl_add_u64 v[138:139], s[10:11], 0, v[2:3]
	v_mov_b32_e32 v0, v1
	v_mov_b32_e32 v2, v1
	v_mov_b32_e32 v3, v1
	v_mov_b32_e32 v10, v1
	v_add_u32_e32 v184, 0, v19
	v_add_u32_e32 v185, 0, v18
	v_add_u32_e32 v186, 0, v17
	v_add_u32_e32 v187, 0, v16
	v_mov_b64_e32 v[30:31], v[14:15]
	v_mov_b64_e32 v[46:47], v[14:15]
	v_mov_b64_e32 v[62:63], v[14:15]
	v_mov_b64_e32 v[78:79], v[14:15]
	s_waitcnt lgkmcnt(0)
	v_mov_b32_e32 v137, v136
	v_mov_b64_e32 v[28:29], v[12:13]
	v_mov_b64_e32 v[26:27], v[10:11]
	v_mov_b64_e32 v[24:25], v[8:9]
	v_mov_b64_e32 v[22:23], v[6:7]
	v_mov_b64_e32 v[20:21], v[4:5]
	v_mov_b64_e32 v[18:19], v[2:3]
	v_mov_b64_e32 v[16:17], v[0:1]
	v_mov_b64_e32 v[44:45], v[12:13]
	v_mov_b64_e32 v[42:43], v[10:11]
	v_mov_b64_e32 v[40:41], v[8:9]
	v_mov_b64_e32 v[38:39], v[6:7]
	v_mov_b64_e32 v[36:37], v[4:5]
	v_mov_b64_e32 v[34:35], v[2:3]
	v_mov_b64_e32 v[32:33], v[0:1]
	v_mov_b64_e32 v[60:61], v[12:13]
	v_mov_b64_e32 v[58:59], v[10:11]
	v_mov_b64_e32 v[56:57], v[8:9]
	v_mov_b64_e32 v[54:55], v[6:7]
	v_mov_b64_e32 v[52:53], v[4:5]
	v_mov_b64_e32 v[50:51], v[2:3]
	v_mov_b64_e32 v[48:49], v[0:1]
	v_mov_b64_e32 v[76:77], v[12:13]
	v_mov_b64_e32 v[74:75], v[10:11]
	v_mov_b64_e32 v[72:73], v[8:9]
	v_mov_b64_e32 v[70:71], v[6:7]
	v_mov_b64_e32 v[68:69], v[4:5]
	v_mov_b64_e32 v[66:67], v[2:3]
	v_mov_b64_e32 v[64:65], v[0:1]
	s_branch .LBB0_19

; template <int MODE>
; __device__ __forceinline__ void attn_item(LAS unsigned char* lds, const AttnArgs& a, const int tid) {
;     ...
;     l += __shfl_xor(l, 32);
;     const float inv = 1.f / l;
;     const size_t qrow = (size_t)(qw0 + r);
;     if (MODE != 2) {
;         int ch = tid & 15, r0 = tid >> 4, lrow = 32 * wave + r, hh = h;
;         asm volatile("" : "+v"(ch), "+v"(r0), "+v"(lrow), "+v"(hh));
; #pragma unroll 1
;         for (int i0 = 0; i0 < 8; i0 += 4) { u32x4 gv[4];
; #pragma unroll
;           for (int i = 0; i < 4; ++i) gv[i] = *(const u32x4*)(a.G + (size_t)(a.q0 + r0 + 32 * (i0 + i)) * a.ldg + 8 * ch);
; #pragma unroll
;           for (int i = 0; i < 4; ++i) *(LAS u32x4*)(lds + off_b(r0 + 32 * (i0 + i), ch)) = gv[i]; }
;         __syncthreads();
; #pragma unroll
;         for (int dt = 0; dt < 4; ++dt)
; #pragma unroll
;             for (int g = 0; g < 4; ++g) { const unsigned ad = off_b(lrow, 4 * dt + g) + 8u * hh;
;                 const u32x2 gw = *(const LAS u32x2*)(lds + ad);
;                 const float v0 = o[dt][4 * g + 0] * inv * silu_f(bflo(gw.x)), v1 = o[dt][4 * g + 1] * inv * silu_f(bfhi(gw.x));
;                 const float v2 = o[dt][4 * g + 2] * inv * silu_f(bflo(gw.y)), v3 = o[dt][4 * g + 3] * inv * silu_f(bfhi(gw.y));
;                 u32x2 w; w.x = pk2(v0, v1); w.y = pk2(v2, v3);
;                 *(LAS u32x2*)(lds + ad) = w; }
;         __syncthreads();
; #pragma unroll 4
;         for (int i = 0; i < 8; ++i) { const u32x4 ov = *(const LAS u32x4*)(lds + off_b(r0 + 32 * i, ch)); *(u32x4*)(a.O + (size_t)(a.q0 + r0 + 32 * i) * a.ldo + 8 * ch) = ov; }
;     } else {
;         LAS float* xb = (LAS float*)(lds + (wave & 3) * 16384);
;         int ch = tid & 15, r0 = tid >> 4, lrow = 32 * (wave & 3) + r, hh = h;
;         asm volatile("" : "+v"(ch), "+v"(r0), "+v"(lrow), "+v"(hh));
;         { u32x4 gv[4];
; #pragma unroll
;           for (int i = 0; i < 4; ++i) gv[i] = *(const u32x4*)(a.G + (size_t)(a.q0 + r0 + 32 * i) * a.ldg + 8 * ch);
; #pragma unroll
;           for (int i = 0; i < 4; ++i) *(LAS u32x4*)(lds + 98304 + off_b(r0 + 32 * i, ch)) = gv[i]; }
;         if (map == 1) {
;             const float f = inv * a.lam;
; #pragma unroll
;             for (int dt = 0; dt < 4; ++dt)
; #pragma unroll
;                 for (int i = 0; i < 16; ++i) xb[(dt * 16 + i) * 64 + lane] = o[dt][i] * f;
;         }
.LBB0_42:
	s_add_u32 s10, s36, s18
	s_addc_u32 s11, s37, 0
	v_or_b32_e32 v3, s38, v157
	v_mov_b32_e32 v0, v160
	v_mov_b32_e32 v135, v167
	v_mov_b32_e32 v2, v158
	s_add_u32 s10, s10, s8
	s_addc_u32 s11, s11, s9
	v_lshlrev_b32_e32 v14, 3, v0
	v_add_u32_e32 v80, s27, v135
	v_ashrrev_i32_e32 v15, 31, v14
	v_lshl_add_u64 v[12:13], v[14:15], 1, s[10:11]
	s_movk_i32 s12, 0x3800
	v_add_u32_e32 v6, 32, v80
	v_add_u32_e32 v81, 64, v80
	v_mad_i64_i32 v[4:5], s[10:11], v80, s12, v[12:13]
	v_mad_i64_i32 v[8:9], s[10:11], v6, s12, v[12:13]
	v_mad_i64_i32 v[82:83], s[10:11], v81, s12, v[12:13]
	v_add_u32_e32 v81, 0x60, v80
	global_load_dwordx4 v[4:7], v[4:5], off offset:1024
	s_nop 0
	global_load_dwordx4 v[8:11], v[8:9], off offset:1024
	v_mad_i64_i32 v[12:13], s[10:11], v81, s12, v[12:13]
	global_load_dwordx4 v[82:85], v[82:83], off offset:1024
	s_nop 0
	global_load_dwordx4 v[86:89], v[12:13], off offset:1024
	v_and_b32_e32 v13, 64, v204
	v_xor_b32_e32 v12, 32, v204
	v_add_u32_e32 v13, 64, v13
	v_cmp_lt_i32_e32 vcc, v12, v13
	v_lshlrev_b32_e32 v81, 2, v135
	v_bfe_u32 v90, v135, 2, 2
	v_cndmask_b32_e32 v12, v204, v12, vcc
	v_lshlrev_b32_e32 v187, 2, v12
	v_and_b32_e32 v12, 12, v81
	ds_bpermute_b32 v81, v187, v181
	v_bitop3_b32 v0, v12, v0, v90 bitop3:0x36
	s_lshl_b32 s10, s34, 14
	v_lshl_add_u32 v184, v0, 4, s91
	s_add_i32 s12, s10, 0
	s_waitcnt lgkmcnt(0)
	v_add_f32_e32 v0, v181, v81
	v_div_scale_f32 v12, s[10:11], v0, v0, 1.0
	v_rcp_f32_e32 v81, v12
	v_lshlrev_b32_e32 v13, 8, v135
	v_add_u32_e32 v181, v184, v13
	v_div_scale_f32 v13, vcc, 1.0, v0, 1.0
	v_fma_f32 v90, -v12, v81, 1.0
	v_fmac_f32_e32 v81, v90, v81
	v_mul_f32_e32 v90, v13, v81
	v_fma_f32 v91, -v12, v90, v13
	v_fmac_f32_e32 v90, v91, v81
	v_fma_f32 v12, -v12, v90, v13
	v_div_fmas_f32 v12, v12, v81, v90
	s_cmp_eq_u32 s29, 1
	v_div_fixup_f32 v0, v12, v0, 1.0
	s_waitcnt vmcnt(0)
	ds_write_b128 v181, v[4:7]
	ds_write_b128 v181, v[8:11] offset:8192
	ds_write_b128 v181, v[82:85] offset:16384
	ds_write_b128 v181, v[86:89] offset:24576
	v_lshl_add_u32 v4, v182, 2, s12
	s_cbranch_scc0 .LBB0_44
	v_mul_f32_e32 v5, v154, v0
	v_mul_f32_e32 v6, v64, v5
	v_mul_f32_e32 v7, v65, v5
	ds_write2st64_b32 v4, v6, v7 offset1:1
	v_mul_f32_e32 v6, v66, v5
	v_mul_f32_e32 v7, v67, v5
	ds_write2st64_b32 v4, v6, v7 offset0:2 offset1:3
	v_mul_f32_e32 v6, v68, v5
	v_mul_f32_e32 v7, v69, v5
	ds_write2st64_b32 v4, v6, v7 offset0:4 offset1:5
	v_mul_f32_e32 v6, v70, v5
	v_mul_f32_e32 v7, v71, v5
	ds_write2st64_b32 v4, v6, v7 offset0:6 offset1:7
	v_mul_f32_e32 v6, v72, v5
	v_mul_f32_e32 v7, v73, v5
	ds_write2st64_b32 v4, v6, v7 offset0:8 offset1:9
	v_mul_f32_e32 v6, v74, v5
	v_mul_f32_e32 v7, v75, v5
	ds_write2st64_b32 v4, v6, v7 offset0:10 offset1:11
	v_mul_f32_e32 v6, v76, v5
	v_mul_f32_e32 v7, v77, v5
	ds_write2st64_b32 v4, v6, v7 offset0:12 offset1:13
	v_mul_f32_e32 v6, v78, v5
	v_mul_f32_e32 v7, v79, v5
	ds_write2st64_b32 v4, v6, v7 offset0:14 offset1:15
	v_mul_f32_e32 v6, v48, v5
	v_mul_f32_e32 v7, v49, v5
	ds_write2st64_b32 v4, v6, v7 offset0:16 offset1:17
	v_mul_f32_e32 v6, v50, v5
	v_mul_f32_e32 v7, v51, v5
	ds_write2st64_b32 v4, v6, v7 offset0:18 offset1:19
	v_mul_f32_e32 v6, v52, v5
	v_mul_f32_e32 v7, v53, v5
	ds_write2st64_b32 v4, v6, v7 offset0:20 offset1:21
	v_mul_f32_e32 v6, v54, v5
	v_mul_f32_e32 v7, v55, v5
	ds_write2st64_b32 v4, v6, v7 offset0:22 offset1:23
	v_mul_f32_e32 v6, v56, v5
	v_mul_f32_e32 v7, v57, v5
	ds_write2st64_b32 v4, v6, v7 offset0:24 offset1:25
	v_mul_f32_e32 v6, v58, v5
	v_mul_f32_e32 v7, v59, v5
	ds_write2st64_b32 v4, v6, v7 offset0:26 offset1:27
	v_mul_f32_e32 v6, v60, v5
	v_mul_f32_e32 v7, v61, v5
	ds_write2st64_b32 v4, v6, v7 offset0:28 offset1:29
	v_mul_f32_e32 v6, v62, v5
	v_mul_f32_e32 v7, v63, v5
	ds_write2st64_b32 v4, v6, v7 offset0:30 offset1:31
	v_mul_f32_e32 v6, v32, v5
	v_mul_f32_e32 v7, v33, v5
	ds_write2st64_b32 v4, v6, v7 offset0:32 offset1:33
	v_mul_f32_e32 v6, v34, v5
	v_mul_f32_e32 v7, v35, v5
	ds_write2st64_b32 v4, v6, v7 offset0:34 offset1:35
	v_mul_f32_e32 v6, v36, v5
	v_mul_f32_e32 v7, v37, v5
	ds_write2st64_b32 v4, v6, v7 offset0:36 offset1:37
	v_mul_f32_e32 v6, v38, v5
	v_mul_f32_e32 v7, v39, v5
	ds_write2st64_b32 v4, v6, v7 offset0:38 offset1:39
	v_mul_f32_e32 v6, v40, v5
	v_mul_f32_e32 v7, v41, v5
	ds_write2st64_b32 v4, v6, v7 offset0:40 offset1:41
	v_mul_f32_e32 v6, v42, v5
	v_mul_f32_e32 v7, v43, v5
	ds_write2st64_b32 v4, v6, v7 offset0:42 offset1:43
	v_mul_f32_e32 v6, v44, v5
	v_mul_f32_e32 v7, v45, v5
	ds_write2st64_b32 v4, v6, v7 offset0:44 offset1:45
	v_mul_f32_e32 v6, v46, v5
	v_mul_f32_e32 v7, v47, v5
	ds_write2st64_b32 v4, v6, v7 offset0:46 offset1:47
	v_mul_f32_e32 v6, v16, v5
	v_mul_f32_e32 v7, v17, v5
	ds_write2st64_b32 v4, v6, v7 offset0:48 offset1:49
	v_mul_f32_e32 v6, v18, v5
	v_mul_f32_e32 v7, v19, v5
	ds_write2st64_b32 v4, v6, v7 offset0:50 offset1:51
	v_mul_f32_e32 v6, v20, v5
	v_mul_f32_e32 v7, v21, v5
	ds_write2st64_b32 v4, v6, v7 offset0:52 offset1:53
	v_mul_f32_e32 v6, v22, v5
	v_mul_f32_e32 v7, v23, v5
	ds_write2st64_b32 v4, v6, v7 offset0:54 offset1:55
	v_mul_f32_e32 v6, v24, v5
	v_mul_f32_e32 v7, v25, v5
	ds_write2st64_b32 v4, v6, v7 offset0:56 offset1:57
	v_mul_f32_e32 v6, v26, v5
	v_mul_f32_e32 v7, v27, v5
	ds_write2st64_b32 v4, v6, v7 offset0:58 offset1:59
	v_mul_f32_e32 v6, v28, v5
	v_mul_f32_e32 v7, v29, v5
	ds_write2st64_b32 v4, v6, v7 offset0:60 offset1:61
	v_mul_f32_e32 v6, v30, v5
	v_mul_f32_e32 v5, v31, v5
	ds_write2st64_b32 v4, v6, v5 offset0:62 offset1:63

; #define LAS __attribute__((address_space(3)))
; template <int MODE>
; __device__ __forceinline__ void attn_item(LAS unsigned char* lds, const AttnArgs& a, const int tid) {
;     ...
;     bf16x8 qf[NKS];
;     { const bf16_t* qrow = a.Q + (size_t)(qw0 + r) * a.ldq + map * 64 + 8 * h;
; #pragma unroll
;       for (int ks = 0; ks < NKS; ++ks) qf[ks] = *(const bf16x8*)(qrow + 16 * ks); }
;     if (MODE == 1) {
;         LAS float* cl = (LAS float*)(lds + A_CS); LAS float* wtot = (LAS float*)(lds + A_LUT);
;         const int n = a.q0 + 256; const bool on = 8 * tid < n;
;         float v[8]; float run = 0.f;
;         const float* lp = a.c + 8 * tid;
;         f32x4 x0 = {0.f, 0.f, 0.f, 0.f}, x1 = x0; if (on) { x0 = *(const f32x4*)lp; x1 = *(const f32x4*)(lp + 4); }
; __global__ void __launch_bounds__(512) mk_fwd(Params P) {
;     ...
;                         const int c = it & 255, rr = it >> 8, bh = rr * 16 + (c & 7) * 2 + (c >> 7); int j = (c >> 3) & 15; if (rr & 1) j = 15 - j;
;                         const int b = bh / 12, hh = bh - b * 12;
;                         const bf16_t* Zb = Z + (size_t)b * SEQ * NZ1;
;                         AttnArgs a; a.Q = Zb + hh * 128; a.K = Zb + 1536 + hh * 128; a.V = Zb + 3072 + hh * 128; a.G = Zb + gate_off + hh * 128; a.O = BR + (size_t)b * SEQ * DM + hh * 128;
;                         a.ldq = NZ1; a.ldkv = NZ1; a.ldg = NZ1; a.ldo = DM; a.q0 = 256 * j; a.ntiles = 4 * j + 4; a.c = LS + (size_t)bh * SEQ; a.lutsrc = nullptr; a.subg = nullptr;
.LBB0_50:
	s_ashr_i32 s18, s46, 4
	s_and_b32 s60, s18, -16
	s_lshl_b32 s18, s46, 1
	s_and_b32 s18, s18, 14
	s_or_b32 s18, s60, s18
	s_bfe_u32 s19, s46, 0x10007
	s_or_b32 s36, s18, s19
	s_bfe_u32 s18, s46, 0x40003
	s_and_b32 s19, s46, 0x100
	s_xor_b32 s26, s18, 15
	s_cmp_eq_u32 s19, 0
	s_cselect_b32 s54, s18, s26
	s_mul_hi_i32 s18, s36, 0x2aaaaaab
	s_lshr_b32 s19, s18, 31
	s_ashr_i32 s18, s18, 1
	s_add_i32 s18, s18, s19
	s_mul_i32 s19, s18, -12
	s_add_i32 s19, s19, s36
	s_mul_i32 s28, s18, 0x3a00000
	s_mul_hi_i32 s29, s18, 0x3a00000
	s_add_u32 s48, s30, s28
	s_addc_u32 s49, s31, s29
	s_lshl_b32 s26, s19, 7
	s_ashr_i32 s27, s26, 31
	s_lshl_b64 s[26:27], s[26:27], 1
	s_add_u32 s34, s48, s26
	v_readfirstlane_b32 s56, v180
	s_addc_u32 s35, s49, s27
	s_ashr_i32 s55, s56, 6
	s_lshl_b32 s47, s54, 8
	s_lshl_b32 s50, s55, 5
	s_add_i32 s51, s50, s47
	v_or_b32_e32 v12, s51, v181
	v_mov_b64_e32 v[2:3], s[34:35]
	v_mad_i64_i32 v[2:3], s[38:39], v12, s38, v[2:3]
	v_mov_b32_e32 v151, v1
	v_lshl_add_u64 v[2:3], v[2:3], 0, v[150:151]
	s_barrier
	global_load_dwordx4 v[116:119], v[2:3], off
	global_load_dwordx4 v[120:123], v[2:3], off offset:32
	global_load_dwordx4 v[124:127], v[2:3], off offset:64
	global_load_dwordx4 v[128:131], v[2:3], off offset:96
	global_load_dwordx4 v[132:135], v[2:3], off offset:128
	global_load_dwordx4 v[136:139], v[2:3], off offset:160
	global_load_dwordx4 v[140:143], v[2:3], off offset:192
	global_load_dwordx4 v[144:147], v[2:3], off offset:224
	s_add_i32 s19, s47, 0x100
	s_movk_i32 s63, 0x3a00
	v_cmp_gt_i32_e32 vcc, s19, v112
	v_mov_b32_e32 v2, 0
	v_mov_b32_e32 v3, 0
	v_mov_b32_e32 v4, 0
	v_mov_b32_e32 v5, 0
	v_mov_b32_e32 v6, 0
	v_mov_b32_e32 v7, 0
	v_mov_b32_e32 v8, 0
	v_mov_b32_e32 v9, 0
	s_and_saveexec_b64 s[38:39], vcc
	s_cbranch_execz .LBB0_52
	s_ashr_i32 s37, s36, 31
	s_lshl_b64 s[36:37], s[36:37], 14
	v_lshl_add_u64 v[2:3], v[148:149], 0, s[36:37]
	global_load_dwordx4 v[6:9], v[2:3], off
	s_nop 0
	global_load_dwordx4 v[2:5], v[2:3], off offset:16

; #define LAS __attribute__((address_space(3)))
; __device__ __forceinline__ float bflo(unsigned w) { return __uint_as_float(w << 16); }
; __device__ __forceinline__ float bfhi(unsigned w) { return __uint_as_float(w & 0xffff0000u); }
; __device__ __forceinline__ unsigned pk2(float lo, float hi) { const f32x2v v = {lo, hi}; return __builtin_bit_cast(unsigned, __builtin_convertvector(v, bf16x2v)); }
; __device__ __forceinline__ float silu_f(float g) { return g * fast_rcp(1.f + fast_exp2(-g * LOG2E)); }
; template <int MODE>
; __device__ __forceinline__ void attn_item(LAS unsigned char* lds, const AttnArgs& a, const int tid) {
;     ...
;     l += __shfl_xor(l, 32);
;     const float inv = 1.f / l;
;     const size_t qrow = (size_t)(qw0 + r);
;     if (MODE != 2) {
;         int ch = tid & 15, r0 = tid >> 4, lrow = 32 * wave + r, hh = h;
;         asm volatile("" : "+v"(ch), "+v"(r0), "+v"(lrow), "+v"(hh));
; #pragma unroll 1
;         for (int i0 = 0; i0 < 8; i0 += 4) { u32x4 gv[4];
; #pragma unroll
;           for (int i = 0; i < 4; ++i) gv[i] = *(const u32x4*)(a.G + (size_t)(a.q0 + r0 + 32 * (i0 + i)) * a.ldg + 8 * ch);
; #pragma unroll
;           for (int i = 0; i < 4; ++i) *(LAS u32x4*)(lds + off_b(r0 + 32 * (i0 + i), ch)) = gv[i]; }
;         __syncthreads();
; #pragma unroll
;         for (int dt = 0; dt < 4; ++dt)
; #pragma unroll
;             for (int g = 0; g < 4; ++g) { const unsigned ad = off_b(lrow, 4 * dt + g) + 8u * hh;
;                 const u32x2 gw = *(const LAS u32x2*)(lds + ad);
;                 const float v0 = o[dt][4 * g + 0] * inv * silu_f(bflo(gw.x)), v1 = o[dt][4 * g + 1] * inv * silu_f(bfhi(gw.x));
;                 const float v2 = o[dt][4 * g + 2] * inv * silu_f(bflo(gw.y)), v3 = o[dt][4 * g + 3] * inv * silu_f(bfhi(gw.y));
;                 u32x2 w; w.x = pk2(v0, v1); w.y = pk2(v2, v3);
;                 *(LAS u32x2*)(lds + ad) = w; }
.LBB0_70:
	v_cndmask_b32_e64 v12, 0, 1, s[28:29]
	s_or_b32 s35, s34, 1
	v_cmp_ne_u32_e32 vcc, 1, v12
	v_lshl_add_u32 v12, s34, 5, v6
	s_or_b32 s36, s34, 2
	v_mad_i64_i32 v[12:13], s[28:29], v12, s38, v[4:5]
	v_lshl_add_u32 v80, s35, 5, v6
	s_or_b32 s37, s34, 3
	global_load_dwordx4 v[12:15], v[12:13], off offset:1024
	v_mad_i64_i32 v[80:81], s[28:29], v80, s38, v[4:5]
	v_lshl_add_u32 v84, s36, 5, v6
	global_load_dwordx4 v[80:83], v[80:81], off offset:1024
	v_mad_i64_i32 v[84:85], s[28:29], v84, s38, v[4:5]
	v_lshl_add_u32 v88, s37, 5, v6
	global_load_dwordx4 v[84:87], v[84:85], off offset:1024
	v_mad_i64_i32 v[88:89], s[28:29], v88, s38, v[4:5]
	global_load_dwordx4 v[88:91], v[88:89], off offset:1024
	v_lshl_add_u32 v92, s34, 13, v11
	s_mov_b32 s34, 4
	s_mov_b64 s[28:29], 0
	s_and_b64 vcc, exec, vcc
	s_waitcnt vmcnt(0) lgkmcnt(0)
	ds_write_b128 v92, v[12:15]
	v_lshl_add_u32 v12, s35, 13, v11
	ds_write_b128 v12, v[80:83]
	v_lshl_add_u32 v12, s36, 13, v11
	ds_write_b128 v12, v[84:87]
	v_lshl_add_u32 v12, s37, 13, v11
	ds_write_b128 v12, v[88:91]
	s_cbranch_vccz .LBB0_70
	s_lshl_b64 s[18:19], s[18:19], 24
	s_add_u32 s18, s93, s18
	s_addc_u32 s19, s95, s19
	s_add_u32 s18, s18, s26
	v_add_f32_e32 v0, v154, v0
	s_addc_u32 s19, s19, s27
	v_div_scale_f32 v4, s[26:27], v0, v0, 1.0
	v_rcp_f32_e32 v5, v4
	s_waitcnt lgkmcnt(0)
	s_barrier
	v_fma_f32 v11, -v4, v5, 1.0
	v_fmac_f32_e32 v5, v11, v5
	v_div_scale_f32 v11, vcc, 1.0, v0, 1.0
	v_mul_f32_e32 v12, v11, v5
	v_fma_f32 v13, -v4, v12, v11
	v_fmac_f32_e32 v12, v13, v5
	v_fma_f32 v4, -v4, v12, v11
	v_div_fmas_f32 v4, v4, v5, v12
	v_div_fixup_f32 v0, v4, v0, 1.0
	v_lshlrev_b32_e32 v4, 8, v9
	v_lshlrev_b32_e32 v5, 2, v9
	v_bfe_u32 v9, v9, 2, 2
	v_and_or_b32 v5, v5, 12, v9
	v_lshlrev_b32_e32 v9, 3, v10
	v_add3_u32 v4, 0, v4, v9
	v_lshlrev_b32_e32 v5, 4, v5
	v_add_u32_e32 v9, v4, v5
	ds_read_b64 v[10:11], v9
	v_pk_mul_f32 v[64:65], v[64:65], v[0:1] op_sel_hi:[1,0]
	v_pk_mul_f32 v[48:49], v[48:49], v[0:1] op_sel_hi:[1,0]
	v_pk_mul_f32 v[32:33], v[32:33], v[0:1] op_sel_hi:[1,0]
	v_pk_mul_f32 v[16:17], v[16:17], v[0:1] op_sel_hi:[1,0]
	s_waitcnt lgkmcnt(0)
	v_lshlrev_b32_e32 v12, 16, v10
	v_and_b32_e32 v13, 0xffff0000, v10
	v_mul_f32_e32 v10, 0xbfb8aa3b, v12
	v_exp_f32_e32 v10, v10
	s_movk_i32 s26, 0xe0
	v_lshl_add_u64 v[2:3], v[2:3], 1, s[18:19]
	s_mov_b32 s18, 0
	v_add_f32_e32 v10, 1.0, v10
	v_rcp_f32_e32 v14, v10
	v_mul_f32_e32 v10, 0xbfb8aa3b, v13
	v_exp_f32_e32 v10, v10
	s_mov_b64 s[56:57], 0x100
	v_add_f32_e32 v10, 1.0, v10
	v_rcp_f32_e32 v15, v10
	v_lshlrev_b32_e32 v10, 16, v11
	v_and_b32_e32 v11, 0xffff0000, v11
	v_pk_mul_f32 v[12:13], v[14:15], v[12:13]
	v_mul_f32_e32 v14, 0xbfb8aa3b, v10
	v_mul_f32_e32 v15, 0xbfb8aa3b, v11
	v_exp_f32_e32 v14, v14
	v_exp_f32_e32 v15, v15
	v_pk_mul_f32 v[12:13], v[64:65], v[12:13]
	v_pk_mul_f32 v[64:65], v[66:67], v[0:1] op_sel_hi:[1,0]
	v_add_f32_e32 v14, 1.0, v14
	v_add_f32_e32 v15, 1.0, v15
	v_rcp_f32_e32 v14, v14
	v_rcp_f32_e32 v15, v15
	v_cvt_pk_bf16_f32 v12, v12, v13
	v_pk_mul_f32 v[10:11], v[14:15], v[10:11]
	s_nop 0
	v_pk_mul_f32 v[10:11], v[64:65], v[10:11]
	v_pk_mul_f32 v[64:65], v[68:69], v[0:1] op_sel_hi:[1,0]
	v_cvt_pk_bf16_f32 v13, v10, v11
	ds_write_b64 v9, v[12:13]
	v_xad_u32 v9, v5, 16, v4
	ds_read_b64 v[10:11], v9
	s_waitcnt lgkmcnt(0)
	v_lshlrev_b32_e32 v12, 16, v10
	v_and_b32_e32 v13, 0xffff0000, v10
	v_mul_f32_e32 v10, 0xbfb8aa3b, v12
	v_exp_f32_e32 v10, v10
	s_nop 0
	v_add_f32_e32 v10, 1.0, v10
	v_rcp_f32_e32 v14, v10
	v_mul_f32_e32 v10, 0xbfb8aa3b, v13
	v_exp_f32_e32 v10, v10
	s_nop 0
	v_add_f32_e32 v10, 1.0, v10
	v_rcp_f32_e32 v15, v10
	v_lshlrev_b32_e32 v10, 16, v11
	v_and_b32_e32 v11, 0xffff0000, v11
	v_pk_mul_f32 v[12:13], v[14:15], v[12:13]
	v_mul_f32_e32 v14, 0xbfb8aa3b, v10
	v_mul_f32_e32 v15, 0xbfb8aa3b, v11
	v_exp_f32_e32 v14, v14
	v_exp_f32_e32 v15, v15
	v_pk_mul_f32 v[12:13], v[64:65], v[12:13]
	v_pk_mul_f32 v[64:65], v[70:71], v[0:1] op_sel_hi:[1,0]
	v_add_f32_e32 v14, 1.0, v14
	v_add_f32_e32 v15, 1.0, v15
	v_rcp_f32_e32 v14, v14
	v_rcp_f32_e32 v15, v15
	v_cvt_pk_bf16_f32 v12, v12, v13
	v_pk_mul_f32 v[10:11], v[14:15], v[10:11]
	s_nop 0
	v_pk_mul_f32 v[10:11], v[64:65], v[10:11]
	v_pk_mul_f32 v[64:65], v[72:73], v[0:1] op_sel_hi:[1,0]
	v_cvt_pk_bf16_f32 v13, v10, v11
	ds_write_b64 v9, v[12:13]
	v_xad_u32 v9, v5, 32, v4
	ds_read_b64 v[10:11], v9
	s_waitcnt lgkmcnt(0)
	v_lshlrev_b32_e32 v12, 16, v10
	v_and_b32_e32 v13, 0xffff0000, v10
	v_mul_f32_e32 v10, 0xbfb8aa3b, v12
	v_exp_f32_e32 v10, v10
	s_nop 0
	v_add_f32_e32 v10, 1.0, v10
	v_rcp_f32_e32 v14, v10
	v_mul_f32_e32 v10, 0xbfb8aa3b, v13
	v_exp_f32_e32 v10, v10
	s_nop 0
	v_add_f32_e32 v10, 1.0, v10
	v_rcp_f32_e32 v15, v10
	v_lshlrev_b32_e32 v10, 16, v11
	v_and_b32_e32 v11, 0xffff0000, v11
	v_pk_mul_f32 v[12:13], v[14:15], v[12:13]
	v_mul_f32_e32 v14, 0xbfb8aa3b, v10
	v_mul_f32_e32 v15, 0xbfb8aa3b, v11
	v_exp_f32_e32 v14, v14
	v_exp_f32_e32 v15, v15
	v_pk_mul_f32 v[12:13], v[64:65], v[12:13]
	v_pk_mul_f32 v[64:65], v[74:75], v[0:1] op_sel_hi:[1,0]
	v_add_f32_e32 v14, 1.0, v14
	v_add_f32_e32 v15, 1.0, v15
	v_rcp_f32_e32 v14, v14
	v_rcp_f32_e32 v15, v15
	v_cvt_pk_bf16_f32 v12, v12, v13
	v_pk_mul_f32 v[10:11], v[14:15], v[10:11]
	s_nop 0
	v_pk_mul_f32 v[10:11], v[64:65], v[10:11]
	v_pk_mul_f32 v[64:65], v[76:77], v[0:1] op_sel_hi:[1,0]
	v_cvt_pk_bf16_f32 v13, v10, v11
	ds_write_b64 v9, v[12:13]
	v_xad_u32 v9, v5, 48, v4
	ds_read_b64 v[10:11], v9
	s_waitcnt lgkmcnt(0)
; #define LAS __attribute__((address_space(3)))
; __device__ __forceinline__ float bflo(unsigned w) { return __uint_as_float(w << 16); }
; __device__ __forceinline__ float bfhi(unsigned w) { return __uint_as_float(w & 0xffff0000u); }
; __device__ __forceinline__ unsigned pk2(float lo, float hi) { const f32x2v v = {lo, hi}; return __builtin_bit_cast(unsigned, __builtin_convertvector(v, bf16x2v)); }
; __device__ __forceinline__ float silu_f(float g) { return g * fast_rcp(1.f + fast_exp2(-g * LOG2E)); }
; template <int MODE>
; __device__ __forceinline__ void attn_item(LAS unsigned char* lds, const AttnArgs& a, const int tid) {
;     ...
;         for (int dt = 0; dt < 4; ++dt)
; #pragma unroll
;             for (int g = 0; g < 4; ++g) { const unsigned ad = off_b(lrow, 4 * dt + g) + 8u * hh;
;                 const u32x2 gw = *(const LAS u32x2*)(lds + ad);
;                 const float v0 = o[dt][4 * g + 0] * inv * silu_f(bflo(gw.x)), v1 = o[dt][4 * g + 1] * inv * silu_f(bfhi(gw.x));
;                 const float v2 = o[dt][4 * g + 2] * inv * silu_f(bflo(gw.y)), v3 = o[dt][4 * g + 3] * inv * silu_f(bfhi(gw.y));
;                 u32x2 w; w.x = pk2(v0, v1); w.y = pk2(v2, v3);
;                 *(LAS u32x2*)(lds + ad) = w; }
	v_lshlrev_b32_e32 v12, 16, v10
	v_and_b32_e32 v13, 0xffff0000, v10
	v_mul_f32_e32 v10, 0xbfb8aa3b, v12
	v_exp_f32_e32 v10, v10
	s_nop 0
	v_add_f32_e32 v10, 1.0, v10
	v_rcp_f32_e32 v14, v10
	v_mul_f32_e32 v10, 0xbfb8aa3b, v13
	v_exp_f32_e32 v10, v10
	s_nop 0
	v_add_f32_e32 v10, 1.0, v10
	v_rcp_f32_e32 v15, v10
	v_lshlrev_b32_e32 v10, 16, v11
	v_and_b32_e32 v11, 0xffff0000, v11
	v_pk_mul_f32 v[12:13], v[14:15], v[12:13]
	v_mul_f32_e32 v14, 0xbfb8aa3b, v10
	v_mul_f32_e32 v15, 0xbfb8aa3b, v11
	v_exp_f32_e32 v14, v14
	v_exp_f32_e32 v15, v15
	v_pk_mul_f32 v[12:13], v[64:65], v[12:13]
	v_pk_mul_f32 v[64:65], v[78:79], v[0:1] op_sel_hi:[1,0]
	v_add_f32_e32 v14, 1.0, v14
	v_add_f32_e32 v15, 1.0, v15
	v_rcp_f32_e32 v14, v14
	v_rcp_f32_e32 v15, v15
	v_cvt_pk_bf16_f32 v12, v12, v13
	v_pk_mul_f32 v[10:11], v[14:15], v[10:11]
	s_nop 0
	v_pk_mul_f32 v[10:11], v[64:65], v[10:11]
	s_nop 0
	v_cvt_pk_bf16_f32 v13, v10, v11
	ds_write_b64 v9, v[12:13]
	v_xad_u32 v9, v5, 64, v4
	ds_read_b64 v[10:11], v9
	s_waitcnt lgkmcnt(0)
	v_lshlrev_b32_e32 v12, 16, v10
	v_and_b32_e32 v13, 0xffff0000, v10
	v_mul_f32_e32 v10, 0xbfb8aa3b, v12
	v_exp_f32_e32 v10, v10
	s_nop 0
	v_add_f32_e32 v10, 1.0, v10
	v_rcp_f32_e32 v14, v10
	v_mul_f32_e32 v10, 0xbfb8aa3b, v13
	v_exp_f32_e32 v10, v10
	s_nop 0
	v_add_f32_e32 v10, 1.0, v10
	v_rcp_f32_e32 v15, v10
	v_lshlrev_b32_e32 v10, 16, v11
	v_and_b32_e32 v11, 0xffff0000, v11
	v_pk_mul_f32 v[12:13], v[14:15], v[12:13]
	v_mul_f32_e32 v14, 0xbfb8aa3b, v10
	v_mul_f32_e32 v15, 0xbfb8aa3b, v11
	v_exp_f32_e32 v14, v14
	v_exp_f32_e32 v15, v15
	v_pk_mul_f32 v[12:13], v[48:49], v[12:13]
	v_pk_mul_f32 v[48:49], v[50:51], v[0:1] op_sel_hi:[1,0]
	v_add_f32_e32 v14, 1.0, v14
	v_add_f32_e32 v15, 1.0, v15
	v_rcp_f32_e32 v14, v14
	v_rcp_f32_e32 v15, v15
	v_cvt_pk_bf16_f32 v12, v12, v13
	v_pk_mul_f32 v[10:11], v[14:15], v[10:11]
	s_nop 0
	v_pk_mul_f32 v[10:11], v[48:49], v[10:11]
	v_pk_mul_f32 v[48:49], v[52:53], v[0:1] op_sel_hi:[1,0]
	v_cvt_pk_bf16_f32 v13, v10, v11
	ds_write_b64 v9, v[12:13]
	v_xad_u32 v9, v5, s80, v4
	ds_read_b64 v[10:11], v9
	s_waitcnt lgkmcnt(0)
	v_lshlrev_b32_e32 v12, 16, v10
	v_and_b32_e32 v13, 0xffff0000, v10
	v_mul_f32_e32 v10, 0xbfb8aa3b, v12
	v_exp_f32_e32 v10, v10
	s_nop 0
	v_add_f32_e32 v10, 1.0, v10
	v_rcp_f32_e32 v14, v10
	v_mul_f32_e32 v10, 0xbfb8aa3b, v13
	v_exp_f32_e32 v10, v10
	s_nop 0
	v_add_f32_e32 v10, 1.0, v10
	v_rcp_f32_e32 v15, v10
	v_lshlrev_b32_e32 v10, 16, v11
	v_and_b32_e32 v11, 0xffff0000, v11
	v_pk_mul_f32 v[12:13], v[14:15], v[12:13]
	v_mul_f32_e32 v14, 0xbfb8aa3b, v10
	v_mul_f32_e32 v15, 0xbfb8aa3b, v11
	v_exp_f32_e32 v14, v14
	v_exp_f32_e32 v15, v15
	v_pk_mul_f32 v[12:13], v[48:49], v[12:13]
	v_pk_mul_f32 v[48:49], v[54:55], v[0:1] op_sel_hi:[1,0]
	v_add_f32_e32 v14, 1.0, v14
	v_add_f32_e32 v15, 1.0, v15
	v_rcp_f32_e32 v14, v14
	v_rcp_f32_e32 v15, v15
	v_cvt_pk_bf16_f32 v12, v12, v13
	v_pk_mul_f32 v[10:11], v[14:15], v[10:11]
	s_nop 0
	v_pk_mul_f32 v[10:11], v[48:49], v[10:11]
	v_pk_mul_f32 v[48:49], v[56:57], v[0:1] op_sel_hi:[1,0]
	v_cvt_pk_bf16_f32 v13, v10, v11
	ds_write_b64 v9, v[12:13]
	v_xad_u32 v9, v5, s79, v4
	ds_read_b64 v[10:11], v9
	s_waitcnt lgkmcnt(0)
	v_lshlrev_b32_e32 v12, 16, v10
	v_and_b32_e32 v13, 0xffff0000, v10
	v_mul_f32_e32 v10, 0xbfb8aa3b, v12
	v_exp_f32_e32 v10, v10
	s_nop 0
	v_add_f32_e32 v10, 1.0, v10
	v_rcp_f32_e32 v14, v10
	v_mul_f32_e32 v10, 0xbfb8aa3b, v13
	v_exp_f32_e32 v10, v10
	s_nop 0
	v_add_f32_e32 v10, 1.0, v10
	v_rcp_f32_e32 v15, v10
	v_lshlrev_b32_e32 v10, 16, v11
	v_and_b32_e32 v11, 0xffff0000, v11
	v_pk_mul_f32 v[12:13], v[14:15], v[12:13]
	v_mul_f32_e32 v14, 0xbfb8aa3b, v10
	v_mul_f32_e32 v15, 0xbfb8aa3b, v11
	v_exp_f32_e32 v14, v14
	v_exp_f32_e32 v15, v15
	v_pk_mul_f32 v[12:13], v[48:49], v[12:13]
	v_pk_mul_f32 v[48:49], v[58:59], v[0:1] op_sel_hi:[1,0]
	v_add_f32_e32 v14, 1.0, v14
	v_add_f32_e32 v15, 1.0, v15
	v_rcp_f32_e32 v14, v14
	v_rcp_f32_e32 v15, v15
	v_cvt_pk_bf16_f32 v12, v12, v13
	v_pk_mul_f32 v[10:11], v[14:15], v[10:11]
	s_nop 0
	v_pk_mul_f32 v[10:11], v[48:49], v[10:11]
	v_pk_mul_f32 v[48:49], v[60:61], v[0:1] op_sel_hi:[1,0]
	v_cvt_pk_bf16_f32 v13, v10, v11
	ds_write_b64 v9, v[12:13]
	v_xad_u32 v9, v5, s22, v4
	ds_read_b64 v[10:11], v9
	s_waitcnt lgkmcnt(0)
	v_lshlrev_b32_e32 v12, 16, v10
	v_and_b32_e32 v13, 0xffff0000, v10
	v_mul_f32_e32 v10, 0xbfb8aa3b, v12
	v_exp_f32_e32 v10, v10
	s_nop 0
	v_add_f32_e32 v10, 1.0, v10
	v_rcp_f32_e32 v14, v10
	v_mul_f32_e32 v10, 0xbfb8aa3b, v13
	v_exp_f32_e32 v10, v10
	s_nop 0
	v_add_f32_e32 v10, 1.0, v10
	v_rcp_f32_e32 v15, v10
	v_lshlrev_b32_e32 v10, 16, v11
	v_and_b32_e32 v11, 0xffff0000, v11
	v_pk_mul_f32 v[12:13], v[14:15], v[12:13]
	v_mul_f32_e32 v14, 0xbfb8aa3b, v10
	v_mul_f32_e32 v15, 0xbfb8aa3b, v11
	v_exp_f32_e32 v14, v14
	v_exp_f32_e32 v15, v15
	v_pk_mul_f32 v[12:13], v[48:49], v[12:13]
	v_pk_mul_f32 v[48:49], v[62:63], v[0:1] op_sel_hi:[1,0]
	v_add_f32_e32 v14, 1.0, v14
	v_add_f32_e32 v15, 1.0, v15
	v_rcp_f32_e32 v14, v14
	v_rcp_f32_e32 v15, v15
	v_cvt_pk_bf16_f32 v12, v12, v13
	v_pk_mul_f32 v[10:11], v[14:15], v[10:11]
	s_nop 0
	v_pk_mul_f32 v[10:11], v[48:49], v[10:11]
	s_nop 0
	v_cvt_pk_bf16_f32 v13, v10, v11
	ds_write_b64 v9, v[12:13]
	v_xad_u32 v9, v5, s24, v4
	ds_read_b64 v[10:11], v9
	s_waitcnt lgkmcnt(0)
; #define LAS __attribute__((address_space(3)))
; __device__ __forceinline__ float bflo(unsigned w) { return __uint_as_float(w << 16); }
; __device__ __forceinline__ float bfhi(unsigned w) { return __uint_as_float(w & 0xffff0000u); }
; __device__ __forceinline__ unsigned pk2(float lo, float hi) { const f32x2v v = {lo, hi}; return __builtin_bit_cast(unsigned, __builtin_convertvector(v, bf16x2v)); }
; __device__ __forceinline__ float silu_f(float g) { return g * fast_rcp(1.f + fast_exp2(-g * LOG2E)); }
; template <int MODE>
; __device__ __forceinline__ void attn_item(LAS unsigned char* lds, const AttnArgs& a, const int tid) {
;     ...
;         for (int dt = 0; dt < 4; ++dt)
; #pragma unroll
;             for (int g = 0; g < 4; ++g) { const unsigned ad = off_b(lrow, 4 * dt + g) + 8u * hh;
;                 const u32x2 gw = *(const LAS u32x2*)(lds + ad);
;                 const float v0 = o[dt][4 * g + 0] * inv * silu_f(bflo(gw.x)), v1 = o[dt][4 * g + 1] * inv * silu_f(bfhi(gw.x));
;                 const float v2 = o[dt][4 * g + 2] * inv * silu_f(bflo(gw.y)), v3 = o[dt][4 * g + 3] * inv * silu_f(bfhi(gw.y));
;                 u32x2 w; w.x = pk2(v0, v1); w.y = pk2(v2, v3);
;                 *(LAS u32x2*)(lds + ad) = w; }
	v_lshlrev_b32_e32 v12, 16, v10
	v_and_b32_e32 v13, 0xffff0000, v10
	v_mul_f32_e32 v10, 0xbfb8aa3b, v12
	v_exp_f32_e32 v10, v10
	s_nop 0
	v_add_f32_e32 v10, 1.0, v10
	v_rcp_f32_e32 v14, v10
	v_mul_f32_e32 v10, 0xbfb8aa3b, v13
	v_exp_f32_e32 v10, v10
	s_nop 0
	v_add_f32_e32 v10, 1.0, v10
	v_rcp_f32_e32 v15, v10
	v_lshlrev_b32_e32 v10, 16, v11
	v_and_b32_e32 v11, 0xffff0000, v11
	v_pk_mul_f32 v[12:13], v[14:15], v[12:13]
	v_mul_f32_e32 v14, 0xbfb8aa3b, v10
	v_mul_f32_e32 v15, 0xbfb8aa3b, v11
	v_exp_f32_e32 v14, v14
	v_exp_f32_e32 v15, v15
	v_pk_mul_f32 v[12:13], v[32:33], v[12:13]
	v_pk_mul_f32 v[32:33], v[34:35], v[0:1] op_sel_hi:[1,0]
	v_add_f32_e32 v14, 1.0, v14
	v_add_f32_e32 v15, 1.0, v15
	v_rcp_f32_e32 v14, v14
	v_rcp_f32_e32 v15, v15
	v_cvt_pk_bf16_f32 v12, v12, v13
	v_pk_mul_f32 v[10:11], v[14:15], v[10:11]
	s_nop 0
	v_pk_mul_f32 v[10:11], v[32:33], v[10:11]
	v_pk_mul_f32 v[32:33], v[36:37], v[0:1] op_sel_hi:[1,0]
	v_cvt_pk_bf16_f32 v13, v10, v11
	ds_write_b64 v9, v[12:13]
	v_xad_u32 v9, v5, s25, v4
	ds_read_b64 v[10:11], v9
	s_waitcnt lgkmcnt(0)
	v_lshlrev_b32_e32 v12, 16, v10
	v_and_b32_e32 v13, 0xffff0000, v10
	v_mul_f32_e32 v10, 0xbfb8aa3b, v12
	v_exp_f32_e32 v10, v10
	s_nop 0
	v_add_f32_e32 v10, 1.0, v10
	v_rcp_f32_e32 v14, v10
	v_mul_f32_e32 v10, 0xbfb8aa3b, v13
	v_exp_f32_e32 v10, v10
	s_nop 0
	v_add_f32_e32 v10, 1.0, v10
	v_rcp_f32_e32 v15, v10
	v_lshlrev_b32_e32 v10, 16, v11
	v_and_b32_e32 v11, 0xffff0000, v11
	v_pk_mul_f32 v[12:13], v[14:15], v[12:13]
	v_mul_f32_e32 v14, 0xbfb8aa3b, v10
	v_mul_f32_e32 v15, 0xbfb8aa3b, v11
	v_exp_f32_e32 v14, v14
	v_exp_f32_e32 v15, v15
	v_pk_mul_f32 v[12:13], v[32:33], v[12:13]
	v_pk_mul_f32 v[32:33], v[38:39], v[0:1] op_sel_hi:[1,0]
	v_add_f32_e32 v14, 1.0, v14
	v_add_f32_e32 v15, 1.0, v15
	v_rcp_f32_e32 v14, v14
	v_rcp_f32_e32 v15, v15
	v_cvt_pk_bf16_f32 v12, v12, v13
	v_pk_mul_f32 v[10:11], v[14:15], v[10:11]
	s_nop 0
	v_pk_mul_f32 v[10:11], v[32:33], v[10:11]
	v_pk_mul_f32 v[32:33], v[40:41], v[0:1] op_sel_hi:[1,0]
	v_cvt_pk_bf16_f32 v13, v10, v11
	ds_write_b64 v9, v[12:13]
	v_xad_u32 v9, v5, s75, v4
	ds_read_b64 v[10:11], v9
	s_waitcnt lgkmcnt(0)
	v_lshlrev_b32_e32 v12, 16, v10
	v_and_b32_e32 v13, 0xffff0000, v10
	v_mul_f32_e32 v10, 0xbfb8aa3b, v12
	v_exp_f32_e32 v10, v10
	s_nop 0
	v_add_f32_e32 v10, 1.0, v10
	v_rcp_f32_e32 v14, v10
	v_mul_f32_e32 v10, 0xbfb8aa3b, v13
	v_exp_f32_e32 v10, v10
	s_nop 0
	v_add_f32_e32 v10, 1.0, v10
	v_rcp_f32_e32 v15, v10
	v_lshlrev_b32_e32 v10, 16, v11
	v_and_b32_e32 v11, 0xffff0000, v11
	v_pk_mul_f32 v[12:13], v[14:15], v[12:13]
	v_mul_f32_e32 v14, 0xbfb8aa3b, v10
	v_mul_f32_e32 v15, 0xbfb8aa3b, v11
	v_exp_f32_e32 v14, v14
	v_exp_f32_e32 v15, v15
	v_pk_mul_f32 v[12:13], v[32:33], v[12:13]
	v_pk_mul_f32 v[32:33], v[42:43], v[0:1] op_sel_hi:[1,0]
	v_add_f32_e32 v14, 1.0, v14
	v_add_f32_e32 v15, 1.0, v15
	v_rcp_f32_e32 v14, v14
	v_rcp_f32_e32 v15, v15
	v_cvt_pk_bf16_f32 v12, v12, v13
	v_pk_mul_f32 v[10:11], v[14:15], v[10:11]
	s_nop 0
	v_pk_mul_f32 v[10:11], v[32:33], v[10:11]
	v_pk_mul_f32 v[32:33], v[44:45], v[0:1] op_sel_hi:[1,0]
	v_cvt_pk_bf16_f32 v13, v10, v11
	ds_write_b64 v9, v[12:13]
	v_xad_u32 v9, v5, s76, v4
	ds_read_b64 v[10:11], v9
	s_waitcnt lgkmcnt(0)
	v_lshlrev_b32_e32 v12, 16, v10
	v_and_b32_e32 v13, 0xffff0000, v10
	v_mul_f32_e32 v10, 0xbfb8aa3b, v12
	v_exp_f32_e32 v10, v10
	s_nop 0
	v_add_f32_e32 v10, 1.0, v10
	v_rcp_f32_e32 v14, v10
	v_mul_f32_e32 v10, 0xbfb8aa3b, v13
	v_exp_f32_e32 v10, v10
	s_nop 0
	v_add_f32_e32 v10, 1.0, v10
	v_rcp_f32_e32 v15, v10
	v_lshlrev_b32_e32 v10, 16, v11
	v_and_b32_e32 v11, 0xffff0000, v11
	v_pk_mul_f32 v[12:13], v[14:15], v[12:13]
	v_mul_f32_e32 v14, 0xbfb8aa3b, v10
	v_mul_f32_e32 v15, 0xbfb8aa3b, v11
	v_exp_f32_e32 v14, v14
	v_exp_f32_e32 v15, v15
	v_pk_mul_f32 v[12:13], v[32:33], v[12:13]
	v_pk_mul_f32 v[32:33], v[46:47], v[0:1] op_sel_hi:[1,0]
	v_add_f32_e32 v14, 1.0, v14
	v_add_f32_e32 v15, 1.0, v15
	v_rcp_f32_e32 v14, v14
	v_rcp_f32_e32 v15, v15
	v_cvt_pk_bf16_f32 v12, v12, v13
	v_pk_mul_f32 v[10:11], v[14:15], v[10:11]
	s_nop 0
	v_pk_mul_f32 v[10:11], v[32:33], v[10:11]
	s_nop 0
	v_cvt_pk_bf16_f32 v13, v10, v11
	ds_write_b64 v9, v[12:13]
	v_xad_u32 v9, v5, s77, v4
	ds_read_b64 v[10:11], v9
	s_waitcnt lgkmcnt(0)
	v_lshlrev_b32_e32 v12, 16, v10
	v_and_b32_e32 v13, 0xffff0000, v10
	v_mul_f32_e32 v10, 0xbfb8aa3b, v12
	v_exp_f32_e32 v10, v10
	s_nop 0
	v_add_f32_e32 v10, 1.0, v10
	v_rcp_f32_e32 v14, v10
	v_mul_f32_e32 v10, 0xbfb8aa3b, v13
	v_exp_f32_e32 v10, v10
	s_nop 0
	v_add_f32_e32 v10, 1.0, v10
	v_rcp_f32_e32 v15, v10
	v_lshlrev_b32_e32 v10, 16, v11
	v_and_b32_e32 v11, 0xffff0000, v11
	v_pk_mul_f32 v[12:13], v[14:15], v[12:13]
	v_mul_f32_e32 v14, 0xbfb8aa3b, v10
	v_mul_f32_e32 v15, 0xbfb8aa3b, v11
	v_exp_f32_e32 v14, v14
	v_exp_f32_e32 v15, v15
	v_pk_mul_f32 v[12:13], v[16:17], v[12:13]
	v_pk_mul_f32 v[16:17], v[18:19], v[0:1] op_sel_hi:[1,0]
	v_add_f32_e32 v14, 1.0, v14
	v_add_f32_e32 v15, 1.0, v15
	v_rcp_f32_e32 v14, v14
	v_rcp_f32_e32 v15, v15
	v_cvt_pk_bf16_f32 v12, v12, v13
	v_pk_mul_f32 v[10:11], v[14:15], v[10:11]
	s_nop 0
	v_pk_mul_f32 v[10:11], v[16:17], v[10:11]
	v_pk_mul_f32 v[16:17], v[20:21], v[0:1] op_sel_hi:[1,0]
	v_cvt_pk_bf16_f32 v13, v10, v11
	ds_write_b64 v9, v[12:13]
	v_xad_u32 v9, v5, s78, v4
	ds_read_b64 v[10:11], v9
	s_waitcnt lgkmcnt(0)
; #define LAS __attribute__((address_space(3)))
; __device__ __forceinline__ float bflo(unsigned w) { return __uint_as_float(w << 16); }
; __device__ __forceinline__ float bfhi(unsigned w) { return __uint_as_float(w & 0xffff0000u); }
; __device__ __forceinline__ unsigned pk2(float lo, float hi) { const f32x2v v = {lo, hi}; return __builtin_bit_cast(unsigned, __builtin_convertvector(v, bf16x2v)); }
; __device__ __forceinline__ float silu_f(float g) { return g * fast_rcp(1.f + fast_exp2(-g * LOG2E)); }
; template <int MODE>
; __device__ __forceinline__ void attn_item(LAS unsigned char* lds, const AttnArgs& a, const int tid) {
;     ...
;         for (int dt = 0; dt < 4; ++dt)
; #pragma unroll
;             for (int g = 0; g < 4; ++g) { const unsigned ad = off_b(lrow, 4 * dt + g) + 8u * hh;
;                 const u32x2 gw = *(const LAS u32x2*)(lds + ad);
;                 const float v0 = o[dt][4 * g + 0] * inv * silu_f(bflo(gw.x)), v1 = o[dt][4 * g + 1] * inv * silu_f(bfhi(gw.x));
;                 const float v2 = o[dt][4 * g + 2] * inv * silu_f(bflo(gw.y)), v3 = o[dt][4 * g + 3] * inv * silu_f(bfhi(gw.y));
;                 u32x2 w; w.x = pk2(v0, v1); w.y = pk2(v2, v3);
;                 *(LAS u32x2*)(lds + ad) = w; }
;         __syncthreads();
; #pragma unroll 4
;         for (int i = 0; i < 8; ++i) { const u32x4 ov = *(const LAS u32x4*)(lds + off_b(r0 + 32 * i, ch)); *(u32x4*)(a.O + (size_t)(a.q0 + r0 + 32 * i) * a.ldo + 8 * ch) = ov; }
	v_lshlrev_b32_e32 v12, 16, v10
	v_and_b32_e32 v13, 0xffff0000, v10
	v_mul_f32_e32 v10, 0xbfb8aa3b, v12
	v_exp_f32_e32 v10, v10
	s_nop 0
	v_add_f32_e32 v10, 1.0, v10
	v_rcp_f32_e32 v14, v10
	v_mul_f32_e32 v10, 0xbfb8aa3b, v13
	v_exp_f32_e32 v10, v10
	s_nop 0
	v_add_f32_e32 v10, 1.0, v10
	v_rcp_f32_e32 v15, v10
	v_lshlrev_b32_e32 v10, 16, v11
	v_and_b32_e32 v11, 0xffff0000, v11
	v_pk_mul_f32 v[12:13], v[14:15], v[12:13]
	v_mul_f32_e32 v14, 0xbfb8aa3b, v10
	v_mul_f32_e32 v15, 0xbfb8aa3b, v11
	v_exp_f32_e32 v14, v14
	v_exp_f32_e32 v15, v15
	v_pk_mul_f32 v[12:13], v[16:17], v[12:13]
	v_pk_mul_f32 v[16:17], v[22:23], v[0:1] op_sel_hi:[1,0]
	v_add_f32_e32 v14, 1.0, v14
	v_add_f32_e32 v15, 1.0, v15
	v_rcp_f32_e32 v14, v14
	v_rcp_f32_e32 v15, v15
	v_cvt_pk_bf16_f32 v12, v12, v13
	v_pk_mul_f32 v[10:11], v[14:15], v[10:11]
	s_nop 0
	v_pk_mul_f32 v[10:11], v[16:17], v[10:11]
	v_pk_mul_f32 v[16:17], v[24:25], v[0:1] op_sel_hi:[1,0]
	v_cvt_pk_bf16_f32 v13, v10, v11
	ds_write_b64 v9, v[12:13]
	v_xad_u32 v9, v5, s26, v4
	ds_read_b64 v[10:11], v9
	s_movk_i32 s26, 0xf0
	s_waitcnt lgkmcnt(0)
	v_lshlrev_b32_e32 v12, 16, v10
	v_and_b32_e32 v13, 0xffff0000, v10
	v_mul_f32_e32 v10, 0xbfb8aa3b, v12
	v_exp_f32_e32 v10, v10
	s_nop 0
	v_add_f32_e32 v10, 1.0, v10
	v_rcp_f32_e32 v14, v10
	v_mul_f32_e32 v10, 0xbfb8aa3b, v13
	v_exp_f32_e32 v10, v10
	s_nop 0
	v_add_f32_e32 v10, 1.0, v10
	v_rcp_f32_e32 v15, v10
	v_lshlrev_b32_e32 v10, 16, v11
	v_and_b32_e32 v11, 0xffff0000, v11
	v_pk_mul_f32 v[12:13], v[14:15], v[12:13]
	v_mul_f32_e32 v14, 0xbfb8aa3b, v10
	v_mul_f32_e32 v15, 0xbfb8aa3b, v11
	v_exp_f32_e32 v14, v14
	v_exp_f32_e32 v15, v15
	v_pk_mul_f32 v[12:13], v[16:17], v[12:13]
	v_pk_mul_f32 v[16:17], v[26:27], v[0:1] op_sel_hi:[1,0]
	v_add_f32_e32 v14, 1.0, v14
	v_add_f32_e32 v15, 1.0, v15
	v_rcp_f32_e32 v14, v14
	v_rcp_f32_e32 v15, v15
	v_cvt_pk_bf16_f32 v12, v12, v13
	v_pk_mul_f32 v[10:11], v[14:15], v[10:11]
	s_nop 0
	v_pk_mul_f32 v[10:11], v[16:17], v[10:11]
	v_pk_mul_f32 v[14:15], v[28:29], v[0:1] op_sel_hi:[1,0]
	v_cvt_pk_bf16_f32 v13, v10, v11
	ds_write_b64 v9, v[12:13]
	v_xad_u32 v9, v5, s26, v4
	ds_read_b64 v[4:5], v9
	s_waitcnt lgkmcnt(0)
	v_lshlrev_b32_e32 v10, 16, v4
	v_and_b32_e32 v11, 0xffff0000, v4
	v_mul_f32_e32 v4, 0xbfb8aa3b, v10
	v_exp_f32_e32 v4, v4
	s_nop 0
	v_add_f32_e32 v4, 1.0, v4
	v_rcp_f32_e32 v12, v4
	v_mul_f32_e32 v4, 0xbfb8aa3b, v11
	v_exp_f32_e32 v4, v4
	s_nop 0
	v_add_f32_e32 v4, 1.0, v4
	v_rcp_f32_e32 v13, v4
	v_lshlrev_b32_e32 v4, 16, v5
	v_and_b32_e32 v5, 0xffff0000, v5
	v_pk_mul_f32 v[10:11], v[12:13], v[10:11]
	s_nop 0
	v_pk_mul_f32 v[10:11], v[14:15], v[10:11]
	v_mul_f32_e32 v12, 0xbfb8aa3b, v4
	v_pk_mul_f32 v[14:15], v[30:31], v[0:1] op_sel_hi:[1,0]
	v_mul_f32_e32 v0, 0xbfb8aa3b, v5
	v_exp_f32_e32 v12, v12
	v_exp_f32_e32 v0, v0
	v_cvt_pk_bf16_f32 v10, v10, v11
	v_add_f32_e32 v12, 1.0, v12
	v_add_f32_e32 v0, 1.0, v0
	v_rcp_f32_e32 v12, v12
	v_rcp_f32_e32 v13, v0
	v_add3_u32 v0, v7, v8, 0
	v_pk_mul_f32 v[4:5], v[12:13], v[4:5]
	s_nop 0
	v_pk_mul_f32 v[4:5], v[14:15], v[4:5]
	s_nop 0
	v_cvt_pk_bf16_f32 v11, v4, v5
	ds_write_b64 v9, v[10:11]
	s_waitcnt lgkmcnt(0)
	s_barrier
.LBB0_72:
	ds_read_b128 v[8:11], v0
	v_add_u32_e32 v4, s18, v6
	v_ashrrev_i32_e32 v5, 31, v4
	v_lshlrev_b64 v[12:13], 12, v[4:5]
	v_lshl_add_u64 v[12:13], v[2:3], 0, v[12:13]
	s_waitcnt lgkmcnt(0)
	global_store_dwordx4 v[12:13], v[8:11], off
	ds_read_b128 v[8:11], v0 offset:8192
	v_add_u32_e32 v12, 32, v4
	v_ashrrev_i32_e32 v13, 31, v12
	v_lshlrev_b64 v[12:13], 12, v[12:13]
	v_lshl_add_u64 v[12:13], v[2:3], 0, v[12:13]
	s_waitcnt lgkmcnt(0)
	global_store_dwordx4 v[12:13], v[8:11], off
	ds_read_b128 v[8:11], v0 offset:16384
	v_add_u32_e32 v12, 64, v4
	v_ashrrev_i32_e32 v13, 31, v12
	v_lshlrev_b64 v[12:13], 12, v[12:13]
	v_lshl_add_u64 v[12:13], v[2:3], 0, v[12:13]
	s_waitcnt lgkmcnt(0)
	global_store_dwordx4 v[12:13], v[8:11], off
	ds_read_b128 v[8:11], v0 offset:24576
	v_add_u32_e32 v4, 0x60, v4
	v_ashrrev_i32_e32 v5, 31, v4
	v_lshlrev_b64 v[4:5], 12, v[4:5]
	s_addk_i32 s18, 0x80
	v_lshl_add_u64 v[4:5], v[2:3], 0, v[4:5]
	v_add_u32_e32 v0, 0x8000, v0
	s_cmpk_lg_i32 s18, 0x100
	s_waitcnt lgkmcnt(0)
	global_store_dwordx4 v[4:5], v[8:11], off
	s_cbranch_scc1 .LBB0_72
	v_readlane_b32 s18, v252, 42
	s_add_i32 s46, s46, s64
	s_add_i32 s45, s45, s18
	s_cmpk_gt_i32 s46, 0x5ff
	s_cbranch_scc0 .LBB0_50
	s_movk_i32 s59, 0x200
	s_movk_i32 s62, 0x5800
	s_mov_b32 s28, 0x3a2aaaab
	s_movk_i32 s63, 0x100

; __device__ __forceinline__ float bflo(unsigned w) { return __uint_as_float(w << 16); }
; __device__ __forceinline__ float bfhi(unsigned w) { return __uint_as_float(w & 0xffff0000u); }
; __device__ __forceinline__ void gmlp_item(LAS unsigned char* lds, const bf16_t* Zt  , bf16_t* BRt  , const bf16_t* wsb, const float* bs_, const float* lng, const float* lnb, const int tid) {
;     ...
;     for (int tq = 0; tq < 4; ++tq) {
;         u32x4 w[4][3];
; #pragma unroll
;         for (int u = 0; u < 4; ++u)
; #pragma unroll
;             for (int c = 0; c < 3; ++c) w[u][c] = *(const u32x4*)(Zt + (size_t)(16 * wave + 4 * tq + u) * NZ0 + 1536 + 8 * (lane + 64 * c));
; #pragma unroll
;         for (int u = 0; u < 4; ++u) { float s = 0.f, s2 = 0.f;
; #pragma unroll
;             for (int c = 0; c < 3; ++c) { const float f[8] = {bflo(w[u][c].x), bfhi(w[u][c].x), bflo(w[u][c].y), bfhi(w[u][c].y), bflo(w[u][c].z), bfhi(w[u][c].z), bflo(w[u][c].w), bfhi(w[u][c].w)};
; #pragma unroll
;                 for (int j = 0; j < 8; ++j) { s += f[j]; s2 += f[j] * f[j]; } }
;             s = wave_sum(s); s2 = wave_sum(s2);
;             const float mean = s * (1.f / 1536.f), var = fmaxf(s2 * (1.f / 1536.f) - mean * mean, 0.f);
;             const int tok = 16 * wave + 4 * tq + u;
;             if (lane == 0) { st[2 * tok] = mean; st[2 * tok + 1] = rsqrtf(var + EPS); } } }
.LBB0_81:
	v_lshl_add_u64 v[2:3], v[46:47], 0, s[10:11]
	s_waitcnt lgkmcnt(0)
	v_add_co_u32_e32 v4, vcc, 0x1b100000, v2
	s_nop 1
	v_addc_co_u32_e32 v5, vcc, 0, v3, vcc
	global_load_dwordx4 v[48:51], v[4:5], off offset:3072
	v_add_co_u32_e32 v4, vcc, 0x1b101000, v2
	s_waitcnt vmcnt(0) lgkmcnt(0)
	v_lshlrev_b32_e32 v0, 16, v48
	v_addc_co_u32_e32 v5, vcc, 0, v3, vcc
	global_load_dwordx4 v[42:45], v[4:5], off
	global_load_dwordx4 v[38:41], v[4:5], off offset:1024
	v_add_co_u32_e32 v4, vcc, 0x1b103000, v2
	v_and_b32_e32 v48, 0xffff0000, v48
	s_nop 0
	v_addc_co_u32_e32 v5, vcc, 0, v3, vcc
	global_load_dwordx4 v[34:37], v[4:5], off offset:2048
	global_load_dwordx4 v[30:33], v[4:5], off offset:3072
	v_add_co_u32_e32 v4, vcc, 0x1b104000, v2
	v_add_f32_e32 v55, 0, v0
	s_nop 0
	v_addc_co_u32_e32 v5, vcc, 0, v3, vcc
	global_load_dwordx4 v[26:29], v[4:5], off
	v_add_co_u32_e32 v4, vcc, 0x1b106000, v2
	v_mul_f32_e32 v56, v48, v48
	s_nop 0
	v_addc_co_u32_e32 v5, vcc, 0, v3, vcc
	v_add_co_u32_e32 v2, vcc, 0x1b109000, v2
	global_load_dwordx4 v[22:25], v[4:5], off offset:1024
	global_load_dwordx4 v[18:21], v[4:5], off offset:2048
	global_load_dwordx4 v[14:17], v[4:5], off offset:3072
	v_addc_co_u32_e32 v3, vcc, 0, v3, vcc
	global_load_dwordx4 v[10:13], v[2:3], off
	global_load_dwordx4 v[6:9], v[2:3], off offset:1024
	s_nop 0
	global_load_dwordx4 v[2:5], v[2:3], off offset:2048
	v_lshlrev_b32_e32 v52, 16, v49
	v_add_f32_e32 v55, v55, v48
	v_fmac_f32_e32 v56, v0, v0
	v_and_b32_e32 v49, 0xffff0000, v49
	v_add_f32_e32 v0, v55, v52
	v_fmac_f32_e32 v56, v52, v52
	v_lshlrev_b32_e32 v53, 16, v50
	v_add_f32_e32 v0, v0, v49
	v_fmac_f32_e32 v56, v49, v49
	v_and_b32_e32 v50, 0xffff0000, v50
	v_add_f32_e32 v0, v0, v53
	v_fmac_f32_e32 v56, v53, v53
	v_lshlrev_b32_e32 v54, 16, v51
	v_add_f32_e32 v0, v0, v50
	v_fmac_f32_e32 v56, v50, v50
	v_and_b32_e32 v51, 0xffff0000, v51
	v_add_f32_e32 v0, v0, v54
	v_fmac_f32_e32 v56, v54, v54
	v_add_f32_e32 v0, v0, v51
	v_fmac_f32_e32 v56, v51, v51
	s_waitcnt vmcnt(0) lgkmcnt(0)
	v_lshlrev_b32_e32 v48, 16, v42
	v_and_b32_e32 v42, 0xffff0000, v42
	v_add_f32_e32 v0, v0, v48
	v_fmac_f32_e32 v56, v48, v48
	v_lshlrev_b32_e32 v49, 16, v43
	v_add_f32_e32 v0, v0, v42
	v_fmac_f32_e32 v56, v42, v42
	v_add_f32_e32 v0, v0, v49
	v_fmac_f32_e32 v56, v49, v49
	v_lshlrev_b32_e32 v49, 16, v44
	v_and_b32_e32 v48, 0xffff0000, v43
	v_pk_mul_f32 v[42:43], v[48:49], v[48:49]
	v_add_f32_e32 v0, v0, v48
	v_add_f32_e32 v42, v42, v56
	v_add_f32_e32 v0, v0, v49
	v_add_f32_e32 v50, v43, v42
	v_lshlrev_b32_e32 v43, 16, v45
	v_and_b32_e32 v42, 0xffff0000, v44
	v_add_f32_e32 v0, v0, v42
	v_pk_mul_f32 v[48:49], v[42:43], v[42:43]
	v_add_f32_e32 v0, v0, v43
	v_add_f32_e32 v42, v48, v50
	v_lshlrev_b32_e32 v44, 16, v38
	v_and_b32_e32 v45, 0xffff0000, v45
	v_add_f32_e32 v42, v49, v42
	v_add_f32_e32 v0, v0, v45
	v_pk_mul_f32 v[48:49], v[44:45], v[44:45]
	v_add_f32_e32 v0, v0, v44
	v_add_f32_e32 v42, v49, v42
	v_lshlrev_b32_e32 v45, 16, v39
	v_and_b32_e32 v44, 0xffff0000, v38
	v_add_f32_e32 v42, v48, v42
	v_add_f32_e32 v0, v0, v44
	v_pk_mul_f32 v[48:49], v[44:45], v[44:45]
	v_add_f32_e32 v0, v0, v45
	v_add_f32_e32 v38, v48, v42
	v_lshlrev_b32_e32 v45, 16, v40
	v_and_b32_e32 v44, 0xffff0000, v39
	v_add_f32_e32 v42, v49, v38
	v_pk_mul_f32 v[38:39], v[44:45], v[44:45]
	v_add_f32_e32 v0, v0, v44
	v_add_f32_e32 v38, v38, v42
	v_add_f32_e32 v42, v39, v38
	v_lshlrev_b32_e32 v39, 16, v41
	v_and_b32_e32 v38, 0xffff0000, v40
	v_and_b32_e32 v43, 0xffff0000, v41
	v_add_f32_e32 v0, v0, v45
	v_pk_mul_f32 v[40:41], v[38:39], v[38:39]
	v_add_f32_e32 v0, v0, v38
	v_add_f32_e32 v38, v40, v42
	v_add_f32_e32 v39, v0, v39
	v_add_f32_e32 v42, v41, v38
	v_mul_f32_e32 v38, v43, v43
	v_pk_add_f32 v[38:39], v[38:39], v[42:43]
	ds_bpermute_b32 v41, v126, v39
	ds_bpermute_b32 v40, v126, v38
	s_waitcnt lgkmcnt(0)
	v_pk_add_f32 v[38:39], v[38:39], v[40:41]
	ds_bpermute_b32 v41, v127, v39
	ds_bpermute_b32 v40, v127, v38
	s_waitcnt lgkmcnt(0)
	v_pk_add_f32 v[38:39], v[38:39], v[40:41]
	ds_bpermute_b32 v41, v128, v39
	ds_bpermute_b32 v40, v128, v38
	s_waitcnt lgkmcnt(0)
	v_pk_add_f32 v[38:39], v[38:39], v[40:41]
	ds_bpermute_b32 v41, v129, v39
	ds_bpermute_b32 v40, v129, v38
	s_waitcnt lgkmcnt(0)
	v_pk_add_f32 v[38:39], v[38:39], v[40:41]
	ds_bpermute_b32 v41, v130, v39
	ds_bpermute_b32 v40, v130, v38
	s_waitcnt lgkmcnt(0)
	v_pk_add_f32 v[38:39], v[38:39], v[40:41]
	ds_bpermute_b32 v41, v131, v39
	ds_bpermute_b32 v40, v131, v38
	s_and_saveexec_b64 s[12:13], s[4:5]
	s_cbranch_execz .LBB0_83
	s_waitcnt lgkmcnt(0)
	v_pk_add_f32 v[38:39], v[38:39], v[40:41]
	s_nop 0
	v_pk_mul_f32 v[38:39], v[38:39], s[28:29] op_sel_hi:[1,0]
	s_nop 0
	v_fma_f32 v0, -v39, v39, v38
	v_max_f32_e32 v0, 0, v0
	v_add_f32_e32 v0, 0x358637bd, v0
	v_mul_f32_e32 v38, 0x4b800000, v0
	v_cmp_gt_f32_e32 vcc, s68, v0
	s_nop 1
	v_cndmask_b32_e32 v0, v0, v38, vcc
	v_rsq_f32_e32 v0, v0
	v_mov_b32_e32 v38, v39
	v_mul_f32_e32 v39, 0x45800000, v0
	v_cndmask_b32_e32 v39, v0, v39, vcc
	v_mov_b32_e32 v0, s9
	ds_write_b64 v0, v[38:39]

; #define LAS __attribute__((address_space(3)))
; __device__ __forceinline__ float bflo(unsigned w) { return __uint_as_float(w << 16); }
; __device__ __forceinline__ float bfhi(unsigned w) { return __uint_as_float(w & 0xffff0000u); }
; __device__ __forceinline__ unsigned pk2(float lo, float hi) { const f32x2v v = {lo, hi}; return __builtin_bit_cast(unsigned, __builtin_convertvector(v, bf16x2v)); }
; __device__ __forceinline__ void gmlp_item(LAS unsigned char* lds, const bf16_t* Zt  , bf16_t* BRt  , const bf16_t* wsb, const float* bs_, const float* lng, const float* lnb, const int tid) {
;     ...
;     for (int g = 0; g < 12; ++g) {
;         GM_LOAD(g);
;         { const int ch = tid & 15, t0 = tid >> 4;
;           if (g > 0) {
; #pragma unroll
;               for (int i = 0; i < 4; ++i) { const int t = t0 + 32 * i; const u32x4 ov = *(const LAS u32x4*)(lds + 65536 + off_b(t, ch)); *(u32x4*)(BRt + (size_t)t * DM + (g - 1) * 128 + 8 * ch) = ov; } }
;           const float* gp = lng + g * 128 + 8 * ch; const float* bp = lnb + g * 128 + 8 * ch;
;           const f32x4 g0 = *(const f32x4*)gp, g1 = *(const f32x4*)(gp + 4), b0 = *(const f32x4*)bp, b1 = *(const f32x4*)(bp + 4);
; #pragma unroll
;           for (int i = 0; i < 4; ++i) { const int t = t0 + 32 * i;
;               *(LAS u32x4*)(lds + off_b(t, ch)) = wb[i];
;               const float mean = st[2 * t], rstd = st[2 * t + 1];
;               u32x4 o;
;               o.x = pk2((bflo(vw[i].x) - mean) * rstd * g0[0] + b0[0], (bfhi(vw[i].x) - mean) * rstd * g0[1] + b0[1]);
;               o.y = pk2((bflo(vw[i].y) - mean) * rstd * g0[2] + b0[2], (bfhi(vw[i].y) - mean) * rstd * g0[3] + b0[3]);
;               o.z = pk2((bflo(vw[i].z) - mean) * rstd * g1[0] + b1[0], (bfhi(vw[i].z) - mean) * rstd * g1[1] + b1[1]);
;               o.w = pk2((bflo(vw[i].w) - mean) * rstd * g1[2] + b1[2], (bfhi(vw[i].w) - mean) * rstd * g1[3] + b1[3]);
;               *(LAS u32x4*)(lds + 32768 + off_b(t, ch)) = o;
;               *(LAS u32x4*)(lds + 65536 + off_b(t, ch)) = uu[i]; *(LAS u32x4*)(lds + 98304 + off_b(t, ch)) = gg4[i]; } }
.LBB0_89:
	s_ashr_i32 s9, s8, 31
	s_mul_i32 s11, s8, 0x160000
	s_mul_hi_i32 s10, s8, 0x160000
	s_add_u32 s16, s30, s11
	s_addc_u32 s17, s31, s10
	s_ashr_i32 s10, s14, 5
	s_and_b32 s12, s10, -8
	v_or_b32_e32 v0, s12, v134
	v_bitop3_b32 v124, v0, v135, 4 bitop3:0x36
	v_bitop3_b32 v123, v0, v136, 4 bitop3:0x36
	v_lshl_add_u64 v[2:3], s[16:17], 0, v[84:85]
	v_lshlrev_b32_e32 v0, 1, v74
	v_lshl_add_u64 v[2:3], v[2:3], 0, v[0:1]
	s_movk_i32 s0, 0x1000
	s_waitcnt lgkmcnt(0)
	s_barrier
	global_load_dwordx4 v[162:165], v[82:83], off
	global_load_dwordx4 v[166:169], v[2:3], off offset:3072
	global_load_dwordx4 v[70:73], v[2:3], off
	v_add_co_u32_e32 v2, vcc, s0, v2
	s_bfe_u32 s11, s14, 0x20006
	s_nop 0
	v_addc_co_u32_e32 v3, vcc, 0, v3, vcc
	global_load_dwordx4 v[66:69], v[2:3], off offset:3072
	global_load_dwordx4 v[62:65], v[86:87], off
	v_lshl_add_u64 v[2:3], s[16:17], 0, v[88:89]
	v_lshl_add_u64 v[2:3], v[2:3], 0, v[0:1]
	global_load_dwordx4 v[54:57], v[2:3], off offset:3072
	global_load_dwordx4 v[42:45], v[2:3], off
	v_add_co_u32_e32 v2, vcc, s0, v2
	v_lshl_or_b32 v122, s11, 13, v133
	s_nop 0
	v_addc_co_u32_e32 v3, vcc, 0, v3, vcc
	global_load_dwordx4 v[50:53], v[2:3], off offset:3072
	global_load_dwordx4 v[46:49], v[90:91], off
	v_lshl_add_u64 v[2:3], s[16:17], 0, v[92:93]
	v_lshl_add_u64 v[2:3], v[2:3], 0, v[0:1]
	global_load_dwordx4 v[38:41], v[2:3], off offset:3072
	global_load_dwordx4 v[26:29], v[2:3], off
	v_add_co_u32_e32 v2, vcc, s0, v2
	s_lshl_b32 s13, s11, 5
	s_nop 0
	v_addc_co_u32_e32 v3, vcc, 0, v3, vcc
	global_load_dwordx4 v[34:37], v[2:3], off offset:3072
	global_load_dwordx4 v[30:33], v[94:95], off
	v_lshl_add_u64 v[2:3], s[16:17], 0, v[96:97]
	v_lshl_add_u64 v[6:7], v[2:3], 0, v[0:1]
	global_load_dwordx4 v[10:13], v[6:7], off offset:3072
	global_load_dwordx4 v[2:5], v[6:7], off
	v_add_co_u32_e32 v6, vcc, s0, v6
	v_add_u32_e32 v160, 0, v142
	s_nop 0
	v_addc_co_u32_e32 v7, vcc, 0, v7, vcc
	global_load_dwordx4 v[6:9], v[6:7], off offset:3072
	s_nop 0
	global_load_dwordx4 v[14:17], v[80:81], off offset:16
	global_load_dwordx4 v[22:25], v[80:81], off
	global_load_dwordx4 v[18:21], v[78:79], off offset:16
	global_load_dwordx4 v[58:61], v[78:79], off
	s_add_i32 s11, 0, 0x20000
	v_add_u32_e32 v161, s11, v143
	v_add_u32_e32 v172, 0, v148
	v_add_u32_e32 v173, s11, v149
	v_bitop3_b32 v185, v134, v135, s12 bitop3:0x36
	v_bitop3_b32 v125, v134, v136, s12 bitop3:0x36
	v_add_u32_e32 v181, s91, v148
	v_add_u32_e32 v179, s71, v148
	v_add_u32_e32 v184, v150, v122
	v_add_u32_e32 v189, v151, v122
	v_add_u32_e32 v190, v152, v122
	v_add_u32_e32 v191, v153, v122
	v_add_u32_e32 v192, v154, v122
	v_add_u32_e32 v193, v155, v122
	v_add_u32_e32 v194, v156, v122
	v_add_u32_e32 v195, v157, v122
	s_or_b32 s14, s12, 1
	s_or_b32 s15, s12, 2
	s_or_b32 s16, s12, 3
	s_or_b32 s17, s12, 4
	s_or_b32 s18, s12, 5
	s_or_b32 s19, s12, 6
	s_or_b32 s26, s10, 7
	s_mov_b64 s[0:1], 0x8000
	s_or_b32 s27, s13, 0x80
	s_waitcnt vmcnt(0) lgkmcnt(0)
	ds_write_b128 v160, v[162:165]
	ds_read_b64 v[170:171], v161
	v_lshlrev_b32_e32 v162, 16, v166
	v_and_b32_e32 v163, 0xffff0000, v166
	v_lshlrev_b32_e32 v164, 16, v167
	v_and_b32_e32 v165, 0xffff0000, v167
	s_waitcnt lgkmcnt(0)
	v_pk_add_f32 v[162:163], v[162:163], v[170:171] op_sel_hi:[1,0] neg_lo:[0,1] neg_hi:[0,1]
	v_pk_add_f32 v[164:165], v[164:165], v[170:171] op_sel_hi:[1,0] neg_lo:[0,1] neg_hi:[0,1]
	v_pk_mul_f32 v[162:163], v[170:171], v[162:163] op_sel:[1,0]
	v_pk_mul_f32 v[164:165], v[170:171], v[164:165] op_sel:[1,0]
	v_lshlrev_b32_e32 v166, 16, v169
	v_and_b32_e32 v167, 0xffff0000, v169
	v_pk_add_f32 v[166:167], v[166:167], v[170:171] op_sel_hi:[1,0] neg_lo:[0,1] neg_hi:[0,1]
	v_add_u32_e32 v169, s11, v147
	v_pk_mul_f32 v[166:167], v[170:171], v[166:167] op_sel:[1,0]
	v_pk_fma_f32 v[162:163], v[58:59], v[162:163], v[22:23]
	v_pk_fma_f32 v[164:165], v[60:61], v[164:165], v[24:25]
	v_cvt_pk_bf16_f32 v162, v162, v163
	v_cvt_pk_bf16_f32 v163, v164, v165
	v_lshlrev_b32_e32 v164, 16, v168
	v_and_b32_e32 v165, 0xffff0000, v168
	v_pk_add_f32 v[164:165], v[164:165], v[170:171] op_sel_hi:[1,0] neg_lo:[0,1] neg_hi:[0,1]
	v_pk_fma_f32 v[166:167], v[20:21], v[166:167], v[16:17]
	v_pk_mul_f32 v[164:165], v[170:171], v[164:165] op_sel:[1,0]
	v_add_u32_e32 v168, 0, v146
	v_pk_fma_f32 v[164:165], v[18:19], v[164:165], v[14:15]
	v_add_u32_e32 v170, s71, v146
	v_cvt_pk_bf16_f32 v164, v164, v165
	v_cvt_pk_bf16_f32 v165, v166, v167
	ds_write_b128 v160, v[162:165] offset:32768
	v_add_u32_e32 v162, s71, v142
	v_add_u32_e32 v163, s91, v142
	v_add_u32_e32 v164, 0, v144
	ds_write_b128 v162, v[70:73]
	ds_write_b128 v163, v[66:69]
	ds_write_b128 v164, v[62:65]
	v_add_u32_e32 v165, s11, v145
	ds_read_b64 v[62:63], v165
	v_lshlrev_b32_e32 v64, 16, v54
	v_and_b32_e32 v65, 0xffff0000, v54
	v_add_u32_e32 v166, s71, v144
	v_add_u32_e32 v167, s91, v144
	s_waitcnt lgkmcnt(0)
; #define LAS __attribute__((address_space(3)))
; __device__ __forceinline__ float bflo(unsigned w) { return __uint_as_float(w << 16); }
; __device__ __forceinline__ float bfhi(unsigned w) { return __uint_as_float(w & 0xffff0000u); }
; __device__ __forceinline__ unsigned pk2(float lo, float hi) { const f32x2v v = {lo, hi}; return __builtin_bit_cast(unsigned, __builtin_convertvector(v, bf16x2v)); }
; __device__ __forceinline__ void gmlp_item(LAS unsigned char* lds, const bf16_t* Zt  , bf16_t* BRt  , const bf16_t* wsb, const float* bs_, const float* lng, const float* lnb, const int tid) {
;     ...
;           const float* gp = lng + g * 128 + 8 * ch; const float* bp = lnb + g * 128 + 8 * ch;
;           const f32x4 g0 = *(const f32x4*)gp, g1 = *(const f32x4*)(gp + 4), b0 = *(const f32x4*)bp, b1 = *(const f32x4*)(bp + 4);
; #pragma unroll
;           for (int i = 0; i < 4; ++i) { const int t = t0 + 32 * i;
;               *(LAS u32x4*)(lds + off_b(t, ch)) = wb[i];
;               const float mean = st[2 * t], rstd = st[2 * t + 1];
;               u32x4 o;
;               o.x = pk2((bflo(vw[i].x) - mean) * rstd * g0[0] + b0[0], (bfhi(vw[i].x) - mean) * rstd * g0[1] + b0[1]);
;               o.y = pk2((bflo(vw[i].y) - mean) * rstd * g0[2] + b0[2], (bfhi(vw[i].y) - mean) * rstd * g0[3] + b0[3]);
;               o.z = pk2((bflo(vw[i].z) - mean) * rstd * g1[0] + b1[0], (bfhi(vw[i].z) - mean) * rstd * g1[1] + b1[1]);
;               o.w = pk2((bflo(vw[i].w) - mean) * rstd * g1[2] + b1[2], (bfhi(vw[i].w) - mean) * rstd * g1[3] + b1[3]);
;               *(LAS u32x4*)(lds + 32768 + off_b(t, ch)) = o;
;               *(LAS u32x4*)(lds + 65536 + off_b(t, ch)) = uu[i]; *(LAS u32x4*)(lds + 98304 + off_b(t, ch)) = gg4[i]; } }
;         __syncthreads();
	v_pk_add_f32 v[64:65], v[64:65], v[62:63] op_sel_hi:[1,0] neg_lo:[0,1] neg_hi:[0,1]
	ds_write_b128 v166, v[42:45]
	v_pk_mul_f32 v[64:65], v[62:63], v[64:65] op_sel:[1,0]
	ds_write_b128 v167, v[50:53]
	v_pk_fma_f32 v[64:65], v[58:59], v[64:65], v[22:23]
	v_lshlrev_b32_e32 v44, 16, v38
	v_cvt_pk_bf16_f32 v54, v64, v65
	v_lshlrev_b32_e32 v64, 16, v55
	v_and_b32_e32 v65, 0xffff0000, v55
	v_pk_add_f32 v[64:65], v[64:65], v[62:63] op_sel_hi:[1,0] neg_lo:[0,1] neg_hi:[0,1]
	v_and_b32_e32 v45, 0xffff0000, v38
	v_pk_mul_f32 v[64:65], v[62:63], v[64:65] op_sel:[1,0]
	v_add_u32_e32 v171, s91, v146
	v_pk_fma_f32 v[64:65], v[60:61], v[64:65], v[24:25]
	s_mov_b64 s[10:11], 0
	v_cvt_pk_bf16_f32 v55, v64, v65
	v_lshlrev_b32_e32 v64, 16, v56
	v_and_b32_e32 v65, 0xffff0000, v56
	v_pk_add_f32 v[64:65], v[64:65], v[62:63] op_sel_hi:[1,0] neg_lo:[0,1] neg_hi:[0,1]
	v_mov_b64_e32 v[66:67], v[120:121]
	v_pk_mul_f32 v[64:65], v[62:63], v[64:65] op_sel:[1,0]
	v_mov_b64_e32 v[68:69], v[118:119]
	v_pk_fma_f32 v[64:65], v[18:19], v[64:65], v[14:15]
	v_mov_b64_e32 v[70:71], v[116:117]
	v_cvt_pk_bf16_f32 v56, v64, v65
	v_lshlrev_b32_e32 v64, 16, v57
	v_and_b32_e32 v65, 0xffff0000, v57
	v_pk_add_f32 v[64:65], v[64:65], v[62:63] op_sel_hi:[1,0] neg_lo:[0,1] neg_hi:[0,1]
	v_mov_b64_e32 v[72:73], v[112:113]
	v_pk_mul_f32 v[62:63], v[62:63], v[64:65] op_sel:[1,0]
	s_nop 0
	v_pk_fma_f32 v[62:63], v[20:21], v[62:63], v[16:17]
	s_nop 0
	v_cvt_pk_bf16_f32 v57, v62, v63
	ds_write_b128 v164, v[54:57] offset:32768
	ds_write_b128 v168, v[46:49]
	ds_read_b64 v[42:43], v169
	ds_write_b128 v170, v[26:29]
	ds_write_b128 v171, v[34:37]
	v_lshlrev_b32_e32 v28, 16, v10
	v_and_b32_e32 v29, 0xffff0000, v10
	s_waitcnt lgkmcnt(2)
	v_pk_add_f32 v[44:45], v[44:45], v[42:43] op_sel_hi:[1,0] neg_lo:[0,1] neg_hi:[0,1]
	s_nop 0
	v_pk_mul_f32 v[44:45], v[42:43], v[44:45] op_sel:[1,0]
	s_nop 0
	v_pk_fma_f32 v[44:45], v[58:59], v[44:45], v[22:23]
	s_nop 0
	v_cvt_pk_bf16_f32 v38, v44, v45
	v_lshlrev_b32_e32 v44, 16, v39
	v_and_b32_e32 v45, 0xffff0000, v39
	v_pk_add_f32 v[44:45], v[44:45], v[42:43] op_sel_hi:[1,0] neg_lo:[0,1] neg_hi:[0,1]
	s_nop 0
	v_pk_mul_f32 v[44:45], v[42:43], v[44:45] op_sel:[1,0]
	s_nop 0
	v_pk_fma_f32 v[44:45], v[60:61], v[44:45], v[24:25]
	s_nop 0
	v_cvt_pk_bf16_f32 v39, v44, v45
	v_lshlrev_b32_e32 v44, 16, v40
	v_and_b32_e32 v45, 0xffff0000, v40
	v_pk_add_f32 v[44:45], v[44:45], v[42:43] op_sel_hi:[1,0] neg_lo:[0,1] neg_hi:[0,1]
	s_nop 0
	v_pk_mul_f32 v[44:45], v[42:43], v[44:45] op_sel:[1,0]
	s_nop 0
	v_pk_fma_f32 v[44:45], v[18:19], v[44:45], v[14:15]
	s_nop 0
	v_cvt_pk_bf16_f32 v40, v44, v45
	v_lshlrev_b32_e32 v44, 16, v41
	v_and_b32_e32 v45, 0xffff0000, v41
	v_pk_add_f32 v[44:45], v[44:45], v[42:43] op_sel_hi:[1,0] neg_lo:[0,1] neg_hi:[0,1]
	s_nop 0
	v_pk_mul_f32 v[42:43], v[42:43], v[44:45] op_sel:[1,0]
	s_nop 0
	v_pk_fma_f32 v[42:43], v[20:21], v[42:43], v[16:17]
	s_nop 0
	v_cvt_pk_bf16_f32 v41, v42, v43
	ds_write_b128 v168, v[38:41] offset:32768
	ds_write_b128 v172, v[30:33]
	ds_read_b64 v[26:27], v173
	ds_write_b128 v181, v[6:9]
	v_lshl_add_u32 v6, v185, 4, v158
	v_lshl_add_u32 v8, v125, 4, v159
	v_add_u32_e32 v185, 0, v6
	s_waitcnt lgkmcnt(1)
	v_pk_add_f32 v[28:29], v[28:29], v[26:27] op_sel_hi:[1,0] neg_lo:[0,1] neg_hi:[0,1]
	v_add_u32_e32 v186, 0, v8
	v_pk_mul_f32 v[28:29], v[26:27], v[28:29] op_sel:[1,0]
	ds_write_b128 v179, v[2:5]
	v_pk_fma_f32 v[22:23], v[58:59], v[28:29], v[22:23]
	s_nop 0
	v_cvt_pk_bf16_f32 v10, v22, v23
	v_lshlrev_b32_e32 v22, 16, v11
	v_and_b32_e32 v23, 0xffff0000, v11
	v_pk_add_f32 v[22:23], v[22:23], v[26:27] op_sel_hi:[1,0] neg_lo:[0,1] neg_hi:[0,1]
	s_nop 0
	v_pk_mul_f32 v[22:23], v[26:27], v[22:23] op_sel:[1,0]
	s_nop 0
	v_pk_fma_f32 v[22:23], v[60:61], v[22:23], v[24:25]
	s_nop 0
	v_cvt_pk_bf16_f32 v11, v22, v23
	v_lshlrev_b32_e32 v22, 16, v12
	v_and_b32_e32 v23, 0xffff0000, v12
	v_pk_add_f32 v[22:23], v[22:23], v[26:27] op_sel_hi:[1,0] neg_lo:[0,1] neg_hi:[0,1]
	s_nop 0
	v_pk_mul_f32 v[22:23], v[26:27], v[22:23] op_sel:[1,0]
	s_nop 0
	v_pk_fma_f32 v[14:15], v[18:19], v[22:23], v[14:15]
	s_nop 0
	v_cvt_pk_bf16_f32 v12, v14, v15
	v_lshlrev_b32_e32 v14, 16, v13
	v_and_b32_e32 v15, 0xffff0000, v13
	v_pk_add_f32 v[14:15], v[14:15], v[26:27] op_sel_hi:[1,0] neg_lo:[0,1] neg_hi:[0,1]
	s_nop 0
	v_pk_mul_f32 v[14:15], v[26:27], v[14:15] op_sel:[1,0]
	s_nop 0
	v_pk_fma_f32 v[14:15], v[20:21], v[14:15], v[16:17]
	s_nop 0
	v_cvt_pk_bf16_f32 v13, v14, v15
	ds_write_b128 v172, v[10:13] offset:32768
	s_waitcnt lgkmcnt(0)
	s_barrier
; #define LAS __attribute__((address_space(3)))
; #define MFMA32(a, b, c) __builtin_amdgcn_mfma_f32_32x32x16_bf16((a), (b), (c), 0, 0, 0)
; __device__ __forceinline__ float bflo(unsigned w) { return __uint_as_float(w << 16); }
; __device__ __forceinline__ float bfhi(unsigned w) { return __uint_as_float(w & 0xffff0000u); }
; __device__ __forceinline__ unsigned pk2(float lo, float hi) { const f32x2v v = {lo, hi}; return __builtin_bit_cast(unsigned, __builtin_convertvector(v, bf16x2v)); }
; __device__ __forceinline__ float silu_f(float g) { return g * fast_rcp(1.f + fast_exp2(-g * LOG2E)); }
; __device__ __forceinline__ void gmlp_item(LAS unsigned char* lds, const bf16_t* Zt  , bf16_t* BRt  , const bf16_t* wsb, const float* bs_, const float* lng, const float* lnb, const int tid) {
;     ...
;         f32x16 acc[2];
; #pragma unroll
;         for (int i = 0; i < 16; ++i) { acc[0][i] = 0.f; acc[1][i] = 0.f; }
; #pragma unroll
;         for (int ks = 0; ks < 8; ++ks) {
;             const bf16x8 af = *(LAS bf16x8*)(lds + aaddr[ks]);
; #pragma unroll
;             for (int cc = 0; cc < 2; ++cc) {
;                 const s16x4 lo = __builtin_amdgcn_ds_read_tr16_b64_v4i16((LAS s16x4*)(lds + baddr[cc][0] + ks * 4096));
;                 const s16x4 hi = __builtin_amdgcn_ds_read_tr16_b64_v4i16((LAS s16x4*)(lds + baddr[cc][1] + ks * 4096));
;                 const bf16x8 bfv = __builtin_shufflevector(lo, hi, 0, 1, 2, 3, 4, 5, 6, 7);
;                 acc[cc] = MFMA32(bfv, af, acc[cc]); }
;         }
;         int r2 = r, h2 = h; asm volatile("" : "+v"(r2), "+v"(h2));
;         { const int t = 32 * tt + r2; const float bsv = bs_[g * 128 + t];
; #pragma unroll
;           for (int k8 = 0; k8 < 8; ++k8) { const int cc = k8 >> 2, q4 = k8 & 3;
;               const unsigned ad = off_b(t, 4 * (2 * cp + cc) + q4) + 8u * h2;
;               const u32x2 uw = *(const LAS u32x2*)(lds + 65536 + ad), gw = *(const LAS u32x2*)(lds + 98304 + ad);
;               const float v0 = bflo(uw.x) * (acc[cc][4 * q4 + 0] + bsv) * silu_f(bflo(gw.x)), v1 = bfhi(uw.x) * (acc[cc][4 * q4 + 1] + bsv) * silu_f(bfhi(gw.x));
;               const float v2 = bflo(uw.y) * (acc[cc][4 * q4 + 2] + bsv) * silu_f(bflo(gw.y)), v3 = bfhi(uw.y) * (acc[cc][4 * q4 + 3] + bsv) * silu_f(bfhi(gw.y));
;               u32x2 w; w.x = pk2(v0, v1); w.y = pk2(v2, v3);
	ds_read_b128 v[2:5], v184
	ds_read_b64_tr_b16 v[6:7], v185 offset:32768
	ds_read_b64_tr_b16 v[8:9], v186 offset:32768
	s_waitcnt lgkmcnt(0)
	v_mfma_f32_32x32x16_bf16 v[18:33], v[6:9], v[2:5], 0
	v_lshl_add_u32 v6, v124, 4, v158
	v_lshl_add_u32 v8, v123, 4, v159
	v_add_u32_e32 v187, 0, v6
	v_add_u32_e32 v188, 0, v8
	ds_read_b64_tr_b16 v[6:7], v187 offset:32768
	ds_read_b64_tr_b16 v[8:9], v188 offset:32768
	ds_read_b128 v[34:37], v189
	ds_read_b64_tr_b16 v[38:39], v185 offset:36864
	ds_read_b64_tr_b16 v[40:41], v186 offset:36864
	s_waitcnt lgkmcnt(3)
	v_mfma_f32_32x32x16_bf16 v[2:17], v[6:9], v[2:5], 0
	v_mov_b64_e32 v[122:123], v[110:111]
	v_mov_b64_e32 v[124:125], v[108:109]
	s_waitcnt lgkmcnt(0)
	v_mfma_f32_32x32x16_bf16 v[18:33], v[38:41], v[34:37], v[18:33]
	ds_read_b64_tr_b16 v[38:39], v187 offset:36864
	ds_read_b64_tr_b16 v[40:41], v188 offset:36864
	s_waitcnt lgkmcnt(0)
	v_mfma_f32_32x32x16_bf16 v[2:17], v[38:41], v[34:37], v[2:17]
	ds_read_b128 v[34:37], v190
	ds_read_b64_tr_b16 v[38:39], v185 offset:40960
	ds_read_b64_tr_b16 v[40:41], v186 offset:40960
	s_waitcnt lgkmcnt(0)
	v_mfma_f32_32x32x16_bf16 v[18:33], v[38:41], v[34:37], v[18:33]
	ds_read_b64_tr_b16 v[38:39], v187 offset:40960
	ds_read_b64_tr_b16 v[40:41], v188 offset:40960
	s_waitcnt lgkmcnt(0)
	v_mfma_f32_32x32x16_bf16 v[2:17], v[38:41], v[34:37], v[2:17]
	ds_read_b128 v[34:37], v191
	ds_read_b64_tr_b16 v[38:39], v185 offset:45056
	ds_read_b64_tr_b16 v[40:41], v186 offset:45056
	s_waitcnt lgkmcnt(0)
	v_mfma_f32_32x32x16_bf16 v[18:33], v[38:41], v[34:37], v[18:33]
	ds_read_b64_tr_b16 v[38:39], v187 offset:45056
	ds_read_b64_tr_b16 v[40:41], v188 offset:45056
	s_waitcnt lgkmcnt(0)
	v_mfma_f32_32x32x16_bf16 v[2:17], v[38:41], v[34:37], v[2:17]
	ds_read_b128 v[34:37], v192
	ds_read_b64_tr_b16 v[38:39], v185 offset:49152
	ds_read_b64_tr_b16 v[40:41], v186 offset:49152
	s_waitcnt lgkmcnt(0)
	v_mfma_f32_32x32x16_bf16 v[18:33], v[38:41], v[34:37], v[18:33]
	ds_read_b64_tr_b16 v[38:39], v187 offset:49152
	ds_read_b64_tr_b16 v[40:41], v188 offset:49152
	s_waitcnt lgkmcnt(0)
	v_mfma_f32_32x32x16_bf16 v[2:17], v[38:41], v[34:37], v[2:17]
	ds_read_b128 v[34:37], v193
	ds_read_b64_tr_b16 v[38:39], v185 offset:53248
	ds_read_b64_tr_b16 v[40:41], v186 offset:53248
	s_waitcnt lgkmcnt(0)
	v_mfma_f32_32x32x16_bf16 v[18:33], v[38:41], v[34:37], v[18:33]
	ds_read_b64_tr_b16 v[38:39], v187 offset:53248
	ds_read_b64_tr_b16 v[40:41], v188 offset:53248
	s_waitcnt lgkmcnt(0)
	v_mfma_f32_32x32x16_bf16 v[2:17], v[38:41], v[34:37], v[2:17]
	ds_read_b128 v[34:37], v194
	ds_read_b64_tr_b16 v[38:39], v185 offset:57344
	ds_read_b64_tr_b16 v[40:41], v186 offset:57344
	s_waitcnt lgkmcnt(0)
	v_mfma_f32_32x32x16_bf16 v[18:33], v[38:41], v[34:37], v[18:33]
	ds_read_b64_tr_b16 v[38:39], v187 offset:57344
	ds_read_b64_tr_b16 v[40:41], v188 offset:57344
	s_waitcnt lgkmcnt(0)
	v_mfma_f32_32x32x16_bf16 v[2:17], v[38:41], v[34:37], v[2:17]
	ds_read_b128 v[34:37], v195
	ds_read_b64_tr_b16 v[38:39], v185 offset:61440
	ds_read_b64_tr_b16 v[40:41], v186 offset:61440
	s_waitcnt lgkmcnt(0)
	v_mfma_f32_32x32x16_bf16 v[18:33], v[38:41], v[34:37], v[18:33]
	ds_read_b64_tr_b16 v[38:39], v187 offset:61440
	ds_read_b64_tr_b16 v[40:41], v188 offset:61440
	s_waitcnt lgkmcnt(0)
	v_mfma_f32_32x32x16_bf16 v[2:17], v[38:41], v[34:37], v[2:17]
	v_mov_b32_e32 v37, v132
	v_mov_b32_e32 v36, v75
	s_nop 0
	v_add_u32_e32 v38, s13, v36
	v_ashrrev_i32_e32 v39, 31, v38
	v_lshl_add_u64 v[34:35], v[38:39], 2, s[6:7]
	global_load_dword v34, v[34:35], off
	v_lshlrev_b32_e32 v35, 2, v36
	v_and_b32_e32 v35, 12, v35
	v_bfe_u32 v36, v36, 2, 2
	v_lshlrev_b32_e32 v37, 3, v37
	v_lshl_add_u32 v37, v38, 8, v37
	v_bitop3_b32 v38, v35, s12, v36 bitop3:0x36
	v_lshl_add_u32 v40, v38, 4, v37
	v_add_u32_e32 v48, s71, v40
	v_add_u32_e32 v40, s91, v40
	ds_read_b64 v[38:39], v48
	ds_read_b64 v[40:41], v40
	s_waitcnt lgkmcnt(1)
	v_lshlrev_b32_e32 v46, 16, v38
	s_waitcnt lgkmcnt(0)
	v_lshlrev_b32_e32 v42, 16, v40
	v_and_b32_e32 v43, 0xffff0000, v40
	v_mul_f32_e32 v40, 0xbfb8aa3b, v42
	v_and_b32_e32 v47, 0xffff0000, v38
	v_mul_f32_e32 v38, 0xbfb8aa3b, v43
	v_exp_f32_e32 v40, v40
	v_exp_f32_e32 v38, v38
	v_add_f32_e32 v40, 1.0, v40
	v_add_f32_e32 v38, 1.0, v38
	v_rcp_f32_e32 v44, v40
	v_rcp_f32_e32 v45, v38
	v_lshlrev_b32_e32 v40, 16, v41
	v_and_b32_e32 v41, 0xffff0000, v41
	v_mul_f32_e32 v38, 0xbfb8aa3b, v40
	v_pk_mul_f32 v[42:43], v[44:45], v[42:43]
	v_exp_f32_e32 v38, v38
	s_waitcnt vmcnt(0)
	v_pk_add_f32 v[18:19], v[18:19], v[34:35] op_sel_hi:[1,0]
	s_nop 0
	v_pk_mul_f32 v[18:19], v[18:19], v[46:47]
	v_add_f32_e32 v38, 1.0, v38
	v_pk_mul_f32 v[18:19], v[18:19], v[42:43]
	v_lshlrev_b32_e32 v42, 16, v39
	v_and_b32_e32 v43, 0xffff0000, v39
	v_mul_f32_e32 v39, 0xbfb8aa3b, v41
	v_exp_f32_e32 v39, v39
	v_rcp_f32_e32 v38, v38
	v_pk_add_f32 v[20:21], v[20:21], v[34:35] op_sel_hi:[1,0]
	v_cvt_pk_bf16_f32 v18, v18, v19
	v_add_f32_e32 v39, 1.0, v39
	v_rcp_f32_e32 v39, v39
	v_pk_mul_f32 v[20:21], v[20:21], v[42:43]
	v_pk_add_f32 v[22:23], v[22:23], v[34:35] op_sel_hi:[1,0]
	v_pk_add_f32 v[24:25], v[24:25], v[34:35] op_sel_hi:[1,0]
	v_pk_mul_f32 v[38:39], v[38:39], v[40:41]
	v_pk_add_f32 v[26:27], v[26:27], v[34:35] op_sel_hi:[1,0]
	v_pk_mul_f32 v[20:21], v[20:21], v[38:39]
	v_pk_add_f32 v[2:3], v[2:3], v[34:35] op_sel_hi:[1,0]
	v_cvt_pk_bf16_f32 v19, v20, v21
	ds_write_b64 v48, v[18:19]
	v_bitop3_b32 v18, v35, s14, v36 bitop3:0x36
	v_lshl_add_u32 v20, v18, 4, v37
	v_add_u32_e32 v44, s71, v20
	v_add_u32_e32 v20, s91, v20
	ds_read_b64 v[18:19], v44
	ds_read_b64 v[20:21], v20
	v_pk_add_f32 v[4:5], v[4:5], v[34:35] op_sel_hi:[1,0]
	v_pk_add_f32 v[6:7], v[6:7], v[34:35] op_sel_hi:[1,0]
	v_pk_add_f32 v[8:9], v[8:9], v[34:35] op_sel_hi:[1,0]
	s_waitcnt lgkmcnt(1)
; #define LAS __attribute__((address_space(3)))
; __device__ __forceinline__ float bflo(unsigned w) { return __uint_as_float(w << 16); }
; __device__ __forceinline__ float bfhi(unsigned w) { return __uint_as_float(w & 0xffff0000u); }
; __device__ __forceinline__ unsigned pk2(float lo, float hi) { const f32x2v v = {lo, hi}; return __builtin_bit_cast(unsigned, __builtin_convertvector(v, bf16x2v)); }
; __device__ __forceinline__ float silu_f(float g) { return g * fast_rcp(1.f + fast_exp2(-g * LOG2E)); }
; __device__ __forceinline__ void gmlp_item(LAS unsigned char* lds, const bf16_t* Zt  , bf16_t* BRt  , const bf16_t* wsb, const float* bs_, const float* lng, const float* lnb, const int tid) {
;     ...
;         int r2 = r, h2 = h; asm volatile("" : "+v"(r2), "+v"(h2));
;         { const int t = 32 * tt + r2; const float bsv = bs_[g * 128 + t];
; #pragma unroll
;           for (int k8 = 0; k8 < 8; ++k8) { const int cc = k8 >> 2, q4 = k8 & 3;
;               const unsigned ad = off_b(t, 4 * (2 * cp + cc) + q4) + 8u * h2;
;               const u32x2 uw = *(const LAS u32x2*)(lds + 65536 + ad), gw = *(const LAS u32x2*)(lds + 98304 + ad);
;               const float v0 = bflo(uw.x) * (acc[cc][4 * q4 + 0] + bsv) * silu_f(bflo(gw.x)), v1 = bfhi(uw.x) * (acc[cc][4 * q4 + 1] + bsv) * silu_f(bfhi(gw.x));
;               const float v2 = bflo(uw.y) * (acc[cc][4 * q4 + 2] + bsv) * silu_f(bflo(gw.y)), v3 = bfhi(uw.y) * (acc[cc][4 * q4 + 3] + bsv) * silu_f(bfhi(gw.y));
;               u32x2 w; w.x = pk2(v0, v1); w.y = pk2(v2, v3);
;               *(LAS u32x2*)(lds + 65536 + ad) = w; } }
	v_lshlrev_b32_e32 v42, 16, v18
	s_waitcnt lgkmcnt(0)
	v_lshlrev_b32_e32 v38, 16, v20
	v_and_b32_e32 v39, 0xffff0000, v20
	v_mul_f32_e32 v20, 0xbfb8aa3b, v38
	v_and_b32_e32 v43, 0xffff0000, v18
	v_mul_f32_e32 v18, 0xbfb8aa3b, v39
	v_exp_f32_e32 v20, v20
	v_exp_f32_e32 v18, v18
	v_pk_mul_f32 v[22:23], v[22:23], v[42:43]
	v_pk_add_f32 v[10:11], v[10:11], v[34:35] op_sel_hi:[1,0]
	v_add_f32_e32 v20, 1.0, v20
	v_add_f32_e32 v18, 1.0, v18
	v_rcp_f32_e32 v40, v20
	v_rcp_f32_e32 v41, v18
	v_lshlrev_b32_e32 v20, 16, v21
	v_and_b32_e32 v21, 0xffff0000, v21
	v_mul_f32_e32 v18, 0xbfb8aa3b, v20
	v_pk_mul_f32 v[38:39], v[40:41], v[38:39]
	v_exp_f32_e32 v18, v18
	v_pk_mul_f32 v[22:23], v[22:23], v[38:39]
	v_lshlrev_b32_e32 v38, 16, v19
	v_and_b32_e32 v39, 0xffff0000, v19
	v_mul_f32_e32 v19, 0xbfb8aa3b, v21
	v_exp_f32_e32 v19, v19
	v_add_f32_e32 v18, 1.0, v18
	v_rcp_f32_e32 v18, v18
	v_pk_mul_f32 v[24:25], v[24:25], v[38:39]
	v_add_f32_e32 v19, 1.0, v19
	v_rcp_f32_e32 v19, v19
	s_nop 0
	v_pk_mul_f32 v[18:19], v[18:19], v[20:21]
	s_nop 0
	v_pk_mul_f32 v[18:19], v[24:25], v[18:19]
	v_cvt_pk_bf16_f32 v20, v22, v23
	v_cvt_pk_bf16_f32 v21, v18, v19
	v_bitop3_b32 v18, v35, s15, v36 bitop3:0x36
	ds_write_b64 v44, v[20:21]
	v_lshl_add_u32 v20, v18, 4, v37
	v_add_u32_e32 v40, s71, v20
	v_add_u32_e32 v20, s91, v20
	ds_read_b64 v[18:19], v40
	ds_read_b64 v[20:21], v20
	s_waitcnt lgkmcnt(1)
	v_lshlrev_b32_e32 v38, 16, v18
	s_waitcnt lgkmcnt(0)
	v_lshlrev_b32_e32 v22, 16, v20
	v_and_b32_e32 v23, 0xffff0000, v20
	v_mul_f32_e32 v20, 0xbfb8aa3b, v22
	v_and_b32_e32 v39, 0xffff0000, v18
	v_mul_f32_e32 v18, 0xbfb8aa3b, v23
	v_exp_f32_e32 v20, v20
	v_exp_f32_e32 v18, v18
	v_pk_mul_f32 v[26:27], v[26:27], v[38:39]
	v_add_f32_e32 v20, 1.0, v20
	v_add_f32_e32 v18, 1.0, v18
	v_rcp_f32_e32 v24, v20
	v_rcp_f32_e32 v25, v18
	v_lshlrev_b32_e32 v20, 16, v21
	v_and_b32_e32 v21, 0xffff0000, v21
	v_mul_f32_e32 v18, 0xbfb8aa3b, v20
	v_pk_mul_f32 v[22:23], v[24:25], v[22:23]
	v_lshlrev_b32_e32 v24, 16, v19
	v_and_b32_e32 v25, 0xffff0000, v19
	v_mul_f32_e32 v19, 0xbfb8aa3b, v21
	v_exp_f32_e32 v18, v18
	v_exp_f32_e32 v19, v19
	v_pk_mul_f32 v[22:23], v[26:27], v[22:23]
	v_pk_add_f32 v[26:27], v[28:29], v[34:35] op_sel_hi:[1,0]
	v_add_f32_e32 v18, 1.0, v18
	v_add_f32_e32 v19, 1.0, v19
	v_rcp_f32_e32 v18, v18
	v_rcp_f32_e32 v19, v19
	v_pk_mul_f32 v[24:25], v[26:27], v[24:25]
	v_pk_add_f32 v[28:29], v[30:31], v[34:35] op_sel_hi:[1,0]
	v_pk_mul_f32 v[18:19], v[18:19], v[20:21]
	s_nop 0
	v_pk_mul_f32 v[18:19], v[24:25], v[18:19]
	v_cvt_pk_bf16_f32 v20, v22, v23
	v_cvt_pk_bf16_f32 v21, v18, v19
	v_bitop3_b32 v18, v35, s16, v36 bitop3:0x36
	ds_write_b64 v40, v[20:21]
	v_lshl_add_u32 v20, v18, 4, v37
	v_add_u32_e32 v38, s71, v20
	v_add_u32_e32 v20, s91, v20
	ds_read_b64 v[18:19], v38
	ds_read_b64 v[20:21], v20
	s_waitcnt lgkmcnt(1)
	v_lshlrev_b32_e32 v26, 16, v18
	s_waitcnt lgkmcnt(0)
	v_lshlrev_b32_e32 v22, 16, v20
	v_and_b32_e32 v23, 0xffff0000, v20
	v_mul_f32_e32 v20, 0xbfb8aa3b, v22
	v_and_b32_e32 v27, 0xffff0000, v18
	v_mul_f32_e32 v18, 0xbfb8aa3b, v23
	v_exp_f32_e32 v20, v20
	v_exp_f32_e32 v18, v18
	v_pk_mul_f32 v[26:27], v[28:29], v[26:27]
	v_add_f32_e32 v20, 1.0, v20
	v_add_f32_e32 v18, 1.0, v18
	v_rcp_f32_e32 v24, v20
	v_rcp_f32_e32 v25, v18
	v_lshlrev_b32_e32 v20, 16, v21
	v_and_b32_e32 v21, 0xffff0000, v21
	v_mul_f32_e32 v18, 0xbfb8aa3b, v20
	v_pk_mul_f32 v[22:23], v[24:25], v[22:23]
	v_lshlrev_b32_e32 v24, 16, v19
	v_and_b32_e32 v25, 0xffff0000, v19
	v_mul_f32_e32 v19, 0xbfb8aa3b, v21
	v_exp_f32_e32 v18, v18
	v_exp_f32_e32 v19, v19
	v_pk_mul_f32 v[22:23], v[26:27], v[22:23]
	v_pk_add_f32 v[26:27], v[32:33], v[34:35] op_sel_hi:[1,0]
	v_add_f32_e32 v18, 1.0, v18
	v_add_f32_e32 v19, 1.0, v19
	v_rcp_f32_e32 v18, v18
	v_rcp_f32_e32 v19, v19
	v_pk_mul_f32 v[24:25], v[26:27], v[24:25]
	v_pk_mul_f32 v[18:19], v[18:19], v[20:21]
	s_nop 0
	v_pk_mul_f32 v[18:19], v[24:25], v[18:19]
	v_cvt_pk_bf16_f32 v20, v22, v23
	v_cvt_pk_bf16_f32 v21, v18, v19
	v_bitop3_b32 v18, v35, s17, v36 bitop3:0x36
	ds_write_b64 v38, v[20:21]
	v_lshl_add_u32 v20, v18, 4, v37
	v_add_u32_e32 v28, s71, v20
	v_add_u32_e32 v20, s91, v20
	ds_read_b64 v[18:19], v28
	ds_read_b64 v[20:21], v20
	s_waitcnt lgkmcnt(1)
	v_lshlrev_b32_e32 v26, 16, v18
	s_waitcnt lgkmcnt(0)
	v_lshlrev_b32_e32 v22, 16, v20
	v_and_b32_e32 v23, 0xffff0000, v20
	v_mul_f32_e32 v20, 0xbfb8aa3b, v22
	v_and_b32_e32 v27, 0xffff0000, v18
	v_mul_f32_e32 v18, 0xbfb8aa3b, v23
	v_exp_f32_e32 v20, v20
	v_exp_f32_e32 v18, v18
	v_pk_mul_f32 v[2:3], v[2:3], v[26:27]
	v_add_f32_e32 v20, 1.0, v20
	v_add_f32_e32 v18, 1.0, v18
	v_rcp_f32_e32 v24, v20
	v_rcp_f32_e32 v25, v18
	v_lshlrev_b32_e32 v20, 16, v21
	v_and_b32_e32 v21, 0xffff0000, v21
	v_mul_f32_e32 v18, 0xbfb8aa3b, v20
	v_pk_mul_f32 v[22:23], v[24:25], v[22:23]
	v_exp_f32_e32 v18, v18
	v_pk_mul_f32 v[2:3], v[2:3], v[22:23]
	v_lshlrev_b32_e32 v22, 16, v19
	v_and_b32_e32 v23, 0xffff0000, v19
	v_mul_f32_e32 v19, 0xbfb8aa3b, v21
	v_exp_f32_e32 v19, v19
	v_add_f32_e32 v18, 1.0, v18
	v_rcp_f32_e32 v18, v18
	v_pk_mul_f32 v[4:5], v[4:5], v[22:23]
	v_add_f32_e32 v19, 1.0, v19
	v_rcp_f32_e32 v19, v19
	v_cvt_pk_bf16_f32 v2, v2, v3
	v_pk_mul_f32 v[18:19], v[18:19], v[20:21]
	s_nop 0
	v_pk_mul_f32 v[4:5], v[4:5], v[18:19]
	s_nop 0
	v_cvt_pk_bf16_f32 v3, v4, v5
	ds_write_b64 v28, v[2:3]
	v_bitop3_b32 v2, v35, s18, v36 bitop3:0x36
	v_lshl_add_u32 v4, v2, 4, v37
	v_add_u32_e32 v24, s71, v4
	v_add_u32_e32 v4, s91, v4
	ds_read_b64 v[2:3], v24
	ds_read_b64 v[4:5], v4
	s_waitcnt lgkmcnt(1)
	v_lshlrev_b32_e32 v22, 16, v2
	s_waitcnt lgkmcnt(0)
; #define LAS __attribute__((address_space(3)))
; __device__ __forceinline__ float bflo(unsigned w) { return __uint_as_float(w << 16); }
; __device__ __forceinline__ float bfhi(unsigned w) { return __uint_as_float(w & 0xffff0000u); }
; __device__ __forceinline__ unsigned pk2(float lo, float hi) { const f32x2v v = {lo, hi}; return __builtin_bit_cast(unsigned, __builtin_convertvector(v, bf16x2v)); }
; __device__ __forceinline__ float silu_f(float g) { return g * fast_rcp(1.f + fast_exp2(-g * LOG2E)); }
; __device__ __forceinline__ void gmlp_item(LAS unsigned char* lds, const bf16_t* Zt  , bf16_t* BRt  , const bf16_t* wsb, const float* bs_, const float* lng, const float* lnb, const int tid) {
;     ...
;     for (int g = 0; g < 12; ++g) {
;         GM_LOAD(g);
;         { const int ch = tid & 15, t0 = tid >> 4;
;           if (g > 0) {
; #pragma unroll
;               for (int i = 0; i < 4; ++i) { const int t = t0 + 32 * i; const u32x4 ov = *(const LAS u32x4*)(lds + 65536 + off_b(t, ch)); *(u32x4*)(BRt + (size_t)t * DM + (g - 1) * 128 + 8 * ch) = ov; } }
;     ...
;         { const int t = 32 * tt + r2; const float bsv = bs_[g * 128 + t];
; #pragma unroll
;           for (int k8 = 0; k8 < 8; ++k8) { const int cc = k8 >> 2, q4 = k8 & 3;
;               const unsigned ad = off_b(t, 4 * (2 * cp + cc) + q4) + 8u * h2;
;               const u32x2 uw = *(const LAS u32x2*)(lds + 65536 + ad), gw = *(const LAS u32x2*)(lds + 98304 + ad);
;               const float v0 = bflo(uw.x) * (acc[cc][4 * q4 + 0] + bsv) * silu_f(bflo(gw.x)), v1 = bfhi(uw.x) * (acc[cc][4 * q4 + 1] + bsv) * silu_f(bfhi(gw.x));
;               const float v2 = bflo(uw.y) * (acc[cc][4 * q4 + 2] + bsv) * silu_f(bflo(gw.y)), v3 = bfhi(uw.y) * (acc[cc][4 * q4 + 3] + bsv) * silu_f(bfhi(gw.y));
;               u32x2 w; w.x = pk2(v0, v1); w.y = pk2(v2, v3);
;               *(LAS u32x2*)(lds + 65536 + ad) = w; } }
	v_lshlrev_b32_e32 v18, 16, v4
	v_and_b32_e32 v19, 0xffff0000, v4
	v_mul_f32_e32 v4, 0xbfb8aa3b, v18
	v_and_b32_e32 v23, 0xffff0000, v2
	v_mul_f32_e32 v2, 0xbfb8aa3b, v19
	v_exp_f32_e32 v4, v4
	v_exp_f32_e32 v2, v2
	v_pk_mul_f32 v[6:7], v[6:7], v[22:23]
	v_add_f32_e32 v4, 1.0, v4
	v_add_f32_e32 v2, 1.0, v2
	v_rcp_f32_e32 v20, v4
	v_rcp_f32_e32 v21, v2
	v_lshlrev_b32_e32 v4, 16, v5
	v_and_b32_e32 v5, 0xffff0000, v5
	v_mul_f32_e32 v2, 0xbfb8aa3b, v4
	v_pk_mul_f32 v[18:19], v[20:21], v[18:19]
	v_exp_f32_e32 v2, v2
	v_pk_mul_f32 v[6:7], v[6:7], v[18:19]
	v_lshlrev_b32_e32 v18, 16, v3
	v_and_b32_e32 v19, 0xffff0000, v3
	v_mul_f32_e32 v3, 0xbfb8aa3b, v5
	v_exp_f32_e32 v3, v3
	v_add_f32_e32 v2, 1.0, v2
	v_rcp_f32_e32 v2, v2
	v_pk_mul_f32 v[8:9], v[8:9], v[18:19]
	v_add_f32_e32 v3, 1.0, v3
	v_rcp_f32_e32 v3, v3
	s_nop 0
	v_pk_mul_f32 v[2:3], v[2:3], v[4:5]
	s_nop 0
	v_pk_mul_f32 v[2:3], v[8:9], v[2:3]
	v_cvt_pk_bf16_f32 v4, v6, v7
	v_cvt_pk_bf16_f32 v5, v2, v3
	v_bitop3_b32 v2, v35, s19, v36 bitop3:0x36
	ds_write_b64 v24, v[4:5]
	v_lshl_add_u32 v4, v2, 4, v37
	v_add_u32_e32 v20, s71, v4
	v_add_u32_e32 v4, s91, v4
	ds_read_b64 v[2:3], v20
	ds_read_b64 v[4:5], v4
	s_waitcnt lgkmcnt(1)
	v_lshlrev_b32_e32 v18, 16, v2
	s_waitcnt lgkmcnt(0)
	v_lshlrev_b32_e32 v6, 16, v4
	v_and_b32_e32 v7, 0xffff0000, v4
	v_mul_f32_e32 v4, 0xbfb8aa3b, v6
	v_and_b32_e32 v19, 0xffff0000, v2
	v_mul_f32_e32 v2, 0xbfb8aa3b, v7
	v_exp_f32_e32 v4, v4
	v_exp_f32_e32 v2, v2
	v_pk_mul_f32 v[10:11], v[10:11], v[18:19]
	v_add_f32_e32 v4, 1.0, v4
	v_add_f32_e32 v2, 1.0, v2
	v_rcp_f32_e32 v8, v4
	v_rcp_f32_e32 v9, v2
	v_lshlrev_b32_e32 v4, 16, v5
	v_and_b32_e32 v5, 0xffff0000, v5
	v_mul_f32_e32 v2, 0xbfb8aa3b, v4
	v_pk_mul_f32 v[6:7], v[8:9], v[6:7]
	v_lshlrev_b32_e32 v8, 16, v3
	v_and_b32_e32 v9, 0xffff0000, v3
	v_mul_f32_e32 v3, 0xbfb8aa3b, v5
	v_exp_f32_e32 v2, v2
	v_exp_f32_e32 v3, v3
	v_pk_mul_f32 v[6:7], v[10:11], v[6:7]
	v_pk_add_f32 v[10:11], v[12:13], v[34:35] op_sel_hi:[1,0]
	v_add_f32_e32 v2, 1.0, v2
	v_add_f32_e32 v3, 1.0, v3
	v_rcp_f32_e32 v2, v2
	v_rcp_f32_e32 v3, v3
	v_pk_mul_f32 v[8:9], v[10:11], v[8:9]
	v_pk_add_f32 v[12:13], v[14:15], v[34:35] op_sel_hi:[1,0]
	v_pk_mul_f32 v[2:3], v[2:3], v[4:5]
	s_nop 0
	v_pk_mul_f32 v[2:3], v[8:9], v[2:3]
	v_cvt_pk_bf16_f32 v4, v6, v7
	v_cvt_pk_bf16_f32 v5, v2, v3
	v_bitop3_b32 v2, v35, s26, v36 bitop3:0x36
	ds_write_b64 v20, v[4:5]
	v_lshl_add_u32 v4, v2, 4, v37
	v_add_u32_e32 v18, s71, v4
	v_add_u32_e32 v4, s91, v4
	ds_read_b64 v[2:3], v18
	ds_read_b64 v[4:5], v4
	s_waitcnt lgkmcnt(1)
	v_lshlrev_b32_e32 v10, 16, v2
	s_waitcnt lgkmcnt(0)
	v_lshlrev_b32_e32 v6, 16, v4
	v_and_b32_e32 v7, 0xffff0000, v4
	v_mul_f32_e32 v4, 0xbfb8aa3b, v6
	v_and_b32_e32 v11, 0xffff0000, v2
	v_mul_f32_e32 v2, 0xbfb8aa3b, v7
	v_exp_f32_e32 v4, v4
	v_exp_f32_e32 v2, v2
	v_pk_mul_f32 v[10:11], v[12:13], v[10:11]
	v_add_f32_e32 v4, 1.0, v4
	v_add_f32_e32 v2, 1.0, v2
	v_rcp_f32_e32 v8, v4
	v_rcp_f32_e32 v9, v2
	v_lshlrev_b32_e32 v4, 16, v5
	v_and_b32_e32 v5, 0xffff0000, v5
	v_mul_f32_e32 v2, 0xbfb8aa3b, v4
	v_pk_mul_f32 v[6:7], v[8:9], v[6:7]
	v_lshlrev_b32_e32 v8, 16, v3
	v_and_b32_e32 v9, 0xffff0000, v3
	v_mul_f32_e32 v3, 0xbfb8aa3b, v5
	v_exp_f32_e32 v2, v2
	v_exp_f32_e32 v3, v3
	v_pk_mul_f32 v[6:7], v[10:11], v[6:7]
	v_pk_add_f32 v[10:11], v[16:17], v[34:35] op_sel_hi:[1,0]
	v_add_f32_e32 v2, 1.0, v2
	v_add_f32_e32 v3, 1.0, v3
	v_rcp_f32_e32 v2, v2
	v_rcp_f32_e32 v3, v3
	v_pk_mul_f32 v[8:9], v[10:11], v[8:9]
	v_pk_mul_f32 v[2:3], v[2:3], v[4:5]
	s_nop 0
	v_pk_mul_f32 v[2:3], v[8:9], v[2:3]
	v_cvt_pk_bf16_f32 v4, v6, v7
	v_cvt_pk_bf16_f32 v5, v2, v3
	ds_write_b64 v18, v[4:5]
	s_waitcnt lgkmcnt(0)
	s_barrier
.LBB0_90:
	v_lshl_add_u64 v[2:3], v[122:123], 0, v[76:77]
	v_lshl_add_u64 v[54:55], v[124:125], 0, v[76:77]
	global_load_dwordx4 v[14:17], v[2:3], off
	v_add_co_u32_e32 v2, vcc, 0x1b100000, v54
	v_lshl_add_u64 v[18:19], v[66:67], 0, v[76:77]
	s_nop 0
	v_addc_co_u32_e32 v3, vcc, 0, v55, vcc
	v_add_co_u32_e32 v6, vcc, 0x1b101000, v54
	global_load_dwordx4 v[10:13], v[2:3], off offset:3328
	s_nop 0
	global_load_dwordx4 v[2:5], v[2:3], off offset:256
	v_addc_co_u32_e32 v7, vcc, 0, v55, vcc
	global_load_dwordx4 v[30:33], v[18:19], off
	v_add_co_u32_e32 v18, vcc, 0x1b158000, v54
	v_lshl_add_u64 v[34:35], v[68:69], 0, v[76:77]
	s_nop 0
	v_addc_co_u32_e32 v19, vcc, 0, v55, vcc
	v_add_co_u32_e32 v22, vcc, 0x1b159000, v54
	global_load_dwordx4 v[6:9], v[6:7], off offset:3328
	s_nop 0
	v_addc_co_u32_e32 v23, vcc, 0, v55, vcc
	global_load_dwordx4 v[26:29], v[18:19], off offset:3328
	s_nop 0
	global_load_dwordx4 v[18:21], v[18:19], off offset:256
	v_lshl_add_u64 v[50:51], v[70:71], 0, v[76:77]
	global_load_dwordx4 v[46:49], v[34:35], off
	v_add_co_u32_e32 v34, vcc, 0x1b1b0000, v54
	global_load_dwordx4 v[22:25], v[22:23], off offset:3328
	s_nop 0
	v_addc_co_u32_e32 v35, vcc, 0, v55, vcc
	v_add_co_u32_e32 v38, vcc, 0x1b1b1000, v54
	global_load_dwordx4 v[42:45], v[34:35], off offset:3328
	s_nop 0
	global_load_dwordx4 v[34:37], v[34:35], off offset:256
	v_addc_co_u32_e32 v39, vcc, 0, v55, vcc
	global_load_dwordx4 v[62:65], v[50:51], off
	v_add_co_u32_e32 v50, vcc, 0x1b208000, v54
	v_add_u32_e32 v196, v137, v138
	s_nop 0
	v_addc_co_u32_e32 v51, vcc, 0, v55, vcc
	global_load_dwordx4 v[38:41], v[38:39], off offset:3328
	s_nop 0
	global_load_dwordx4 v[58:61], v[50:51], off offset:3328
	s_nop 0
	global_load_dwordx4 v[50:53], v[50:51], off offset:256
	ds_read_b128 v[198:201], v196
	v_add_co_u32_e32 v54, vcc, 0x1b209000, v54
	v_lshl_add_u64 v[218:219], v[72:73], 0, v[76:77]
	s_nop 0
	v_addc_co_u32_e32 v55, vcc, 0, v55, vcc
	v_add_co_u32_e32 v214, vcc, 0x13100000, v218
	global_load_dwordx4 v[54:57], v[54:55], off offset:3328
	s_nop 0
	v_addc_co_u32_e32 v215, vcc, 0, v219, vcc
	s_waitcnt lgkmcnt(0)
; #define LAS __attribute__((address_space(3)))
; __device__ __forceinline__ float bflo(unsigned w) { return __uint_as_float(w << 16); }
; __device__ __forceinline__ float bfhi(unsigned w) { return __uint_as_float(w & 0xffff0000u); }
; __device__ __forceinline__ unsigned pk2(float lo, float hi) { const f32x2v v = {lo, hi}; return __builtin_bit_cast(unsigned, __builtin_convertvector(v, bf16x2v)); }
; __device__ __forceinline__ void gmlp_item(LAS unsigned char* lds, const bf16_t* Zt  , bf16_t* BRt  , const bf16_t* wsb, const float* bs_, const float* lng, const float* lnb, const int tid) {
;     ...
;           if (g > 0) {
; #pragma unroll
;               for (int i = 0; i < 4; ++i) { const int t = t0 + 32 * i; const u32x4 ov = *(const LAS u32x4*)(lds + 65536 + off_b(t, ch)); *(u32x4*)(BRt + (size_t)t * DM + (g - 1) * 128 + 8 * ch) = ov; } }
;           const float* gp = lng + g * 128 + 8 * ch; const float* bp = lnb + g * 128 + 8 * ch;
;           const f32x4 g0 = *(const f32x4*)gp, g1 = *(const f32x4*)(gp + 4), b0 = *(const f32x4*)bp, b1 = *(const f32x4*)(bp + 4);
; #pragma unroll
;           for (int i = 0; i < 4; ++i) { const int t = t0 + 32 * i;
;               *(LAS u32x4*)(lds + off_b(t, ch)) = wb[i];
;               const float mean = st[2 * t], rstd = st[2 * t + 1];
;               u32x4 o;
;               o.x = pk2((bflo(vw[i].x) - mean) * rstd * g0[0] + b0[0], (bfhi(vw[i].x) - mean) * rstd * g0[1] + b0[1]);
;               o.y = pk2((bflo(vw[i].y) - mean) * rstd * g0[2] + b0[2], (bfhi(vw[i].y) - mean) * rstd * g0[3] + b0[3]);
;               o.z = pk2((bflo(vw[i].z) - mean) * rstd * g1[0] + b1[0], (bfhi(vw[i].z) - mean) * rstd * g1[1] + b1[1]);
;               o.w = pk2((bflo(vw[i].w) - mean) * rstd * g1[2] + b1[2], (bfhi(vw[i].w) - mean) * rstd * g1[3] + b1[3]);
;               *(LAS u32x4*)(lds + 32768 + off_b(t, ch)) = o;
;               *(LAS u32x4*)(lds + 65536 + off_b(t, ch)) = uu[i]; *(LAS u32x4*)(lds + 98304 + off_b(t, ch)) = gg4[i]; } }
;         __syncthreads();
	global_store_dwordx4 v[214:215], v[198:201], off
	v_add_u32_e32 v197, v137, v139
	ds_read_b128 v[198:201], v197
	v_add_co_u32_e32 v214, vcc, 0x13120000, v218
	v_lshl_add_u64 v[226:227], v[80:81], 0, s[10:11]
	s_nop 0
	v_addc_co_u32_e32 v215, vcc, 0, v219, vcc
	s_waitcnt lgkmcnt(0)
	global_store_dwordx4 v[214:215], v[198:201], off
	v_lshl_add_u64 v[124:125], v[124:125], 0, s[56:57]
	v_lshl_add_u64 v[122:123], v[122:123], 0, s[0:1]
	v_add_u32_e32 v198, v137, v140
	ds_read_b128 v[214:217], v198
	v_add_co_u32_e32 v200, vcc, 0x13140000, v218
	v_add_u32_e32 v199, v137, v141
	s_nop 0
	v_addc_co_u32_e32 v201, vcc, 0, v219, vcc
	s_waitcnt lgkmcnt(0)
	global_store_dwordx4 v[200:201], v[214:217], off
	ds_read_b128 v[214:217], v199
	v_add_co_u32_e32 v200, vcc, 0x13160000, v218
	v_lshl_add_u64 v[72:73], v[72:73], 0, s[56:57]
	s_nop 0
	v_addc_co_u32_e32 v201, vcc, 0, v219, vcc
	s_waitcnt lgkmcnt(0)
	global_store_dwordx4 v[200:201], v[214:217], off
	v_lshl_add_u64 v[200:201], v[78:79], 0, s[10:11]
	global_load_dwordx4 v[214:217], v[200:201], off offset:528
	global_load_dwordx4 v[218:221], v[200:201], off offset:512
	global_load_dwordx4 v[222:225], v[226:227], off offset:528
	global_load_dwordx4 v[232:235], v[226:227], off offset:512
	s_waitcnt vmcnt(0)
	ds_write_b128 v160, v[14:17]
	ds_read_b64 v[14:15], v161
	s_add_u32 s10, s10, 0x200
	s_addc_u32 s11, s11, 0
	v_lshl_add_u64 v[70:71], v[70:71], 0, s[0:1]
	v_lshlrev_b32_e32 v16, 16, v10
	v_and_b32_e32 v17, 0xffff0000, v10
	s_waitcnt lgkmcnt(0)
	v_pk_add_f32 v[16:17], v[16:17], v[14:15] op_sel_hi:[1,0] neg_lo:[0,1] neg_hi:[0,1]
	v_lshl_add_u64 v[68:69], v[68:69], 0, s[0:1]
	v_pk_mul_f32 v[16:17], v[14:15], v[16:17] op_sel:[1,0]
	v_lshl_add_u64 v[66:67], v[66:67], 0, s[0:1]
	v_pk_fma_f32 v[16:17], v[218:219], v[16:17], v[232:233]
	s_nop 0
	v_cvt_pk_bf16_f32 v10, v16, v17
	v_lshlrev_b32_e32 v16, 16, v11
	v_and_b32_e32 v17, 0xffff0000, v11
	v_pk_add_f32 v[16:17], v[16:17], v[14:15] op_sel_hi:[1,0] neg_lo:[0,1] neg_hi:[0,1]
	s_nop 0
	v_pk_mul_f32 v[16:17], v[14:15], v[16:17] op_sel:[1,0]
	s_nop 0
	v_pk_fma_f32 v[16:17], v[220:221], v[16:17], v[234:235]
	s_nop 0
	v_cvt_pk_bf16_f32 v11, v16, v17
	v_lshlrev_b32_e32 v16, 16, v12
	v_and_b32_e32 v17, 0xffff0000, v12
	v_pk_add_f32 v[16:17], v[16:17], v[14:15] op_sel_hi:[1,0] neg_lo:[0,1] neg_hi:[0,1]
	s_nop 0
	v_pk_mul_f32 v[16:17], v[14:15], v[16:17] op_sel:[1,0]
	s_nop 0
	v_pk_fma_f32 v[16:17], v[214:215], v[16:17], v[222:223]
	s_nop 0
	v_cvt_pk_bf16_f32 v12, v16, v17
	v_lshlrev_b32_e32 v16, 16, v13
	v_and_b32_e32 v17, 0xffff0000, v13
	v_pk_add_f32 v[16:17], v[16:17], v[14:15] op_sel_hi:[1,0] neg_lo:[0,1] neg_hi:[0,1]
	s_nop 0
	v_pk_mul_f32 v[14:15], v[14:15], v[16:17] op_sel:[1,0]
	s_nop 0
	v_pk_fma_f32 v[14:15], v[216:217], v[14:15], v[224:225]
	s_nop 0
	v_cvt_pk_bf16_f32 v13, v14, v15
	ds_write_b128 v160, v[10:13] offset:32768
	ds_write_b128 v162, v[2:5]
	ds_write_b128 v163, v[6:9]
	ds_write_b128 v164, v[30:33]
	ds_read_b64 v[6:7], v165
	v_lshlrev_b32_e32 v2, 16, v26
	v_and_b32_e32 v3, 0xffff0000, v26
	v_lshlrev_b32_e32 v4, 16, v27
	v_and_b32_e32 v5, 0xffff0000, v27
	s_waitcnt lgkmcnt(0)
	v_pk_add_f32 v[2:3], v[2:3], v[6:7] op_sel_hi:[1,0] neg_lo:[0,1] neg_hi:[0,1]
	v_pk_add_f32 v[4:5], v[4:5], v[6:7] op_sel_hi:[1,0] neg_lo:[0,1] neg_hi:[0,1]
	v_pk_mul_f32 v[2:3], v[6:7], v[2:3] op_sel:[1,0]
	v_pk_mul_f32 v[4:5], v[6:7], v[4:5] op_sel:[1,0]
	v_pk_fma_f32 v[2:3], v[218:219], v[2:3], v[232:233]
	v_pk_fma_f32 v[4:5], v[220:221], v[4:5], v[234:235]
	v_cvt_pk_bf16_f32 v2, v2, v3
	v_cvt_pk_bf16_f32 v3, v4, v5
	v_lshlrev_b32_e32 v4, 16, v28
	v_and_b32_e32 v5, 0xffff0000, v28
	v_lshlrev_b32_e32 v8, 16, v29
	v_and_b32_e32 v9, 0xffff0000, v29
	v_pk_add_f32 v[4:5], v[4:5], v[6:7] op_sel_hi:[1,0] neg_lo:[0,1] neg_hi:[0,1]
	v_pk_add_f32 v[8:9], v[8:9], v[6:7] op_sel_hi:[1,0] neg_lo:[0,1] neg_hi:[0,1]
	v_pk_mul_f32 v[4:5], v[6:7], v[4:5] op_sel:[1,0]
	v_pk_mul_f32 v[6:7], v[6:7], v[8:9] op_sel:[1,0]
	v_pk_fma_f32 v[4:5], v[214:215], v[4:5], v[222:223]
	v_pk_fma_f32 v[6:7], v[216:217], v[6:7], v[224:225]
	v_cvt_pk_bf16_f32 v4, v4, v5
	v_cvt_pk_bf16_f32 v5, v6, v7
	ds_write_b128 v164, v[2:5] offset:32768
	ds_write_b128 v166, v[18:21]
	ds_write_b128 v167, v[22:25]
	ds_write_b128 v168, v[46:49]
	ds_read_b64 v[6:7], v169
	v_lshlrev_b32_e32 v2, 16, v42
	v_and_b32_e32 v3, 0xffff0000, v42
	v_lshlrev_b32_e32 v4, 16, v43
	v_and_b32_e32 v5, 0xffff0000, v43
	s_waitcnt lgkmcnt(0)
	v_pk_add_f32 v[2:3], v[2:3], v[6:7] op_sel_hi:[1,0] neg_lo:[0,1] neg_hi:[0,1]
	v_pk_add_f32 v[4:5], v[4:5], v[6:7] op_sel_hi:[1,0] neg_lo:[0,1] neg_hi:[0,1]
	v_pk_mul_f32 v[2:3], v[6:7], v[2:3] op_sel:[1,0]
	v_pk_mul_f32 v[4:5], v[6:7], v[4:5] op_sel:[1,0]
	v_pk_fma_f32 v[2:3], v[218:219], v[2:3], v[232:233]
	v_pk_fma_f32 v[4:5], v[220:221], v[4:5], v[234:235]
	v_cvt_pk_bf16_f32 v2, v2, v3
	v_cvt_pk_bf16_f32 v3, v4, v5
	v_lshlrev_b32_e32 v4, 16, v44
	v_and_b32_e32 v5, 0xffff0000, v44
	v_lshlrev_b32_e32 v8, 16, v45
	v_and_b32_e32 v9, 0xffff0000, v45
	v_pk_add_f32 v[4:5], v[4:5], v[6:7] op_sel_hi:[1,0] neg_lo:[0,1] neg_hi:[0,1]
	v_pk_add_f32 v[8:9], v[8:9], v[6:7] op_sel_hi:[1,0] neg_lo:[0,1] neg_hi:[0,1]
	v_pk_mul_f32 v[4:5], v[6:7], v[4:5] op_sel:[1,0]
	v_pk_mul_f32 v[6:7], v[6:7], v[8:9] op_sel:[1,0]
	v_pk_fma_f32 v[4:5], v[214:215], v[4:5], v[222:223]
	v_pk_fma_f32 v[6:7], v[216:217], v[6:7], v[224:225]
	v_cvt_pk_bf16_f32 v4, v4, v5
	v_cvt_pk_bf16_f32 v5, v6, v7
	ds_write_b128 v168, v[2:5] offset:32768
	ds_write_b128 v170, v[34:37]
	ds_write_b128 v171, v[38:41]
	ds_write_b128 v172, v[62:65]
	ds_read_b64 v[6:7], v173
	v_lshlrev_b32_e32 v2, 16, v58
	v_and_b32_e32 v3, 0xffff0000, v58
	v_lshlrev_b32_e32 v4, 16, v59
	v_and_b32_e32 v5, 0xffff0000, v59
	s_waitcnt lgkmcnt(0)
	v_pk_add_f32 v[2:3], v[2:3], v[6:7] op_sel_hi:[1,0] neg_lo:[0,1] neg_hi:[0,1]
	v_pk_add_f32 v[4:5], v[4:5], v[6:7] op_sel_hi:[1,0] neg_lo:[0,1] neg_hi:[0,1]
	v_pk_mul_f32 v[2:3], v[6:7], v[2:3] op_sel:[1,0]
	v_pk_mul_f32 v[4:5], v[6:7], v[4:5] op_sel:[1,0]
	v_pk_fma_f32 v[2:3], v[218:219], v[2:3], v[232:233]
	v_pk_fma_f32 v[4:5], v[220:221], v[4:5], v[234:235]
	v_cvt_pk_bf16_f32 v2, v2, v3
	v_cvt_pk_bf16_f32 v3, v4, v5
	v_lshlrev_b32_e32 v4, 16, v60
	v_and_b32_e32 v5, 0xffff0000, v60
	v_lshlrev_b32_e32 v8, 16, v61
	v_and_b32_e32 v9, 0xffff0000, v61
	v_pk_add_f32 v[4:5], v[4:5], v[6:7] op_sel_hi:[1,0] neg_lo:[0,1] neg_hi:[0,1]
	v_pk_add_f32 v[8:9], v[8:9], v[6:7] op_sel_hi:[1,0] neg_lo:[0,1] neg_hi:[0,1]
	v_pk_mul_f32 v[4:5], v[6:7], v[4:5] op_sel:[1,0]
	v_pk_mul_f32 v[6:7], v[6:7], v[8:9] op_sel:[1,0]
	v_pk_fma_f32 v[4:5], v[214:215], v[4:5], v[222:223]
	v_pk_fma_f32 v[6:7], v[216:217], v[6:7], v[224:225]
	v_cvt_pk_bf16_f32 v4, v4, v5
	v_cvt_pk_bf16_f32 v5, v6, v7
	ds_write_b128 v172, v[2:5] offset:32768
	ds_write_b128 v179, v[50:53]
	ds_write_b128 v181, v[54:57]
	s_waitcnt lgkmcnt(0)
	s_barrier
; #define LAS __attribute__((address_space(3)))
; #define MFMA32(a, b, c) __builtin_amdgcn_mfma_f32_32x32x16_bf16((a), (b), (c), 0, 0, 0)
; __device__ __forceinline__ float bflo(unsigned w) { return __uint_as_float(w << 16); }
; __device__ __forceinline__ float bfhi(unsigned w) { return __uint_as_float(w & 0xffff0000u); }
; __device__ __forceinline__ unsigned pk2(float lo, float hi) { const f32x2v v = {lo, hi}; return __builtin_bit_cast(unsigned, __builtin_convertvector(v, bf16x2v)); }
; __device__ __forceinline__ float silu_f(float g) { return g * fast_rcp(1.f + fast_exp2(-g * LOG2E)); }
; __device__ __forceinline__ void gmlp_item(LAS unsigned char* lds, const bf16_t* Zt  , bf16_t* BRt  , const bf16_t* wsb, const float* bs_, const float* lng, const float* lnb, const int tid) {
;     ...
;         f32x16 acc[2];
; #pragma unroll
;         for (int i = 0; i < 16; ++i) { acc[0][i] = 0.f; acc[1][i] = 0.f; }
; #pragma unroll
;         for (int ks = 0; ks < 8; ++ks) {
;             const bf16x8 af = *(LAS bf16x8*)(lds + aaddr[ks]);
; #pragma unroll
;             for (int cc = 0; cc < 2; ++cc) {
;                 const s16x4 lo = __builtin_amdgcn_ds_read_tr16_b64_v4i16((LAS s16x4*)(lds + baddr[cc][0] + ks * 4096));
;                 const s16x4 hi = __builtin_amdgcn_ds_read_tr16_b64_v4i16((LAS s16x4*)(lds + baddr[cc][1] + ks * 4096));
;                 const bf16x8 bfv = __builtin_shufflevector(lo, hi, 0, 1, 2, 3, 4, 5, 6, 7);
;                 acc[cc] = MFMA32(bfv, af, acc[cc]); }
;         }
;         int r2 = r, h2 = h; asm volatile("" : "+v"(r2), "+v"(h2));
;         { const int t = 32 * tt + r2; const float bsv = bs_[g * 128 + t];
; #pragma unroll
;           for (int k8 = 0; k8 < 8; ++k8) { const int cc = k8 >> 2, q4 = k8 & 3;
;               const unsigned ad = off_b(t, 4 * (2 * cp + cc) + q4) + 8u * h2;
;               const u32x2 uw = *(const LAS u32x2*)(lds + 65536 + ad), gw = *(const LAS u32x2*)(lds + 98304 + ad);
;               const float v0 = bflo(uw.x) * (acc[cc][4 * q4 + 0] + bsv) * silu_f(bflo(gw.x)), v1 = bfhi(uw.x) * (acc[cc][4 * q4 + 1] + bsv) * silu_f(bfhi(gw.x));
;               const float v2 = bflo(uw.y) * (acc[cc][4 * q4 + 2] + bsv) * silu_f(bflo(gw.y)), v3 = bfhi(uw.y) * (acc[cc][4 * q4 + 3] + bsv) * silu_f(bfhi(gw.y));
;               u32x2 w; w.x = pk2(v0, v1); w.y = pk2(v2, v3);
;               *(LAS u32x2*)(lds + 65536 + ad) = w; } }
	ds_read_b128 v[2:5], v184
	ds_read_b64_tr_b16 v[6:7], v185 offset:32768
	ds_read_b64_tr_b16 v[8:9], v186 offset:32768
	s_waitcnt lgkmcnt(0)
	v_mfma_f32_32x32x16_bf16 v[18:33], v[6:9], v[2:5], 0
	ds_read_b64_tr_b16 v[6:7], v187 offset:32768
	ds_read_b64_tr_b16 v[8:9], v188 offset:32768
	ds_read_b128 v[34:37], v189
	ds_read_b64_tr_b16 v[38:39], v185 offset:36864
	ds_read_b64_tr_b16 v[40:41], v186 offset:36864
	s_waitcnt lgkmcnt(3)
	v_mfma_f32_32x32x16_bf16 v[2:17], v[6:9], v[2:5], 0
	s_waitcnt lgkmcnt(0)
	v_mfma_f32_32x32x16_bf16 v[18:33], v[38:41], v[34:37], v[18:33]
	ds_read_b64_tr_b16 v[38:39], v187 offset:36864
	ds_read_b64_tr_b16 v[40:41], v188 offset:36864
	s_waitcnt lgkmcnt(0)
	v_mfma_f32_32x32x16_bf16 v[2:17], v[38:41], v[34:37], v[2:17]
	ds_read_b128 v[34:37], v190
	ds_read_b64_tr_b16 v[38:39], v185 offset:40960
	ds_read_b64_tr_b16 v[40:41], v186 offset:40960
	s_waitcnt lgkmcnt(0)
	v_mfma_f32_32x32x16_bf16 v[18:33], v[38:41], v[34:37], v[18:33]
	ds_read_b64_tr_b16 v[38:39], v187 offset:40960
	ds_read_b64_tr_b16 v[40:41], v188 offset:40960
	s_waitcnt lgkmcnt(0)
	v_mfma_f32_32x32x16_bf16 v[2:17], v[38:41], v[34:37], v[2:17]
	ds_read_b128 v[34:37], v191
	ds_read_b64_tr_b16 v[38:39], v185 offset:45056
	ds_read_b64_tr_b16 v[40:41], v186 offset:45056
	s_waitcnt lgkmcnt(0)
	v_mfma_f32_32x32x16_bf16 v[18:33], v[38:41], v[34:37], v[18:33]
	ds_read_b64_tr_b16 v[38:39], v187 offset:45056
	ds_read_b64_tr_b16 v[40:41], v188 offset:45056
	s_waitcnt lgkmcnt(0)
	v_mfma_f32_32x32x16_bf16 v[2:17], v[38:41], v[34:37], v[2:17]
	ds_read_b128 v[34:37], v192
	ds_read_b64_tr_b16 v[38:39], v185 offset:49152
	ds_read_b64_tr_b16 v[40:41], v186 offset:49152
	s_waitcnt lgkmcnt(0)
	v_mfma_f32_32x32x16_bf16 v[18:33], v[38:41], v[34:37], v[18:33]
	ds_read_b64_tr_b16 v[38:39], v187 offset:49152
	ds_read_b64_tr_b16 v[40:41], v188 offset:49152
	s_waitcnt lgkmcnt(0)
	v_mfma_f32_32x32x16_bf16 v[2:17], v[38:41], v[34:37], v[2:17]
	ds_read_b128 v[34:37], v193
	ds_read_b64_tr_b16 v[38:39], v185 offset:53248
	ds_read_b64_tr_b16 v[40:41], v186 offset:53248
	s_waitcnt lgkmcnt(0)
	v_mfma_f32_32x32x16_bf16 v[18:33], v[38:41], v[34:37], v[18:33]
	ds_read_b64_tr_b16 v[38:39], v187 offset:53248
	ds_read_b64_tr_b16 v[40:41], v188 offset:53248
	s_waitcnt lgkmcnt(0)
	v_mfma_f32_32x32x16_bf16 v[2:17], v[38:41], v[34:37], v[2:17]
	ds_read_b128 v[34:37], v194
	ds_read_b64_tr_b16 v[38:39], v185 offset:57344
	ds_read_b64_tr_b16 v[40:41], v186 offset:57344
	s_waitcnt lgkmcnt(0)
	v_mfma_f32_32x32x16_bf16 v[18:33], v[38:41], v[34:37], v[18:33]
	ds_read_b64_tr_b16 v[38:39], v187 offset:57344
	ds_read_b64_tr_b16 v[40:41], v188 offset:57344
	s_waitcnt lgkmcnt(0)
	v_mfma_f32_32x32x16_bf16 v[2:17], v[38:41], v[34:37], v[2:17]
	ds_read_b128 v[34:37], v195
	ds_read_b64_tr_b16 v[38:39], v185 offset:61440
	ds_read_b64_tr_b16 v[40:41], v186 offset:61440
	s_waitcnt lgkmcnt(0)
	v_mfma_f32_32x32x16_bf16 v[18:33], v[38:41], v[34:37], v[18:33]
	ds_read_b64_tr_b16 v[38:39], v187 offset:61440
	ds_read_b64_tr_b16 v[40:41], v188 offset:61440
	s_waitcnt lgkmcnt(0)
	v_mfma_f32_32x32x16_bf16 v[2:17], v[38:41], v[34:37], v[2:17]
	v_mov_b32_e32 v36, v75
	v_mov_b32_e32 v37, v132
	s_nop 0
	v_add_u32_e32 v34, s27, v36
	v_ashrrev_i32_e32 v35, 31, v34
	v_lshl_add_u64 v[34:35], v[34:35], 2, s[6:7]
	global_load_dword v34, v[34:35], off
	v_lshlrev_b32_e32 v35, 2, v36
	v_add_u32_e32 v38, s13, v36
	v_and_b32_e32 v35, 12, v35
	v_bfe_u32 v46, v36, 2, 2
	v_lshlrev_b32_e32 v36, 3, v37
	v_lshl_add_u32 v47, v38, 8, v36
	v_bitop3_b32 v36, v35, s12, v46 bitop3:0x36
	v_lshl_add_u32 v38, v36, 4, v47
	v_add_u32_e32 v48, s71, v38
	v_add_u32_e32 v38, s91, v38
	ds_read_b64 v[36:37], v48
	ds_read_b64 v[38:39], v38
	s_addk_i32 s27, 0x80
	s_cmpk_lg_i32 s10, 0x1600
	s_waitcnt lgkmcnt(1)
	v_lshlrev_b32_e32 v44, 16, v36
	s_waitcnt lgkmcnt(0)
	v_lshlrev_b32_e32 v40, 16, v38
	v_and_b32_e32 v41, 0xffff0000, v38
	v_mul_f32_e32 v38, 0xbfb8aa3b, v40
	v_and_b32_e32 v45, 0xffff0000, v36
	v_mul_f32_e32 v36, 0xbfb8aa3b, v41
	v_exp_f32_e32 v38, v38
	v_exp_f32_e32 v36, v36
	v_add_f32_e32 v38, 1.0, v38
	v_add_f32_e32 v36, 1.0, v36
	v_rcp_f32_e32 v42, v38
	v_rcp_f32_e32 v43, v36
	v_lshlrev_b32_e32 v38, 16, v39
	v_and_b32_e32 v39, 0xffff0000, v39
	v_mul_f32_e32 v36, 0xbfb8aa3b, v38
	v_pk_mul_f32 v[40:41], v[42:43], v[40:41]
	v_exp_f32_e32 v36, v36
	s_waitcnt vmcnt(0)
	v_pk_add_f32 v[18:19], v[18:19], v[34:35] op_sel_hi:[1,0]
	s_nop 0
	v_pk_mul_f32 v[18:19], v[18:19], v[44:45]
	v_add_f32_e32 v36, 1.0, v36
	v_pk_mul_f32 v[18:19], v[18:19], v[40:41]
	v_lshlrev_b32_e32 v40, 16, v37
	v_and_b32_e32 v41, 0xffff0000, v37
	v_mul_f32_e32 v37, 0xbfb8aa3b, v39
	v_exp_f32_e32 v37, v37
	v_rcp_f32_e32 v36, v36
	v_pk_add_f32 v[20:21], v[20:21], v[34:35] op_sel_hi:[1,0]
	v_cvt_pk_bf16_f32 v18, v18, v19
	v_add_f32_e32 v37, 1.0, v37
	v_rcp_f32_e32 v37, v37
	v_pk_mul_f32 v[20:21], v[20:21], v[40:41]
	v_pk_add_f32 v[22:23], v[22:23], v[34:35] op_sel_hi:[1,0]
	v_pk_add_f32 v[24:25], v[24:25], v[34:35] op_sel_hi:[1,0]
	v_pk_mul_f32 v[36:37], v[36:37], v[38:39]
	v_pk_add_f32 v[26:27], v[26:27], v[34:35] op_sel_hi:[1,0]
	v_pk_mul_f32 v[20:21], v[20:21], v[36:37]
	v_pk_add_f32 v[2:3], v[2:3], v[34:35] op_sel_hi:[1,0]
	v_cvt_pk_bf16_f32 v19, v20, v21
	ds_write_b64 v48, v[18:19]
	v_bitop3_b32 v18, v35, s14, v46 bitop3:0x36
	v_lshl_add_u32 v20, v18, 4, v47
	v_add_u32_e32 v42, s71, v20
	v_add_u32_e32 v20, s91, v20
	ds_read_b64 v[18:19], v42
	ds_read_b64 v[20:21], v20
	v_pk_add_f32 v[4:5], v[4:5], v[34:35] op_sel_hi:[1,0]
	v_pk_add_f32 v[6:7], v[6:7], v[34:35] op_sel_hi:[1,0]
	v_pk_add_f32 v[8:9], v[8:9], v[34:35] op_sel_hi:[1,0]
	s_waitcnt lgkmcnt(1)
	v_lshlrev_b32_e32 v40, 16, v18
	s_waitcnt lgkmcnt(0)
; #define LAS __attribute__((address_space(3)))
; __device__ __forceinline__ float bflo(unsigned w) { return __uint_as_float(w << 16); }
; __device__ __forceinline__ float bfhi(unsigned w) { return __uint_as_float(w & 0xffff0000u); }
; __device__ __forceinline__ unsigned pk2(float lo, float hi) { const f32x2v v = {lo, hi}; return __builtin_bit_cast(unsigned, __builtin_convertvector(v, bf16x2v)); }
; __device__ __forceinline__ float silu_f(float g) { return g * fast_rcp(1.f + fast_exp2(-g * LOG2E)); }
; __device__ __forceinline__ void gmlp_item(LAS unsigned char* lds, const bf16_t* Zt  , bf16_t* BRt  , const bf16_t* wsb, const float* bs_, const float* lng, const float* lnb, const int tid) {
;     ...
;         { const int t = 32 * tt + r2; const float bsv = bs_[g * 128 + t];
; #pragma unroll
;           for (int k8 = 0; k8 < 8; ++k8) { const int cc = k8 >> 2, q4 = k8 & 3;
;               const unsigned ad = off_b(t, 4 * (2 * cp + cc) + q4) + 8u * h2;
;               const u32x2 uw = *(const LAS u32x2*)(lds + 65536 + ad), gw = *(const LAS u32x2*)(lds + 98304 + ad);
;               const float v0 = bflo(uw.x) * (acc[cc][4 * q4 + 0] + bsv) * silu_f(bflo(gw.x)), v1 = bfhi(uw.x) * (acc[cc][4 * q4 + 1] + bsv) * silu_f(bfhi(gw.x));
;               const float v2 = bflo(uw.y) * (acc[cc][4 * q4 + 2] + bsv) * silu_f(bflo(gw.y)), v3 = bfhi(uw.y) * (acc[cc][4 * q4 + 3] + bsv) * silu_f(bfhi(gw.y));
;               u32x2 w; w.x = pk2(v0, v1); w.y = pk2(v2, v3);
;               *(LAS u32x2*)(lds + 65536 + ad) = w; } }
	v_lshlrev_b32_e32 v36, 16, v20
	v_and_b32_e32 v37, 0xffff0000, v20
	v_mul_f32_e32 v20, 0xbfb8aa3b, v36
	v_and_b32_e32 v41, 0xffff0000, v18
	v_mul_f32_e32 v18, 0xbfb8aa3b, v37
	v_exp_f32_e32 v20, v20
	v_exp_f32_e32 v18, v18
	v_pk_mul_f32 v[22:23], v[22:23], v[40:41]
	v_pk_add_f32 v[10:11], v[10:11], v[34:35] op_sel_hi:[1,0]
	v_add_f32_e32 v20, 1.0, v20
	v_add_f32_e32 v18, 1.0, v18
	v_rcp_f32_e32 v38, v20
	v_rcp_f32_e32 v39, v18
	v_lshlrev_b32_e32 v20, 16, v21
	v_and_b32_e32 v21, 0xffff0000, v21
	v_mul_f32_e32 v18, 0xbfb8aa3b, v20
	v_pk_mul_f32 v[36:37], v[38:39], v[36:37]
	v_exp_f32_e32 v18, v18
	v_pk_mul_f32 v[22:23], v[22:23], v[36:37]
	v_lshlrev_b32_e32 v36, 16, v19
	v_and_b32_e32 v37, 0xffff0000, v19
	v_mul_f32_e32 v19, 0xbfb8aa3b, v21
	v_exp_f32_e32 v19, v19
	v_add_f32_e32 v18, 1.0, v18
	v_rcp_f32_e32 v18, v18
	v_pk_mul_f32 v[24:25], v[24:25], v[36:37]
	v_add_f32_e32 v19, 1.0, v19
	v_rcp_f32_e32 v19, v19
	s_nop 0
	v_pk_mul_f32 v[18:19], v[18:19], v[20:21]
	s_nop 0
	v_pk_mul_f32 v[18:19], v[24:25], v[18:19]
	v_cvt_pk_bf16_f32 v20, v22, v23
	v_cvt_pk_bf16_f32 v21, v18, v19
	v_bitop3_b32 v18, v35, s15, v46 bitop3:0x36
	ds_write_b64 v42, v[20:21]
	v_lshl_add_u32 v20, v18, 4, v47
	v_add_u32_e32 v38, s71, v20
	v_add_u32_e32 v20, s91, v20
	ds_read_b64 v[18:19], v38
	ds_read_b64 v[20:21], v20
	s_waitcnt lgkmcnt(1)
	v_lshlrev_b32_e32 v36, 16, v18
	s_waitcnt lgkmcnt(0)
	v_lshlrev_b32_e32 v22, 16, v20
	v_and_b32_e32 v23, 0xffff0000, v20
	v_mul_f32_e32 v20, 0xbfb8aa3b, v22
	v_and_b32_e32 v37, 0xffff0000, v18
	v_mul_f32_e32 v18, 0xbfb8aa3b, v23
	v_exp_f32_e32 v20, v20
	v_exp_f32_e32 v18, v18
	v_pk_mul_f32 v[26:27], v[26:27], v[36:37]
	v_add_f32_e32 v20, 1.0, v20
	v_add_f32_e32 v18, 1.0, v18
	v_rcp_f32_e32 v24, v20
	v_rcp_f32_e32 v25, v18
	v_lshlrev_b32_e32 v20, 16, v21
	v_and_b32_e32 v21, 0xffff0000, v21
	v_mul_f32_e32 v18, 0xbfb8aa3b, v20
	v_pk_mul_f32 v[22:23], v[24:25], v[22:23]
	v_lshlrev_b32_e32 v24, 16, v19
	v_and_b32_e32 v25, 0xffff0000, v19
	v_mul_f32_e32 v19, 0xbfb8aa3b, v21
	v_exp_f32_e32 v18, v18
	v_exp_f32_e32 v19, v19
	v_pk_mul_f32 v[22:23], v[26:27], v[22:23]
	v_pk_add_f32 v[26:27], v[28:29], v[34:35] op_sel_hi:[1,0]
	v_add_f32_e32 v18, 1.0, v18
	v_add_f32_e32 v19, 1.0, v19
	v_rcp_f32_e32 v18, v18
	v_rcp_f32_e32 v19, v19
	v_pk_mul_f32 v[24:25], v[26:27], v[24:25]
	v_pk_add_f32 v[28:29], v[30:31], v[34:35] op_sel_hi:[1,0]
	v_pk_mul_f32 v[18:19], v[18:19], v[20:21]
	s_nop 0
	v_pk_mul_f32 v[18:19], v[24:25], v[18:19]
	v_cvt_pk_bf16_f32 v20, v22, v23
	v_cvt_pk_bf16_f32 v21, v18, v19
	v_bitop3_b32 v18, v35, s16, v46 bitop3:0x36
	ds_write_b64 v38, v[20:21]
	v_lshl_add_u32 v20, v18, 4, v47
	v_add_u32_e32 v36, s71, v20
	v_add_u32_e32 v20, s91, v20
	ds_read_b64 v[18:19], v36
	ds_read_b64 v[20:21], v20
	s_waitcnt lgkmcnt(1)
	v_lshlrev_b32_e32 v26, 16, v18
	s_waitcnt lgkmcnt(0)
	v_lshlrev_b32_e32 v22, 16, v20
	v_and_b32_e32 v23, 0xffff0000, v20
	v_mul_f32_e32 v20, 0xbfb8aa3b, v22
	v_and_b32_e32 v27, 0xffff0000, v18
	v_mul_f32_e32 v18, 0xbfb8aa3b, v23
	v_exp_f32_e32 v20, v20
	v_exp_f32_e32 v18, v18
	v_pk_mul_f32 v[26:27], v[28:29], v[26:27]
	v_add_f32_e32 v20, 1.0, v20
	v_add_f32_e32 v18, 1.0, v18
	v_rcp_f32_e32 v24, v20
	v_rcp_f32_e32 v25, v18
	v_lshlrev_b32_e32 v20, 16, v21
	v_and_b32_e32 v21, 0xffff0000, v21
	v_mul_f32_e32 v18, 0xbfb8aa3b, v20
	v_pk_mul_f32 v[22:23], v[24:25], v[22:23]
	v_lshlrev_b32_e32 v24, 16, v19
	v_and_b32_e32 v25, 0xffff0000, v19
	v_mul_f32_e32 v19, 0xbfb8aa3b, v21
	v_exp_f32_e32 v18, v18
	v_exp_f32_e32 v19, v19
	v_pk_mul_f32 v[22:23], v[26:27], v[22:23]
	v_pk_add_f32 v[26:27], v[32:33], v[34:35] op_sel_hi:[1,0]
	v_add_f32_e32 v18, 1.0, v18
	v_add_f32_e32 v19, 1.0, v19
	v_rcp_f32_e32 v18, v18
	v_rcp_f32_e32 v19, v19
	v_pk_mul_f32 v[24:25], v[26:27], v[24:25]
	v_pk_mul_f32 v[18:19], v[18:19], v[20:21]
	s_nop 0
	v_pk_mul_f32 v[18:19], v[24:25], v[18:19]
	v_cvt_pk_bf16_f32 v20, v22, v23
	v_cvt_pk_bf16_f32 v21, v18, v19
	v_bitop3_b32 v18, v35, s17, v46 bitop3:0x36
	ds_write_b64 v36, v[20:21]
	v_lshl_add_u32 v20, v18, 4, v47
	v_add_u32_e32 v28, s71, v20
	v_add_u32_e32 v20, s91, v20
	ds_read_b64 v[18:19], v28
	ds_read_b64 v[20:21], v20
	s_waitcnt lgkmcnt(1)
	v_lshlrev_b32_e32 v26, 16, v18
	s_waitcnt lgkmcnt(0)
	v_lshlrev_b32_e32 v22, 16, v20
	v_and_b32_e32 v23, 0xffff0000, v20
	v_mul_f32_e32 v20, 0xbfb8aa3b, v22
	v_and_b32_e32 v27, 0xffff0000, v18
	v_mul_f32_e32 v18, 0xbfb8aa3b, v23
	v_exp_f32_e32 v20, v20
	v_exp_f32_e32 v18, v18
	v_pk_mul_f32 v[2:3], v[2:3], v[26:27]
	v_add_f32_e32 v20, 1.0, v20
	v_add_f32_e32 v18, 1.0, v18
	v_rcp_f32_e32 v24, v20
	v_rcp_f32_e32 v25, v18
	v_lshlrev_b32_e32 v20, 16, v21
	v_and_b32_e32 v21, 0xffff0000, v21
	v_mul_f32_e32 v18, 0xbfb8aa3b, v20
	v_pk_mul_f32 v[22:23], v[24:25], v[22:23]
	v_exp_f32_e32 v18, v18
	v_pk_mul_f32 v[2:3], v[2:3], v[22:23]
	v_lshlrev_b32_e32 v22, 16, v19
	v_and_b32_e32 v23, 0xffff0000, v19
	v_mul_f32_e32 v19, 0xbfb8aa3b, v21
	v_exp_f32_e32 v19, v19
	v_add_f32_e32 v18, 1.0, v18
	v_rcp_f32_e32 v18, v18
	v_pk_mul_f32 v[4:5], v[4:5], v[22:23]
	v_add_f32_e32 v19, 1.0, v19
	v_rcp_f32_e32 v19, v19
	v_cvt_pk_bf16_f32 v2, v2, v3
	v_pk_mul_f32 v[18:19], v[18:19], v[20:21]
	s_nop 0
	v_pk_mul_f32 v[4:5], v[4:5], v[18:19]
	s_nop 0
	v_cvt_pk_bf16_f32 v3, v4, v5
	ds_write_b64 v28, v[2:3]
	v_bitop3_b32 v2, v35, s18, v46 bitop3:0x36
	v_lshl_add_u32 v4, v2, 4, v47
	v_add_u32_e32 v24, s71, v4
	v_add_u32_e32 v4, s91, v4
	ds_read_b64 v[2:3], v24
	ds_read_b64 v[4:5], v4
	s_waitcnt lgkmcnt(1)
; #define LAS __attribute__((address_space(3)))
; __device__ __forceinline__ float bflo(unsigned w) { return __uint_as_float(w << 16); }
; __device__ __forceinline__ float bfhi(unsigned w) { return __uint_as_float(w & 0xffff0000u); }
; __device__ __forceinline__ unsigned pk2(float lo, float hi) { const f32x2v v = {lo, hi}; return __builtin_bit_cast(unsigned, __builtin_convertvector(v, bf16x2v)); }
; __device__ __forceinline__ float silu_f(float g) { return g * fast_rcp(1.f + fast_exp2(-g * LOG2E)); }
; __device__ __forceinline__ void gmlp_item(LAS unsigned char* lds, const bf16_t* Zt  , bf16_t* BRt  , const bf16_t* wsb, const float* bs_, const float* lng, const float* lnb, const int tid) {
;     ...
;         { const int t = 32 * tt + r2; const float bsv = bs_[g * 128 + t];
; #pragma unroll
;           for (int k8 = 0; k8 < 8; ++k8) { const int cc = k8 >> 2, q4 = k8 & 3;
;               const unsigned ad = off_b(t, 4 * (2 * cp + cc) + q4) + 8u * h2;
;               const u32x2 uw = *(const LAS u32x2*)(lds + 65536 + ad), gw = *(const LAS u32x2*)(lds + 98304 + ad);
;               const float v0 = bflo(uw.x) * (acc[cc][4 * q4 + 0] + bsv) * silu_f(bflo(gw.x)), v1 = bfhi(uw.x) * (acc[cc][4 * q4 + 1] + bsv) * silu_f(bfhi(gw.x));
;               const float v2 = bflo(uw.y) * (acc[cc][4 * q4 + 2] + bsv) * silu_f(bflo(gw.y)), v3 = bfhi(uw.y) * (acc[cc][4 * q4 + 3] + bsv) * silu_f(bfhi(gw.y));
;               u32x2 w; w.x = pk2(v0, v1); w.y = pk2(v2, v3);
;               *(LAS u32x2*)(lds + 65536 + ad) = w; } }
;         __syncthreads();
;     }
;     { const int ch = tid & 15, t0 = tid >> 4;
; #pragma unroll
;       for (int i = 0; i < 4; ++i) { const int t = t0 + 32 * i; const u32x4 ov = *(const LAS u32x4*)(lds + 65536 + off_b(t, ch)); *(u32x4*)(BRt + (size_t)t * DM + 11 * 128 + 8 * ch) = ov; } }
	v_lshlrev_b32_e32 v22, 16, v2
	s_waitcnt lgkmcnt(0)
	v_lshlrev_b32_e32 v18, 16, v4
	v_and_b32_e32 v19, 0xffff0000, v4
	v_mul_f32_e32 v4, 0xbfb8aa3b, v18
	v_and_b32_e32 v23, 0xffff0000, v2
	v_mul_f32_e32 v2, 0xbfb8aa3b, v19
	v_exp_f32_e32 v4, v4
	v_exp_f32_e32 v2, v2
	v_pk_mul_f32 v[6:7], v[6:7], v[22:23]
	v_add_f32_e32 v4, 1.0, v4
	v_add_f32_e32 v2, 1.0, v2
	v_rcp_f32_e32 v20, v4
	v_rcp_f32_e32 v21, v2
	v_lshlrev_b32_e32 v4, 16, v5
	v_and_b32_e32 v5, 0xffff0000, v5
	v_mul_f32_e32 v2, 0xbfb8aa3b, v4
	v_pk_mul_f32 v[18:19], v[20:21], v[18:19]
	v_exp_f32_e32 v2, v2
	v_pk_mul_f32 v[6:7], v[6:7], v[18:19]
	v_lshlrev_b32_e32 v18, 16, v3
	v_and_b32_e32 v19, 0xffff0000, v3
	v_mul_f32_e32 v3, 0xbfb8aa3b, v5
	v_exp_f32_e32 v3, v3
	v_add_f32_e32 v2, 1.0, v2
	v_rcp_f32_e32 v2, v2
	v_pk_mul_f32 v[8:9], v[8:9], v[18:19]
	v_add_f32_e32 v3, 1.0, v3
	v_rcp_f32_e32 v3, v3
	s_nop 0
	v_pk_mul_f32 v[2:3], v[2:3], v[4:5]
	s_nop 0
	v_pk_mul_f32 v[2:3], v[8:9], v[2:3]
	v_cvt_pk_bf16_f32 v4, v6, v7
	v_cvt_pk_bf16_f32 v5, v2, v3
	v_bitop3_b32 v2, v35, s19, v46 bitop3:0x36
	ds_write_b64 v24, v[4:5]
	v_lshl_add_u32 v4, v2, 4, v47
	v_add_u32_e32 v20, s71, v4
	v_add_u32_e32 v4, s91, v4
	ds_read_b64 v[2:3], v20
	ds_read_b64 v[4:5], v4
	s_waitcnt lgkmcnt(1)
	v_lshlrev_b32_e32 v18, 16, v2
	s_waitcnt lgkmcnt(0)
	v_lshlrev_b32_e32 v6, 16, v4
	v_and_b32_e32 v7, 0xffff0000, v4
	v_mul_f32_e32 v4, 0xbfb8aa3b, v6
	v_and_b32_e32 v19, 0xffff0000, v2
	v_mul_f32_e32 v2, 0xbfb8aa3b, v7
	v_exp_f32_e32 v4, v4
	v_exp_f32_e32 v2, v2
	v_pk_mul_f32 v[10:11], v[10:11], v[18:19]
	v_add_f32_e32 v4, 1.0, v4
	v_add_f32_e32 v2, 1.0, v2
	v_rcp_f32_e32 v8, v4
	v_rcp_f32_e32 v9, v2
	v_lshlrev_b32_e32 v4, 16, v5
	v_and_b32_e32 v5, 0xffff0000, v5
	v_mul_f32_e32 v2, 0xbfb8aa3b, v4
	v_pk_mul_f32 v[6:7], v[8:9], v[6:7]
	v_lshlrev_b32_e32 v8, 16, v3
	v_and_b32_e32 v9, 0xffff0000, v3
	v_mul_f32_e32 v3, 0xbfb8aa3b, v5
	v_exp_f32_e32 v2, v2
	v_exp_f32_e32 v3, v3
	v_pk_mul_f32 v[6:7], v[10:11], v[6:7]
	v_pk_add_f32 v[10:11], v[12:13], v[34:35] op_sel_hi:[1,0]
	v_add_f32_e32 v2, 1.0, v2
	v_add_f32_e32 v3, 1.0, v3
	v_rcp_f32_e32 v2, v2
	v_rcp_f32_e32 v3, v3
	v_pk_mul_f32 v[8:9], v[10:11], v[8:9]
	v_pk_add_f32 v[12:13], v[14:15], v[34:35] op_sel_hi:[1,0]
	v_pk_mul_f32 v[2:3], v[2:3], v[4:5]
	s_nop 0
	v_pk_mul_f32 v[2:3], v[8:9], v[2:3]
	v_cvt_pk_bf16_f32 v4, v6, v7
	v_cvt_pk_bf16_f32 v5, v2, v3
	v_bitop3_b32 v2, v35, s26, v46 bitop3:0x36
	ds_write_b64 v20, v[4:5]
	v_lshl_add_u32 v4, v2, 4, v47
	v_add_u32_e32 v18, s71, v4
	v_add_u32_e32 v4, s91, v4
	ds_read_b64 v[2:3], v18
	ds_read_b64 v[4:5], v4
	s_waitcnt lgkmcnt(1)
	v_lshlrev_b32_e32 v10, 16, v2
	s_waitcnt lgkmcnt(0)
	v_lshlrev_b32_e32 v6, 16, v4
	v_and_b32_e32 v7, 0xffff0000, v4
	v_mul_f32_e32 v4, 0xbfb8aa3b, v6
	v_and_b32_e32 v11, 0xffff0000, v2
	v_mul_f32_e32 v2, 0xbfb8aa3b, v7
	v_exp_f32_e32 v4, v4
	v_exp_f32_e32 v2, v2
	v_pk_mul_f32 v[10:11], v[12:13], v[10:11]
	v_add_f32_e32 v4, 1.0, v4
	v_add_f32_e32 v2, 1.0, v2
	v_rcp_f32_e32 v8, v4
	v_rcp_f32_e32 v9, v2
	v_lshlrev_b32_e32 v4, 16, v5
	v_and_b32_e32 v5, 0xffff0000, v5
	v_mul_f32_e32 v2, 0xbfb8aa3b, v4
	v_pk_mul_f32 v[6:7], v[8:9], v[6:7]
	v_lshlrev_b32_e32 v8, 16, v3
	v_and_b32_e32 v9, 0xffff0000, v3
	v_mul_f32_e32 v3, 0xbfb8aa3b, v5
	v_exp_f32_e32 v2, v2
	v_exp_f32_e32 v3, v3
	v_pk_mul_f32 v[6:7], v[10:11], v[6:7]
	v_pk_add_f32 v[10:11], v[16:17], v[34:35] op_sel_hi:[1,0]
	v_add_f32_e32 v2, 1.0, v2
	v_add_f32_e32 v3, 1.0, v3
	v_rcp_f32_e32 v2, v2
	v_rcp_f32_e32 v3, v3
	v_pk_mul_f32 v[8:9], v[10:11], v[8:9]
	v_pk_mul_f32 v[2:3], v[2:3], v[4:5]
	s_nop 0
	v_pk_mul_f32 v[2:3], v[8:9], v[2:3]
	v_cvt_pk_bf16_f32 v4, v6, v7
	v_cvt_pk_bf16_f32 v5, v2, v3
	ds_write_b64 v18, v[4:5]
	s_waitcnt lgkmcnt(0)
	s_barrier
	s_cbranch_scc1 .LBB0_90
	s_lshl_b64 s[10:11], s[8:9], 19
	ds_read_b128 v[2:5], v196
	s_add_u32 s10, s93, s10
	s_addc_u32 s11, s95, s11
	v_lshl_add_u64 v[6:7], s[10:11], 0, v[98:99]
	v_lshl_add_u64 v[6:7], v[6:7], 0, v[0:1]
	s_waitcnt lgkmcnt(0)
	global_store_dwordx4 v[6:7], v[2:5], off offset:2816
	ds_read_b128 v[2:5], v197
	v_lshl_add_u64 v[6:7], s[10:11], 0, v[100:101]
	v_lshl_add_u64 v[6:7], v[6:7], 0, v[0:1]
	v_readlane_b32 s12, v252, 37
	v_readlane_b32 s13, v252, 38
	s_waitcnt lgkmcnt(0)
	global_store_dwordx4 v[6:7], v[2:5], off offset:2816
	ds_read_b128 v[2:5], v198
	v_lshl_add_u64 v[6:7], s[10:11], 0, v[102:103]
	v_lshl_add_u64 v[6:7], v[6:7], 0, v[0:1]
	s_add_i32 s8, s8, s64
	v_lshl_add_u64 v[106:107], v[106:107], 0, s[12:13]
	s_waitcnt lgkmcnt(0)
	global_store_dwordx4 v[6:7], v[2:5], off offset:2816
	ds_read_b128 v[2:5], v199
	v_lshl_add_u64 v[6:7], s[10:11], 0, v[104:105]
	v_readlane_b32 s10, v252, 58
	v_readlane_b32 s11, v252, 59
	v_lshl_add_u64 v[108:109], v[108:109], 0, s[12:13]
	s_cmpk_gt_i32 s8, 0xff
	v_lshl_add_u64 v[6:7], v[6:7], 0, v[0:1]
	v_lshl_add_u64 v[112:113], v[112:113], 0, s[10:11]
	s_waitcnt lgkmcnt(0)
	global_store_dwordx4 v[6:7], v[2:5], off offset:2816
	s_cbranch_scc0 .LBB0_79

; template <int MODE>
; __device__ __forceinline__ void attn_item(LAS unsigned char* lds, const AttnArgs& a, const int tid) {
;     ...
;     { const bf16_t* qrow = a.Q + (size_t)(qw0 + r) * a.ldq + map * 64 + 8 * h;
; #pragma unroll
;       for (int ks = 0; ks < NKS; ++ks) qf[ks] = *(const bf16x8*)(qrow + 16 * ks); }
;     if (MODE == 1) {
;         LAS float* cl = (LAS float*)(lds + A_CS); LAS float* wtot = (LAS float*)(lds + A_LUT);
;         const int n = a.q0 + 256; const bool on = 8 * tid < n;
;         float v[8]; float run = 0.f;
;         const float* lp = a.c + 8 * tid;
;         f32x4 x0 = {0.f, 0.f, 0.f, 0.f}, x1 = x0; if (on) { x0 = *(const f32x4*)lp; x1 = *(const f32x4*)(lp + 4); }
; #pragma unroll
;         for (int e = 0; e < 8; ++e) { run += (e < 4) ? x0[e & 3] : x1[e & 3]; v[e] = run; }
;         float incl = run;
; #pragma unroll
;         for (int o = 1; o < 64; o <<= 1) { const float x = __shfl_up(incl, o); if (lane >= o) incl += x; }
;         if (lane == 63) wtot[wave] = incl;
;         __syncthreads();
;         float pre = incl - run;
;         for (int w = 0; w < wave; ++w) pre += wtot[w];
;         if (on) {
; #pragma unroll
;             for (int e = 0; e < 8; ++e) cl[8 * tid + e] = -(pre + v[e]) * LOG2E; }
;     }
;     unsigned kaddr[NKS];
;     { const unsigned X = ((r & 3u) << 2) | ((r >> 2) & 3u);
; #pragma unroll
;       for (int ks = 0; ks < NKS; ++ks) kaddr[ks] = 256u * r + 16u * ((unsigned)(2 * (map * 4 + ks) + h) ^ X); }
;     unsigned vaddr[4][2];
;     { const unsigned q = (lane & 15) >> 2, p = lane & 3, blk = (lane >> 4) & 1;
; #pragma unroll
; __global__ void __launch_bounds__(512) mk_fwd(Params P) {
;     ...
;                     const int qb = it & 15, hm = (it >> 4) & 3, b = it >> 6;
;                     const bf16_t* Zb = Z + (size_t)b * SEQ * NZ;
;                     AttnArgs a; a.Q = Zb + memq_off + hm * 128; a.K = KVM + (size_t)b * NMEM * 4096 + L * 1024 + hm * 128; a.V = a.K + 512; a.G = Zb + gate_off + 1536 + hm * 128;
;                     a.O = BR + (size_t)b * SEQ * DM + 1536 + hm * 128;
;                     a.ldq = NZ; a.ldkv = 4096; a.ldg = NZ; a.ldo = DM; a.q0 = 256 * qb; a.ntiles = 4; a.c = nullptr; a.lutsrc = nullptr; a.subg = nullptr;
;                     a.sc = 0.08838834764831845f * LOG2E; a.lam = 0.f; a.outmul = 1.f; a.m2 = m2_mem;
;                     attn_item<0>(lds, a, tid);
.LBB0_94:
	s_ashr_i32 s4, s18, 6
	s_mul_hi_i32 s7, s12, s4
	s_mul_i32 s6, s12, s4
	s_ashr_i32 s5, s4, 31
	s_lshl_b64 s[6:7], s[6:7], 1
	s_add_u32 s26, s15, s6
	s_addc_u32 s27, s16, s7
	s_lshl_b32 s6, s18, 3
	s_and_b32 s28, s6, 0x180
	s_lshl_b32 s10, s28, 1
	s_add_u32 s6, s26, s10
	s_addc_u32 s7, s27, 0
	s_lshl_b64 s[8:9], s[4:5], 21
	s_add_u32 s8, s13, s8
	s_addc_u32 s9, s14, s9
	s_add_u32 s8, s8, s10
	s_addc_u32 s9, s9, 0
	s_lshl_b32 s10, s18, 8
	s_and_b32 s19, s10, 0xf00
	v_readfirstlane_b32 s10, v180
	s_ashr_i32 s30, s10, 6
	s_lshl_b32 s29, s30, 5
	v_or_b32_e32 v2, s19, v142
	v_add_u32_e32 v2, s29, v2
	v_mad_i64_i32 v[2:3], s[10:11], v2, s67, 0
	v_lshl_add_u64 v[2:3], v[2:3], 1, s[6:7]
	v_lshl_add_u64 v[2:3], v[2:3], 0, v[0:1]
	s_barrier
	global_load_dwordx4 v[98:101], v[2:3], off
	global_load_dwordx4 v[102:105], v[2:3], off offset:32
	global_load_dwordx4 v[106:109], v[2:3], off offset:64
	global_load_dwordx4 v[110:113], v[2:3], off offset:96
	global_load_dwordx4 v[114:117], v[2:3], off offset:128
	global_load_dwordx4 v[118:121], v[2:3], off offset:160
	global_load_dwordx4 v[122:125], v[2:3], off offset:192
	global_load_dwordx4 v[126:129], v[2:3], off offset:224
	v_lshl_or_b32 v4, s30, 2, v145
	s_and_b32 s6, s30, 3
	v_ashrrev_i32_e32 v5, 31, v4
	v_bitop3_b32 v6, s6, v144, v146 bitop3:0x36
	v_lshlrev_b64 v[4:5], 13, v[4:5]
	v_lshl_or_b32 v4, v6, 4, v4
	s_lshl_b32 s6, s30, 10
	v_lshl_add_u64 v[130:131], s[8:9], 0, v[4:5]
	s_add_i32 s30, s6, 0
	s_mov_b32 m0, s30
	s_nop 0
	global_load_lds_dwordx4 v[130:131], off
	s_mov_b64 s[10:11], 0x40000
	s_mov_b64 s[0:1], 0x400
	v_lshl_add_u64 v[2:3], v[130:131], 0, s[10:11]
	s_add_i32 s31, s30, 0x2000
	s_mov_b32 m0, s31
	s_nop 0
	global_load_lds_dwordx4 v[2:3], off
	v_lshl_add_u64 v[4:5], v[130:131], 0, s[0:1]
	s_add_i32 s34, s30, 0x4000
	s_mov_b32 m0, s34
	s_nop 0
	global_load_lds_dwordx4 v[4:5], off
	s_mov_b64 s[0:1], 0x40400
	s_mov_b64 s[6:7], 0x100000
	v_lshl_add_u64 v[2:3], v[130:131], 0, s[0:1]
	s_add_i32 s35, s30, 0x6000
	s_mov_b32 m0, s35
	s_nop 0
	global_load_lds_dwordx4 v[2:3], off
	v_lshl_add_u64 v[132:133], v[130:131], 0, s[6:7]
	s_mov_b64 s[6:7], 0x100400
	s_waitcnt vmcnt(0)
	v_lshl_add_u64 v[134:135], v[130:131], 0, s[6:7]
	s_mov_b64 s[6:7], 0x140000
	v_lshl_add_u64 v[136:137], v[130:131], 0, s[6:7]
	s_mov_b64 s[6:7], 0x140400
	v_mov_b32_e32 v140, 0
	s_add_i32 s36, s30, 0x8000
	s_add_i32 s37, s30, 0xa000
	s_add_i32 s38, s30, 0xc000
	s_add_i32 s39, s30, 0xe000
	v_lshl_add_u64 v[138:139], v[130:131], 0, s[6:7]
	s_mov_b64 s[8:9], -1
	v_mov_b32_e32 v2, 0
	v_mov_b32_e32 v3, v140
	v_mov_b32_e32 v4, v140
	v_mov_b32_e32 v5, v140
	v_mov_b32_e32 v6, v140
	v_mov_b32_e32 v7, v140
	v_mov_b32_e32 v8, v140
	v_mov_b32_e32 v9, v140
	v_mov_b32_e32 v10, v140
	v_mov_b32_e32 v11, v140
	v_mov_b32_e32 v12, v140
	v_mov_b32_e32 v13, v140
	v_mov_b32_e32 v14, v140
	v_mov_b32_e32 v15, v140
	v_mov_b32_e32 v16, v140
	v_mov_b32_e32 v17, v140
	v_mov_b32_e32 v18, 0
	v_mov_b32_e32 v19, v140
	v_mov_b32_e32 v20, v140
	v_mov_b32_e32 v21, v140
	v_mov_b32_e32 v22, v140
	v_mov_b32_e32 v23, v140
	v_mov_b32_e32 v24, v140
	v_mov_b32_e32 v25, v140
	v_mov_b32_e32 v26, v140
	v_mov_b32_e32 v27, v140
	v_mov_b32_e32 v28, v140
	v_mov_b32_e32 v29, v140
	v_mov_b32_e32 v30, v140
	v_mov_b32_e32 v31, v140
	v_mov_b32_e32 v32, v140
	v_mov_b32_e32 v33, v140
	v_mov_b32_e32 v34, 0
	v_mov_b32_e32 v35, v140
	v_mov_b32_e32 v36, v140
	v_mov_b32_e32 v37, v140
	v_mov_b32_e32 v38, v140
	v_mov_b32_e32 v39, v140
	v_mov_b32_e32 v40, v140
	v_mov_b32_e32 v41, v140
	v_mov_b32_e32 v42, v140
	v_mov_b32_e32 v43, v140
	v_mov_b32_e32 v44, v140
	v_mov_b32_e32 v45, v140
	v_mov_b32_e32 v46, v140
	v_mov_b32_e32 v47, v140
	v_mov_b32_e32 v48, v140
	v_mov_b32_e32 v49, v140
	v_mov_b32_e32 v50, 0
	v_mov_b32_e32 v51, v140
	v_mov_b32_e32 v52, v140
	v_mov_b32_e32 v53, v140
	v_mov_b32_e32 v54, v140
	v_mov_b32_e32 v55, v140
	v_mov_b32_e32 v56, v140
	v_mov_b32_e32 v57, v140
	v_mov_b32_e32 v58, v140
	v_mov_b32_e32 v59, v140
	v_mov_b32_e32 v60, v140
	v_mov_b32_e32 v61, v140
	v_mov_b32_e32 v62, v140
	v_mov_b32_e32 v63, v140
	v_mov_b32_e32 v64, v140
	v_mov_b32_e32 v65, v140
	s_waitcnt lgkmcnt(0)
	s_barrier
	s_waitcnt vmcnt(0)
	s_branch .LBB0_96

; #define LAS __attribute__((address_space(3)))
; __device__ __forceinline__ float bflo(unsigned w) { return __uint_as_float(w << 16); }
; __device__ __forceinline__ float bfhi(unsigned w) { return __uint_as_float(w & 0xffff0000u); }
; __device__ __forceinline__ unsigned pk2(float lo, float hi) { const f32x2v v = {lo, hi}; return __builtin_bit_cast(unsigned, __builtin_convertvector(v, bf16x2v)); }
; __device__ __forceinline__ float silu_f(float g) { return g * fast_rcp(1.f + fast_exp2(-g * LOG2E)); }
; template <int MODE>
; __device__ __forceinline__ void attn_item(LAS unsigned char* lds, const AttnArgs& a, const int tid) {
;     ...
;     l += __shfl_xor(l, 32);
;     const float inv = 1.f / l;
;     const size_t qrow = (size_t)(qw0 + r);
;     if (MODE != 2) {
;         int ch = tid & 15, r0 = tid >> 4, lrow = 32 * wave + r, hh = h;
;         asm volatile("" : "+v"(ch), "+v"(r0), "+v"(lrow), "+v"(hh));
; #pragma unroll 1
;         for (int i0 = 0; i0 < 8; i0 += 4) { u32x4 gv[4];
; #pragma unroll
;           for (int i = 0; i < 4; ++i) gv[i] = *(const u32x4*)(a.G + (size_t)(a.q0 + r0 + 32 * (i0 + i)) * a.ldg + 8 * ch);
; #pragma unroll
;           for (int i = 0; i < 4; ++i) *(LAS u32x4*)(lds + off_b(r0 + 32 * (i0 + i), ch)) = gv[i]; }
;         __syncthreads();
; #pragma unroll
;         for (int dt = 0; dt < 4; ++dt)
; #pragma unroll
;             for (int g = 0; g < 4; ++g) { const unsigned ad = off_b(lrow, 4 * dt + g) + 8u * hh;
;                 const u32x2 gw = *(const LAS u32x2*)(lds + ad);
;                 const float v0 = o[dt][4 * g + 0] * inv * silu_f(bflo(gw.x)), v1 = o[dt][4 * g + 1] * inv * silu_f(bfhi(gw.x));
;                 const float v2 = o[dt][4 * g + 2] * inv * silu_f(bflo(gw.y)), v3 = o[dt][4 * g + 3] * inv * silu_f(bfhi(gw.y));
;                 u32x2 w; w.x = pk2(v0, v1); w.y = pk2(v2, v3);
;                 *(LAS u32x2*)(lds + ad) = w; }
.LBB0_99:
	v_cndmask_b32_e64 v78, 0, 1, s[6:7]
	s_or_b32 s10, s9, 1
	v_cmp_ne_u32_e32 vcc, 1, v78
	v_lshl_add_u32 v78, s9, 5, v77
	s_or_b32 s11, s9, 2
	v_mad_i64_i32 v[78:79], s[6:7], v78, s67, 0
	v_lshl_add_u32 v82, s10, 5, v77
	s_or_b32 s19, s9, 3
	v_lshl_add_u64 v[78:79], v[78:79], 1, v[68:69]
	v_mad_i64_i32 v[82:83], s[6:7], v82, s67, 0
	v_lshl_add_u32 v86, s11, 5, v77
	global_load_dwordx4 v[78:81], v[78:79], off offset:3072
	v_lshl_add_u64 v[82:83], v[82:83], 1, v[68:69]
	v_mad_i64_i32 v[86:87], s[6:7], v86, s67, 0
	v_lshl_add_u32 v90, s19, 5, v77
	global_load_dwordx4 v[82:85], v[82:83], off offset:3072
	v_lshl_add_u64 v[86:87], v[86:87], 1, v[68:69]
	v_mad_i64_i32 v[90:91], s[6:7], v90, s67, 0
	global_load_dwordx4 v[86:89], v[86:87], off offset:3072
	v_lshl_add_u64 v[90:91], v[90:91], 1, v[68:69]
	global_load_dwordx4 v[90:93], v[90:91], off offset:3072
	v_lshl_add_u32 v94, s9, 13, v76
	s_mov_b32 s9, 4
	s_mov_b64 s[6:7], 0
	s_and_b64 vcc, exec, vcc
	s_waitcnt vmcnt(0) lgkmcnt(0)
	ds_write_b128 v94, v[78:81]
	v_lshl_add_u32 v78, s10, 13, v76
	ds_write_b128 v78, v[82:85]
	v_lshl_add_u32 v78, s11, 13, v76
	ds_write_b128 v78, v[86:89]
	v_lshl_add_u32 v78, s19, 13, v76
	ds_write_b128 v78, v[90:93]
	s_cbranch_vccz .LBB0_99
	s_and_b32 s6, s17, 0xf00
	s_lshl_b64 s[4:5], s[4:5], 24
	s_add_u32 s4, s93, s4
	s_addc_u32 s5, s95, s5
	v_add_f32_e32 v68, v140, v75
	s_add_u32 s4, s4, s8
	v_div_scale_f32 v69, s[8:9], v68, v68, 1.0
	v_rcp_f32_e32 v75, v69
	v_lshlrev_b32_e32 v74, 3, v74
	s_waitcnt lgkmcnt(0)
	s_barrier
	v_fma_f32 v76, -v69, v75, 1.0
	v_fmac_f32_e32 v75, v76, v75
	v_div_scale_f32 v76, vcc, 1.0, v68, 1.0
	v_mul_f32_e32 v77, v76, v75
	v_fma_f32 v78, -v69, v77, v76
	v_fmac_f32_e32 v77, v78, v75
	v_fma_f32 v69, -v69, v77, v76
	v_div_fmas_f32 v69, v69, v75, v77
	v_div_fixup_f32 v68, v69, v68, 1.0
	v_lshlrev_b32_e32 v69, 8, v73
	v_lshlrev_b32_e32 v75, 2, v73
	v_bfe_u32 v73, v73, 2, 2
	v_and_or_b32 v73, v75, 12, v73
	v_add3_u32 v69, 0, v69, v74
	v_lshlrev_b32_e32 v73, 4, v73
	v_add_u32_e32 v80, v69, v73
	ds_read_b64 v[74:75], v80
	v_pk_mul_f32 v[50:51], v[50:51], v[68:69] op_sel_hi:[1,0]
	v_pk_mul_f32 v[52:53], v[52:53], v[68:69] op_sel_hi:[1,0]
	v_pk_mul_f32 v[54:55], v[54:55], v[68:69] op_sel_hi:[1,0]
	v_pk_mul_f32 v[56:57], v[56:57], v[68:69] op_sel_hi:[1,0]
	s_waitcnt lgkmcnt(0)
	v_lshlrev_b32_e32 v76, 16, v74
	v_and_b32_e32 v77, 0xffff0000, v74
	v_mul_f32_e32 v74, 0xbfb8aa3b, v76
	v_exp_f32_e32 v74, v74
	v_pk_mul_f32 v[34:35], v[34:35], v[68:69] op_sel_hi:[1,0]
	v_pk_mul_f32 v[36:37], v[36:37], v[68:69] op_sel_hi:[1,0]
	v_pk_mul_f32 v[38:39], v[38:39], v[68:69] op_sel_hi:[1,0]
	v_add_f32_e32 v74, 1.0, v74
	v_rcp_f32_e32 v78, v74
	v_mul_f32_e32 v74, 0xbfb8aa3b, v77
	v_exp_f32_e32 v74, v74
	v_pk_mul_f32 v[40:41], v[40:41], v[68:69] op_sel_hi:[1,0]
	v_pk_mul_f32 v[18:19], v[18:19], v[68:69] op_sel_hi:[1,0]
	v_pk_mul_f32 v[20:21], v[20:21], v[68:69] op_sel_hi:[1,0]
	v_add_f32_e32 v74, 1.0, v74
	v_rcp_f32_e32 v79, v74
	v_lshlrev_b32_e32 v74, 16, v75
	v_and_b32_e32 v75, 0xffff0000, v75
	v_pk_mul_f32 v[22:23], v[22:23], v[68:69] op_sel_hi:[1,0]
	v_pk_mul_f32 v[76:77], v[78:79], v[76:77]
	v_pk_mul_f32 v[24:25], v[24:25], v[68:69] op_sel_hi:[1,0]
	v_pk_mul_f32 v[50:51], v[50:51], v[76:77]
	v_mul_f32_e32 v76, 0xbfb8aa3b, v74
	v_mul_f32_e32 v77, 0xbfb8aa3b, v75
	v_exp_f32_e32 v76, v76
	v_exp_f32_e32 v77, v77
	v_cvt_pk_bf16_f32 v50, v50, v51
	v_pk_mul_f32 v[2:3], v[2:3], v[68:69] op_sel_hi:[1,0]
	v_add_f32_e32 v76, 1.0, v76
	v_add_f32_e32 v77, 1.0, v77
	v_rcp_f32_e32 v76, v76
	v_rcp_f32_e32 v77, v77
	v_pk_mul_f32 v[4:5], v[4:5], v[68:69] op_sel_hi:[1,0]
	v_pk_mul_f32 v[6:7], v[6:7], v[68:69] op_sel_hi:[1,0]
	v_pk_mul_f32 v[8:9], v[8:9], v[68:69] op_sel_hi:[1,0]
	v_pk_mul_f32 v[74:75], v[76:77], v[74:75]
	v_xad_u32 v76, v73, 16, v69
	v_pk_mul_f32 v[52:53], v[52:53], v[74:75]
	s_movk_i32 s7, 0xe0
	v_cvt_pk_bf16_f32 v51, v52, v53
	ds_write_b64 v80, v[50:51]
	ds_read_b64 v[50:51], v76
	s_addc_u32 s5, s5, 0
	s_waitcnt lgkmcnt(0)
	v_lshlrev_b32_e32 v52, 16, v50
	v_and_b32_e32 v53, 0xffff0000, v50
	v_mul_f32_e32 v50, 0xbfb8aa3b, v52
	v_exp_f32_e32 v50, v50
	s_nop 0
	v_add_f32_e32 v50, 1.0, v50
	v_rcp_f32_e32 v74, v50
	v_mul_f32_e32 v50, 0xbfb8aa3b, v53
	v_exp_f32_e32 v50, v50
	s_nop 0
	v_add_f32_e32 v50, 1.0, v50
	v_rcp_f32_e32 v75, v50
	v_lshlrev_b32_e32 v50, 16, v51
	v_and_b32_e32 v51, 0xffff0000, v51
	v_pk_mul_f32 v[52:53], v[74:75], v[52:53]
	s_nop 0
	v_pk_mul_f32 v[52:53], v[54:55], v[52:53]
	v_mul_f32_e32 v54, 0xbfb8aa3b, v50
	v_mul_f32_e32 v55, 0xbfb8aa3b, v51
	v_exp_f32_e32 v54, v54
	v_exp_f32_e32 v55, v55
	v_cvt_pk_bf16_f32 v52, v52, v53
	v_xad_u32 v74, v73, 32, v69
	v_add_f32_e32 v54, 1.0, v54
	v_add_f32_e32 v55, 1.0, v55
	v_rcp_f32_e32 v54, v54
	v_rcp_f32_e32 v55, v55
	s_nop 0
	v_pk_mul_f32 v[50:51], v[54:55], v[50:51]
	s_nop 0
	v_pk_mul_f32 v[50:51], v[56:57], v[50:51]
	v_pk_mul_f32 v[56:57], v[58:59], v[68:69] op_sel_hi:[1,0]
	v_cvt_pk_bf16_f32 v53, v50, v51
	ds_write_b64 v76, v[52:53]
	ds_read_b64 v[50:51], v74
	v_xad_u32 v58, v73, 48, v69
	s_waitcnt lgkmcnt(0)
	v_lshlrev_b32_e32 v52, 16, v50
	v_and_b32_e32 v53, 0xffff0000, v50
	v_mul_f32_e32 v50, 0xbfb8aa3b, v52
	v_exp_f32_e32 v50, v50
	s_nop 0
	v_add_f32_e32 v50, 1.0, v50
	v_rcp_f32_e32 v54, v50
	v_mul_f32_e32 v50, 0xbfb8aa3b, v53
	v_exp_f32_e32 v50, v50
	s_nop 0
	v_add_f32_e32 v50, 1.0, v50
	v_rcp_f32_e32 v55, v50
	v_lshlrev_b32_e32 v50, 16, v51
	v_and_b32_e32 v51, 0xffff0000, v51
	v_pk_mul_f32 v[52:53], v[54:55], v[52:53]
	v_mul_f32_e32 v54, 0xbfb8aa3b, v50
	v_mul_f32_e32 v55, 0xbfb8aa3b, v51
	v_exp_f32_e32 v54, v54
	v_exp_f32_e32 v55, v55
	v_pk_mul_f32 v[52:53], v[56:57], v[52:53]
	v_pk_mul_f32 v[56:57], v[60:61], v[68:69] op_sel_hi:[1,0]
	v_add_f32_e32 v54, 1.0, v54
	v_add_f32_e32 v55, 1.0, v55
	v_rcp_f32_e32 v54, v54
	v_rcp_f32_e32 v55, v55
	v_cvt_pk_bf16_f32 v52, v52, v53
	v_pk_mul_f32 v[50:51], v[54:55], v[50:51]
	s_nop 0
	v_pk_mul_f32 v[50:51], v[56:57], v[50:51]
	v_pk_mul_f32 v[56:57], v[62:63], v[68:69] op_sel_hi:[1,0]
	v_cvt_pk_bf16_f32 v53, v50, v51
	ds_write_b64 v74, v[52:53]
	ds_read_b64 v[50:51], v58
	s_waitcnt lgkmcnt(0)
; #define LAS __attribute__((address_space(3)))
; __device__ __forceinline__ float bflo(unsigned w) { return __uint_as_float(w << 16); }
; __device__ __forceinline__ float bfhi(unsigned w) { return __uint_as_float(w & 0xffff0000u); }
; __device__ __forceinline__ unsigned pk2(float lo, float hi) { const f32x2v v = {lo, hi}; return __builtin_bit_cast(unsigned, __builtin_convertvector(v, bf16x2v)); }
; __device__ __forceinline__ float silu_f(float g) { return g * fast_rcp(1.f + fast_exp2(-g * LOG2E)); }
; template <int MODE>
; __device__ __forceinline__ void attn_item(LAS unsigned char* lds, const AttnArgs& a, const int tid) {
;     ...
;         for (int dt = 0; dt < 4; ++dt)
; #pragma unroll
;             for (int g = 0; g < 4; ++g) { const unsigned ad = off_b(lrow, 4 * dt + g) + 8u * hh;
;                 const u32x2 gw = *(const LAS u32x2*)(lds + ad);
;                 const float v0 = o[dt][4 * g + 0] * inv * silu_f(bflo(gw.x)), v1 = o[dt][4 * g + 1] * inv * silu_f(bfhi(gw.x));
;                 const float v2 = o[dt][4 * g + 2] * inv * silu_f(bflo(gw.y)), v3 = o[dt][4 * g + 3] * inv * silu_f(bfhi(gw.y));
;                 u32x2 w; w.x = pk2(v0, v1); w.y = pk2(v2, v3);
;                 *(LAS u32x2*)(lds + ad) = w; }
	v_lshlrev_b32_e32 v52, 16, v50
	v_and_b32_e32 v53, 0xffff0000, v50
	v_mul_f32_e32 v50, 0xbfb8aa3b, v52
	v_exp_f32_e32 v50, v50
	s_nop 0
	v_add_f32_e32 v50, 1.0, v50
	v_rcp_f32_e32 v54, v50
	v_mul_f32_e32 v50, 0xbfb8aa3b, v53
	v_exp_f32_e32 v50, v50
	s_nop 0
	v_add_f32_e32 v50, 1.0, v50
	v_rcp_f32_e32 v55, v50
	v_lshlrev_b32_e32 v50, 16, v51
	v_and_b32_e32 v51, 0xffff0000, v51
	v_pk_mul_f32 v[52:53], v[54:55], v[52:53]
	v_mul_f32_e32 v54, 0xbfb8aa3b, v50
	v_mul_f32_e32 v55, 0xbfb8aa3b, v51
	v_exp_f32_e32 v54, v54
	v_exp_f32_e32 v55, v55
	v_pk_mul_f32 v[52:53], v[56:57], v[52:53]
	v_pk_mul_f32 v[56:57], v[64:65], v[68:69] op_sel_hi:[1,0]
	v_add_f32_e32 v54, 1.0, v54
	v_add_f32_e32 v55, 1.0, v55
	v_rcp_f32_e32 v54, v54
	v_rcp_f32_e32 v55, v55
	v_cvt_pk_bf16_f32 v52, v52, v53
	v_pk_mul_f32 v[50:51], v[54:55], v[50:51]
	s_nop 0
	v_pk_mul_f32 v[50:51], v[56:57], v[50:51]
	v_xad_u32 v56, v73, 64, v69
	v_cvt_pk_bf16_f32 v53, v50, v51
	ds_write_b64 v58, v[52:53]
	ds_read_b64 v[50:51], v56
	s_waitcnt lgkmcnt(0)
	v_lshlrev_b32_e32 v52, 16, v50
	v_and_b32_e32 v53, 0xffff0000, v50
	v_mul_f32_e32 v50, 0xbfb8aa3b, v52
	v_exp_f32_e32 v50, v50
	s_nop 0
	v_add_f32_e32 v50, 1.0, v50
	v_rcp_f32_e32 v54, v50
	v_mul_f32_e32 v50, 0xbfb8aa3b, v53
	v_exp_f32_e32 v50, v50
	s_nop 0
	v_add_f32_e32 v50, 1.0, v50
	v_rcp_f32_e32 v55, v50
	v_lshlrev_b32_e32 v50, 16, v51
	v_and_b32_e32 v51, 0xffff0000, v51
	v_pk_mul_f32 v[52:53], v[54:55], v[52:53]
	s_nop 0
	v_pk_mul_f32 v[34:35], v[34:35], v[52:53]
	v_mul_f32_e32 v52, 0xbfb8aa3b, v50
	v_mul_f32_e32 v53, 0xbfb8aa3b, v51
	v_exp_f32_e32 v52, v52
	v_exp_f32_e32 v53, v53
	v_cvt_pk_bf16_f32 v34, v34, v35
	v_add_f32_e32 v52, 1.0, v52
	v_add_f32_e32 v53, 1.0, v53
	v_rcp_f32_e32 v52, v52
	v_rcp_f32_e32 v53, v53
	s_nop 0
	v_pk_mul_f32 v[50:51], v[52:53], v[50:51]
	s_nop 0
	v_pk_mul_f32 v[36:37], v[36:37], v[50:51]
	v_xad_u32 v52, v73, s80, v69
	v_cvt_pk_bf16_f32 v35, v36, v37
	ds_write_b64 v56, v[34:35]
	ds_read_b64 v[34:35], v52
	s_waitcnt lgkmcnt(0)
	v_lshlrev_b32_e32 v36, 16, v34
	v_and_b32_e32 v37, 0xffff0000, v34
	v_mul_f32_e32 v34, 0xbfb8aa3b, v36
	v_exp_f32_e32 v34, v34
	s_nop 0
	v_add_f32_e32 v34, 1.0, v34
	v_rcp_f32_e32 v50, v34
	v_mul_f32_e32 v34, 0xbfb8aa3b, v37
	v_exp_f32_e32 v34, v34
	s_nop 0
	v_add_f32_e32 v34, 1.0, v34
	v_rcp_f32_e32 v51, v34
	v_lshlrev_b32_e32 v34, 16, v35
	v_and_b32_e32 v35, 0xffff0000, v35
	v_pk_mul_f32 v[36:37], v[50:51], v[36:37]
	s_nop 0
	v_pk_mul_f32 v[36:37], v[38:39], v[36:37]
	v_mul_f32_e32 v38, 0xbfb8aa3b, v34
	v_mul_f32_e32 v39, 0xbfb8aa3b, v35
	v_exp_f32_e32 v38, v38
	v_exp_f32_e32 v39, v39
	v_cvt_pk_bf16_f32 v36, v36, v37
	v_xad_u32 v50, v73, s79, v69
	v_add_f32_e32 v38, 1.0, v38
	v_add_f32_e32 v39, 1.0, v39
	v_rcp_f32_e32 v38, v38
	v_rcp_f32_e32 v39, v39
	s_nop 0
	v_pk_mul_f32 v[34:35], v[38:39], v[34:35]
	s_nop 0
	v_pk_mul_f32 v[34:35], v[40:41], v[34:35]
	v_pk_mul_f32 v[40:41], v[42:43], v[68:69] op_sel_hi:[1,0]
	v_cvt_pk_bf16_f32 v37, v34, v35
	ds_write_b64 v52, v[36:37]
	ds_read_b64 v[34:35], v50
	v_xad_u32 v42, v73, s22, v69
	s_waitcnt lgkmcnt(0)
	v_lshlrev_b32_e32 v36, 16, v34
	v_and_b32_e32 v37, 0xffff0000, v34
	v_mul_f32_e32 v34, 0xbfb8aa3b, v36
	v_exp_f32_e32 v34, v34
	s_nop 0
	v_add_f32_e32 v34, 1.0, v34
	v_rcp_f32_e32 v38, v34
	v_mul_f32_e32 v34, 0xbfb8aa3b, v37
	v_exp_f32_e32 v34, v34
	s_nop 0
	v_add_f32_e32 v34, 1.0, v34
	v_rcp_f32_e32 v39, v34
	v_lshlrev_b32_e32 v34, 16, v35
	v_and_b32_e32 v35, 0xffff0000, v35
	v_pk_mul_f32 v[36:37], v[38:39], v[36:37]
	v_mul_f32_e32 v38, 0xbfb8aa3b, v34
	v_mul_f32_e32 v39, 0xbfb8aa3b, v35
	v_exp_f32_e32 v38, v38
	v_exp_f32_e32 v39, v39
	v_pk_mul_f32 v[36:37], v[40:41], v[36:37]
	v_pk_mul_f32 v[40:41], v[44:45], v[68:69] op_sel_hi:[1,0]
	v_add_f32_e32 v38, 1.0, v38
	v_add_f32_e32 v39, 1.0, v39
	v_rcp_f32_e32 v38, v38
	v_rcp_f32_e32 v39, v39
	v_cvt_pk_bf16_f32 v36, v36, v37
	v_pk_mul_f32 v[34:35], v[38:39], v[34:35]
	s_nop 0
	v_pk_mul_f32 v[34:35], v[40:41], v[34:35]
	v_pk_mul_f32 v[40:41], v[46:47], v[68:69] op_sel_hi:[1,0]
	v_cvt_pk_bf16_f32 v37, v34, v35
	ds_write_b64 v50, v[36:37]
	ds_read_b64 v[34:35], v42
	s_waitcnt lgkmcnt(0)
	v_lshlrev_b32_e32 v36, 16, v34
	v_and_b32_e32 v37, 0xffff0000, v34
	v_mul_f32_e32 v34, 0xbfb8aa3b, v36
	v_exp_f32_e32 v34, v34
	s_nop 0
	v_add_f32_e32 v34, 1.0, v34
	v_rcp_f32_e32 v38, v34
	v_mul_f32_e32 v34, 0xbfb8aa3b, v37
	v_exp_f32_e32 v34, v34
	s_nop 0
	v_add_f32_e32 v34, 1.0, v34
	v_rcp_f32_e32 v39, v34
	v_lshlrev_b32_e32 v34, 16, v35
	v_and_b32_e32 v35, 0xffff0000, v35
	v_pk_mul_f32 v[36:37], v[38:39], v[36:37]
	v_mul_f32_e32 v38, 0xbfb8aa3b, v34
	v_mul_f32_e32 v39, 0xbfb8aa3b, v35
	v_exp_f32_e32 v38, v38
	v_exp_f32_e32 v39, v39
	v_pk_mul_f32 v[36:37], v[40:41], v[36:37]
	v_pk_mul_f32 v[40:41], v[48:49], v[68:69] op_sel_hi:[1,0]
	v_add_f32_e32 v38, 1.0, v38
	v_add_f32_e32 v39, 1.0, v39
	v_rcp_f32_e32 v38, v38
	v_rcp_f32_e32 v39, v39
	v_cvt_pk_bf16_f32 v36, v36, v37
	v_pk_mul_f32 v[34:35], v[38:39], v[34:35]
	s_nop 0
	v_pk_mul_f32 v[34:35], v[40:41], v[34:35]
	v_xad_u32 v40, v73, s24, v69
	v_cvt_pk_bf16_f32 v37, v34, v35
	ds_write_b64 v42, v[36:37]
	ds_read_b64 v[34:35], v40
	s_waitcnt lgkmcnt(0)
	v_lshlrev_b32_e32 v36, 16, v34
	v_and_b32_e32 v37, 0xffff0000, v34
	v_mul_f32_e32 v34, 0xbfb8aa3b, v36
	v_exp_f32_e32 v34, v34
	s_nop 0
	v_add_f32_e32 v34, 1.0, v34
	v_rcp_f32_e32 v38, v34
	v_mul_f32_e32 v34, 0xbfb8aa3b, v37
	v_exp_f32_e32 v34, v34
	s_nop 0
	v_add_f32_e32 v34, 1.0, v34
	v_rcp_f32_e32 v39, v34
	v_lshlrev_b32_e32 v34, 16, v35
	v_and_b32_e32 v35, 0xffff0000, v35
	v_pk_mul_f32 v[36:37], v[38:39], v[36:37]
	s_nop 0
	v_pk_mul_f32 v[18:19], v[18:19], v[36:37]
	v_mul_f32_e32 v36, 0xbfb8aa3b, v34
	v_mul_f32_e32 v37, 0xbfb8aa3b, v35
	v_exp_f32_e32 v36, v36
	v_exp_f32_e32 v37, v37
	v_cvt_pk_bf16_f32 v18, v18, v19
	v_add_f32_e32 v36, 1.0, v36
	v_add_f32_e32 v37, 1.0, v37
	v_rcp_f32_e32 v36, v36
	v_rcp_f32_e32 v37, v37
	s_nop 0
	v_pk_mul_f32 v[34:35], v[36:37], v[34:35]
	s_nop 0
	v_pk_mul_f32 v[20:21], v[20:21], v[34:35]
	v_xad_u32 v36, v73, s25, v69
	v_cvt_pk_bf16_f32 v19, v20, v21
	ds_write_b64 v40, v[18:19]
	ds_read_b64 v[18:19], v36
	s_waitcnt lgkmcnt(0)
; #define LAS __attribute__((address_space(3)))
; __device__ __forceinline__ float bflo(unsigned w) { return __uint_as_float(w << 16); }
; __device__ __forceinline__ float bfhi(unsigned w) { return __uint_as_float(w & 0xffff0000u); }
; __device__ __forceinline__ unsigned pk2(float lo, float hi) { const f32x2v v = {lo, hi}; return __builtin_bit_cast(unsigned, __builtin_convertvector(v, bf16x2v)); }
; __device__ __forceinline__ float silu_f(float g) { return g * fast_rcp(1.f + fast_exp2(-g * LOG2E)); }
; template <int MODE>
; __device__ __forceinline__ void attn_item(LAS unsigned char* lds, const AttnArgs& a, const int tid) {
;     ...
;         for (int dt = 0; dt < 4; ++dt)
; #pragma unroll
;             for (int g = 0; g < 4; ++g) { const unsigned ad = off_b(lrow, 4 * dt + g) + 8u * hh;
;                 const u32x2 gw = *(const LAS u32x2*)(lds + ad);
;                 const float v0 = o[dt][4 * g + 0] * inv * silu_f(bflo(gw.x)), v1 = o[dt][4 * g + 1] * inv * silu_f(bfhi(gw.x));
;                 const float v2 = o[dt][4 * g + 2] * inv * silu_f(bflo(gw.y)), v3 = o[dt][4 * g + 3] * inv * silu_f(bfhi(gw.y));
;                 u32x2 w; w.x = pk2(v0, v1); w.y = pk2(v2, v3);
;                 *(LAS u32x2*)(lds + ad) = w; }
	v_lshlrev_b32_e32 v20, 16, v18
	v_and_b32_e32 v21, 0xffff0000, v18
	v_mul_f32_e32 v18, 0xbfb8aa3b, v20
	v_exp_f32_e32 v18, v18
	s_nop 0
	v_add_f32_e32 v18, 1.0, v18
	v_rcp_f32_e32 v34, v18
	v_mul_f32_e32 v18, 0xbfb8aa3b, v21
	v_exp_f32_e32 v18, v18
	s_nop 0
	v_add_f32_e32 v18, 1.0, v18
	v_rcp_f32_e32 v35, v18
	v_lshlrev_b32_e32 v18, 16, v19
	v_and_b32_e32 v19, 0xffff0000, v19
	v_pk_mul_f32 v[20:21], v[34:35], v[20:21]
	s_nop 0
	v_pk_mul_f32 v[20:21], v[22:23], v[20:21]
	v_mul_f32_e32 v22, 0xbfb8aa3b, v18
	v_mul_f32_e32 v23, 0xbfb8aa3b, v19
	v_exp_f32_e32 v22, v22
	v_exp_f32_e32 v23, v23
	v_cvt_pk_bf16_f32 v20, v20, v21
	v_xad_u32 v34, v73, s75, v69
	v_add_f32_e32 v22, 1.0, v22
	v_add_f32_e32 v23, 1.0, v23
	v_rcp_f32_e32 v22, v22
	v_rcp_f32_e32 v23, v23
	s_nop 0
	v_pk_mul_f32 v[18:19], v[22:23], v[18:19]
	s_nop 0
	v_pk_mul_f32 v[18:19], v[24:25], v[18:19]
	v_pk_mul_f32 v[24:25], v[26:27], v[68:69] op_sel_hi:[1,0]
	v_cvt_pk_bf16_f32 v21, v18, v19
	ds_write_b64 v36, v[20:21]
	ds_read_b64 v[18:19], v34
	v_xad_u32 v26, v73, s76, v69
	s_waitcnt lgkmcnt(0)
	v_lshlrev_b32_e32 v20, 16, v18
	v_and_b32_e32 v21, 0xffff0000, v18
	v_mul_f32_e32 v18, 0xbfb8aa3b, v20
	v_exp_f32_e32 v18, v18
	s_nop 0
	v_add_f32_e32 v18, 1.0, v18
	v_rcp_f32_e32 v22, v18
	v_mul_f32_e32 v18, 0xbfb8aa3b, v21
	v_exp_f32_e32 v18, v18
	s_nop 0
	v_add_f32_e32 v18, 1.0, v18
	v_rcp_f32_e32 v23, v18
	v_lshlrev_b32_e32 v18, 16, v19
	v_and_b32_e32 v19, 0xffff0000, v19
	v_pk_mul_f32 v[20:21], v[22:23], v[20:21]
	v_mul_f32_e32 v22, 0xbfb8aa3b, v18
	v_mul_f32_e32 v23, 0xbfb8aa3b, v19
	v_exp_f32_e32 v22, v22
	v_exp_f32_e32 v23, v23
	v_pk_mul_f32 v[20:21], v[24:25], v[20:21]
	v_pk_mul_f32 v[24:25], v[28:29], v[68:69] op_sel_hi:[1,0]
	v_add_f32_e32 v22, 1.0, v22
	v_add_f32_e32 v23, 1.0, v23
	v_rcp_f32_e32 v22, v22
	v_rcp_f32_e32 v23, v23
	v_cvt_pk_bf16_f32 v20, v20, v21
	v_pk_mul_f32 v[18:19], v[22:23], v[18:19]
	s_nop 0
	v_pk_mul_f32 v[18:19], v[24:25], v[18:19]
	v_pk_mul_f32 v[24:25], v[30:31], v[68:69] op_sel_hi:[1,0]
	v_cvt_pk_bf16_f32 v21, v18, v19
	ds_write_b64 v34, v[20:21]
	ds_read_b64 v[18:19], v26
	s_waitcnt lgkmcnt(0)
	v_lshlrev_b32_e32 v20, 16, v18
	v_and_b32_e32 v21, 0xffff0000, v18
	v_mul_f32_e32 v18, 0xbfb8aa3b, v20
	v_exp_f32_e32 v18, v18
	s_nop 0
	v_add_f32_e32 v18, 1.0, v18
	v_rcp_f32_e32 v22, v18
	v_mul_f32_e32 v18, 0xbfb8aa3b, v21
	v_exp_f32_e32 v18, v18
	s_nop 0
	v_add_f32_e32 v18, 1.0, v18
	v_rcp_f32_e32 v23, v18
	v_lshlrev_b32_e32 v18, 16, v19
	v_and_b32_e32 v19, 0xffff0000, v19
	v_pk_mul_f32 v[20:21], v[22:23], v[20:21]
	v_mul_f32_e32 v22, 0xbfb8aa3b, v18
	v_mul_f32_e32 v23, 0xbfb8aa3b, v19
	v_exp_f32_e32 v22, v22
	v_exp_f32_e32 v23, v23
	v_pk_mul_f32 v[20:21], v[24:25], v[20:21]
	v_pk_mul_f32 v[24:25], v[32:33], v[68:69] op_sel_hi:[1,0]
	v_add_f32_e32 v22, 1.0, v22
	v_add_f32_e32 v23, 1.0, v23
	v_rcp_f32_e32 v22, v22
	v_rcp_f32_e32 v23, v23
	v_cvt_pk_bf16_f32 v20, v20, v21
	v_pk_mul_f32 v[18:19], v[22:23], v[18:19]
	s_nop 0
	v_pk_mul_f32 v[18:19], v[24:25], v[18:19]
	v_xad_u32 v24, v73, s77, v69
	v_cvt_pk_bf16_f32 v21, v18, v19
	ds_write_b64 v26, v[20:21]
	ds_read_b64 v[18:19], v24
	s_waitcnt lgkmcnt(0)
	v_lshlrev_b32_e32 v20, 16, v18
	v_and_b32_e32 v21, 0xffff0000, v18
	v_mul_f32_e32 v18, 0xbfb8aa3b, v20
	v_exp_f32_e32 v18, v18
	s_nop 0
	v_add_f32_e32 v18, 1.0, v18
	v_rcp_f32_e32 v22, v18
	v_mul_f32_e32 v18, 0xbfb8aa3b, v21
	v_exp_f32_e32 v18, v18
	s_nop 0
	v_add_f32_e32 v18, 1.0, v18
	v_rcp_f32_e32 v23, v18
	v_lshlrev_b32_e32 v18, 16, v19
	v_and_b32_e32 v19, 0xffff0000, v19
	v_pk_mul_f32 v[20:21], v[22:23], v[20:21]
	s_nop 0
	v_pk_mul_f32 v[2:3], v[2:3], v[20:21]
	v_mul_f32_e32 v20, 0xbfb8aa3b, v18
	v_mul_f32_e32 v21, 0xbfb8aa3b, v19
	v_exp_f32_e32 v20, v20
	v_exp_f32_e32 v21, v21
	v_cvt_pk_bf16_f32 v2, v2, v3
	v_add_f32_e32 v20, 1.0, v20
	v_add_f32_e32 v21, 1.0, v21
	v_rcp_f32_e32 v20, v20
	v_rcp_f32_e32 v21, v21
	s_nop 0
	v_pk_mul_f32 v[18:19], v[20:21], v[18:19]
	s_nop 0
	v_pk_mul_f32 v[4:5], v[4:5], v[18:19]
	v_xad_u32 v20, v73, s78, v69
	v_cvt_pk_bf16_f32 v3, v4, v5
	ds_write_b64 v24, v[2:3]
	ds_read_b64 v[2:3], v20
	s_waitcnt lgkmcnt(0)
; #define LAS __attribute__((address_space(3)))
; __device__ __forceinline__ float bflo(unsigned w) { return __uint_as_float(w << 16); }
; __device__ __forceinline__ float bfhi(unsigned w) { return __uint_as_float(w & 0xffff0000u); }
; __device__ __forceinline__ unsigned pk2(float lo, float hi) { const f32x2v v = {lo, hi}; return __builtin_bit_cast(unsigned, __builtin_convertvector(v, bf16x2v)); }
; __device__ __forceinline__ float silu_f(float g) { return g * fast_rcp(1.f + fast_exp2(-g * LOG2E)); }
; template <int MODE>
; __device__ __forceinline__ void attn_item(LAS unsigned char* lds, const AttnArgs& a, const int tid) {
;     ...
;         for (int dt = 0; dt < 4; ++dt)
; #pragma unroll
;             for (int g = 0; g < 4; ++g) { const unsigned ad = off_b(lrow, 4 * dt + g) + 8u * hh;
;                 const u32x2 gw = *(const LAS u32x2*)(lds + ad);
;                 const float v0 = o[dt][4 * g + 0] * inv * silu_f(bflo(gw.x)), v1 = o[dt][4 * g + 1] * inv * silu_f(bfhi(gw.x));
;                 const float v2 = o[dt][4 * g + 2] * inv * silu_f(bflo(gw.y)), v3 = o[dt][4 * g + 3] * inv * silu_f(bfhi(gw.y));
;                 u32x2 w; w.x = pk2(v0, v1); w.y = pk2(v2, v3);
;                 *(LAS u32x2*)(lds + ad) = w; }
;         __syncthreads();
; #pragma unroll 4
;         for (int i = 0; i < 8; ++i) { const u32x4 ov = *(const LAS u32x4*)(lds + off_b(r0 + 32 * i, ch)); *(u32x4*)(a.O + (size_t)(a.q0 + r0 + 32 * i) * a.ldo + 8 * ch) = ov; }
; __global__ void __launch_bounds__(512) mk_fwd(Params P) {
;     ...
;                 for (int it = blockIdx.x; it < 512; it += G) {
;                     const int qb = it & 15, hm = (it >> 4) & 3, b = it >> 6;
;                     const bf16_t* Zb = Z + (size_t)b * SEQ * NZ;
;                     AttnArgs a; a.Q = Zb + memq_off + hm * 128; a.K = KVM + (size_t)b * NMEM * 4096 + L * 1024 + hm * 128; a.V = a.K + 512; a.G = Zb + gate_off + 1536 + hm * 128;
;                     a.O = BR + (size_t)b * SEQ * DM + 1536 + hm * 128;
;                     a.ldq = NZ; a.ldkv = 4096; a.ldg = NZ; a.ldo = DM; a.q0 = 256 * qb; a.ntiles = 4; a.c = nullptr; a.lutsrc = nullptr; a.subg = nullptr;
;                     a.sc = 0.08838834764831845f * LOG2E; a.lam = 0.f; a.outmul = 1.f; a.m2 = m2_mem;
;                     attn_item<0>(lds, a, tid);
;                 }
	v_lshlrev_b32_e32 v4, 16, v2
	v_and_b32_e32 v5, 0xffff0000, v2
	v_mul_f32_e32 v2, 0xbfb8aa3b, v4
	v_exp_f32_e32 v2, v2
	s_nop 0
	v_add_f32_e32 v2, 1.0, v2
	v_rcp_f32_e32 v18, v2
	v_mul_f32_e32 v2, 0xbfb8aa3b, v5
	v_exp_f32_e32 v2, v2
	s_nop 0
	v_add_f32_e32 v2, 1.0, v2
	v_rcp_f32_e32 v19, v2
	v_lshlrev_b32_e32 v2, 16, v3
	v_and_b32_e32 v3, 0xffff0000, v3
	v_pk_mul_f32 v[4:5], v[18:19], v[4:5]
	s_nop 0
	v_pk_mul_f32 v[4:5], v[6:7], v[4:5]
	v_mul_f32_e32 v6, 0xbfb8aa3b, v2
	v_mul_f32_e32 v7, 0xbfb8aa3b, v3
	v_exp_f32_e32 v6, v6
	v_exp_f32_e32 v7, v7
	v_cvt_pk_bf16_f32 v4, v4, v5
	v_xad_u32 v18, v73, s7, v69
	v_add_f32_e32 v6, 1.0, v6
	v_add_f32_e32 v7, 1.0, v7
	v_rcp_f32_e32 v6, v6
	v_rcp_f32_e32 v7, v7
	s_movk_i32 s7, 0xf0
	v_pk_mul_f32 v[2:3], v[6:7], v[2:3]
	s_nop 0
	v_pk_mul_f32 v[2:3], v[8:9], v[2:3]
	v_pk_mul_f32 v[8:9], v[10:11], v[68:69] op_sel_hi:[1,0]
	v_cvt_pk_bf16_f32 v5, v2, v3
	ds_write_b64 v20, v[4:5]
	ds_read_b64 v[2:3], v18
	v_xad_u32 v10, v73, s7, v69
	s_waitcnt lgkmcnt(0)
	v_lshlrev_b32_e32 v4, 16, v2
	v_and_b32_e32 v5, 0xffff0000, v2
	v_mul_f32_e32 v2, 0xbfb8aa3b, v4
	v_exp_f32_e32 v2, v2
	s_nop 0
	v_add_f32_e32 v2, 1.0, v2
	v_rcp_f32_e32 v6, v2
	v_mul_f32_e32 v2, 0xbfb8aa3b, v5
	v_exp_f32_e32 v2, v2
	s_nop 0
	v_add_f32_e32 v2, 1.0, v2
	v_rcp_f32_e32 v7, v2
	v_lshlrev_b32_e32 v2, 16, v3
	v_and_b32_e32 v3, 0xffff0000, v3
	v_pk_mul_f32 v[4:5], v[6:7], v[4:5]
	v_mul_f32_e32 v6, 0xbfb8aa3b, v2
	v_mul_f32_e32 v7, 0xbfb8aa3b, v3
	v_exp_f32_e32 v6, v6
	v_exp_f32_e32 v7, v7
	v_pk_mul_f32 v[4:5], v[8:9], v[4:5]
	v_pk_mul_f32 v[8:9], v[12:13], v[68:69] op_sel_hi:[1,0]
	v_add_f32_e32 v6, 1.0, v6
	v_add_f32_e32 v7, 1.0, v7
	v_rcp_f32_e32 v6, v6
	v_rcp_f32_e32 v7, v7
	v_cvt_pk_bf16_f32 v4, v4, v5
	v_pk_mul_f32 v[2:3], v[6:7], v[2:3]
	s_nop 0
	v_pk_mul_f32 v[2:3], v[8:9], v[2:3]
	v_pk_mul_f32 v[8:9], v[14:15], v[68:69] op_sel_hi:[1,0]
	v_cvt_pk_bf16_f32 v5, v2, v3
	ds_write_b64 v18, v[4:5]
	ds_read_b64 v[2:3], v10
	s_waitcnt lgkmcnt(0)
	v_lshlrev_b32_e32 v4, 16, v2
	v_and_b32_e32 v5, 0xffff0000, v2
	v_mul_f32_e32 v2, 0xbfb8aa3b, v4
	v_exp_f32_e32 v2, v2
	s_nop 0
	v_add_f32_e32 v2, 1.0, v2
	v_rcp_f32_e32 v6, v2
	v_mul_f32_e32 v2, 0xbfb8aa3b, v5
	v_exp_f32_e32 v2, v2
	s_nop 0
	v_add_f32_e32 v2, 1.0, v2
	v_rcp_f32_e32 v7, v2
	v_lshlrev_b32_e32 v2, 16, v3
	v_and_b32_e32 v3, 0xffff0000, v3
	v_pk_mul_f32 v[4:5], v[6:7], v[4:5]
	v_mul_f32_e32 v6, 0xbfb8aa3b, v2
	v_mul_f32_e32 v7, 0xbfb8aa3b, v3
	v_exp_f32_e32 v6, v6
	v_exp_f32_e32 v7, v7
	v_pk_mul_f32 v[4:5], v[8:9], v[4:5]
	v_pk_mul_f32 v[8:9], v[16:17], v[68:69] op_sel_hi:[1,0]
	v_add_f32_e32 v6, 1.0, v6
	v_add_f32_e32 v7, 1.0, v7
	v_rcp_f32_e32 v6, v6
	v_rcp_f32_e32 v7, v7
	v_cvt_pk_bf16_f32 v4, v4, v5
	v_pk_mul_f32 v[2:3], v[6:7], v[2:3]
	s_nop 0
	v_pk_mul_f32 v[2:3], v[8:9], v[2:3]
	s_nop 0
	v_cvt_pk_bf16_f32 v5, v2, v3
	ds_write_b64 v10, v[4:5]
	v_lshl_add_u64 v[2:3], v[66:67], 1, s[4:5]
	v_add_u32_e32 v4, s6, v70
	v_add3_u32 v5, v71, v72, 0
	s_mov_b32 s4, 0
	s_waitcnt lgkmcnt(0)
	s_barrier
.LBB0_101:
	ds_read_b128 v[6:9], v5
	v_add_u32_e32 v10, s4, v4
	v_ashrrev_i32_e32 v11, 31, v10
	v_lshlrev_b64 v[12:13], 12, v[10:11]
	v_lshl_add_u64 v[12:13], v[2:3], 0, v[12:13]
	s_waitcnt lgkmcnt(0)
	global_store_dwordx4 v[12:13], v[6:9], off offset:3072
	ds_read_b128 v[6:9], v5 offset:8192
	v_add_u32_e32 v12, 32, v10
	v_ashrrev_i32_e32 v13, 31, v12
	v_lshlrev_b64 v[12:13], 12, v[12:13]
	v_lshl_add_u64 v[12:13], v[2:3], 0, v[12:13]
	s_waitcnt lgkmcnt(0)
	global_store_dwordx4 v[12:13], v[6:9], off offset:3072
	ds_read_b128 v[6:9], v5 offset:16384
	v_add_u32_e32 v12, 64, v10
	v_ashrrev_i32_e32 v13, 31, v12
	v_lshlrev_b64 v[12:13], 12, v[12:13]
	v_lshl_add_u64 v[12:13], v[2:3], 0, v[12:13]
	s_waitcnt lgkmcnt(0)
	global_store_dwordx4 v[12:13], v[6:9], off offset:3072
	ds_read_b128 v[6:9], v5 offset:24576
	v_add_u32_e32 v10, 0x60, v10
	v_ashrrev_i32_e32 v11, 31, v10
	v_lshlrev_b64 v[10:11], 12, v[10:11]
	s_addk_i32 s4, 0x80
	v_lshl_add_u64 v[10:11], v[2:3], 0, v[10:11]
	v_add_u32_e32 v5, 0x8000, v5
	s_cmpk_lg_i32 s4, 0x100
	s_waitcnt lgkmcnt(0)
	global_store_dwordx4 v[10:11], v[6:9], off offset:3072
	s_cbranch_scc1 .LBB0_101
	s_add_i32 s18, s18, s64
	s_add_i32 s17, s17, s96
	s_cmpk_gt_i32 s18, 0x1ff
	s_cbranch_scc0 .LBB0_94

;     __device__ __forceinline__ void operator()(const f32x4 (&acc)[2][2][4][2], const pg8::Unit& u, int wr, int wc, int fr, int fq) const {
;     ...
;         if (kind == 1 && pn == 28) {
;             if (wc == 0) {
; #pragma unroll
;                 for (int ai = 0; ai < 2; ++ai)
; #pragma unroll
;                     for (int m = 0; m < 4; ++m) { const int row = row0 + ai * 128 + m * 16;
; #pragma unroll
;                         for (int n = 0; n < 2; ++n)
; #pragma unroll
;                             for (int j = 0; j < 4; ++j) { const int col = 8 * fq + 4 * n + j;
;                                 if (col < 12) { const float xv = acc[ai][0][m][n][j] * rsqrtf(ssq[row] * (1.f / DM) + EPS) + bfp[col]; LS[((size_t)(row >> 12) * 12 + col) * SEQ + (row & (SEQ - 1))] = fminf(xv, 0.f) - log1pf(expf(-fabsf(xv))); } } }
.LBB0_511:
	v_ashrrev_i32_e32 v0, 12, v154
	v_mul_i32_i24_e32 v80, 12, v0
	v_and_b32_e32 v0, 0xfff, v154
	v_readlane_b32 s0, v250, 17
	v_lshlrev_b32_e32 v68, 3, v179
	v_ashrrev_i32_e32 v155, 31, v154
	v_lshlrev_b32_e32 v0, 2, v0
	v_readlane_b32 s1, v250, 18
	v_lshl_add_u64 v[66:67], v[154:155], 2, s[44:45]
	v_ashrrev_i32_e32 v81, 31, v80
	v_lshl_add_u64 v[78:79], s[0:1], 0, v[0:1]
	v_cmp_gt_i32_e32 vcc, 2, v179
	v_ashrrev_i32_e32 v69, 31, v68
	s_and_saveexec_b64 s[6:7], vcc
	s_cbranch_execz .LBB0_513
	global_load_dword v0, v[66:67], off
	s_waitcnt vmcnt(0) lgkmcnt(0)
	v_fmamk_f32 v0, v0, 0x3a000000, v205
	v_cmp_gt_f32_e64 s[0:1], s68, v0
	v_mul_f32_e32 v70, 0x4b800000, v0
	s_nop 0
	v_cndmask_b32_e64 v0, v0, v70, s[0:1]
	v_rsq_f32_e32 v0, v0
	s_nop 0
	v_mul_f32_e32 v70, 0x45800000, v0
	v_cndmask_b32_e64 v0, v0, v70, s[0:1]
	v_lshl_add_u64 v[70:71], v[68:69], 2, s[60:61]
	global_load_dword v70, v[70:71], off
	s_waitcnt vmcnt(0) lgkmcnt(0)
	v_fmac_f32_e32 v70, v62, v0
	v_mul_f32_e64 v62, |v70|, s88
	v_fma_f32 v71, |v70|, s88, -v62
	v_rndne_f32_e32 v72, v62
	v_fma_f32 v71, |v70|, s89, v71
	v_sub_f32_e32 v62, v62, v72
	v_add_f32_e32 v62, v62, v71
	v_exp_f32_e32 v62, v62
	v_cvt_i32_f32_e32 v71, v72
	v_cmp_ngt_f32_e64 s[0:1], |v70|, s70
	v_min_f32_e32 v0, 0, v70
	v_ldexp_f32 v62, v62, v71
	v_cndmask_b32_e64 v62, 0, v62, s[0:1]
	v_cmp_nlt_f32_e64 s[0:1], |v70|, s90
	s_nop 1
	v_cndmask_b32_e64 v62, v208, v62, s[0:1]
	v_add_f32_e32 v72, 1.0, v62
	v_add_f32_e32 v70, -1.0, v72
	v_sub_f32_e32 v71, v70, v72
	v_add_f32_e32 v71, 1.0, v71
	v_sub_f32_e32 v70, v62, v70
	v_add_f32_e32 v73, v70, v71
	v_frexp_mant_f32_e32 v70, v72
	v_cmp_gt_f32_e64 s[0:1], s3, v70
	v_cvt_f64_f32_e32 v[70:71], v72
	v_frexp_exp_i32_f64_e32 v70, v[70:71]
	v_subbrev_co_u32_e64 v82, s[0:1], 0, v70, s[0:1]
	v_sub_u32_e32 v70, 0, v82
	v_ldexp_f32 v71, v72, v70
	v_add_f32_e32 v72, -1.0, v71
	v_add_f32_e32 v74, 1.0, v71
	v_ldexp_f32 v70, v73, v70
	v_add_f32_e32 v73, 1.0, v72
	v_add_f32_e32 v75, -1.0, v74
	v_sub_f32_e32 v73, v71, v73
	v_sub_f32_e32 v71, v71, v75
	v_add_f32_e32 v73, v70, v73
	v_add_f32_e32 v70, v70, v71
	v_add_f32_e32 v83, v74, v70
	v_rcp_f32_e32 v85, v83
	v_sub_f32_e32 v71, v74, v83
	v_add_f32_e32 v84, v70, v71
	v_add_f32_e32 v71, v72, v73
	v_mul_f32_e32 v87, v71, v85
	v_sub_f32_e32 v70, v72, v71
	v_mul_f32_e32 v72, v83, v87
	v_fma_f32 v74, v87, v83, -v72
	v_fmac_f32_e32 v74, v87, v84
	v_add_f32_e32 v86, v73, v70
	v_add_f32_e32 v70, v72, v74
	v_sub_f32_e32 v73, v71, v70
	v_pk_add_f32 v[76:77], v[70:71], v[72:73] neg_lo:[0,1] neg_hi:[0,1]
	v_mov_b32_e32 v75, v70
	v_pk_add_f32 v[70:71], v[76:77], v[74:75] neg_lo:[0,1] neg_hi:[0,1]
	v_cmp_neq_f32_e64 s[0:1], s2, v62
	v_add_f32_e32 v71, v86, v71
	v_add_f32_e32 v70, v70, v71
	v_add_f32_e32 v71, v73, v70
	v_mul_f32_e32 v86, v85, v71
	v_mul_f32_e32 v72, v83, v86
	v_fma_f32 v74, v86, v83, -v72
	v_fmac_f32_e32 v74, v86, v84
	v_sub_f32_e32 v73, v73, v71
	v_add_f32_e32 v83, v70, v73
	v_add_f32_e32 v70, v72, v74
	v_sub_f32_e32 v73, v71, v70
	v_pk_add_f32 v[76:77], v[70:71], v[72:73] neg_lo:[0,1] neg_hi:[0,1]
	v_mov_b32_e32 v75, v70
	v_pk_add_f32 v[70:71], v[76:77], v[74:75] neg_lo:[0,1] neg_hi:[0,1]
	s_nop 0
	v_add_f32_e32 v71, v83, v71
	v_add_f32_e32 v70, v70, v71
	v_add_f32_e32 v71, v87, v86
	v_add_f32_e32 v70, v73, v70
	v_sub_f32_e32 v72, v71, v87
	v_mul_f32_e32 v70, v85, v70
	v_sub_f32_e32 v72, v86, v72
	v_add_f32_e32 v72, v72, v70
	v_add_f32_e32 v74, v71, v72
	v_mul_f32_e32 v75, v74, v74
	v_fmamk_f32 v70, v75, 0x3e9b6dac, v206
	v_fmaak_f32 v179, v75, v70, 0x3f2aaada
	v_cvt_f32_i32_e32 v70, v82
	v_sub_f32_e32 v71, v74, v71
	v_sub_f32_e32 v71, v72, v71
	v_ldexp_f32 v76, v71, 1
	v_mul_f32_e32 v71, v74, v75
	v_ldexp_f32 v73, v74, 1
	v_pk_mul_f32 v[74:75], v[70:71], v[178:179]
	s_nop 0
	v_fma_f32 v72, v70, s69, -v74
	v_fmac_f32_e32 v72, 0xb102e308, v70
	v_pk_add_f32 v[70:71], v[74:75], v[72:73]
	s_nop 0
	v_sub_f32_e32 v73, v71, v73
	v_sub_f32_e32 v73, v75, v73
	v_add_f32_e32 v77, v76, v73
	v_mov_b32_e32 v76, v74
	v_pk_add_f32 v[74:75], v[70:71], v[74:75] neg_lo:[0,1] neg_hi:[0,1]
	v_pk_add_f32 v[82:83], v[70:71], v[76:77]
	v_mov_b32_e32 v73, v70
	v_mov_b32_e32 v75, v83
	v_pk_add_f32 v[84:85], v[72:73], v[74:75] neg_lo:[0,1] neg_hi:[0,1]
	v_pk_add_f32 v[72:73], v[72:73], v[74:75]
	v_mov_b32_e32 v76, v77
	v_pk_add_f32 v[74:75], v[72:73], v[70:71] op_sel:[1,0] op_sel_hi:[0,1] neg_lo:[0,1] neg_hi:[0,1]
	v_pk_add_f32 v[86:87], v[82:83], v[74:75] op_sel_hi:[1,0] neg_lo:[0,1] neg_hi:[0,1]
	v_mov_b32_e32 v82, v83
	v_mov_b32_e32 v83, v73
	v_pk_mov_b32 v[74:75], v[70:71], v[74:75] op_sel:[1,0]
	v_mov_b32_e32 v77, v70
	v_pk_add_f32 v[74:75], v[82:83], v[74:75] neg_lo:[0,1] neg_hi:[0,1]
	v_mov_b32_e32 v86, v84
	v_pk_add_f32 v[70:71], v[76:77], v[74:75] neg_lo:[0,1] neg_hi:[0,1]
	v_mov_b32_e32 v85, v73
	v_pk_add_f32 v[74:75], v[86:87], v[70:71]
	s_nop 0
	v_pk_add_f32 v[76:77], v[74:75], v[74:75] op_sel:[0,1] op_sel_hi:[1,0]
	s_nop 0
	v_pk_add_f32 v[72:73], v[72:73], v[76:77] op_sel:[1,0] op_sel_hi:[0,1]
	v_mov_b32_e32 v75, v72
	v_pk_add_f32 v[82:83], v[74:75], v[84:85] neg_lo:[0,1] neg_hi:[0,1]
	v_mov_b32_e32 v71, v76
	v_sub_f32_e32 v73, v74, v82
	v_pk_add_f32 v[70:71], v[70:71], v[82:83] neg_lo:[0,1] neg_hi:[0,1]
	v_sub_f32_e32 v73, v84, v73
	v_add_f32_e32 v70, v70, v73
	v_add_f32_e32 v70, v70, v71
	v_add_f32_e32 v70, v72, v70
	v_cndmask_b32_e64 v70, v208, v70, s[0:1]
	v_cmp_lt_f32_e64 s[0:1], |v62|, s66
	s_nop 1
	v_cndmask_b32_e64 v62, v70, v62, s[0:1]
	v_lshl_add_u64 v[70:71], v[80:81], 0, v[68:69]
	v_lshlrev_b64 v[70:71], 14, v[70:71]
	v_sub_f32_e32 v0, v0, v62
	v_lshl_add_u64 v[70:71], v[78:79], 0, v[70:71]
	global_store_dword v[70:71], v0, off
;     __device__ __forceinline__ void operator()(const f32x4 (&acc)[2][2][4][2], const pg8::Unit& u, int wr, int wc, int fr, int fq) const {
;     ...
;         if (kind == 1 && pn == 28) {
;             if (wc == 0) {
; #pragma unroll
;                 for (int ai = 0; ai < 2; ++ai)
; #pragma unroll
;                     for (int m = 0; m < 4; ++m) { const int row = row0 + ai * 128 + m * 16;
; #pragma unroll
;                         for (int n = 0; n < 2; ++n)
; #pragma unroll
;                             for (int j = 0; j < 4; ++j) { const int col = 8 * fq + 4 * n + j;
;                                 if (col < 12) { const float xv = acc[ai][0][m][n][j] * rsqrtf(ssq[row] * (1.f / DM) + EPS) + bfp[col]; LS[((size_t)(row >> 12) * 12 + col) * SEQ + (row & (SEQ - 1))] = fminf(xv, 0.f) - log1pf(expf(-fabsf(xv))); } } }
.LBB0_513:
	s_or_b64 exec, exec, s[6:7]
	v_or_b32_e32 v70, 1, v68
	v_cmp_gt_i32_e64 s[6:7], 12, v70
	v_ashrrev_i32_e32 v71, 31, v70
	s_and_saveexec_b64 s[8:9], s[6:7]
	s_cbranch_execz .LBB0_515
	global_load_dword v0, v[66:67], off
	v_lshl_add_u64 v[72:73], v[70:71], 2, s[60:61]
	s_waitcnt vmcnt(0) lgkmcnt(0)
	v_fmamk_f32 v0, v0, 0x3a000000, v205
	v_cmp_gt_f32_e64 s[0:1], s68, v0
	v_mul_f32_e32 v62, 0x4b800000, v0
	s_nop 0
	v_cndmask_b32_e64 v0, v0, v62, s[0:1]
	v_rsq_f32_e32 v0, v0
	s_nop 0
	v_mul_f32_e32 v62, 0x45800000, v0
	v_cndmask_b32_e64 v0, v0, v62, s[0:1]
	global_load_dword v62, v[72:73], off
	s_waitcnt vmcnt(0) lgkmcnt(0)
	v_fmac_f32_e32 v62, v63, v0
	v_mul_f32_e64 v63, |v62|, s88
	v_fma_f32 v72, |v62|, s88, -v63
	v_rndne_f32_e32 v73, v63
	v_fma_f32 v72, |v62|, s89, v72
	v_sub_f32_e32 v63, v63, v73
	v_add_f32_e32 v63, v63, v72
	v_exp_f32_e32 v63, v63
	v_cvt_i32_f32_e32 v72, v73
	v_cmp_ngt_f32_e64 s[0:1], |v62|, s70
	v_min_f32_e32 v0, 0, v62
	v_ldexp_f32 v63, v63, v72
	v_cndmask_b32_e64 v63, 0, v63, s[0:1]
	v_cmp_nlt_f32_e64 s[0:1], |v62|, s90
	s_nop 1
	v_cndmask_b32_e64 v88, v208, v63, s[0:1]
	v_add_f32_e32 v72, 1.0, v88
	v_add_f32_e32 v62, -1.0, v72
	v_sub_f32_e32 v63, v62, v72
	v_add_f32_e32 v63, 1.0, v63
	v_sub_f32_e32 v62, v88, v62
	v_add_f32_e32 v73, v62, v63
	v_frexp_mant_f32_e32 v62, v72
	v_cmp_gt_f32_e64 s[0:1], s3, v62
	v_cvt_f64_f32_e32 v[62:63], v72
	v_frexp_exp_i32_f64_e32 v62, v[62:63]
	v_subbrev_co_u32_e64 v82, s[0:1], 0, v62, s[0:1]
	v_sub_u32_e32 v62, 0, v82
	v_ldexp_f32 v63, v72, v62
	v_add_f32_e32 v72, -1.0, v63
	v_add_f32_e32 v74, 1.0, v63
	v_ldexp_f32 v62, v73, v62
	v_add_f32_e32 v73, 1.0, v72
	v_add_f32_e32 v75, -1.0, v74
	v_sub_f32_e32 v73, v63, v73
	v_sub_f32_e32 v63, v63, v75
	v_add_f32_e32 v73, v62, v73
	v_add_f32_e32 v62, v62, v63
	v_add_f32_e32 v83, v74, v62
	v_rcp_f32_e32 v85, v83
	v_sub_f32_e32 v63, v74, v83
	v_add_f32_e32 v84, v62, v63
	v_add_f32_e32 v63, v72, v73
	v_mul_f32_e32 v87, v63, v85
	v_sub_f32_e32 v62, v72, v63
	v_mul_f32_e32 v72, v83, v87
	v_fma_f32 v74, v87, v83, -v72
	v_fmac_f32_e32 v74, v87, v84
	v_add_f32_e32 v86, v73, v62
	v_add_f32_e32 v62, v72, v74
	v_sub_f32_e32 v73, v63, v62
	v_pk_add_f32 v[76:77], v[62:63], v[72:73] neg_lo:[0,1] neg_hi:[0,1]
	v_mov_b32_e32 v75, v62
	v_pk_add_f32 v[62:63], v[76:77], v[74:75] neg_lo:[0,1] neg_hi:[0,1]
	v_cmp_neq_f32_e64 s[0:1], s2, v88
	v_add_f32_e32 v63, v86, v63
	v_add_f32_e32 v62, v62, v63
	v_add_f32_e32 v63, v73, v62
	v_mul_f32_e32 v86, v85, v63
	v_mul_f32_e32 v72, v83, v86
	v_fma_f32 v74, v86, v83, -v72
	v_fmac_f32_e32 v74, v86, v84
	v_sub_f32_e32 v73, v73, v63
	v_add_f32_e32 v83, v62, v73
	v_add_f32_e32 v62, v72, v74
	v_sub_f32_e32 v73, v63, v62
	v_pk_add_f32 v[76:77], v[62:63], v[72:73] neg_lo:[0,1] neg_hi:[0,1]
	v_mov_b32_e32 v75, v62
	v_pk_add_f32 v[62:63], v[76:77], v[74:75] neg_lo:[0,1] neg_hi:[0,1]
	s_nop 0
	v_add_f32_e32 v63, v83, v63
	v_add_f32_e32 v62, v62, v63
	v_add_f32_e32 v63, v87, v86
	v_add_f32_e32 v62, v73, v62
	v_sub_f32_e32 v72, v63, v87
	v_mul_f32_e32 v62, v85, v62
	v_sub_f32_e32 v72, v86, v72
	v_add_f32_e32 v72, v72, v62
	v_add_f32_e32 v74, v63, v72
	v_mul_f32_e32 v75, v74, v74
	v_fmamk_f32 v62, v75, 0x3e9b6dac, v206
	v_fmaak_f32 v179, v75, v62, 0x3f2aaada
	v_cvt_f32_i32_e32 v62, v82
	v_sub_f32_e32 v63, v74, v63
	v_sub_f32_e32 v63, v72, v63
	v_ldexp_f32 v76, v63, 1
	v_mul_f32_e32 v63, v74, v75
	v_ldexp_f32 v73, v74, 1
	v_pk_mul_f32 v[74:75], v[62:63], v[178:179]
	s_nop 0
	v_fma_f32 v72, v62, s69, -v74
	v_fmac_f32_e32 v72, 0xb102e308, v62
	v_pk_add_f32 v[62:63], v[74:75], v[72:73]
	s_nop 0
	v_sub_f32_e32 v73, v63, v73
	v_sub_f32_e32 v73, v75, v73
	v_add_f32_e32 v77, v76, v73
	v_mov_b32_e32 v76, v74
	v_pk_add_f32 v[74:75], v[62:63], v[74:75] neg_lo:[0,1] neg_hi:[0,1]
	v_pk_add_f32 v[82:83], v[62:63], v[76:77]
	v_mov_b32_e32 v73, v62
	v_mov_b32_e32 v75, v83
	v_pk_add_f32 v[84:85], v[72:73], v[74:75] neg_lo:[0,1] neg_hi:[0,1]
	v_pk_add_f32 v[72:73], v[72:73], v[74:75]
	v_mov_b32_e32 v76, v77
	v_pk_add_f32 v[74:75], v[72:73], v[62:63] op_sel:[1,0] op_sel_hi:[0,1] neg_lo:[0,1] neg_hi:[0,1]
	v_pk_add_f32 v[86:87], v[82:83], v[74:75] op_sel_hi:[1,0] neg_lo:[0,1] neg_hi:[0,1]
	v_mov_b32_e32 v82, v83
	v_mov_b32_e32 v83, v73
	v_pk_mov_b32 v[74:75], v[62:63], v[74:75] op_sel:[1,0]
	v_mov_b32_e32 v77, v62
	v_pk_add_f32 v[74:75], v[82:83], v[74:75] neg_lo:[0,1] neg_hi:[0,1]
	v_mov_b32_e32 v86, v84
	v_pk_add_f32 v[62:63], v[76:77], v[74:75] neg_lo:[0,1] neg_hi:[0,1]
	v_mov_b32_e32 v85, v73
	v_pk_add_f32 v[74:75], v[86:87], v[62:63]
	s_nop 0
	v_pk_add_f32 v[76:77], v[74:75], v[74:75] op_sel:[0,1] op_sel_hi:[1,0]
	s_nop 0
	v_pk_add_f32 v[72:73], v[72:73], v[76:77] op_sel:[1,0] op_sel_hi:[0,1]
	v_mov_b32_e32 v75, v72
	v_pk_add_f32 v[82:83], v[74:75], v[84:85] neg_lo:[0,1] neg_hi:[0,1]
	v_mov_b32_e32 v63, v76
	v_sub_f32_e32 v73, v74, v82
	v_pk_add_f32 v[62:63], v[62:63], v[82:83] neg_lo:[0,1] neg_hi:[0,1]
	v_sub_f32_e32 v73, v84, v73
	v_add_f32_e32 v62, v62, v73
	v_add_f32_e32 v62, v62, v63
	v_add_f32_e32 v62, v72, v62
	v_cndmask_b32_e64 v62, v208, v62, s[0:1]
	v_cmp_lt_f32_e64 s[0:1], |v88|, s66
	s_nop 1
	v_cndmask_b32_e64 v62, v62, v88, s[0:1]
	v_sub_f32_e32 v0, v0, v62
	v_lshl_add_u64 v[62:63], v[80:81], 0, v[70:71]
	v_lshlrev_b64 v[62:63], 14, v[62:63]
	v_lshl_add_u64 v[62:63], v[78:79], 0, v[62:63]
	global_store_dword v[62:63], v0, off
;     __device__ __forceinline__ void operator()(const f32x4 (&acc)[2][2][4][2], const pg8::Unit& u, int wr, int wc, int fr, int fq) const {
;     ...
;         if (kind == 1 && pn == 28) {
;             if (wc == 0) {
; #pragma unroll
;                 for (int ai = 0; ai < 2; ++ai)
; #pragma unroll
;                     for (int m = 0; m < 4; ++m) { const int row = row0 + ai * 128 + m * 16;
; #pragma unroll
;                         for (int n = 0; n < 2; ++n)
; #pragma unroll
;                             for (int j = 0; j < 4; ++j) { const int col = 8 * fq + 4 * n + j;
;                                 if (col < 12) { const float xv = acc[ai][0][m][n][j] * rsqrtf(ssq[row] * (1.f / DM) + EPS) + bfp[col]; LS[((size_t)(row >> 12) * 12 + col) * SEQ + (row & (SEQ - 1))] = fminf(xv, 0.f) - log1pf(expf(-fabsf(xv))); } } }
.LBB0_515:
	s_or_b64 exec, exec, s[8:9]
	v_or_b32_e32 v62, 2, v68
	v_cmp_gt_i32_e64 s[8:9], 12, v62
	v_ashrrev_i32_e32 v63, 31, v62
	s_and_saveexec_b64 s[10:11], s[8:9]
	s_cbranch_execz .LBB0_517
	global_load_dword v0, v[66:67], off
	s_waitcnt vmcnt(0) lgkmcnt(0)
	v_fmamk_f32 v0, v0, 0x3a000000, v205
	v_cmp_gt_f32_e64 s[0:1], s68, v0
	v_mul_f32_e32 v72, 0x4b800000, v0
	s_nop 0
	v_cndmask_b32_e64 v0, v0, v72, s[0:1]
	v_rsq_f32_e32 v0, v0
	s_nop 0
	v_mul_f32_e32 v72, 0x45800000, v0
	v_cndmask_b32_e64 v0, v0, v72, s[0:1]
	v_lshl_add_u64 v[72:73], v[62:63], 2, s[60:61]
	global_load_dword v72, v[72:73], off
	s_waitcnt vmcnt(0) lgkmcnt(0)
	v_fmac_f32_e32 v72, v64, v0
	v_mul_f32_e64 v64, |v72|, s88
	v_fma_f32 v73, |v72|, s88, -v64
	v_rndne_f32_e32 v74, v64
	v_fma_f32 v73, |v72|, s89, v73
	v_sub_f32_e32 v64, v64, v74
	v_add_f32_e32 v64, v64, v73
	v_exp_f32_e32 v64, v64
	v_cvt_i32_f32_e32 v73, v74
	v_cmp_ngt_f32_e64 s[0:1], |v72|, s70
	v_min_f32_e32 v0, 0, v72
	v_ldexp_f32 v64, v64, v73
	v_cndmask_b32_e64 v64, 0, v64, s[0:1]
	v_cmp_nlt_f32_e64 s[0:1], |v72|, s90
	s_nop 1
	v_cndmask_b32_e64 v64, v208, v64, s[0:1]
	v_add_f32_e32 v74, 1.0, v64
	v_add_f32_e32 v72, -1.0, v74
	v_sub_f32_e32 v73, v72, v74
	v_add_f32_e32 v73, 1.0, v73
	v_sub_f32_e32 v72, v64, v72
	v_add_f32_e32 v75, v72, v73
	v_frexp_mant_f32_e32 v72, v74
	v_cmp_gt_f32_e64 s[0:1], s3, v72
	v_cvt_f64_f32_e32 v[72:73], v74
	v_frexp_exp_i32_f64_e32 v72, v[72:73]
	v_subbrev_co_u32_e64 v84, s[0:1], 0, v72, s[0:1]
	v_sub_u32_e32 v72, 0, v84
	v_ldexp_f32 v73, v74, v72
	v_add_f32_e32 v74, -1.0, v73
	v_add_f32_e32 v76, 1.0, v73
	v_ldexp_f32 v72, v75, v72
	v_add_f32_e32 v75, 1.0, v74
	v_add_f32_e32 v77, -1.0, v76
	v_sub_f32_e32 v75, v73, v75
	v_sub_f32_e32 v73, v73, v77
	v_add_f32_e32 v75, v72, v75
	v_add_f32_e32 v72, v72, v73
	v_add_f32_e32 v85, v76, v72
	v_rcp_f32_e32 v87, v85
	v_sub_f32_e32 v73, v76, v85
	v_add_f32_e32 v86, v72, v73
	v_add_f32_e32 v73, v74, v75
	v_mul_f32_e32 v89, v73, v87
	v_sub_f32_e32 v72, v74, v73
	v_mul_f32_e32 v74, v85, v89
	v_fma_f32 v76, v89, v85, -v74
	v_fmac_f32_e32 v76, v89, v86
	v_add_f32_e32 v88, v75, v72
	v_add_f32_e32 v72, v74, v76
	v_sub_f32_e32 v75, v73, v72
	v_pk_add_f32 v[82:83], v[72:73], v[74:75] neg_lo:[0,1] neg_hi:[0,1]
	v_mov_b32_e32 v77, v72
	v_pk_add_f32 v[72:73], v[82:83], v[76:77] neg_lo:[0,1] neg_hi:[0,1]
	v_cmp_neq_f32_e64 s[0:1], s2, v64
	v_add_f32_e32 v73, v88, v73
	v_add_f32_e32 v72, v72, v73
	v_add_f32_e32 v73, v75, v72
	v_mul_f32_e32 v88, v87, v73
	v_mul_f32_e32 v74, v85, v88
	v_fma_f32 v76, v88, v85, -v74
	v_fmac_f32_e32 v76, v88, v86
	v_sub_f32_e32 v75, v75, v73
	v_add_f32_e32 v85, v72, v75
	v_add_f32_e32 v72, v74, v76
	v_sub_f32_e32 v75, v73, v72
	v_pk_add_f32 v[82:83], v[72:73], v[74:75] neg_lo:[0,1] neg_hi:[0,1]
	v_mov_b32_e32 v77, v72
	v_pk_add_f32 v[72:73], v[82:83], v[76:77] neg_lo:[0,1] neg_hi:[0,1]
	s_nop 0
	v_add_f32_e32 v73, v85, v73
	v_add_f32_e32 v72, v72, v73
	v_add_f32_e32 v73, v89, v88
	v_add_f32_e32 v72, v75, v72
	v_sub_f32_e32 v74, v73, v89
	v_mul_f32_e32 v72, v87, v72
	v_sub_f32_e32 v74, v88, v74
	v_add_f32_e32 v74, v74, v72
	v_add_f32_e32 v76, v73, v74
	v_mul_f32_e32 v77, v76, v76
	v_fmamk_f32 v72, v77, 0x3e9b6dac, v206
	v_fmaak_f32 v179, v77, v72, 0x3f2aaada
	v_cvt_f32_i32_e32 v72, v84
	v_sub_f32_e32 v73, v76, v73
	v_sub_f32_e32 v73, v74, v73
	v_ldexp_f32 v82, v73, 1
	v_mul_f32_e32 v73, v76, v77
	v_ldexp_f32 v75, v76, 1
	v_pk_mul_f32 v[76:77], v[72:73], v[178:179]
	s_nop 0
	v_fma_f32 v74, v72, s69, -v76
	v_fmac_f32_e32 v74, 0xb102e308, v72
	v_pk_add_f32 v[72:73], v[76:77], v[74:75]
	s_nop 0
	v_sub_f32_e32 v75, v73, v75
	v_sub_f32_e32 v75, v77, v75
	v_add_f32_e32 v83, v82, v75
	v_mov_b32_e32 v82, v76
	v_pk_add_f32 v[76:77], v[72:73], v[76:77] neg_lo:[0,1] neg_hi:[0,1]
	v_pk_add_f32 v[84:85], v[72:73], v[82:83]
	v_mov_b32_e32 v75, v72
	v_mov_b32_e32 v77, v85
	v_pk_add_f32 v[86:87], v[74:75], v[76:77] neg_lo:[0,1] neg_hi:[0,1]
	v_pk_add_f32 v[74:75], v[74:75], v[76:77]
	v_mov_b32_e32 v82, v83
	v_pk_add_f32 v[76:77], v[74:75], v[72:73] op_sel:[1,0] op_sel_hi:[0,1] neg_lo:[0,1] neg_hi:[0,1]
	v_pk_add_f32 v[88:89], v[84:85], v[76:77] op_sel_hi:[1,0] neg_lo:[0,1] neg_hi:[0,1]
	v_mov_b32_e32 v84, v85
	v_mov_b32_e32 v85, v75
	v_pk_mov_b32 v[76:77], v[72:73], v[76:77] op_sel:[1,0]
	v_mov_b32_e32 v83, v72
	v_pk_add_f32 v[76:77], v[84:85], v[76:77] neg_lo:[0,1] neg_hi:[0,1]
	v_mov_b32_e32 v88, v86
	v_pk_add_f32 v[72:73], v[82:83], v[76:77] neg_lo:[0,1] neg_hi:[0,1]
	v_mov_b32_e32 v87, v75
	v_pk_add_f32 v[76:77], v[88:89], v[72:73]
	s_nop 0
	v_pk_add_f32 v[82:83], v[76:77], v[76:77] op_sel:[0,1] op_sel_hi:[1,0]
	s_nop 0
	v_pk_add_f32 v[74:75], v[74:75], v[82:83] op_sel:[1,0] op_sel_hi:[0,1]
	v_mov_b32_e32 v77, v74
	v_pk_add_f32 v[84:85], v[76:77], v[86:87] neg_lo:[0,1] neg_hi:[0,1]
	v_mov_b32_e32 v73, v82
	v_sub_f32_e32 v75, v76, v84
	v_pk_add_f32 v[72:73], v[72:73], v[84:85] neg_lo:[0,1] neg_hi:[0,1]
	v_sub_f32_e32 v75, v86, v75
	v_add_f32_e32 v72, v72, v75
	v_add_f32_e32 v72, v72, v73
	v_add_f32_e32 v72, v74, v72
	v_cndmask_b32_e64 v72, v208, v72, s[0:1]
	v_cmp_lt_f32_e64 s[0:1], |v64|, s66
	s_nop 1
	v_cndmask_b32_e64 v64, v72, v64, s[0:1]
	v_lshl_add_u64 v[72:73], v[80:81], 0, v[62:63]
	v_lshlrev_b64 v[72:73], 14, v[72:73]
	v_sub_f32_e32 v0, v0, v64
	v_lshl_add_u64 v[72:73], v[78:79], 0, v[72:73]
	global_store_dword v[72:73], v0, off
;     __device__ __forceinline__ void operator()(const f32x4 (&acc)[2][2][4][2], const pg8::Unit& u, int wr, int wc, int fr, int fq) const {
;     ...
;         if (kind == 1 && pn == 28) {
;             if (wc == 0) {
; #pragma unroll
;                 for (int ai = 0; ai < 2; ++ai)
; #pragma unroll
;                     for (int m = 0; m < 4; ++m) { const int row = row0 + ai * 128 + m * 16;
; #pragma unroll
;                         for (int n = 0; n < 2; ++n)
; #pragma unroll
;                             for (int j = 0; j < 4; ++j) { const int col = 8 * fq + 4 * n + j;
;                                 if (col < 12) { const float xv = acc[ai][0][m][n][j] * rsqrtf(ssq[row] * (1.f / DM) + EPS) + bfp[col]; LS[((size_t)(row >> 12) * 12 + col) * SEQ + (row & (SEQ - 1))] = fminf(xv, 0.f) - log1pf(expf(-fabsf(xv))); } } }
.LBB0_517:
	s_or_b64 exec, exec, s[10:11]
	v_or_b32_e32 v72, 3, v68
	v_cmp_gt_i32_e64 s[10:11], 12, v72
	v_ashrrev_i32_e32 v73, 31, v72
	s_and_saveexec_b64 s[12:13], s[10:11]
	s_cbranch_execz .LBB0_519
	global_load_dword v0, v[66:67], off
	v_lshl_add_u64 v[74:75], v[72:73], 2, s[60:61]
	s_waitcnt vmcnt(0) lgkmcnt(0)
	v_fmamk_f32 v0, v0, 0x3a000000, v205
	v_cmp_gt_f32_e64 s[0:1], s68, v0
	v_mul_f32_e32 v64, 0x4b800000, v0
	s_nop 0
	v_cndmask_b32_e64 v0, v0, v64, s[0:1]
	v_rsq_f32_e32 v0, v0
	s_nop 0
	v_mul_f32_e32 v64, 0x45800000, v0
	v_cndmask_b32_e64 v0, v0, v64, s[0:1]
	global_load_dword v64, v[74:75], off
	s_waitcnt vmcnt(0) lgkmcnt(0)
	v_fmac_f32_e32 v64, v65, v0
	v_mul_f32_e64 v65, |v64|, s88
	v_fma_f32 v74, |v64|, s88, -v65
	v_rndne_f32_e32 v75, v65
	v_fma_f32 v74, |v64|, s89, v74
	v_sub_f32_e32 v65, v65, v75
	v_add_f32_e32 v65, v65, v74
	v_exp_f32_e32 v65, v65
	v_cvt_i32_f32_e32 v74, v75
	v_cmp_ngt_f32_e64 s[0:1], |v64|, s70
	v_min_f32_e32 v0, 0, v64
	v_ldexp_f32 v65, v65, v74
	v_cndmask_b32_e64 v65, 0, v65, s[0:1]
	v_cmp_nlt_f32_e64 s[0:1], |v64|, s90
	s_nop 1
	v_cndmask_b32_e64 v90, v208, v65, s[0:1]
	v_add_f32_e32 v74, 1.0, v90
	v_add_f32_e32 v64, -1.0, v74
	v_sub_f32_e32 v65, v64, v74
	v_add_f32_e32 v65, 1.0, v65
	v_sub_f32_e32 v64, v90, v64
	v_add_f32_e32 v75, v64, v65
	v_frexp_mant_f32_e32 v64, v74
	v_cmp_gt_f32_e64 s[0:1], s3, v64
	v_cvt_f64_f32_e32 v[64:65], v74
	v_frexp_exp_i32_f64_e32 v64, v[64:65]
	v_subbrev_co_u32_e64 v84, s[0:1], 0, v64, s[0:1]
	v_sub_u32_e32 v64, 0, v84
	v_ldexp_f32 v65, v74, v64
	v_add_f32_e32 v74, -1.0, v65
	v_add_f32_e32 v76, 1.0, v65
	v_ldexp_f32 v64, v75, v64
	v_add_f32_e32 v75, 1.0, v74
	v_add_f32_e32 v77, -1.0, v76
	v_sub_f32_e32 v75, v65, v75
	v_sub_f32_e32 v65, v65, v77
	v_add_f32_e32 v75, v64, v75
	v_add_f32_e32 v64, v64, v65
	v_add_f32_e32 v85, v76, v64
	v_rcp_f32_e32 v87, v85
	v_sub_f32_e32 v65, v76, v85
	v_add_f32_e32 v86, v64, v65
	v_add_f32_e32 v65, v74, v75
	v_mul_f32_e32 v89, v65, v87
	v_sub_f32_e32 v64, v74, v65
	v_mul_f32_e32 v74, v85, v89
	v_fma_f32 v76, v89, v85, -v74
	v_fmac_f32_e32 v76, v89, v86
	v_add_f32_e32 v88, v75, v64
	v_add_f32_e32 v64, v74, v76
	v_sub_f32_e32 v75, v65, v64
	v_pk_add_f32 v[82:83], v[64:65], v[74:75] neg_lo:[0,1] neg_hi:[0,1]
	v_mov_b32_e32 v77, v64
	v_pk_add_f32 v[64:65], v[82:83], v[76:77] neg_lo:[0,1] neg_hi:[0,1]
	v_cmp_neq_f32_e64 s[0:1], s2, v90
	v_add_f32_e32 v65, v88, v65
	v_add_f32_e32 v64, v64, v65
	v_add_f32_e32 v65, v75, v64
	v_mul_f32_e32 v88, v87, v65
	v_mul_f32_e32 v74, v85, v88
	v_fma_f32 v76, v88, v85, -v74
	v_fmac_f32_e32 v76, v88, v86
	v_sub_f32_e32 v75, v75, v65
	v_add_f32_e32 v85, v64, v75
	v_add_f32_e32 v64, v74, v76
	v_sub_f32_e32 v75, v65, v64
	v_pk_add_f32 v[82:83], v[64:65], v[74:75] neg_lo:[0,1] neg_hi:[0,1]
	v_mov_b32_e32 v77, v64
	v_pk_add_f32 v[64:65], v[82:83], v[76:77] neg_lo:[0,1] neg_hi:[0,1]
	s_nop 0
	v_add_f32_e32 v65, v85, v65
	v_add_f32_e32 v64, v64, v65
	v_add_f32_e32 v65, v89, v88
	v_add_f32_e32 v64, v75, v64
	v_sub_f32_e32 v74, v65, v89
	v_mul_f32_e32 v64, v87, v64
	v_sub_f32_e32 v74, v88, v74
	v_add_f32_e32 v74, v74, v64
	v_add_f32_e32 v76, v65, v74
	v_mul_f32_e32 v77, v76, v76
	v_fmamk_f32 v64, v77, 0x3e9b6dac, v206
	v_fmaak_f32 v179, v77, v64, 0x3f2aaada
	v_cvt_f32_i32_e32 v64, v84
	v_sub_f32_e32 v65, v76, v65
	v_sub_f32_e32 v65, v74, v65
	v_ldexp_f32 v82, v65, 1
	v_mul_f32_e32 v65, v76, v77
	v_ldexp_f32 v75, v76, 1
	v_pk_mul_f32 v[76:77], v[64:65], v[178:179]
	s_nop 0
	v_fma_f32 v74, v64, s69, -v76
	v_fmac_f32_e32 v74, 0xb102e308, v64
	v_pk_add_f32 v[64:65], v[76:77], v[74:75]
	s_nop 0
	v_sub_f32_e32 v75, v65, v75
	v_sub_f32_e32 v75, v77, v75
	v_add_f32_e32 v83, v82, v75
	v_mov_b32_e32 v82, v76
	v_pk_add_f32 v[76:77], v[64:65], v[76:77] neg_lo:[0,1] neg_hi:[0,1]
	v_pk_add_f32 v[84:85], v[64:65], v[82:83]
	v_mov_b32_e32 v75, v64
	v_mov_b32_e32 v77, v85
	v_pk_add_f32 v[86:87], v[74:75], v[76:77] neg_lo:[0,1] neg_hi:[0,1]
	v_pk_add_f32 v[74:75], v[74:75], v[76:77]
	v_mov_b32_e32 v82, v83
	v_pk_add_f32 v[76:77], v[74:75], v[64:65] op_sel:[1,0] op_sel_hi:[0,1] neg_lo:[0,1] neg_hi:[0,1]
	v_pk_add_f32 v[88:89], v[84:85], v[76:77] op_sel_hi:[1,0] neg_lo:[0,1] neg_hi:[0,1]
	v_mov_b32_e32 v84, v85
	v_mov_b32_e32 v85, v75
	v_pk_mov_b32 v[76:77], v[64:65], v[76:77] op_sel:[1,0]
	v_mov_b32_e32 v83, v64
	v_pk_add_f32 v[76:77], v[84:85], v[76:77] neg_lo:[0,1] neg_hi:[0,1]
	v_mov_b32_e32 v88, v86
	v_pk_add_f32 v[64:65], v[82:83], v[76:77] neg_lo:[0,1] neg_hi:[0,1]
	v_mov_b32_e32 v87, v75
	v_pk_add_f32 v[76:77], v[88:89], v[64:65]
	s_nop 0
	v_pk_add_f32 v[82:83], v[76:77], v[76:77] op_sel:[0,1] op_sel_hi:[1,0]
	s_nop 0
	v_pk_add_f32 v[74:75], v[74:75], v[82:83] op_sel:[1,0] op_sel_hi:[0,1]
	v_mov_b32_e32 v77, v74
	v_pk_add_f32 v[84:85], v[76:77], v[86:87] neg_lo:[0,1] neg_hi:[0,1]
	v_mov_b32_e32 v65, v82
	v_sub_f32_e32 v75, v76, v84
	v_pk_add_f32 v[64:65], v[64:65], v[84:85] neg_lo:[0,1] neg_hi:[0,1]
	v_sub_f32_e32 v75, v86, v75
	v_add_f32_e32 v64, v64, v75
	v_add_f32_e32 v64, v64, v65
	v_add_f32_e32 v64, v74, v64
	v_cndmask_b32_e64 v64, v208, v64, s[0:1]
	v_cmp_lt_f32_e64 s[0:1], |v90|, s66
	s_nop 1
	v_cndmask_b32_e64 v64, v64, v90, s[0:1]
	v_sub_f32_e32 v0, v0, v64
	v_lshl_add_u64 v[64:65], v[80:81], 0, v[72:73]
	v_lshlrev_b64 v[64:65], 14, v[64:65]
	v_lshl_add_u64 v[64:65], v[78:79], 0, v[64:65]
	global_store_dword v[64:65], v0, off
;     __device__ __forceinline__ void operator()(const f32x4 (&acc)[2][2][4][2], const pg8::Unit& u, int wr, int wc, int fr, int fq) const {
;     ...
;         if (kind == 1 && pn == 28) {
;             if (wc == 0) {
; #pragma unroll
;                 for (int ai = 0; ai < 2; ++ai)
; #pragma unroll
;                     for (int m = 0; m < 4; ++m) { const int row = row0 + ai * 128 + m * 16;
; #pragma unroll
;                         for (int n = 0; n < 2; ++n)
; #pragma unroll
;                             for (int j = 0; j < 4; ++j) { const int col = 8 * fq + 4 * n + j;
;                                 if (col < 12) { const float xv = acc[ai][0][m][n][j] * rsqrtf(ssq[row] * (1.f / DM) + EPS) + bfp[col]; LS[((size_t)(row >> 12) * 12 + col) * SEQ + (row & (SEQ - 1))] = fminf(xv, 0.f) - log1pf(expf(-fabsf(xv))); } } }
.LBB0_519:
	s_or_b64 exec, exec, s[12:13]
	v_or_b32_e32 v64, 4, v68
	v_cmp_gt_i32_e64 s[12:13], 12, v64
	v_ashrrev_i32_e32 v65, 31, v64
	s_and_saveexec_b64 s[14:15], s[12:13]
	s_cbranch_execz .LBB0_521
	global_load_dword v0, v[66:67], off
	s_waitcnt vmcnt(0) lgkmcnt(0)
	v_fmamk_f32 v0, v0, 0x3a000000, v205
	v_cmp_gt_f32_e64 s[0:1], s68, v0
	v_mul_f32_e32 v74, 0x4b800000, v0
	s_nop 0
	v_cndmask_b32_e64 v0, v0, v74, s[0:1]
	v_rsq_f32_e32 v0, v0
	s_nop 0
	v_mul_f32_e32 v74, 0x45800000, v0
	v_cndmask_b32_e64 v0, v0, v74, s[0:1]
	v_lshl_add_u64 v[74:75], v[64:65], 2, s[60:61]
	global_load_dword v74, v[74:75], off
	s_waitcnt vmcnt(0) lgkmcnt(0)
	v_fmac_f32_e32 v74, v58, v0
	v_mul_f32_e64 v58, |v74|, s88
	v_fma_f32 v75, |v74|, s88, -v58
	v_rndne_f32_e32 v76, v58
	v_fma_f32 v75, |v74|, s89, v75
	v_sub_f32_e32 v58, v58, v76
	v_add_f32_e32 v58, v58, v75
	v_exp_f32_e32 v58, v58
	v_cvt_i32_f32_e32 v75, v76
	v_cmp_ngt_f32_e64 s[0:1], |v74|, s70
	v_min_f32_e32 v0, 0, v74
	v_ldexp_f32 v58, v58, v75
	v_cndmask_b32_e64 v58, 0, v58, s[0:1]
	v_cmp_nlt_f32_e64 s[0:1], |v74|, s90
	s_nop 1
	v_cndmask_b32_e64 v58, v208, v58, s[0:1]
	v_add_f32_e32 v76, 1.0, v58
	v_add_f32_e32 v74, -1.0, v76
	v_sub_f32_e32 v75, v74, v76
	v_add_f32_e32 v75, 1.0, v75
	v_sub_f32_e32 v74, v58, v74
	v_add_f32_e32 v77, v74, v75
	v_frexp_mant_f32_e32 v74, v76
	v_cmp_gt_f32_e64 s[0:1], s3, v74
	v_cvt_f64_f32_e32 v[74:75], v76
	v_frexp_exp_i32_f64_e32 v74, v[74:75]
	v_subbrev_co_u32_e64 v86, s[0:1], 0, v74, s[0:1]
	v_sub_u32_e32 v74, 0, v86
	v_ldexp_f32 v75, v76, v74
	v_add_f32_e32 v76, -1.0, v75
	v_add_f32_e32 v82, 1.0, v75
	v_ldexp_f32 v74, v77, v74
	v_add_f32_e32 v77, 1.0, v76
	v_add_f32_e32 v83, -1.0, v82
	v_sub_f32_e32 v77, v75, v77
	v_sub_f32_e32 v75, v75, v83
	v_add_f32_e32 v77, v74, v77
	v_add_f32_e32 v74, v74, v75
	v_add_f32_e32 v87, v82, v74
	v_rcp_f32_e32 v89, v87
	v_sub_f32_e32 v75, v82, v87
	v_add_f32_e32 v88, v74, v75
	v_add_f32_e32 v75, v76, v77
	v_mul_f32_e32 v91, v75, v89
	v_sub_f32_e32 v74, v76, v75
	v_mul_f32_e32 v76, v87, v91
	v_fma_f32 v82, v91, v87, -v76
	v_fmac_f32_e32 v82, v91, v88
	v_add_f32_e32 v90, v77, v74
	v_add_f32_e32 v74, v76, v82
	v_sub_f32_e32 v77, v75, v74
	v_pk_add_f32 v[84:85], v[74:75], v[76:77] neg_lo:[0,1] neg_hi:[0,1]
	v_mov_b32_e32 v83, v74
	v_pk_add_f32 v[74:75], v[84:85], v[82:83] neg_lo:[0,1] neg_hi:[0,1]
	v_cmp_neq_f32_e64 s[0:1], s2, v58
	v_add_f32_e32 v75, v90, v75
	v_add_f32_e32 v74, v74, v75
	v_add_f32_e32 v75, v77, v74
	v_mul_f32_e32 v90, v89, v75
	v_mul_f32_e32 v76, v87, v90
	v_fma_f32 v82, v90, v87, -v76
	v_fmac_f32_e32 v82, v90, v88
	v_sub_f32_e32 v77, v77, v75
	v_add_f32_e32 v87, v74, v77
	v_add_f32_e32 v74, v76, v82
	v_sub_f32_e32 v77, v75, v74
	v_pk_add_f32 v[84:85], v[74:75], v[76:77] neg_lo:[0,1] neg_hi:[0,1]
	v_mov_b32_e32 v83, v74
	v_pk_add_f32 v[74:75], v[84:85], v[82:83] neg_lo:[0,1] neg_hi:[0,1]
	s_nop 0
	v_add_f32_e32 v75, v87, v75
	v_add_f32_e32 v74, v74, v75
	v_add_f32_e32 v75, v91, v90
	v_add_f32_e32 v74, v77, v74
	v_sub_f32_e32 v76, v75, v91
	v_mul_f32_e32 v74, v89, v74
	v_sub_f32_e32 v76, v90, v76
	v_add_f32_e32 v76, v76, v74
	v_add_f32_e32 v82, v75, v76
	v_mul_f32_e32 v83, v82, v82
	v_fmamk_f32 v74, v83, 0x3e9b6dac, v206
	v_fmaak_f32 v179, v83, v74, 0x3f2aaada
	v_cvt_f32_i32_e32 v74, v86
	v_sub_f32_e32 v75, v82, v75
	v_sub_f32_e32 v75, v76, v75
	v_ldexp_f32 v84, v75, 1
	v_mul_f32_e32 v75, v82, v83
	v_ldexp_f32 v77, v82, 1
	v_pk_mul_f32 v[82:83], v[74:75], v[178:179]
	s_nop 0
	v_fma_f32 v76, v74, s69, -v82
	v_fmac_f32_e32 v76, 0xb102e308, v74
	v_pk_add_f32 v[74:75], v[82:83], v[76:77]
	s_nop 0
	v_sub_f32_e32 v77, v75, v77
	v_sub_f32_e32 v77, v83, v77
	v_add_f32_e32 v85, v84, v77
	v_mov_b32_e32 v84, v82
	v_pk_add_f32 v[82:83], v[74:75], v[82:83] neg_lo:[0,1] neg_hi:[0,1]
	v_pk_add_f32 v[86:87], v[74:75], v[84:85]
	v_mov_b32_e32 v77, v74
	v_mov_b32_e32 v83, v87
	v_pk_add_f32 v[88:89], v[76:77], v[82:83] neg_lo:[0,1] neg_hi:[0,1]
	v_pk_add_f32 v[76:77], v[76:77], v[82:83]
	v_mov_b32_e32 v84, v85
	v_pk_add_f32 v[82:83], v[76:77], v[74:75] op_sel:[1,0] op_sel_hi:[0,1] neg_lo:[0,1] neg_hi:[0,1]
	v_pk_add_f32 v[90:91], v[86:87], v[82:83] op_sel_hi:[1,0] neg_lo:[0,1] neg_hi:[0,1]
	v_mov_b32_e32 v86, v87
	v_mov_b32_e32 v87, v77
	v_pk_mov_b32 v[82:83], v[74:75], v[82:83] op_sel:[1,0]
	v_mov_b32_e32 v85, v74
	v_pk_add_f32 v[82:83], v[86:87], v[82:83] neg_lo:[0,1] neg_hi:[0,1]
	v_mov_b32_e32 v90, v88
	v_pk_add_f32 v[74:75], v[84:85], v[82:83] neg_lo:[0,1] neg_hi:[0,1]
	v_mov_b32_e32 v89, v77
	v_pk_add_f32 v[82:83], v[90:91], v[74:75]
	s_nop 0
	v_pk_add_f32 v[84:85], v[82:83], v[82:83] op_sel:[0,1] op_sel_hi:[1,0]
	s_nop 0
	v_pk_add_f32 v[76:77], v[76:77], v[84:85] op_sel:[1,0] op_sel_hi:[0,1]
	v_mov_b32_e32 v83, v76
	v_pk_add_f32 v[86:87], v[82:83], v[88:89] neg_lo:[0,1] neg_hi:[0,1]
	v_mov_b32_e32 v75, v84
	v_sub_f32_e32 v77, v82, v86
	v_pk_add_f32 v[74:75], v[74:75], v[86:87] neg_lo:[0,1] neg_hi:[0,1]
	v_sub_f32_e32 v77, v88, v77
	v_add_f32_e32 v74, v74, v77
	v_add_f32_e32 v74, v74, v75
	v_add_f32_e32 v74, v76, v74
	v_cndmask_b32_e64 v74, v208, v74, s[0:1]
	v_cmp_lt_f32_e64 s[0:1], |v58|, s66
	s_nop 1
	v_cndmask_b32_e64 v58, v74, v58, s[0:1]
	v_lshl_add_u64 v[74:75], v[80:81], 0, v[64:65]
	v_lshlrev_b64 v[74:75], 14, v[74:75]
	v_sub_f32_e32 v0, v0, v58
	v_lshl_add_u64 v[74:75], v[78:79], 0, v[74:75]
	global_store_dword v[74:75], v0, off
;     __device__ __forceinline__ void operator()(const f32x4 (&acc)[2][2][4][2], const pg8::Unit& u, int wr, int wc, int fr, int fq) const {
;     ...
;         if (kind == 1 && pn == 28) {
;             if (wc == 0) {
; #pragma unroll
;                 for (int ai = 0; ai < 2; ++ai)
; #pragma unroll
;                     for (int m = 0; m < 4; ++m) { const int row = row0 + ai * 128 + m * 16;
; #pragma unroll
;                         for (int n = 0; n < 2; ++n)
; #pragma unroll
;                             for (int j = 0; j < 4; ++j) { const int col = 8 * fq + 4 * n + j;
;                                 if (col < 12) { const float xv = acc[ai][0][m][n][j] * rsqrtf(ssq[row] * (1.f / DM) + EPS) + bfp[col]; LS[((size_t)(row >> 12) * 12 + col) * SEQ + (row & (SEQ - 1))] = fminf(xv, 0.f) - log1pf(expf(-fabsf(xv))); } } }
.LBB0_521:
	s_or_b64 exec, exec, s[14:15]
	v_or_b32_e32 v74, 5, v68
	v_cmp_gt_i32_e64 s[14:15], 12, v74
	v_ashrrev_i32_e32 v75, 31, v74
	s_and_saveexec_b64 s[16:17], s[14:15]
	s_cbranch_execz .LBB0_523
	global_load_dword v0, v[66:67], off
	v_lshl_add_u64 v[76:77], v[74:75], 2, s[60:61]
	s_waitcnt vmcnt(0) lgkmcnt(0)
	v_fmamk_f32 v0, v0, 0x3a000000, v205
	v_cmp_gt_f32_e64 s[0:1], s68, v0
	v_mul_f32_e32 v58, 0x4b800000, v0
	s_nop 0
	v_cndmask_b32_e64 v0, v0, v58, s[0:1]
	v_rsq_f32_e32 v0, v0
	s_nop 0
	v_mul_f32_e32 v58, 0x45800000, v0
	v_cndmask_b32_e64 v0, v0, v58, s[0:1]
	global_load_dword v58, v[76:77], off
	s_waitcnt vmcnt(0) lgkmcnt(0)
	v_fmac_f32_e32 v58, v59, v0
	v_mul_f32_e64 v59, |v58|, s88
	v_fma_f32 v76, |v58|, s88, -v59
	v_rndne_f32_e32 v77, v59
	v_fma_f32 v76, |v58|, s89, v76
	v_sub_f32_e32 v59, v59, v77
	v_add_f32_e32 v59, v59, v76
	v_exp_f32_e32 v59, v59
	v_cvt_i32_f32_e32 v76, v77
	v_cmp_ngt_f32_e64 s[0:1], |v58|, s70
	v_min_f32_e32 v0, 0, v58
	v_ldexp_f32 v59, v59, v76
	v_cndmask_b32_e64 v59, 0, v59, s[0:1]
	v_cmp_nlt_f32_e64 s[0:1], |v58|, s90
	s_nop 1
	v_cndmask_b32_e64 v92, v208, v59, s[0:1]
	v_add_f32_e32 v76, 1.0, v92
	v_add_f32_e32 v58, -1.0, v76
	v_sub_f32_e32 v59, v58, v76
	v_add_f32_e32 v59, 1.0, v59
	v_sub_f32_e32 v58, v92, v58
	v_add_f32_e32 v77, v58, v59
	v_frexp_mant_f32_e32 v58, v76
	v_cmp_gt_f32_e64 s[0:1], s3, v58
	v_cvt_f64_f32_e32 v[58:59], v76
	v_frexp_exp_i32_f64_e32 v58, v[58:59]
	v_subbrev_co_u32_e64 v86, s[0:1], 0, v58, s[0:1]
	v_sub_u32_e32 v58, 0, v86
	v_ldexp_f32 v59, v76, v58
	v_add_f32_e32 v76, -1.0, v59
	v_add_f32_e32 v82, 1.0, v59
	v_ldexp_f32 v58, v77, v58
	v_add_f32_e32 v77, 1.0, v76
	v_add_f32_e32 v83, -1.0, v82
	v_sub_f32_e32 v77, v59, v77
	v_sub_f32_e32 v59, v59, v83
	v_add_f32_e32 v77, v58, v77
	v_add_f32_e32 v58, v58, v59
	v_add_f32_e32 v87, v82, v58
	v_rcp_f32_e32 v89, v87
	v_sub_f32_e32 v59, v82, v87
	v_add_f32_e32 v88, v58, v59
	v_add_f32_e32 v59, v76, v77
	v_mul_f32_e32 v91, v59, v89
	v_sub_f32_e32 v58, v76, v59
	v_mul_f32_e32 v76, v87, v91
	v_fma_f32 v82, v91, v87, -v76
	v_fmac_f32_e32 v82, v91, v88
	v_add_f32_e32 v90, v77, v58
	v_add_f32_e32 v58, v76, v82
	v_sub_f32_e32 v77, v59, v58
	v_pk_add_f32 v[84:85], v[58:59], v[76:77] neg_lo:[0,1] neg_hi:[0,1]
	v_mov_b32_e32 v83, v58
	v_pk_add_f32 v[58:59], v[84:85], v[82:83] neg_lo:[0,1] neg_hi:[0,1]
	v_cmp_neq_f32_e64 s[0:1], s2, v92
	v_add_f32_e32 v59, v90, v59
	v_add_f32_e32 v58, v58, v59
	v_add_f32_e32 v59, v77, v58
	v_mul_f32_e32 v90, v89, v59
	v_mul_f32_e32 v76, v87, v90
	v_fma_f32 v82, v90, v87, -v76
	v_fmac_f32_e32 v82, v90, v88
	v_sub_f32_e32 v77, v77, v59
	v_add_f32_e32 v87, v58, v77
	v_add_f32_e32 v58, v76, v82
	v_sub_f32_e32 v77, v59, v58
	v_pk_add_f32 v[84:85], v[58:59], v[76:77] neg_lo:[0,1] neg_hi:[0,1]
	v_mov_b32_e32 v83, v58
	v_pk_add_f32 v[58:59], v[84:85], v[82:83] neg_lo:[0,1] neg_hi:[0,1]
	s_nop 0
	v_add_f32_e32 v59, v87, v59
	v_add_f32_e32 v58, v58, v59
	v_add_f32_e32 v59, v91, v90
	v_add_f32_e32 v58, v77, v58
	v_sub_f32_e32 v76, v59, v91
	v_mul_f32_e32 v58, v89, v58
	v_sub_f32_e32 v76, v90, v76
	v_add_f32_e32 v76, v76, v58
	v_add_f32_e32 v82, v59, v76
	v_mul_f32_e32 v83, v82, v82
	v_fmamk_f32 v58, v83, 0x3e9b6dac, v206
	v_fmaak_f32 v179, v83, v58, 0x3f2aaada
	v_cvt_f32_i32_e32 v58, v86
	v_sub_f32_e32 v59, v82, v59
	v_sub_f32_e32 v59, v76, v59
	v_ldexp_f32 v84, v59, 1
	v_mul_f32_e32 v59, v82, v83
	v_ldexp_f32 v77, v82, 1
	v_pk_mul_f32 v[82:83], v[58:59], v[178:179]
	s_nop 0
	v_fma_f32 v76, v58, s69, -v82
	v_fmac_f32_e32 v76, 0xb102e308, v58
	v_pk_add_f32 v[58:59], v[82:83], v[76:77]
	s_nop 0
	v_sub_f32_e32 v77, v59, v77
	v_sub_f32_e32 v77, v83, v77
	v_add_f32_e32 v85, v84, v77
	v_mov_b32_e32 v84, v82
	v_pk_add_f32 v[82:83], v[58:59], v[82:83] neg_lo:[0,1] neg_hi:[0,1]
	v_pk_add_f32 v[86:87], v[58:59], v[84:85]
	v_mov_b32_e32 v77, v58
	v_mov_b32_e32 v83, v87
	v_pk_add_f32 v[88:89], v[76:77], v[82:83] neg_lo:[0,1] neg_hi:[0,1]
	v_pk_add_f32 v[76:77], v[76:77], v[82:83]
	v_mov_b32_e32 v84, v85
	v_pk_add_f32 v[82:83], v[76:77], v[58:59] op_sel:[1,0] op_sel_hi:[0,1] neg_lo:[0,1] neg_hi:[0,1]
	v_pk_add_f32 v[90:91], v[86:87], v[82:83] op_sel_hi:[1,0] neg_lo:[0,1] neg_hi:[0,1]
	v_mov_b32_e32 v86, v87
	v_mov_b32_e32 v87, v77
	v_pk_mov_b32 v[82:83], v[58:59], v[82:83] op_sel:[1,0]
	v_mov_b32_e32 v85, v58
	v_pk_add_f32 v[82:83], v[86:87], v[82:83] neg_lo:[0,1] neg_hi:[0,1]
	v_mov_b32_e32 v90, v88
	v_pk_add_f32 v[58:59], v[84:85], v[82:83] neg_lo:[0,1] neg_hi:[0,1]
	v_mov_b32_e32 v89, v77
	v_pk_add_f32 v[82:83], v[90:91], v[58:59]
	s_nop 0
	v_pk_add_f32 v[84:85], v[82:83], v[82:83] op_sel:[0,1] op_sel_hi:[1,0]
	s_nop 0
	v_pk_add_f32 v[76:77], v[76:77], v[84:85] op_sel:[1,0] op_sel_hi:[0,1]
	v_mov_b32_e32 v83, v76
	v_pk_add_f32 v[86:87], v[82:83], v[88:89] neg_lo:[0,1] neg_hi:[0,1]
	v_mov_b32_e32 v59, v84
	v_sub_f32_e32 v77, v82, v86
	v_pk_add_f32 v[58:59], v[58:59], v[86:87] neg_lo:[0,1] neg_hi:[0,1]
	v_sub_f32_e32 v77, v88, v77
	v_add_f32_e32 v58, v58, v77
	v_add_f32_e32 v58, v58, v59
	v_add_f32_e32 v58, v76, v58
	v_cndmask_b32_e64 v58, v208, v58, s[0:1]
	v_cmp_lt_f32_e64 s[0:1], |v92|, s66
	s_nop 1
	v_cndmask_b32_e64 v58, v58, v92, s[0:1]
	v_sub_f32_e32 v0, v0, v58
	v_lshl_add_u64 v[58:59], v[80:81], 0, v[74:75]
	v_lshlrev_b64 v[58:59], 14, v[58:59]
	v_lshl_add_u64 v[58:59], v[78:79], 0, v[58:59]
	global_store_dword v[58:59], v0, off
;     __device__ __forceinline__ void operator()(const f32x4 (&acc)[2][2][4][2], const pg8::Unit& u, int wr, int wc, int fr, int fq) const {
;     ...
;         if (kind == 1 && pn == 28) {
;             if (wc == 0) {
; #pragma unroll
;                 for (int ai = 0; ai < 2; ++ai)
; #pragma unroll
;                     for (int m = 0; m < 4; ++m) { const int row = row0 + ai * 128 + m * 16;
; #pragma unroll
;                         for (int n = 0; n < 2; ++n)
; #pragma unroll
;                             for (int j = 0; j < 4; ++j) { const int col = 8 * fq + 4 * n + j;
;                                 if (col < 12) { const float xv = acc[ai][0][m][n][j] * rsqrtf(ssq[row] * (1.f / DM) + EPS) + bfp[col]; LS[((size_t)(row >> 12) * 12 + col) * SEQ + (row & (SEQ - 1))] = fminf(xv, 0.f) - log1pf(expf(-fabsf(xv))); } } }
.LBB0_523:
	s_or_b64 exec, exec, s[16:17]
	v_or_b32_e32 v58, 6, v68
	v_cmp_gt_i32_e64 s[16:17], 12, v58
	v_ashrrev_i32_e32 v59, 31, v58
	s_and_saveexec_b64 s[18:19], s[16:17]
	s_cbranch_execz .LBB0_525
	global_load_dword v0, v[66:67], off
	s_waitcnt vmcnt(0) lgkmcnt(0)
	v_fmamk_f32 v0, v0, 0x3a000000, v205
	v_cmp_gt_f32_e64 s[0:1], s68, v0
	v_mul_f32_e32 v76, 0x4b800000, v0
	s_nop 0
	v_cndmask_b32_e64 v0, v0, v76, s[0:1]
	v_rsq_f32_e32 v0, v0
	s_nop 0
	v_mul_f32_e32 v76, 0x45800000, v0
	v_cndmask_b32_e64 v0, v0, v76, s[0:1]
	v_lshl_add_u64 v[76:77], v[58:59], 2, s[60:61]
	global_load_dword v76, v[76:77], off
	s_waitcnt vmcnt(0) lgkmcnt(0)
	v_fmac_f32_e32 v76, v60, v0
	v_mul_f32_e64 v60, |v76|, s88
	v_fma_f32 v77, |v76|, s88, -v60
	v_rndne_f32_e32 v82, v60
	v_fma_f32 v77, |v76|, s89, v77
	v_sub_f32_e32 v60, v60, v82
	v_add_f32_e32 v60, v60, v77
	v_exp_f32_e32 v60, v60
	v_cvt_i32_f32_e32 v77, v82
	v_cmp_ngt_f32_e64 s[0:1], |v76|, s70
	v_min_f32_e32 v0, 0, v76
	v_ldexp_f32 v60, v60, v77
	v_cndmask_b32_e64 v60, 0, v60, s[0:1]
	v_cmp_nlt_f32_e64 s[0:1], |v76|, s90
	s_nop 1
	v_cndmask_b32_e64 v60, v208, v60, s[0:1]
	v_add_f32_e32 v82, 1.0, v60
	v_add_f32_e32 v76, -1.0, v82
	v_sub_f32_e32 v77, v76, v82
	v_add_f32_e32 v77, 1.0, v77
	v_sub_f32_e32 v76, v60, v76
	v_add_f32_e32 v83, v76, v77
	v_frexp_mant_f32_e32 v76, v82
	v_cmp_gt_f32_e64 s[0:1], s3, v76
	v_cvt_f64_f32_e32 v[76:77], v82
	v_frexp_exp_i32_f64_e32 v76, v[76:77]
	v_subbrev_co_u32_e64 v88, s[0:1], 0, v76, s[0:1]
	v_sub_u32_e32 v76, 0, v88
	v_ldexp_f32 v77, v82, v76
	v_add_f32_e32 v82, -1.0, v77
	v_add_f32_e32 v84, 1.0, v77
	v_ldexp_f32 v76, v83, v76
	v_add_f32_e32 v83, 1.0, v82
	v_add_f32_e32 v85, -1.0, v84
	v_sub_f32_e32 v83, v77, v83
	v_sub_f32_e32 v77, v77, v85
	v_add_f32_e32 v83, v76, v83
	v_add_f32_e32 v76, v76, v77
	v_add_f32_e32 v89, v84, v76
	v_rcp_f32_e32 v91, v89
	v_sub_f32_e32 v77, v84, v89
	v_add_f32_e32 v90, v76, v77
	v_add_f32_e32 v77, v82, v83
	v_mul_f32_e32 v93, v77, v91
	v_sub_f32_e32 v76, v82, v77
	v_mul_f32_e32 v82, v89, v93
	v_fma_f32 v84, v93, v89, -v82
	v_fmac_f32_e32 v84, v93, v90
	v_add_f32_e32 v92, v83, v76
	v_add_f32_e32 v76, v82, v84
	v_sub_f32_e32 v83, v77, v76
	v_pk_add_f32 v[86:87], v[76:77], v[82:83] neg_lo:[0,1] neg_hi:[0,1]
	v_mov_b32_e32 v85, v76
	v_pk_add_f32 v[76:77], v[86:87], v[84:85] neg_lo:[0,1] neg_hi:[0,1]
	v_cmp_neq_f32_e64 s[0:1], s2, v60
	v_add_f32_e32 v77, v92, v77
	v_add_f32_e32 v76, v76, v77
	v_add_f32_e32 v77, v83, v76
	v_mul_f32_e32 v92, v91, v77
	v_mul_f32_e32 v82, v89, v92
	v_fma_f32 v84, v92, v89, -v82
	v_fmac_f32_e32 v84, v92, v90
	v_sub_f32_e32 v83, v83, v77
	v_add_f32_e32 v89, v76, v83
	v_add_f32_e32 v76, v82, v84
	v_sub_f32_e32 v83, v77, v76
	v_pk_add_f32 v[86:87], v[76:77], v[82:83] neg_lo:[0,1] neg_hi:[0,1]
	v_mov_b32_e32 v85, v76
	v_pk_add_f32 v[76:77], v[86:87], v[84:85] neg_lo:[0,1] neg_hi:[0,1]
	s_nop 0
	v_add_f32_e32 v77, v89, v77
	v_add_f32_e32 v76, v76, v77
	v_add_f32_e32 v77, v93, v92
	v_add_f32_e32 v76, v83, v76
	v_sub_f32_e32 v82, v77, v93
	v_mul_f32_e32 v76, v91, v76
	v_sub_f32_e32 v82, v92, v82
	v_add_f32_e32 v82, v82, v76
	v_add_f32_e32 v84, v77, v82
	v_mul_f32_e32 v85, v84, v84
	v_fmamk_f32 v76, v85, 0x3e9b6dac, v206
	v_fmaak_f32 v179, v85, v76, 0x3f2aaada
	v_cvt_f32_i32_e32 v76, v88
	v_sub_f32_e32 v77, v84, v77
	v_sub_f32_e32 v77, v82, v77
	v_ldexp_f32 v86, v77, 1
	v_mul_f32_e32 v77, v84, v85
	v_ldexp_f32 v83, v84, 1
	v_pk_mul_f32 v[84:85], v[76:77], v[178:179]
	s_nop 0
	v_fma_f32 v82, v76, s69, -v84
	v_fmac_f32_e32 v82, 0xb102e308, v76
	v_pk_add_f32 v[76:77], v[84:85], v[82:83]
	s_nop 0
	v_sub_f32_e32 v83, v77, v83
	v_sub_f32_e32 v83, v85, v83
	v_add_f32_e32 v87, v86, v83
	v_mov_b32_e32 v86, v84
	v_pk_add_f32 v[84:85], v[76:77], v[84:85] neg_lo:[0,1] neg_hi:[0,1]
	v_pk_add_f32 v[88:89], v[76:77], v[86:87]
	v_mov_b32_e32 v83, v76
	v_mov_b32_e32 v85, v89
	v_pk_add_f32 v[90:91], v[82:83], v[84:85] neg_lo:[0,1] neg_hi:[0,1]
	v_pk_add_f32 v[82:83], v[82:83], v[84:85]
	v_mov_b32_e32 v86, v87
	v_pk_add_f32 v[84:85], v[82:83], v[76:77] op_sel:[1,0] op_sel_hi:[0,1] neg_lo:[0,1] neg_hi:[0,1]
	v_pk_add_f32 v[92:93], v[88:89], v[84:85] op_sel_hi:[1,0] neg_lo:[0,1] neg_hi:[0,1]
	v_mov_b32_e32 v88, v89
	v_mov_b32_e32 v89, v83
	v_pk_mov_b32 v[84:85], v[76:77], v[84:85] op_sel:[1,0]
	v_mov_b32_e32 v87, v76
	v_pk_add_f32 v[84:85], v[88:89], v[84:85] neg_lo:[0,1] neg_hi:[0,1]
	v_mov_b32_e32 v92, v90
	v_pk_add_f32 v[76:77], v[86:87], v[84:85] neg_lo:[0,1] neg_hi:[0,1]
	v_mov_b32_e32 v91, v83
	v_pk_add_f32 v[84:85], v[92:93], v[76:77]
	s_nop 0
	v_pk_add_f32 v[86:87], v[84:85], v[84:85] op_sel:[0,1] op_sel_hi:[1,0]
	s_nop 0
	v_pk_add_f32 v[82:83], v[82:83], v[86:87] op_sel:[1,0] op_sel_hi:[0,1]
	v_mov_b32_e32 v85, v82
	v_pk_add_f32 v[88:89], v[84:85], v[90:91] neg_lo:[0,1] neg_hi:[0,1]
	v_mov_b32_e32 v77, v86
	v_sub_f32_e32 v83, v84, v88
	v_pk_add_f32 v[76:77], v[76:77], v[88:89] neg_lo:[0,1] neg_hi:[0,1]
	v_sub_f32_e32 v83, v90, v83
	v_add_f32_e32 v76, v76, v83
	v_add_f32_e32 v76, v76, v77
	v_add_f32_e32 v76, v82, v76
	v_cndmask_b32_e64 v76, v208, v76, s[0:1]
	v_cmp_lt_f32_e64 s[0:1], |v60|, s66
	s_nop 1
	v_cndmask_b32_e64 v60, v76, v60, s[0:1]
	v_lshl_add_u64 v[76:77], v[80:81], 0, v[58:59]
	v_lshlrev_b64 v[76:77], 14, v[76:77]
	v_sub_f32_e32 v0, v0, v60
	v_lshl_add_u64 v[76:77], v[78:79], 0, v[76:77]
	global_store_dword v[76:77], v0, off
;     __device__ __forceinline__ void operator()(const f32x4 (&acc)[2][2][4][2], const pg8::Unit& u, int wr, int wc, int fr, int fq) const {
;     ...
;         if (kind == 1 && pn == 28) {
;             if (wc == 0) {
; #pragma unroll
;                 for (int ai = 0; ai < 2; ++ai)
; #pragma unroll
;                     for (int m = 0; m < 4; ++m) { const int row = row0 + ai * 128 + m * 16;
; #pragma unroll
;                         for (int n = 0; n < 2; ++n)
; #pragma unroll
;                             for (int j = 0; j < 4; ++j) { const int col = 8 * fq + 4 * n + j;
;                                 if (col < 12) { const float xv = acc[ai][0][m][n][j] * rsqrtf(ssq[row] * (1.f / DM) + EPS) + bfp[col]; LS[((size_t)(row >> 12) * 12 + col) * SEQ + (row & (SEQ - 1))] = fminf(xv, 0.f) - log1pf(expf(-fabsf(xv))); } } }
.LBB0_525:
	s_or_b64 exec, exec, s[18:19]
	v_or_b32_e32 v76, 7, v68
	v_cmp_gt_i32_e64 s[18:19], 12, v76
	v_ashrrev_i32_e32 v77, 31, v76
	s_and_saveexec_b64 s[84:85], s[18:19]
	s_cbranch_execz .LBB0_527
	global_load_dword v0, v[66:67], off
	v_lshl_add_u64 v[82:83], v[76:77], 2, s[60:61]
	s_waitcnt vmcnt(0) lgkmcnt(0)
	v_fmamk_f32 v0, v0, 0x3a000000, v205
	v_cmp_gt_f32_e64 s[0:1], s68, v0
	v_mul_f32_e32 v60, 0x4b800000, v0
	s_nop 0
	v_cndmask_b32_e64 v0, v0, v60, s[0:1]
	v_rsq_f32_e32 v0, v0
	s_nop 0
	v_mul_f32_e32 v60, 0x45800000, v0
	v_cndmask_b32_e64 v0, v0, v60, s[0:1]
	global_load_dword v60, v[82:83], off
	s_waitcnt vmcnt(0) lgkmcnt(0)
	v_fmac_f32_e32 v60, v61, v0
	v_mul_f32_e64 v61, |v60|, s88
	v_fma_f32 v82, |v60|, s88, -v61
	v_rndne_f32_e32 v83, v61
	v_fma_f32 v82, |v60|, s89, v82
	v_sub_f32_e32 v61, v61, v83
	v_add_f32_e32 v61, v61, v82
	v_exp_f32_e32 v61, v61
	v_cvt_i32_f32_e32 v82, v83
	v_cmp_ngt_f32_e64 s[0:1], |v60|, s70
	v_min_f32_e32 v0, 0, v60
	v_ldexp_f32 v61, v61, v82
	v_cndmask_b32_e64 v61, 0, v61, s[0:1]
	v_cmp_nlt_f32_e64 s[0:1], |v60|, s90
	s_nop 1
	v_cndmask_b32_e64 v94, v208, v61, s[0:1]
	v_add_f32_e32 v82, 1.0, v94
	v_add_f32_e32 v60, -1.0, v82
	v_sub_f32_e32 v61, v60, v82
	v_add_f32_e32 v61, 1.0, v61
	v_sub_f32_e32 v60, v94, v60
	v_add_f32_e32 v83, v60, v61
	v_frexp_mant_f32_e32 v60, v82
	v_cmp_gt_f32_e64 s[0:1], s3, v60
	v_cvt_f64_f32_e32 v[60:61], v82
	v_frexp_exp_i32_f64_e32 v60, v[60:61]
	v_subbrev_co_u32_e64 v88, s[0:1], 0, v60, s[0:1]
	v_sub_u32_e32 v60, 0, v88
	v_ldexp_f32 v61, v82, v60
	v_add_f32_e32 v82, -1.0, v61
	v_add_f32_e32 v84, 1.0, v61
	v_ldexp_f32 v60, v83, v60
	v_add_f32_e32 v83, 1.0, v82
	v_add_f32_e32 v85, -1.0, v84
	v_sub_f32_e32 v83, v61, v83
	v_sub_f32_e32 v61, v61, v85
	v_add_f32_e32 v83, v60, v83
	v_add_f32_e32 v60, v60, v61
	v_add_f32_e32 v89, v84, v60
	v_rcp_f32_e32 v91, v89
	v_sub_f32_e32 v61, v84, v89
	v_add_f32_e32 v90, v60, v61
	v_add_f32_e32 v61, v82, v83
	v_mul_f32_e32 v93, v61, v91
	v_sub_f32_e32 v60, v82, v61
	v_mul_f32_e32 v82, v89, v93
	v_fma_f32 v84, v93, v89, -v82
	v_fmac_f32_e32 v84, v93, v90
	v_add_f32_e32 v92, v83, v60
	v_add_f32_e32 v60, v82, v84
	v_sub_f32_e32 v83, v61, v60
	v_pk_add_f32 v[86:87], v[60:61], v[82:83] neg_lo:[0,1] neg_hi:[0,1]
	v_mov_b32_e32 v85, v60
	v_pk_add_f32 v[60:61], v[86:87], v[84:85] neg_lo:[0,1] neg_hi:[0,1]
	v_cmp_neq_f32_e64 s[0:1], s2, v94
	v_add_f32_e32 v61, v92, v61
	v_add_f32_e32 v60, v60, v61
	v_add_f32_e32 v61, v83, v60
	v_mul_f32_e32 v92, v91, v61
	v_mul_f32_e32 v82, v89, v92
	v_fma_f32 v84, v92, v89, -v82
	v_fmac_f32_e32 v84, v92, v90
	v_sub_f32_e32 v83, v83, v61
	v_add_f32_e32 v89, v60, v83
	v_add_f32_e32 v60, v82, v84
	v_sub_f32_e32 v83, v61, v60
	v_pk_add_f32 v[86:87], v[60:61], v[82:83] neg_lo:[0,1] neg_hi:[0,1]
	v_mov_b32_e32 v85, v60
	v_pk_add_f32 v[60:61], v[86:87], v[84:85] neg_lo:[0,1] neg_hi:[0,1]
	s_nop 0
	v_add_f32_e32 v61, v89, v61
	v_add_f32_e32 v60, v60, v61
	v_add_f32_e32 v61, v93, v92
	v_add_f32_e32 v60, v83, v60
	v_sub_f32_e32 v82, v61, v93
	v_mul_f32_e32 v60, v91, v60
	v_sub_f32_e32 v82, v92, v82
	v_add_f32_e32 v82, v82, v60
	v_add_f32_e32 v84, v61, v82
	v_mul_f32_e32 v85, v84, v84
	v_fmamk_f32 v60, v85, 0x3e9b6dac, v206
	v_fmaak_f32 v179, v85, v60, 0x3f2aaada
	v_cvt_f32_i32_e32 v60, v88
	v_sub_f32_e32 v61, v84, v61
	v_sub_f32_e32 v61, v82, v61
	v_ldexp_f32 v86, v61, 1
	v_mul_f32_e32 v61, v84, v85
	v_ldexp_f32 v83, v84, 1
	v_pk_mul_f32 v[84:85], v[60:61], v[178:179]
	s_nop 0
	v_fma_f32 v82, v60, s69, -v84
	v_fmac_f32_e32 v82, 0xb102e308, v60
	v_pk_add_f32 v[60:61], v[84:85], v[82:83]
	s_nop 0
	v_sub_f32_e32 v83, v61, v83
	v_sub_f32_e32 v83, v85, v83
	v_add_f32_e32 v87, v86, v83
	v_mov_b32_e32 v86, v84
	v_pk_add_f32 v[84:85], v[60:61], v[84:85] neg_lo:[0,1] neg_hi:[0,1]
	v_pk_add_f32 v[88:89], v[60:61], v[86:87]
	v_mov_b32_e32 v83, v60
	v_mov_b32_e32 v85, v89
	v_pk_add_f32 v[90:91], v[82:83], v[84:85] neg_lo:[0,1] neg_hi:[0,1]
	v_pk_add_f32 v[82:83], v[82:83], v[84:85]
	v_mov_b32_e32 v86, v87
	v_pk_add_f32 v[84:85], v[82:83], v[60:61] op_sel:[1,0] op_sel_hi:[0,1] neg_lo:[0,1] neg_hi:[0,1]
	v_pk_add_f32 v[92:93], v[88:89], v[84:85] op_sel_hi:[1,0] neg_lo:[0,1] neg_hi:[0,1]
	v_mov_b32_e32 v88, v89
	v_mov_b32_e32 v89, v83
	v_pk_mov_b32 v[84:85], v[60:61], v[84:85] op_sel:[1,0]
	v_mov_b32_e32 v87, v60
	v_pk_add_f32 v[84:85], v[88:89], v[84:85] neg_lo:[0,1] neg_hi:[0,1]
	v_mov_b32_e32 v92, v90
	v_pk_add_f32 v[60:61], v[86:87], v[84:85] neg_lo:[0,1] neg_hi:[0,1]
	v_mov_b32_e32 v91, v83
	v_pk_add_f32 v[84:85], v[92:93], v[60:61]
	s_nop 0
	v_pk_add_f32 v[86:87], v[84:85], v[84:85] op_sel:[0,1] op_sel_hi:[1,0]
	s_nop 0
	v_pk_add_f32 v[82:83], v[82:83], v[86:87] op_sel:[1,0] op_sel_hi:[0,1]
	v_mov_b32_e32 v85, v82
	v_pk_add_f32 v[88:89], v[84:85], v[90:91] neg_lo:[0,1] neg_hi:[0,1]
	v_mov_b32_e32 v61, v86
	v_sub_f32_e32 v83, v84, v88
	v_pk_add_f32 v[60:61], v[60:61], v[88:89] neg_lo:[0,1] neg_hi:[0,1]
	v_sub_f32_e32 v83, v90, v83
	v_add_f32_e32 v60, v60, v83
	v_add_f32_e32 v60, v60, v61
	v_add_f32_e32 v60, v82, v60
	v_cndmask_b32_e64 v60, v208, v60, s[0:1]
	v_cmp_lt_f32_e64 s[0:1], |v94|, s66
	s_nop 1
	v_cndmask_b32_e64 v60, v60, v94, s[0:1]
	v_sub_f32_e32 v0, v0, v60
	v_lshl_add_u64 v[60:61], v[80:81], 0, v[76:77]
	v_lshlrev_b64 v[60:61], 14, v[60:61]
	v_lshl_add_u64 v[60:61], v[78:79], 0, v[60:61]
	global_store_dword v[60:61], v0, off

;     __device__ __forceinline__ void operator()(const f32x4 (&acc)[2][2][4][2], const pg8::Unit& u, int wr, int wc, int fr, int fq) const {
;     ...
;         if (kind == 1 && pn == 28) {
;             if (wc == 0) {
; #pragma unroll
;                 for (int ai = 0; ai < 2; ++ai)
; #pragma unroll
;                     for (int m = 0; m < 4; ++m) { const int row = row0 + ai * 128 + m * 16;
; #pragma unroll
;                         for (int n = 0; n < 2; ++n)
; #pragma unroll
;                             for (int j = 0; j < 4; ++j) { const int col = 8 * fq + 4 * n + j;
;                                 if (col < 12) { const float xv = acc[ai][0][m][n][j] * rsqrtf(ssq[row] * (1.f / DM) + EPS) + bfp[col]; LS[((size_t)(row >> 12) * 12 + col) * SEQ + (row & (SEQ - 1))] = fminf(xv, 0.f) - log1pf(expf(-fabsf(xv))); } } }
.LBB0_535:
	global_load_dword v0, v[66:67], off offset:64
	s_waitcnt vmcnt(0) lgkmcnt(0)
	v_fmamk_f32 v0, v0, 0x3a000000, v205
	v_cmp_gt_f32_e64 s[0:1], s68, v0
	v_mul_f32_e32 v50, 0x4b800000, v0
	s_nop 0
	v_cndmask_b32_e64 v0, v0, v50, s[0:1]
	v_rsq_f32_e32 v0, v0
	s_nop 0
	v_mul_f32_e32 v50, 0x45800000, v0
	v_cndmask_b32_e64 v0, v0, v50, s[0:1]
	v_lshl_add_u64 v[50:51], v[76:77], 2, s[60:61]
	global_load_dword v50, v[50:51], off
	s_waitcnt vmcnt(0) lgkmcnt(0)
	v_fmac_f32_e32 v50, v53, v0
	v_mul_f32_e64 v51, |v50|, s88
	v_fma_f32 v52, |v50|, s88, -v51
	v_rndne_f32_e32 v53, v51
	v_fma_f32 v52, |v50|, s89, v52
	v_sub_f32_e32 v51, v51, v53
	v_add_f32_e32 v51, v51, v52
	v_exp_f32_e32 v51, v51
	v_cvt_i32_f32_e32 v52, v53
	v_cmp_ngt_f32_e64 s[0:1], |v50|, s70
	v_min_f32_e32 v0, 0, v50
	v_ldexp_f32 v51, v51, v52
	v_cndmask_b32_e64 v51, 0, v51, s[0:1]
	v_cmp_nlt_f32_e64 s[0:1], |v50|, s90
	s_nop 1
	v_cndmask_b32_e64 v86, v208, v51, s[0:1]
	v_add_f32_e32 v52, 1.0, v86
	v_add_f32_e32 v50, -1.0, v52
	v_sub_f32_e32 v51, v50, v52
	v_add_f32_e32 v51, 1.0, v51
	v_sub_f32_e32 v50, v86, v50
	v_add_f32_e32 v53, v50, v51
	v_frexp_mant_f32_e32 v50, v52
	v_cmp_gt_f32_e64 s[0:1], s3, v50
	v_cvt_f64_f32_e32 v[50:51], v52
	v_frexp_exp_i32_f64_e32 v50, v[50:51]
	v_subbrev_co_u32_e64 v80, s[0:1], 0, v50, s[0:1]
	v_sub_u32_e32 v50, 0, v80
	v_ldexp_f32 v51, v52, v50
	v_add_f32_e32 v52, -1.0, v51
	v_add_f32_e32 v54, 1.0, v51
	v_ldexp_f32 v50, v53, v50
	v_add_f32_e32 v53, 1.0, v52
	v_add_f32_e32 v55, -1.0, v54
	v_sub_f32_e32 v53, v51, v53
	v_sub_f32_e32 v51, v51, v55
	v_add_f32_e32 v53, v50, v53
	v_add_f32_e32 v50, v50, v51
	v_add_f32_e32 v81, v54, v50
	v_rcp_f32_e32 v83, v81
	v_sub_f32_e32 v51, v54, v81
	v_add_f32_e32 v82, v50, v51
	v_add_f32_e32 v51, v52, v53
	v_mul_f32_e32 v85, v51, v83
	v_sub_f32_e32 v50, v52, v51
	v_mul_f32_e32 v52, v81, v85
	v_fma_f32 v54, v85, v81, -v52
	v_fmac_f32_e32 v54, v85, v82
	v_add_f32_e32 v84, v53, v50
	v_add_f32_e32 v50, v52, v54
	v_sub_f32_e32 v53, v51, v50
	v_pk_add_f32 v[56:57], v[50:51], v[52:53] neg_lo:[0,1] neg_hi:[0,1]
	v_mov_b32_e32 v55, v50
	v_pk_add_f32 v[50:51], v[56:57], v[54:55] neg_lo:[0,1] neg_hi:[0,1]
	v_cmp_neq_f32_e64 s[0:1], s2, v86
	v_add_f32_e32 v51, v84, v51
	v_add_f32_e32 v50, v50, v51
	v_add_f32_e32 v51, v53, v50
	v_mul_f32_e32 v84, v83, v51
	v_mul_f32_e32 v52, v81, v84
	v_fma_f32 v54, v84, v81, -v52
	v_fmac_f32_e32 v54, v84, v82
	v_sub_f32_e32 v53, v53, v51
	v_add_f32_e32 v81, v50, v53
	v_add_f32_e32 v50, v52, v54
	v_sub_f32_e32 v53, v51, v50
	v_pk_add_f32 v[56:57], v[50:51], v[52:53] neg_lo:[0,1] neg_hi:[0,1]
	v_mov_b32_e32 v55, v50
	v_pk_add_f32 v[50:51], v[56:57], v[54:55] neg_lo:[0,1] neg_hi:[0,1]
	s_nop 0
	v_add_f32_e32 v51, v81, v51
	v_add_f32_e32 v50, v50, v51
	v_add_f32_e32 v51, v85, v84
	v_add_f32_e32 v50, v53, v50
	v_sub_f32_e32 v52, v51, v85
	v_mul_f32_e32 v50, v83, v50
	v_sub_f32_e32 v52, v84, v52
	v_add_f32_e32 v52, v52, v50
	v_add_f32_e32 v54, v51, v52
	v_mul_f32_e32 v55, v54, v54
	v_fmamk_f32 v50, v55, 0x3e9b6dac, v206
	v_fmaak_f32 v179, v55, v50, 0x3f2aaada
	v_cvt_f32_i32_e32 v50, v80
	v_sub_f32_e32 v51, v54, v51
	v_sub_f32_e32 v51, v52, v51
	v_ldexp_f32 v56, v51, 1
	v_mul_f32_e32 v51, v54, v55
	v_ldexp_f32 v53, v54, 1
	v_pk_mul_f32 v[54:55], v[50:51], v[178:179]
	s_nop 0
	v_fma_f32 v52, v50, s69, -v54
	v_fmac_f32_e32 v52, 0xb102e308, v50
	v_pk_add_f32 v[50:51], v[54:55], v[52:53]
	s_nop 0
	v_sub_f32_e32 v53, v51, v53
	v_sub_f32_e32 v53, v55, v53
	v_add_f32_e32 v57, v56, v53
	v_mov_b32_e32 v56, v54
	v_pk_add_f32 v[54:55], v[50:51], v[54:55] neg_lo:[0,1] neg_hi:[0,1]
	v_pk_add_f32 v[80:81], v[50:51], v[56:57]
	v_mov_b32_e32 v53, v50
	v_mov_b32_e32 v55, v81
	v_pk_add_f32 v[82:83], v[52:53], v[54:55] neg_lo:[0,1] neg_hi:[0,1]
	v_pk_add_f32 v[52:53], v[52:53], v[54:55]
	v_mov_b32_e32 v56, v57
	v_pk_add_f32 v[54:55], v[52:53], v[50:51] op_sel:[1,0] op_sel_hi:[0,1] neg_lo:[0,1] neg_hi:[0,1]
	v_pk_add_f32 v[84:85], v[80:81], v[54:55] op_sel_hi:[1,0] neg_lo:[0,1] neg_hi:[0,1]
	v_mov_b32_e32 v80, v81
	v_mov_b32_e32 v81, v53
	v_pk_mov_b32 v[54:55], v[50:51], v[54:55] op_sel:[1,0]
	v_mov_b32_e32 v57, v50
	v_pk_add_f32 v[54:55], v[80:81], v[54:55] neg_lo:[0,1] neg_hi:[0,1]
	v_mov_b32_e32 v84, v82
	v_pk_add_f32 v[50:51], v[56:57], v[54:55] neg_lo:[0,1] neg_hi:[0,1]
	v_mov_b32_e32 v83, v53
	v_pk_add_f32 v[54:55], v[84:85], v[50:51]
	s_nop 0
	v_pk_add_f32 v[56:57], v[54:55], v[54:55] op_sel:[0,1] op_sel_hi:[1,0]
	s_nop 0
	v_pk_add_f32 v[52:53], v[52:53], v[56:57] op_sel:[1,0] op_sel_hi:[0,1]
	v_mov_b32_e32 v55, v52
	v_pk_add_f32 v[80:81], v[54:55], v[82:83] neg_lo:[0,1] neg_hi:[0,1]
	v_mov_b32_e32 v51, v56
	v_sub_f32_e32 v53, v54, v80
	v_pk_add_f32 v[50:51], v[50:51], v[80:81] neg_lo:[0,1] neg_hi:[0,1]
	v_sub_f32_e32 v53, v82, v53
	v_add_f32_e32 v50, v50, v53
	v_add_f32_e32 v50, v50, v51
	v_add_f32_e32 v50, v52, v50
	v_cndmask_b32_e64 v50, v208, v50, s[0:1]
	v_cmp_lt_f32_e64 s[0:1], |v86|, s66
	s_nop 1
	v_cndmask_b32_e64 v50, v50, v86, s[0:1]
	v_sub_f32_e32 v0, v0, v50
	v_lshl_add_u64 v[50:51], v[78:79], 0, v[76:77]
	v_lshlrev_b64 v[50:51], 14, v[50:51]
	v_lshl_add_u64 v[50:51], v[60:61], 0, v[50:51]
	global_store_dword v[50:51], v0, off

;     __device__ __forceinline__ void operator()(const f32x4 (&acc)[2][2][4][2], const pg8::Unit& u, int wr, int wc, int fr, int fq) const {
;     ...
;         if (kind == 1 && pn == 28) {
;             if (wc == 0) {
; #pragma unroll
;                 for (int ai = 0; ai < 2; ++ai)
; #pragma unroll
;                     for (int m = 0; m < 4; ++m) { const int row = row0 + ai * 128 + m * 16;
; #pragma unroll
;                         for (int n = 0; n < 2; ++n)
; #pragma unroll
;                             for (int j = 0; j < 4; ++j) { const int col = 8 * fq + 4 * n + j;
;                                 if (col < 12) { const float xv = acc[ai][0][m][n][j] * rsqrtf(ssq[row] * (1.f / DM) + EPS) + bfp[col]; LS[((size_t)(row >> 12) * 12 + col) * SEQ + (row & (SEQ - 1))] = fminf(xv, 0.f) - log1pf(expf(-fabsf(xv))); } } }
.LBB0_544:
	global_load_dword v0, v[66:67], off offset:128
	s_waitcnt vmcnt(0) lgkmcnt(0)
	v_fmamk_f32 v0, v0, 0x3a000000, v205
	v_cmp_gt_f32_e64 s[0:1], s68, v0
	v_mul_f32_e32 v42, 0x4b800000, v0
	s_nop 0
	v_cndmask_b32_e64 v0, v0, v42, s[0:1]
	v_rsq_f32_e32 v0, v0
	s_nop 0
	v_mul_f32_e32 v42, 0x45800000, v0
	v_cndmask_b32_e64 v0, v0, v42, s[0:1]
	v_lshl_add_u64 v[42:43], v[76:77], 2, s[60:61]
	global_load_dword v42, v[42:43], off
	s_waitcnt vmcnt(0) lgkmcnt(0)
	v_fmac_f32_e32 v42, v45, v0
	v_mul_f32_e64 v43, |v42|, s88
	v_fma_f32 v44, |v42|, s88, -v43
	v_rndne_f32_e32 v45, v43
	v_fma_f32 v44, |v42|, s89, v44
	v_sub_f32_e32 v43, v43, v45
	v_add_f32_e32 v43, v43, v44
	v_exp_f32_e32 v43, v43
	v_cvt_i32_f32_e32 v44, v45
	v_cmp_ngt_f32_e64 s[0:1], |v42|, s70
	v_min_f32_e32 v0, 0, v42
	v_ldexp_f32 v43, v43, v44
	v_cndmask_b32_e64 v43, 0, v43, s[0:1]
	v_cmp_nlt_f32_e64 s[0:1], |v42|, s90
	s_nop 1
	v_cndmask_b32_e64 v78, v208, v43, s[0:1]
	v_add_f32_e32 v44, 1.0, v78
	v_add_f32_e32 v42, -1.0, v44
	v_sub_f32_e32 v43, v42, v44
	v_add_f32_e32 v43, 1.0, v43
	v_sub_f32_e32 v42, v78, v42
	v_add_f32_e32 v45, v42, v43
	v_frexp_mant_f32_e32 v42, v44
	v_cmp_gt_f32_e64 s[0:1], s3, v42
	v_cvt_f64_f32_e32 v[42:43], v44
	v_frexp_exp_i32_f64_e32 v42, v[42:43]
	v_subbrev_co_u32_e64 v54, s[0:1], 0, v42, s[0:1]
	v_sub_u32_e32 v42, 0, v54
	v_ldexp_f32 v43, v44, v42
	v_add_f32_e32 v44, -1.0, v43
	v_add_f32_e32 v46, 1.0, v43
	v_ldexp_f32 v42, v45, v42
	v_add_f32_e32 v45, 1.0, v44
	v_add_f32_e32 v47, -1.0, v46
	v_sub_f32_e32 v45, v43, v45
	v_sub_f32_e32 v43, v43, v47
	v_add_f32_e32 v45, v42, v45
	v_add_f32_e32 v42, v42, v43
	v_add_f32_e32 v55, v46, v42
	v_rcp_f32_e32 v57, v55
	v_sub_f32_e32 v43, v46, v55
	v_add_f32_e32 v56, v42, v43
	v_add_f32_e32 v43, v44, v45
	v_mul_f32_e32 v61, v43, v57
	v_sub_f32_e32 v42, v44, v43
	v_mul_f32_e32 v44, v55, v61
	v_fma_f32 v46, v61, v55, -v44
	v_fmac_f32_e32 v46, v61, v56
	v_add_f32_e32 v60, v45, v42
	v_add_f32_e32 v42, v44, v46
	v_sub_f32_e32 v45, v43, v42
	v_pk_add_f32 v[48:49], v[42:43], v[44:45] neg_lo:[0,1] neg_hi:[0,1]
	v_mov_b32_e32 v47, v42
	v_pk_add_f32 v[42:43], v[48:49], v[46:47] neg_lo:[0,1] neg_hi:[0,1]
	v_cmp_neq_f32_e64 s[0:1], s2, v78
	v_add_f32_e32 v43, v60, v43
	v_add_f32_e32 v42, v42, v43
	v_add_f32_e32 v43, v45, v42
	v_mul_f32_e32 v60, v57, v43
	v_mul_f32_e32 v44, v55, v60
	v_fma_f32 v46, v60, v55, -v44
	v_fmac_f32_e32 v46, v60, v56
	v_sub_f32_e32 v45, v45, v43
	v_add_f32_e32 v55, v42, v45
	v_add_f32_e32 v42, v44, v46
	v_sub_f32_e32 v45, v43, v42
	v_pk_add_f32 v[48:49], v[42:43], v[44:45] neg_lo:[0,1] neg_hi:[0,1]
	v_mov_b32_e32 v47, v42
	v_pk_add_f32 v[42:43], v[48:49], v[46:47] neg_lo:[0,1] neg_hi:[0,1]
	s_nop 0
	v_add_f32_e32 v43, v55, v43
	v_add_f32_e32 v42, v42, v43
	v_add_f32_e32 v43, v61, v60
	v_add_f32_e32 v42, v45, v42
	v_sub_f32_e32 v44, v43, v61
	v_mul_f32_e32 v42, v57, v42
	v_sub_f32_e32 v44, v60, v44
	v_add_f32_e32 v44, v44, v42
	v_add_f32_e32 v46, v43, v44
	v_mul_f32_e32 v47, v46, v46
	v_fmamk_f32 v42, v47, 0x3e9b6dac, v206
	v_fmaak_f32 v179, v47, v42, 0x3f2aaada
	v_cvt_f32_i32_e32 v42, v54
	v_sub_f32_e32 v43, v46, v43
	v_sub_f32_e32 v43, v44, v43
	v_ldexp_f32 v48, v43, 1
	v_mul_f32_e32 v43, v46, v47
	v_ldexp_f32 v45, v46, 1
	v_pk_mul_f32 v[46:47], v[42:43], v[178:179]
	s_nop 0
	v_fma_f32 v44, v42, s69, -v46
	v_fmac_f32_e32 v44, 0xb102e308, v42
	v_pk_add_f32 v[42:43], v[46:47], v[44:45]
	s_nop 0
	v_sub_f32_e32 v45, v43, v45
	v_sub_f32_e32 v45, v47, v45
	v_add_f32_e32 v49, v48, v45
	v_mov_b32_e32 v48, v46
	v_pk_add_f32 v[46:47], v[42:43], v[46:47] neg_lo:[0,1] neg_hi:[0,1]
	v_pk_add_f32 v[54:55], v[42:43], v[48:49]
	v_mov_b32_e32 v45, v42
	v_mov_b32_e32 v47, v55
	v_pk_add_f32 v[56:57], v[44:45], v[46:47] neg_lo:[0,1] neg_hi:[0,1]
	v_pk_add_f32 v[44:45], v[44:45], v[46:47]
	v_mov_b32_e32 v48, v49
	v_pk_add_f32 v[46:47], v[44:45], v[42:43] op_sel:[1,0] op_sel_hi:[0,1] neg_lo:[0,1] neg_hi:[0,1]
	v_pk_add_f32 v[60:61], v[54:55], v[46:47] op_sel_hi:[1,0] neg_lo:[0,1] neg_hi:[0,1]
	v_mov_b32_e32 v54, v55
	v_mov_b32_e32 v55, v45
	v_pk_mov_b32 v[46:47], v[42:43], v[46:47] op_sel:[1,0]
	v_mov_b32_e32 v49, v42
	v_pk_add_f32 v[46:47], v[54:55], v[46:47] neg_lo:[0,1] neg_hi:[0,1]
	v_mov_b32_e32 v60, v56
	v_pk_add_f32 v[42:43], v[48:49], v[46:47] neg_lo:[0,1] neg_hi:[0,1]
	v_mov_b32_e32 v57, v45
	v_pk_add_f32 v[46:47], v[60:61], v[42:43]
	s_nop 0
	v_pk_add_f32 v[48:49], v[46:47], v[46:47] op_sel:[0,1] op_sel_hi:[1,0]
	s_nop 0
	v_pk_add_f32 v[44:45], v[44:45], v[48:49] op_sel:[1,0] op_sel_hi:[0,1]
	v_mov_b32_e32 v47, v44
	v_pk_add_f32 v[54:55], v[46:47], v[56:57] neg_lo:[0,1] neg_hi:[0,1]
	v_mov_b32_e32 v43, v48
	v_sub_f32_e32 v45, v46, v54
	v_pk_add_f32 v[42:43], v[42:43], v[54:55] neg_lo:[0,1] neg_hi:[0,1]
	v_sub_f32_e32 v45, v56, v45
	v_add_f32_e32 v42, v42, v45
	v_add_f32_e32 v42, v42, v43
	v_add_f32_e32 v42, v44, v42
	v_cndmask_b32_e64 v42, v208, v42, s[0:1]
	v_cmp_lt_f32_e64 s[0:1], |v78|, s66
	s_nop 1
	v_cndmask_b32_e64 v42, v42, v78, s[0:1]
	v_sub_f32_e32 v0, v0, v42
	v_lshl_add_u64 v[42:43], v[52:53], 0, v[76:77]
	v_lshlrev_b64 v[42:43], 14, v[42:43]
	v_lshl_add_u64 v[42:43], v[50:51], 0, v[42:43]
	global_store_dword v[42:43], v0, off

;     __device__ __forceinline__ void operator()(const f32x4 (&acc)[2][2][4][2], const pg8::Unit& u, int wr, int wc, int fr, int fq) const {
;     ...
;         if (kind == 1 && pn == 28) {
;             if (wc == 0) {
; #pragma unroll
;                 for (int ai = 0; ai < 2; ++ai)
; #pragma unroll
;                     for (int m = 0; m < 4; ++m) { const int row = row0 + ai * 128 + m * 16;
; #pragma unroll
;                         for (int n = 0; n < 2; ++n)
; #pragma unroll
;                             for (int j = 0; j < 4; ++j) { const int col = 8 * fq + 4 * n + j;
;                                 if (col < 12) { const float xv = acc[ai][0][m][n][j] * rsqrtf(ssq[row] * (1.f / DM) + EPS) + bfp[col]; LS[((size_t)(row >> 12) * 12 + col) * SEQ + (row & (SEQ - 1))] = fminf(xv, 0.f) - log1pf(expf(-fabsf(xv))); } } }
.LBB0_553:
	global_load_dword v0, v[66:67], off offset:192
	s_waitcnt vmcnt(0) lgkmcnt(0)
	v_fmamk_f32 v0, v0, 0x3a000000, v205
	v_cmp_gt_f32_e64 s[0:1], s68, v0
	v_mul_f32_e32 v34, 0x4b800000, v0
	s_nop 0
	v_cndmask_b32_e64 v0, v0, v34, s[0:1]
	v_rsq_f32_e32 v0, v0
	s_nop 0
	v_mul_f32_e32 v34, 0x45800000, v0
	v_cndmask_b32_e64 v0, v0, v34, s[0:1]
	v_lshl_add_u64 v[34:35], v[76:77], 2, s[60:61]
	global_load_dword v34, v[34:35], off
	s_waitcnt vmcnt(0) lgkmcnt(0)
	v_fmac_f32_e32 v34, v37, v0
	v_mul_f32_e64 v35, |v34|, s88
	v_fma_f32 v36, |v34|, s88, -v35
	v_rndne_f32_e32 v37, v35
	v_fma_f32 v36, |v34|, s89, v36
	v_sub_f32_e32 v35, v35, v37
	v_add_f32_e32 v35, v35, v36
	v_exp_f32_e32 v35, v35
	v_cvt_i32_f32_e32 v36, v37
	v_cmp_ngt_f32_e64 s[0:1], |v34|, s70
	v_min_f32_e32 v0, 0, v34
	v_ldexp_f32 v35, v35, v36
	v_cndmask_b32_e64 v35, 0, v35, s[0:1]
	v_cmp_nlt_f32_e64 s[0:1], |v34|, s90
	s_nop 1
	v_cndmask_b32_e64 v52, v208, v35, s[0:1]
	v_add_f32_e32 v36, 1.0, v52
	v_add_f32_e32 v34, -1.0, v36
	v_sub_f32_e32 v35, v34, v36
	v_add_f32_e32 v35, 1.0, v35
	v_sub_f32_e32 v34, v52, v34
	v_add_f32_e32 v37, v34, v35
	v_frexp_mant_f32_e32 v34, v36
	v_cmp_gt_f32_e64 s[0:1], s3, v34
	v_cvt_f64_f32_e32 v[34:35], v36
	v_frexp_exp_i32_f64_e32 v34, v[34:35]
	v_subbrev_co_u32_e64 v46, s[0:1], 0, v34, s[0:1]
	v_sub_u32_e32 v34, 0, v46
	v_ldexp_f32 v35, v36, v34
	v_add_f32_e32 v36, -1.0, v35
	v_add_f32_e32 v38, 1.0, v35
	v_ldexp_f32 v34, v37, v34
	v_add_f32_e32 v37, 1.0, v36
	v_add_f32_e32 v39, -1.0, v38
	v_sub_f32_e32 v37, v35, v37
	v_sub_f32_e32 v35, v35, v39
	v_add_f32_e32 v37, v34, v37
	v_add_f32_e32 v34, v34, v35
	v_add_f32_e32 v47, v38, v34
	v_rcp_f32_e32 v49, v47
	v_sub_f32_e32 v35, v38, v47
	v_add_f32_e32 v48, v34, v35
	v_add_f32_e32 v35, v36, v37
	v_mul_f32_e32 v51, v35, v49
	v_sub_f32_e32 v34, v36, v35
	v_mul_f32_e32 v36, v47, v51
	v_fma_f32 v38, v51, v47, -v36
	v_fmac_f32_e32 v38, v51, v48
	v_add_f32_e32 v50, v37, v34
	v_add_f32_e32 v34, v36, v38
	v_sub_f32_e32 v37, v35, v34
	v_pk_add_f32 v[40:41], v[34:35], v[36:37] neg_lo:[0,1] neg_hi:[0,1]
	v_mov_b32_e32 v39, v34
	v_pk_add_f32 v[34:35], v[40:41], v[38:39] neg_lo:[0,1] neg_hi:[0,1]
	v_cmp_neq_f32_e64 s[0:1], s2, v52
	v_add_f32_e32 v35, v50, v35
	v_add_f32_e32 v34, v34, v35
	v_add_f32_e32 v35, v37, v34
	v_mul_f32_e32 v50, v49, v35
	v_mul_f32_e32 v36, v47, v50
	v_fma_f32 v38, v50, v47, -v36
	v_fmac_f32_e32 v38, v50, v48
	v_sub_f32_e32 v37, v37, v35
	v_add_f32_e32 v47, v34, v37
	v_add_f32_e32 v34, v36, v38
	v_sub_f32_e32 v37, v35, v34
	v_pk_add_f32 v[40:41], v[34:35], v[36:37] neg_lo:[0,1] neg_hi:[0,1]
	v_mov_b32_e32 v39, v34
	v_pk_add_f32 v[34:35], v[40:41], v[38:39] neg_lo:[0,1] neg_hi:[0,1]
	s_nop 0
	v_add_f32_e32 v35, v47, v35
	v_add_f32_e32 v34, v34, v35
	v_add_f32_e32 v35, v51, v50
	v_add_f32_e32 v34, v37, v34
	v_sub_f32_e32 v36, v35, v51
	v_mul_f32_e32 v34, v49, v34
	v_sub_f32_e32 v36, v50, v36
	v_add_f32_e32 v36, v36, v34
	v_add_f32_e32 v38, v35, v36
	v_mul_f32_e32 v39, v38, v38
	v_fmamk_f32 v34, v39, 0x3e9b6dac, v206
	v_fmaak_f32 v179, v39, v34, 0x3f2aaada
	v_cvt_f32_i32_e32 v34, v46
	v_sub_f32_e32 v35, v38, v35
	v_sub_f32_e32 v35, v36, v35
	v_ldexp_f32 v40, v35, 1
	v_mul_f32_e32 v35, v38, v39
	v_ldexp_f32 v37, v38, 1
	v_pk_mul_f32 v[38:39], v[34:35], v[178:179]
	s_nop 0
	v_fma_f32 v36, v34, s69, -v38
	v_fmac_f32_e32 v36, 0xb102e308, v34
	v_pk_add_f32 v[34:35], v[38:39], v[36:37]
	s_nop 0
	v_sub_f32_e32 v37, v35, v37
	v_sub_f32_e32 v37, v39, v37
	v_add_f32_e32 v41, v40, v37
	v_mov_b32_e32 v40, v38
	v_pk_add_f32 v[38:39], v[34:35], v[38:39] neg_lo:[0,1] neg_hi:[0,1]
	v_pk_add_f32 v[46:47], v[34:35], v[40:41]
	v_mov_b32_e32 v37, v34
	v_mov_b32_e32 v39, v47
	v_pk_add_f32 v[48:49], v[36:37], v[38:39] neg_lo:[0,1] neg_hi:[0,1]
	v_pk_add_f32 v[36:37], v[36:37], v[38:39]
	v_mov_b32_e32 v40, v41
	v_pk_add_f32 v[38:39], v[36:37], v[34:35] op_sel:[1,0] op_sel_hi:[0,1] neg_lo:[0,1] neg_hi:[0,1]
	v_pk_add_f32 v[50:51], v[46:47], v[38:39] op_sel_hi:[1,0] neg_lo:[0,1] neg_hi:[0,1]
	v_mov_b32_e32 v46, v47
	v_mov_b32_e32 v47, v37
	v_pk_mov_b32 v[38:39], v[34:35], v[38:39] op_sel:[1,0]
	v_mov_b32_e32 v41, v34
	v_pk_add_f32 v[38:39], v[46:47], v[38:39] neg_lo:[0,1] neg_hi:[0,1]
	v_mov_b32_e32 v50, v48
	v_pk_add_f32 v[34:35], v[40:41], v[38:39] neg_lo:[0,1] neg_hi:[0,1]
	v_mov_b32_e32 v49, v37
	v_pk_add_f32 v[38:39], v[50:51], v[34:35]
	s_nop 0
	v_pk_add_f32 v[40:41], v[38:39], v[38:39] op_sel:[0,1] op_sel_hi:[1,0]
	s_nop 0
	v_pk_add_f32 v[36:37], v[36:37], v[40:41] op_sel:[1,0] op_sel_hi:[0,1]
	v_mov_b32_e32 v39, v36
	v_pk_add_f32 v[46:47], v[38:39], v[48:49] neg_lo:[0,1] neg_hi:[0,1]
	v_mov_b32_e32 v35, v40
	v_sub_f32_e32 v37, v38, v46
	v_pk_add_f32 v[34:35], v[34:35], v[46:47] neg_lo:[0,1] neg_hi:[0,1]
	v_sub_f32_e32 v37, v48, v37
	v_add_f32_e32 v34, v34, v37
	v_add_f32_e32 v34, v34, v35
	v_add_f32_e32 v34, v36, v34
	v_cndmask_b32_e64 v34, v208, v34, s[0:1]
	v_cmp_lt_f32_e64 s[0:1], |v52|, s66
	s_nop 1
	v_cndmask_b32_e64 v34, v34, v52, s[0:1]
	v_sub_f32_e32 v0, v0, v34
	v_lshl_add_u64 v[34:35], v[44:45], 0, v[76:77]
	v_lshlrev_b64 v[34:35], 14, v[34:35]
	v_lshl_add_u64 v[34:35], v[42:43], 0, v[34:35]
	global_store_dword v[34:35], v0, off

;     __device__ __forceinline__ void operator()(const f32x4 (&acc)[2][2][4][2], const pg8::Unit& u, int wr, int wc, int fr, int fq) const {
;     ...
;         if (kind == 1 && pn == 28) {
;             if (wc == 0) {
; #pragma unroll
;                 for (int ai = 0; ai < 2; ++ai)
; #pragma unroll
;                     for (int m = 0; m < 4; ++m) { const int row = row0 + ai * 128 + m * 16;
; #pragma unroll
;                         for (int n = 0; n < 2; ++n)
; #pragma unroll
;                             for (int j = 0; j < 4; ++j) { const int col = 8 * fq + 4 * n + j;
;                                 if (col < 12) { const float xv = acc[ai][0][m][n][j] * rsqrtf(ssq[row] * (1.f / DM) + EPS) + bfp[col]; LS[((size_t)(row >> 12) * 12 + col) * SEQ + (row & (SEQ - 1))] = fminf(xv, 0.f) - log1pf(expf(-fabsf(xv))); } } }
.LBB0_562:
	global_load_dword v0, v[66:67], off offset:512
	s_waitcnt vmcnt(0) lgkmcnt(0)
	v_fmamk_f32 v0, v0, 0x3a000000, v205
	v_cmp_gt_f32_e64 s[0:1], s68, v0
	v_mul_f32_e32 v26, 0x4b800000, v0
	s_nop 0
	v_cndmask_b32_e64 v0, v0, v26, s[0:1]
	v_rsq_f32_e32 v0, v0
	s_nop 0
	v_mul_f32_e32 v26, 0x45800000, v0
	v_cndmask_b32_e64 v0, v0, v26, s[0:1]
	v_lshl_add_u64 v[26:27], v[76:77], 2, s[60:61]
	global_load_dword v26, v[26:27], off
	s_waitcnt vmcnt(0) lgkmcnt(0)
	v_fmac_f32_e32 v26, v29, v0
	v_mul_f32_e64 v27, |v26|, s88
	v_fma_f32 v28, |v26|, s88, -v27
	v_rndne_f32_e32 v29, v27
	v_fma_f32 v28, |v26|, s89, v28
	v_sub_f32_e32 v27, v27, v29
	v_add_f32_e32 v27, v27, v28
	v_exp_f32_e32 v27, v27
	v_cvt_i32_f32_e32 v28, v29
	v_cmp_ngt_f32_e64 s[0:1], |v26|, s70
	v_min_f32_e32 v0, 0, v26
	v_ldexp_f32 v27, v27, v28
	v_cndmask_b32_e64 v27, 0, v27, s[0:1]
	v_cmp_nlt_f32_e64 s[0:1], |v26|, s90
	s_nop 1
	v_cndmask_b32_e64 v44, v208, v27, s[0:1]
	v_add_f32_e32 v28, 1.0, v44
	v_add_f32_e32 v26, -1.0, v28
	v_sub_f32_e32 v27, v26, v28
	v_add_f32_e32 v27, 1.0, v27
	v_sub_f32_e32 v26, v44, v26
	v_add_f32_e32 v29, v26, v27
	v_frexp_mant_f32_e32 v26, v28
	v_cmp_gt_f32_e64 s[0:1], s3, v26
	v_cvt_f64_f32_e32 v[26:27], v28
	v_frexp_exp_i32_f64_e32 v26, v[26:27]
	v_subbrev_co_u32_e64 v38, s[0:1], 0, v26, s[0:1]
	v_sub_u32_e32 v26, 0, v38
	v_ldexp_f32 v27, v28, v26
	v_add_f32_e32 v28, -1.0, v27
	v_add_f32_e32 v30, 1.0, v27
	v_ldexp_f32 v26, v29, v26
	v_add_f32_e32 v29, 1.0, v28
	v_add_f32_e32 v31, -1.0, v30
	v_sub_f32_e32 v29, v27, v29
	v_sub_f32_e32 v27, v27, v31
	v_add_f32_e32 v29, v26, v29
	v_add_f32_e32 v26, v26, v27
	v_add_f32_e32 v39, v30, v26
	v_rcp_f32_e32 v41, v39
	v_sub_f32_e32 v27, v30, v39
	v_add_f32_e32 v40, v26, v27
	v_add_f32_e32 v27, v28, v29
	v_mul_f32_e32 v43, v27, v41
	v_sub_f32_e32 v26, v28, v27
	v_mul_f32_e32 v28, v39, v43
	v_fma_f32 v30, v43, v39, -v28
	v_fmac_f32_e32 v30, v43, v40
	v_add_f32_e32 v42, v29, v26
	v_add_f32_e32 v26, v28, v30
	v_sub_f32_e32 v29, v27, v26
	v_pk_add_f32 v[32:33], v[26:27], v[28:29] neg_lo:[0,1] neg_hi:[0,1]
	v_mov_b32_e32 v31, v26
	v_pk_add_f32 v[26:27], v[32:33], v[30:31] neg_lo:[0,1] neg_hi:[0,1]
	v_cmp_neq_f32_e64 s[0:1], s2, v44
	v_add_f32_e32 v27, v42, v27
	v_add_f32_e32 v26, v26, v27
	v_add_f32_e32 v27, v29, v26
	v_mul_f32_e32 v42, v41, v27
	v_mul_f32_e32 v28, v39, v42
	v_fma_f32 v30, v42, v39, -v28
	v_fmac_f32_e32 v30, v42, v40
	v_sub_f32_e32 v29, v29, v27
	v_add_f32_e32 v39, v26, v29
	v_add_f32_e32 v26, v28, v30
	v_sub_f32_e32 v29, v27, v26
	v_pk_add_f32 v[32:33], v[26:27], v[28:29] neg_lo:[0,1] neg_hi:[0,1]
	v_mov_b32_e32 v31, v26
	v_pk_add_f32 v[26:27], v[32:33], v[30:31] neg_lo:[0,1] neg_hi:[0,1]
	s_nop 0
	v_add_f32_e32 v27, v39, v27
	v_add_f32_e32 v26, v26, v27
	v_add_f32_e32 v27, v43, v42
	v_add_f32_e32 v26, v29, v26
	v_sub_f32_e32 v28, v27, v43
	v_mul_f32_e32 v26, v41, v26
	v_sub_f32_e32 v28, v42, v28
	v_add_f32_e32 v28, v28, v26
	v_add_f32_e32 v30, v27, v28
	v_mul_f32_e32 v31, v30, v30
	v_fmamk_f32 v26, v31, 0x3e9b6dac, v206
	v_fmaak_f32 v179, v31, v26, 0x3f2aaada
	v_cvt_f32_i32_e32 v26, v38
	v_sub_f32_e32 v27, v30, v27
	v_sub_f32_e32 v27, v28, v27
	v_ldexp_f32 v32, v27, 1
	v_mul_f32_e32 v27, v30, v31
	v_ldexp_f32 v29, v30, 1
	v_pk_mul_f32 v[30:31], v[26:27], v[178:179]
	s_nop 0
	v_fma_f32 v28, v26, s69, -v30
	v_fmac_f32_e32 v28, 0xb102e308, v26
	v_pk_add_f32 v[26:27], v[30:31], v[28:29]
	s_nop 0
	v_sub_f32_e32 v29, v27, v29
	v_sub_f32_e32 v29, v31, v29
	v_add_f32_e32 v33, v32, v29
	v_mov_b32_e32 v32, v30
	v_pk_add_f32 v[30:31], v[26:27], v[30:31] neg_lo:[0,1] neg_hi:[0,1]
	v_pk_add_f32 v[38:39], v[26:27], v[32:33]
	v_mov_b32_e32 v29, v26
	v_mov_b32_e32 v31, v39
	v_pk_add_f32 v[40:41], v[28:29], v[30:31] neg_lo:[0,1] neg_hi:[0,1]
	v_pk_add_f32 v[28:29], v[28:29], v[30:31]
	v_mov_b32_e32 v32, v33
	v_pk_add_f32 v[30:31], v[28:29], v[26:27] op_sel:[1,0] op_sel_hi:[0,1] neg_lo:[0,1] neg_hi:[0,1]
	v_pk_add_f32 v[42:43], v[38:39], v[30:31] op_sel_hi:[1,0] neg_lo:[0,1] neg_hi:[0,1]
	v_mov_b32_e32 v38, v39
	v_mov_b32_e32 v39, v29
	v_pk_mov_b32 v[30:31], v[26:27], v[30:31] op_sel:[1,0]
	v_mov_b32_e32 v33, v26
	v_pk_add_f32 v[30:31], v[38:39], v[30:31] neg_lo:[0,1] neg_hi:[0,1]
	v_mov_b32_e32 v42, v40
	v_pk_add_f32 v[26:27], v[32:33], v[30:31] neg_lo:[0,1] neg_hi:[0,1]
	v_mov_b32_e32 v41, v29
	v_pk_add_f32 v[30:31], v[42:43], v[26:27]
	s_nop 0
	v_pk_add_f32 v[32:33], v[30:31], v[30:31] op_sel:[0,1] op_sel_hi:[1,0]
	s_nop 0
	v_pk_add_f32 v[28:29], v[28:29], v[32:33] op_sel:[1,0] op_sel_hi:[0,1]
	v_mov_b32_e32 v31, v28
	v_pk_add_f32 v[38:39], v[30:31], v[40:41] neg_lo:[0,1] neg_hi:[0,1]
	v_mov_b32_e32 v27, v32
	v_sub_f32_e32 v29, v30, v38
	v_pk_add_f32 v[26:27], v[26:27], v[38:39] neg_lo:[0,1] neg_hi:[0,1]
	v_sub_f32_e32 v29, v40, v29
	v_add_f32_e32 v26, v26, v29
	v_add_f32_e32 v26, v26, v27
	v_add_f32_e32 v26, v28, v26
	v_cndmask_b32_e64 v26, v208, v26, s[0:1]
	v_cmp_lt_f32_e64 s[0:1], |v44|, s66
	s_nop 1
	v_cndmask_b32_e64 v26, v26, v44, s[0:1]
	v_sub_f32_e32 v0, v0, v26
	v_lshl_add_u64 v[26:27], v[36:37], 0, v[76:77]
	v_lshlrev_b64 v[26:27], 14, v[26:27]
	v_lshl_add_u64 v[26:27], v[34:35], 0, v[26:27]
	global_store_dword v[26:27], v0, off

;     __device__ __forceinline__ void operator()(const f32x4 (&acc)[2][2][4][2], const pg8::Unit& u, int wr, int wc, int fr, int fq) const {
;     ...
;         if (kind == 1 && pn == 28) {
;             if (wc == 0) {
; #pragma unroll
;                 for (int ai = 0; ai < 2; ++ai)
; #pragma unroll
;                     for (int m = 0; m < 4; ++m) { const int row = row0 + ai * 128 + m * 16;
; #pragma unroll
;                         for (int n = 0; n < 2; ++n)
; #pragma unroll
;                             for (int j = 0; j < 4; ++j) { const int col = 8 * fq + 4 * n + j;
;                                 if (col < 12) { const float xv = acc[ai][0][m][n][j] * rsqrtf(ssq[row] * (1.f / DM) + EPS) + bfp[col]; LS[((size_t)(row >> 12) * 12 + col) * SEQ + (row & (SEQ - 1))] = fminf(xv, 0.f) - log1pf(expf(-fabsf(xv))); } } }
.LBB0_571:
	global_load_dword v0, v[66:67], off offset:576
	s_waitcnt vmcnt(0) lgkmcnt(0)
	v_fmamk_f32 v0, v0, 0x3a000000, v205
	v_cmp_gt_f32_e64 s[0:1], s68, v0
	v_mul_f32_e32 v18, 0x4b800000, v0
	s_nop 0
	v_cndmask_b32_e64 v0, v0, v18, s[0:1]
	v_rsq_f32_e32 v0, v0
	s_nop 0
	v_mul_f32_e32 v18, 0x45800000, v0
	v_cndmask_b32_e64 v0, v0, v18, s[0:1]
	v_lshl_add_u64 v[18:19], v[76:77], 2, s[60:61]
	global_load_dword v18, v[18:19], off
	s_waitcnt vmcnt(0) lgkmcnt(0)
	v_fmac_f32_e32 v18, v21, v0
	v_mul_f32_e64 v19, |v18|, s88
	v_fma_f32 v20, |v18|, s88, -v19
	v_rndne_f32_e32 v21, v19
	v_fma_f32 v20, |v18|, s89, v20
	v_sub_f32_e32 v19, v19, v21
	v_add_f32_e32 v19, v19, v20
	v_exp_f32_e32 v19, v19
	v_cvt_i32_f32_e32 v20, v21
	v_cmp_ngt_f32_e64 s[0:1], |v18|, s70
	v_min_f32_e32 v0, 0, v18
	v_ldexp_f32 v19, v19, v20
	v_cndmask_b32_e64 v19, 0, v19, s[0:1]
	v_cmp_nlt_f32_e64 s[0:1], |v18|, s90
	s_nop 1
	v_cndmask_b32_e64 v36, v208, v19, s[0:1]
	v_add_f32_e32 v20, 1.0, v36
	v_add_f32_e32 v18, -1.0, v20
	v_sub_f32_e32 v19, v18, v20
	v_add_f32_e32 v19, 1.0, v19
	v_sub_f32_e32 v18, v36, v18
	v_add_f32_e32 v21, v18, v19
	v_frexp_mant_f32_e32 v18, v20
	v_cmp_gt_f32_e64 s[0:1], s3, v18
	v_cvt_f64_f32_e32 v[18:19], v20
	v_frexp_exp_i32_f64_e32 v18, v[18:19]
	v_subbrev_co_u32_e64 v30, s[0:1], 0, v18, s[0:1]
	v_sub_u32_e32 v18, 0, v30
	v_ldexp_f32 v19, v20, v18
	v_add_f32_e32 v20, -1.0, v19
	v_add_f32_e32 v22, 1.0, v19
	v_ldexp_f32 v18, v21, v18
	v_add_f32_e32 v21, 1.0, v20
	v_add_f32_e32 v23, -1.0, v22
	v_sub_f32_e32 v21, v19, v21
	v_sub_f32_e32 v19, v19, v23
	v_add_f32_e32 v21, v18, v21
	v_add_f32_e32 v18, v18, v19
	v_add_f32_e32 v31, v22, v18
	v_rcp_f32_e32 v33, v31
	v_sub_f32_e32 v19, v22, v31
	v_add_f32_e32 v32, v18, v19
	v_add_f32_e32 v19, v20, v21
	v_mul_f32_e32 v35, v19, v33
	v_sub_f32_e32 v18, v20, v19
	v_mul_f32_e32 v20, v31, v35
	v_fma_f32 v22, v35, v31, -v20
	v_fmac_f32_e32 v22, v35, v32
	v_add_f32_e32 v34, v21, v18
	v_add_f32_e32 v18, v20, v22
	v_sub_f32_e32 v21, v19, v18
	v_pk_add_f32 v[24:25], v[18:19], v[20:21] neg_lo:[0,1] neg_hi:[0,1]
	v_mov_b32_e32 v23, v18
	v_pk_add_f32 v[18:19], v[24:25], v[22:23] neg_lo:[0,1] neg_hi:[0,1]
	v_cmp_neq_f32_e64 s[0:1], s2, v36
	v_add_f32_e32 v19, v34, v19
	v_add_f32_e32 v18, v18, v19
	v_add_f32_e32 v19, v21, v18
	v_mul_f32_e32 v34, v33, v19
	v_mul_f32_e32 v20, v31, v34
	v_fma_f32 v22, v34, v31, -v20
	v_fmac_f32_e32 v22, v34, v32
	v_sub_f32_e32 v21, v21, v19
	v_add_f32_e32 v31, v18, v21
	v_add_f32_e32 v18, v20, v22
	v_sub_f32_e32 v21, v19, v18
	v_pk_add_f32 v[24:25], v[18:19], v[20:21] neg_lo:[0,1] neg_hi:[0,1]
	v_mov_b32_e32 v23, v18
	v_pk_add_f32 v[18:19], v[24:25], v[22:23] neg_lo:[0,1] neg_hi:[0,1]
	s_nop 0
	v_add_f32_e32 v19, v31, v19
	v_add_f32_e32 v18, v18, v19
	v_add_f32_e32 v19, v35, v34
	v_add_f32_e32 v18, v21, v18
	v_sub_f32_e32 v20, v19, v35
	v_mul_f32_e32 v18, v33, v18
	v_sub_f32_e32 v20, v34, v20
	v_add_f32_e32 v20, v20, v18
	v_add_f32_e32 v22, v19, v20
	v_mul_f32_e32 v23, v22, v22
	v_fmamk_f32 v18, v23, 0x3e9b6dac, v206
	v_fmaak_f32 v179, v23, v18, 0x3f2aaada
	v_cvt_f32_i32_e32 v18, v30
	v_sub_f32_e32 v19, v22, v19
	v_sub_f32_e32 v19, v20, v19
	v_ldexp_f32 v24, v19, 1
	v_mul_f32_e32 v19, v22, v23
	v_ldexp_f32 v21, v22, 1
	v_pk_mul_f32 v[22:23], v[18:19], v[178:179]
	s_nop 0
	v_fma_f32 v20, v18, s69, -v22
	v_fmac_f32_e32 v20, 0xb102e308, v18
	v_pk_add_f32 v[18:19], v[22:23], v[20:21]
	s_nop 0
	v_sub_f32_e32 v21, v19, v21
	v_sub_f32_e32 v21, v23, v21
	v_add_f32_e32 v25, v24, v21
	v_mov_b32_e32 v24, v22
	v_pk_add_f32 v[22:23], v[18:19], v[22:23] neg_lo:[0,1] neg_hi:[0,1]
	v_pk_add_f32 v[30:31], v[18:19], v[24:25]
	v_mov_b32_e32 v21, v18
	v_mov_b32_e32 v23, v31
	v_pk_add_f32 v[32:33], v[20:21], v[22:23] neg_lo:[0,1] neg_hi:[0,1]
	v_pk_add_f32 v[20:21], v[20:21], v[22:23]
	v_mov_b32_e32 v24, v25
	v_pk_add_f32 v[22:23], v[20:21], v[18:19] op_sel:[1,0] op_sel_hi:[0,1] neg_lo:[0,1] neg_hi:[0,1]
	v_pk_add_f32 v[34:35], v[30:31], v[22:23] op_sel_hi:[1,0] neg_lo:[0,1] neg_hi:[0,1]
	v_mov_b32_e32 v30, v31
	v_mov_b32_e32 v31, v21
	v_pk_mov_b32 v[22:23], v[18:19], v[22:23] op_sel:[1,0]
	v_mov_b32_e32 v25, v18
	v_pk_add_f32 v[22:23], v[30:31], v[22:23] neg_lo:[0,1] neg_hi:[0,1]
	v_mov_b32_e32 v34, v32
	v_pk_add_f32 v[18:19], v[24:25], v[22:23] neg_lo:[0,1] neg_hi:[0,1]
	v_mov_b32_e32 v33, v21
	v_pk_add_f32 v[22:23], v[34:35], v[18:19]
	s_nop 0
	v_pk_add_f32 v[24:25], v[22:23], v[22:23] op_sel:[0,1] op_sel_hi:[1,0]
	s_nop 0
	v_pk_add_f32 v[20:21], v[20:21], v[24:25] op_sel:[1,0] op_sel_hi:[0,1]
	v_mov_b32_e32 v23, v20
	v_pk_add_f32 v[30:31], v[22:23], v[32:33] neg_lo:[0,1] neg_hi:[0,1]
	v_mov_b32_e32 v19, v24
	v_sub_f32_e32 v21, v22, v30
	v_pk_add_f32 v[18:19], v[18:19], v[30:31] neg_lo:[0,1] neg_hi:[0,1]
	v_sub_f32_e32 v21, v32, v21
	v_add_f32_e32 v18, v18, v21
	v_add_f32_e32 v18, v18, v19
	v_add_f32_e32 v18, v20, v18
	v_cndmask_b32_e64 v18, v208, v18, s[0:1]
	v_cmp_lt_f32_e64 s[0:1], |v36|, s66
	s_nop 1
	v_cndmask_b32_e64 v18, v18, v36, s[0:1]
	v_sub_f32_e32 v0, v0, v18
	v_lshl_add_u64 v[18:19], v[28:29], 0, v[76:77]
	v_lshlrev_b64 v[18:19], 14, v[18:19]
	v_lshl_add_u64 v[18:19], v[26:27], 0, v[18:19]
	global_store_dword v[18:19], v0, off

;     __device__ __forceinline__ void operator()(const f32x4 (&acc)[2][2][4][2], const pg8::Unit& u, int wr, int wc, int fr, int fq) const {
;     ...
;         if (kind == 1 && pn == 28) {
;             if (wc == 0) {
; #pragma unroll
;                 for (int ai = 0; ai < 2; ++ai)
; #pragma unroll
;                     for (int m = 0; m < 4; ++m) { const int row = row0 + ai * 128 + m * 16;
; #pragma unroll
;                         for (int n = 0; n < 2; ++n)
; #pragma unroll
;                             for (int j = 0; j < 4; ++j) { const int col = 8 * fq + 4 * n + j;
;                                 if (col < 12) { const float xv = acc[ai][0][m][n][j] * rsqrtf(ssq[row] * (1.f / DM) + EPS) + bfp[col]; LS[((size_t)(row >> 12) * 12 + col) * SEQ + (row & (SEQ - 1))] = fminf(xv, 0.f) - log1pf(expf(-fabsf(xv))); } } }
.LBB0_580:
	global_load_dword v0, v[66:67], off offset:640
	s_waitcnt vmcnt(0) lgkmcnt(0)
	v_fmamk_f32 v0, v0, 0x3a000000, v205
	v_cmp_gt_f32_e64 s[0:1], s68, v0
	v_mul_f32_e32 v10, 0x4b800000, v0
	s_nop 0
	v_cndmask_b32_e64 v0, v0, v10, s[0:1]
	v_rsq_f32_e32 v0, v0
	s_nop 0
	v_mul_f32_e32 v10, 0x45800000, v0
	v_cndmask_b32_e64 v0, v0, v10, s[0:1]
	v_lshl_add_u64 v[10:11], v[76:77], 2, s[60:61]
	global_load_dword v10, v[10:11], off
	s_waitcnt vmcnt(0) lgkmcnt(0)
	v_fmac_f32_e32 v10, v13, v0
	v_mul_f32_e64 v11, |v10|, s88
	v_fma_f32 v12, |v10|, s88, -v11
	v_rndne_f32_e32 v13, v11
	v_fma_f32 v12, |v10|, s89, v12
	v_sub_f32_e32 v11, v11, v13
	v_add_f32_e32 v11, v11, v12
	v_exp_f32_e32 v11, v11
	v_cvt_i32_f32_e32 v12, v13
	v_cmp_ngt_f32_e64 s[0:1], |v10|, s70
	v_min_f32_e32 v0, 0, v10
	v_ldexp_f32 v11, v11, v12
	v_cndmask_b32_e64 v11, 0, v11, s[0:1]
	v_cmp_nlt_f32_e64 s[0:1], |v10|, s90
	s_nop 1
	v_cndmask_b32_e64 v28, v208, v11, s[0:1]
	v_add_f32_e32 v12, 1.0, v28
	v_add_f32_e32 v10, -1.0, v12
	v_sub_f32_e32 v11, v10, v12
	v_add_f32_e32 v11, 1.0, v11
	v_sub_f32_e32 v10, v28, v10
	v_add_f32_e32 v13, v10, v11
	v_frexp_mant_f32_e32 v10, v12
	v_cmp_gt_f32_e64 s[0:1], s3, v10
	v_cvt_f64_f32_e32 v[10:11], v12
	v_frexp_exp_i32_f64_e32 v10, v[10:11]
	v_subbrev_co_u32_e64 v22, s[0:1], 0, v10, s[0:1]
	v_sub_u32_e32 v10, 0, v22
	v_ldexp_f32 v11, v12, v10
	v_add_f32_e32 v12, -1.0, v11
	v_add_f32_e32 v14, 1.0, v11
	v_ldexp_f32 v10, v13, v10
	v_add_f32_e32 v13, 1.0, v12
	v_add_f32_e32 v15, -1.0, v14
	v_sub_f32_e32 v13, v11, v13
	v_sub_f32_e32 v11, v11, v15
	v_add_f32_e32 v13, v10, v13
	v_add_f32_e32 v10, v10, v11
	v_add_f32_e32 v23, v14, v10
	v_rcp_f32_e32 v25, v23
	v_sub_f32_e32 v11, v14, v23
	v_add_f32_e32 v24, v10, v11
	v_add_f32_e32 v11, v12, v13
	v_mul_f32_e32 v27, v11, v25
	v_sub_f32_e32 v10, v12, v11
	v_mul_f32_e32 v12, v23, v27
	v_fma_f32 v14, v27, v23, -v12
	v_fmac_f32_e32 v14, v27, v24
	v_add_f32_e32 v26, v13, v10
	v_add_f32_e32 v10, v12, v14
	v_sub_f32_e32 v13, v11, v10
	v_pk_add_f32 v[16:17], v[10:11], v[12:13] neg_lo:[0,1] neg_hi:[0,1]
	v_mov_b32_e32 v15, v10
	v_pk_add_f32 v[10:11], v[16:17], v[14:15] neg_lo:[0,1] neg_hi:[0,1]
	v_cmp_neq_f32_e64 s[0:1], s2, v28
	v_add_f32_e32 v11, v26, v11
	v_add_f32_e32 v10, v10, v11
	v_add_f32_e32 v11, v13, v10
	v_mul_f32_e32 v26, v25, v11
	v_mul_f32_e32 v12, v23, v26
	v_fma_f32 v14, v26, v23, -v12
	v_fmac_f32_e32 v14, v26, v24
	v_sub_f32_e32 v13, v13, v11
	v_add_f32_e32 v23, v10, v13
	v_add_f32_e32 v10, v12, v14
	v_sub_f32_e32 v13, v11, v10
	v_pk_add_f32 v[16:17], v[10:11], v[12:13] neg_lo:[0,1] neg_hi:[0,1]
	v_mov_b32_e32 v15, v10
	v_pk_add_f32 v[10:11], v[16:17], v[14:15] neg_lo:[0,1] neg_hi:[0,1]
	s_nop 0
	v_add_f32_e32 v11, v23, v11
	v_add_f32_e32 v10, v10, v11
	v_add_f32_e32 v11, v27, v26
	v_add_f32_e32 v10, v13, v10
	v_sub_f32_e32 v12, v11, v27
	v_mul_f32_e32 v10, v25, v10
	v_sub_f32_e32 v12, v26, v12
	v_add_f32_e32 v12, v12, v10
	v_add_f32_e32 v14, v11, v12
	v_mul_f32_e32 v15, v14, v14
	v_fmamk_f32 v10, v15, 0x3e9b6dac, v206
	v_fmaak_f32 v179, v15, v10, 0x3f2aaada
	v_cvt_f32_i32_e32 v10, v22
	v_sub_f32_e32 v11, v14, v11
	v_sub_f32_e32 v11, v12, v11
	v_ldexp_f32 v16, v11, 1
	v_mul_f32_e32 v11, v14, v15
	v_ldexp_f32 v13, v14, 1
	v_pk_mul_f32 v[14:15], v[10:11], v[178:179]
	s_nop 0
	v_fma_f32 v12, v10, s69, -v14
	v_fmac_f32_e32 v12, 0xb102e308, v10
	v_pk_add_f32 v[10:11], v[14:15], v[12:13]
	s_nop 0
	v_sub_f32_e32 v13, v11, v13
	v_sub_f32_e32 v13, v15, v13
	v_add_f32_e32 v17, v16, v13
	v_mov_b32_e32 v16, v14
	v_pk_add_f32 v[14:15], v[10:11], v[14:15] neg_lo:[0,1] neg_hi:[0,1]
	v_pk_add_f32 v[22:23], v[10:11], v[16:17]
	v_mov_b32_e32 v13, v10
	v_mov_b32_e32 v15, v23
	v_pk_add_f32 v[24:25], v[12:13], v[14:15] neg_lo:[0,1] neg_hi:[0,1]
	v_pk_add_f32 v[12:13], v[12:13], v[14:15]
	v_mov_b32_e32 v16, v17
	v_pk_add_f32 v[14:15], v[12:13], v[10:11] op_sel:[1,0] op_sel_hi:[0,1] neg_lo:[0,1] neg_hi:[0,1]
	v_pk_add_f32 v[26:27], v[22:23], v[14:15] op_sel_hi:[1,0] neg_lo:[0,1] neg_hi:[0,1]
	v_mov_b32_e32 v22, v23
	v_mov_b32_e32 v23, v13
	v_pk_mov_b32 v[14:15], v[10:11], v[14:15] op_sel:[1,0]
	v_mov_b32_e32 v17, v10
	v_pk_add_f32 v[14:15], v[22:23], v[14:15] neg_lo:[0,1] neg_hi:[0,1]
	v_mov_b32_e32 v26, v24
	v_pk_add_f32 v[10:11], v[16:17], v[14:15] neg_lo:[0,1] neg_hi:[0,1]
	v_mov_b32_e32 v25, v13
	v_pk_add_f32 v[14:15], v[26:27], v[10:11]
	s_nop 0
	v_pk_add_f32 v[16:17], v[14:15], v[14:15] op_sel:[0,1] op_sel_hi:[1,0]
	s_nop 0
	v_pk_add_f32 v[12:13], v[12:13], v[16:17] op_sel:[1,0] op_sel_hi:[0,1]
	v_mov_b32_e32 v15, v12
	v_pk_add_f32 v[22:23], v[14:15], v[24:25] neg_lo:[0,1] neg_hi:[0,1]
	v_mov_b32_e32 v11, v16
	v_sub_f32_e32 v13, v14, v22
	v_pk_add_f32 v[10:11], v[10:11], v[22:23] neg_lo:[0,1] neg_hi:[0,1]
	v_sub_f32_e32 v13, v24, v13
	v_add_f32_e32 v10, v10, v13
	v_add_f32_e32 v10, v10, v11
	v_add_f32_e32 v10, v12, v10
	v_cndmask_b32_e64 v10, v208, v10, s[0:1]
	v_cmp_lt_f32_e64 s[0:1], |v28|, s66
	s_nop 1
	v_cndmask_b32_e64 v10, v10, v28, s[0:1]
	v_sub_f32_e32 v0, v0, v10
	v_lshl_add_u64 v[10:11], v[20:21], 0, v[76:77]
	v_lshlrev_b64 v[10:11], 14, v[10:11]
	v_lshl_add_u64 v[10:11], v[18:19], 0, v[10:11]
	global_store_dword v[10:11], v0, off

;     __device__ __forceinline__ void operator()(const f32x4 (&acc)[2][2][4][2], const pg8::Unit& u, int wr, int wc, int fr, int fq) const {
;     ...
;         if (kind == 1 && pn == 28) {
;             if (wc == 0) {
; #pragma unroll
;                 for (int ai = 0; ai < 2; ++ai)
; #pragma unroll
;                     for (int m = 0; m < 4; ++m) { const int row = row0 + ai * 128 + m * 16;
; #pragma unroll
;                         for (int n = 0; n < 2; ++n)
; #pragma unroll
;                             for (int j = 0; j < 4; ++j) { const int col = 8 * fq + 4 * n + j;
;                                 if (col < 12) { const float xv = acc[ai][0][m][n][j] * rsqrtf(ssq[row] * (1.f / DM) + EPS) + bfp[col]; LS[((size_t)(row >> 12) * 12 + col) * SEQ + (row & (SEQ - 1))] = fminf(xv, 0.f) - log1pf(expf(-fabsf(xv))); } } }
.LBB0_589:
	global_load_dword v0, v[66:67], off offset:704
	v_lshl_add_u64 v[2:3], v[76:77], 2, s[60:61]
	global_load_dword v4, v[2:3], off
	s_waitcnt vmcnt(0) lgkmcnt(0)
	v_fmamk_f32 v0, v0, 0x3a000000, v205
	v_mul_f32_e32 v2, 0x4b800000, v0
	v_cmp_gt_f32_e32 vcc, s68, v0
	s_nop 1
	v_cndmask_b32_e32 v0, v0, v2, vcc
	v_rsq_f32_e32 v0, v0
	s_nop 0
	v_mul_f32_e32 v2, 0x45800000, v0
	v_cndmask_b32_e32 v0, v0, v2, vcc
	v_fmac_f32_e32 v4, v5, v0
	v_mul_f32_e64 v0, |v4|, s88
	v_fma_f32 v2, |v4|, s88, -v0
	v_rndne_f32_e32 v3, v0
	v_fma_f32 v2, |v4|, s89, v2
	v_sub_f32_e32 v0, v0, v3
	v_add_f32_e32 v0, v0, v2
	v_cvt_i32_f32_e32 v5, v3
	v_exp_f32_e32 v0, v0
	v_cmp_ngt_f32_e64 vcc, |v4|, s70
	v_min_f32_e32 v20, 0, v4
	v_lshl_add_u64 v[2:3], v[12:13], 0, v[76:77]
	v_ldexp_f32 v0, v0, v5
	v_cndmask_b32_e32 v0, 0, v0, vcc
	v_cmp_nlt_f32_e64 vcc, |v4|, s90
	v_lshlrev_b64 v[2:3], 14, v[2:3]
	v_lshl_add_u64 v[2:3], v[10:11], 0, v[2:3]
	v_cndmask_b32_e32 v0, v208, v0, vcc
	v_add_f32_e32 v6, 1.0, v0
	v_add_f32_e32 v7, -1.0, v6
	v_frexp_mant_f32_e32 v8, v6
	v_cvt_f64_f32_e32 v[4:5], v6
	v_sub_f32_e32 v9, v7, v6
	v_frexp_exp_i32_f64_e32 v4, v[4:5]
	v_cmp_gt_f32_e32 vcc, s3, v8
	v_sub_f32_e32 v7, v0, v7
	v_add_f32_e32 v5, 1.0, v9
	v_subbrev_co_u32_e32 v4, vcc, 0, v4, vcc
	v_add_f32_e32 v5, v7, v5
	v_sub_u32_e32 v7, 0, v4
	v_ldexp_f32 v6, v6, v7
	v_add_f32_e32 v8, -1.0, v6
	v_add_f32_e32 v9, 1.0, v6
	v_ldexp_f32 v5, v5, v7
	v_add_f32_e32 v7, 1.0, v8
	v_add_f32_e32 v12, -1.0, v9
	v_sub_f32_e32 v7, v6, v7
	v_sub_f32_e32 v6, v6, v12
	v_add_f32_e32 v12, v5, v7
	v_add_f32_e32 v5, v5, v6
	v_add_f32_e32 v14, v9, v5
	v_rcp_f32_e32 v15, v14
	v_add_f32_e32 v7, v8, v12
	v_sub_f32_e32 v8, v8, v7
	v_sub_f32_e32 v6, v9, v14
	v_mul_f32_e32 v17, v7, v15
	v_add_f32_e32 v16, v12, v8
	v_mul_f32_e32 v8, v14, v17
	v_add_f32_e32 v5, v5, v6
	v_fma_f32 v12, v17, v14, -v8
	v_fmac_f32_e32 v12, v17, v5
	v_add_f32_e32 v6, v8, v12
	v_sub_f32_e32 v9, v7, v6
	v_mov_b32_e32 v13, v6
	v_pk_add_f32 v[6:7], v[6:7], v[8:9] neg_lo:[0,1] neg_hi:[0,1]
	v_cvt_f32_i32_e32 v4, v4
	v_pk_add_f32 v[6:7], v[6:7], v[12:13] neg_lo:[0,1] neg_hi:[0,1]
	v_cmp_neq_f32_e32 vcc, s2, v0
	v_add_f32_e32 v7, v16, v7
	v_add_f32_e32 v6, v6, v7
	v_add_f32_e32 v7, v9, v6
	v_mul_f32_e32 v13, v15, v7
	v_mul_f32_e32 v8, v14, v13
	v_sub_f32_e32 v9, v9, v7
	v_add_f32_e32 v18, v17, v13
	v_fma_f32 v12, v13, v14, -v8
	v_add_f32_e32 v16, v6, v9
	v_sub_f32_e32 v6, v18, v17
	v_fmac_f32_e32 v12, v13, v5
	v_sub_f32_e32 v5, v13, v6
	v_add_f32_e32 v6, v8, v12
	v_sub_f32_e32 v9, v7, v6
	v_mov_b32_e32 v13, v6
	v_pk_add_f32 v[6:7], v[6:7], v[8:9] neg_lo:[0,1] neg_hi:[0,1]
	s_nop 0
	v_pk_add_f32 v[6:7], v[6:7], v[12:13] neg_lo:[0,1] neg_hi:[0,1]
	s_nop 0
	v_add_f32_e32 v7, v16, v7
	v_add_f32_e32 v6, v6, v7
	v_add_f32_e32 v6, v9, v6
	v_mul_f32_e32 v6, v15, v6
	v_add_f32_e32 v5, v5, v6
	v_add_f32_e32 v6, v18, v5
	v_mul_f32_e32 v8, v6, v6
	v_sub_f32_e32 v9, v6, v18
	v_fmamk_f32 v12, v8, 0x3e9b6dac, v206
	v_sub_f32_e32 v9, v5, v9
	v_mul_f32_e32 v5, v6, v8
	v_fmaak_f32 v179, v8, v12, 0x3f2aaada
	v_ldexp_f32 v13, v9, 1
	v_pk_mul_f32 v[8:9], v[4:5], v[178:179]
	v_ldexp_f32 v7, v6, 1
	v_fma_f32 v6, v4, s69, -v8
	v_fmac_f32_e32 v6, 0xb102e308, v4
	v_pk_add_f32 v[4:5], v[8:9], v[6:7]
	v_mov_b32_e32 v12, v8
	v_sub_f32_e32 v16, v5, v7
	v_pk_add_f32 v[14:15], v[4:5], v[8:9] neg_lo:[0,1] neg_hi:[0,1]
	v_sub_f32_e32 v8, v9, v16
	v_add_f32_e32 v13, v13, v8
	v_pk_add_f32 v[8:9], v[4:5], v[12:13]
	v_mov_b32_e32 v7, v4
	v_mov_b32_e32 v15, v9
	v_pk_add_f32 v[18:19], v[6:7], v[14:15] neg_lo:[0,1] neg_hi:[0,1]
	v_pk_add_f32 v[6:7], v[6:7], v[14:15]
	v_mov_b32_e32 v17, v4
	v_pk_add_f32 v[14:15], v[6:7], v[4:5] op_sel:[1,0] op_sel_hi:[0,1] neg_lo:[0,1] neg_hi:[0,1]
	v_mov_b32_e32 v16, v13
	v_mov_b32_e32 v12, v9
	v_mov_b32_e32 v13, v7
	v_pk_mov_b32 v[4:5], v[4:5], v[14:15] op_sel:[1,0]
	v_pk_add_f32 v[8:9], v[8:9], v[14:15] op_sel_hi:[1,0] neg_lo:[0,1] neg_hi:[0,1]
	v_pk_add_f32 v[4:5], v[12:13], v[4:5] neg_lo:[0,1] neg_hi:[0,1]
	v_mov_b32_e32 v8, v18
	v_pk_add_f32 v[4:5], v[16:17], v[4:5] neg_lo:[0,1] neg_hi:[0,1]
	v_mov_b32_e32 v19, v7
	v_pk_add_f32 v[8:9], v[8:9], v[4:5]
	s_nop 0
	v_pk_add_f32 v[12:13], v[8:9], v[8:9] op_sel:[0,1] op_sel_hi:[1,0]
	s_nop 0
	v_pk_add_f32 v[6:7], v[6:7], v[12:13] op_sel:[1,0] op_sel_hi:[0,1]
	v_mov_b32_e32 v9, v6
	v_mov_b32_e32 v5, v12
	v_pk_add_f32 v[12:13], v[8:9], v[18:19] neg_lo:[0,1] neg_hi:[0,1]
	s_nop 0
	v_sub_f32_e32 v7, v8, v12
	v_pk_add_f32 v[4:5], v[4:5], v[12:13] neg_lo:[0,1] neg_hi:[0,1]
	v_sub_f32_e32 v7, v18, v7
	v_add_f32_e32 v4, v4, v7
	v_add_f32_e32 v4, v4, v5
	v_add_f32_e32 v4, v6, v4
	v_cndmask_b32_e32 v4, v208, v4, vcc
	v_cmp_lt_f32_e64 vcc, |v0|, s66
	s_nop 1
	v_cndmask_b32_e32 v0, v4, v0, vcc
	v_sub_f32_e32 v0, v20, v0
	global_store_dword v[2:3], v0, off

;     __device__ __forceinline__ void operator()(const f32x4 (&acc)[2][2][4][2], const pg8::Unit& u, int wr, int wc, int fr, int fq) const {
;     ...
;         if (kind == 1 && pn == 28) {
;             if (wc == 0) {
; #pragma unroll
;                 for (int ai = 0; ai < 2; ++ai)
; #pragma unroll
;                     for (int m = 0; m < 4; ++m) { const int row = row0 + ai * 128 + m * 16;
; #pragma unroll
;                         for (int n = 0; n < 2; ++n)
; #pragma unroll
;                             for (int j = 0; j < 4; ++j) { const int col = 8 * fq + 4 * n + j;
;                                 if (col < 12) { const float xv = acc[ai][0][m][n][j] * rsqrtf(ssq[row] * (1.f / DM) + EPS) + bfp[col]; LS[((size_t)(row >> 12) * 12 + col) * SEQ + (row & (SEQ - 1))] = fminf(xv, 0.f) - log1pf(expf(-fabsf(xv))); } } }
.LBB0_591:
	global_load_dword v0, v[66:67], off offset:64
	s_waitcnt vmcnt(0) lgkmcnt(0)
	v_fmamk_f32 v0, v0, 0x3a000000, v205
	v_cmp_gt_f32_e64 s[0:1], s68, v0
	v_mul_f32_e32 v80, 0x4b800000, v0
	s_nop 0
	v_cndmask_b32_e64 v0, v0, v80, s[0:1]
	v_rsq_f32_e32 v0, v0
	s_nop 0
	v_mul_f32_e32 v80, 0x45800000, v0
	v_cndmask_b32_e64 v0, v0, v80, s[0:1]
	v_lshl_add_u64 v[80:81], v[68:69], 2, s[60:61]
	global_load_dword v80, v[80:81], off
	s_waitcnt vmcnt(0) lgkmcnt(0)
	v_fmac_f32_e32 v80, v54, v0
	v_mul_f32_e64 v54, |v80|, s88
	v_fma_f32 v81, |v80|, s88, -v54
	v_rndne_f32_e32 v82, v54
	v_fma_f32 v81, |v80|, s89, v81
	v_sub_f32_e32 v54, v54, v82
	v_add_f32_e32 v54, v54, v81
	v_exp_f32_e32 v54, v54
	v_cvt_i32_f32_e32 v81, v82
	v_cmp_ngt_f32_e64 s[0:1], |v80|, s70
	v_min_f32_e32 v0, 0, v80
	v_ldexp_f32 v54, v54, v81
	v_cndmask_b32_e64 v54, 0, v54, s[0:1]
	v_cmp_nlt_f32_e64 s[0:1], |v80|, s90
	s_nop 1
	v_cndmask_b32_e64 v54, v208, v54, s[0:1]
	v_add_f32_e32 v82, 1.0, v54
	v_add_f32_e32 v80, -1.0, v82
	v_sub_f32_e32 v81, v80, v82
	v_add_f32_e32 v81, 1.0, v81
	v_sub_f32_e32 v80, v54, v80
	v_add_f32_e32 v83, v80, v81
	v_frexp_mant_f32_e32 v80, v82
	v_cmp_gt_f32_e64 s[0:1], s3, v80
	v_cvt_f64_f32_e32 v[80:81], v82
	v_frexp_exp_i32_f64_e32 v80, v[80:81]
	v_subbrev_co_u32_e64 v88, s[0:1], 0, v80, s[0:1]
	v_sub_u32_e32 v80, 0, v88
	v_ldexp_f32 v81, v82, v80
	v_add_f32_e32 v82, -1.0, v81
	v_add_f32_e32 v84, 1.0, v81
	v_ldexp_f32 v80, v83, v80
	v_add_f32_e32 v83, 1.0, v82
	v_add_f32_e32 v85, -1.0, v84
	v_sub_f32_e32 v83, v81, v83
	v_sub_f32_e32 v81, v81, v85
	v_add_f32_e32 v83, v80, v83
	v_add_f32_e32 v80, v80, v81
	v_add_f32_e32 v89, v84, v80
	v_rcp_f32_e32 v91, v89
	v_sub_f32_e32 v81, v84, v89
	v_add_f32_e32 v90, v80, v81
	v_add_f32_e32 v81, v82, v83
	v_mul_f32_e32 v93, v81, v91
	v_sub_f32_e32 v80, v82, v81
	v_mul_f32_e32 v82, v89, v93
	v_fma_f32 v84, v93, v89, -v82
	v_fmac_f32_e32 v84, v93, v90
	v_add_f32_e32 v92, v83, v80
	v_add_f32_e32 v80, v82, v84
	v_sub_f32_e32 v83, v81, v80
	v_pk_add_f32 v[86:87], v[80:81], v[82:83] neg_lo:[0,1] neg_hi:[0,1]
	v_mov_b32_e32 v85, v80
	v_pk_add_f32 v[80:81], v[86:87], v[84:85] neg_lo:[0,1] neg_hi:[0,1]
	v_cmp_neq_f32_e64 s[0:1], s2, v54
	v_add_f32_e32 v81, v92, v81
	v_add_f32_e32 v80, v80, v81
	v_add_f32_e32 v81, v83, v80
	v_mul_f32_e32 v92, v91, v81
	v_mul_f32_e32 v82, v89, v92
	v_fma_f32 v84, v92, v89, -v82
	v_fmac_f32_e32 v84, v92, v90
	v_sub_f32_e32 v83, v83, v81
	v_add_f32_e32 v89, v80, v83
	v_add_f32_e32 v80, v82, v84
	v_sub_f32_e32 v83, v81, v80
	v_pk_add_f32 v[86:87], v[80:81], v[82:83] neg_lo:[0,1] neg_hi:[0,1]
	v_mov_b32_e32 v85, v80
	v_pk_add_f32 v[80:81], v[86:87], v[84:85] neg_lo:[0,1] neg_hi:[0,1]
	s_nop 0
	v_add_f32_e32 v81, v89, v81
	v_add_f32_e32 v80, v80, v81
	v_add_f32_e32 v81, v93, v92
	v_add_f32_e32 v80, v83, v80
	v_sub_f32_e32 v82, v81, v93
	v_mul_f32_e32 v80, v91, v80
	v_sub_f32_e32 v82, v92, v82
	v_add_f32_e32 v82, v82, v80
	v_add_f32_e32 v84, v81, v82
	v_mul_f32_e32 v85, v84, v84
	v_fmamk_f32 v80, v85, 0x3e9b6dac, v206
	v_fmaak_f32 v179, v85, v80, 0x3f2aaada
	v_cvt_f32_i32_e32 v80, v88
	v_sub_f32_e32 v81, v84, v81
	v_sub_f32_e32 v81, v82, v81
	v_ldexp_f32 v86, v81, 1
	v_mul_f32_e32 v81, v84, v85
	v_ldexp_f32 v83, v84, 1
	v_pk_mul_f32 v[84:85], v[80:81], v[178:179]
	s_nop 0
	v_fma_f32 v82, v80, s69, -v84
	v_fmac_f32_e32 v82, 0xb102e308, v80
	v_pk_add_f32 v[80:81], v[84:85], v[82:83]
	s_nop 0
	v_sub_f32_e32 v83, v81, v83
	v_sub_f32_e32 v83, v85, v83
	v_add_f32_e32 v87, v86, v83
	v_mov_b32_e32 v86, v84
	v_pk_add_f32 v[84:85], v[80:81], v[84:85] neg_lo:[0,1] neg_hi:[0,1]
	v_pk_add_f32 v[88:89], v[80:81], v[86:87]
	v_mov_b32_e32 v83, v80
	v_mov_b32_e32 v85, v89
	v_pk_add_f32 v[90:91], v[82:83], v[84:85] neg_lo:[0,1] neg_hi:[0,1]
	v_pk_add_f32 v[82:83], v[82:83], v[84:85]
	v_mov_b32_e32 v86, v87
	v_pk_add_f32 v[84:85], v[82:83], v[80:81] op_sel:[1,0] op_sel_hi:[0,1] neg_lo:[0,1] neg_hi:[0,1]
	v_pk_add_f32 v[92:93], v[88:89], v[84:85] op_sel_hi:[1,0] neg_lo:[0,1] neg_hi:[0,1]
	v_mov_b32_e32 v88, v89
	v_mov_b32_e32 v89, v83
	v_pk_mov_b32 v[84:85], v[80:81], v[84:85] op_sel:[1,0]
	v_mov_b32_e32 v87, v80
	v_pk_add_f32 v[84:85], v[88:89], v[84:85] neg_lo:[0,1] neg_hi:[0,1]
	v_mov_b32_e32 v92, v90
	v_pk_add_f32 v[80:81], v[86:87], v[84:85] neg_lo:[0,1] neg_hi:[0,1]
	v_mov_b32_e32 v91, v83
	v_pk_add_f32 v[84:85], v[92:93], v[80:81]
	s_nop 0
	v_pk_add_f32 v[86:87], v[84:85], v[84:85] op_sel:[0,1] op_sel_hi:[1,0]
	s_nop 0
	v_pk_add_f32 v[82:83], v[82:83], v[86:87] op_sel:[1,0] op_sel_hi:[0,1]
	v_mov_b32_e32 v85, v82
	v_pk_add_f32 v[88:89], v[84:85], v[90:91] neg_lo:[0,1] neg_hi:[0,1]
	v_mov_b32_e32 v81, v86
	v_sub_f32_e32 v83, v84, v88
	v_pk_add_f32 v[80:81], v[80:81], v[88:89] neg_lo:[0,1] neg_hi:[0,1]
	v_sub_f32_e32 v83, v90, v83
	v_add_f32_e32 v80, v80, v83
	v_add_f32_e32 v80, v80, v81
	v_add_f32_e32 v80, v82, v80
	v_cndmask_b32_e64 v80, v208, v80, s[0:1]
	v_cmp_lt_f32_e64 s[0:1], |v54|, s66
	s_nop 1
	v_cndmask_b32_e64 v54, v80, v54, s[0:1]
	v_lshl_add_u64 v[80:81], v[78:79], 0, v[68:69]
	v_lshlrev_b64 v[80:81], 14, v[80:81]
	v_sub_f32_e32 v0, v0, v54
	v_lshl_add_u64 v[80:81], v[60:61], 0, v[80:81]
	global_store_dword v[80:81], v0, off
	s_or_b64 exec, exec, s[84:85]
	s_and_saveexec_b64 s[84:85], s[6:7]
	s_cbranch_execz .LBB0_529
;     __device__ __forceinline__ void operator()(const f32x4 (&acc)[2][2][4][2], const pg8::Unit& u, int wr, int wc, int fr, int fq) const {
;     ...
;         if (kind == 1 && pn == 28) {
;             if (wc == 0) {
; #pragma unroll
;                 for (int ai = 0; ai < 2; ++ai)
; #pragma unroll
;                     for (int m = 0; m < 4; ++m) { const int row = row0 + ai * 128 + m * 16;
; #pragma unroll
;                         for (int n = 0; n < 2; ++n)
; #pragma unroll
;                             for (int j = 0; j < 4; ++j) { const int col = 8 * fq + 4 * n + j;
;                                 if (col < 12) { const float xv = acc[ai][0][m][n][j] * rsqrtf(ssq[row] * (1.f / DM) + EPS) + bfp[col]; LS[((size_t)(row >> 12) * 12 + col) * SEQ + (row & (SEQ - 1))] = fminf(xv, 0.f) - log1pf(expf(-fabsf(xv))); } } }
.LBB0_592:
	global_load_dword v0, v[66:67], off offset:64
	v_lshl_add_u64 v[80:81], v[70:71], 2, s[60:61]
	s_waitcnt vmcnt(0) lgkmcnt(0)
	v_fmamk_f32 v0, v0, 0x3a000000, v205
	v_cmp_gt_f32_e64 s[0:1], s68, v0
	v_mul_f32_e32 v54, 0x4b800000, v0
	s_nop 0
	v_cndmask_b32_e64 v0, v0, v54, s[0:1]
	v_rsq_f32_e32 v0, v0
	s_nop 0
	v_mul_f32_e32 v54, 0x45800000, v0
	v_cndmask_b32_e64 v0, v0, v54, s[0:1]
	global_load_dword v54, v[80:81], off
	s_waitcnt vmcnt(0) lgkmcnt(0)
	v_fmac_f32_e32 v54, v55, v0
	v_mul_f32_e64 v55, |v54|, s88
	v_fma_f32 v80, |v54|, s88, -v55
	v_rndne_f32_e32 v81, v55
	v_fma_f32 v80, |v54|, s89, v80
	v_sub_f32_e32 v55, v55, v81
	v_add_f32_e32 v55, v55, v80
	v_exp_f32_e32 v55, v55
	v_cvt_i32_f32_e32 v80, v81
	v_cmp_ngt_f32_e64 s[0:1], |v54|, s70
	v_min_f32_e32 v0, 0, v54
	v_ldexp_f32 v55, v55, v80
	v_cndmask_b32_e64 v55, 0, v55, s[0:1]
	v_cmp_nlt_f32_e64 s[0:1], |v54|, s90
	s_nop 1
	v_cndmask_b32_e64 v92, v208, v55, s[0:1]
	v_add_f32_e32 v80, 1.0, v92
	v_add_f32_e32 v54, -1.0, v80
	v_sub_f32_e32 v55, v54, v80
	v_add_f32_e32 v55, 1.0, v55
	v_sub_f32_e32 v54, v92, v54
	v_add_f32_e32 v81, v54, v55
	v_frexp_mant_f32_e32 v54, v80
	v_cmp_gt_f32_e64 s[0:1], s3, v54
	v_cvt_f64_f32_e32 v[54:55], v80
	v_frexp_exp_i32_f64_e32 v54, v[54:55]
	v_subbrev_co_u32_e64 v86, s[0:1], 0, v54, s[0:1]
	v_sub_u32_e32 v54, 0, v86
	v_ldexp_f32 v55, v80, v54
	v_add_f32_e32 v80, -1.0, v55
	v_add_f32_e32 v82, 1.0, v55
	v_ldexp_f32 v54, v81, v54
	v_add_f32_e32 v81, 1.0, v80
	v_add_f32_e32 v83, -1.0, v82
	v_sub_f32_e32 v81, v55, v81
	v_sub_f32_e32 v55, v55, v83
	v_add_f32_e32 v81, v54, v81
	v_add_f32_e32 v54, v54, v55
	v_add_f32_e32 v87, v82, v54
	v_rcp_f32_e32 v89, v87
	v_sub_f32_e32 v55, v82, v87
	v_add_f32_e32 v88, v54, v55
	v_add_f32_e32 v55, v80, v81
	v_mul_f32_e32 v91, v55, v89
	v_sub_f32_e32 v54, v80, v55
	v_mul_f32_e32 v80, v87, v91
	v_fma_f32 v82, v91, v87, -v80
	v_fmac_f32_e32 v82, v91, v88
	v_add_f32_e32 v90, v81, v54
	v_add_f32_e32 v54, v80, v82
	v_sub_f32_e32 v81, v55, v54
	v_pk_add_f32 v[84:85], v[54:55], v[80:81] neg_lo:[0,1] neg_hi:[0,1]
	v_mov_b32_e32 v83, v54
	v_pk_add_f32 v[54:55], v[84:85], v[82:83] neg_lo:[0,1] neg_hi:[0,1]
	v_cmp_neq_f32_e64 s[0:1], s2, v92
	v_add_f32_e32 v55, v90, v55
	v_add_f32_e32 v54, v54, v55
	v_add_f32_e32 v55, v81, v54
	v_mul_f32_e32 v90, v89, v55
	v_mul_f32_e32 v80, v87, v90
	v_fma_f32 v82, v90, v87, -v80
	v_fmac_f32_e32 v82, v90, v88
	v_sub_f32_e32 v81, v81, v55
	v_add_f32_e32 v87, v54, v81
	v_add_f32_e32 v54, v80, v82
	v_sub_f32_e32 v81, v55, v54
	v_pk_add_f32 v[84:85], v[54:55], v[80:81] neg_lo:[0,1] neg_hi:[0,1]
	v_mov_b32_e32 v83, v54
	v_pk_add_f32 v[54:55], v[84:85], v[82:83] neg_lo:[0,1] neg_hi:[0,1]
	s_nop 0
	v_add_f32_e32 v55, v87, v55
	v_add_f32_e32 v54, v54, v55
	v_add_f32_e32 v55, v91, v90
	v_add_f32_e32 v54, v81, v54
	v_sub_f32_e32 v80, v55, v91
	v_mul_f32_e32 v54, v89, v54
	v_sub_f32_e32 v80, v90, v80
	v_add_f32_e32 v80, v80, v54
	v_add_f32_e32 v82, v55, v80
	v_mul_f32_e32 v83, v82, v82
	v_fmamk_f32 v54, v83, 0x3e9b6dac, v206
	v_fmaak_f32 v179, v83, v54, 0x3f2aaada
	v_cvt_f32_i32_e32 v54, v86
	v_sub_f32_e32 v55, v82, v55
	v_sub_f32_e32 v55, v80, v55
	v_ldexp_f32 v84, v55, 1
	v_mul_f32_e32 v55, v82, v83
	v_ldexp_f32 v81, v82, 1
	v_pk_mul_f32 v[82:83], v[54:55], v[178:179]
	s_nop 0
	v_fma_f32 v80, v54, s69, -v82
	v_fmac_f32_e32 v80, 0xb102e308, v54
	v_pk_add_f32 v[54:55], v[82:83], v[80:81]
	s_nop 0
	v_sub_f32_e32 v81, v55, v81
	v_sub_f32_e32 v81, v83, v81
	v_add_f32_e32 v85, v84, v81
	v_mov_b32_e32 v84, v82
	v_pk_add_f32 v[82:83], v[54:55], v[82:83] neg_lo:[0,1] neg_hi:[0,1]
	v_pk_add_f32 v[86:87], v[54:55], v[84:85]
	v_mov_b32_e32 v81, v54
	v_mov_b32_e32 v83, v87
	v_pk_add_f32 v[88:89], v[80:81], v[82:83] neg_lo:[0,1] neg_hi:[0,1]
	v_pk_add_f32 v[80:81], v[80:81], v[82:83]
	v_mov_b32_e32 v84, v85
	v_pk_add_f32 v[82:83], v[80:81], v[54:55] op_sel:[1,0] op_sel_hi:[0,1] neg_lo:[0,1] neg_hi:[0,1]
	v_pk_add_f32 v[90:91], v[86:87], v[82:83] op_sel_hi:[1,0] neg_lo:[0,1] neg_hi:[0,1]
	v_mov_b32_e32 v86, v87
	v_mov_b32_e32 v87, v81
	v_pk_mov_b32 v[82:83], v[54:55], v[82:83] op_sel:[1,0]
	v_mov_b32_e32 v85, v54
	v_pk_add_f32 v[82:83], v[86:87], v[82:83] neg_lo:[0,1] neg_hi:[0,1]
	v_mov_b32_e32 v90, v88
	v_pk_add_f32 v[54:55], v[84:85], v[82:83] neg_lo:[0,1] neg_hi:[0,1]
	v_mov_b32_e32 v89, v81
	v_pk_add_f32 v[82:83], v[90:91], v[54:55]
	s_nop 0
	v_pk_add_f32 v[84:85], v[82:83], v[82:83] op_sel:[0,1] op_sel_hi:[1,0]
	s_nop 0
	v_pk_add_f32 v[80:81], v[80:81], v[84:85] op_sel:[1,0] op_sel_hi:[0,1]
	v_mov_b32_e32 v83, v80
	v_pk_add_f32 v[86:87], v[82:83], v[88:89] neg_lo:[0,1] neg_hi:[0,1]
	v_mov_b32_e32 v55, v84
	v_sub_f32_e32 v81, v82, v86
	v_pk_add_f32 v[54:55], v[54:55], v[86:87] neg_lo:[0,1] neg_hi:[0,1]
	v_sub_f32_e32 v81, v88, v81
	v_add_f32_e32 v54, v54, v81
	v_add_f32_e32 v54, v54, v55
	v_add_f32_e32 v54, v80, v54
	v_cndmask_b32_e64 v54, v208, v54, s[0:1]
	v_cmp_lt_f32_e64 s[0:1], |v92|, s66
	s_nop 1
	v_cndmask_b32_e64 v54, v54, v92, s[0:1]
	v_sub_f32_e32 v0, v0, v54
	v_lshl_add_u64 v[54:55], v[78:79], 0, v[70:71]
	v_lshlrev_b64 v[54:55], 14, v[54:55]
	v_lshl_add_u64 v[54:55], v[60:61], 0, v[54:55]
	global_store_dword v[54:55], v0, off
	s_or_b64 exec, exec, s[84:85]
	s_and_saveexec_b64 s[84:85], s[8:9]
	s_cbranch_execz .LBB0_530
;     __device__ __forceinline__ void operator()(const f32x4 (&acc)[2][2][4][2], const pg8::Unit& u, int wr, int wc, int fr, int fq) const {
;     ...
;         if (kind == 1 && pn == 28) {
;             if (wc == 0) {
; #pragma unroll
;                 for (int ai = 0; ai < 2; ++ai)
; #pragma unroll
;                     for (int m = 0; m < 4; ++m) { const int row = row0 + ai * 128 + m * 16;
; #pragma unroll
;                         for (int n = 0; n < 2; ++n)
; #pragma unroll
;                             for (int j = 0; j < 4; ++j) { const int col = 8 * fq + 4 * n + j;
;                                 if (col < 12) { const float xv = acc[ai][0][m][n][j] * rsqrtf(ssq[row] * (1.f / DM) + EPS) + bfp[col]; LS[((size_t)(row >> 12) * 12 + col) * SEQ + (row & (SEQ - 1))] = fminf(xv, 0.f) - log1pf(expf(-fabsf(xv))); } } }
.LBB0_593:
	global_load_dword v0, v[66:67], off offset:64
	s_waitcnt vmcnt(0) lgkmcnt(0)
	v_fmamk_f32 v0, v0, 0x3a000000, v205
	v_cmp_gt_f32_e64 s[0:1], s68, v0
	v_mul_f32_e32 v54, 0x4b800000, v0
	s_nop 0
	v_cndmask_b32_e64 v0, v0, v54, s[0:1]
	v_rsq_f32_e32 v0, v0
	s_nop 0
	v_mul_f32_e32 v54, 0x45800000, v0
	v_cndmask_b32_e64 v0, v0, v54, s[0:1]
	v_lshl_add_u64 v[54:55], v[62:63], 2, s[60:61]
	global_load_dword v54, v[54:55], off
	s_waitcnt vmcnt(0) lgkmcnt(0)
	v_fmac_f32_e32 v54, v56, v0
	v_mul_f32_e64 v55, |v54|, s88
	v_fma_f32 v56, |v54|, s88, -v55
	v_rndne_f32_e32 v80, v55
	v_fma_f32 v56, |v54|, s89, v56
	v_sub_f32_e32 v55, v55, v80
	v_add_f32_e32 v55, v55, v56
	v_exp_f32_e32 v55, v55
	v_cvt_i32_f32_e32 v56, v80
	v_cmp_ngt_f32_e64 s[0:1], |v54|, s70
	v_min_f32_e32 v0, 0, v54
	v_ldexp_f32 v55, v55, v56
	v_cndmask_b32_e64 v55, 0, v55, s[0:1]
	v_cmp_nlt_f32_e64 s[0:1], |v54|, s90
	s_nop 1
	v_cndmask_b32_e64 v56, v208, v55, s[0:1]
	v_add_f32_e32 v80, 1.0, v56
	v_add_f32_e32 v54, -1.0, v80
	v_sub_f32_e32 v55, v54, v80
	v_add_f32_e32 v55, 1.0, v55
	v_sub_f32_e32 v54, v56, v54
	v_add_f32_e32 v81, v54, v55
	v_frexp_mant_f32_e32 v54, v80
	v_cmp_gt_f32_e64 s[0:1], s3, v54
	v_cvt_f64_f32_e32 v[54:55], v80
	v_frexp_exp_i32_f64_e32 v54, v[54:55]
	v_subbrev_co_u32_e64 v86, s[0:1], 0, v54, s[0:1]
	v_sub_u32_e32 v54, 0, v86
	v_ldexp_f32 v55, v80, v54
	v_add_f32_e32 v80, -1.0, v55
	v_add_f32_e32 v82, 1.0, v55
	v_ldexp_f32 v54, v81, v54
	v_add_f32_e32 v81, 1.0, v80
	v_add_f32_e32 v83, -1.0, v82
	v_sub_f32_e32 v81, v55, v81
	v_sub_f32_e32 v55, v55, v83
	v_add_f32_e32 v81, v54, v81
	v_add_f32_e32 v54, v54, v55
	v_add_f32_e32 v87, v82, v54
	v_rcp_f32_e32 v89, v87
	v_sub_f32_e32 v55, v82, v87
	v_add_f32_e32 v88, v54, v55
	v_add_f32_e32 v55, v80, v81
	v_mul_f32_e32 v91, v55, v89
	v_sub_f32_e32 v54, v80, v55
	v_mul_f32_e32 v80, v87, v91
	v_fma_f32 v82, v91, v87, -v80
	v_fmac_f32_e32 v82, v91, v88
	v_add_f32_e32 v90, v81, v54
	v_add_f32_e32 v54, v80, v82
	v_sub_f32_e32 v81, v55, v54
	v_pk_add_f32 v[84:85], v[54:55], v[80:81] neg_lo:[0,1] neg_hi:[0,1]
	v_mov_b32_e32 v83, v54
	v_pk_add_f32 v[54:55], v[84:85], v[82:83] neg_lo:[0,1] neg_hi:[0,1]
	v_cmp_neq_f32_e64 s[0:1], s2, v56
	v_add_f32_e32 v55, v90, v55
	v_add_f32_e32 v54, v54, v55
	v_add_f32_e32 v55, v81, v54
	v_mul_f32_e32 v90, v89, v55
	v_mul_f32_e32 v80, v87, v90
	v_fma_f32 v82, v90, v87, -v80
	v_fmac_f32_e32 v82, v90, v88
	v_sub_f32_e32 v81, v81, v55
	v_add_f32_e32 v87, v54, v81
	v_add_f32_e32 v54, v80, v82
	v_sub_f32_e32 v81, v55, v54
	v_pk_add_f32 v[84:85], v[54:55], v[80:81] neg_lo:[0,1] neg_hi:[0,1]
	v_mov_b32_e32 v83, v54
	v_pk_add_f32 v[54:55], v[84:85], v[82:83] neg_lo:[0,1] neg_hi:[0,1]
	s_nop 0
	v_add_f32_e32 v55, v87, v55
	v_add_f32_e32 v54, v54, v55
	v_add_f32_e32 v55, v91, v90
	v_add_f32_e32 v54, v81, v54
	v_sub_f32_e32 v80, v55, v91
	v_mul_f32_e32 v54, v89, v54
	v_sub_f32_e32 v80, v90, v80
	v_add_f32_e32 v80, v80, v54
	v_add_f32_e32 v82, v55, v80
	v_mul_f32_e32 v83, v82, v82
	v_fmamk_f32 v54, v83, 0x3e9b6dac, v206
	v_fmaak_f32 v179, v83, v54, 0x3f2aaada
	v_cvt_f32_i32_e32 v54, v86
	v_sub_f32_e32 v55, v82, v55
	v_sub_f32_e32 v55, v80, v55
	v_ldexp_f32 v84, v55, 1
	v_mul_f32_e32 v55, v82, v83
	v_ldexp_f32 v81, v82, 1
	v_pk_mul_f32 v[82:83], v[54:55], v[178:179]
	s_nop 0
	v_fma_f32 v80, v54, s69, -v82
	v_fmac_f32_e32 v80, 0xb102e308, v54
	v_pk_add_f32 v[54:55], v[82:83], v[80:81]
	s_nop 0
	v_sub_f32_e32 v81, v55, v81
	v_sub_f32_e32 v81, v83, v81
	v_add_f32_e32 v85, v84, v81
	v_mov_b32_e32 v84, v82
	v_pk_add_f32 v[82:83], v[54:55], v[82:83] neg_lo:[0,1] neg_hi:[0,1]
	v_pk_add_f32 v[86:87], v[54:55], v[84:85]
	v_mov_b32_e32 v81, v54
	v_mov_b32_e32 v83, v87
	v_pk_add_f32 v[88:89], v[80:81], v[82:83] neg_lo:[0,1] neg_hi:[0,1]
	v_pk_add_f32 v[80:81], v[80:81], v[82:83]
	v_mov_b32_e32 v84, v85
	v_pk_add_f32 v[82:83], v[80:81], v[54:55] op_sel:[1,0] op_sel_hi:[0,1] neg_lo:[0,1] neg_hi:[0,1]
	v_pk_add_f32 v[90:91], v[86:87], v[82:83] op_sel_hi:[1,0] neg_lo:[0,1] neg_hi:[0,1]
	v_mov_b32_e32 v86, v87
	v_mov_b32_e32 v87, v81
	v_pk_mov_b32 v[82:83], v[54:55], v[82:83] op_sel:[1,0]
	v_mov_b32_e32 v85, v54
	v_pk_add_f32 v[82:83], v[86:87], v[82:83] neg_lo:[0,1] neg_hi:[0,1]
	v_mov_b32_e32 v90, v88
	v_pk_add_f32 v[54:55], v[84:85], v[82:83] neg_lo:[0,1] neg_hi:[0,1]
	v_mov_b32_e32 v89, v81
	v_pk_add_f32 v[82:83], v[90:91], v[54:55]
	s_nop 0
	v_pk_add_f32 v[84:85], v[82:83], v[82:83] op_sel:[0,1] op_sel_hi:[1,0]
	s_nop 0
	v_pk_add_f32 v[80:81], v[80:81], v[84:85] op_sel:[1,0] op_sel_hi:[0,1]
	v_mov_b32_e32 v83, v80
	v_pk_add_f32 v[86:87], v[82:83], v[88:89] neg_lo:[0,1] neg_hi:[0,1]
	v_mov_b32_e32 v55, v84
	v_sub_f32_e32 v81, v82, v86
	v_pk_add_f32 v[54:55], v[54:55], v[86:87] neg_lo:[0,1] neg_hi:[0,1]
	v_sub_f32_e32 v81, v88, v81
	v_add_f32_e32 v54, v54, v81
	v_add_f32_e32 v54, v54, v55
	v_add_f32_e32 v54, v80, v54
	v_cndmask_b32_e64 v54, v208, v54, s[0:1]
	v_cmp_lt_f32_e64 s[0:1], |v56|, s66
	s_nop 1
	v_cndmask_b32_e64 v54, v54, v56, s[0:1]
	v_sub_f32_e32 v0, v0, v54
	v_lshl_add_u64 v[54:55], v[78:79], 0, v[62:63]
	v_lshlrev_b64 v[54:55], 14, v[54:55]
	v_lshl_add_u64 v[54:55], v[60:61], 0, v[54:55]
	global_store_dword v[54:55], v0, off
	s_or_b64 exec, exec, s[84:85]
	s_and_saveexec_b64 s[84:85], s[10:11]
	s_cbranch_execz .LBB0_531
;     __device__ __forceinline__ void operator()(const f32x4 (&acc)[2][2][4][2], const pg8::Unit& u, int wr, int wc, int fr, int fq) const {
;     ...
;         if (kind == 1 && pn == 28) {
;             if (wc == 0) {
; #pragma unroll
;                 for (int ai = 0; ai < 2; ++ai)
; #pragma unroll
;                     for (int m = 0; m < 4; ++m) { const int row = row0 + ai * 128 + m * 16;
; #pragma unroll
;                         for (int n = 0; n < 2; ++n)
; #pragma unroll
;                             for (int j = 0; j < 4; ++j) { const int col = 8 * fq + 4 * n + j;
;                                 if (col < 12) { const float xv = acc[ai][0][m][n][j] * rsqrtf(ssq[row] * (1.f / DM) + EPS) + bfp[col]; LS[((size_t)(row >> 12) * 12 + col) * SEQ + (row & (SEQ - 1))] = fminf(xv, 0.f) - log1pf(expf(-fabsf(xv))); } } }
.LBB0_594:
	global_load_dword v0, v[66:67], off offset:64
	s_waitcnt vmcnt(0) lgkmcnt(0)
	v_fmamk_f32 v0, v0, 0x3a000000, v205
	v_cmp_gt_f32_e64 s[0:1], s68, v0
	v_mul_f32_e32 v54, 0x4b800000, v0
	s_nop 0
	v_cndmask_b32_e64 v0, v0, v54, s[0:1]
	v_rsq_f32_e32 v0, v0
	s_nop 0
	v_mul_f32_e32 v54, 0x45800000, v0
	v_cndmask_b32_e64 v0, v0, v54, s[0:1]
	v_lshl_add_u64 v[54:55], v[72:73], 2, s[60:61]
	global_load_dword v54, v[54:55], off
	s_waitcnt vmcnt(0) lgkmcnt(0)
	v_fmac_f32_e32 v54, v57, v0
	v_mul_f32_e64 v55, |v54|, s88
	v_fma_f32 v56, |v54|, s88, -v55
	v_rndne_f32_e32 v57, v55
	v_fma_f32 v56, |v54|, s89, v56
	v_sub_f32_e32 v55, v55, v57
	v_add_f32_e32 v55, v55, v56
	v_exp_f32_e32 v55, v55
	v_cvt_i32_f32_e32 v56, v57
	v_cmp_ngt_f32_e64 s[0:1], |v54|, s70
	v_min_f32_e32 v0, 0, v54
	v_ldexp_f32 v55, v55, v56
	v_cndmask_b32_e64 v55, 0, v55, s[0:1]
	v_cmp_nlt_f32_e64 s[0:1], |v54|, s90
	s_nop 1
	v_cndmask_b32_e64 v90, v208, v55, s[0:1]
	v_add_f32_e32 v56, 1.0, v90
	v_add_f32_e32 v54, -1.0, v56
	v_sub_f32_e32 v55, v54, v56
	v_add_f32_e32 v55, 1.0, v55
	v_sub_f32_e32 v54, v90, v54
	v_add_f32_e32 v57, v54, v55
	v_frexp_mant_f32_e32 v54, v56
	v_cmp_gt_f32_e64 s[0:1], s3, v54
	v_cvt_f64_f32_e32 v[54:55], v56
	v_frexp_exp_i32_f64_e32 v54, v[54:55]
	v_subbrev_co_u32_e64 v84, s[0:1], 0, v54, s[0:1]
	v_sub_u32_e32 v54, 0, v84
	v_ldexp_f32 v55, v56, v54
	v_add_f32_e32 v56, -1.0, v55
	v_add_f32_e32 v80, 1.0, v55
	v_ldexp_f32 v54, v57, v54
	v_add_f32_e32 v57, 1.0, v56
	v_add_f32_e32 v81, -1.0, v80
	v_sub_f32_e32 v57, v55, v57
	v_sub_f32_e32 v55, v55, v81
	v_add_f32_e32 v57, v54, v57
	v_add_f32_e32 v54, v54, v55
	v_add_f32_e32 v85, v80, v54
	v_rcp_f32_e32 v87, v85
	v_sub_f32_e32 v55, v80, v85
	v_add_f32_e32 v86, v54, v55
	v_add_f32_e32 v55, v56, v57
	v_mul_f32_e32 v89, v55, v87
	v_sub_f32_e32 v54, v56, v55
	v_mul_f32_e32 v56, v85, v89
	v_fma_f32 v80, v89, v85, -v56
	v_fmac_f32_e32 v80, v89, v86
	v_add_f32_e32 v88, v57, v54
	v_add_f32_e32 v54, v56, v80
	v_sub_f32_e32 v57, v55, v54
	v_pk_add_f32 v[82:83], v[54:55], v[56:57] neg_lo:[0,1] neg_hi:[0,1]
	v_mov_b32_e32 v81, v54
	v_pk_add_f32 v[54:55], v[82:83], v[80:81] neg_lo:[0,1] neg_hi:[0,1]
	v_cmp_neq_f32_e64 s[0:1], s2, v90
	v_add_f32_e32 v55, v88, v55
	v_add_f32_e32 v54, v54, v55
	v_add_f32_e32 v55, v57, v54
	v_mul_f32_e32 v88, v87, v55
	v_mul_f32_e32 v56, v85, v88
	v_fma_f32 v80, v88, v85, -v56
	v_fmac_f32_e32 v80, v88, v86
	v_sub_f32_e32 v57, v57, v55
	v_add_f32_e32 v85, v54, v57
	v_add_f32_e32 v54, v56, v80
	v_sub_f32_e32 v57, v55, v54
	v_pk_add_f32 v[82:83], v[54:55], v[56:57] neg_lo:[0,1] neg_hi:[0,1]
	v_mov_b32_e32 v81, v54
	v_pk_add_f32 v[54:55], v[82:83], v[80:81] neg_lo:[0,1] neg_hi:[0,1]
	s_nop 0
	v_add_f32_e32 v55, v85, v55
	v_add_f32_e32 v54, v54, v55
	v_add_f32_e32 v55, v89, v88
	v_add_f32_e32 v54, v57, v54
	v_sub_f32_e32 v56, v55, v89
	v_mul_f32_e32 v54, v87, v54
	v_sub_f32_e32 v56, v88, v56
	v_add_f32_e32 v56, v56, v54
	v_add_f32_e32 v80, v55, v56
	v_mul_f32_e32 v81, v80, v80
	v_fmamk_f32 v54, v81, 0x3e9b6dac, v206
	v_fmaak_f32 v179, v81, v54, 0x3f2aaada
	v_cvt_f32_i32_e32 v54, v84
	v_sub_f32_e32 v55, v80, v55
	v_sub_f32_e32 v55, v56, v55
	v_ldexp_f32 v82, v55, 1
	v_mul_f32_e32 v55, v80, v81
	v_ldexp_f32 v57, v80, 1
	v_pk_mul_f32 v[80:81], v[54:55], v[178:179]
	s_nop 0
	v_fma_f32 v56, v54, s69, -v80
	v_fmac_f32_e32 v56, 0xb102e308, v54
	v_pk_add_f32 v[54:55], v[80:81], v[56:57]
	s_nop 0
	v_sub_f32_e32 v57, v55, v57
	v_sub_f32_e32 v57, v81, v57
	v_add_f32_e32 v83, v82, v57
	v_mov_b32_e32 v82, v80
	v_pk_add_f32 v[80:81], v[54:55], v[80:81] neg_lo:[0,1] neg_hi:[0,1]
	v_pk_add_f32 v[84:85], v[54:55], v[82:83]
	v_mov_b32_e32 v57, v54
	v_mov_b32_e32 v81, v85
	v_pk_add_f32 v[86:87], v[56:57], v[80:81] neg_lo:[0,1] neg_hi:[0,1]
	v_pk_add_f32 v[56:57], v[56:57], v[80:81]
	v_mov_b32_e32 v82, v83
	v_pk_add_f32 v[80:81], v[56:57], v[54:55] op_sel:[1,0] op_sel_hi:[0,1] neg_lo:[0,1] neg_hi:[0,1]
	v_pk_add_f32 v[88:89], v[84:85], v[80:81] op_sel_hi:[1,0] neg_lo:[0,1] neg_hi:[0,1]
	v_mov_b32_e32 v84, v85
	v_mov_b32_e32 v85, v57
	v_pk_mov_b32 v[80:81], v[54:55], v[80:81] op_sel:[1,0]
	v_mov_b32_e32 v83, v54
	v_pk_add_f32 v[80:81], v[84:85], v[80:81] neg_lo:[0,1] neg_hi:[0,1]
	v_mov_b32_e32 v88, v86
	v_pk_add_f32 v[54:55], v[82:83], v[80:81] neg_lo:[0,1] neg_hi:[0,1]
	v_mov_b32_e32 v87, v57
	v_pk_add_f32 v[80:81], v[88:89], v[54:55]
	s_nop 0
	v_pk_add_f32 v[82:83], v[80:81], v[80:81] op_sel:[0,1] op_sel_hi:[1,0]
	s_nop 0
	v_pk_add_f32 v[56:57], v[56:57], v[82:83] op_sel:[1,0] op_sel_hi:[0,1]
	v_mov_b32_e32 v81, v56
	v_pk_add_f32 v[84:85], v[80:81], v[86:87] neg_lo:[0,1] neg_hi:[0,1]
	v_mov_b32_e32 v55, v82
	v_sub_f32_e32 v57, v80, v84
	v_pk_add_f32 v[54:55], v[54:55], v[84:85] neg_lo:[0,1] neg_hi:[0,1]
	v_sub_f32_e32 v57, v86, v57
	v_add_f32_e32 v54, v54, v57
	v_add_f32_e32 v54, v54, v55
	v_add_f32_e32 v54, v56, v54
	v_cndmask_b32_e64 v54, v208, v54, s[0:1]
	v_cmp_lt_f32_e64 s[0:1], |v90|, s66
	s_nop 1
	v_cndmask_b32_e64 v54, v54, v90, s[0:1]
	v_sub_f32_e32 v0, v0, v54
	v_lshl_add_u64 v[54:55], v[78:79], 0, v[72:73]
	v_lshlrev_b64 v[54:55], 14, v[54:55]
	v_lshl_add_u64 v[54:55], v[60:61], 0, v[54:55]
	global_store_dword v[54:55], v0, off
	s_or_b64 exec, exec, s[84:85]
	s_and_saveexec_b64 s[84:85], s[12:13]
	s_cbranch_execz .LBB0_532
;     __device__ __forceinline__ void operator()(const f32x4 (&acc)[2][2][4][2], const pg8::Unit& u, int wr, int wc, int fr, int fq) const {
;     ...
;         if (kind == 1 && pn == 28) {
;             if (wc == 0) {
; #pragma unroll
;                 for (int ai = 0; ai < 2; ++ai)
; #pragma unroll
;                     for (int m = 0; m < 4; ++m) { const int row = row0 + ai * 128 + m * 16;
; #pragma unroll
;                         for (int n = 0; n < 2; ++n)
; #pragma unroll
;                             for (int j = 0; j < 4; ++j) { const int col = 8 * fq + 4 * n + j;
;                                 if (col < 12) { const float xv = acc[ai][0][m][n][j] * rsqrtf(ssq[row] * (1.f / DM) + EPS) + bfp[col]; LS[((size_t)(row >> 12) * 12 + col) * SEQ + (row & (SEQ - 1))] = fminf(xv, 0.f) - log1pf(expf(-fabsf(xv))); } } }
.LBB0_595:
	global_load_dword v0, v[66:67], off offset:64
	s_waitcnt vmcnt(0) lgkmcnt(0)
	v_fmamk_f32 v0, v0, 0x3a000000, v205
	v_cmp_gt_f32_e64 s[0:1], s68, v0
	v_mul_f32_e32 v54, 0x4b800000, v0
	s_nop 0
	v_cndmask_b32_e64 v0, v0, v54, s[0:1]
	v_rsq_f32_e32 v0, v0
	s_nop 0
	v_mul_f32_e32 v54, 0x45800000, v0
	v_cndmask_b32_e64 v0, v0, v54, s[0:1]
	v_lshl_add_u64 v[54:55], v[64:65], 2, s[60:61]
	global_load_dword v54, v[54:55], off
	s_waitcnt vmcnt(0) lgkmcnt(0)
	v_fmac_f32_e32 v54, v50, v0
	v_mul_f32_e64 v50, |v54|, s88
	v_fma_f32 v55, |v54|, s88, -v50
	v_rndne_f32_e32 v56, v50
	v_fma_f32 v55, |v54|, s89, v55
	v_sub_f32_e32 v50, v50, v56
	v_add_f32_e32 v50, v50, v55
	v_exp_f32_e32 v50, v50
	v_cvt_i32_f32_e32 v55, v56
	v_cmp_ngt_f32_e64 s[0:1], |v54|, s70
	v_min_f32_e32 v0, 0, v54
	v_ldexp_f32 v50, v50, v55
	v_cndmask_b32_e64 v50, 0, v50, s[0:1]
	v_cmp_nlt_f32_e64 s[0:1], |v54|, s90
	s_nop 1
	v_cndmask_b32_e64 v50, v208, v50, s[0:1]
	v_add_f32_e32 v56, 1.0, v50
	v_add_f32_e32 v54, -1.0, v56
	v_sub_f32_e32 v55, v54, v56
	v_add_f32_e32 v55, 1.0, v55
	v_sub_f32_e32 v54, v50, v54
	v_add_f32_e32 v57, v54, v55
	v_frexp_mant_f32_e32 v54, v56
	v_cmp_gt_f32_e64 s[0:1], s3, v54
	v_cvt_f64_f32_e32 v[54:55], v56
	v_frexp_exp_i32_f64_e32 v54, v[54:55]
	v_subbrev_co_u32_e64 v84, s[0:1], 0, v54, s[0:1]
	v_sub_u32_e32 v54, 0, v84
	v_ldexp_f32 v55, v56, v54
	v_add_f32_e32 v56, -1.0, v55
	v_add_f32_e32 v80, 1.0, v55
	v_ldexp_f32 v54, v57, v54
	v_add_f32_e32 v57, 1.0, v56
	v_add_f32_e32 v81, -1.0, v80
	v_sub_f32_e32 v57, v55, v57
	v_sub_f32_e32 v55, v55, v81
	v_add_f32_e32 v57, v54, v57
	v_add_f32_e32 v54, v54, v55
	v_add_f32_e32 v85, v80, v54
	v_rcp_f32_e32 v87, v85
	v_sub_f32_e32 v55, v80, v85
	v_add_f32_e32 v86, v54, v55
	v_add_f32_e32 v55, v56, v57
	v_mul_f32_e32 v89, v55, v87
	v_sub_f32_e32 v54, v56, v55
	v_mul_f32_e32 v56, v85, v89
	v_fma_f32 v80, v89, v85, -v56
	v_fmac_f32_e32 v80, v89, v86
	v_add_f32_e32 v88, v57, v54
	v_add_f32_e32 v54, v56, v80
	v_sub_f32_e32 v57, v55, v54
	v_pk_add_f32 v[82:83], v[54:55], v[56:57] neg_lo:[0,1] neg_hi:[0,1]
	v_mov_b32_e32 v81, v54
	v_pk_add_f32 v[54:55], v[82:83], v[80:81] neg_lo:[0,1] neg_hi:[0,1]
	v_cmp_neq_f32_e64 s[0:1], s2, v50
	v_add_f32_e32 v55, v88, v55
	v_add_f32_e32 v54, v54, v55
	v_add_f32_e32 v55, v57, v54
	v_mul_f32_e32 v88, v87, v55
	v_mul_f32_e32 v56, v85, v88
	v_fma_f32 v80, v88, v85, -v56
	v_fmac_f32_e32 v80, v88, v86
	v_sub_f32_e32 v57, v57, v55
	v_add_f32_e32 v85, v54, v57
	v_add_f32_e32 v54, v56, v80
	v_sub_f32_e32 v57, v55, v54
	v_pk_add_f32 v[82:83], v[54:55], v[56:57] neg_lo:[0,1] neg_hi:[0,1]
	v_mov_b32_e32 v81, v54
	v_pk_add_f32 v[54:55], v[82:83], v[80:81] neg_lo:[0,1] neg_hi:[0,1]
	s_nop 0
	v_add_f32_e32 v55, v85, v55
	v_add_f32_e32 v54, v54, v55
	v_add_f32_e32 v55, v89, v88
	v_add_f32_e32 v54, v57, v54
	v_sub_f32_e32 v56, v55, v89
	v_mul_f32_e32 v54, v87, v54
	v_sub_f32_e32 v56, v88, v56
	v_add_f32_e32 v56, v56, v54
	v_add_f32_e32 v80, v55, v56
	v_mul_f32_e32 v81, v80, v80
	v_fmamk_f32 v54, v81, 0x3e9b6dac, v206
	v_fmaak_f32 v179, v81, v54, 0x3f2aaada
	v_cvt_f32_i32_e32 v54, v84
	v_sub_f32_e32 v55, v80, v55
	v_sub_f32_e32 v55, v56, v55
	v_ldexp_f32 v82, v55, 1
	v_mul_f32_e32 v55, v80, v81
	v_ldexp_f32 v57, v80, 1
	v_pk_mul_f32 v[80:81], v[54:55], v[178:179]
	s_nop 0
	v_fma_f32 v56, v54, s69, -v80
	v_fmac_f32_e32 v56, 0xb102e308, v54
	v_pk_add_f32 v[54:55], v[80:81], v[56:57]
	s_nop 0
	v_sub_f32_e32 v57, v55, v57
	v_sub_f32_e32 v57, v81, v57
	v_add_f32_e32 v83, v82, v57
	v_mov_b32_e32 v82, v80
	v_pk_add_f32 v[80:81], v[54:55], v[80:81] neg_lo:[0,1] neg_hi:[0,1]
	v_pk_add_f32 v[84:85], v[54:55], v[82:83]
	v_mov_b32_e32 v57, v54
	v_mov_b32_e32 v81, v85
	v_pk_add_f32 v[86:87], v[56:57], v[80:81] neg_lo:[0,1] neg_hi:[0,1]
	v_pk_add_f32 v[56:57], v[56:57], v[80:81]
	v_mov_b32_e32 v82, v83
	v_pk_add_f32 v[80:81], v[56:57], v[54:55] op_sel:[1,0] op_sel_hi:[0,1] neg_lo:[0,1] neg_hi:[0,1]
	v_pk_add_f32 v[88:89], v[84:85], v[80:81] op_sel_hi:[1,0] neg_lo:[0,1] neg_hi:[0,1]
	v_mov_b32_e32 v84, v85
	v_mov_b32_e32 v85, v57
	v_pk_mov_b32 v[80:81], v[54:55], v[80:81] op_sel:[1,0]
	v_mov_b32_e32 v83, v54
	v_pk_add_f32 v[80:81], v[84:85], v[80:81] neg_lo:[0,1] neg_hi:[0,1]
	v_mov_b32_e32 v88, v86
	v_pk_add_f32 v[54:55], v[82:83], v[80:81] neg_lo:[0,1] neg_hi:[0,1]
	v_mov_b32_e32 v87, v57
	v_pk_add_f32 v[80:81], v[88:89], v[54:55]
	s_nop 0
	v_pk_add_f32 v[82:83], v[80:81], v[80:81] op_sel:[0,1] op_sel_hi:[1,0]
	s_nop 0
	v_pk_add_f32 v[56:57], v[56:57], v[82:83] op_sel:[1,0] op_sel_hi:[0,1]
	v_mov_b32_e32 v81, v56
	v_pk_add_f32 v[84:85], v[80:81], v[86:87] neg_lo:[0,1] neg_hi:[0,1]
	v_mov_b32_e32 v55, v82
	v_sub_f32_e32 v57, v80, v84
	v_pk_add_f32 v[54:55], v[54:55], v[84:85] neg_lo:[0,1] neg_hi:[0,1]
	v_sub_f32_e32 v57, v86, v57
	v_add_f32_e32 v54, v54, v57
	v_add_f32_e32 v54, v54, v55
	v_add_f32_e32 v54, v56, v54
	v_cndmask_b32_e64 v54, v208, v54, s[0:1]
	v_cmp_lt_f32_e64 s[0:1], |v50|, s66
	s_nop 1
	v_cndmask_b32_e64 v50, v54, v50, s[0:1]
	v_lshl_add_u64 v[54:55], v[78:79], 0, v[64:65]
	v_lshlrev_b64 v[54:55], 14, v[54:55]
	v_sub_f32_e32 v0, v0, v50
	v_lshl_add_u64 v[54:55], v[60:61], 0, v[54:55]
	global_store_dword v[54:55], v0, off
	s_or_b64 exec, exec, s[84:85]
	s_and_saveexec_b64 s[84:85], s[14:15]
	s_cbranch_execz .LBB0_533
;     __device__ __forceinline__ void operator()(const f32x4 (&acc)[2][2][4][2], const pg8::Unit& u, int wr, int wc, int fr, int fq) const {
;     ...
;         if (kind == 1 && pn == 28) {
;             if (wc == 0) {
; #pragma unroll
;                 for (int ai = 0; ai < 2; ++ai)
; #pragma unroll
;                     for (int m = 0; m < 4; ++m) { const int row = row0 + ai * 128 + m * 16;
; #pragma unroll
;                         for (int n = 0; n < 2; ++n)
; #pragma unroll
;                             for (int j = 0; j < 4; ++j) { const int col = 8 * fq + 4 * n + j;
;                                 if (col < 12) { const float xv = acc[ai][0][m][n][j] * rsqrtf(ssq[row] * (1.f / DM) + EPS) + bfp[col]; LS[((size_t)(row >> 12) * 12 + col) * SEQ + (row & (SEQ - 1))] = fminf(xv, 0.f) - log1pf(expf(-fabsf(xv))); } } }
.LBB0_596:
	global_load_dword v0, v[66:67], off offset:64
	v_lshl_add_u64 v[54:55], v[74:75], 2, s[60:61]
	s_waitcnt vmcnt(0) lgkmcnt(0)
	v_fmamk_f32 v0, v0, 0x3a000000, v205
	v_cmp_gt_f32_e64 s[0:1], s68, v0
	v_mul_f32_e32 v50, 0x4b800000, v0
	s_nop 0
	v_cndmask_b32_e64 v0, v0, v50, s[0:1]
	v_rsq_f32_e32 v0, v0
	s_nop 0
	v_mul_f32_e32 v50, 0x45800000, v0
	v_cndmask_b32_e64 v0, v0, v50, s[0:1]
	global_load_dword v50, v[54:55], off
	s_waitcnt vmcnt(0) lgkmcnt(0)
	v_fmac_f32_e32 v50, v51, v0
	v_mul_f32_e64 v51, |v50|, s88
	v_fma_f32 v54, |v50|, s88, -v51
	v_rndne_f32_e32 v55, v51
	v_fma_f32 v54, |v50|, s89, v54
	v_sub_f32_e32 v51, v51, v55
	v_add_f32_e32 v51, v51, v54
	v_exp_f32_e32 v51, v51
	v_cvt_i32_f32_e32 v54, v55
	v_cmp_ngt_f32_e64 s[0:1], |v50|, s70
	v_min_f32_e32 v0, 0, v50
	v_ldexp_f32 v51, v51, v54
	v_cndmask_b32_e64 v51, 0, v51, s[0:1]
	v_cmp_nlt_f32_e64 s[0:1], |v50|, s90
	s_nop 1
	v_cndmask_b32_e64 v88, v208, v51, s[0:1]
	v_add_f32_e32 v54, 1.0, v88
	v_add_f32_e32 v50, -1.0, v54
	v_sub_f32_e32 v51, v50, v54
	v_add_f32_e32 v51, 1.0, v51
	v_sub_f32_e32 v50, v88, v50
	v_add_f32_e32 v55, v50, v51
	v_frexp_mant_f32_e32 v50, v54
	v_cmp_gt_f32_e64 s[0:1], s3, v50
	v_cvt_f64_f32_e32 v[50:51], v54
	v_frexp_exp_i32_f64_e32 v50, v[50:51]
	v_subbrev_co_u32_e64 v82, s[0:1], 0, v50, s[0:1]
	v_sub_u32_e32 v50, 0, v82
	v_ldexp_f32 v51, v54, v50
	v_add_f32_e32 v54, -1.0, v51
	v_add_f32_e32 v56, 1.0, v51
	v_ldexp_f32 v50, v55, v50
	v_add_f32_e32 v55, 1.0, v54
	v_add_f32_e32 v57, -1.0, v56
	v_sub_f32_e32 v55, v51, v55
	v_sub_f32_e32 v51, v51, v57
	v_add_f32_e32 v55, v50, v55
	v_add_f32_e32 v50, v50, v51
	v_add_f32_e32 v83, v56, v50
	v_rcp_f32_e32 v85, v83
	v_sub_f32_e32 v51, v56, v83
	v_add_f32_e32 v84, v50, v51
	v_add_f32_e32 v51, v54, v55
	v_mul_f32_e32 v87, v51, v85
	v_sub_f32_e32 v50, v54, v51
	v_mul_f32_e32 v54, v83, v87
	v_fma_f32 v56, v87, v83, -v54
	v_fmac_f32_e32 v56, v87, v84
	v_add_f32_e32 v86, v55, v50
	v_add_f32_e32 v50, v54, v56
	v_sub_f32_e32 v55, v51, v50
	v_pk_add_f32 v[80:81], v[50:51], v[54:55] neg_lo:[0,1] neg_hi:[0,1]
	v_mov_b32_e32 v57, v50
	v_pk_add_f32 v[50:51], v[80:81], v[56:57] neg_lo:[0,1] neg_hi:[0,1]
	v_cmp_neq_f32_e64 s[0:1], s2, v88
	v_add_f32_e32 v51, v86, v51
	v_add_f32_e32 v50, v50, v51
	v_add_f32_e32 v51, v55, v50
	v_mul_f32_e32 v86, v85, v51
	v_mul_f32_e32 v54, v83, v86
	v_fma_f32 v56, v86, v83, -v54
	v_fmac_f32_e32 v56, v86, v84
	v_sub_f32_e32 v55, v55, v51
	v_add_f32_e32 v83, v50, v55
	v_add_f32_e32 v50, v54, v56
	v_sub_f32_e32 v55, v51, v50
	v_pk_add_f32 v[80:81], v[50:51], v[54:55] neg_lo:[0,1] neg_hi:[0,1]
	v_mov_b32_e32 v57, v50
	v_pk_add_f32 v[50:51], v[80:81], v[56:57] neg_lo:[0,1] neg_hi:[0,1]
	s_nop 0
	v_add_f32_e32 v51, v83, v51
	v_add_f32_e32 v50, v50, v51
	v_add_f32_e32 v51, v87, v86
	v_add_f32_e32 v50, v55, v50
	v_sub_f32_e32 v54, v51, v87
	v_mul_f32_e32 v50, v85, v50
	v_sub_f32_e32 v54, v86, v54
	v_add_f32_e32 v54, v54, v50
	v_add_f32_e32 v56, v51, v54
	v_mul_f32_e32 v57, v56, v56
	v_fmamk_f32 v50, v57, 0x3e9b6dac, v206
	v_fmaak_f32 v179, v57, v50, 0x3f2aaada
	v_cvt_f32_i32_e32 v50, v82
	v_sub_f32_e32 v51, v56, v51
	v_sub_f32_e32 v51, v54, v51
	v_ldexp_f32 v80, v51, 1
	v_mul_f32_e32 v51, v56, v57
	v_ldexp_f32 v55, v56, 1
	v_pk_mul_f32 v[56:57], v[50:51], v[178:179]
	s_nop 0
	v_fma_f32 v54, v50, s69, -v56
	v_fmac_f32_e32 v54, 0xb102e308, v50
	v_pk_add_f32 v[50:51], v[56:57], v[54:55]
	s_nop 0
	v_sub_f32_e32 v55, v51, v55
	v_sub_f32_e32 v55, v57, v55
	v_add_f32_e32 v81, v80, v55
	v_mov_b32_e32 v80, v56
	v_pk_add_f32 v[56:57], v[50:51], v[56:57] neg_lo:[0,1] neg_hi:[0,1]
	v_pk_add_f32 v[82:83], v[50:51], v[80:81]
	v_mov_b32_e32 v55, v50
	v_mov_b32_e32 v57, v83
	v_pk_add_f32 v[84:85], v[54:55], v[56:57] neg_lo:[0,1] neg_hi:[0,1]
	v_pk_add_f32 v[54:55], v[54:55], v[56:57]
	v_mov_b32_e32 v80, v81
	v_pk_add_f32 v[56:57], v[54:55], v[50:51] op_sel:[1,0] op_sel_hi:[0,1] neg_lo:[0,1] neg_hi:[0,1]
	v_pk_add_f32 v[86:87], v[82:83], v[56:57] op_sel_hi:[1,0] neg_lo:[0,1] neg_hi:[0,1]
	v_mov_b32_e32 v82, v83
	v_mov_b32_e32 v83, v55
	v_pk_mov_b32 v[56:57], v[50:51], v[56:57] op_sel:[1,0]
	v_mov_b32_e32 v81, v50
	v_pk_add_f32 v[56:57], v[82:83], v[56:57] neg_lo:[0,1] neg_hi:[0,1]
	v_mov_b32_e32 v86, v84
	v_pk_add_f32 v[50:51], v[80:81], v[56:57] neg_lo:[0,1] neg_hi:[0,1]
	v_mov_b32_e32 v85, v55
	v_pk_add_f32 v[56:57], v[86:87], v[50:51]
	s_nop 0
	v_pk_add_f32 v[80:81], v[56:57], v[56:57] op_sel:[0,1] op_sel_hi:[1,0]
	s_nop 0
	v_pk_add_f32 v[54:55], v[54:55], v[80:81] op_sel:[1,0] op_sel_hi:[0,1]
	v_mov_b32_e32 v57, v54
	v_pk_add_f32 v[82:83], v[56:57], v[84:85] neg_lo:[0,1] neg_hi:[0,1]
	v_mov_b32_e32 v51, v80
	v_sub_f32_e32 v55, v56, v82
	v_pk_add_f32 v[50:51], v[50:51], v[82:83] neg_lo:[0,1] neg_hi:[0,1]
	v_sub_f32_e32 v55, v84, v55
	v_add_f32_e32 v50, v50, v55
	v_add_f32_e32 v50, v50, v51
	v_add_f32_e32 v50, v54, v50
	v_cndmask_b32_e64 v50, v208, v50, s[0:1]
	v_cmp_lt_f32_e64 s[0:1], |v88|, s66
	s_nop 1
	v_cndmask_b32_e64 v50, v50, v88, s[0:1]
	v_sub_f32_e32 v0, v0, v50
	v_lshl_add_u64 v[50:51], v[78:79], 0, v[74:75]
	v_lshlrev_b64 v[50:51], 14, v[50:51]
	v_lshl_add_u64 v[50:51], v[60:61], 0, v[50:51]
	global_store_dword v[50:51], v0, off
	s_or_b64 exec, exec, s[84:85]
	s_and_saveexec_b64 s[84:85], s[16:17]
	s_cbranch_execz .LBB0_534
;     __device__ __forceinline__ void operator()(const f32x4 (&acc)[2][2][4][2], const pg8::Unit& u, int wr, int wc, int fr, int fq) const {
;     ...
;         if (kind == 1 && pn == 28) {
;             if (wc == 0) {
; #pragma unroll
;                 for (int ai = 0; ai < 2; ++ai)
; #pragma unroll
;                     for (int m = 0; m < 4; ++m) { const int row = row0 + ai * 128 + m * 16;
; #pragma unroll
;                         for (int n = 0; n < 2; ++n)
; #pragma unroll
;                             for (int j = 0; j < 4; ++j) { const int col = 8 * fq + 4 * n + j;
;                                 if (col < 12) { const float xv = acc[ai][0][m][n][j] * rsqrtf(ssq[row] * (1.f / DM) + EPS) + bfp[col]; LS[((size_t)(row >> 12) * 12 + col) * SEQ + (row & (SEQ - 1))] = fminf(xv, 0.f) - log1pf(expf(-fabsf(xv))); } } }
.LBB0_597:
	global_load_dword v0, v[66:67], off offset:64
	s_waitcnt vmcnt(0) lgkmcnt(0)
	v_fmamk_f32 v0, v0, 0x3a000000, v205
	v_cmp_gt_f32_e64 s[0:1], s68, v0
	v_mul_f32_e32 v50, 0x4b800000, v0
	s_nop 0
	v_cndmask_b32_e64 v0, v0, v50, s[0:1]
	v_rsq_f32_e32 v0, v0
	s_nop 0
	v_mul_f32_e32 v50, 0x45800000, v0
	v_cndmask_b32_e64 v0, v0, v50, s[0:1]
	v_lshl_add_u64 v[50:51], v[58:59], 2, s[60:61]
	global_load_dword v50, v[50:51], off
	s_waitcnt vmcnt(0) lgkmcnt(0)
	v_fmac_f32_e32 v50, v52, v0
	v_mul_f32_e64 v51, |v50|, s88
	v_fma_f32 v52, |v50|, s88, -v51
	v_rndne_f32_e32 v54, v51
	v_fma_f32 v52, |v50|, s89, v52
	v_sub_f32_e32 v51, v51, v54
	v_add_f32_e32 v51, v51, v52
	v_exp_f32_e32 v51, v51
	v_cvt_i32_f32_e32 v52, v54
	v_cmp_ngt_f32_e64 s[0:1], |v50|, s70
	v_min_f32_e32 v0, 0, v50
	v_ldexp_f32 v51, v51, v52
	v_cndmask_b32_e64 v51, 0, v51, s[0:1]
	v_cmp_nlt_f32_e64 s[0:1], |v50|, s90
	s_nop 1
	v_cndmask_b32_e64 v52, v208, v51, s[0:1]
	v_add_f32_e32 v54, 1.0, v52
	v_add_f32_e32 v50, -1.0, v54
	v_sub_f32_e32 v51, v50, v54
	v_add_f32_e32 v51, 1.0, v51
	v_sub_f32_e32 v50, v52, v50
	v_add_f32_e32 v55, v50, v51
	v_frexp_mant_f32_e32 v50, v54
	v_cmp_gt_f32_e64 s[0:1], s3, v50
	v_cvt_f64_f32_e32 v[50:51], v54
	v_frexp_exp_i32_f64_e32 v50, v[50:51]
	v_subbrev_co_u32_e64 v82, s[0:1], 0, v50, s[0:1]
	v_sub_u32_e32 v50, 0, v82
	v_ldexp_f32 v51, v54, v50
	v_add_f32_e32 v54, -1.0, v51
	v_add_f32_e32 v56, 1.0, v51
	v_ldexp_f32 v50, v55, v50
	v_add_f32_e32 v55, 1.0, v54
	v_add_f32_e32 v57, -1.0, v56
	v_sub_f32_e32 v55, v51, v55
	v_sub_f32_e32 v51, v51, v57
	v_add_f32_e32 v55, v50, v55
	v_add_f32_e32 v50, v50, v51
	v_add_f32_e32 v83, v56, v50
	v_rcp_f32_e32 v85, v83
	v_sub_f32_e32 v51, v56, v83
	v_add_f32_e32 v84, v50, v51
	v_add_f32_e32 v51, v54, v55
	v_mul_f32_e32 v87, v51, v85
	v_sub_f32_e32 v50, v54, v51
	v_mul_f32_e32 v54, v83, v87
	v_fma_f32 v56, v87, v83, -v54
	v_fmac_f32_e32 v56, v87, v84
	v_add_f32_e32 v86, v55, v50
	v_add_f32_e32 v50, v54, v56
	v_sub_f32_e32 v55, v51, v50
	v_pk_add_f32 v[80:81], v[50:51], v[54:55] neg_lo:[0,1] neg_hi:[0,1]
	v_mov_b32_e32 v57, v50
	v_pk_add_f32 v[50:51], v[80:81], v[56:57] neg_lo:[0,1] neg_hi:[0,1]
	v_cmp_neq_f32_e64 s[0:1], s2, v52
	v_add_f32_e32 v51, v86, v51
	v_add_f32_e32 v50, v50, v51
	v_add_f32_e32 v51, v55, v50
	v_mul_f32_e32 v86, v85, v51
	v_mul_f32_e32 v54, v83, v86
	v_fma_f32 v56, v86, v83, -v54
	v_fmac_f32_e32 v56, v86, v84
	v_sub_f32_e32 v55, v55, v51
	v_add_f32_e32 v83, v50, v55
	v_add_f32_e32 v50, v54, v56
	v_sub_f32_e32 v55, v51, v50
	v_pk_add_f32 v[80:81], v[50:51], v[54:55] neg_lo:[0,1] neg_hi:[0,1]
	v_mov_b32_e32 v57, v50
	v_pk_add_f32 v[50:51], v[80:81], v[56:57] neg_lo:[0,1] neg_hi:[0,1]
	s_nop 0
	v_add_f32_e32 v51, v83, v51
	v_add_f32_e32 v50, v50, v51
	v_add_f32_e32 v51, v87, v86
	v_add_f32_e32 v50, v55, v50
	v_sub_f32_e32 v54, v51, v87
	v_mul_f32_e32 v50, v85, v50
	v_sub_f32_e32 v54, v86, v54
	v_add_f32_e32 v54, v54, v50
	v_add_f32_e32 v56, v51, v54
	v_mul_f32_e32 v57, v56, v56
	v_fmamk_f32 v50, v57, 0x3e9b6dac, v206
	v_fmaak_f32 v179, v57, v50, 0x3f2aaada
	v_cvt_f32_i32_e32 v50, v82
	v_sub_f32_e32 v51, v56, v51
	v_sub_f32_e32 v51, v54, v51
	v_ldexp_f32 v80, v51, 1
	v_mul_f32_e32 v51, v56, v57
	v_ldexp_f32 v55, v56, 1
	v_pk_mul_f32 v[56:57], v[50:51], v[178:179]
	s_nop 0
	v_fma_f32 v54, v50, s69, -v56
	v_fmac_f32_e32 v54, 0xb102e308, v50
	v_pk_add_f32 v[50:51], v[56:57], v[54:55]
	s_nop 0
	v_sub_f32_e32 v55, v51, v55
	v_sub_f32_e32 v55, v57, v55
	v_add_f32_e32 v81, v80, v55
	v_mov_b32_e32 v80, v56
	v_pk_add_f32 v[56:57], v[50:51], v[56:57] neg_lo:[0,1] neg_hi:[0,1]
	v_pk_add_f32 v[82:83], v[50:51], v[80:81]
	v_mov_b32_e32 v55, v50
	v_mov_b32_e32 v57, v83
	v_pk_add_f32 v[84:85], v[54:55], v[56:57] neg_lo:[0,1] neg_hi:[0,1]
	v_pk_add_f32 v[54:55], v[54:55], v[56:57]
	v_mov_b32_e32 v80, v81
	v_pk_add_f32 v[56:57], v[54:55], v[50:51] op_sel:[1,0] op_sel_hi:[0,1] neg_lo:[0,1] neg_hi:[0,1]
	v_pk_add_f32 v[86:87], v[82:83], v[56:57] op_sel_hi:[1,0] neg_lo:[0,1] neg_hi:[0,1]
	v_mov_b32_e32 v82, v83
	v_mov_b32_e32 v83, v55
	v_pk_mov_b32 v[56:57], v[50:51], v[56:57] op_sel:[1,0]
	v_mov_b32_e32 v81, v50
	v_pk_add_f32 v[56:57], v[82:83], v[56:57] neg_lo:[0,1] neg_hi:[0,1]
	v_mov_b32_e32 v86, v84
	v_pk_add_f32 v[50:51], v[80:81], v[56:57] neg_lo:[0,1] neg_hi:[0,1]
	v_mov_b32_e32 v85, v55
	v_pk_add_f32 v[56:57], v[86:87], v[50:51]
	s_nop 0
	v_pk_add_f32 v[80:81], v[56:57], v[56:57] op_sel:[0,1] op_sel_hi:[1,0]
	s_nop 0
	v_pk_add_f32 v[54:55], v[54:55], v[80:81] op_sel:[1,0] op_sel_hi:[0,1]
	v_mov_b32_e32 v57, v54
	v_pk_add_f32 v[82:83], v[56:57], v[84:85] neg_lo:[0,1] neg_hi:[0,1]
	v_mov_b32_e32 v51, v80
	v_sub_f32_e32 v55, v56, v82
	v_pk_add_f32 v[50:51], v[50:51], v[82:83] neg_lo:[0,1] neg_hi:[0,1]
	v_sub_f32_e32 v55, v84, v55
	v_add_f32_e32 v50, v50, v55
	v_add_f32_e32 v50, v50, v51
	v_add_f32_e32 v50, v54, v50
	v_cndmask_b32_e64 v50, v208, v50, s[0:1]
	v_cmp_lt_f32_e64 s[0:1], |v52|, s66
	s_nop 1
	v_cndmask_b32_e64 v50, v50, v52, s[0:1]
	v_sub_f32_e32 v0, v0, v50
	v_lshl_add_u64 v[50:51], v[78:79], 0, v[58:59]
	v_lshlrev_b64 v[50:51], 14, v[50:51]
	v_lshl_add_u64 v[50:51], v[60:61], 0, v[50:51]
	global_store_dword v[50:51], v0, off
	s_or_b64 exec, exec, s[84:85]
	s_and_saveexec_b64 s[84:85], s[18:19]
	s_cbranch_execnz .LBB0_535
	s_branch .LBB0_536
;     __device__ __forceinline__ void operator()(const f32x4 (&acc)[2][2][4][2], const pg8::Unit& u, int wr, int wc, int fr, int fq) const {
;     ...
;         if (kind == 1 && pn == 28) {
;             if (wc == 0) {
; #pragma unroll
;                 for (int ai = 0; ai < 2; ++ai)
; #pragma unroll
;                     for (int m = 0; m < 4; ++m) { const int row = row0 + ai * 128 + m * 16;
; #pragma unroll
;                         for (int n = 0; n < 2; ++n)
; #pragma unroll
;                             for (int j = 0; j < 4; ++j) { const int col = 8 * fq + 4 * n + j;
;                                 if (col < 12) { const float xv = acc[ai][0][m][n][j] * rsqrtf(ssq[row] * (1.f / DM) + EPS) + bfp[col]; LS[((size_t)(row >> 12) * 12 + col) * SEQ + (row & (SEQ - 1))] = fminf(xv, 0.f) - log1pf(expf(-fabsf(xv))); } } }
.LBB0_598:
	global_load_dword v0, v[66:67], off offset:128
	s_waitcnt vmcnt(0) lgkmcnt(0)
	v_fmamk_f32 v0, v0, 0x3a000000, v205
	v_cmp_gt_f32_e64 s[0:1], s68, v0
	v_mul_f32_e32 v54, 0x4b800000, v0
	s_nop 0
	v_cndmask_b32_e64 v0, v0, v54, s[0:1]
	v_rsq_f32_e32 v0, v0
	s_nop 0
	v_mul_f32_e32 v54, 0x45800000, v0
	v_cndmask_b32_e64 v0, v0, v54, s[0:1]
	v_lshl_add_u64 v[54:55], v[68:69], 2, s[60:61]
	global_load_dword v54, v[54:55], off
	s_waitcnt vmcnt(0) lgkmcnt(0)
	v_fmac_f32_e32 v54, v46, v0
	v_mul_f32_e64 v46, |v54|, s88
	v_fma_f32 v55, |v54|, s88, -v46
	v_rndne_f32_e32 v56, v46
	v_fma_f32 v55, |v54|, s89, v55
	v_sub_f32_e32 v46, v46, v56
	v_add_f32_e32 v46, v46, v55
	v_exp_f32_e32 v46, v46
	v_cvt_i32_f32_e32 v55, v56
	v_cmp_ngt_f32_e64 s[0:1], |v54|, s70
	v_min_f32_e32 v0, 0, v54
	v_ldexp_f32 v46, v46, v55
	v_cndmask_b32_e64 v46, 0, v46, s[0:1]
	v_cmp_nlt_f32_e64 s[0:1], |v54|, s90
	s_nop 1
	v_cndmask_b32_e64 v46, v208, v46, s[0:1]
	v_add_f32_e32 v56, 1.0, v46
	v_add_f32_e32 v54, -1.0, v56
	v_sub_f32_e32 v55, v54, v56
	v_add_f32_e32 v55, 1.0, v55
	v_sub_f32_e32 v54, v46, v54
	v_add_f32_e32 v57, v54, v55
	v_frexp_mant_f32_e32 v54, v56
	v_cmp_gt_f32_e64 s[0:1], s3, v54
	v_cvt_f64_f32_e32 v[54:55], v56
	v_frexp_exp_i32_f64_e32 v54, v[54:55]
	v_subbrev_co_u32_e64 v80, s[0:1], 0, v54, s[0:1]
	v_sub_u32_e32 v54, 0, v80
	v_ldexp_f32 v55, v56, v54
	v_add_f32_e32 v56, -1.0, v55
	v_add_f32_e32 v60, 1.0, v55
	v_ldexp_f32 v54, v57, v54
	v_add_f32_e32 v57, 1.0, v56
	v_add_f32_e32 v61, -1.0, v60
	v_sub_f32_e32 v57, v55, v57
	v_sub_f32_e32 v55, v55, v61
	v_add_f32_e32 v57, v54, v57
	v_add_f32_e32 v54, v54, v55
	v_add_f32_e32 v81, v60, v54
	v_rcp_f32_e32 v83, v81
	v_sub_f32_e32 v55, v60, v81
	v_add_f32_e32 v82, v54, v55
	v_add_f32_e32 v55, v56, v57
	v_mul_f32_e32 v85, v55, v83
	v_sub_f32_e32 v54, v56, v55
	v_mul_f32_e32 v56, v81, v85
	v_fma_f32 v60, v85, v81, -v56
	v_fmac_f32_e32 v60, v85, v82
	v_add_f32_e32 v84, v57, v54
	v_add_f32_e32 v54, v56, v60
	v_sub_f32_e32 v57, v55, v54
	v_pk_add_f32 v[78:79], v[54:55], v[56:57] neg_lo:[0,1] neg_hi:[0,1]
	v_mov_b32_e32 v61, v54
	v_pk_add_f32 v[54:55], v[78:79], v[60:61] neg_lo:[0,1] neg_hi:[0,1]
	v_cmp_neq_f32_e64 s[0:1], s2, v46
	v_add_f32_e32 v55, v84, v55
	v_add_f32_e32 v54, v54, v55
	v_add_f32_e32 v55, v57, v54
	v_mul_f32_e32 v84, v83, v55
	v_mul_f32_e32 v56, v81, v84
	v_fma_f32 v60, v84, v81, -v56
	v_fmac_f32_e32 v60, v84, v82
	v_sub_f32_e32 v57, v57, v55
	v_add_f32_e32 v81, v54, v57
	v_add_f32_e32 v54, v56, v60
	v_sub_f32_e32 v57, v55, v54
	v_pk_add_f32 v[78:79], v[54:55], v[56:57] neg_lo:[0,1] neg_hi:[0,1]
	v_mov_b32_e32 v61, v54
	v_pk_add_f32 v[54:55], v[78:79], v[60:61] neg_lo:[0,1] neg_hi:[0,1]
	s_nop 0
	v_add_f32_e32 v55, v81, v55
	v_add_f32_e32 v54, v54, v55
	v_add_f32_e32 v55, v85, v84
	v_add_f32_e32 v54, v57, v54
	v_sub_f32_e32 v56, v55, v85
	v_mul_f32_e32 v54, v83, v54
	v_sub_f32_e32 v56, v84, v56
	v_add_f32_e32 v56, v56, v54
	v_add_f32_e32 v60, v55, v56
	v_mul_f32_e32 v61, v60, v60
	v_fmamk_f32 v54, v61, 0x3e9b6dac, v206
	v_fmaak_f32 v179, v61, v54, 0x3f2aaada
	v_cvt_f32_i32_e32 v54, v80
	v_sub_f32_e32 v55, v60, v55
	v_sub_f32_e32 v55, v56, v55
	v_ldexp_f32 v78, v55, 1
	v_mul_f32_e32 v55, v60, v61
	v_ldexp_f32 v57, v60, 1
	v_pk_mul_f32 v[60:61], v[54:55], v[178:179]
	s_nop 0
	v_fma_f32 v56, v54, s69, -v60
	v_fmac_f32_e32 v56, 0xb102e308, v54
	v_pk_add_f32 v[54:55], v[60:61], v[56:57]
	s_nop 0
	v_sub_f32_e32 v57, v55, v57
	v_sub_f32_e32 v57, v61, v57
	v_add_f32_e32 v79, v78, v57
	v_mov_b32_e32 v78, v60
	v_pk_add_f32 v[60:61], v[54:55], v[60:61] neg_lo:[0,1] neg_hi:[0,1]
	v_pk_add_f32 v[80:81], v[54:55], v[78:79]
	v_mov_b32_e32 v57, v54
	v_mov_b32_e32 v61, v81
	v_pk_add_f32 v[82:83], v[56:57], v[60:61] neg_lo:[0,1] neg_hi:[0,1]
	v_pk_add_f32 v[56:57], v[56:57], v[60:61]
	v_mov_b32_e32 v78, v79
	v_pk_add_f32 v[60:61], v[56:57], v[54:55] op_sel:[1,0] op_sel_hi:[0,1] neg_lo:[0,1] neg_hi:[0,1]
	v_pk_add_f32 v[84:85], v[80:81], v[60:61] op_sel_hi:[1,0] neg_lo:[0,1] neg_hi:[0,1]
	v_mov_b32_e32 v80, v81
	v_mov_b32_e32 v81, v57
	v_pk_mov_b32 v[60:61], v[54:55], v[60:61] op_sel:[1,0]
	v_mov_b32_e32 v79, v54
	v_pk_add_f32 v[60:61], v[80:81], v[60:61] neg_lo:[0,1] neg_hi:[0,1]
	v_mov_b32_e32 v84, v82
	v_pk_add_f32 v[54:55], v[78:79], v[60:61] neg_lo:[0,1] neg_hi:[0,1]
	v_mov_b32_e32 v83, v57
	v_pk_add_f32 v[60:61], v[84:85], v[54:55]
	s_nop 0
	v_pk_add_f32 v[78:79], v[60:61], v[60:61] op_sel:[0,1] op_sel_hi:[1,0]
	s_nop 0
	v_pk_add_f32 v[56:57], v[56:57], v[78:79] op_sel:[1,0] op_sel_hi:[0,1]
	v_mov_b32_e32 v61, v56
	v_pk_add_f32 v[80:81], v[60:61], v[82:83] neg_lo:[0,1] neg_hi:[0,1]
	v_mov_b32_e32 v55, v78
	v_sub_f32_e32 v57, v60, v80
	v_pk_add_f32 v[54:55], v[54:55], v[80:81] neg_lo:[0,1] neg_hi:[0,1]
	v_sub_f32_e32 v57, v82, v57
	v_add_f32_e32 v54, v54, v57
	v_add_f32_e32 v54, v54, v55
	v_add_f32_e32 v54, v56, v54
	v_cndmask_b32_e64 v54, v208, v54, s[0:1]
	v_cmp_lt_f32_e64 s[0:1], |v46|, s66
	s_nop 1
	v_cndmask_b32_e64 v46, v54, v46, s[0:1]
	v_lshl_add_u64 v[54:55], v[52:53], 0, v[68:69]
	v_lshlrev_b64 v[54:55], 14, v[54:55]
	v_sub_f32_e32 v0, v0, v46
	v_lshl_add_u64 v[54:55], v[50:51], 0, v[54:55]
	global_store_dword v[54:55], v0, off
	s_or_b64 exec, exec, s[84:85]
	s_and_saveexec_b64 s[84:85], s[6:7]
	s_cbranch_execz .LBB0_538
;     __device__ __forceinline__ void operator()(const f32x4 (&acc)[2][2][4][2], const pg8::Unit& u, int wr, int wc, int fr, int fq) const {
;     ...
;         if (kind == 1 && pn == 28) {
;             if (wc == 0) {
; #pragma unroll
;                 for (int ai = 0; ai < 2; ++ai)
; #pragma unroll
;                     for (int m = 0; m < 4; ++m) { const int row = row0 + ai * 128 + m * 16;
; #pragma unroll
;                         for (int n = 0; n < 2; ++n)
; #pragma unroll
;                             for (int j = 0; j < 4; ++j) { const int col = 8 * fq + 4 * n + j;
;                                 if (col < 12) { const float xv = acc[ai][0][m][n][j] * rsqrtf(ssq[row] * (1.f / DM) + EPS) + bfp[col]; LS[((size_t)(row >> 12) * 12 + col) * SEQ + (row & (SEQ - 1))] = fminf(xv, 0.f) - log1pf(expf(-fabsf(xv))); } } }
.LBB0_599:
	global_load_dword v0, v[66:67], off offset:128
	v_lshl_add_u64 v[54:55], v[70:71], 2, s[60:61]
	s_waitcnt vmcnt(0) lgkmcnt(0)
	v_fmamk_f32 v0, v0, 0x3a000000, v205
	v_cmp_gt_f32_e64 s[0:1], s68, v0
	v_mul_f32_e32 v46, 0x4b800000, v0
	s_nop 0
	v_cndmask_b32_e64 v0, v0, v46, s[0:1]
	v_rsq_f32_e32 v0, v0
	s_nop 0
	v_mul_f32_e32 v46, 0x45800000, v0
	v_cndmask_b32_e64 v0, v0, v46, s[0:1]
	global_load_dword v46, v[54:55], off
	s_waitcnt vmcnt(0) lgkmcnt(0)
	v_fmac_f32_e32 v46, v47, v0
	v_mul_f32_e64 v47, |v46|, s88
	v_fma_f32 v54, |v46|, s88, -v47
	v_rndne_f32_e32 v55, v47
	v_fma_f32 v54, |v46|, s89, v54
	v_sub_f32_e32 v47, v47, v55
	v_add_f32_e32 v47, v47, v54
	v_exp_f32_e32 v47, v47
	v_cvt_i32_f32_e32 v54, v55
	v_cmp_ngt_f32_e64 s[0:1], |v46|, s70
	v_min_f32_e32 v0, 0, v46
	v_ldexp_f32 v47, v47, v54
	v_cndmask_b32_e64 v47, 0, v47, s[0:1]
	v_cmp_nlt_f32_e64 s[0:1], |v46|, s90
	s_nop 1
	v_cndmask_b32_e64 v84, v208, v47, s[0:1]
	v_add_f32_e32 v54, 1.0, v84
	v_add_f32_e32 v46, -1.0, v54
	v_sub_f32_e32 v47, v46, v54
	v_add_f32_e32 v47, 1.0, v47
	v_sub_f32_e32 v46, v84, v46
	v_add_f32_e32 v55, v46, v47
	v_frexp_mant_f32_e32 v46, v54
	v_cmp_gt_f32_e64 s[0:1], s3, v46
	v_cvt_f64_f32_e32 v[46:47], v54
	v_frexp_exp_i32_f64_e32 v46, v[46:47]
	v_subbrev_co_u32_e64 v78, s[0:1], 0, v46, s[0:1]
	v_sub_u32_e32 v46, 0, v78
	v_ldexp_f32 v47, v54, v46
	v_add_f32_e32 v54, -1.0, v47
	v_add_f32_e32 v56, 1.0, v47
	v_ldexp_f32 v46, v55, v46
	v_add_f32_e32 v55, 1.0, v54
	v_add_f32_e32 v57, -1.0, v56
	v_sub_f32_e32 v55, v47, v55
	v_sub_f32_e32 v47, v47, v57
	v_add_f32_e32 v55, v46, v55
	v_add_f32_e32 v46, v46, v47
	v_add_f32_e32 v79, v56, v46
	v_rcp_f32_e32 v81, v79
	v_sub_f32_e32 v47, v56, v79
	v_add_f32_e32 v80, v46, v47
	v_add_f32_e32 v47, v54, v55
	v_mul_f32_e32 v83, v47, v81
	v_sub_f32_e32 v46, v54, v47
	v_mul_f32_e32 v54, v79, v83
	v_fma_f32 v56, v83, v79, -v54
	v_fmac_f32_e32 v56, v83, v80
	v_add_f32_e32 v82, v55, v46
	v_add_f32_e32 v46, v54, v56
	v_sub_f32_e32 v55, v47, v46
	v_pk_add_f32 v[60:61], v[46:47], v[54:55] neg_lo:[0,1] neg_hi:[0,1]
	v_mov_b32_e32 v57, v46
	v_pk_add_f32 v[46:47], v[60:61], v[56:57] neg_lo:[0,1] neg_hi:[0,1]
	v_cmp_neq_f32_e64 s[0:1], s2, v84
	v_add_f32_e32 v47, v82, v47
	v_add_f32_e32 v46, v46, v47
	v_add_f32_e32 v47, v55, v46
	v_mul_f32_e32 v82, v81, v47
	v_mul_f32_e32 v54, v79, v82
	v_fma_f32 v56, v82, v79, -v54
	v_fmac_f32_e32 v56, v82, v80
	v_sub_f32_e32 v55, v55, v47
	v_add_f32_e32 v79, v46, v55
	v_add_f32_e32 v46, v54, v56
	v_sub_f32_e32 v55, v47, v46
	v_pk_add_f32 v[60:61], v[46:47], v[54:55] neg_lo:[0,1] neg_hi:[0,1]
	v_mov_b32_e32 v57, v46
	v_pk_add_f32 v[46:47], v[60:61], v[56:57] neg_lo:[0,1] neg_hi:[0,1]
	s_nop 0
	v_add_f32_e32 v47, v79, v47
	v_add_f32_e32 v46, v46, v47
	v_add_f32_e32 v47, v83, v82
	v_add_f32_e32 v46, v55, v46
	v_sub_f32_e32 v54, v47, v83
	v_mul_f32_e32 v46, v81, v46
	v_sub_f32_e32 v54, v82, v54
	v_add_f32_e32 v54, v54, v46
	v_add_f32_e32 v56, v47, v54
	v_mul_f32_e32 v57, v56, v56
	v_fmamk_f32 v46, v57, 0x3e9b6dac, v206
	v_fmaak_f32 v179, v57, v46, 0x3f2aaada
	v_cvt_f32_i32_e32 v46, v78
	v_sub_f32_e32 v47, v56, v47
	v_sub_f32_e32 v47, v54, v47
	v_ldexp_f32 v60, v47, 1
	v_mul_f32_e32 v47, v56, v57
	v_ldexp_f32 v55, v56, 1
	v_pk_mul_f32 v[56:57], v[46:47], v[178:179]
	s_nop 0
	v_fma_f32 v54, v46, s69, -v56
	v_fmac_f32_e32 v54, 0xb102e308, v46
	v_pk_add_f32 v[46:47], v[56:57], v[54:55]
	s_nop 0
	v_sub_f32_e32 v55, v47, v55
	v_sub_f32_e32 v55, v57, v55
	v_add_f32_e32 v61, v60, v55
	v_mov_b32_e32 v60, v56
	v_pk_add_f32 v[56:57], v[46:47], v[56:57] neg_lo:[0,1] neg_hi:[0,1]
	v_pk_add_f32 v[78:79], v[46:47], v[60:61]
	v_mov_b32_e32 v55, v46
	v_mov_b32_e32 v57, v79
	v_pk_add_f32 v[80:81], v[54:55], v[56:57] neg_lo:[0,1] neg_hi:[0,1]
	v_pk_add_f32 v[54:55], v[54:55], v[56:57]
	v_mov_b32_e32 v60, v61
	v_pk_add_f32 v[56:57], v[54:55], v[46:47] op_sel:[1,0] op_sel_hi:[0,1] neg_lo:[0,1] neg_hi:[0,1]
	v_pk_add_f32 v[82:83], v[78:79], v[56:57] op_sel_hi:[1,0] neg_lo:[0,1] neg_hi:[0,1]
	v_mov_b32_e32 v78, v79
	v_mov_b32_e32 v79, v55
	v_pk_mov_b32 v[56:57], v[46:47], v[56:57] op_sel:[1,0]
	v_mov_b32_e32 v61, v46
	v_pk_add_f32 v[56:57], v[78:79], v[56:57] neg_lo:[0,1] neg_hi:[0,1]
	v_mov_b32_e32 v82, v80
	v_pk_add_f32 v[46:47], v[60:61], v[56:57] neg_lo:[0,1] neg_hi:[0,1]
	v_mov_b32_e32 v81, v55
	v_pk_add_f32 v[56:57], v[82:83], v[46:47]
	s_nop 0
	v_pk_add_f32 v[60:61], v[56:57], v[56:57] op_sel:[0,1] op_sel_hi:[1,0]
	s_nop 0
	v_pk_add_f32 v[54:55], v[54:55], v[60:61] op_sel:[1,0] op_sel_hi:[0,1]
	v_mov_b32_e32 v57, v54
	v_pk_add_f32 v[78:79], v[56:57], v[80:81] neg_lo:[0,1] neg_hi:[0,1]
	v_mov_b32_e32 v47, v60
	v_sub_f32_e32 v55, v56, v78
	v_pk_add_f32 v[46:47], v[46:47], v[78:79] neg_lo:[0,1] neg_hi:[0,1]
	v_sub_f32_e32 v55, v80, v55
	v_add_f32_e32 v46, v46, v55
	v_add_f32_e32 v46, v46, v47
	v_add_f32_e32 v46, v54, v46
	v_cndmask_b32_e64 v46, v208, v46, s[0:1]
	v_cmp_lt_f32_e64 s[0:1], |v84|, s66
	s_nop 1
	v_cndmask_b32_e64 v46, v46, v84, s[0:1]
	v_sub_f32_e32 v0, v0, v46
	v_lshl_add_u64 v[46:47], v[52:53], 0, v[70:71]
	v_lshlrev_b64 v[46:47], 14, v[46:47]
	v_lshl_add_u64 v[46:47], v[50:51], 0, v[46:47]
	global_store_dword v[46:47], v0, off
	s_or_b64 exec, exec, s[84:85]
	s_and_saveexec_b64 s[84:85], s[8:9]
	s_cbranch_execz .LBB0_539
;     __device__ __forceinline__ void operator()(const f32x4 (&acc)[2][2][4][2], const pg8::Unit& u, int wr, int wc, int fr, int fq) const {
;     ...
;         if (kind == 1 && pn == 28) {
;             if (wc == 0) {
; #pragma unroll
;                 for (int ai = 0; ai < 2; ++ai)
; #pragma unroll
;                     for (int m = 0; m < 4; ++m) { const int row = row0 + ai * 128 + m * 16;
; #pragma unroll
;                         for (int n = 0; n < 2; ++n)
; #pragma unroll
;                             for (int j = 0; j < 4; ++j) { const int col = 8 * fq + 4 * n + j;
;                                 if (col < 12) { const float xv = acc[ai][0][m][n][j] * rsqrtf(ssq[row] * (1.f / DM) + EPS) + bfp[col]; LS[((size_t)(row >> 12) * 12 + col) * SEQ + (row & (SEQ - 1))] = fminf(xv, 0.f) - log1pf(expf(-fabsf(xv))); } } }
.LBB0_600:
	global_load_dword v0, v[66:67], off offset:128
	s_waitcnt vmcnt(0) lgkmcnt(0)
	v_fmamk_f32 v0, v0, 0x3a000000, v205
	v_cmp_gt_f32_e64 s[0:1], s68, v0
	v_mul_f32_e32 v46, 0x4b800000, v0
	s_nop 0
	v_cndmask_b32_e64 v0, v0, v46, s[0:1]
	v_rsq_f32_e32 v0, v0
	s_nop 0
	v_mul_f32_e32 v46, 0x45800000, v0
	v_cndmask_b32_e64 v0, v0, v46, s[0:1]
	v_lshl_add_u64 v[46:47], v[62:63], 2, s[60:61]
	global_load_dword v46, v[46:47], off
	s_waitcnt vmcnt(0) lgkmcnt(0)
	v_fmac_f32_e32 v46, v48, v0
	v_mul_f32_e64 v47, |v46|, s88
	v_fma_f32 v48, |v46|, s88, -v47
	v_rndne_f32_e32 v54, v47
	v_fma_f32 v48, |v46|, s89, v48
	v_sub_f32_e32 v47, v47, v54
	v_add_f32_e32 v47, v47, v48
	v_exp_f32_e32 v47, v47
	v_cvt_i32_f32_e32 v48, v54
	v_cmp_ngt_f32_e64 s[0:1], |v46|, s70
	v_min_f32_e32 v0, 0, v46
	v_ldexp_f32 v47, v47, v48
	v_cndmask_b32_e64 v47, 0, v47, s[0:1]
	v_cmp_nlt_f32_e64 s[0:1], |v46|, s90
	s_nop 1
	v_cndmask_b32_e64 v48, v208, v47, s[0:1]
	v_add_f32_e32 v54, 1.0, v48
	v_add_f32_e32 v46, -1.0, v54
	v_sub_f32_e32 v47, v46, v54
	v_add_f32_e32 v47, 1.0, v47
	v_sub_f32_e32 v46, v48, v46
	v_add_f32_e32 v55, v46, v47
	v_frexp_mant_f32_e32 v46, v54
	v_cmp_gt_f32_e64 s[0:1], s3, v46
	v_cvt_f64_f32_e32 v[46:47], v54
	v_frexp_exp_i32_f64_e32 v46, v[46:47]
	v_subbrev_co_u32_e64 v78, s[0:1], 0, v46, s[0:1]
	v_sub_u32_e32 v46, 0, v78
	v_ldexp_f32 v47, v54, v46
	v_add_f32_e32 v54, -1.0, v47
	v_add_f32_e32 v56, 1.0, v47
	v_ldexp_f32 v46, v55, v46
	v_add_f32_e32 v55, 1.0, v54
	v_add_f32_e32 v57, -1.0, v56
	v_sub_f32_e32 v55, v47, v55
	v_sub_f32_e32 v47, v47, v57
	v_add_f32_e32 v55, v46, v55
	v_add_f32_e32 v46, v46, v47
	v_add_f32_e32 v79, v56, v46
	v_rcp_f32_e32 v81, v79
	v_sub_f32_e32 v47, v56, v79
	v_add_f32_e32 v80, v46, v47
	v_add_f32_e32 v47, v54, v55
	v_mul_f32_e32 v83, v47, v81
	v_sub_f32_e32 v46, v54, v47
	v_mul_f32_e32 v54, v79, v83
	v_fma_f32 v56, v83, v79, -v54
	v_fmac_f32_e32 v56, v83, v80
	v_add_f32_e32 v82, v55, v46
	v_add_f32_e32 v46, v54, v56
	v_sub_f32_e32 v55, v47, v46
	v_pk_add_f32 v[60:61], v[46:47], v[54:55] neg_lo:[0,1] neg_hi:[0,1]
	v_mov_b32_e32 v57, v46
	v_pk_add_f32 v[46:47], v[60:61], v[56:57] neg_lo:[0,1] neg_hi:[0,1]
	v_cmp_neq_f32_e64 s[0:1], s2, v48
	v_add_f32_e32 v47, v82, v47
	v_add_f32_e32 v46, v46, v47
	v_add_f32_e32 v47, v55, v46
	v_mul_f32_e32 v82, v81, v47
	v_mul_f32_e32 v54, v79, v82
	v_fma_f32 v56, v82, v79, -v54
	v_fmac_f32_e32 v56, v82, v80
	v_sub_f32_e32 v55, v55, v47
	v_add_f32_e32 v79, v46, v55
	v_add_f32_e32 v46, v54, v56
	v_sub_f32_e32 v55, v47, v46
	v_pk_add_f32 v[60:61], v[46:47], v[54:55] neg_lo:[0,1] neg_hi:[0,1]
	v_mov_b32_e32 v57, v46
	v_pk_add_f32 v[46:47], v[60:61], v[56:57] neg_lo:[0,1] neg_hi:[0,1]
	s_nop 0
	v_add_f32_e32 v47, v79, v47
	v_add_f32_e32 v46, v46, v47
	v_add_f32_e32 v47, v83, v82
	v_add_f32_e32 v46, v55, v46
	v_sub_f32_e32 v54, v47, v83
	v_mul_f32_e32 v46, v81, v46
	v_sub_f32_e32 v54, v82, v54
	v_add_f32_e32 v54, v54, v46
	v_add_f32_e32 v56, v47, v54
	v_mul_f32_e32 v57, v56, v56
	v_fmamk_f32 v46, v57, 0x3e9b6dac, v206
	v_fmaak_f32 v179, v57, v46, 0x3f2aaada
	v_cvt_f32_i32_e32 v46, v78
	v_sub_f32_e32 v47, v56, v47
	v_sub_f32_e32 v47, v54, v47
	v_ldexp_f32 v60, v47, 1
	v_mul_f32_e32 v47, v56, v57
	v_ldexp_f32 v55, v56, 1
	v_pk_mul_f32 v[56:57], v[46:47], v[178:179]
	s_nop 0
	v_fma_f32 v54, v46, s69, -v56
	v_fmac_f32_e32 v54, 0xb102e308, v46
	v_pk_add_f32 v[46:47], v[56:57], v[54:55]
	s_nop 0
	v_sub_f32_e32 v55, v47, v55
	v_sub_f32_e32 v55, v57, v55
	v_add_f32_e32 v61, v60, v55
	v_mov_b32_e32 v60, v56
	v_pk_add_f32 v[56:57], v[46:47], v[56:57] neg_lo:[0,1] neg_hi:[0,1]
	v_pk_add_f32 v[78:79], v[46:47], v[60:61]
	v_mov_b32_e32 v55, v46
	v_mov_b32_e32 v57, v79
	v_pk_add_f32 v[80:81], v[54:55], v[56:57] neg_lo:[0,1] neg_hi:[0,1]
	v_pk_add_f32 v[54:55], v[54:55], v[56:57]
	v_mov_b32_e32 v60, v61
	v_pk_add_f32 v[56:57], v[54:55], v[46:47] op_sel:[1,0] op_sel_hi:[0,1] neg_lo:[0,1] neg_hi:[0,1]
	v_pk_add_f32 v[82:83], v[78:79], v[56:57] op_sel_hi:[1,0] neg_lo:[0,1] neg_hi:[0,1]
	v_mov_b32_e32 v78, v79
	v_mov_b32_e32 v79, v55
	v_pk_mov_b32 v[56:57], v[46:47], v[56:57] op_sel:[1,0]
	v_mov_b32_e32 v61, v46
	v_pk_add_f32 v[56:57], v[78:79], v[56:57] neg_lo:[0,1] neg_hi:[0,1]
	v_mov_b32_e32 v82, v80
	v_pk_add_f32 v[46:47], v[60:61], v[56:57] neg_lo:[0,1] neg_hi:[0,1]
	v_mov_b32_e32 v81, v55
	v_pk_add_f32 v[56:57], v[82:83], v[46:47]
	s_nop 0
	v_pk_add_f32 v[60:61], v[56:57], v[56:57] op_sel:[0,1] op_sel_hi:[1,0]
	s_nop 0
	v_pk_add_f32 v[54:55], v[54:55], v[60:61] op_sel:[1,0] op_sel_hi:[0,1]
	v_mov_b32_e32 v57, v54
	v_pk_add_f32 v[78:79], v[56:57], v[80:81] neg_lo:[0,1] neg_hi:[0,1]
	v_mov_b32_e32 v47, v60
	v_sub_f32_e32 v55, v56, v78
	v_pk_add_f32 v[46:47], v[46:47], v[78:79] neg_lo:[0,1] neg_hi:[0,1]
	v_sub_f32_e32 v55, v80, v55
	v_add_f32_e32 v46, v46, v55
	v_add_f32_e32 v46, v46, v47
	v_add_f32_e32 v46, v54, v46
	v_cndmask_b32_e64 v46, v208, v46, s[0:1]
	v_cmp_lt_f32_e64 s[0:1], |v48|, s66
	s_nop 1
	v_cndmask_b32_e64 v46, v46, v48, s[0:1]
	v_sub_f32_e32 v0, v0, v46
	v_lshl_add_u64 v[46:47], v[52:53], 0, v[62:63]
	v_lshlrev_b64 v[46:47], 14, v[46:47]
	v_lshl_add_u64 v[46:47], v[50:51], 0, v[46:47]
	global_store_dword v[46:47], v0, off
	s_or_b64 exec, exec, s[84:85]
	s_and_saveexec_b64 s[84:85], s[10:11]
	s_cbranch_execz .LBB0_540
;     __device__ __forceinline__ void operator()(const f32x4 (&acc)[2][2][4][2], const pg8::Unit& u, int wr, int wc, int fr, int fq) const {
;     ...
;         if (kind == 1 && pn == 28) {
;             if (wc == 0) {
; #pragma unroll
;                 for (int ai = 0; ai < 2; ++ai)
; #pragma unroll
;                     for (int m = 0; m < 4; ++m) { const int row = row0 + ai * 128 + m * 16;
; #pragma unroll
;                         for (int n = 0; n < 2; ++n)
; #pragma unroll
;                             for (int j = 0; j < 4; ++j) { const int col = 8 * fq + 4 * n + j;
;                                 if (col < 12) { const float xv = acc[ai][0][m][n][j] * rsqrtf(ssq[row] * (1.f / DM) + EPS) + bfp[col]; LS[((size_t)(row >> 12) * 12 + col) * SEQ + (row & (SEQ - 1))] = fminf(xv, 0.f) - log1pf(expf(-fabsf(xv))); } } }
.LBB0_601:
	global_load_dword v0, v[66:67], off offset:128
	s_waitcnt vmcnt(0) lgkmcnt(0)
	v_fmamk_f32 v0, v0, 0x3a000000, v205
	v_cmp_gt_f32_e64 s[0:1], s68, v0
	v_mul_f32_e32 v46, 0x4b800000, v0
	s_nop 0
	v_cndmask_b32_e64 v0, v0, v46, s[0:1]
	v_rsq_f32_e32 v0, v0
	s_nop 0
	v_mul_f32_e32 v46, 0x45800000, v0
	v_cndmask_b32_e64 v0, v0, v46, s[0:1]
	v_lshl_add_u64 v[46:47], v[72:73], 2, s[60:61]
	global_load_dword v46, v[46:47], off
	s_waitcnt vmcnt(0) lgkmcnt(0)
	v_fmac_f32_e32 v46, v49, v0
	v_mul_f32_e64 v47, |v46|, s88
	v_fma_f32 v48, |v46|, s88, -v47
	v_rndne_f32_e32 v49, v47
	v_fma_f32 v48, |v46|, s89, v48
	v_sub_f32_e32 v47, v47, v49
	v_add_f32_e32 v47, v47, v48
	v_exp_f32_e32 v47, v47
	v_cvt_i32_f32_e32 v48, v49
	v_cmp_ngt_f32_e64 s[0:1], |v46|, s70
	v_min_f32_e32 v0, 0, v46
	v_ldexp_f32 v47, v47, v48
	v_cndmask_b32_e64 v47, 0, v47, s[0:1]
	v_cmp_nlt_f32_e64 s[0:1], |v46|, s90
	s_nop 1
	v_cndmask_b32_e64 v82, v208, v47, s[0:1]
	v_add_f32_e32 v48, 1.0, v82
	v_add_f32_e32 v46, -1.0, v48
	v_sub_f32_e32 v47, v46, v48
	v_add_f32_e32 v47, 1.0, v47
	v_sub_f32_e32 v46, v82, v46
	v_add_f32_e32 v49, v46, v47
	v_frexp_mant_f32_e32 v46, v48
	v_cmp_gt_f32_e64 s[0:1], s3, v46
	v_cvt_f64_f32_e32 v[46:47], v48
	v_frexp_exp_i32_f64_e32 v46, v[46:47]
	v_subbrev_co_u32_e64 v60, s[0:1], 0, v46, s[0:1]
	v_sub_u32_e32 v46, 0, v60
	v_ldexp_f32 v47, v48, v46
	v_add_f32_e32 v48, -1.0, v47
	v_add_f32_e32 v54, 1.0, v47
	v_ldexp_f32 v46, v49, v46
	v_add_f32_e32 v49, 1.0, v48
	v_add_f32_e32 v55, -1.0, v54
	v_sub_f32_e32 v49, v47, v49
	v_sub_f32_e32 v47, v47, v55
	v_add_f32_e32 v49, v46, v49
	v_add_f32_e32 v46, v46, v47
	v_add_f32_e32 v61, v54, v46
	v_rcp_f32_e32 v79, v61
	v_sub_f32_e32 v47, v54, v61
	v_add_f32_e32 v78, v46, v47
	v_add_f32_e32 v47, v48, v49
	v_mul_f32_e32 v81, v47, v79
	v_sub_f32_e32 v46, v48, v47
	v_mul_f32_e32 v48, v61, v81
	v_fma_f32 v54, v81, v61, -v48
	v_fmac_f32_e32 v54, v81, v78
	v_add_f32_e32 v80, v49, v46
	v_add_f32_e32 v46, v48, v54
	v_sub_f32_e32 v49, v47, v46
	v_pk_add_f32 v[56:57], v[46:47], v[48:49] neg_lo:[0,1] neg_hi:[0,1]
	v_mov_b32_e32 v55, v46
	v_pk_add_f32 v[46:47], v[56:57], v[54:55] neg_lo:[0,1] neg_hi:[0,1]
	v_cmp_neq_f32_e64 s[0:1], s2, v82
	v_add_f32_e32 v47, v80, v47
	v_add_f32_e32 v46, v46, v47
	v_add_f32_e32 v47, v49, v46
	v_mul_f32_e32 v80, v79, v47
	v_mul_f32_e32 v48, v61, v80
	v_fma_f32 v54, v80, v61, -v48
	v_fmac_f32_e32 v54, v80, v78
	v_sub_f32_e32 v49, v49, v47
	v_add_f32_e32 v61, v46, v49
	v_add_f32_e32 v46, v48, v54
	v_sub_f32_e32 v49, v47, v46
	v_pk_add_f32 v[56:57], v[46:47], v[48:49] neg_lo:[0,1] neg_hi:[0,1]
	v_mov_b32_e32 v55, v46
	v_pk_add_f32 v[46:47], v[56:57], v[54:55] neg_lo:[0,1] neg_hi:[0,1]
	s_nop 0
	v_add_f32_e32 v47, v61, v47
	v_add_f32_e32 v46, v46, v47
	v_add_f32_e32 v47, v81, v80
	v_add_f32_e32 v46, v49, v46
	v_sub_f32_e32 v48, v47, v81
	v_mul_f32_e32 v46, v79, v46
	v_sub_f32_e32 v48, v80, v48
	v_add_f32_e32 v48, v48, v46
	v_add_f32_e32 v54, v47, v48
	v_mul_f32_e32 v55, v54, v54
	v_fmamk_f32 v46, v55, 0x3e9b6dac, v206
	v_fmaak_f32 v179, v55, v46, 0x3f2aaada
	v_cvt_f32_i32_e32 v46, v60
	v_sub_f32_e32 v47, v54, v47
	v_sub_f32_e32 v47, v48, v47
	v_ldexp_f32 v56, v47, 1
	v_mul_f32_e32 v47, v54, v55
	v_ldexp_f32 v49, v54, 1
	v_pk_mul_f32 v[54:55], v[46:47], v[178:179]
	s_nop 0
	v_fma_f32 v48, v46, s69, -v54
	v_fmac_f32_e32 v48, 0xb102e308, v46
	v_pk_add_f32 v[46:47], v[54:55], v[48:49]
	s_nop 0
	v_sub_f32_e32 v49, v47, v49
	v_sub_f32_e32 v49, v55, v49
	v_add_f32_e32 v57, v56, v49
	v_mov_b32_e32 v56, v54
	v_pk_add_f32 v[54:55], v[46:47], v[54:55] neg_lo:[0,1] neg_hi:[0,1]
	v_pk_add_f32 v[60:61], v[46:47], v[56:57]
	v_mov_b32_e32 v49, v46
	v_mov_b32_e32 v55, v61
	v_pk_add_f32 v[78:79], v[48:49], v[54:55] neg_lo:[0,1] neg_hi:[0,1]
	v_pk_add_f32 v[48:49], v[48:49], v[54:55]
	v_mov_b32_e32 v56, v57
	v_pk_add_f32 v[54:55], v[48:49], v[46:47] op_sel:[1,0] op_sel_hi:[0,1] neg_lo:[0,1] neg_hi:[0,1]
	v_pk_add_f32 v[80:81], v[60:61], v[54:55] op_sel_hi:[1,0] neg_lo:[0,1] neg_hi:[0,1]
	v_mov_b32_e32 v60, v61
	v_mov_b32_e32 v61, v49
	v_pk_mov_b32 v[54:55], v[46:47], v[54:55] op_sel:[1,0]
	v_mov_b32_e32 v57, v46
	v_pk_add_f32 v[54:55], v[60:61], v[54:55] neg_lo:[0,1] neg_hi:[0,1]
	v_mov_b32_e32 v80, v78
	v_pk_add_f32 v[46:47], v[56:57], v[54:55] neg_lo:[0,1] neg_hi:[0,1]
	v_mov_b32_e32 v79, v49
	v_pk_add_f32 v[54:55], v[80:81], v[46:47]
	s_nop 0
	v_pk_add_f32 v[56:57], v[54:55], v[54:55] op_sel:[0,1] op_sel_hi:[1,0]
	s_nop 0
	v_pk_add_f32 v[48:49], v[48:49], v[56:57] op_sel:[1,0] op_sel_hi:[0,1]
	v_mov_b32_e32 v55, v48
	v_pk_add_f32 v[60:61], v[54:55], v[78:79] neg_lo:[0,1] neg_hi:[0,1]
	v_mov_b32_e32 v47, v56
	v_sub_f32_e32 v49, v54, v60
	v_pk_add_f32 v[46:47], v[46:47], v[60:61] neg_lo:[0,1] neg_hi:[0,1]
	v_sub_f32_e32 v49, v78, v49
	v_add_f32_e32 v46, v46, v49
	v_add_f32_e32 v46, v46, v47
	v_add_f32_e32 v46, v48, v46
	v_cndmask_b32_e64 v46, v208, v46, s[0:1]
	v_cmp_lt_f32_e64 s[0:1], |v82|, s66
	s_nop 1
	v_cndmask_b32_e64 v46, v46, v82, s[0:1]
	v_sub_f32_e32 v0, v0, v46
	v_lshl_add_u64 v[46:47], v[52:53], 0, v[72:73]
	v_lshlrev_b64 v[46:47], 14, v[46:47]
	v_lshl_add_u64 v[46:47], v[50:51], 0, v[46:47]
	global_store_dword v[46:47], v0, off
	s_or_b64 exec, exec, s[84:85]
	s_and_saveexec_b64 s[84:85], s[12:13]
	s_cbranch_execz .LBB0_541
;     __device__ __forceinline__ void operator()(const f32x4 (&acc)[2][2][4][2], const pg8::Unit& u, int wr, int wc, int fr, int fq) const {
;     ...
;         if (kind == 1 && pn == 28) {
;             if (wc == 0) {
; #pragma unroll
;                 for (int ai = 0; ai < 2; ++ai)
; #pragma unroll
;                     for (int m = 0; m < 4; ++m) { const int row = row0 + ai * 128 + m * 16;
; #pragma unroll
;                         for (int n = 0; n < 2; ++n)
; #pragma unroll
;                             for (int j = 0; j < 4; ++j) { const int col = 8 * fq + 4 * n + j;
;                                 if (col < 12) { const float xv = acc[ai][0][m][n][j] * rsqrtf(ssq[row] * (1.f / DM) + EPS) + bfp[col]; LS[((size_t)(row >> 12) * 12 + col) * SEQ + (row & (SEQ - 1))] = fminf(xv, 0.f) - log1pf(expf(-fabsf(xv))); } } }
.LBB0_602:
	global_load_dword v0, v[66:67], off offset:128
	s_waitcnt vmcnt(0) lgkmcnt(0)
	v_fmamk_f32 v0, v0, 0x3a000000, v205
	v_cmp_gt_f32_e64 s[0:1], s68, v0
	v_mul_f32_e32 v46, 0x4b800000, v0
	s_nop 0
	v_cndmask_b32_e64 v0, v0, v46, s[0:1]
	v_rsq_f32_e32 v0, v0
	s_nop 0
	v_mul_f32_e32 v46, 0x45800000, v0
	v_cndmask_b32_e64 v0, v0, v46, s[0:1]
	v_lshl_add_u64 v[46:47], v[64:65], 2, s[60:61]
	global_load_dword v46, v[46:47], off
	s_waitcnt vmcnt(0) lgkmcnt(0)
	v_fmac_f32_e32 v46, v42, v0
	v_mul_f32_e64 v42, |v46|, s88
	v_fma_f32 v47, |v46|, s88, -v42
	v_rndne_f32_e32 v48, v42
	v_fma_f32 v47, |v46|, s89, v47
	v_sub_f32_e32 v42, v42, v48
	v_add_f32_e32 v42, v42, v47
	v_exp_f32_e32 v42, v42
	v_cvt_i32_f32_e32 v47, v48
	v_cmp_ngt_f32_e64 s[0:1], |v46|, s70
	v_min_f32_e32 v0, 0, v46
	v_ldexp_f32 v42, v42, v47
	v_cndmask_b32_e64 v42, 0, v42, s[0:1]
	v_cmp_nlt_f32_e64 s[0:1], |v46|, s90
	s_nop 1
	v_cndmask_b32_e64 v42, v208, v42, s[0:1]
	v_add_f32_e32 v48, 1.0, v42
	v_add_f32_e32 v46, -1.0, v48
	v_sub_f32_e32 v47, v46, v48
	v_add_f32_e32 v47, 1.0, v47
	v_sub_f32_e32 v46, v42, v46
	v_add_f32_e32 v49, v46, v47
	v_frexp_mant_f32_e32 v46, v48
	v_cmp_gt_f32_e64 s[0:1], s3, v46
	v_cvt_f64_f32_e32 v[46:47], v48
	v_frexp_exp_i32_f64_e32 v46, v[46:47]
	v_subbrev_co_u32_e64 v60, s[0:1], 0, v46, s[0:1]
	v_sub_u32_e32 v46, 0, v60
	v_ldexp_f32 v47, v48, v46
	v_add_f32_e32 v48, -1.0, v47
	v_add_f32_e32 v54, 1.0, v47
	v_ldexp_f32 v46, v49, v46
	v_add_f32_e32 v49, 1.0, v48
	v_add_f32_e32 v55, -1.0, v54
	v_sub_f32_e32 v49, v47, v49
	v_sub_f32_e32 v47, v47, v55
	v_add_f32_e32 v49, v46, v49
	v_add_f32_e32 v46, v46, v47
	v_add_f32_e32 v61, v54, v46
	v_rcp_f32_e32 v79, v61
	v_sub_f32_e32 v47, v54, v61
	v_add_f32_e32 v78, v46, v47
	v_add_f32_e32 v47, v48, v49
	v_mul_f32_e32 v81, v47, v79
	v_sub_f32_e32 v46, v48, v47
	v_mul_f32_e32 v48, v61, v81
	v_fma_f32 v54, v81, v61, -v48
	v_fmac_f32_e32 v54, v81, v78
	v_add_f32_e32 v80, v49, v46
	v_add_f32_e32 v46, v48, v54
	v_sub_f32_e32 v49, v47, v46
	v_pk_add_f32 v[56:57], v[46:47], v[48:49] neg_lo:[0,1] neg_hi:[0,1]
	v_mov_b32_e32 v55, v46
	v_pk_add_f32 v[46:47], v[56:57], v[54:55] neg_lo:[0,1] neg_hi:[0,1]
	v_cmp_neq_f32_e64 s[0:1], s2, v42
	v_add_f32_e32 v47, v80, v47
	v_add_f32_e32 v46, v46, v47
	v_add_f32_e32 v47, v49, v46
	v_mul_f32_e32 v80, v79, v47
	v_mul_f32_e32 v48, v61, v80
	v_fma_f32 v54, v80, v61, -v48
	v_fmac_f32_e32 v54, v80, v78
	v_sub_f32_e32 v49, v49, v47
	v_add_f32_e32 v61, v46, v49
	v_add_f32_e32 v46, v48, v54
	v_sub_f32_e32 v49, v47, v46
	v_pk_add_f32 v[56:57], v[46:47], v[48:49] neg_lo:[0,1] neg_hi:[0,1]
	v_mov_b32_e32 v55, v46
	v_pk_add_f32 v[46:47], v[56:57], v[54:55] neg_lo:[0,1] neg_hi:[0,1]
	s_nop 0
	v_add_f32_e32 v47, v61, v47
	v_add_f32_e32 v46, v46, v47
	v_add_f32_e32 v47, v81, v80
	v_add_f32_e32 v46, v49, v46
	v_sub_f32_e32 v48, v47, v81
	v_mul_f32_e32 v46, v79, v46
	v_sub_f32_e32 v48, v80, v48
	v_add_f32_e32 v48, v48, v46
	v_add_f32_e32 v54, v47, v48
	v_mul_f32_e32 v55, v54, v54
	v_fmamk_f32 v46, v55, 0x3e9b6dac, v206
	v_fmaak_f32 v179, v55, v46, 0x3f2aaada
	v_cvt_f32_i32_e32 v46, v60
	v_sub_f32_e32 v47, v54, v47
	v_sub_f32_e32 v47, v48, v47
	v_ldexp_f32 v56, v47, 1
	v_mul_f32_e32 v47, v54, v55
	v_ldexp_f32 v49, v54, 1
	v_pk_mul_f32 v[54:55], v[46:47], v[178:179]
	s_nop 0
	v_fma_f32 v48, v46, s69, -v54
	v_fmac_f32_e32 v48, 0xb102e308, v46
	v_pk_add_f32 v[46:47], v[54:55], v[48:49]
	s_nop 0
	v_sub_f32_e32 v49, v47, v49
	v_sub_f32_e32 v49, v55, v49
	v_add_f32_e32 v57, v56, v49
	v_mov_b32_e32 v56, v54
	v_pk_add_f32 v[54:55], v[46:47], v[54:55] neg_lo:[0,1] neg_hi:[0,1]
	v_pk_add_f32 v[60:61], v[46:47], v[56:57]
	v_mov_b32_e32 v49, v46
	v_mov_b32_e32 v55, v61
	v_pk_add_f32 v[78:79], v[48:49], v[54:55] neg_lo:[0,1] neg_hi:[0,1]
	v_pk_add_f32 v[48:49], v[48:49], v[54:55]
	v_mov_b32_e32 v56, v57
	v_pk_add_f32 v[54:55], v[48:49], v[46:47] op_sel:[1,0] op_sel_hi:[0,1] neg_lo:[0,1] neg_hi:[0,1]
	v_pk_add_f32 v[80:81], v[60:61], v[54:55] op_sel_hi:[1,0] neg_lo:[0,1] neg_hi:[0,1]
	v_mov_b32_e32 v60, v61
	v_mov_b32_e32 v61, v49
	v_pk_mov_b32 v[54:55], v[46:47], v[54:55] op_sel:[1,0]
	v_mov_b32_e32 v57, v46
	v_pk_add_f32 v[54:55], v[60:61], v[54:55] neg_lo:[0,1] neg_hi:[0,1]
	v_mov_b32_e32 v80, v78
	v_pk_add_f32 v[46:47], v[56:57], v[54:55] neg_lo:[0,1] neg_hi:[0,1]
	v_mov_b32_e32 v79, v49
	v_pk_add_f32 v[54:55], v[80:81], v[46:47]
	s_nop 0
	v_pk_add_f32 v[56:57], v[54:55], v[54:55] op_sel:[0,1] op_sel_hi:[1,0]
	s_nop 0
	v_pk_add_f32 v[48:49], v[48:49], v[56:57] op_sel:[1,0] op_sel_hi:[0,1]
	v_mov_b32_e32 v55, v48
	v_pk_add_f32 v[60:61], v[54:55], v[78:79] neg_lo:[0,1] neg_hi:[0,1]
	v_mov_b32_e32 v47, v56
	v_sub_f32_e32 v49, v54, v60
	v_pk_add_f32 v[46:47], v[46:47], v[60:61] neg_lo:[0,1] neg_hi:[0,1]
	v_sub_f32_e32 v49, v78, v49
	v_add_f32_e32 v46, v46, v49
	v_add_f32_e32 v46, v46, v47
	v_add_f32_e32 v46, v48, v46
	v_cndmask_b32_e64 v46, v208, v46, s[0:1]
	v_cmp_lt_f32_e64 s[0:1], |v42|, s66
	s_nop 1
	v_cndmask_b32_e64 v42, v46, v42, s[0:1]
	v_lshl_add_u64 v[46:47], v[52:53], 0, v[64:65]
	v_lshlrev_b64 v[46:47], 14, v[46:47]
	v_sub_f32_e32 v0, v0, v42
	v_lshl_add_u64 v[46:47], v[50:51], 0, v[46:47]
	global_store_dword v[46:47], v0, off
	s_or_b64 exec, exec, s[84:85]
	s_and_saveexec_b64 s[84:85], s[14:15]
	s_cbranch_execz .LBB0_542
;     __device__ __forceinline__ void operator()(const f32x4 (&acc)[2][2][4][2], const pg8::Unit& u, int wr, int wc, int fr, int fq) const {
;     ...
;         if (kind == 1 && pn == 28) {
;             if (wc == 0) {
; #pragma unroll
;                 for (int ai = 0; ai < 2; ++ai)
; #pragma unroll
;                     for (int m = 0; m < 4; ++m) { const int row = row0 + ai * 128 + m * 16;
; #pragma unroll
;                         for (int n = 0; n < 2; ++n)
; #pragma unroll
;                             for (int j = 0; j < 4; ++j) { const int col = 8 * fq + 4 * n + j;
;                                 if (col < 12) { const float xv = acc[ai][0][m][n][j] * rsqrtf(ssq[row] * (1.f / DM) + EPS) + bfp[col]; LS[((size_t)(row >> 12) * 12 + col) * SEQ + (row & (SEQ - 1))] = fminf(xv, 0.f) - log1pf(expf(-fabsf(xv))); } } }
.LBB0_603:
	global_load_dword v0, v[66:67], off offset:128
	v_lshl_add_u64 v[46:47], v[74:75], 2, s[60:61]
	s_waitcnt vmcnt(0) lgkmcnt(0)
	v_fmamk_f32 v0, v0, 0x3a000000, v205
	v_cmp_gt_f32_e64 s[0:1], s68, v0
	v_mul_f32_e32 v42, 0x4b800000, v0
	s_nop 0
	v_cndmask_b32_e64 v0, v0, v42, s[0:1]
	v_rsq_f32_e32 v0, v0
	s_nop 0
	v_mul_f32_e32 v42, 0x45800000, v0
	v_cndmask_b32_e64 v0, v0, v42, s[0:1]
	global_load_dword v42, v[46:47], off
	s_waitcnt vmcnt(0) lgkmcnt(0)
	v_fmac_f32_e32 v42, v43, v0
	v_mul_f32_e64 v43, |v42|, s88
	v_fma_f32 v46, |v42|, s88, -v43
	v_rndne_f32_e32 v47, v43
	v_fma_f32 v46, |v42|, s89, v46
	v_sub_f32_e32 v43, v43, v47
	v_add_f32_e32 v43, v43, v46
	v_exp_f32_e32 v43, v43
	v_cvt_i32_f32_e32 v46, v47
	v_cmp_ngt_f32_e64 s[0:1], |v42|, s70
	v_min_f32_e32 v0, 0, v42
	v_ldexp_f32 v43, v43, v46
	v_cndmask_b32_e64 v43, 0, v43, s[0:1]
	v_cmp_nlt_f32_e64 s[0:1], |v42|, s90
	s_nop 1
	v_cndmask_b32_e64 v80, v208, v43, s[0:1]
	v_add_f32_e32 v46, 1.0, v80
	v_add_f32_e32 v42, -1.0, v46
	v_sub_f32_e32 v43, v42, v46
	v_add_f32_e32 v43, 1.0, v43
	v_sub_f32_e32 v42, v80, v42
	v_add_f32_e32 v47, v42, v43
	v_frexp_mant_f32_e32 v42, v46
	v_cmp_gt_f32_e64 s[0:1], s3, v42
	v_cvt_f64_f32_e32 v[42:43], v46
	v_frexp_exp_i32_f64_e32 v42, v[42:43]
	v_subbrev_co_u32_e64 v56, s[0:1], 0, v42, s[0:1]
	v_sub_u32_e32 v42, 0, v56
	v_ldexp_f32 v43, v46, v42
	v_add_f32_e32 v46, -1.0, v43
	v_add_f32_e32 v48, 1.0, v43
	v_ldexp_f32 v42, v47, v42
	v_add_f32_e32 v47, 1.0, v46
	v_add_f32_e32 v49, -1.0, v48
	v_sub_f32_e32 v47, v43, v47
	v_sub_f32_e32 v43, v43, v49
	v_add_f32_e32 v47, v42, v47
	v_add_f32_e32 v42, v42, v43
	v_add_f32_e32 v57, v48, v42
	v_rcp_f32_e32 v61, v57
	v_sub_f32_e32 v43, v48, v57
	v_add_f32_e32 v60, v42, v43
	v_add_f32_e32 v43, v46, v47
	v_mul_f32_e32 v79, v43, v61
	v_sub_f32_e32 v42, v46, v43
	v_mul_f32_e32 v46, v57, v79
	v_fma_f32 v48, v79, v57, -v46
	v_fmac_f32_e32 v48, v79, v60
	v_add_f32_e32 v78, v47, v42
	v_add_f32_e32 v42, v46, v48
	v_sub_f32_e32 v47, v43, v42
	v_pk_add_f32 v[54:55], v[42:43], v[46:47] neg_lo:[0,1] neg_hi:[0,1]
	v_mov_b32_e32 v49, v42
	v_pk_add_f32 v[42:43], v[54:55], v[48:49] neg_lo:[0,1] neg_hi:[0,1]
	v_cmp_neq_f32_e64 s[0:1], s2, v80
	v_add_f32_e32 v43, v78, v43
	v_add_f32_e32 v42, v42, v43
	v_add_f32_e32 v43, v47, v42
	v_mul_f32_e32 v78, v61, v43
	v_mul_f32_e32 v46, v57, v78
	v_fma_f32 v48, v78, v57, -v46
	v_fmac_f32_e32 v48, v78, v60
	v_sub_f32_e32 v47, v47, v43
	v_add_f32_e32 v57, v42, v47
	v_add_f32_e32 v42, v46, v48
	v_sub_f32_e32 v47, v43, v42
	v_pk_add_f32 v[54:55], v[42:43], v[46:47] neg_lo:[0,1] neg_hi:[0,1]
	v_mov_b32_e32 v49, v42
	v_pk_add_f32 v[42:43], v[54:55], v[48:49] neg_lo:[0,1] neg_hi:[0,1]
	s_nop 0
	v_add_f32_e32 v43, v57, v43
	v_add_f32_e32 v42, v42, v43
	v_add_f32_e32 v43, v79, v78
	v_add_f32_e32 v42, v47, v42
	v_sub_f32_e32 v46, v43, v79
	v_mul_f32_e32 v42, v61, v42
	v_sub_f32_e32 v46, v78, v46
	v_add_f32_e32 v46, v46, v42
	v_add_f32_e32 v48, v43, v46
	v_mul_f32_e32 v49, v48, v48
	v_fmamk_f32 v42, v49, 0x3e9b6dac, v206
	v_fmaak_f32 v179, v49, v42, 0x3f2aaada
	v_cvt_f32_i32_e32 v42, v56
	v_sub_f32_e32 v43, v48, v43
	v_sub_f32_e32 v43, v46, v43
	v_ldexp_f32 v54, v43, 1
	v_mul_f32_e32 v43, v48, v49
	v_ldexp_f32 v47, v48, 1
	v_pk_mul_f32 v[48:49], v[42:43], v[178:179]
	s_nop 0
	v_fma_f32 v46, v42, s69, -v48
	v_fmac_f32_e32 v46, 0xb102e308, v42
	v_pk_add_f32 v[42:43], v[48:49], v[46:47]
	s_nop 0
	v_sub_f32_e32 v47, v43, v47
	v_sub_f32_e32 v47, v49, v47
	v_add_f32_e32 v55, v54, v47
	v_mov_b32_e32 v54, v48
	v_pk_add_f32 v[48:49], v[42:43], v[48:49] neg_lo:[0,1] neg_hi:[0,1]
	v_pk_add_f32 v[56:57], v[42:43], v[54:55]
	v_mov_b32_e32 v47, v42
	v_mov_b32_e32 v49, v57
	v_pk_add_f32 v[60:61], v[46:47], v[48:49] neg_lo:[0,1] neg_hi:[0,1]
	v_pk_add_f32 v[46:47], v[46:47], v[48:49]
	v_mov_b32_e32 v54, v55
	v_pk_add_f32 v[48:49], v[46:47], v[42:43] op_sel:[1,0] op_sel_hi:[0,1] neg_lo:[0,1] neg_hi:[0,1]
	v_pk_add_f32 v[78:79], v[56:57], v[48:49] op_sel_hi:[1,0] neg_lo:[0,1] neg_hi:[0,1]
	v_mov_b32_e32 v56, v57
	v_mov_b32_e32 v57, v47
	v_pk_mov_b32 v[48:49], v[42:43], v[48:49] op_sel:[1,0]
	v_mov_b32_e32 v55, v42
	v_pk_add_f32 v[48:49], v[56:57], v[48:49] neg_lo:[0,1] neg_hi:[0,1]
	v_mov_b32_e32 v78, v60
	v_pk_add_f32 v[42:43], v[54:55], v[48:49] neg_lo:[0,1] neg_hi:[0,1]
	v_mov_b32_e32 v61, v47
	v_pk_add_f32 v[48:49], v[78:79], v[42:43]
	s_nop 0
	v_pk_add_f32 v[54:55], v[48:49], v[48:49] op_sel:[0,1] op_sel_hi:[1,0]
	s_nop 0
	v_pk_add_f32 v[46:47], v[46:47], v[54:55] op_sel:[1,0] op_sel_hi:[0,1]
	v_mov_b32_e32 v49, v46
	v_pk_add_f32 v[56:57], v[48:49], v[60:61] neg_lo:[0,1] neg_hi:[0,1]
	v_mov_b32_e32 v43, v54
	v_sub_f32_e32 v47, v48, v56
	v_pk_add_f32 v[42:43], v[42:43], v[56:57] neg_lo:[0,1] neg_hi:[0,1]
	v_sub_f32_e32 v47, v60, v47
	v_add_f32_e32 v42, v42, v47
	v_add_f32_e32 v42, v42, v43
	v_add_f32_e32 v42, v46, v42
	v_cndmask_b32_e64 v42, v208, v42, s[0:1]
	v_cmp_lt_f32_e64 s[0:1], |v80|, s66
	s_nop 1
	v_cndmask_b32_e64 v42, v42, v80, s[0:1]
	v_sub_f32_e32 v0, v0, v42
	v_lshl_add_u64 v[42:43], v[52:53], 0, v[74:75]
	v_lshlrev_b64 v[42:43], 14, v[42:43]
	v_lshl_add_u64 v[42:43], v[50:51], 0, v[42:43]
	global_store_dword v[42:43], v0, off
	s_or_b64 exec, exec, s[84:85]
	s_and_saveexec_b64 s[84:85], s[16:17]
	s_cbranch_execz .LBB0_543
;     __device__ __forceinline__ void operator()(const f32x4 (&acc)[2][2][4][2], const pg8::Unit& u, int wr, int wc, int fr, int fq) const {
;     ...
;         if (kind == 1 && pn == 28) {
;             if (wc == 0) {
; #pragma unroll
;                 for (int ai = 0; ai < 2; ++ai)
; #pragma unroll
;                     for (int m = 0; m < 4; ++m) { const int row = row0 + ai * 128 + m * 16;
; #pragma unroll
;                         for (int n = 0; n < 2; ++n)
; #pragma unroll
;                             for (int j = 0; j < 4; ++j) { const int col = 8 * fq + 4 * n + j;
;                                 if (col < 12) { const float xv = acc[ai][0][m][n][j] * rsqrtf(ssq[row] * (1.f / DM) + EPS) + bfp[col]; LS[((size_t)(row >> 12) * 12 + col) * SEQ + (row & (SEQ - 1))] = fminf(xv, 0.f) - log1pf(expf(-fabsf(xv))); } } }
.LBB0_604:
	global_load_dword v0, v[66:67], off offset:128
	s_waitcnt vmcnt(0) lgkmcnt(0)
	v_fmamk_f32 v0, v0, 0x3a000000, v205
	v_cmp_gt_f32_e64 s[0:1], s68, v0
	v_mul_f32_e32 v42, 0x4b800000, v0
	s_nop 0
	v_cndmask_b32_e64 v0, v0, v42, s[0:1]
	v_rsq_f32_e32 v0, v0
	s_nop 0
	v_mul_f32_e32 v42, 0x45800000, v0
	v_cndmask_b32_e64 v0, v0, v42, s[0:1]
	v_lshl_add_u64 v[42:43], v[58:59], 2, s[60:61]
	global_load_dword v42, v[42:43], off
	s_waitcnt vmcnt(0) lgkmcnt(0)
	v_fmac_f32_e32 v42, v44, v0
	v_mul_f32_e64 v43, |v42|, s88
	v_fma_f32 v44, |v42|, s88, -v43
	v_rndne_f32_e32 v46, v43
	v_fma_f32 v44, |v42|, s89, v44
	v_sub_f32_e32 v43, v43, v46
	v_add_f32_e32 v43, v43, v44
	v_exp_f32_e32 v43, v43
	v_cvt_i32_f32_e32 v44, v46
	v_cmp_ngt_f32_e64 s[0:1], |v42|, s70
	v_min_f32_e32 v0, 0, v42
	v_ldexp_f32 v43, v43, v44
	v_cndmask_b32_e64 v43, 0, v43, s[0:1]
	v_cmp_nlt_f32_e64 s[0:1], |v42|, s90
	s_nop 1
	v_cndmask_b32_e64 v44, v208, v43, s[0:1]
	v_add_f32_e32 v46, 1.0, v44
	v_add_f32_e32 v42, -1.0, v46
	v_sub_f32_e32 v43, v42, v46
	v_add_f32_e32 v43, 1.0, v43
	v_sub_f32_e32 v42, v44, v42
	v_add_f32_e32 v47, v42, v43
	v_frexp_mant_f32_e32 v42, v46
	v_cmp_gt_f32_e64 s[0:1], s3, v42
	v_cvt_f64_f32_e32 v[42:43], v46
	v_frexp_exp_i32_f64_e32 v42, v[42:43]
	v_subbrev_co_u32_e64 v56, s[0:1], 0, v42, s[0:1]
	v_sub_u32_e32 v42, 0, v56
	v_ldexp_f32 v43, v46, v42
	v_add_f32_e32 v46, -1.0, v43
	v_add_f32_e32 v48, 1.0, v43
	v_ldexp_f32 v42, v47, v42
	v_add_f32_e32 v47, 1.0, v46
	v_add_f32_e32 v49, -1.0, v48
	v_sub_f32_e32 v47, v43, v47
	v_sub_f32_e32 v43, v43, v49
	v_add_f32_e32 v47, v42, v47
	v_add_f32_e32 v42, v42, v43
	v_add_f32_e32 v57, v48, v42
	v_rcp_f32_e32 v61, v57
	v_sub_f32_e32 v43, v48, v57
	v_add_f32_e32 v60, v42, v43
	v_add_f32_e32 v43, v46, v47
	v_mul_f32_e32 v79, v43, v61
	v_sub_f32_e32 v42, v46, v43
	v_mul_f32_e32 v46, v57, v79
	v_fma_f32 v48, v79, v57, -v46
	v_fmac_f32_e32 v48, v79, v60
	v_add_f32_e32 v78, v47, v42
	v_add_f32_e32 v42, v46, v48
	v_sub_f32_e32 v47, v43, v42
	v_pk_add_f32 v[54:55], v[42:43], v[46:47] neg_lo:[0,1] neg_hi:[0,1]
	v_mov_b32_e32 v49, v42
	v_pk_add_f32 v[42:43], v[54:55], v[48:49] neg_lo:[0,1] neg_hi:[0,1]
	v_cmp_neq_f32_e64 s[0:1], s2, v44
	v_add_f32_e32 v43, v78, v43
	v_add_f32_e32 v42, v42, v43
	v_add_f32_e32 v43, v47, v42
	v_mul_f32_e32 v78, v61, v43
	v_mul_f32_e32 v46, v57, v78
	v_fma_f32 v48, v78, v57, -v46
	v_fmac_f32_e32 v48, v78, v60
	v_sub_f32_e32 v47, v47, v43
	v_add_f32_e32 v57, v42, v47
	v_add_f32_e32 v42, v46, v48
	v_sub_f32_e32 v47, v43, v42
	v_pk_add_f32 v[54:55], v[42:43], v[46:47] neg_lo:[0,1] neg_hi:[0,1]
	v_mov_b32_e32 v49, v42
	v_pk_add_f32 v[42:43], v[54:55], v[48:49] neg_lo:[0,1] neg_hi:[0,1]
	s_nop 0
	v_add_f32_e32 v43, v57, v43
	v_add_f32_e32 v42, v42, v43
	v_add_f32_e32 v43, v79, v78
	v_add_f32_e32 v42, v47, v42
	v_sub_f32_e32 v46, v43, v79
	v_mul_f32_e32 v42, v61, v42
	v_sub_f32_e32 v46, v78, v46
	v_add_f32_e32 v46, v46, v42
	v_add_f32_e32 v48, v43, v46
	v_mul_f32_e32 v49, v48, v48
	v_fmamk_f32 v42, v49, 0x3e9b6dac, v206
	v_fmaak_f32 v179, v49, v42, 0x3f2aaada
	v_cvt_f32_i32_e32 v42, v56
	v_sub_f32_e32 v43, v48, v43
	v_sub_f32_e32 v43, v46, v43
	v_ldexp_f32 v54, v43, 1
	v_mul_f32_e32 v43, v48, v49
	v_ldexp_f32 v47, v48, 1
	v_pk_mul_f32 v[48:49], v[42:43], v[178:179]
	s_nop 0
	v_fma_f32 v46, v42, s69, -v48
	v_fmac_f32_e32 v46, 0xb102e308, v42
	v_pk_add_f32 v[42:43], v[48:49], v[46:47]
	s_nop 0
	v_sub_f32_e32 v47, v43, v47
	v_sub_f32_e32 v47, v49, v47
	v_add_f32_e32 v55, v54, v47
	v_mov_b32_e32 v54, v48
	v_pk_add_f32 v[48:49], v[42:43], v[48:49] neg_lo:[0,1] neg_hi:[0,1]
	v_pk_add_f32 v[56:57], v[42:43], v[54:55]
	v_mov_b32_e32 v47, v42
	v_mov_b32_e32 v49, v57
	v_pk_add_f32 v[60:61], v[46:47], v[48:49] neg_lo:[0,1] neg_hi:[0,1]
	v_pk_add_f32 v[46:47], v[46:47], v[48:49]
	v_mov_b32_e32 v54, v55
	v_pk_add_f32 v[48:49], v[46:47], v[42:43] op_sel:[1,0] op_sel_hi:[0,1] neg_lo:[0,1] neg_hi:[0,1]
	v_pk_add_f32 v[78:79], v[56:57], v[48:49] op_sel_hi:[1,0] neg_lo:[0,1] neg_hi:[0,1]
	v_mov_b32_e32 v56, v57
	v_mov_b32_e32 v57, v47
	v_pk_mov_b32 v[48:49], v[42:43], v[48:49] op_sel:[1,0]
	v_mov_b32_e32 v55, v42
	v_pk_add_f32 v[48:49], v[56:57], v[48:49] neg_lo:[0,1] neg_hi:[0,1]
	v_mov_b32_e32 v78, v60
	v_pk_add_f32 v[42:43], v[54:55], v[48:49] neg_lo:[0,1] neg_hi:[0,1]
	v_mov_b32_e32 v61, v47
	v_pk_add_f32 v[48:49], v[78:79], v[42:43]
	s_nop 0
	v_pk_add_f32 v[54:55], v[48:49], v[48:49] op_sel:[0,1] op_sel_hi:[1,0]
	s_nop 0
	v_pk_add_f32 v[46:47], v[46:47], v[54:55] op_sel:[1,0] op_sel_hi:[0,1]
	v_mov_b32_e32 v49, v46
	v_pk_add_f32 v[56:57], v[48:49], v[60:61] neg_lo:[0,1] neg_hi:[0,1]
	v_mov_b32_e32 v43, v54
	v_sub_f32_e32 v47, v48, v56
	v_pk_add_f32 v[42:43], v[42:43], v[56:57] neg_lo:[0,1] neg_hi:[0,1]
	v_sub_f32_e32 v47, v60, v47
	v_add_f32_e32 v42, v42, v47
	v_add_f32_e32 v42, v42, v43
	v_add_f32_e32 v42, v46, v42
	v_cndmask_b32_e64 v42, v208, v42, s[0:1]
	v_cmp_lt_f32_e64 s[0:1], |v44|, s66
	s_nop 1
	v_cndmask_b32_e64 v42, v42, v44, s[0:1]
	v_sub_f32_e32 v0, v0, v42
	v_lshl_add_u64 v[42:43], v[52:53], 0, v[58:59]
	v_lshlrev_b64 v[42:43], 14, v[42:43]
	v_lshl_add_u64 v[42:43], v[50:51], 0, v[42:43]
	global_store_dword v[42:43], v0, off
	s_or_b64 exec, exec, s[84:85]
	s_and_saveexec_b64 s[84:85], s[18:19]
	s_cbranch_execnz .LBB0_544
	s_branch .LBB0_545
;     __device__ __forceinline__ void operator()(const f32x4 (&acc)[2][2][4][2], const pg8::Unit& u, int wr, int wc, int fr, int fq) const {
;     ...
;         if (kind == 1 && pn == 28) {
;             if (wc == 0) {
; #pragma unroll
;                 for (int ai = 0; ai < 2; ++ai)
; #pragma unroll
;                     for (int m = 0; m < 4; ++m) { const int row = row0 + ai * 128 + m * 16;
; #pragma unroll
;                         for (int n = 0; n < 2; ++n)
; #pragma unroll
;                             for (int j = 0; j < 4; ++j) { const int col = 8 * fq + 4 * n + j;
;                                 if (col < 12) { const float xv = acc[ai][0][m][n][j] * rsqrtf(ssq[row] * (1.f / DM) + EPS) + bfp[col]; LS[((size_t)(row >> 12) * 12 + col) * SEQ + (row & (SEQ - 1))] = fminf(xv, 0.f) - log1pf(expf(-fabsf(xv))); } } }
.LBB0_605:
	global_load_dword v0, v[66:67], off offset:192
	s_waitcnt vmcnt(0) lgkmcnt(0)
	v_fmamk_f32 v0, v0, 0x3a000000, v205
	v_cmp_gt_f32_e64 s[0:1], s68, v0
	v_mul_f32_e32 v46, 0x4b800000, v0
	s_nop 0
	v_cndmask_b32_e64 v0, v0, v46, s[0:1]
	v_rsq_f32_e32 v0, v0
	s_nop 0
	v_mul_f32_e32 v46, 0x45800000, v0
	v_cndmask_b32_e64 v0, v0, v46, s[0:1]
	v_lshl_add_u64 v[46:47], v[68:69], 2, s[60:61]
	global_load_dword v46, v[46:47], off
	s_waitcnt vmcnt(0) lgkmcnt(0)
	v_fmac_f32_e32 v46, v38, v0
	v_mul_f32_e64 v38, |v46|, s88
	v_fma_f32 v47, |v46|, s88, -v38
	v_rndne_f32_e32 v48, v38
	v_fma_f32 v47, |v46|, s89, v47
	v_sub_f32_e32 v38, v38, v48
	v_add_f32_e32 v38, v38, v47
	v_exp_f32_e32 v38, v38
	v_cvt_i32_f32_e32 v47, v48
	v_cmp_ngt_f32_e64 s[0:1], |v46|, s70
	v_min_f32_e32 v0, 0, v46
	v_ldexp_f32 v38, v38, v47
	v_cndmask_b32_e64 v38, 0, v38, s[0:1]
	v_cmp_nlt_f32_e64 s[0:1], |v46|, s90
	s_nop 1
	v_cndmask_b32_e64 v38, v208, v38, s[0:1]
	v_add_f32_e32 v48, 1.0, v38
	v_add_f32_e32 v46, -1.0, v48
	v_sub_f32_e32 v47, v46, v48
	v_add_f32_e32 v47, 1.0, v47
	v_sub_f32_e32 v46, v38, v46
	v_add_f32_e32 v49, v46, v47
	v_frexp_mant_f32_e32 v46, v48
	v_cmp_gt_f32_e64 s[0:1], s3, v46
	v_cvt_f64_f32_e32 v[46:47], v48
	v_frexp_exp_i32_f64_e32 v46, v[46:47]
	v_subbrev_co_u32_e64 v54, s[0:1], 0, v46, s[0:1]
	v_sub_u32_e32 v46, 0, v54
	v_ldexp_f32 v47, v48, v46
	v_add_f32_e32 v48, -1.0, v47
	v_add_f32_e32 v50, 1.0, v47
	v_ldexp_f32 v46, v49, v46
	v_add_f32_e32 v49, 1.0, v48
	v_add_f32_e32 v51, -1.0, v50
	v_sub_f32_e32 v49, v47, v49
	v_sub_f32_e32 v47, v47, v51
	v_add_f32_e32 v49, v46, v49
	v_add_f32_e32 v46, v46, v47
	v_add_f32_e32 v55, v50, v46
	v_rcp_f32_e32 v57, v55
	v_sub_f32_e32 v47, v50, v55
	v_add_f32_e32 v56, v46, v47
	v_add_f32_e32 v47, v48, v49
	v_mul_f32_e32 v61, v47, v57
	v_sub_f32_e32 v46, v48, v47
	v_mul_f32_e32 v48, v55, v61
	v_fma_f32 v50, v61, v55, -v48
	v_fmac_f32_e32 v50, v61, v56
	v_add_f32_e32 v60, v49, v46
	v_add_f32_e32 v46, v48, v50
	v_sub_f32_e32 v49, v47, v46
	v_pk_add_f32 v[52:53], v[46:47], v[48:49] neg_lo:[0,1] neg_hi:[0,1]
	v_mov_b32_e32 v51, v46
	v_pk_add_f32 v[46:47], v[52:53], v[50:51] neg_lo:[0,1] neg_hi:[0,1]
	v_cmp_neq_f32_e64 s[0:1], s2, v38
	v_add_f32_e32 v47, v60, v47
	v_add_f32_e32 v46, v46, v47
	v_add_f32_e32 v47, v49, v46
	v_mul_f32_e32 v60, v57, v47
	v_mul_f32_e32 v48, v55, v60
	v_fma_f32 v50, v60, v55, -v48
	v_fmac_f32_e32 v50, v60, v56
	v_sub_f32_e32 v49, v49, v47
	v_add_f32_e32 v55, v46, v49
	v_add_f32_e32 v46, v48, v50
	v_sub_f32_e32 v49, v47, v46
	v_pk_add_f32 v[52:53], v[46:47], v[48:49] neg_lo:[0,1] neg_hi:[0,1]
	v_mov_b32_e32 v51, v46
	v_pk_add_f32 v[46:47], v[52:53], v[50:51] neg_lo:[0,1] neg_hi:[0,1]
	s_nop 0
	v_add_f32_e32 v47, v55, v47
	v_add_f32_e32 v46, v46, v47
	v_add_f32_e32 v47, v61, v60
	v_add_f32_e32 v46, v49, v46
	v_sub_f32_e32 v48, v47, v61
	v_mul_f32_e32 v46, v57, v46
	v_sub_f32_e32 v48, v60, v48
	v_add_f32_e32 v48, v48, v46
	v_add_f32_e32 v50, v47, v48
	v_mul_f32_e32 v51, v50, v50
	v_fmamk_f32 v46, v51, 0x3e9b6dac, v206
	v_fmaak_f32 v179, v51, v46, 0x3f2aaada
	v_cvt_f32_i32_e32 v46, v54
	v_sub_f32_e32 v47, v50, v47
	v_sub_f32_e32 v47, v48, v47
	v_ldexp_f32 v52, v47, 1
	v_mul_f32_e32 v47, v50, v51
	v_ldexp_f32 v49, v50, 1
	v_pk_mul_f32 v[50:51], v[46:47], v[178:179]
	s_nop 0
	v_fma_f32 v48, v46, s69, -v50
	v_fmac_f32_e32 v48, 0xb102e308, v46
	v_pk_add_f32 v[46:47], v[50:51], v[48:49]
	s_nop 0
	v_sub_f32_e32 v49, v47, v49
	v_sub_f32_e32 v49, v51, v49
	v_add_f32_e32 v53, v52, v49
	v_mov_b32_e32 v52, v50
	v_pk_add_f32 v[50:51], v[46:47], v[50:51] neg_lo:[0,1] neg_hi:[0,1]
	v_pk_add_f32 v[54:55], v[46:47], v[52:53]
	v_mov_b32_e32 v49, v46
	v_mov_b32_e32 v51, v55
	v_pk_add_f32 v[56:57], v[48:49], v[50:51] neg_lo:[0,1] neg_hi:[0,1]
	v_pk_add_f32 v[48:49], v[48:49], v[50:51]
	v_mov_b32_e32 v52, v53
	v_pk_add_f32 v[50:51], v[48:49], v[46:47] op_sel:[1,0] op_sel_hi:[0,1] neg_lo:[0,1] neg_hi:[0,1]
	v_pk_add_f32 v[60:61], v[54:55], v[50:51] op_sel_hi:[1,0] neg_lo:[0,1] neg_hi:[0,1]
	v_mov_b32_e32 v54, v55
	v_mov_b32_e32 v55, v49
	v_pk_mov_b32 v[50:51], v[46:47], v[50:51] op_sel:[1,0]
	v_mov_b32_e32 v53, v46
	v_pk_add_f32 v[50:51], v[54:55], v[50:51] neg_lo:[0,1] neg_hi:[0,1]
	v_mov_b32_e32 v60, v56
	v_pk_add_f32 v[46:47], v[52:53], v[50:51] neg_lo:[0,1] neg_hi:[0,1]
	v_mov_b32_e32 v57, v49
	v_pk_add_f32 v[50:51], v[60:61], v[46:47]
	s_nop 0
	v_pk_add_f32 v[52:53], v[50:51], v[50:51] op_sel:[0,1] op_sel_hi:[1,0]
	s_nop 0
	v_pk_add_f32 v[48:49], v[48:49], v[52:53] op_sel:[1,0] op_sel_hi:[0,1]
	v_mov_b32_e32 v51, v48
	v_pk_add_f32 v[54:55], v[50:51], v[56:57] neg_lo:[0,1] neg_hi:[0,1]
	v_mov_b32_e32 v47, v52
	v_sub_f32_e32 v49, v50, v54
	v_pk_add_f32 v[46:47], v[46:47], v[54:55] neg_lo:[0,1] neg_hi:[0,1]
	v_sub_f32_e32 v49, v56, v49
	v_add_f32_e32 v46, v46, v49
	v_add_f32_e32 v46, v46, v47
	v_add_f32_e32 v46, v48, v46
	v_cndmask_b32_e64 v46, v208, v46, s[0:1]
	v_cmp_lt_f32_e64 s[0:1], |v38|, s66
	s_nop 1
	v_cndmask_b32_e64 v38, v46, v38, s[0:1]
	v_lshl_add_u64 v[46:47], v[44:45], 0, v[68:69]
	v_lshlrev_b64 v[46:47], 14, v[46:47]
	v_sub_f32_e32 v0, v0, v38
	v_lshl_add_u64 v[46:47], v[42:43], 0, v[46:47]
	global_store_dword v[46:47], v0, off
	s_or_b64 exec, exec, s[84:85]
	s_and_saveexec_b64 s[84:85], s[6:7]
	s_cbranch_execz .LBB0_547
;     __device__ __forceinline__ void operator()(const f32x4 (&acc)[2][2][4][2], const pg8::Unit& u, int wr, int wc, int fr, int fq) const {
;     ...
;         if (kind == 1 && pn == 28) {
;             if (wc == 0) {
; #pragma unroll
;                 for (int ai = 0; ai < 2; ++ai)
; #pragma unroll
;                     for (int m = 0; m < 4; ++m) { const int row = row0 + ai * 128 + m * 16;
; #pragma unroll
;                         for (int n = 0; n < 2; ++n)
; #pragma unroll
;                             for (int j = 0; j < 4; ++j) { const int col = 8 * fq + 4 * n + j;
;                                 if (col < 12) { const float xv = acc[ai][0][m][n][j] * rsqrtf(ssq[row] * (1.f / DM) + EPS) + bfp[col]; LS[((size_t)(row >> 12) * 12 + col) * SEQ + (row & (SEQ - 1))] = fminf(xv, 0.f) - log1pf(expf(-fabsf(xv))); } } }
.LBB0_606:
	global_load_dword v0, v[66:67], off offset:192
	v_lshl_add_u64 v[46:47], v[70:71], 2, s[60:61]
	s_waitcnt vmcnt(0) lgkmcnt(0)
	v_fmamk_f32 v0, v0, 0x3a000000, v205
	v_cmp_gt_f32_e64 s[0:1], s68, v0
	v_mul_f32_e32 v38, 0x4b800000, v0
	s_nop 0
	v_cndmask_b32_e64 v0, v0, v38, s[0:1]
	v_rsq_f32_e32 v0, v0
	s_nop 0
	v_mul_f32_e32 v38, 0x45800000, v0
	v_cndmask_b32_e64 v0, v0, v38, s[0:1]
	global_load_dword v38, v[46:47], off
	s_waitcnt vmcnt(0) lgkmcnt(0)
	v_fmac_f32_e32 v38, v39, v0
	v_mul_f32_e64 v39, |v38|, s88
	v_fma_f32 v46, |v38|, s88, -v39
	v_rndne_f32_e32 v47, v39
	v_fma_f32 v46, |v38|, s89, v46
	v_sub_f32_e32 v39, v39, v47
	v_add_f32_e32 v39, v39, v46
	v_exp_f32_e32 v39, v39
	v_cvt_i32_f32_e32 v46, v47
	v_cmp_ngt_f32_e64 s[0:1], |v38|, s70
	v_min_f32_e32 v0, 0, v38
	v_ldexp_f32 v39, v39, v46
	v_cndmask_b32_e64 v39, 0, v39, s[0:1]
	v_cmp_nlt_f32_e64 s[0:1], |v38|, s90
	s_nop 1
	v_cndmask_b32_e64 v60, v208, v39, s[0:1]
	v_add_f32_e32 v46, 1.0, v60
	v_add_f32_e32 v38, -1.0, v46
	v_sub_f32_e32 v39, v38, v46
	v_add_f32_e32 v39, 1.0, v39
	v_sub_f32_e32 v38, v60, v38
	v_add_f32_e32 v47, v38, v39
	v_frexp_mant_f32_e32 v38, v46
	v_cmp_gt_f32_e64 s[0:1], s3, v38
	v_cvt_f64_f32_e32 v[38:39], v46
	v_frexp_exp_i32_f64_e32 v38, v[38:39]
	v_subbrev_co_u32_e64 v52, s[0:1], 0, v38, s[0:1]
	v_sub_u32_e32 v38, 0, v52
	v_ldexp_f32 v39, v46, v38
	v_add_f32_e32 v46, -1.0, v39
	v_add_f32_e32 v48, 1.0, v39
	v_ldexp_f32 v38, v47, v38
	v_add_f32_e32 v47, 1.0, v46
	v_add_f32_e32 v49, -1.0, v48
	v_sub_f32_e32 v47, v39, v47
	v_sub_f32_e32 v39, v39, v49
	v_add_f32_e32 v47, v38, v47
	v_add_f32_e32 v38, v38, v39
	v_add_f32_e32 v53, v48, v38
	v_rcp_f32_e32 v55, v53
	v_sub_f32_e32 v39, v48, v53
	v_add_f32_e32 v54, v38, v39
	v_add_f32_e32 v39, v46, v47
	v_mul_f32_e32 v57, v39, v55
	v_sub_f32_e32 v38, v46, v39
	v_mul_f32_e32 v46, v53, v57
	v_fma_f32 v48, v57, v53, -v46
	v_fmac_f32_e32 v48, v57, v54
	v_add_f32_e32 v56, v47, v38
	v_add_f32_e32 v38, v46, v48
	v_sub_f32_e32 v47, v39, v38
	v_pk_add_f32 v[50:51], v[38:39], v[46:47] neg_lo:[0,1] neg_hi:[0,1]
	v_mov_b32_e32 v49, v38
	v_pk_add_f32 v[38:39], v[50:51], v[48:49] neg_lo:[0,1] neg_hi:[0,1]
	v_cmp_neq_f32_e64 s[0:1], s2, v60
	v_add_f32_e32 v39, v56, v39
	v_add_f32_e32 v38, v38, v39
	v_add_f32_e32 v39, v47, v38
	v_mul_f32_e32 v56, v55, v39
	v_mul_f32_e32 v46, v53, v56
	v_fma_f32 v48, v56, v53, -v46
	v_fmac_f32_e32 v48, v56, v54
	v_sub_f32_e32 v47, v47, v39
	v_add_f32_e32 v53, v38, v47
	v_add_f32_e32 v38, v46, v48
	v_sub_f32_e32 v47, v39, v38
	v_pk_add_f32 v[50:51], v[38:39], v[46:47] neg_lo:[0,1] neg_hi:[0,1]
	v_mov_b32_e32 v49, v38
	v_pk_add_f32 v[38:39], v[50:51], v[48:49] neg_lo:[0,1] neg_hi:[0,1]
	s_nop 0
	v_add_f32_e32 v39, v53, v39
	v_add_f32_e32 v38, v38, v39
	v_add_f32_e32 v39, v57, v56
	v_add_f32_e32 v38, v47, v38
	v_sub_f32_e32 v46, v39, v57
	v_mul_f32_e32 v38, v55, v38
	v_sub_f32_e32 v46, v56, v46
	v_add_f32_e32 v46, v46, v38
	v_add_f32_e32 v48, v39, v46
	v_mul_f32_e32 v49, v48, v48
	v_fmamk_f32 v38, v49, 0x3e9b6dac, v206
	v_fmaak_f32 v179, v49, v38, 0x3f2aaada
	v_cvt_f32_i32_e32 v38, v52
	v_sub_f32_e32 v39, v48, v39
	v_sub_f32_e32 v39, v46, v39
	v_ldexp_f32 v50, v39, 1
	v_mul_f32_e32 v39, v48, v49
	v_ldexp_f32 v47, v48, 1
	v_pk_mul_f32 v[48:49], v[38:39], v[178:179]
	s_nop 0
	v_fma_f32 v46, v38, s69, -v48
	v_fmac_f32_e32 v46, 0xb102e308, v38
	v_pk_add_f32 v[38:39], v[48:49], v[46:47]
	s_nop 0
	v_sub_f32_e32 v47, v39, v47
	v_sub_f32_e32 v47, v49, v47
	v_add_f32_e32 v51, v50, v47
	v_mov_b32_e32 v50, v48
	v_pk_add_f32 v[48:49], v[38:39], v[48:49] neg_lo:[0,1] neg_hi:[0,1]
	v_pk_add_f32 v[52:53], v[38:39], v[50:51]
	v_mov_b32_e32 v47, v38
	v_mov_b32_e32 v49, v53
	v_pk_add_f32 v[54:55], v[46:47], v[48:49] neg_lo:[0,1] neg_hi:[0,1]
	v_pk_add_f32 v[46:47], v[46:47], v[48:49]
	v_mov_b32_e32 v50, v51
	v_pk_add_f32 v[48:49], v[46:47], v[38:39] op_sel:[1,0] op_sel_hi:[0,1] neg_lo:[0,1] neg_hi:[0,1]
	v_pk_add_f32 v[56:57], v[52:53], v[48:49] op_sel_hi:[1,0] neg_lo:[0,1] neg_hi:[0,1]
	v_mov_b32_e32 v52, v53
	v_mov_b32_e32 v53, v47
	v_pk_mov_b32 v[48:49], v[38:39], v[48:49] op_sel:[1,0]
	v_mov_b32_e32 v51, v38
	v_pk_add_f32 v[48:49], v[52:53], v[48:49] neg_lo:[0,1] neg_hi:[0,1]
	v_mov_b32_e32 v56, v54
	v_pk_add_f32 v[38:39], v[50:51], v[48:49] neg_lo:[0,1] neg_hi:[0,1]
	v_mov_b32_e32 v55, v47
	v_pk_add_f32 v[48:49], v[56:57], v[38:39]
	s_nop 0
	v_pk_add_f32 v[50:51], v[48:49], v[48:49] op_sel:[0,1] op_sel_hi:[1,0]
	s_nop 0
	v_pk_add_f32 v[46:47], v[46:47], v[50:51] op_sel:[1,0] op_sel_hi:[0,1]
	v_mov_b32_e32 v49, v46
	v_pk_add_f32 v[52:53], v[48:49], v[54:55] neg_lo:[0,1] neg_hi:[0,1]
	v_mov_b32_e32 v39, v50
	v_sub_f32_e32 v47, v48, v52
	v_pk_add_f32 v[38:39], v[38:39], v[52:53] neg_lo:[0,1] neg_hi:[0,1]
	v_sub_f32_e32 v47, v54, v47
	v_add_f32_e32 v38, v38, v47
	v_add_f32_e32 v38, v38, v39
	v_add_f32_e32 v38, v46, v38
	v_cndmask_b32_e64 v38, v208, v38, s[0:1]
	v_cmp_lt_f32_e64 s[0:1], |v60|, s66
	s_nop 1
	v_cndmask_b32_e64 v38, v38, v60, s[0:1]
	v_sub_f32_e32 v0, v0, v38
	v_lshl_add_u64 v[38:39], v[44:45], 0, v[70:71]
	v_lshlrev_b64 v[38:39], 14, v[38:39]
	v_lshl_add_u64 v[38:39], v[42:43], 0, v[38:39]
	global_store_dword v[38:39], v0, off
	s_or_b64 exec, exec, s[84:85]
	s_and_saveexec_b64 s[84:85], s[8:9]
	s_cbranch_execz .LBB0_548
;     __device__ __forceinline__ void operator()(const f32x4 (&acc)[2][2][4][2], const pg8::Unit& u, int wr, int wc, int fr, int fq) const {
;     ...
;         if (kind == 1 && pn == 28) {
;             if (wc == 0) {
; #pragma unroll
;                 for (int ai = 0; ai < 2; ++ai)
; #pragma unroll
;                     for (int m = 0; m < 4; ++m) { const int row = row0 + ai * 128 + m * 16;
; #pragma unroll
;                         for (int n = 0; n < 2; ++n)
; #pragma unroll
;                             for (int j = 0; j < 4; ++j) { const int col = 8 * fq + 4 * n + j;
;                                 if (col < 12) { const float xv = acc[ai][0][m][n][j] * rsqrtf(ssq[row] * (1.f / DM) + EPS) + bfp[col]; LS[((size_t)(row >> 12) * 12 + col) * SEQ + (row & (SEQ - 1))] = fminf(xv, 0.f) - log1pf(expf(-fabsf(xv))); } } }
.LBB0_607:
	global_load_dword v0, v[66:67], off offset:192
	s_waitcnt vmcnt(0) lgkmcnt(0)
	v_fmamk_f32 v0, v0, 0x3a000000, v205
	v_cmp_gt_f32_e64 s[0:1], s68, v0
	v_mul_f32_e32 v38, 0x4b800000, v0
	s_nop 0
	v_cndmask_b32_e64 v0, v0, v38, s[0:1]
	v_rsq_f32_e32 v0, v0
	s_nop 0
	v_mul_f32_e32 v38, 0x45800000, v0
	v_cndmask_b32_e64 v0, v0, v38, s[0:1]
	v_lshl_add_u64 v[38:39], v[62:63], 2, s[60:61]
	global_load_dword v38, v[38:39], off
	s_waitcnt vmcnt(0) lgkmcnt(0)
	v_fmac_f32_e32 v38, v40, v0
	v_mul_f32_e64 v39, |v38|, s88
	v_fma_f32 v40, |v38|, s88, -v39
	v_rndne_f32_e32 v46, v39
	v_fma_f32 v40, |v38|, s89, v40
	v_sub_f32_e32 v39, v39, v46
	v_add_f32_e32 v39, v39, v40
	v_exp_f32_e32 v39, v39
	v_cvt_i32_f32_e32 v40, v46
	v_cmp_ngt_f32_e64 s[0:1], |v38|, s70
	v_min_f32_e32 v0, 0, v38
	v_ldexp_f32 v39, v39, v40
	v_cndmask_b32_e64 v39, 0, v39, s[0:1]
	v_cmp_nlt_f32_e64 s[0:1], |v38|, s90
	s_nop 1
	v_cndmask_b32_e64 v40, v208, v39, s[0:1]
	v_add_f32_e32 v46, 1.0, v40
	v_add_f32_e32 v38, -1.0, v46
	v_sub_f32_e32 v39, v38, v46
	v_add_f32_e32 v39, 1.0, v39
	v_sub_f32_e32 v38, v40, v38
	v_add_f32_e32 v47, v38, v39
	v_frexp_mant_f32_e32 v38, v46
	v_cmp_gt_f32_e64 s[0:1], s3, v38
	v_cvt_f64_f32_e32 v[38:39], v46
	v_frexp_exp_i32_f64_e32 v38, v[38:39]
	v_subbrev_co_u32_e64 v52, s[0:1], 0, v38, s[0:1]
	v_sub_u32_e32 v38, 0, v52
	v_ldexp_f32 v39, v46, v38
	v_add_f32_e32 v46, -1.0, v39
	v_add_f32_e32 v48, 1.0, v39
	v_ldexp_f32 v38, v47, v38
	v_add_f32_e32 v47, 1.0, v46
	v_add_f32_e32 v49, -1.0, v48
	v_sub_f32_e32 v47, v39, v47
	v_sub_f32_e32 v39, v39, v49
	v_add_f32_e32 v47, v38, v47
	v_add_f32_e32 v38, v38, v39
	v_add_f32_e32 v53, v48, v38
	v_rcp_f32_e32 v55, v53
	v_sub_f32_e32 v39, v48, v53
	v_add_f32_e32 v54, v38, v39
	v_add_f32_e32 v39, v46, v47
	v_mul_f32_e32 v57, v39, v55
	v_sub_f32_e32 v38, v46, v39
	v_mul_f32_e32 v46, v53, v57
	v_fma_f32 v48, v57, v53, -v46
	v_fmac_f32_e32 v48, v57, v54
	v_add_f32_e32 v56, v47, v38
	v_add_f32_e32 v38, v46, v48
	v_sub_f32_e32 v47, v39, v38
	v_pk_add_f32 v[50:51], v[38:39], v[46:47] neg_lo:[0,1] neg_hi:[0,1]
	v_mov_b32_e32 v49, v38
	v_pk_add_f32 v[38:39], v[50:51], v[48:49] neg_lo:[0,1] neg_hi:[0,1]
	v_cmp_neq_f32_e64 s[0:1], s2, v40
	v_add_f32_e32 v39, v56, v39
	v_add_f32_e32 v38, v38, v39
	v_add_f32_e32 v39, v47, v38
	v_mul_f32_e32 v56, v55, v39
	v_mul_f32_e32 v46, v53, v56
	v_fma_f32 v48, v56, v53, -v46
	v_fmac_f32_e32 v48, v56, v54
	v_sub_f32_e32 v47, v47, v39
	v_add_f32_e32 v53, v38, v47
	v_add_f32_e32 v38, v46, v48
	v_sub_f32_e32 v47, v39, v38
	v_pk_add_f32 v[50:51], v[38:39], v[46:47] neg_lo:[0,1] neg_hi:[0,1]
	v_mov_b32_e32 v49, v38
	v_pk_add_f32 v[38:39], v[50:51], v[48:49] neg_lo:[0,1] neg_hi:[0,1]
	s_nop 0
	v_add_f32_e32 v39, v53, v39
	v_add_f32_e32 v38, v38, v39
	v_add_f32_e32 v39, v57, v56
	v_add_f32_e32 v38, v47, v38
	v_sub_f32_e32 v46, v39, v57
	v_mul_f32_e32 v38, v55, v38
	v_sub_f32_e32 v46, v56, v46
	v_add_f32_e32 v46, v46, v38
	v_add_f32_e32 v48, v39, v46
	v_mul_f32_e32 v49, v48, v48
	v_fmamk_f32 v38, v49, 0x3e9b6dac, v206
	v_fmaak_f32 v179, v49, v38, 0x3f2aaada
	v_cvt_f32_i32_e32 v38, v52
	v_sub_f32_e32 v39, v48, v39
	v_sub_f32_e32 v39, v46, v39
	v_ldexp_f32 v50, v39, 1
	v_mul_f32_e32 v39, v48, v49
	v_ldexp_f32 v47, v48, 1
	v_pk_mul_f32 v[48:49], v[38:39], v[178:179]
	s_nop 0
	v_fma_f32 v46, v38, s69, -v48
	v_fmac_f32_e32 v46, 0xb102e308, v38
	v_pk_add_f32 v[38:39], v[48:49], v[46:47]
	s_nop 0
	v_sub_f32_e32 v47, v39, v47
	v_sub_f32_e32 v47, v49, v47
	v_add_f32_e32 v51, v50, v47
	v_mov_b32_e32 v50, v48
	v_pk_add_f32 v[48:49], v[38:39], v[48:49] neg_lo:[0,1] neg_hi:[0,1]
	v_pk_add_f32 v[52:53], v[38:39], v[50:51]
	v_mov_b32_e32 v47, v38
	v_mov_b32_e32 v49, v53
	v_pk_add_f32 v[54:55], v[46:47], v[48:49] neg_lo:[0,1] neg_hi:[0,1]
	v_pk_add_f32 v[46:47], v[46:47], v[48:49]
	v_mov_b32_e32 v50, v51
	v_pk_add_f32 v[48:49], v[46:47], v[38:39] op_sel:[1,0] op_sel_hi:[0,1] neg_lo:[0,1] neg_hi:[0,1]
	v_pk_add_f32 v[56:57], v[52:53], v[48:49] op_sel_hi:[1,0] neg_lo:[0,1] neg_hi:[0,1]
	v_mov_b32_e32 v52, v53
	v_mov_b32_e32 v53, v47
	v_pk_mov_b32 v[48:49], v[38:39], v[48:49] op_sel:[1,0]
	v_mov_b32_e32 v51, v38
	v_pk_add_f32 v[48:49], v[52:53], v[48:49] neg_lo:[0,1] neg_hi:[0,1]
	v_mov_b32_e32 v56, v54
	v_pk_add_f32 v[38:39], v[50:51], v[48:49] neg_lo:[0,1] neg_hi:[0,1]
	v_mov_b32_e32 v55, v47
	v_pk_add_f32 v[48:49], v[56:57], v[38:39]
	s_nop 0
	v_pk_add_f32 v[50:51], v[48:49], v[48:49] op_sel:[0,1] op_sel_hi:[1,0]
	s_nop 0
	v_pk_add_f32 v[46:47], v[46:47], v[50:51] op_sel:[1,0] op_sel_hi:[0,1]
	v_mov_b32_e32 v49, v46
	v_pk_add_f32 v[52:53], v[48:49], v[54:55] neg_lo:[0,1] neg_hi:[0,1]
	v_mov_b32_e32 v39, v50
	v_sub_f32_e32 v47, v48, v52
	v_pk_add_f32 v[38:39], v[38:39], v[52:53] neg_lo:[0,1] neg_hi:[0,1]
	v_sub_f32_e32 v47, v54, v47
	v_add_f32_e32 v38, v38, v47
	v_add_f32_e32 v38, v38, v39
	v_add_f32_e32 v38, v46, v38
	v_cndmask_b32_e64 v38, v208, v38, s[0:1]
	v_cmp_lt_f32_e64 s[0:1], |v40|, s66
	s_nop 1
	v_cndmask_b32_e64 v38, v38, v40, s[0:1]
	v_sub_f32_e32 v0, v0, v38
	v_lshl_add_u64 v[38:39], v[44:45], 0, v[62:63]
	v_lshlrev_b64 v[38:39], 14, v[38:39]
	v_lshl_add_u64 v[38:39], v[42:43], 0, v[38:39]
	global_store_dword v[38:39], v0, off
	s_or_b64 exec, exec, s[84:85]
	s_and_saveexec_b64 s[84:85], s[10:11]
	s_cbranch_execz .LBB0_549
;     __device__ __forceinline__ void operator()(const f32x4 (&acc)[2][2][4][2], const pg8::Unit& u, int wr, int wc, int fr, int fq) const {
;     ...
;         if (kind == 1 && pn == 28) {
;             if (wc == 0) {
; #pragma unroll
;                 for (int ai = 0; ai < 2; ++ai)
; #pragma unroll
;                     for (int m = 0; m < 4; ++m) { const int row = row0 + ai * 128 + m * 16;
; #pragma unroll
;                         for (int n = 0; n < 2; ++n)
; #pragma unroll
;                             for (int j = 0; j < 4; ++j) { const int col = 8 * fq + 4 * n + j;
;                                 if (col < 12) { const float xv = acc[ai][0][m][n][j] * rsqrtf(ssq[row] * (1.f / DM) + EPS) + bfp[col]; LS[((size_t)(row >> 12) * 12 + col) * SEQ + (row & (SEQ - 1))] = fminf(xv, 0.f) - log1pf(expf(-fabsf(xv))); } } }
.LBB0_608:
	global_load_dword v0, v[66:67], off offset:192
	s_waitcnt vmcnt(0) lgkmcnt(0)
	v_fmamk_f32 v0, v0, 0x3a000000, v205
	v_cmp_gt_f32_e64 s[0:1], s68, v0
	v_mul_f32_e32 v38, 0x4b800000, v0
	s_nop 0
	v_cndmask_b32_e64 v0, v0, v38, s[0:1]
	v_rsq_f32_e32 v0, v0
	s_nop 0
	v_mul_f32_e32 v38, 0x45800000, v0
	v_cndmask_b32_e64 v0, v0, v38, s[0:1]
	v_lshl_add_u64 v[38:39], v[72:73], 2, s[60:61]
	global_load_dword v38, v[38:39], off
	s_waitcnt vmcnt(0) lgkmcnt(0)
	v_fmac_f32_e32 v38, v41, v0
	v_mul_f32_e64 v39, |v38|, s88
	v_fma_f32 v40, |v38|, s88, -v39
	v_rndne_f32_e32 v41, v39
	v_fma_f32 v40, |v38|, s89, v40
	v_sub_f32_e32 v39, v39, v41
	v_add_f32_e32 v39, v39, v40
	v_exp_f32_e32 v39, v39
	v_cvt_i32_f32_e32 v40, v41
	v_cmp_ngt_f32_e64 s[0:1], |v38|, s70
	v_min_f32_e32 v0, 0, v38
	v_ldexp_f32 v39, v39, v40
	v_cndmask_b32_e64 v39, 0, v39, s[0:1]
	v_cmp_nlt_f32_e64 s[0:1], |v38|, s90
	s_nop 1
	v_cndmask_b32_e64 v56, v208, v39, s[0:1]
	v_add_f32_e32 v40, 1.0, v56
	v_add_f32_e32 v38, -1.0, v40
	v_sub_f32_e32 v39, v38, v40
	v_add_f32_e32 v39, 1.0, v39
	v_sub_f32_e32 v38, v56, v38
	v_add_f32_e32 v41, v38, v39
	v_frexp_mant_f32_e32 v38, v40
	v_cmp_gt_f32_e64 s[0:1], s3, v38
	v_cvt_f64_f32_e32 v[38:39], v40
	v_frexp_exp_i32_f64_e32 v38, v[38:39]
	v_subbrev_co_u32_e64 v50, s[0:1], 0, v38, s[0:1]
	v_sub_u32_e32 v38, 0, v50
	v_ldexp_f32 v39, v40, v38
	v_add_f32_e32 v40, -1.0, v39
	v_add_f32_e32 v46, 1.0, v39
	v_ldexp_f32 v38, v41, v38
	v_add_f32_e32 v41, 1.0, v40
	v_add_f32_e32 v47, -1.0, v46
	v_sub_f32_e32 v41, v39, v41
	v_sub_f32_e32 v39, v39, v47
	v_add_f32_e32 v41, v38, v41
	v_add_f32_e32 v38, v38, v39
	v_add_f32_e32 v51, v46, v38
	v_rcp_f32_e32 v53, v51
	v_sub_f32_e32 v39, v46, v51
	v_add_f32_e32 v52, v38, v39
	v_add_f32_e32 v39, v40, v41
	v_mul_f32_e32 v55, v39, v53
	v_sub_f32_e32 v38, v40, v39
	v_mul_f32_e32 v40, v51, v55
	v_fma_f32 v46, v55, v51, -v40
	v_fmac_f32_e32 v46, v55, v52
	v_add_f32_e32 v54, v41, v38
	v_add_f32_e32 v38, v40, v46
	v_sub_f32_e32 v41, v39, v38
	v_pk_add_f32 v[48:49], v[38:39], v[40:41] neg_lo:[0,1] neg_hi:[0,1]
	v_mov_b32_e32 v47, v38
	v_pk_add_f32 v[38:39], v[48:49], v[46:47] neg_lo:[0,1] neg_hi:[0,1]
	v_cmp_neq_f32_e64 s[0:1], s2, v56
	v_add_f32_e32 v39, v54, v39
	v_add_f32_e32 v38, v38, v39
	v_add_f32_e32 v39, v41, v38
	v_mul_f32_e32 v54, v53, v39
	v_mul_f32_e32 v40, v51, v54
	v_fma_f32 v46, v54, v51, -v40
	v_fmac_f32_e32 v46, v54, v52
	v_sub_f32_e32 v41, v41, v39
	v_add_f32_e32 v51, v38, v41
	v_add_f32_e32 v38, v40, v46
	v_sub_f32_e32 v41, v39, v38
	v_pk_add_f32 v[48:49], v[38:39], v[40:41] neg_lo:[0,1] neg_hi:[0,1]
	v_mov_b32_e32 v47, v38
	v_pk_add_f32 v[38:39], v[48:49], v[46:47] neg_lo:[0,1] neg_hi:[0,1]
	s_nop 0
	v_add_f32_e32 v39, v51, v39
	v_add_f32_e32 v38, v38, v39
	v_add_f32_e32 v39, v55, v54
	v_add_f32_e32 v38, v41, v38
	v_sub_f32_e32 v40, v39, v55
	v_mul_f32_e32 v38, v53, v38
	v_sub_f32_e32 v40, v54, v40
	v_add_f32_e32 v40, v40, v38
	v_add_f32_e32 v46, v39, v40
	v_mul_f32_e32 v47, v46, v46
	v_fmamk_f32 v38, v47, 0x3e9b6dac, v206
	v_fmaak_f32 v179, v47, v38, 0x3f2aaada
	v_cvt_f32_i32_e32 v38, v50
	v_sub_f32_e32 v39, v46, v39
	v_sub_f32_e32 v39, v40, v39
	v_ldexp_f32 v48, v39, 1
	v_mul_f32_e32 v39, v46, v47
	v_ldexp_f32 v41, v46, 1
	v_pk_mul_f32 v[46:47], v[38:39], v[178:179]
	s_nop 0
	v_fma_f32 v40, v38, s69, -v46
	v_fmac_f32_e32 v40, 0xb102e308, v38
	v_pk_add_f32 v[38:39], v[46:47], v[40:41]
	s_nop 0
	v_sub_f32_e32 v41, v39, v41
	v_sub_f32_e32 v41, v47, v41
	v_add_f32_e32 v49, v48, v41
	v_mov_b32_e32 v48, v46
	v_pk_add_f32 v[46:47], v[38:39], v[46:47] neg_lo:[0,1] neg_hi:[0,1]
	v_pk_add_f32 v[50:51], v[38:39], v[48:49]
	v_mov_b32_e32 v41, v38
	v_mov_b32_e32 v47, v51
	v_pk_add_f32 v[52:53], v[40:41], v[46:47] neg_lo:[0,1] neg_hi:[0,1]
	v_pk_add_f32 v[40:41], v[40:41], v[46:47]
	v_mov_b32_e32 v48, v49
	v_pk_add_f32 v[46:47], v[40:41], v[38:39] op_sel:[1,0] op_sel_hi:[0,1] neg_lo:[0,1] neg_hi:[0,1]
	v_pk_add_f32 v[54:55], v[50:51], v[46:47] op_sel_hi:[1,0] neg_lo:[0,1] neg_hi:[0,1]
	v_mov_b32_e32 v50, v51
	v_mov_b32_e32 v51, v41
	v_pk_mov_b32 v[46:47], v[38:39], v[46:47] op_sel:[1,0]
	v_mov_b32_e32 v49, v38
	v_pk_add_f32 v[46:47], v[50:51], v[46:47] neg_lo:[0,1] neg_hi:[0,1]
	v_mov_b32_e32 v54, v52
	v_pk_add_f32 v[38:39], v[48:49], v[46:47] neg_lo:[0,1] neg_hi:[0,1]
	v_mov_b32_e32 v53, v41
	v_pk_add_f32 v[46:47], v[54:55], v[38:39]
	s_nop 0
	v_pk_add_f32 v[48:49], v[46:47], v[46:47] op_sel:[0,1] op_sel_hi:[1,0]
	s_nop 0
	v_pk_add_f32 v[40:41], v[40:41], v[48:49] op_sel:[1,0] op_sel_hi:[0,1]
	v_mov_b32_e32 v47, v40
	v_pk_add_f32 v[50:51], v[46:47], v[52:53] neg_lo:[0,1] neg_hi:[0,1]
	v_mov_b32_e32 v39, v48
	v_sub_f32_e32 v41, v46, v50
	v_pk_add_f32 v[38:39], v[38:39], v[50:51] neg_lo:[0,1] neg_hi:[0,1]
	v_sub_f32_e32 v41, v52, v41
	v_add_f32_e32 v38, v38, v41
	v_add_f32_e32 v38, v38, v39
	v_add_f32_e32 v38, v40, v38
	v_cndmask_b32_e64 v38, v208, v38, s[0:1]
	v_cmp_lt_f32_e64 s[0:1], |v56|, s66
	s_nop 1
	v_cndmask_b32_e64 v38, v38, v56, s[0:1]
	v_sub_f32_e32 v0, v0, v38
	v_lshl_add_u64 v[38:39], v[44:45], 0, v[72:73]
	v_lshlrev_b64 v[38:39], 14, v[38:39]
	v_lshl_add_u64 v[38:39], v[42:43], 0, v[38:39]
	global_store_dword v[38:39], v0, off
	s_or_b64 exec, exec, s[84:85]
	s_and_saveexec_b64 s[84:85], s[12:13]
	s_cbranch_execz .LBB0_550
;     __device__ __forceinline__ void operator()(const f32x4 (&acc)[2][2][4][2], const pg8::Unit& u, int wr, int wc, int fr, int fq) const {
;     ...
;         if (kind == 1 && pn == 28) {
;             if (wc == 0) {
; #pragma unroll
;                 for (int ai = 0; ai < 2; ++ai)
; #pragma unroll
;                     for (int m = 0; m < 4; ++m) { const int row = row0 + ai * 128 + m * 16;
; #pragma unroll
;                         for (int n = 0; n < 2; ++n)
; #pragma unroll
;                             for (int j = 0; j < 4; ++j) { const int col = 8 * fq + 4 * n + j;
;                                 if (col < 12) { const float xv = acc[ai][0][m][n][j] * rsqrtf(ssq[row] * (1.f / DM) + EPS) + bfp[col]; LS[((size_t)(row >> 12) * 12 + col) * SEQ + (row & (SEQ - 1))] = fminf(xv, 0.f) - log1pf(expf(-fabsf(xv))); } } }
.LBB0_609:
	global_load_dword v0, v[66:67], off offset:192
	s_waitcnt vmcnt(0) lgkmcnt(0)
	v_fmamk_f32 v0, v0, 0x3a000000, v205
	v_cmp_gt_f32_e64 s[0:1], s68, v0
	v_mul_f32_e32 v38, 0x4b800000, v0
	s_nop 0
	v_cndmask_b32_e64 v0, v0, v38, s[0:1]
	v_rsq_f32_e32 v0, v0
	s_nop 0
	v_mul_f32_e32 v38, 0x45800000, v0
	v_cndmask_b32_e64 v0, v0, v38, s[0:1]
	v_lshl_add_u64 v[38:39], v[64:65], 2, s[60:61]
	global_load_dword v38, v[38:39], off
	s_waitcnt vmcnt(0) lgkmcnt(0)
	v_fmac_f32_e32 v38, v34, v0
	v_mul_f32_e64 v34, |v38|, s88
	v_fma_f32 v39, |v38|, s88, -v34
	v_rndne_f32_e32 v40, v34
	v_fma_f32 v39, |v38|, s89, v39
	v_sub_f32_e32 v34, v34, v40
	v_add_f32_e32 v34, v34, v39
	v_exp_f32_e32 v34, v34
	v_cvt_i32_f32_e32 v39, v40
	v_cmp_ngt_f32_e64 s[0:1], |v38|, s70
	v_min_f32_e32 v0, 0, v38
	v_ldexp_f32 v34, v34, v39
	v_cndmask_b32_e64 v34, 0, v34, s[0:1]
	v_cmp_nlt_f32_e64 s[0:1], |v38|, s90
	s_nop 1
	v_cndmask_b32_e64 v34, v208, v34, s[0:1]
	v_add_f32_e32 v40, 1.0, v34
	v_add_f32_e32 v38, -1.0, v40
	v_sub_f32_e32 v39, v38, v40
	v_add_f32_e32 v39, 1.0, v39
	v_sub_f32_e32 v38, v34, v38
	v_add_f32_e32 v41, v38, v39
	v_frexp_mant_f32_e32 v38, v40
	v_cmp_gt_f32_e64 s[0:1], s3, v38
	v_cvt_f64_f32_e32 v[38:39], v40
	v_frexp_exp_i32_f64_e32 v38, v[38:39]
	v_subbrev_co_u32_e64 v50, s[0:1], 0, v38, s[0:1]
	v_sub_u32_e32 v38, 0, v50
	v_ldexp_f32 v39, v40, v38
	v_add_f32_e32 v40, -1.0, v39
	v_add_f32_e32 v46, 1.0, v39
	v_ldexp_f32 v38, v41, v38
	v_add_f32_e32 v41, 1.0, v40
	v_add_f32_e32 v47, -1.0, v46
	v_sub_f32_e32 v41, v39, v41
	v_sub_f32_e32 v39, v39, v47
	v_add_f32_e32 v41, v38, v41
	v_add_f32_e32 v38, v38, v39
	v_add_f32_e32 v51, v46, v38
	v_rcp_f32_e32 v53, v51
	v_sub_f32_e32 v39, v46, v51
	v_add_f32_e32 v52, v38, v39
	v_add_f32_e32 v39, v40, v41
	v_mul_f32_e32 v55, v39, v53
	v_sub_f32_e32 v38, v40, v39
	v_mul_f32_e32 v40, v51, v55
	v_fma_f32 v46, v55, v51, -v40
	v_fmac_f32_e32 v46, v55, v52
	v_add_f32_e32 v54, v41, v38
	v_add_f32_e32 v38, v40, v46
	v_sub_f32_e32 v41, v39, v38
	v_pk_add_f32 v[48:49], v[38:39], v[40:41] neg_lo:[0,1] neg_hi:[0,1]
	v_mov_b32_e32 v47, v38
	v_pk_add_f32 v[38:39], v[48:49], v[46:47] neg_lo:[0,1] neg_hi:[0,1]
	v_cmp_neq_f32_e64 s[0:1], s2, v34
	v_add_f32_e32 v39, v54, v39
	v_add_f32_e32 v38, v38, v39
	v_add_f32_e32 v39, v41, v38
	v_mul_f32_e32 v54, v53, v39
	v_mul_f32_e32 v40, v51, v54
	v_fma_f32 v46, v54, v51, -v40
	v_fmac_f32_e32 v46, v54, v52
	v_sub_f32_e32 v41, v41, v39
	v_add_f32_e32 v51, v38, v41
	v_add_f32_e32 v38, v40, v46
	v_sub_f32_e32 v41, v39, v38
	v_pk_add_f32 v[48:49], v[38:39], v[40:41] neg_lo:[0,1] neg_hi:[0,1]
	v_mov_b32_e32 v47, v38
	v_pk_add_f32 v[38:39], v[48:49], v[46:47] neg_lo:[0,1] neg_hi:[0,1]
	s_nop 0
	v_add_f32_e32 v39, v51, v39
	v_add_f32_e32 v38, v38, v39
	v_add_f32_e32 v39, v55, v54
	v_add_f32_e32 v38, v41, v38
	v_sub_f32_e32 v40, v39, v55
	v_mul_f32_e32 v38, v53, v38
	v_sub_f32_e32 v40, v54, v40
	v_add_f32_e32 v40, v40, v38
	v_add_f32_e32 v46, v39, v40
	v_mul_f32_e32 v47, v46, v46
	v_fmamk_f32 v38, v47, 0x3e9b6dac, v206
	v_fmaak_f32 v179, v47, v38, 0x3f2aaada
	v_cvt_f32_i32_e32 v38, v50
	v_sub_f32_e32 v39, v46, v39
	v_sub_f32_e32 v39, v40, v39
	v_ldexp_f32 v48, v39, 1
	v_mul_f32_e32 v39, v46, v47
	v_ldexp_f32 v41, v46, 1
	v_pk_mul_f32 v[46:47], v[38:39], v[178:179]
	s_nop 0
	v_fma_f32 v40, v38, s69, -v46
	v_fmac_f32_e32 v40, 0xb102e308, v38
	v_pk_add_f32 v[38:39], v[46:47], v[40:41]
	s_nop 0
	v_sub_f32_e32 v41, v39, v41
	v_sub_f32_e32 v41, v47, v41
	v_add_f32_e32 v49, v48, v41
	v_mov_b32_e32 v48, v46
	v_pk_add_f32 v[46:47], v[38:39], v[46:47] neg_lo:[0,1] neg_hi:[0,1]
	v_pk_add_f32 v[50:51], v[38:39], v[48:49]
	v_mov_b32_e32 v41, v38
	v_mov_b32_e32 v47, v51
	v_pk_add_f32 v[52:53], v[40:41], v[46:47] neg_lo:[0,1] neg_hi:[0,1]
	v_pk_add_f32 v[40:41], v[40:41], v[46:47]
	v_mov_b32_e32 v48, v49
	v_pk_add_f32 v[46:47], v[40:41], v[38:39] op_sel:[1,0] op_sel_hi:[0,1] neg_lo:[0,1] neg_hi:[0,1]
	v_pk_add_f32 v[54:55], v[50:51], v[46:47] op_sel_hi:[1,0] neg_lo:[0,1] neg_hi:[0,1]
	v_mov_b32_e32 v50, v51
	v_mov_b32_e32 v51, v41
	v_pk_mov_b32 v[46:47], v[38:39], v[46:47] op_sel:[1,0]
	v_mov_b32_e32 v49, v38
	v_pk_add_f32 v[46:47], v[50:51], v[46:47] neg_lo:[0,1] neg_hi:[0,1]
	v_mov_b32_e32 v54, v52
	v_pk_add_f32 v[38:39], v[48:49], v[46:47] neg_lo:[0,1] neg_hi:[0,1]
	v_mov_b32_e32 v53, v41
	v_pk_add_f32 v[46:47], v[54:55], v[38:39]
	s_nop 0
	v_pk_add_f32 v[48:49], v[46:47], v[46:47] op_sel:[0,1] op_sel_hi:[1,0]
	s_nop 0
	v_pk_add_f32 v[40:41], v[40:41], v[48:49] op_sel:[1,0] op_sel_hi:[0,1]
	v_mov_b32_e32 v47, v40
	v_pk_add_f32 v[50:51], v[46:47], v[52:53] neg_lo:[0,1] neg_hi:[0,1]
	v_mov_b32_e32 v39, v48
	v_sub_f32_e32 v41, v46, v50
	v_pk_add_f32 v[38:39], v[38:39], v[50:51] neg_lo:[0,1] neg_hi:[0,1]
	v_sub_f32_e32 v41, v52, v41
	v_add_f32_e32 v38, v38, v41
	v_add_f32_e32 v38, v38, v39
	v_add_f32_e32 v38, v40, v38
	v_cndmask_b32_e64 v38, v208, v38, s[0:1]
	v_cmp_lt_f32_e64 s[0:1], |v34|, s66
	s_nop 1
	v_cndmask_b32_e64 v34, v38, v34, s[0:1]
	v_lshl_add_u64 v[38:39], v[44:45], 0, v[64:65]
	v_lshlrev_b64 v[38:39], 14, v[38:39]
	v_sub_f32_e32 v0, v0, v34
	v_lshl_add_u64 v[38:39], v[42:43], 0, v[38:39]
	global_store_dword v[38:39], v0, off
	s_or_b64 exec, exec, s[84:85]
	s_and_saveexec_b64 s[84:85], s[14:15]
	s_cbranch_execz .LBB0_551
;     __device__ __forceinline__ void operator()(const f32x4 (&acc)[2][2][4][2], const pg8::Unit& u, int wr, int wc, int fr, int fq) const {
;     ...
;         if (kind == 1 && pn == 28) {
;             if (wc == 0) {
; #pragma unroll
;                 for (int ai = 0; ai < 2; ++ai)
; #pragma unroll
;                     for (int m = 0; m < 4; ++m) { const int row = row0 + ai * 128 + m * 16;
; #pragma unroll
;                         for (int n = 0; n < 2; ++n)
; #pragma unroll
;                             for (int j = 0; j < 4; ++j) { const int col = 8 * fq + 4 * n + j;
;                                 if (col < 12) { const float xv = acc[ai][0][m][n][j] * rsqrtf(ssq[row] * (1.f / DM) + EPS) + bfp[col]; LS[((size_t)(row >> 12) * 12 + col) * SEQ + (row & (SEQ - 1))] = fminf(xv, 0.f) - log1pf(expf(-fabsf(xv))); } } }
.LBB0_610:
	global_load_dword v0, v[66:67], off offset:192
	v_lshl_add_u64 v[38:39], v[74:75], 2, s[60:61]
	s_waitcnt vmcnt(0) lgkmcnt(0)
	v_fmamk_f32 v0, v0, 0x3a000000, v205
	v_cmp_gt_f32_e64 s[0:1], s68, v0
	v_mul_f32_e32 v34, 0x4b800000, v0
	s_nop 0
	v_cndmask_b32_e64 v0, v0, v34, s[0:1]
	v_rsq_f32_e32 v0, v0
	s_nop 0
	v_mul_f32_e32 v34, 0x45800000, v0
	v_cndmask_b32_e64 v0, v0, v34, s[0:1]
	global_load_dword v34, v[38:39], off
	s_waitcnt vmcnt(0) lgkmcnt(0)
	v_fmac_f32_e32 v34, v35, v0
	v_mul_f32_e64 v35, |v34|, s88
	v_fma_f32 v38, |v34|, s88, -v35
	v_rndne_f32_e32 v39, v35
	v_fma_f32 v38, |v34|, s89, v38
	v_sub_f32_e32 v35, v35, v39
	v_add_f32_e32 v35, v35, v38
	v_exp_f32_e32 v35, v35
	v_cvt_i32_f32_e32 v38, v39
	v_cmp_ngt_f32_e64 s[0:1], |v34|, s70
	v_min_f32_e32 v0, 0, v34
	v_ldexp_f32 v35, v35, v38
	v_cndmask_b32_e64 v35, 0, v35, s[0:1]
	v_cmp_nlt_f32_e64 s[0:1], |v34|, s90
	s_nop 1
	v_cndmask_b32_e64 v54, v208, v35, s[0:1]
	v_add_f32_e32 v38, 1.0, v54
	v_add_f32_e32 v34, -1.0, v38
	v_sub_f32_e32 v35, v34, v38
	v_add_f32_e32 v35, 1.0, v35
	v_sub_f32_e32 v34, v54, v34
	v_add_f32_e32 v39, v34, v35
	v_frexp_mant_f32_e32 v34, v38
	v_cmp_gt_f32_e64 s[0:1], s3, v34
	v_cvt_f64_f32_e32 v[34:35], v38
	v_frexp_exp_i32_f64_e32 v34, v[34:35]
	v_subbrev_co_u32_e64 v48, s[0:1], 0, v34, s[0:1]
	v_sub_u32_e32 v34, 0, v48
	v_ldexp_f32 v35, v38, v34
	v_add_f32_e32 v38, -1.0, v35
	v_add_f32_e32 v40, 1.0, v35
	v_ldexp_f32 v34, v39, v34
	v_add_f32_e32 v39, 1.0, v38
	v_add_f32_e32 v41, -1.0, v40
	v_sub_f32_e32 v39, v35, v39
	v_sub_f32_e32 v35, v35, v41
	v_add_f32_e32 v39, v34, v39
	v_add_f32_e32 v34, v34, v35
	v_add_f32_e32 v49, v40, v34
	v_rcp_f32_e32 v51, v49
	v_sub_f32_e32 v35, v40, v49
	v_add_f32_e32 v50, v34, v35
	v_add_f32_e32 v35, v38, v39
	v_mul_f32_e32 v53, v35, v51
	v_sub_f32_e32 v34, v38, v35
	v_mul_f32_e32 v38, v49, v53
	v_fma_f32 v40, v53, v49, -v38
	v_fmac_f32_e32 v40, v53, v50
	v_add_f32_e32 v52, v39, v34
	v_add_f32_e32 v34, v38, v40
	v_sub_f32_e32 v39, v35, v34
	v_pk_add_f32 v[46:47], v[34:35], v[38:39] neg_lo:[0,1] neg_hi:[0,1]
	v_mov_b32_e32 v41, v34
	v_pk_add_f32 v[34:35], v[46:47], v[40:41] neg_lo:[0,1] neg_hi:[0,1]
	v_cmp_neq_f32_e64 s[0:1], s2, v54
	v_add_f32_e32 v35, v52, v35
	v_add_f32_e32 v34, v34, v35
	v_add_f32_e32 v35, v39, v34
	v_mul_f32_e32 v52, v51, v35
	v_mul_f32_e32 v38, v49, v52
	v_fma_f32 v40, v52, v49, -v38
	v_fmac_f32_e32 v40, v52, v50
	v_sub_f32_e32 v39, v39, v35
	v_add_f32_e32 v49, v34, v39
	v_add_f32_e32 v34, v38, v40
	v_sub_f32_e32 v39, v35, v34
	v_pk_add_f32 v[46:47], v[34:35], v[38:39] neg_lo:[0,1] neg_hi:[0,1]
	v_mov_b32_e32 v41, v34
	v_pk_add_f32 v[34:35], v[46:47], v[40:41] neg_lo:[0,1] neg_hi:[0,1]
	s_nop 0
	v_add_f32_e32 v35, v49, v35
	v_add_f32_e32 v34, v34, v35
	v_add_f32_e32 v35, v53, v52
	v_add_f32_e32 v34, v39, v34
	v_sub_f32_e32 v38, v35, v53
	v_mul_f32_e32 v34, v51, v34
	v_sub_f32_e32 v38, v52, v38
	v_add_f32_e32 v38, v38, v34
	v_add_f32_e32 v40, v35, v38
	v_mul_f32_e32 v41, v40, v40
	v_fmamk_f32 v34, v41, 0x3e9b6dac, v206
	v_fmaak_f32 v179, v41, v34, 0x3f2aaada
	v_cvt_f32_i32_e32 v34, v48
	v_sub_f32_e32 v35, v40, v35
	v_sub_f32_e32 v35, v38, v35
	v_ldexp_f32 v46, v35, 1
	v_mul_f32_e32 v35, v40, v41
	v_ldexp_f32 v39, v40, 1
	v_pk_mul_f32 v[40:41], v[34:35], v[178:179]
	s_nop 0
	v_fma_f32 v38, v34, s69, -v40
	v_fmac_f32_e32 v38, 0xb102e308, v34
	v_pk_add_f32 v[34:35], v[40:41], v[38:39]
	s_nop 0
	v_sub_f32_e32 v39, v35, v39
	v_sub_f32_e32 v39, v41, v39
	v_add_f32_e32 v47, v46, v39
	v_mov_b32_e32 v46, v40
	v_pk_add_f32 v[40:41], v[34:35], v[40:41] neg_lo:[0,1] neg_hi:[0,1]
	v_pk_add_f32 v[48:49], v[34:35], v[46:47]
	v_mov_b32_e32 v39, v34
	v_mov_b32_e32 v41, v49
	v_pk_add_f32 v[50:51], v[38:39], v[40:41] neg_lo:[0,1] neg_hi:[0,1]
	v_pk_add_f32 v[38:39], v[38:39], v[40:41]
	v_mov_b32_e32 v46, v47
	v_pk_add_f32 v[40:41], v[38:39], v[34:35] op_sel:[1,0] op_sel_hi:[0,1] neg_lo:[0,1] neg_hi:[0,1]
	v_pk_add_f32 v[52:53], v[48:49], v[40:41] op_sel_hi:[1,0] neg_lo:[0,1] neg_hi:[0,1]
	v_mov_b32_e32 v48, v49
	v_mov_b32_e32 v49, v39
	v_pk_mov_b32 v[40:41], v[34:35], v[40:41] op_sel:[1,0]
	v_mov_b32_e32 v47, v34
	v_pk_add_f32 v[40:41], v[48:49], v[40:41] neg_lo:[0,1] neg_hi:[0,1]
	v_mov_b32_e32 v52, v50
	v_pk_add_f32 v[34:35], v[46:47], v[40:41] neg_lo:[0,1] neg_hi:[0,1]
	v_mov_b32_e32 v51, v39
	v_pk_add_f32 v[40:41], v[52:53], v[34:35]
	s_nop 0
	v_pk_add_f32 v[46:47], v[40:41], v[40:41] op_sel:[0,1] op_sel_hi:[1,0]
	s_nop 0
	v_pk_add_f32 v[38:39], v[38:39], v[46:47] op_sel:[1,0] op_sel_hi:[0,1]
	v_mov_b32_e32 v41, v38
	v_pk_add_f32 v[48:49], v[40:41], v[50:51] neg_lo:[0,1] neg_hi:[0,1]
	v_mov_b32_e32 v35, v46
	v_sub_f32_e32 v39, v40, v48
	v_pk_add_f32 v[34:35], v[34:35], v[48:49] neg_lo:[0,1] neg_hi:[0,1]
	v_sub_f32_e32 v39, v50, v39
	v_add_f32_e32 v34, v34, v39
	v_add_f32_e32 v34, v34, v35
	v_add_f32_e32 v34, v38, v34
	v_cndmask_b32_e64 v34, v208, v34, s[0:1]
	v_cmp_lt_f32_e64 s[0:1], |v54|, s66
	s_nop 1
	v_cndmask_b32_e64 v34, v34, v54, s[0:1]
	v_sub_f32_e32 v0, v0, v34
	v_lshl_add_u64 v[34:35], v[44:45], 0, v[74:75]
	v_lshlrev_b64 v[34:35], 14, v[34:35]
	v_lshl_add_u64 v[34:35], v[42:43], 0, v[34:35]
	global_store_dword v[34:35], v0, off
	s_or_b64 exec, exec, s[84:85]
	s_and_saveexec_b64 s[84:85], s[16:17]
	s_cbranch_execz .LBB0_552
;     __device__ __forceinline__ void operator()(const f32x4 (&acc)[2][2][4][2], const pg8::Unit& u, int wr, int wc, int fr, int fq) const {
;     ...
;             if (wc == 0) {
; #pragma unroll
;                 for (int ai = 0; ai < 2; ++ai)
; #pragma unroll
;                     for (int m = 0; m < 4; ++m) { const int row = row0 + ai * 128 + m * 16;
; #pragma unroll
;                         for (int n = 0; n < 2; ++n)
; #pragma unroll
;                             for (int j = 0; j < 4; ++j) { const int col = 8 * fq + 4 * n + j;
;                                 if (col < 12) { const float xv = acc[ai][0][m][n][j] * rsqrtf(ssq[row] * (1.f / DM) + EPS) + bfp[col]; LS[((size_t)(row >> 12) * 12 + col) * SEQ + (row & (SEQ - 1))] = fminf(xv, 0.f) - log1pf(expf(-fabsf(xv))); } } }
.LBB0_611:
	global_load_dword v0, v[66:67], off offset:192
	s_waitcnt vmcnt(0) lgkmcnt(0)
	v_fmamk_f32 v0, v0, 0x3a000000, v205
	v_cmp_gt_f32_e64 s[0:1], s68, v0
	v_mul_f32_e32 v34, 0x4b800000, v0
	s_nop 0
	v_cndmask_b32_e64 v0, v0, v34, s[0:1]
	v_rsq_f32_e32 v0, v0
	s_nop 0
	v_mul_f32_e32 v34, 0x45800000, v0
	v_cndmask_b32_e64 v0, v0, v34, s[0:1]
	v_lshl_add_u64 v[34:35], v[58:59], 2, s[60:61]
	global_load_dword v34, v[34:35], off
	s_waitcnt vmcnt(0) lgkmcnt(0)
	v_fmac_f32_e32 v34, v36, v0
	v_mul_f32_e64 v35, |v34|, s88
	v_fma_f32 v36, |v34|, s88, -v35
	v_rndne_f32_e32 v38, v35
	v_fma_f32 v36, |v34|, s89, v36
	v_sub_f32_e32 v35, v35, v38
	v_add_f32_e32 v35, v35, v36
	v_exp_f32_e32 v35, v35
	v_cvt_i32_f32_e32 v36, v38
	v_cmp_ngt_f32_e64 s[0:1], |v34|, s70
	v_min_f32_e32 v0, 0, v34
	v_ldexp_f32 v35, v35, v36
	v_cndmask_b32_e64 v35, 0, v35, s[0:1]
	v_cmp_nlt_f32_e64 s[0:1], |v34|, s90
	s_nop 1
	v_cndmask_b32_e64 v36, v208, v35, s[0:1]
	v_add_f32_e32 v38, 1.0, v36
	v_add_f32_e32 v34, -1.0, v38
	v_sub_f32_e32 v35, v34, v38
	v_add_f32_e32 v35, 1.0, v35
	v_sub_f32_e32 v34, v36, v34
	v_add_f32_e32 v39, v34, v35
	v_frexp_mant_f32_e32 v34, v38
	v_cmp_gt_f32_e64 s[0:1], s3, v34
	v_cvt_f64_f32_e32 v[34:35], v38
	v_frexp_exp_i32_f64_e32 v34, v[34:35]
	v_subbrev_co_u32_e64 v48, s[0:1], 0, v34, s[0:1]
	v_sub_u32_e32 v34, 0, v48
	v_ldexp_f32 v35, v38, v34
	v_add_f32_e32 v38, -1.0, v35
	v_add_f32_e32 v40, 1.0, v35
	v_ldexp_f32 v34, v39, v34
	v_add_f32_e32 v39, 1.0, v38
	v_add_f32_e32 v41, -1.0, v40
	v_sub_f32_e32 v39, v35, v39
	v_sub_f32_e32 v35, v35, v41
	v_add_f32_e32 v39, v34, v39
	v_add_f32_e32 v34, v34, v35
	v_add_f32_e32 v49, v40, v34
	v_rcp_f32_e32 v51, v49
	v_sub_f32_e32 v35, v40, v49
	v_add_f32_e32 v50, v34, v35
	v_add_f32_e32 v35, v38, v39
	v_mul_f32_e32 v53, v35, v51
	v_sub_f32_e32 v34, v38, v35
	v_mul_f32_e32 v38, v49, v53
	v_fma_f32 v40, v53, v49, -v38
	v_fmac_f32_e32 v40, v53, v50
	v_add_f32_e32 v52, v39, v34
	v_add_f32_e32 v34, v38, v40
	v_sub_f32_e32 v39, v35, v34
	v_pk_add_f32 v[46:47], v[34:35], v[38:39] neg_lo:[0,1] neg_hi:[0,1]
	v_mov_b32_e32 v41, v34
	v_pk_add_f32 v[34:35], v[46:47], v[40:41] neg_lo:[0,1] neg_hi:[0,1]
	v_cmp_neq_f32_e64 s[0:1], s2, v36
	v_add_f32_e32 v35, v52, v35
	v_add_f32_e32 v34, v34, v35
	v_add_f32_e32 v35, v39, v34
	v_mul_f32_e32 v52, v51, v35
	v_mul_f32_e32 v38, v49, v52
	v_fma_f32 v40, v52, v49, -v38
	v_fmac_f32_e32 v40, v52, v50
	v_sub_f32_e32 v39, v39, v35
	v_add_f32_e32 v49, v34, v39
	v_add_f32_e32 v34, v38, v40
	v_sub_f32_e32 v39, v35, v34
	v_pk_add_f32 v[46:47], v[34:35], v[38:39] neg_lo:[0,1] neg_hi:[0,1]
	v_mov_b32_e32 v41, v34
	v_pk_add_f32 v[34:35], v[46:47], v[40:41] neg_lo:[0,1] neg_hi:[0,1]
	s_nop 0
	v_add_f32_e32 v35, v49, v35
	v_add_f32_e32 v34, v34, v35
	v_add_f32_e32 v35, v53, v52
	v_add_f32_e32 v34, v39, v34
	v_sub_f32_e32 v38, v35, v53
	v_mul_f32_e32 v34, v51, v34
	v_sub_f32_e32 v38, v52, v38
	v_add_f32_e32 v38, v38, v34
	v_add_f32_e32 v40, v35, v38
	v_mul_f32_e32 v41, v40, v40
	v_fmamk_f32 v34, v41, 0x3e9b6dac, v206
	v_fmaak_f32 v179, v41, v34, 0x3f2aaada
	v_cvt_f32_i32_e32 v34, v48
	v_sub_f32_e32 v35, v40, v35
	v_sub_f32_e32 v35, v38, v35
	v_ldexp_f32 v46, v35, 1
	v_mul_f32_e32 v35, v40, v41
	v_ldexp_f32 v39, v40, 1
	v_pk_mul_f32 v[40:41], v[34:35], v[178:179]
	s_nop 0
	v_fma_f32 v38, v34, s69, -v40
	v_fmac_f32_e32 v38, 0xb102e308, v34
	v_pk_add_f32 v[34:35], v[40:41], v[38:39]
	s_nop 0
	v_sub_f32_e32 v39, v35, v39
	v_sub_f32_e32 v39, v41, v39
	v_add_f32_e32 v47, v46, v39
	v_mov_b32_e32 v46, v40
	v_pk_add_f32 v[40:41], v[34:35], v[40:41] neg_lo:[0,1] neg_hi:[0,1]
	v_pk_add_f32 v[48:49], v[34:35], v[46:47]
	v_mov_b32_e32 v39, v34
	v_mov_b32_e32 v41, v49
	v_pk_add_f32 v[50:51], v[38:39], v[40:41] neg_lo:[0,1] neg_hi:[0,1]
	v_pk_add_f32 v[38:39], v[38:39], v[40:41]
	v_mov_b32_e32 v46, v47
	v_pk_add_f32 v[40:41], v[38:39], v[34:35] op_sel:[1,0] op_sel_hi:[0,1] neg_lo:[0,1] neg_hi:[0,1]
	v_pk_add_f32 v[52:53], v[48:49], v[40:41] op_sel_hi:[1,0] neg_lo:[0,1] neg_hi:[0,1]
	v_mov_b32_e32 v48, v49
	v_mov_b32_e32 v49, v39
	v_pk_mov_b32 v[40:41], v[34:35], v[40:41] op_sel:[1,0]
	v_mov_b32_e32 v47, v34
	v_pk_add_f32 v[40:41], v[48:49], v[40:41] neg_lo:[0,1] neg_hi:[0,1]
	v_mov_b32_e32 v52, v50
	v_pk_add_f32 v[34:35], v[46:47], v[40:41] neg_lo:[0,1] neg_hi:[0,1]
	v_mov_b32_e32 v51, v39
	v_pk_add_f32 v[40:41], v[52:53], v[34:35]
	s_nop 0
	v_pk_add_f32 v[46:47], v[40:41], v[40:41] op_sel:[0,1] op_sel_hi:[1,0]
	s_nop 0
	v_pk_add_f32 v[38:39], v[38:39], v[46:47] op_sel:[1,0] op_sel_hi:[0,1]
	v_mov_b32_e32 v41, v38
	v_pk_add_f32 v[48:49], v[40:41], v[50:51] neg_lo:[0,1] neg_hi:[0,1]
	v_mov_b32_e32 v35, v46
	v_sub_f32_e32 v39, v40, v48
	v_pk_add_f32 v[34:35], v[34:35], v[48:49] neg_lo:[0,1] neg_hi:[0,1]
	v_sub_f32_e32 v39, v50, v39
	v_add_f32_e32 v34, v34, v39
	v_add_f32_e32 v34, v34, v35
	v_add_f32_e32 v34, v38, v34
	v_cndmask_b32_e64 v34, v208, v34, s[0:1]
	v_cmp_lt_f32_e64 s[0:1], |v36|, s66
	s_nop 1
	v_cndmask_b32_e64 v34, v34, v36, s[0:1]
	v_sub_f32_e32 v0, v0, v34
	v_lshl_add_u64 v[34:35], v[44:45], 0, v[58:59]
	v_lshlrev_b64 v[34:35], 14, v[34:35]
	v_lshl_add_u64 v[34:35], v[42:43], 0, v[34:35]
	global_store_dword v[34:35], v0, off
	s_or_b64 exec, exec, s[84:85]
	s_and_saveexec_b64 s[84:85], s[18:19]
	s_cbranch_execnz .LBB0_553
	s_branch .LBB0_554
;     __device__ __forceinline__ void operator()(const f32x4 (&acc)[2][2][4][2], const pg8::Unit& u, int wr, int wc, int fr, int fq) const {
;     ...
;             if (wc == 0) {
; #pragma unroll
;                 for (int ai = 0; ai < 2; ++ai)
; #pragma unroll
;                     for (int m = 0; m < 4; ++m) { const int row = row0 + ai * 128 + m * 16;
; #pragma unroll
;                         for (int n = 0; n < 2; ++n)
; #pragma unroll
;                             for (int j = 0; j < 4; ++j) { const int col = 8 * fq + 4 * n + j;
;                                 if (col < 12) { const float xv = acc[ai][0][m][n][j] * rsqrtf(ssq[row] * (1.f / DM) + EPS) + bfp[col]; LS[((size_t)(row >> 12) * 12 + col) * SEQ + (row & (SEQ - 1))] = fminf(xv, 0.f) - log1pf(expf(-fabsf(xv))); } } }
.LBB0_612:
	global_load_dword v0, v[66:67], off offset:512
	s_waitcnt vmcnt(0) lgkmcnt(0)
	v_fmamk_f32 v0, v0, 0x3a000000, v205
	v_cmp_gt_f32_e64 s[0:1], s68, v0
	v_mul_f32_e32 v38, 0x4b800000, v0
	s_nop 0
	v_cndmask_b32_e64 v0, v0, v38, s[0:1]
	v_rsq_f32_e32 v0, v0
	s_nop 0
	v_mul_f32_e32 v38, 0x45800000, v0
	v_cndmask_b32_e64 v0, v0, v38, s[0:1]
	v_lshl_add_u64 v[38:39], v[68:69], 2, s[60:61]
	global_load_dword v38, v[38:39], off
	s_waitcnt vmcnt(0) lgkmcnt(0)
	v_fmac_f32_e32 v38, v30, v0
	v_mul_f32_e64 v30, |v38|, s88
	v_fma_f32 v39, |v38|, s88, -v30
	v_rndne_f32_e32 v40, v30
	v_fma_f32 v39, |v38|, s89, v39
	v_sub_f32_e32 v30, v30, v40
	v_add_f32_e32 v30, v30, v39
	v_exp_f32_e32 v30, v30
	v_cvt_i32_f32_e32 v39, v40
	v_cmp_ngt_f32_e64 s[0:1], |v38|, s70
	v_min_f32_e32 v0, 0, v38
	v_ldexp_f32 v30, v30, v39
	v_cndmask_b32_e64 v30, 0, v30, s[0:1]
	v_cmp_nlt_f32_e64 s[0:1], |v38|, s90
	s_nop 1
	v_cndmask_b32_e64 v30, v208, v30, s[0:1]
	v_add_f32_e32 v40, 1.0, v30
	v_add_f32_e32 v38, -1.0, v40
	v_sub_f32_e32 v39, v38, v40
	v_add_f32_e32 v39, 1.0, v39
	v_sub_f32_e32 v38, v30, v38
	v_add_f32_e32 v41, v38, v39
	v_frexp_mant_f32_e32 v38, v40
	v_cmp_gt_f32_e64 s[0:1], s3, v38
	v_cvt_f64_f32_e32 v[38:39], v40
	v_frexp_exp_i32_f64_e32 v38, v[38:39]
	v_subbrev_co_u32_e64 v46, s[0:1], 0, v38, s[0:1]
	v_sub_u32_e32 v38, 0, v46
	v_ldexp_f32 v39, v40, v38
	v_add_f32_e32 v40, -1.0, v39
	v_add_f32_e32 v42, 1.0, v39
	v_ldexp_f32 v38, v41, v38
	v_add_f32_e32 v41, 1.0, v40
	v_add_f32_e32 v43, -1.0, v42
	v_sub_f32_e32 v41, v39, v41
	v_sub_f32_e32 v39, v39, v43
	v_add_f32_e32 v41, v38, v41
	v_add_f32_e32 v38, v38, v39
	v_add_f32_e32 v47, v42, v38
	v_rcp_f32_e32 v49, v47
	v_sub_f32_e32 v39, v42, v47
	v_add_f32_e32 v48, v38, v39
	v_add_f32_e32 v39, v40, v41
	v_mul_f32_e32 v51, v39, v49
	v_sub_f32_e32 v38, v40, v39
	v_mul_f32_e32 v40, v47, v51
	v_fma_f32 v42, v51, v47, -v40
	v_fmac_f32_e32 v42, v51, v48
	v_add_f32_e32 v50, v41, v38
	v_add_f32_e32 v38, v40, v42
	v_sub_f32_e32 v41, v39, v38
	v_pk_add_f32 v[44:45], v[38:39], v[40:41] neg_lo:[0,1] neg_hi:[0,1]
	v_mov_b32_e32 v43, v38
	v_pk_add_f32 v[38:39], v[44:45], v[42:43] neg_lo:[0,1] neg_hi:[0,1]
	v_cmp_neq_f32_e64 s[0:1], s2, v30
	v_add_f32_e32 v39, v50, v39
	v_add_f32_e32 v38, v38, v39
	v_add_f32_e32 v39, v41, v38
	v_mul_f32_e32 v50, v49, v39
	v_mul_f32_e32 v40, v47, v50
	v_fma_f32 v42, v50, v47, -v40
	v_fmac_f32_e32 v42, v50, v48
	v_sub_f32_e32 v41, v41, v39
	v_add_f32_e32 v47, v38, v41
	v_add_f32_e32 v38, v40, v42
	v_sub_f32_e32 v41, v39, v38
	v_pk_add_f32 v[44:45], v[38:39], v[40:41] neg_lo:[0,1] neg_hi:[0,1]
	v_mov_b32_e32 v43, v38
	v_pk_add_f32 v[38:39], v[44:45], v[42:43] neg_lo:[0,1] neg_hi:[0,1]
	s_nop 0
	v_add_f32_e32 v39, v47, v39
	v_add_f32_e32 v38, v38, v39
	v_add_f32_e32 v39, v51, v50
	v_add_f32_e32 v38, v41, v38
	v_sub_f32_e32 v40, v39, v51
	v_mul_f32_e32 v38, v49, v38
	v_sub_f32_e32 v40, v50, v40
	v_add_f32_e32 v40, v40, v38
	v_add_f32_e32 v42, v39, v40
	v_mul_f32_e32 v43, v42, v42
	v_fmamk_f32 v38, v43, 0x3e9b6dac, v206
	v_fmaak_f32 v179, v43, v38, 0x3f2aaada
	v_cvt_f32_i32_e32 v38, v46
	v_sub_f32_e32 v39, v42, v39
	v_sub_f32_e32 v39, v40, v39
	v_ldexp_f32 v44, v39, 1
	v_mul_f32_e32 v39, v42, v43
	v_ldexp_f32 v41, v42, 1
	v_pk_mul_f32 v[42:43], v[38:39], v[178:179]
	s_nop 0
	v_fma_f32 v40, v38, s69, -v42
	v_fmac_f32_e32 v40, 0xb102e308, v38
	v_pk_add_f32 v[38:39], v[42:43], v[40:41]
	s_nop 0
	v_sub_f32_e32 v41, v39, v41
	v_sub_f32_e32 v41, v43, v41
	v_add_f32_e32 v45, v44, v41
	v_mov_b32_e32 v44, v42
	v_pk_add_f32 v[42:43], v[38:39], v[42:43] neg_lo:[0,1] neg_hi:[0,1]
	v_pk_add_f32 v[46:47], v[38:39], v[44:45]
	v_mov_b32_e32 v41, v38
	v_mov_b32_e32 v43, v47
	v_pk_add_f32 v[48:49], v[40:41], v[42:43] neg_lo:[0,1] neg_hi:[0,1]
	v_pk_add_f32 v[40:41], v[40:41], v[42:43]
	v_mov_b32_e32 v44, v45
	v_pk_add_f32 v[42:43], v[40:41], v[38:39] op_sel:[1,0] op_sel_hi:[0,1] neg_lo:[0,1] neg_hi:[0,1]
	v_pk_add_f32 v[50:51], v[46:47], v[42:43] op_sel_hi:[1,0] neg_lo:[0,1] neg_hi:[0,1]
	v_mov_b32_e32 v46, v47
	v_mov_b32_e32 v47, v41
	v_pk_mov_b32 v[42:43], v[38:39], v[42:43] op_sel:[1,0]
	v_mov_b32_e32 v45, v38
	v_pk_add_f32 v[42:43], v[46:47], v[42:43] neg_lo:[0,1] neg_hi:[0,1]
	v_mov_b32_e32 v50, v48
	v_pk_add_f32 v[38:39], v[44:45], v[42:43] neg_lo:[0,1] neg_hi:[0,1]
	v_mov_b32_e32 v49, v41
	v_pk_add_f32 v[42:43], v[50:51], v[38:39]
	s_nop 0
	v_pk_add_f32 v[44:45], v[42:43], v[42:43] op_sel:[0,1] op_sel_hi:[1,0]
	s_nop 0
	v_pk_add_f32 v[40:41], v[40:41], v[44:45] op_sel:[1,0] op_sel_hi:[0,1]
	v_mov_b32_e32 v43, v40
	v_pk_add_f32 v[46:47], v[42:43], v[48:49] neg_lo:[0,1] neg_hi:[0,1]
	v_mov_b32_e32 v39, v44
	v_sub_f32_e32 v41, v42, v46
	v_pk_add_f32 v[38:39], v[38:39], v[46:47] neg_lo:[0,1] neg_hi:[0,1]
	v_sub_f32_e32 v41, v48, v41
	v_add_f32_e32 v38, v38, v41
	v_add_f32_e32 v38, v38, v39
	v_add_f32_e32 v38, v40, v38
	v_cndmask_b32_e64 v38, v208, v38, s[0:1]
	v_cmp_lt_f32_e64 s[0:1], |v30|, s66
	s_nop 1
	v_cndmask_b32_e64 v30, v38, v30, s[0:1]
	v_lshl_add_u64 v[38:39], v[36:37], 0, v[68:69]
	v_lshlrev_b64 v[38:39], 14, v[38:39]
	v_sub_f32_e32 v0, v0, v30
	v_lshl_add_u64 v[38:39], v[34:35], 0, v[38:39]
	global_store_dword v[38:39], v0, off
	s_or_b64 exec, exec, s[84:85]
	s_and_saveexec_b64 s[84:85], s[6:7]
	s_cbranch_execz .LBB0_556
;     __device__ __forceinline__ void operator()(const f32x4 (&acc)[2][2][4][2], const pg8::Unit& u, int wr, int wc, int fr, int fq) const {
;     ...
;             if (wc == 0) {
; #pragma unroll
;                 for (int ai = 0; ai < 2; ++ai)
; #pragma unroll
;                     for (int m = 0; m < 4; ++m) { const int row = row0 + ai * 128 + m * 16;
; #pragma unroll
;                         for (int n = 0; n < 2; ++n)
; #pragma unroll
;                             for (int j = 0; j < 4; ++j) { const int col = 8 * fq + 4 * n + j;
;                                 if (col < 12) { const float xv = acc[ai][0][m][n][j] * rsqrtf(ssq[row] * (1.f / DM) + EPS) + bfp[col]; LS[((size_t)(row >> 12) * 12 + col) * SEQ + (row & (SEQ - 1))] = fminf(xv, 0.f) - log1pf(expf(-fabsf(xv))); } } }
.LBB0_613:
	global_load_dword v0, v[66:67], off offset:512
	v_lshl_add_u64 v[38:39], v[70:71], 2, s[60:61]
	s_waitcnt vmcnt(0) lgkmcnt(0)
	v_fmamk_f32 v0, v0, 0x3a000000, v205
	v_cmp_gt_f32_e64 s[0:1], s68, v0
	v_mul_f32_e32 v30, 0x4b800000, v0
	s_nop 0
	v_cndmask_b32_e64 v0, v0, v30, s[0:1]
	v_rsq_f32_e32 v0, v0
	s_nop 0
	v_mul_f32_e32 v30, 0x45800000, v0
	v_cndmask_b32_e64 v0, v0, v30, s[0:1]
	global_load_dword v30, v[38:39], off
	s_waitcnt vmcnt(0) lgkmcnt(0)
	v_fmac_f32_e32 v30, v31, v0
	v_mul_f32_e64 v31, |v30|, s88
	v_fma_f32 v38, |v30|, s88, -v31
	v_rndne_f32_e32 v39, v31
	v_fma_f32 v38, |v30|, s89, v38
	v_sub_f32_e32 v31, v31, v39
	v_add_f32_e32 v31, v31, v38
	v_exp_f32_e32 v31, v31
	v_cvt_i32_f32_e32 v38, v39
	v_cmp_ngt_f32_e64 s[0:1], |v30|, s70
	v_min_f32_e32 v0, 0, v30
	v_ldexp_f32 v31, v31, v38
	v_cndmask_b32_e64 v31, 0, v31, s[0:1]
	v_cmp_nlt_f32_e64 s[0:1], |v30|, s90
	s_nop 1
	v_cndmask_b32_e64 v50, v208, v31, s[0:1]
	v_add_f32_e32 v38, 1.0, v50
	v_add_f32_e32 v30, -1.0, v38
	v_sub_f32_e32 v31, v30, v38
	v_add_f32_e32 v31, 1.0, v31
	v_sub_f32_e32 v30, v50, v30
	v_add_f32_e32 v39, v30, v31
	v_frexp_mant_f32_e32 v30, v38
	v_cmp_gt_f32_e64 s[0:1], s3, v30
	v_cvt_f64_f32_e32 v[30:31], v38
	v_frexp_exp_i32_f64_e32 v30, v[30:31]
	v_subbrev_co_u32_e64 v44, s[0:1], 0, v30, s[0:1]
	v_sub_u32_e32 v30, 0, v44
	v_ldexp_f32 v31, v38, v30
	v_add_f32_e32 v38, -1.0, v31
	v_add_f32_e32 v40, 1.0, v31
	v_ldexp_f32 v30, v39, v30
	v_add_f32_e32 v39, 1.0, v38
	v_add_f32_e32 v41, -1.0, v40
	v_sub_f32_e32 v39, v31, v39
	v_sub_f32_e32 v31, v31, v41
	v_add_f32_e32 v39, v30, v39
	v_add_f32_e32 v30, v30, v31
	v_add_f32_e32 v45, v40, v30
	v_rcp_f32_e32 v47, v45
	v_sub_f32_e32 v31, v40, v45
	v_add_f32_e32 v46, v30, v31
	v_add_f32_e32 v31, v38, v39
	v_mul_f32_e32 v49, v31, v47
	v_sub_f32_e32 v30, v38, v31
	v_mul_f32_e32 v38, v45, v49
	v_fma_f32 v40, v49, v45, -v38
	v_fmac_f32_e32 v40, v49, v46
	v_add_f32_e32 v48, v39, v30
	v_add_f32_e32 v30, v38, v40
	v_sub_f32_e32 v39, v31, v30
	v_pk_add_f32 v[42:43], v[30:31], v[38:39] neg_lo:[0,1] neg_hi:[0,1]
	v_mov_b32_e32 v41, v30
	v_pk_add_f32 v[30:31], v[42:43], v[40:41] neg_lo:[0,1] neg_hi:[0,1]
	v_cmp_neq_f32_e64 s[0:1], s2, v50
	v_add_f32_e32 v31, v48, v31
	v_add_f32_e32 v30, v30, v31
	v_add_f32_e32 v31, v39, v30
	v_mul_f32_e32 v48, v47, v31
	v_mul_f32_e32 v38, v45, v48
	v_fma_f32 v40, v48, v45, -v38
	v_fmac_f32_e32 v40, v48, v46
	v_sub_f32_e32 v39, v39, v31
	v_add_f32_e32 v45, v30, v39
	v_add_f32_e32 v30, v38, v40
	v_sub_f32_e32 v39, v31, v30
	v_pk_add_f32 v[42:43], v[30:31], v[38:39] neg_lo:[0,1] neg_hi:[0,1]
	v_mov_b32_e32 v41, v30
	v_pk_add_f32 v[30:31], v[42:43], v[40:41] neg_lo:[0,1] neg_hi:[0,1]
	s_nop 0
	v_add_f32_e32 v31, v45, v31
	v_add_f32_e32 v30, v30, v31
	v_add_f32_e32 v31, v49, v48
	v_add_f32_e32 v30, v39, v30
	v_sub_f32_e32 v38, v31, v49
	v_mul_f32_e32 v30, v47, v30
	v_sub_f32_e32 v38, v48, v38
	v_add_f32_e32 v38, v38, v30
	v_add_f32_e32 v40, v31, v38
	v_mul_f32_e32 v41, v40, v40
	v_fmamk_f32 v30, v41, 0x3e9b6dac, v206
	v_fmaak_f32 v179, v41, v30, 0x3f2aaada
	v_cvt_f32_i32_e32 v30, v44
	v_sub_f32_e32 v31, v40, v31
	v_sub_f32_e32 v31, v38, v31
	v_ldexp_f32 v42, v31, 1
	v_mul_f32_e32 v31, v40, v41
	v_ldexp_f32 v39, v40, 1
	v_pk_mul_f32 v[40:41], v[30:31], v[178:179]
	s_nop 0
	v_fma_f32 v38, v30, s69, -v40
	v_fmac_f32_e32 v38, 0xb102e308, v30
	v_pk_add_f32 v[30:31], v[40:41], v[38:39]
	s_nop 0
	v_sub_f32_e32 v39, v31, v39
	v_sub_f32_e32 v39, v41, v39
	v_add_f32_e32 v43, v42, v39
	v_mov_b32_e32 v42, v40
	v_pk_add_f32 v[40:41], v[30:31], v[40:41] neg_lo:[0,1] neg_hi:[0,1]
	v_pk_add_f32 v[44:45], v[30:31], v[42:43]
	v_mov_b32_e32 v39, v30
	v_mov_b32_e32 v41, v45
	v_pk_add_f32 v[46:47], v[38:39], v[40:41] neg_lo:[0,1] neg_hi:[0,1]
	v_pk_add_f32 v[38:39], v[38:39], v[40:41]
	v_mov_b32_e32 v42, v43
	v_pk_add_f32 v[40:41], v[38:39], v[30:31] op_sel:[1,0] op_sel_hi:[0,1] neg_lo:[0,1] neg_hi:[0,1]
	v_pk_add_f32 v[48:49], v[44:45], v[40:41] op_sel_hi:[1,0] neg_lo:[0,1] neg_hi:[0,1]
	v_mov_b32_e32 v44, v45
	v_mov_b32_e32 v45, v39
	v_pk_mov_b32 v[40:41], v[30:31], v[40:41] op_sel:[1,0]
	v_mov_b32_e32 v43, v30
	v_pk_add_f32 v[40:41], v[44:45], v[40:41] neg_lo:[0,1] neg_hi:[0,1]
	v_mov_b32_e32 v48, v46
	v_pk_add_f32 v[30:31], v[42:43], v[40:41] neg_lo:[0,1] neg_hi:[0,1]
	v_mov_b32_e32 v47, v39
	v_pk_add_f32 v[40:41], v[48:49], v[30:31]
	s_nop 0
	v_pk_add_f32 v[42:43], v[40:41], v[40:41] op_sel:[0,1] op_sel_hi:[1,0]
	s_nop 0
	v_pk_add_f32 v[38:39], v[38:39], v[42:43] op_sel:[1,0] op_sel_hi:[0,1]
	v_mov_b32_e32 v41, v38
	v_pk_add_f32 v[44:45], v[40:41], v[46:47] neg_lo:[0,1] neg_hi:[0,1]
	v_mov_b32_e32 v31, v42
	v_sub_f32_e32 v39, v40, v44
	v_pk_add_f32 v[30:31], v[30:31], v[44:45] neg_lo:[0,1] neg_hi:[0,1]
	v_sub_f32_e32 v39, v46, v39
	v_add_f32_e32 v30, v30, v39
	v_add_f32_e32 v30, v30, v31
	v_add_f32_e32 v30, v38, v30
	v_cndmask_b32_e64 v30, v208, v30, s[0:1]
	v_cmp_lt_f32_e64 s[0:1], |v50|, s66
	s_nop 1
	v_cndmask_b32_e64 v30, v30, v50, s[0:1]
	v_sub_f32_e32 v0, v0, v30
	v_lshl_add_u64 v[30:31], v[36:37], 0, v[70:71]
	v_lshlrev_b64 v[30:31], 14, v[30:31]
	v_lshl_add_u64 v[30:31], v[34:35], 0, v[30:31]
	global_store_dword v[30:31], v0, off
	s_or_b64 exec, exec, s[84:85]
	s_and_saveexec_b64 s[84:85], s[8:9]
	s_cbranch_execz .LBB0_557
;     __device__ __forceinline__ void operator()(const f32x4 (&acc)[2][2][4][2], const pg8::Unit& u, int wr, int wc, int fr, int fq) const {
;     ...
;             if (wc == 0) {
; #pragma unroll
;                 for (int ai = 0; ai < 2; ++ai)
; #pragma unroll
;                     for (int m = 0; m < 4; ++m) { const int row = row0 + ai * 128 + m * 16;
; #pragma unroll
;                         for (int n = 0; n < 2; ++n)
; #pragma unroll
;                             for (int j = 0; j < 4; ++j) { const int col = 8 * fq + 4 * n + j;
;                                 if (col < 12) { const float xv = acc[ai][0][m][n][j] * rsqrtf(ssq[row] * (1.f / DM) + EPS) + bfp[col]; LS[((size_t)(row >> 12) * 12 + col) * SEQ + (row & (SEQ - 1))] = fminf(xv, 0.f) - log1pf(expf(-fabsf(xv))); } } }
.LBB0_614:
	global_load_dword v0, v[66:67], off offset:512
	s_waitcnt vmcnt(0) lgkmcnt(0)
	v_fmamk_f32 v0, v0, 0x3a000000, v205
	v_cmp_gt_f32_e64 s[0:1], s68, v0
	v_mul_f32_e32 v30, 0x4b800000, v0
	s_nop 0
	v_cndmask_b32_e64 v0, v0, v30, s[0:1]
	v_rsq_f32_e32 v0, v0
	s_nop 0
	v_mul_f32_e32 v30, 0x45800000, v0
	v_cndmask_b32_e64 v0, v0, v30, s[0:1]
	v_lshl_add_u64 v[30:31], v[62:63], 2, s[60:61]
	global_load_dword v30, v[30:31], off
	s_waitcnt vmcnt(0) lgkmcnt(0)
	v_fmac_f32_e32 v30, v32, v0
	v_mul_f32_e64 v31, |v30|, s88
	v_fma_f32 v32, |v30|, s88, -v31
	v_rndne_f32_e32 v38, v31
	v_fma_f32 v32, |v30|, s89, v32
	v_sub_f32_e32 v31, v31, v38
	v_add_f32_e32 v31, v31, v32
	v_exp_f32_e32 v31, v31
	v_cvt_i32_f32_e32 v32, v38
	v_cmp_ngt_f32_e64 s[0:1], |v30|, s70
	v_min_f32_e32 v0, 0, v30
	v_ldexp_f32 v31, v31, v32
	v_cndmask_b32_e64 v31, 0, v31, s[0:1]
	v_cmp_nlt_f32_e64 s[0:1], |v30|, s90
	s_nop 1
	v_cndmask_b32_e64 v32, v208, v31, s[0:1]
	v_add_f32_e32 v38, 1.0, v32
	v_add_f32_e32 v30, -1.0, v38
	v_sub_f32_e32 v31, v30, v38
	v_add_f32_e32 v31, 1.0, v31
	v_sub_f32_e32 v30, v32, v30
	v_add_f32_e32 v39, v30, v31
	v_frexp_mant_f32_e32 v30, v38
	v_cmp_gt_f32_e64 s[0:1], s3, v30
	v_cvt_f64_f32_e32 v[30:31], v38
	v_frexp_exp_i32_f64_e32 v30, v[30:31]
	v_subbrev_co_u32_e64 v44, s[0:1], 0, v30, s[0:1]
	v_sub_u32_e32 v30, 0, v44
	v_ldexp_f32 v31, v38, v30
	v_add_f32_e32 v38, -1.0, v31
	v_add_f32_e32 v40, 1.0, v31
	v_ldexp_f32 v30, v39, v30
	v_add_f32_e32 v39, 1.0, v38
	v_add_f32_e32 v41, -1.0, v40
	v_sub_f32_e32 v39, v31, v39
	v_sub_f32_e32 v31, v31, v41
	v_add_f32_e32 v39, v30, v39
	v_add_f32_e32 v30, v30, v31
	v_add_f32_e32 v45, v40, v30
	v_rcp_f32_e32 v47, v45
	v_sub_f32_e32 v31, v40, v45
	v_add_f32_e32 v46, v30, v31
	v_add_f32_e32 v31, v38, v39
	v_mul_f32_e32 v49, v31, v47
	v_sub_f32_e32 v30, v38, v31
	v_mul_f32_e32 v38, v45, v49
	v_fma_f32 v40, v49, v45, -v38
	v_fmac_f32_e32 v40, v49, v46
	v_add_f32_e32 v48, v39, v30
	v_add_f32_e32 v30, v38, v40
	v_sub_f32_e32 v39, v31, v30
	v_pk_add_f32 v[42:43], v[30:31], v[38:39] neg_lo:[0,1] neg_hi:[0,1]
	v_mov_b32_e32 v41, v30
	v_pk_add_f32 v[30:31], v[42:43], v[40:41] neg_lo:[0,1] neg_hi:[0,1]
	v_cmp_neq_f32_e64 s[0:1], s2, v32
	v_add_f32_e32 v31, v48, v31
	v_add_f32_e32 v30, v30, v31
	v_add_f32_e32 v31, v39, v30
	v_mul_f32_e32 v48, v47, v31
	v_mul_f32_e32 v38, v45, v48
	v_fma_f32 v40, v48, v45, -v38
	v_fmac_f32_e32 v40, v48, v46
	v_sub_f32_e32 v39, v39, v31
	v_add_f32_e32 v45, v30, v39
	v_add_f32_e32 v30, v38, v40
	v_sub_f32_e32 v39, v31, v30
	v_pk_add_f32 v[42:43], v[30:31], v[38:39] neg_lo:[0,1] neg_hi:[0,1]
	v_mov_b32_e32 v41, v30
	v_pk_add_f32 v[30:31], v[42:43], v[40:41] neg_lo:[0,1] neg_hi:[0,1]
	s_nop 0
	v_add_f32_e32 v31, v45, v31
	v_add_f32_e32 v30, v30, v31
	v_add_f32_e32 v31, v49, v48
	v_add_f32_e32 v30, v39, v30
	v_sub_f32_e32 v38, v31, v49
	v_mul_f32_e32 v30, v47, v30
	v_sub_f32_e32 v38, v48, v38
	v_add_f32_e32 v38, v38, v30
	v_add_f32_e32 v40, v31, v38
	v_mul_f32_e32 v41, v40, v40
	v_fmamk_f32 v30, v41, 0x3e9b6dac, v206
	v_fmaak_f32 v179, v41, v30, 0x3f2aaada
	v_cvt_f32_i32_e32 v30, v44
	v_sub_f32_e32 v31, v40, v31
	v_sub_f32_e32 v31, v38, v31
	v_ldexp_f32 v42, v31, 1
	v_mul_f32_e32 v31, v40, v41
	v_ldexp_f32 v39, v40, 1
	v_pk_mul_f32 v[40:41], v[30:31], v[178:179]
	s_nop 0
	v_fma_f32 v38, v30, s69, -v40
	v_fmac_f32_e32 v38, 0xb102e308, v30
	v_pk_add_f32 v[30:31], v[40:41], v[38:39]
	s_nop 0
	v_sub_f32_e32 v39, v31, v39
	v_sub_f32_e32 v39, v41, v39
	v_add_f32_e32 v43, v42, v39
	v_mov_b32_e32 v42, v40
	v_pk_add_f32 v[40:41], v[30:31], v[40:41] neg_lo:[0,1] neg_hi:[0,1]
	v_pk_add_f32 v[44:45], v[30:31], v[42:43]
	v_mov_b32_e32 v39, v30
	v_mov_b32_e32 v41, v45
	v_pk_add_f32 v[46:47], v[38:39], v[40:41] neg_lo:[0,1] neg_hi:[0,1]
	v_pk_add_f32 v[38:39], v[38:39], v[40:41]
	v_mov_b32_e32 v42, v43
	v_pk_add_f32 v[40:41], v[38:39], v[30:31] op_sel:[1,0] op_sel_hi:[0,1] neg_lo:[0,1] neg_hi:[0,1]
	v_pk_add_f32 v[48:49], v[44:45], v[40:41] op_sel_hi:[1,0] neg_lo:[0,1] neg_hi:[0,1]
	v_mov_b32_e32 v44, v45
	v_mov_b32_e32 v45, v39
	v_pk_mov_b32 v[40:41], v[30:31], v[40:41] op_sel:[1,0]
	v_mov_b32_e32 v43, v30
	v_pk_add_f32 v[40:41], v[44:45], v[40:41] neg_lo:[0,1] neg_hi:[0,1]
	v_mov_b32_e32 v48, v46
	v_pk_add_f32 v[30:31], v[42:43], v[40:41] neg_lo:[0,1] neg_hi:[0,1]
	v_mov_b32_e32 v47, v39
	v_pk_add_f32 v[40:41], v[48:49], v[30:31]
	s_nop 0
	v_pk_add_f32 v[42:43], v[40:41], v[40:41] op_sel:[0,1] op_sel_hi:[1,0]
	s_nop 0
	v_pk_add_f32 v[38:39], v[38:39], v[42:43] op_sel:[1,0] op_sel_hi:[0,1]
	v_mov_b32_e32 v41, v38
	v_pk_add_f32 v[44:45], v[40:41], v[46:47] neg_lo:[0,1] neg_hi:[0,1]
	v_mov_b32_e32 v31, v42
	v_sub_f32_e32 v39, v40, v44
	v_pk_add_f32 v[30:31], v[30:31], v[44:45] neg_lo:[0,1] neg_hi:[0,1]
	v_sub_f32_e32 v39, v46, v39
	v_add_f32_e32 v30, v30, v39
	v_add_f32_e32 v30, v30, v31
	v_add_f32_e32 v30, v38, v30
	v_cndmask_b32_e64 v30, v208, v30, s[0:1]
	v_cmp_lt_f32_e64 s[0:1], |v32|, s66
	s_nop 1
	v_cndmask_b32_e64 v30, v30, v32, s[0:1]
	v_sub_f32_e32 v0, v0, v30
	v_lshl_add_u64 v[30:31], v[36:37], 0, v[62:63]
	v_lshlrev_b64 v[30:31], 14, v[30:31]
	v_lshl_add_u64 v[30:31], v[34:35], 0, v[30:31]
	global_store_dword v[30:31], v0, off
	s_or_b64 exec, exec, s[84:85]
	s_and_saveexec_b64 s[84:85], s[10:11]
	s_cbranch_execz .LBB0_558
;     __device__ __forceinline__ void operator()(const f32x4 (&acc)[2][2][4][2], const pg8::Unit& u, int wr, int wc, int fr, int fq) const {
;     ...
;             if (wc == 0) {
; #pragma unroll
;                 for (int ai = 0; ai < 2; ++ai)
; #pragma unroll
;                     for (int m = 0; m < 4; ++m) { const int row = row0 + ai * 128 + m * 16;
; #pragma unroll
;                         for (int n = 0; n < 2; ++n)
; #pragma unroll
;                             for (int j = 0; j < 4; ++j) { const int col = 8 * fq + 4 * n + j;
;                                 if (col < 12) { const float xv = acc[ai][0][m][n][j] * rsqrtf(ssq[row] * (1.f / DM) + EPS) + bfp[col]; LS[((size_t)(row >> 12) * 12 + col) * SEQ + (row & (SEQ - 1))] = fminf(xv, 0.f) - log1pf(expf(-fabsf(xv))); } } }
.LBB0_615:
	global_load_dword v0, v[66:67], off offset:512
	s_waitcnt vmcnt(0) lgkmcnt(0)
	v_fmamk_f32 v0, v0, 0x3a000000, v205
	v_cmp_gt_f32_e64 s[0:1], s68, v0
	v_mul_f32_e32 v30, 0x4b800000, v0
	s_nop 0
	v_cndmask_b32_e64 v0, v0, v30, s[0:1]
	v_rsq_f32_e32 v0, v0
	s_nop 0
	v_mul_f32_e32 v30, 0x45800000, v0
	v_cndmask_b32_e64 v0, v0, v30, s[0:1]
	v_lshl_add_u64 v[30:31], v[72:73], 2, s[60:61]
	global_load_dword v30, v[30:31], off
	s_waitcnt vmcnt(0) lgkmcnt(0)
	v_fmac_f32_e32 v30, v33, v0
	v_mul_f32_e64 v31, |v30|, s88
	v_fma_f32 v32, |v30|, s88, -v31
	v_rndne_f32_e32 v33, v31
	v_fma_f32 v32, |v30|, s89, v32
	v_sub_f32_e32 v31, v31, v33
	v_add_f32_e32 v31, v31, v32
	v_exp_f32_e32 v31, v31
	v_cvt_i32_f32_e32 v32, v33
	v_cmp_ngt_f32_e64 s[0:1], |v30|, s70
	v_min_f32_e32 v0, 0, v30
	v_ldexp_f32 v31, v31, v32
	v_cndmask_b32_e64 v31, 0, v31, s[0:1]
	v_cmp_nlt_f32_e64 s[0:1], |v30|, s90
	s_nop 1
	v_cndmask_b32_e64 v48, v208, v31, s[0:1]
	v_add_f32_e32 v32, 1.0, v48
	v_add_f32_e32 v30, -1.0, v32
	v_sub_f32_e32 v31, v30, v32
	v_add_f32_e32 v31, 1.0, v31
	v_sub_f32_e32 v30, v48, v30
	v_add_f32_e32 v33, v30, v31
	v_frexp_mant_f32_e32 v30, v32
	v_cmp_gt_f32_e64 s[0:1], s3, v30
	v_cvt_f64_f32_e32 v[30:31], v32
	v_frexp_exp_i32_f64_e32 v30, v[30:31]
	v_subbrev_co_u32_e64 v42, s[0:1], 0, v30, s[0:1]
	v_sub_u32_e32 v30, 0, v42
	v_ldexp_f32 v31, v32, v30
	v_add_f32_e32 v32, -1.0, v31
	v_add_f32_e32 v38, 1.0, v31
	v_ldexp_f32 v30, v33, v30
	v_add_f32_e32 v33, 1.0, v32
	v_add_f32_e32 v39, -1.0, v38
	v_sub_f32_e32 v33, v31, v33
	v_sub_f32_e32 v31, v31, v39
	v_add_f32_e32 v33, v30, v33
	v_add_f32_e32 v30, v30, v31
	v_add_f32_e32 v43, v38, v30
	v_rcp_f32_e32 v45, v43
	v_sub_f32_e32 v31, v38, v43
	v_add_f32_e32 v44, v30, v31
	v_add_f32_e32 v31, v32, v33
	v_mul_f32_e32 v47, v31, v45
	v_sub_f32_e32 v30, v32, v31
	v_mul_f32_e32 v32, v43, v47
	v_fma_f32 v38, v47, v43, -v32
	v_fmac_f32_e32 v38, v47, v44
	v_add_f32_e32 v46, v33, v30
	v_add_f32_e32 v30, v32, v38
	v_sub_f32_e32 v33, v31, v30
	v_pk_add_f32 v[40:41], v[30:31], v[32:33] neg_lo:[0,1] neg_hi:[0,1]
	v_mov_b32_e32 v39, v30
	v_pk_add_f32 v[30:31], v[40:41], v[38:39] neg_lo:[0,1] neg_hi:[0,1]
	v_cmp_neq_f32_e64 s[0:1], s2, v48
	v_add_f32_e32 v31, v46, v31
	v_add_f32_e32 v30, v30, v31
	v_add_f32_e32 v31, v33, v30
	v_mul_f32_e32 v46, v45, v31
	v_mul_f32_e32 v32, v43, v46
	v_fma_f32 v38, v46, v43, -v32
	v_fmac_f32_e32 v38, v46, v44
	v_sub_f32_e32 v33, v33, v31
	v_add_f32_e32 v43, v30, v33
	v_add_f32_e32 v30, v32, v38
	v_sub_f32_e32 v33, v31, v30
	v_pk_add_f32 v[40:41], v[30:31], v[32:33] neg_lo:[0,1] neg_hi:[0,1]
	v_mov_b32_e32 v39, v30
	v_pk_add_f32 v[30:31], v[40:41], v[38:39] neg_lo:[0,1] neg_hi:[0,1]
	s_nop 0
	v_add_f32_e32 v31, v43, v31
	v_add_f32_e32 v30, v30, v31
	v_add_f32_e32 v31, v47, v46
	v_add_f32_e32 v30, v33, v30
	v_sub_f32_e32 v32, v31, v47
	v_mul_f32_e32 v30, v45, v30
	v_sub_f32_e32 v32, v46, v32
	v_add_f32_e32 v32, v32, v30
	v_add_f32_e32 v38, v31, v32
	v_mul_f32_e32 v39, v38, v38
	v_fmamk_f32 v30, v39, 0x3e9b6dac, v206
	v_fmaak_f32 v179, v39, v30, 0x3f2aaada
	v_cvt_f32_i32_e32 v30, v42
	v_sub_f32_e32 v31, v38, v31
	v_sub_f32_e32 v31, v32, v31
	v_ldexp_f32 v40, v31, 1
	v_mul_f32_e32 v31, v38, v39
	v_ldexp_f32 v33, v38, 1
	v_pk_mul_f32 v[38:39], v[30:31], v[178:179]
	s_nop 0
	v_fma_f32 v32, v30, s69, -v38
	v_fmac_f32_e32 v32, 0xb102e308, v30
	v_pk_add_f32 v[30:31], v[38:39], v[32:33]
	s_nop 0
	v_sub_f32_e32 v33, v31, v33
	v_sub_f32_e32 v33, v39, v33
	v_add_f32_e32 v41, v40, v33
	v_mov_b32_e32 v40, v38
	v_pk_add_f32 v[38:39], v[30:31], v[38:39] neg_lo:[0,1] neg_hi:[0,1]
	v_pk_add_f32 v[42:43], v[30:31], v[40:41]
	v_mov_b32_e32 v33, v30
	v_mov_b32_e32 v39, v43
	v_pk_add_f32 v[44:45], v[32:33], v[38:39] neg_lo:[0,1] neg_hi:[0,1]
	v_pk_add_f32 v[32:33], v[32:33], v[38:39]
	v_mov_b32_e32 v40, v41
	v_pk_add_f32 v[38:39], v[32:33], v[30:31] op_sel:[1,0] op_sel_hi:[0,1] neg_lo:[0,1] neg_hi:[0,1]
	v_pk_add_f32 v[46:47], v[42:43], v[38:39] op_sel_hi:[1,0] neg_lo:[0,1] neg_hi:[0,1]
	v_mov_b32_e32 v42, v43
	v_mov_b32_e32 v43, v33
	v_pk_mov_b32 v[38:39], v[30:31], v[38:39] op_sel:[1,0]
	v_mov_b32_e32 v41, v30
	v_pk_add_f32 v[38:39], v[42:43], v[38:39] neg_lo:[0,1] neg_hi:[0,1]
	v_mov_b32_e32 v46, v44
	v_pk_add_f32 v[30:31], v[40:41], v[38:39] neg_lo:[0,1] neg_hi:[0,1]
	v_mov_b32_e32 v45, v33
	v_pk_add_f32 v[38:39], v[46:47], v[30:31]
	s_nop 0
	v_pk_add_f32 v[40:41], v[38:39], v[38:39] op_sel:[0,1] op_sel_hi:[1,0]
	s_nop 0
	v_pk_add_f32 v[32:33], v[32:33], v[40:41] op_sel:[1,0] op_sel_hi:[0,1]
	v_mov_b32_e32 v39, v32
	v_pk_add_f32 v[42:43], v[38:39], v[44:45] neg_lo:[0,1] neg_hi:[0,1]
	v_mov_b32_e32 v31, v40
	v_sub_f32_e32 v33, v38, v42
	v_pk_add_f32 v[30:31], v[30:31], v[42:43] neg_lo:[0,1] neg_hi:[0,1]
	v_sub_f32_e32 v33, v44, v33
	v_add_f32_e32 v30, v30, v33
	v_add_f32_e32 v30, v30, v31
	v_add_f32_e32 v30, v32, v30
	v_cndmask_b32_e64 v30, v208, v30, s[0:1]
	v_cmp_lt_f32_e64 s[0:1], |v48|, s66
	s_nop 1
	v_cndmask_b32_e64 v30, v30, v48, s[0:1]
	v_sub_f32_e32 v0, v0, v30
	v_lshl_add_u64 v[30:31], v[36:37], 0, v[72:73]
	v_lshlrev_b64 v[30:31], 14, v[30:31]
	v_lshl_add_u64 v[30:31], v[34:35], 0, v[30:31]
	global_store_dword v[30:31], v0, off
	s_or_b64 exec, exec, s[84:85]
	s_and_saveexec_b64 s[84:85], s[12:13]
	s_cbranch_execz .LBB0_559
;     __device__ __forceinline__ void operator()(const f32x4 (&acc)[2][2][4][2], const pg8::Unit& u, int wr, int wc, int fr, int fq) const {
;     ...
;             if (wc == 0) {
; #pragma unroll
;                 for (int ai = 0; ai < 2; ++ai)
; #pragma unroll
;                     for (int m = 0; m < 4; ++m) { const int row = row0 + ai * 128 + m * 16;
; #pragma unroll
;                         for (int n = 0; n < 2; ++n)
; #pragma unroll
;                             for (int j = 0; j < 4; ++j) { const int col = 8 * fq + 4 * n + j;
;                                 if (col < 12) { const float xv = acc[ai][0][m][n][j] * rsqrtf(ssq[row] * (1.f / DM) + EPS) + bfp[col]; LS[((size_t)(row >> 12) * 12 + col) * SEQ + (row & (SEQ - 1))] = fminf(xv, 0.f) - log1pf(expf(-fabsf(xv))); } } }
.LBB0_616:
	global_load_dword v0, v[66:67], off offset:512
	s_waitcnt vmcnt(0) lgkmcnt(0)
	v_fmamk_f32 v0, v0, 0x3a000000, v205
	v_cmp_gt_f32_e64 s[0:1], s68, v0
	v_mul_f32_e32 v30, 0x4b800000, v0
	s_nop 0
	v_cndmask_b32_e64 v0, v0, v30, s[0:1]
	v_rsq_f32_e32 v0, v0
	s_nop 0
	v_mul_f32_e32 v30, 0x45800000, v0
	v_cndmask_b32_e64 v0, v0, v30, s[0:1]
	v_lshl_add_u64 v[30:31], v[64:65], 2, s[60:61]
	global_load_dword v30, v[30:31], off
	s_waitcnt vmcnt(0) lgkmcnt(0)
	v_fmac_f32_e32 v30, v26, v0
	v_mul_f32_e64 v26, |v30|, s88
	v_fma_f32 v31, |v30|, s88, -v26
	v_rndne_f32_e32 v32, v26
	v_fma_f32 v31, |v30|, s89, v31
	v_sub_f32_e32 v26, v26, v32
	v_add_f32_e32 v26, v26, v31
	v_exp_f32_e32 v26, v26
	v_cvt_i32_f32_e32 v31, v32
	v_cmp_ngt_f32_e64 s[0:1], |v30|, s70
	v_min_f32_e32 v0, 0, v30
	v_ldexp_f32 v26, v26, v31
	v_cndmask_b32_e64 v26, 0, v26, s[0:1]
	v_cmp_nlt_f32_e64 s[0:1], |v30|, s90
	s_nop 1
	v_cndmask_b32_e64 v26, v208, v26, s[0:1]
	v_add_f32_e32 v32, 1.0, v26
	v_add_f32_e32 v30, -1.0, v32
	v_sub_f32_e32 v31, v30, v32
	v_add_f32_e32 v31, 1.0, v31
	v_sub_f32_e32 v30, v26, v30
	v_add_f32_e32 v33, v30, v31
	v_frexp_mant_f32_e32 v30, v32
	v_cmp_gt_f32_e64 s[0:1], s3, v30
	v_cvt_f64_f32_e32 v[30:31], v32
	v_frexp_exp_i32_f64_e32 v30, v[30:31]
	v_subbrev_co_u32_e64 v42, s[0:1], 0, v30, s[0:1]
	v_sub_u32_e32 v30, 0, v42
	v_ldexp_f32 v31, v32, v30
	v_add_f32_e32 v32, -1.0, v31
	v_add_f32_e32 v38, 1.0, v31
	v_ldexp_f32 v30, v33, v30
	v_add_f32_e32 v33, 1.0, v32
	v_add_f32_e32 v39, -1.0, v38
	v_sub_f32_e32 v33, v31, v33
	v_sub_f32_e32 v31, v31, v39
	v_add_f32_e32 v33, v30, v33
	v_add_f32_e32 v30, v30, v31
	v_add_f32_e32 v43, v38, v30
	v_rcp_f32_e32 v45, v43
	v_sub_f32_e32 v31, v38, v43
	v_add_f32_e32 v44, v30, v31
	v_add_f32_e32 v31, v32, v33
	v_mul_f32_e32 v47, v31, v45
	v_sub_f32_e32 v30, v32, v31
	v_mul_f32_e32 v32, v43, v47
	v_fma_f32 v38, v47, v43, -v32
	v_fmac_f32_e32 v38, v47, v44
	v_add_f32_e32 v46, v33, v30
	v_add_f32_e32 v30, v32, v38
	v_sub_f32_e32 v33, v31, v30
	v_pk_add_f32 v[40:41], v[30:31], v[32:33] neg_lo:[0,1] neg_hi:[0,1]
	v_mov_b32_e32 v39, v30
	v_pk_add_f32 v[30:31], v[40:41], v[38:39] neg_lo:[0,1] neg_hi:[0,1]
	v_cmp_neq_f32_e64 s[0:1], s2, v26
	v_add_f32_e32 v31, v46, v31
	v_add_f32_e32 v30, v30, v31
	v_add_f32_e32 v31, v33, v30
	v_mul_f32_e32 v46, v45, v31
	v_mul_f32_e32 v32, v43, v46
	v_fma_f32 v38, v46, v43, -v32
	v_fmac_f32_e32 v38, v46, v44
	v_sub_f32_e32 v33, v33, v31
	v_add_f32_e32 v43, v30, v33
	v_add_f32_e32 v30, v32, v38
	v_sub_f32_e32 v33, v31, v30
	v_pk_add_f32 v[40:41], v[30:31], v[32:33] neg_lo:[0,1] neg_hi:[0,1]
	v_mov_b32_e32 v39, v30
	v_pk_add_f32 v[30:31], v[40:41], v[38:39] neg_lo:[0,1] neg_hi:[0,1]
	s_nop 0
	v_add_f32_e32 v31, v43, v31
	v_add_f32_e32 v30, v30, v31
	v_add_f32_e32 v31, v47, v46
	v_add_f32_e32 v30, v33, v30
	v_sub_f32_e32 v32, v31, v47
	v_mul_f32_e32 v30, v45, v30
	v_sub_f32_e32 v32, v46, v32
	v_add_f32_e32 v32, v32, v30
	v_add_f32_e32 v38, v31, v32
	v_mul_f32_e32 v39, v38, v38
	v_fmamk_f32 v30, v39, 0x3e9b6dac, v206
	v_fmaak_f32 v179, v39, v30, 0x3f2aaada
	v_cvt_f32_i32_e32 v30, v42
	v_sub_f32_e32 v31, v38, v31
	v_sub_f32_e32 v31, v32, v31
	v_ldexp_f32 v40, v31, 1
	v_mul_f32_e32 v31, v38, v39
	v_ldexp_f32 v33, v38, 1
	v_pk_mul_f32 v[38:39], v[30:31], v[178:179]
	s_nop 0
	v_fma_f32 v32, v30, s69, -v38
	v_fmac_f32_e32 v32, 0xb102e308, v30
	v_pk_add_f32 v[30:31], v[38:39], v[32:33]
	s_nop 0
	v_sub_f32_e32 v33, v31, v33
	v_sub_f32_e32 v33, v39, v33
	v_add_f32_e32 v41, v40, v33
	v_mov_b32_e32 v40, v38
	v_pk_add_f32 v[38:39], v[30:31], v[38:39] neg_lo:[0,1] neg_hi:[0,1]
	v_pk_add_f32 v[42:43], v[30:31], v[40:41]
	v_mov_b32_e32 v33, v30
	v_mov_b32_e32 v39, v43
	v_pk_add_f32 v[44:45], v[32:33], v[38:39] neg_lo:[0,1] neg_hi:[0,1]
	v_pk_add_f32 v[32:33], v[32:33], v[38:39]
	v_mov_b32_e32 v40, v41
	v_pk_add_f32 v[38:39], v[32:33], v[30:31] op_sel:[1,0] op_sel_hi:[0,1] neg_lo:[0,1] neg_hi:[0,1]
	v_pk_add_f32 v[46:47], v[42:43], v[38:39] op_sel_hi:[1,0] neg_lo:[0,1] neg_hi:[0,1]
	v_mov_b32_e32 v42, v43
	v_mov_b32_e32 v43, v33
	v_pk_mov_b32 v[38:39], v[30:31], v[38:39] op_sel:[1,0]
	v_mov_b32_e32 v41, v30
	v_pk_add_f32 v[38:39], v[42:43], v[38:39] neg_lo:[0,1] neg_hi:[0,1]
	v_mov_b32_e32 v46, v44
	v_pk_add_f32 v[30:31], v[40:41], v[38:39] neg_lo:[0,1] neg_hi:[0,1]
	v_mov_b32_e32 v45, v33
	v_pk_add_f32 v[38:39], v[46:47], v[30:31]
	s_nop 0
	v_pk_add_f32 v[40:41], v[38:39], v[38:39] op_sel:[0,1] op_sel_hi:[1,0]
	s_nop 0
	v_pk_add_f32 v[32:33], v[32:33], v[40:41] op_sel:[1,0] op_sel_hi:[0,1]
	v_mov_b32_e32 v39, v32
	v_pk_add_f32 v[42:43], v[38:39], v[44:45] neg_lo:[0,1] neg_hi:[0,1]
	v_mov_b32_e32 v31, v40
	v_sub_f32_e32 v33, v38, v42
	v_pk_add_f32 v[30:31], v[30:31], v[42:43] neg_lo:[0,1] neg_hi:[0,1]
	v_sub_f32_e32 v33, v44, v33
	v_add_f32_e32 v30, v30, v33
	v_add_f32_e32 v30, v30, v31
	v_add_f32_e32 v30, v32, v30
	v_cndmask_b32_e64 v30, v208, v30, s[0:1]
	v_cmp_lt_f32_e64 s[0:1], |v26|, s66
	s_nop 1
	v_cndmask_b32_e64 v26, v30, v26, s[0:1]
	v_lshl_add_u64 v[30:31], v[36:37], 0, v[64:65]
	v_lshlrev_b64 v[30:31], 14, v[30:31]
	v_sub_f32_e32 v0, v0, v26
	v_lshl_add_u64 v[30:31], v[34:35], 0, v[30:31]
	global_store_dword v[30:31], v0, off
	s_or_b64 exec, exec, s[84:85]
	s_and_saveexec_b64 s[84:85], s[14:15]
	s_cbranch_execz .LBB0_560
;     __device__ __forceinline__ void operator()(const f32x4 (&acc)[2][2][4][2], const pg8::Unit& u, int wr, int wc, int fr, int fq) const {
;     ...
;             if (wc == 0) {
; #pragma unroll
;                 for (int ai = 0; ai < 2; ++ai)
; #pragma unroll
;                     for (int m = 0; m < 4; ++m) { const int row = row0 + ai * 128 + m * 16;
; #pragma unroll
;                         for (int n = 0; n < 2; ++n)
; #pragma unroll
;                             for (int j = 0; j < 4; ++j) { const int col = 8 * fq + 4 * n + j;
;                                 if (col < 12) { const float xv = acc[ai][0][m][n][j] * rsqrtf(ssq[row] * (1.f / DM) + EPS) + bfp[col]; LS[((size_t)(row >> 12) * 12 + col) * SEQ + (row & (SEQ - 1))] = fminf(xv, 0.f) - log1pf(expf(-fabsf(xv))); } } }
.LBB0_617:
	global_load_dword v0, v[66:67], off offset:512
	v_lshl_add_u64 v[30:31], v[74:75], 2, s[60:61]
	s_waitcnt vmcnt(0) lgkmcnt(0)
	v_fmamk_f32 v0, v0, 0x3a000000, v205
	v_cmp_gt_f32_e64 s[0:1], s68, v0
	v_mul_f32_e32 v26, 0x4b800000, v0
	s_nop 0
	v_cndmask_b32_e64 v0, v0, v26, s[0:1]
	v_rsq_f32_e32 v0, v0
	s_nop 0
	v_mul_f32_e32 v26, 0x45800000, v0
	v_cndmask_b32_e64 v0, v0, v26, s[0:1]
	global_load_dword v26, v[30:31], off
	s_waitcnt vmcnt(0) lgkmcnt(0)
	v_fmac_f32_e32 v26, v27, v0
	v_mul_f32_e64 v27, |v26|, s88
	v_fma_f32 v30, |v26|, s88, -v27
	v_rndne_f32_e32 v31, v27
	v_fma_f32 v30, |v26|, s89, v30
	v_sub_f32_e32 v27, v27, v31
	v_add_f32_e32 v27, v27, v30
	v_exp_f32_e32 v27, v27
	v_cvt_i32_f32_e32 v30, v31
	v_cmp_ngt_f32_e64 s[0:1], |v26|, s70
	v_min_f32_e32 v0, 0, v26
	v_ldexp_f32 v27, v27, v30
	v_cndmask_b32_e64 v27, 0, v27, s[0:1]
	v_cmp_nlt_f32_e64 s[0:1], |v26|, s90
	s_nop 1
	v_cndmask_b32_e64 v46, v208, v27, s[0:1]
	v_add_f32_e32 v30, 1.0, v46
	v_add_f32_e32 v26, -1.0, v30
	v_sub_f32_e32 v27, v26, v30
	v_add_f32_e32 v27, 1.0, v27
	v_sub_f32_e32 v26, v46, v26
	v_add_f32_e32 v31, v26, v27
	v_frexp_mant_f32_e32 v26, v30
	v_cmp_gt_f32_e64 s[0:1], s3, v26
	v_cvt_f64_f32_e32 v[26:27], v30
	v_frexp_exp_i32_f64_e32 v26, v[26:27]
	v_subbrev_co_u32_e64 v40, s[0:1], 0, v26, s[0:1]
	v_sub_u32_e32 v26, 0, v40
	v_ldexp_f32 v27, v30, v26
	v_add_f32_e32 v30, -1.0, v27
	v_add_f32_e32 v32, 1.0, v27
	v_ldexp_f32 v26, v31, v26
	v_add_f32_e32 v31, 1.0, v30
	v_add_f32_e32 v33, -1.0, v32
	v_sub_f32_e32 v31, v27, v31
	v_sub_f32_e32 v27, v27, v33
	v_add_f32_e32 v31, v26, v31
	v_add_f32_e32 v26, v26, v27
	v_add_f32_e32 v41, v32, v26
	v_rcp_f32_e32 v43, v41
	v_sub_f32_e32 v27, v32, v41
	v_add_f32_e32 v42, v26, v27
	v_add_f32_e32 v27, v30, v31
	v_mul_f32_e32 v45, v27, v43
	v_sub_f32_e32 v26, v30, v27
	v_mul_f32_e32 v30, v41, v45
	v_fma_f32 v32, v45, v41, -v30
	v_fmac_f32_e32 v32, v45, v42
	v_add_f32_e32 v44, v31, v26
	v_add_f32_e32 v26, v30, v32
	v_sub_f32_e32 v31, v27, v26
	v_pk_add_f32 v[38:39], v[26:27], v[30:31] neg_lo:[0,1] neg_hi:[0,1]
	v_mov_b32_e32 v33, v26
	v_pk_add_f32 v[26:27], v[38:39], v[32:33] neg_lo:[0,1] neg_hi:[0,1]
	v_cmp_neq_f32_e64 s[0:1], s2, v46
	v_add_f32_e32 v27, v44, v27
	v_add_f32_e32 v26, v26, v27
	v_add_f32_e32 v27, v31, v26
	v_mul_f32_e32 v44, v43, v27
	v_mul_f32_e32 v30, v41, v44
	v_fma_f32 v32, v44, v41, -v30
	v_fmac_f32_e32 v32, v44, v42
	v_sub_f32_e32 v31, v31, v27
	v_add_f32_e32 v41, v26, v31
	v_add_f32_e32 v26, v30, v32
	v_sub_f32_e32 v31, v27, v26
	v_pk_add_f32 v[38:39], v[26:27], v[30:31] neg_lo:[0,1] neg_hi:[0,1]
	v_mov_b32_e32 v33, v26
	v_pk_add_f32 v[26:27], v[38:39], v[32:33] neg_lo:[0,1] neg_hi:[0,1]
	s_nop 0
	v_add_f32_e32 v27, v41, v27
	v_add_f32_e32 v26, v26, v27
	v_add_f32_e32 v27, v45, v44
	v_add_f32_e32 v26, v31, v26
	v_sub_f32_e32 v30, v27, v45
	v_mul_f32_e32 v26, v43, v26
	v_sub_f32_e32 v30, v44, v30
	v_add_f32_e32 v30, v30, v26
	v_add_f32_e32 v32, v27, v30
	v_mul_f32_e32 v33, v32, v32
	v_fmamk_f32 v26, v33, 0x3e9b6dac, v206
	v_fmaak_f32 v179, v33, v26, 0x3f2aaada
	v_cvt_f32_i32_e32 v26, v40
	v_sub_f32_e32 v27, v32, v27
	v_sub_f32_e32 v27, v30, v27
	v_ldexp_f32 v38, v27, 1
	v_mul_f32_e32 v27, v32, v33
	v_ldexp_f32 v31, v32, 1
	v_pk_mul_f32 v[32:33], v[26:27], v[178:179]
	s_nop 0
	v_fma_f32 v30, v26, s69, -v32
	v_fmac_f32_e32 v30, 0xb102e308, v26
	v_pk_add_f32 v[26:27], v[32:33], v[30:31]
	s_nop 0
	v_sub_f32_e32 v31, v27, v31
	v_sub_f32_e32 v31, v33, v31
	v_add_f32_e32 v39, v38, v31
	v_mov_b32_e32 v38, v32
	v_pk_add_f32 v[32:33], v[26:27], v[32:33] neg_lo:[0,1] neg_hi:[0,1]
	v_pk_add_f32 v[40:41], v[26:27], v[38:39]
	v_mov_b32_e32 v31, v26
	v_mov_b32_e32 v33, v41
	v_pk_add_f32 v[42:43], v[30:31], v[32:33] neg_lo:[0,1] neg_hi:[0,1]
	v_pk_add_f32 v[30:31], v[30:31], v[32:33]
	v_mov_b32_e32 v38, v39
	v_pk_add_f32 v[32:33], v[30:31], v[26:27] op_sel:[1,0] op_sel_hi:[0,1] neg_lo:[0,1] neg_hi:[0,1]
	v_pk_add_f32 v[44:45], v[40:41], v[32:33] op_sel_hi:[1,0] neg_lo:[0,1] neg_hi:[0,1]
	v_mov_b32_e32 v40, v41
	v_mov_b32_e32 v41, v31
	v_pk_mov_b32 v[32:33], v[26:27], v[32:33] op_sel:[1,0]
	v_mov_b32_e32 v39, v26
	v_pk_add_f32 v[32:33], v[40:41], v[32:33] neg_lo:[0,1] neg_hi:[0,1]
	v_mov_b32_e32 v44, v42
	v_pk_add_f32 v[26:27], v[38:39], v[32:33] neg_lo:[0,1] neg_hi:[0,1]
	v_mov_b32_e32 v43, v31
	v_pk_add_f32 v[32:33], v[44:45], v[26:27]
	s_nop 0
	v_pk_add_f32 v[38:39], v[32:33], v[32:33] op_sel:[0,1] op_sel_hi:[1,0]
	s_nop 0
	v_pk_add_f32 v[30:31], v[30:31], v[38:39] op_sel:[1,0] op_sel_hi:[0,1]
	v_mov_b32_e32 v33, v30
	v_pk_add_f32 v[40:41], v[32:33], v[42:43] neg_lo:[0,1] neg_hi:[0,1]
	v_mov_b32_e32 v27, v38
	v_sub_f32_e32 v31, v32, v40
	v_pk_add_f32 v[26:27], v[26:27], v[40:41] neg_lo:[0,1] neg_hi:[0,1]
	v_sub_f32_e32 v31, v42, v31
	v_add_f32_e32 v26, v26, v31
	v_add_f32_e32 v26, v26, v27
	v_add_f32_e32 v26, v30, v26
	v_cndmask_b32_e64 v26, v208, v26, s[0:1]
	v_cmp_lt_f32_e64 s[0:1], |v46|, s66
	s_nop 1
	v_cndmask_b32_e64 v26, v26, v46, s[0:1]
	v_sub_f32_e32 v0, v0, v26
	v_lshl_add_u64 v[26:27], v[36:37], 0, v[74:75]
	v_lshlrev_b64 v[26:27], 14, v[26:27]
	v_lshl_add_u64 v[26:27], v[34:35], 0, v[26:27]
	global_store_dword v[26:27], v0, off
	s_or_b64 exec, exec, s[84:85]
	s_and_saveexec_b64 s[84:85], s[16:17]
	s_cbranch_execz .LBB0_561
;     __device__ __forceinline__ void operator()(const f32x4 (&acc)[2][2][4][2], const pg8::Unit& u, int wr, int wc, int fr, int fq) const {
;     ...
;             if (wc == 0) {
; #pragma unroll
;                 for (int ai = 0; ai < 2; ++ai)
; #pragma unroll
;                     for (int m = 0; m < 4; ++m) { const int row = row0 + ai * 128 + m * 16;
; #pragma unroll
;                         for (int n = 0; n < 2; ++n)
; #pragma unroll
;                             for (int j = 0; j < 4; ++j) { const int col = 8 * fq + 4 * n + j;
;                                 if (col < 12) { const float xv = acc[ai][0][m][n][j] * rsqrtf(ssq[row] * (1.f / DM) + EPS) + bfp[col]; LS[((size_t)(row >> 12) * 12 + col) * SEQ + (row & (SEQ - 1))] = fminf(xv, 0.f) - log1pf(expf(-fabsf(xv))); } } }
.LBB0_618:
	global_load_dword v0, v[66:67], off offset:512
	s_waitcnt vmcnt(0) lgkmcnt(0)
	v_fmamk_f32 v0, v0, 0x3a000000, v205
	v_cmp_gt_f32_e64 s[0:1], s68, v0
	v_mul_f32_e32 v26, 0x4b800000, v0
	s_nop 0
	v_cndmask_b32_e64 v0, v0, v26, s[0:1]
	v_rsq_f32_e32 v0, v0
	s_nop 0
	v_mul_f32_e32 v26, 0x45800000, v0
	v_cndmask_b32_e64 v0, v0, v26, s[0:1]
	v_lshl_add_u64 v[26:27], v[58:59], 2, s[60:61]
	global_load_dword v26, v[26:27], off
	s_waitcnt vmcnt(0) lgkmcnt(0)
	v_fmac_f32_e32 v26, v28, v0
	v_mul_f32_e64 v27, |v26|, s88
	v_fma_f32 v28, |v26|, s88, -v27
	v_rndne_f32_e32 v30, v27
	v_fma_f32 v28, |v26|, s89, v28
	v_sub_f32_e32 v27, v27, v30
	v_add_f32_e32 v27, v27, v28
	v_exp_f32_e32 v27, v27
	v_cvt_i32_f32_e32 v28, v30
	v_cmp_ngt_f32_e64 s[0:1], |v26|, s70
	v_min_f32_e32 v0, 0, v26
	v_ldexp_f32 v27, v27, v28
	v_cndmask_b32_e64 v27, 0, v27, s[0:1]
	v_cmp_nlt_f32_e64 s[0:1], |v26|, s90
	s_nop 1
	v_cndmask_b32_e64 v28, v208, v27, s[0:1]
	v_add_f32_e32 v30, 1.0, v28
	v_add_f32_e32 v26, -1.0, v30
	v_sub_f32_e32 v27, v26, v30
	v_add_f32_e32 v27, 1.0, v27
	v_sub_f32_e32 v26, v28, v26
	v_add_f32_e32 v31, v26, v27
	v_frexp_mant_f32_e32 v26, v30
	v_cmp_gt_f32_e64 s[0:1], s3, v26
	v_cvt_f64_f32_e32 v[26:27], v30
	v_frexp_exp_i32_f64_e32 v26, v[26:27]
	v_subbrev_co_u32_e64 v40, s[0:1], 0, v26, s[0:1]
	v_sub_u32_e32 v26, 0, v40
	v_ldexp_f32 v27, v30, v26
	v_add_f32_e32 v30, -1.0, v27
	v_add_f32_e32 v32, 1.0, v27
	v_ldexp_f32 v26, v31, v26
	v_add_f32_e32 v31, 1.0, v30
	v_add_f32_e32 v33, -1.0, v32
	v_sub_f32_e32 v31, v27, v31
	v_sub_f32_e32 v27, v27, v33
	v_add_f32_e32 v31, v26, v31
	v_add_f32_e32 v26, v26, v27
	v_add_f32_e32 v41, v32, v26
	v_rcp_f32_e32 v43, v41
	v_sub_f32_e32 v27, v32, v41
	v_add_f32_e32 v42, v26, v27
	v_add_f32_e32 v27, v30, v31
	v_mul_f32_e32 v45, v27, v43
	v_sub_f32_e32 v26, v30, v27
	v_mul_f32_e32 v30, v41, v45
	v_fma_f32 v32, v45, v41, -v30
	v_fmac_f32_e32 v32, v45, v42
	v_add_f32_e32 v44, v31, v26
	v_add_f32_e32 v26, v30, v32
	v_sub_f32_e32 v31, v27, v26
	v_pk_add_f32 v[38:39], v[26:27], v[30:31] neg_lo:[0,1] neg_hi:[0,1]
	v_mov_b32_e32 v33, v26
	v_pk_add_f32 v[26:27], v[38:39], v[32:33] neg_lo:[0,1] neg_hi:[0,1]
	v_cmp_neq_f32_e64 s[0:1], s2, v28
	v_add_f32_e32 v27, v44, v27
	v_add_f32_e32 v26, v26, v27
	v_add_f32_e32 v27, v31, v26
	v_mul_f32_e32 v44, v43, v27
	v_mul_f32_e32 v30, v41, v44
	v_fma_f32 v32, v44, v41, -v30
	v_fmac_f32_e32 v32, v44, v42
	v_sub_f32_e32 v31, v31, v27
	v_add_f32_e32 v41, v26, v31
	v_add_f32_e32 v26, v30, v32
	v_sub_f32_e32 v31, v27, v26
	v_pk_add_f32 v[38:39], v[26:27], v[30:31] neg_lo:[0,1] neg_hi:[0,1]
	v_mov_b32_e32 v33, v26
	v_pk_add_f32 v[26:27], v[38:39], v[32:33] neg_lo:[0,1] neg_hi:[0,1]
	s_nop 0
	v_add_f32_e32 v27, v41, v27
	v_add_f32_e32 v26, v26, v27
	v_add_f32_e32 v27, v45, v44
	v_add_f32_e32 v26, v31, v26
	v_sub_f32_e32 v30, v27, v45
	v_mul_f32_e32 v26, v43, v26
	v_sub_f32_e32 v30, v44, v30
	v_add_f32_e32 v30, v30, v26
	v_add_f32_e32 v32, v27, v30
	v_mul_f32_e32 v33, v32, v32
	v_fmamk_f32 v26, v33, 0x3e9b6dac, v206
	v_fmaak_f32 v179, v33, v26, 0x3f2aaada
	v_cvt_f32_i32_e32 v26, v40
	v_sub_f32_e32 v27, v32, v27
	v_sub_f32_e32 v27, v30, v27
	v_ldexp_f32 v38, v27, 1
	v_mul_f32_e32 v27, v32, v33
	v_ldexp_f32 v31, v32, 1
	v_pk_mul_f32 v[32:33], v[26:27], v[178:179]
	s_nop 0
	v_fma_f32 v30, v26, s69, -v32
	v_fmac_f32_e32 v30, 0xb102e308, v26
	v_pk_add_f32 v[26:27], v[32:33], v[30:31]
	s_nop 0
	v_sub_f32_e32 v31, v27, v31
	v_sub_f32_e32 v31, v33, v31
	v_add_f32_e32 v39, v38, v31
	v_mov_b32_e32 v38, v32
	v_pk_add_f32 v[32:33], v[26:27], v[32:33] neg_lo:[0,1] neg_hi:[0,1]
	v_pk_add_f32 v[40:41], v[26:27], v[38:39]
	v_mov_b32_e32 v31, v26
	v_mov_b32_e32 v33, v41
	v_pk_add_f32 v[42:43], v[30:31], v[32:33] neg_lo:[0,1] neg_hi:[0,1]
	v_pk_add_f32 v[30:31], v[30:31], v[32:33]
	v_mov_b32_e32 v38, v39
	v_pk_add_f32 v[32:33], v[30:31], v[26:27] op_sel:[1,0] op_sel_hi:[0,1] neg_lo:[0,1] neg_hi:[0,1]
	v_pk_add_f32 v[44:45], v[40:41], v[32:33] op_sel_hi:[1,0] neg_lo:[0,1] neg_hi:[0,1]
	v_mov_b32_e32 v40, v41
	v_mov_b32_e32 v41, v31
	v_pk_mov_b32 v[32:33], v[26:27], v[32:33] op_sel:[1,0]
	v_mov_b32_e32 v39, v26
	v_pk_add_f32 v[32:33], v[40:41], v[32:33] neg_lo:[0,1] neg_hi:[0,1]
	v_mov_b32_e32 v44, v42
	v_pk_add_f32 v[26:27], v[38:39], v[32:33] neg_lo:[0,1] neg_hi:[0,1]
	v_mov_b32_e32 v43, v31
	v_pk_add_f32 v[32:33], v[44:45], v[26:27]
	s_nop 0
	v_pk_add_f32 v[38:39], v[32:33], v[32:33] op_sel:[0,1] op_sel_hi:[1,0]
	s_nop 0
	v_pk_add_f32 v[30:31], v[30:31], v[38:39] op_sel:[1,0] op_sel_hi:[0,1]
	v_mov_b32_e32 v33, v30
	v_pk_add_f32 v[40:41], v[32:33], v[42:43] neg_lo:[0,1] neg_hi:[0,1]
	v_mov_b32_e32 v27, v38
	v_sub_f32_e32 v31, v32, v40
	v_pk_add_f32 v[26:27], v[26:27], v[40:41] neg_lo:[0,1] neg_hi:[0,1]
	v_sub_f32_e32 v31, v42, v31
	v_add_f32_e32 v26, v26, v31
	v_add_f32_e32 v26, v26, v27
	v_add_f32_e32 v26, v30, v26
	v_cndmask_b32_e64 v26, v208, v26, s[0:1]
	v_cmp_lt_f32_e64 s[0:1], |v28|, s66
	s_nop 1
	v_cndmask_b32_e64 v26, v26, v28, s[0:1]
	v_sub_f32_e32 v0, v0, v26
	v_lshl_add_u64 v[26:27], v[36:37], 0, v[58:59]
	v_lshlrev_b64 v[26:27], 14, v[26:27]
	v_lshl_add_u64 v[26:27], v[34:35], 0, v[26:27]
	global_store_dword v[26:27], v0, off
	s_or_b64 exec, exec, s[84:85]
	s_and_saveexec_b64 s[84:85], s[18:19]
	s_cbranch_execnz .LBB0_562
	s_branch .LBB0_563
;     __device__ __forceinline__ void operator()(const f32x4 (&acc)[2][2][4][2], const pg8::Unit& u, int wr, int wc, int fr, int fq) const {
;     ...
;             if (wc == 0) {
; #pragma unroll
;                 for (int ai = 0; ai < 2; ++ai)
; #pragma unroll
;                     for (int m = 0; m < 4; ++m) { const int row = row0 + ai * 128 + m * 16;
; #pragma unroll
;                         for (int n = 0; n < 2; ++n)
; #pragma unroll
;                             for (int j = 0; j < 4; ++j) { const int col = 8 * fq + 4 * n + j;
;                                 if (col < 12) { const float xv = acc[ai][0][m][n][j] * rsqrtf(ssq[row] * (1.f / DM) + EPS) + bfp[col]; LS[((size_t)(row >> 12) * 12 + col) * SEQ + (row & (SEQ - 1))] = fminf(xv, 0.f) - log1pf(expf(-fabsf(xv))); } } }
.LBB0_619:
	global_load_dword v0, v[66:67], off offset:576
	s_waitcnt vmcnt(0) lgkmcnt(0)
	v_fmamk_f32 v0, v0, 0x3a000000, v205
	v_cmp_gt_f32_e64 s[0:1], s68, v0
	v_mul_f32_e32 v30, 0x4b800000, v0
	s_nop 0
	v_cndmask_b32_e64 v0, v0, v30, s[0:1]
	v_rsq_f32_e32 v0, v0
	s_nop 0
	v_mul_f32_e32 v30, 0x45800000, v0
	v_cndmask_b32_e64 v0, v0, v30, s[0:1]
	v_lshl_add_u64 v[30:31], v[68:69], 2, s[60:61]
	global_load_dword v30, v[30:31], off
	s_waitcnt vmcnt(0) lgkmcnt(0)
	v_fmac_f32_e32 v30, v22, v0
	v_mul_f32_e64 v22, |v30|, s88
	v_fma_f32 v31, |v30|, s88, -v22
	v_rndne_f32_e32 v32, v22
	v_fma_f32 v31, |v30|, s89, v31
	v_sub_f32_e32 v22, v22, v32
	v_add_f32_e32 v22, v22, v31
	v_exp_f32_e32 v22, v22
	v_cvt_i32_f32_e32 v31, v32
	v_cmp_ngt_f32_e64 s[0:1], |v30|, s70
	v_min_f32_e32 v0, 0, v30
	v_ldexp_f32 v22, v22, v31
	v_cndmask_b32_e64 v22, 0, v22, s[0:1]
	v_cmp_nlt_f32_e64 s[0:1], |v30|, s90
	s_nop 1
	v_cndmask_b32_e64 v22, v208, v22, s[0:1]
	v_add_f32_e32 v32, 1.0, v22
	v_add_f32_e32 v30, -1.0, v32
	v_sub_f32_e32 v31, v30, v32
	v_add_f32_e32 v31, 1.0, v31
	v_sub_f32_e32 v30, v22, v30
	v_add_f32_e32 v33, v30, v31
	v_frexp_mant_f32_e32 v30, v32
	v_cmp_gt_f32_e64 s[0:1], s3, v30
	v_cvt_f64_f32_e32 v[30:31], v32
	v_frexp_exp_i32_f64_e32 v30, v[30:31]
	v_subbrev_co_u32_e64 v38, s[0:1], 0, v30, s[0:1]
	v_sub_u32_e32 v30, 0, v38
	v_ldexp_f32 v31, v32, v30
	v_add_f32_e32 v32, -1.0, v31
	v_add_f32_e32 v34, 1.0, v31
	v_ldexp_f32 v30, v33, v30
	v_add_f32_e32 v33, 1.0, v32
	v_add_f32_e32 v35, -1.0, v34
	v_sub_f32_e32 v33, v31, v33
	v_sub_f32_e32 v31, v31, v35
	v_add_f32_e32 v33, v30, v33
	v_add_f32_e32 v30, v30, v31
	v_add_f32_e32 v39, v34, v30
	v_rcp_f32_e32 v41, v39
	v_sub_f32_e32 v31, v34, v39
	v_add_f32_e32 v40, v30, v31
	v_add_f32_e32 v31, v32, v33
	v_mul_f32_e32 v43, v31, v41
	v_sub_f32_e32 v30, v32, v31
	v_mul_f32_e32 v32, v39, v43
	v_fma_f32 v34, v43, v39, -v32
	v_fmac_f32_e32 v34, v43, v40
	v_add_f32_e32 v42, v33, v30
	v_add_f32_e32 v30, v32, v34
	v_sub_f32_e32 v33, v31, v30
	v_pk_add_f32 v[36:37], v[30:31], v[32:33] neg_lo:[0,1] neg_hi:[0,1]
	v_mov_b32_e32 v35, v30
	v_pk_add_f32 v[30:31], v[36:37], v[34:35] neg_lo:[0,1] neg_hi:[0,1]
	v_cmp_neq_f32_e64 s[0:1], s2, v22
	v_add_f32_e32 v31, v42, v31
	v_add_f32_e32 v30, v30, v31
	v_add_f32_e32 v31, v33, v30
	v_mul_f32_e32 v42, v41, v31
	v_mul_f32_e32 v32, v39, v42
	v_fma_f32 v34, v42, v39, -v32
	v_fmac_f32_e32 v34, v42, v40
	v_sub_f32_e32 v33, v33, v31
	v_add_f32_e32 v39, v30, v33
	v_add_f32_e32 v30, v32, v34
	v_sub_f32_e32 v33, v31, v30
	v_pk_add_f32 v[36:37], v[30:31], v[32:33] neg_lo:[0,1] neg_hi:[0,1]
	v_mov_b32_e32 v35, v30
	v_pk_add_f32 v[30:31], v[36:37], v[34:35] neg_lo:[0,1] neg_hi:[0,1]
	s_nop 0
	v_add_f32_e32 v31, v39, v31
	v_add_f32_e32 v30, v30, v31
	v_add_f32_e32 v31, v43, v42
	v_add_f32_e32 v30, v33, v30
	v_sub_f32_e32 v32, v31, v43
	v_mul_f32_e32 v30, v41, v30
	v_sub_f32_e32 v32, v42, v32
	v_add_f32_e32 v32, v32, v30
	v_add_f32_e32 v34, v31, v32
	v_mul_f32_e32 v35, v34, v34
	v_fmamk_f32 v30, v35, 0x3e9b6dac, v206
	v_fmaak_f32 v179, v35, v30, 0x3f2aaada
	v_cvt_f32_i32_e32 v30, v38
	v_sub_f32_e32 v31, v34, v31
	v_sub_f32_e32 v31, v32, v31
	v_ldexp_f32 v36, v31, 1
	v_mul_f32_e32 v31, v34, v35
	v_ldexp_f32 v33, v34, 1
	v_pk_mul_f32 v[34:35], v[30:31], v[178:179]
	s_nop 0
	v_fma_f32 v32, v30, s69, -v34
	v_fmac_f32_e32 v32, 0xb102e308, v30
	v_pk_add_f32 v[30:31], v[34:35], v[32:33]
	s_nop 0
	v_sub_f32_e32 v33, v31, v33
	v_sub_f32_e32 v33, v35, v33
	v_add_f32_e32 v37, v36, v33
	v_mov_b32_e32 v36, v34
	v_pk_add_f32 v[34:35], v[30:31], v[34:35] neg_lo:[0,1] neg_hi:[0,1]
	v_pk_add_f32 v[38:39], v[30:31], v[36:37]
	v_mov_b32_e32 v33, v30
	v_mov_b32_e32 v35, v39
	v_pk_add_f32 v[40:41], v[32:33], v[34:35] neg_lo:[0,1] neg_hi:[0,1]
	v_pk_add_f32 v[32:33], v[32:33], v[34:35]
	v_mov_b32_e32 v36, v37
	v_pk_add_f32 v[34:35], v[32:33], v[30:31] op_sel:[1,0] op_sel_hi:[0,1] neg_lo:[0,1] neg_hi:[0,1]
	v_pk_add_f32 v[42:43], v[38:39], v[34:35] op_sel_hi:[1,0] neg_lo:[0,1] neg_hi:[0,1]
	v_mov_b32_e32 v38, v39
	v_mov_b32_e32 v39, v33
	v_pk_mov_b32 v[34:35], v[30:31], v[34:35] op_sel:[1,0]
	v_mov_b32_e32 v37, v30
	v_pk_add_f32 v[34:35], v[38:39], v[34:35] neg_lo:[0,1] neg_hi:[0,1]
	v_mov_b32_e32 v42, v40
	v_pk_add_f32 v[30:31], v[36:37], v[34:35] neg_lo:[0,1] neg_hi:[0,1]
	v_mov_b32_e32 v41, v33
	v_pk_add_f32 v[34:35], v[42:43], v[30:31]
	s_nop 0
	v_pk_add_f32 v[36:37], v[34:35], v[34:35] op_sel:[0,1] op_sel_hi:[1,0]
	s_nop 0
	v_pk_add_f32 v[32:33], v[32:33], v[36:37] op_sel:[1,0] op_sel_hi:[0,1]
	v_mov_b32_e32 v35, v32
	v_pk_add_f32 v[38:39], v[34:35], v[40:41] neg_lo:[0,1] neg_hi:[0,1]
	v_mov_b32_e32 v31, v36
	v_sub_f32_e32 v33, v34, v38
	v_pk_add_f32 v[30:31], v[30:31], v[38:39] neg_lo:[0,1] neg_hi:[0,1]
	v_sub_f32_e32 v33, v40, v33
	v_add_f32_e32 v30, v30, v33
	v_add_f32_e32 v30, v30, v31
	v_add_f32_e32 v30, v32, v30
	v_cndmask_b32_e64 v30, v208, v30, s[0:1]
	v_cmp_lt_f32_e64 s[0:1], |v22|, s66
	s_nop 1
	v_cndmask_b32_e64 v22, v30, v22, s[0:1]
	v_lshl_add_u64 v[30:31], v[28:29], 0, v[68:69]
	v_lshlrev_b64 v[30:31], 14, v[30:31]
	v_sub_f32_e32 v0, v0, v22
	v_lshl_add_u64 v[30:31], v[26:27], 0, v[30:31]
	global_store_dword v[30:31], v0, off
	s_or_b64 exec, exec, s[84:85]
	s_and_saveexec_b64 s[84:85], s[6:7]
	s_cbranch_execz .LBB0_565
;     __device__ __forceinline__ void operator()(const f32x4 (&acc)[2][2][4][2], const pg8::Unit& u, int wr, int wc, int fr, int fq) const {
;     ...
;             if (wc == 0) {
; #pragma unroll
;                 for (int ai = 0; ai < 2; ++ai)
; #pragma unroll
;                     for (int m = 0; m < 4; ++m) { const int row = row0 + ai * 128 + m * 16;
; #pragma unroll
;                         for (int n = 0; n < 2; ++n)
; #pragma unroll
;                             for (int j = 0; j < 4; ++j) { const int col = 8 * fq + 4 * n + j;
;                                 if (col < 12) { const float xv = acc[ai][0][m][n][j] * rsqrtf(ssq[row] * (1.f / DM) + EPS) + bfp[col]; LS[((size_t)(row >> 12) * 12 + col) * SEQ + (row & (SEQ - 1))] = fminf(xv, 0.f) - log1pf(expf(-fabsf(xv))); } } }
.LBB0_620:
	global_load_dword v0, v[66:67], off offset:576
	v_lshl_add_u64 v[30:31], v[70:71], 2, s[60:61]
	s_waitcnt vmcnt(0) lgkmcnt(0)
	v_fmamk_f32 v0, v0, 0x3a000000, v205
	v_cmp_gt_f32_e64 s[0:1], s68, v0
	v_mul_f32_e32 v22, 0x4b800000, v0
	s_nop 0
	v_cndmask_b32_e64 v0, v0, v22, s[0:1]
	v_rsq_f32_e32 v0, v0
	s_nop 0
	v_mul_f32_e32 v22, 0x45800000, v0
	v_cndmask_b32_e64 v0, v0, v22, s[0:1]
	global_load_dword v22, v[30:31], off
	s_waitcnt vmcnt(0) lgkmcnt(0)
	v_fmac_f32_e32 v22, v23, v0
	v_mul_f32_e64 v23, |v22|, s88
	v_fma_f32 v30, |v22|, s88, -v23
	v_rndne_f32_e32 v31, v23
	v_fma_f32 v30, |v22|, s89, v30
	v_sub_f32_e32 v23, v23, v31
	v_add_f32_e32 v23, v23, v30
	v_exp_f32_e32 v23, v23
	v_cvt_i32_f32_e32 v30, v31
	v_cmp_ngt_f32_e64 s[0:1], |v22|, s70
	v_min_f32_e32 v0, 0, v22
	v_ldexp_f32 v23, v23, v30
	v_cndmask_b32_e64 v23, 0, v23, s[0:1]
	v_cmp_nlt_f32_e64 s[0:1], |v22|, s90
	s_nop 1
	v_cndmask_b32_e64 v42, v208, v23, s[0:1]
	v_add_f32_e32 v30, 1.0, v42
	v_add_f32_e32 v22, -1.0, v30
	v_sub_f32_e32 v23, v22, v30
	v_add_f32_e32 v23, 1.0, v23
	v_sub_f32_e32 v22, v42, v22
	v_add_f32_e32 v31, v22, v23
	v_frexp_mant_f32_e32 v22, v30
	v_cmp_gt_f32_e64 s[0:1], s3, v22
	v_cvt_f64_f32_e32 v[22:23], v30
	v_frexp_exp_i32_f64_e32 v22, v[22:23]
	v_subbrev_co_u32_e64 v36, s[0:1], 0, v22, s[0:1]
	v_sub_u32_e32 v22, 0, v36
	v_ldexp_f32 v23, v30, v22
	v_add_f32_e32 v30, -1.0, v23
	v_add_f32_e32 v32, 1.0, v23
	v_ldexp_f32 v22, v31, v22
	v_add_f32_e32 v31, 1.0, v30
	v_add_f32_e32 v33, -1.0, v32
	v_sub_f32_e32 v31, v23, v31
	v_sub_f32_e32 v23, v23, v33
	v_add_f32_e32 v31, v22, v31
	v_add_f32_e32 v22, v22, v23
	v_add_f32_e32 v37, v32, v22
	v_rcp_f32_e32 v39, v37
	v_sub_f32_e32 v23, v32, v37
	v_add_f32_e32 v38, v22, v23
	v_add_f32_e32 v23, v30, v31
	v_mul_f32_e32 v41, v23, v39
	v_sub_f32_e32 v22, v30, v23
	v_mul_f32_e32 v30, v37, v41
	v_fma_f32 v32, v41, v37, -v30
	v_fmac_f32_e32 v32, v41, v38
	v_add_f32_e32 v40, v31, v22
	v_add_f32_e32 v22, v30, v32
	v_sub_f32_e32 v31, v23, v22
	v_pk_add_f32 v[34:35], v[22:23], v[30:31] neg_lo:[0,1] neg_hi:[0,1]
	v_mov_b32_e32 v33, v22
	v_pk_add_f32 v[22:23], v[34:35], v[32:33] neg_lo:[0,1] neg_hi:[0,1]
	v_cmp_neq_f32_e64 s[0:1], s2, v42
	v_add_f32_e32 v23, v40, v23
	v_add_f32_e32 v22, v22, v23
	v_add_f32_e32 v23, v31, v22
	v_mul_f32_e32 v40, v39, v23
	v_mul_f32_e32 v30, v37, v40
	v_fma_f32 v32, v40, v37, -v30
	v_fmac_f32_e32 v32, v40, v38
	v_sub_f32_e32 v31, v31, v23
	v_add_f32_e32 v37, v22, v31
	v_add_f32_e32 v22, v30, v32
	v_sub_f32_e32 v31, v23, v22
	v_pk_add_f32 v[34:35], v[22:23], v[30:31] neg_lo:[0,1] neg_hi:[0,1]
	v_mov_b32_e32 v33, v22
	v_pk_add_f32 v[22:23], v[34:35], v[32:33] neg_lo:[0,1] neg_hi:[0,1]
	s_nop 0
	v_add_f32_e32 v23, v37, v23
	v_add_f32_e32 v22, v22, v23
	v_add_f32_e32 v23, v41, v40
	v_add_f32_e32 v22, v31, v22
	v_sub_f32_e32 v30, v23, v41
	v_mul_f32_e32 v22, v39, v22
	v_sub_f32_e32 v30, v40, v30
	v_add_f32_e32 v30, v30, v22
	v_add_f32_e32 v32, v23, v30
	v_mul_f32_e32 v33, v32, v32
	v_fmamk_f32 v22, v33, 0x3e9b6dac, v206
	v_fmaak_f32 v179, v33, v22, 0x3f2aaada
	v_cvt_f32_i32_e32 v22, v36
	v_sub_f32_e32 v23, v32, v23
	v_sub_f32_e32 v23, v30, v23
	v_ldexp_f32 v34, v23, 1
	v_mul_f32_e32 v23, v32, v33
	v_ldexp_f32 v31, v32, 1
	v_pk_mul_f32 v[32:33], v[22:23], v[178:179]
	s_nop 0
	v_fma_f32 v30, v22, s69, -v32
	v_fmac_f32_e32 v30, 0xb102e308, v22
	v_pk_add_f32 v[22:23], v[32:33], v[30:31]
	s_nop 0
	v_sub_f32_e32 v31, v23, v31
	v_sub_f32_e32 v31, v33, v31
	v_add_f32_e32 v35, v34, v31
	v_mov_b32_e32 v34, v32
	v_pk_add_f32 v[32:33], v[22:23], v[32:33] neg_lo:[0,1] neg_hi:[0,1]
	v_pk_add_f32 v[36:37], v[22:23], v[34:35]
	v_mov_b32_e32 v31, v22
	v_mov_b32_e32 v33, v37
	v_pk_add_f32 v[38:39], v[30:31], v[32:33] neg_lo:[0,1] neg_hi:[0,1]
	v_pk_add_f32 v[30:31], v[30:31], v[32:33]
	v_mov_b32_e32 v34, v35
	v_pk_add_f32 v[32:33], v[30:31], v[22:23] op_sel:[1,0] op_sel_hi:[0,1] neg_lo:[0,1] neg_hi:[0,1]
	v_pk_add_f32 v[40:41], v[36:37], v[32:33] op_sel_hi:[1,0] neg_lo:[0,1] neg_hi:[0,1]
	v_mov_b32_e32 v36, v37
	v_mov_b32_e32 v37, v31
	v_pk_mov_b32 v[32:33], v[22:23], v[32:33] op_sel:[1,0]
	v_mov_b32_e32 v35, v22
	v_pk_add_f32 v[32:33], v[36:37], v[32:33] neg_lo:[0,1] neg_hi:[0,1]
	v_mov_b32_e32 v40, v38
	v_pk_add_f32 v[22:23], v[34:35], v[32:33] neg_lo:[0,1] neg_hi:[0,1]
	v_mov_b32_e32 v39, v31
	v_pk_add_f32 v[32:33], v[40:41], v[22:23]
	s_nop 0
	v_pk_add_f32 v[34:35], v[32:33], v[32:33] op_sel:[0,1] op_sel_hi:[1,0]
	s_nop 0
	v_pk_add_f32 v[30:31], v[30:31], v[34:35] op_sel:[1,0] op_sel_hi:[0,1]
	v_mov_b32_e32 v33, v30
	v_pk_add_f32 v[36:37], v[32:33], v[38:39] neg_lo:[0,1] neg_hi:[0,1]
	v_mov_b32_e32 v23, v34
	v_sub_f32_e32 v31, v32, v36
	v_pk_add_f32 v[22:23], v[22:23], v[36:37] neg_lo:[0,1] neg_hi:[0,1]
	v_sub_f32_e32 v31, v38, v31
	v_add_f32_e32 v22, v22, v31
	v_add_f32_e32 v22, v22, v23
	v_add_f32_e32 v22, v30, v22
	v_cndmask_b32_e64 v22, v208, v22, s[0:1]
	v_cmp_lt_f32_e64 s[0:1], |v42|, s66
	s_nop 1
	v_cndmask_b32_e64 v22, v22, v42, s[0:1]
	v_sub_f32_e32 v0, v0, v22
	v_lshl_add_u64 v[22:23], v[28:29], 0, v[70:71]
	v_lshlrev_b64 v[22:23], 14, v[22:23]
	v_lshl_add_u64 v[22:23], v[26:27], 0, v[22:23]
	global_store_dword v[22:23], v0, off
	s_or_b64 exec, exec, s[84:85]
	s_and_saveexec_b64 s[84:85], s[8:9]
	s_cbranch_execz .LBB0_566
;     __device__ __forceinline__ void operator()(const f32x4 (&acc)[2][2][4][2], const pg8::Unit& u, int wr, int wc, int fr, int fq) const {
;     ...
;             if (wc == 0) {
; #pragma unroll
;                 for (int ai = 0; ai < 2; ++ai)
; #pragma unroll
;                     for (int m = 0; m < 4; ++m) { const int row = row0 + ai * 128 + m * 16;
; #pragma unroll
;                         for (int n = 0; n < 2; ++n)
; #pragma unroll
;                             for (int j = 0; j < 4; ++j) { const int col = 8 * fq + 4 * n + j;
;                                 if (col < 12) { const float xv = acc[ai][0][m][n][j] * rsqrtf(ssq[row] * (1.f / DM) + EPS) + bfp[col]; LS[((size_t)(row >> 12) * 12 + col) * SEQ + (row & (SEQ - 1))] = fminf(xv, 0.f) - log1pf(expf(-fabsf(xv))); } } }
.LBB0_621:
	global_load_dword v0, v[66:67], off offset:576
	s_waitcnt vmcnt(0) lgkmcnt(0)
	v_fmamk_f32 v0, v0, 0x3a000000, v205
	v_cmp_gt_f32_e64 s[0:1], s68, v0
	v_mul_f32_e32 v22, 0x4b800000, v0
	s_nop 0
	v_cndmask_b32_e64 v0, v0, v22, s[0:1]
	v_rsq_f32_e32 v0, v0
	s_nop 0
	v_mul_f32_e32 v22, 0x45800000, v0
	v_cndmask_b32_e64 v0, v0, v22, s[0:1]
	v_lshl_add_u64 v[22:23], v[62:63], 2, s[60:61]
	global_load_dword v22, v[22:23], off
	s_waitcnt vmcnt(0) lgkmcnt(0)
	v_fmac_f32_e32 v22, v24, v0
	v_mul_f32_e64 v23, |v22|, s88
	v_fma_f32 v24, |v22|, s88, -v23
	v_rndne_f32_e32 v30, v23
	v_fma_f32 v24, |v22|, s89, v24
	v_sub_f32_e32 v23, v23, v30
	v_add_f32_e32 v23, v23, v24
	v_exp_f32_e32 v23, v23
	v_cvt_i32_f32_e32 v24, v30
	v_cmp_ngt_f32_e64 s[0:1], |v22|, s70
	v_min_f32_e32 v0, 0, v22
	v_ldexp_f32 v23, v23, v24
	v_cndmask_b32_e64 v23, 0, v23, s[0:1]
	v_cmp_nlt_f32_e64 s[0:1], |v22|, s90
	s_nop 1
	v_cndmask_b32_e64 v24, v208, v23, s[0:1]
	v_add_f32_e32 v30, 1.0, v24
	v_add_f32_e32 v22, -1.0, v30
	v_sub_f32_e32 v23, v22, v30
	v_add_f32_e32 v23, 1.0, v23
	v_sub_f32_e32 v22, v24, v22
	v_add_f32_e32 v31, v22, v23
	v_frexp_mant_f32_e32 v22, v30
	v_cmp_gt_f32_e64 s[0:1], s3, v22
	v_cvt_f64_f32_e32 v[22:23], v30
	v_frexp_exp_i32_f64_e32 v22, v[22:23]
	v_subbrev_co_u32_e64 v36, s[0:1], 0, v22, s[0:1]
	v_sub_u32_e32 v22, 0, v36
	v_ldexp_f32 v23, v30, v22
	v_add_f32_e32 v30, -1.0, v23
	v_add_f32_e32 v32, 1.0, v23
	v_ldexp_f32 v22, v31, v22
	v_add_f32_e32 v31, 1.0, v30
	v_add_f32_e32 v33, -1.0, v32
	v_sub_f32_e32 v31, v23, v31
	v_sub_f32_e32 v23, v23, v33
	v_add_f32_e32 v31, v22, v31
	v_add_f32_e32 v22, v22, v23
	v_add_f32_e32 v37, v32, v22
	v_rcp_f32_e32 v39, v37
	v_sub_f32_e32 v23, v32, v37
	v_add_f32_e32 v38, v22, v23
	v_add_f32_e32 v23, v30, v31
	v_mul_f32_e32 v41, v23, v39
	v_sub_f32_e32 v22, v30, v23
	v_mul_f32_e32 v30, v37, v41
	v_fma_f32 v32, v41, v37, -v30
	v_fmac_f32_e32 v32, v41, v38
	v_add_f32_e32 v40, v31, v22
	v_add_f32_e32 v22, v30, v32
	v_sub_f32_e32 v31, v23, v22
	v_pk_add_f32 v[34:35], v[22:23], v[30:31] neg_lo:[0,1] neg_hi:[0,1]
	v_mov_b32_e32 v33, v22
	v_pk_add_f32 v[22:23], v[34:35], v[32:33] neg_lo:[0,1] neg_hi:[0,1]
	v_cmp_neq_f32_e64 s[0:1], s2, v24
	v_add_f32_e32 v23, v40, v23
	v_add_f32_e32 v22, v22, v23
	v_add_f32_e32 v23, v31, v22
	v_mul_f32_e32 v40, v39, v23
	v_mul_f32_e32 v30, v37, v40
	v_fma_f32 v32, v40, v37, -v30
	v_fmac_f32_e32 v32, v40, v38
	v_sub_f32_e32 v31, v31, v23
	v_add_f32_e32 v37, v22, v31
	v_add_f32_e32 v22, v30, v32
	v_sub_f32_e32 v31, v23, v22
	v_pk_add_f32 v[34:35], v[22:23], v[30:31] neg_lo:[0,1] neg_hi:[0,1]
	v_mov_b32_e32 v33, v22
	v_pk_add_f32 v[22:23], v[34:35], v[32:33] neg_lo:[0,1] neg_hi:[0,1]
	s_nop 0
	v_add_f32_e32 v23, v37, v23
	v_add_f32_e32 v22, v22, v23
	v_add_f32_e32 v23, v41, v40
	v_add_f32_e32 v22, v31, v22
	v_sub_f32_e32 v30, v23, v41
	v_mul_f32_e32 v22, v39, v22
	v_sub_f32_e32 v30, v40, v30
	v_add_f32_e32 v30, v30, v22
	v_add_f32_e32 v32, v23, v30
	v_mul_f32_e32 v33, v32, v32
	v_fmamk_f32 v22, v33, 0x3e9b6dac, v206
	v_fmaak_f32 v179, v33, v22, 0x3f2aaada
	v_cvt_f32_i32_e32 v22, v36
	v_sub_f32_e32 v23, v32, v23
	v_sub_f32_e32 v23, v30, v23
	v_ldexp_f32 v34, v23, 1
	v_mul_f32_e32 v23, v32, v33
	v_ldexp_f32 v31, v32, 1
	v_pk_mul_f32 v[32:33], v[22:23], v[178:179]
	s_nop 0
	v_fma_f32 v30, v22, s69, -v32
	v_fmac_f32_e32 v30, 0xb102e308, v22
	v_pk_add_f32 v[22:23], v[32:33], v[30:31]
	s_nop 0
	v_sub_f32_e32 v31, v23, v31
	v_sub_f32_e32 v31, v33, v31
	v_add_f32_e32 v35, v34, v31
	v_mov_b32_e32 v34, v32
	v_pk_add_f32 v[32:33], v[22:23], v[32:33] neg_lo:[0,1] neg_hi:[0,1]
	v_pk_add_f32 v[36:37], v[22:23], v[34:35]
	v_mov_b32_e32 v31, v22
	v_mov_b32_e32 v33, v37
	v_pk_add_f32 v[38:39], v[30:31], v[32:33] neg_lo:[0,1] neg_hi:[0,1]
	v_pk_add_f32 v[30:31], v[30:31], v[32:33]
	v_mov_b32_e32 v34, v35
	v_pk_add_f32 v[32:33], v[30:31], v[22:23] op_sel:[1,0] op_sel_hi:[0,1] neg_lo:[0,1] neg_hi:[0,1]
	v_pk_add_f32 v[40:41], v[36:37], v[32:33] op_sel_hi:[1,0] neg_lo:[0,1] neg_hi:[0,1]
	v_mov_b32_e32 v36, v37
	v_mov_b32_e32 v37, v31
	v_pk_mov_b32 v[32:33], v[22:23], v[32:33] op_sel:[1,0]
	v_mov_b32_e32 v35, v22
	v_pk_add_f32 v[32:33], v[36:37], v[32:33] neg_lo:[0,1] neg_hi:[0,1]
	v_mov_b32_e32 v40, v38
	v_pk_add_f32 v[22:23], v[34:35], v[32:33] neg_lo:[0,1] neg_hi:[0,1]
	v_mov_b32_e32 v39, v31
	v_pk_add_f32 v[32:33], v[40:41], v[22:23]
	s_nop 0
	v_pk_add_f32 v[34:35], v[32:33], v[32:33] op_sel:[0,1] op_sel_hi:[1,0]
	s_nop 0
	v_pk_add_f32 v[30:31], v[30:31], v[34:35] op_sel:[1,0] op_sel_hi:[0,1]
	v_mov_b32_e32 v33, v30
	v_pk_add_f32 v[36:37], v[32:33], v[38:39] neg_lo:[0,1] neg_hi:[0,1]
	v_mov_b32_e32 v23, v34
	v_sub_f32_e32 v31, v32, v36
	v_pk_add_f32 v[22:23], v[22:23], v[36:37] neg_lo:[0,1] neg_hi:[0,1]
	v_sub_f32_e32 v31, v38, v31
	v_add_f32_e32 v22, v22, v31
	v_add_f32_e32 v22, v22, v23
	v_add_f32_e32 v22, v30, v22
	v_cndmask_b32_e64 v22, v208, v22, s[0:1]
	v_cmp_lt_f32_e64 s[0:1], |v24|, s66
	s_nop 1
	v_cndmask_b32_e64 v22, v22, v24, s[0:1]
	v_sub_f32_e32 v0, v0, v22
	v_lshl_add_u64 v[22:23], v[28:29], 0, v[62:63]
	v_lshlrev_b64 v[22:23], 14, v[22:23]
	v_lshl_add_u64 v[22:23], v[26:27], 0, v[22:23]
	global_store_dword v[22:23], v0, off
	s_or_b64 exec, exec, s[84:85]
	s_and_saveexec_b64 s[84:85], s[10:11]
	s_cbranch_execz .LBB0_567
;     __device__ __forceinline__ void operator()(const f32x4 (&acc)[2][2][4][2], const pg8::Unit& u, int wr, int wc, int fr, int fq) const {
;     ...
;             if (wc == 0) {
; #pragma unroll
;                 for (int ai = 0; ai < 2; ++ai)
; #pragma unroll
;                     for (int m = 0; m < 4; ++m) { const int row = row0 + ai * 128 + m * 16;
; #pragma unroll
;                         for (int n = 0; n < 2; ++n)
; #pragma unroll
;                             for (int j = 0; j < 4; ++j) { const int col = 8 * fq + 4 * n + j;
;                                 if (col < 12) { const float xv = acc[ai][0][m][n][j] * rsqrtf(ssq[row] * (1.f / DM) + EPS) + bfp[col]; LS[((size_t)(row >> 12) * 12 + col) * SEQ + (row & (SEQ - 1))] = fminf(xv, 0.f) - log1pf(expf(-fabsf(xv))); } } }
.LBB0_622:
	global_load_dword v0, v[66:67], off offset:576
	s_waitcnt vmcnt(0) lgkmcnt(0)
	v_fmamk_f32 v0, v0, 0x3a000000, v205
	v_cmp_gt_f32_e64 s[0:1], s68, v0
	v_mul_f32_e32 v22, 0x4b800000, v0
	s_nop 0
	v_cndmask_b32_e64 v0, v0, v22, s[0:1]
	v_rsq_f32_e32 v0, v0
	s_nop 0
	v_mul_f32_e32 v22, 0x45800000, v0
	v_cndmask_b32_e64 v0, v0, v22, s[0:1]
	v_lshl_add_u64 v[22:23], v[72:73], 2, s[60:61]
	global_load_dword v22, v[22:23], off
	s_waitcnt vmcnt(0) lgkmcnt(0)
	v_fmac_f32_e32 v22, v25, v0
	v_mul_f32_e64 v23, |v22|, s88
	v_fma_f32 v24, |v22|, s88, -v23
	v_rndne_f32_e32 v25, v23
	v_fma_f32 v24, |v22|, s89, v24
	v_sub_f32_e32 v23, v23, v25
	v_add_f32_e32 v23, v23, v24
	v_exp_f32_e32 v23, v23
	v_cvt_i32_f32_e32 v24, v25
	v_cmp_ngt_f32_e64 s[0:1], |v22|, s70
	v_min_f32_e32 v0, 0, v22
	v_ldexp_f32 v23, v23, v24
	v_cndmask_b32_e64 v23, 0, v23, s[0:1]
	v_cmp_nlt_f32_e64 s[0:1], |v22|, s90
	s_nop 1
	v_cndmask_b32_e64 v40, v208, v23, s[0:1]
	v_add_f32_e32 v24, 1.0, v40
	v_add_f32_e32 v22, -1.0, v24
	v_sub_f32_e32 v23, v22, v24
	v_add_f32_e32 v23, 1.0, v23
	v_sub_f32_e32 v22, v40, v22
	v_add_f32_e32 v25, v22, v23
	v_frexp_mant_f32_e32 v22, v24
	v_cmp_gt_f32_e64 s[0:1], s3, v22
	v_cvt_f64_f32_e32 v[22:23], v24
	v_frexp_exp_i32_f64_e32 v22, v[22:23]
	v_subbrev_co_u32_e64 v34, s[0:1], 0, v22, s[0:1]
	v_sub_u32_e32 v22, 0, v34
	v_ldexp_f32 v23, v24, v22
	v_add_f32_e32 v24, -1.0, v23
	v_add_f32_e32 v30, 1.0, v23
	v_ldexp_f32 v22, v25, v22
	v_add_f32_e32 v25, 1.0, v24
	v_add_f32_e32 v31, -1.0, v30
	v_sub_f32_e32 v25, v23, v25
	v_sub_f32_e32 v23, v23, v31
	v_add_f32_e32 v25, v22, v25
	v_add_f32_e32 v22, v22, v23
	v_add_f32_e32 v35, v30, v22
	v_rcp_f32_e32 v37, v35
	v_sub_f32_e32 v23, v30, v35
	v_add_f32_e32 v36, v22, v23
	v_add_f32_e32 v23, v24, v25
	v_mul_f32_e32 v39, v23, v37
	v_sub_f32_e32 v22, v24, v23
	v_mul_f32_e32 v24, v35, v39
	v_fma_f32 v30, v39, v35, -v24
	v_fmac_f32_e32 v30, v39, v36
	v_add_f32_e32 v38, v25, v22
	v_add_f32_e32 v22, v24, v30
	v_sub_f32_e32 v25, v23, v22
	v_pk_add_f32 v[32:33], v[22:23], v[24:25] neg_lo:[0,1] neg_hi:[0,1]
	v_mov_b32_e32 v31, v22
	v_pk_add_f32 v[22:23], v[32:33], v[30:31] neg_lo:[0,1] neg_hi:[0,1]
	v_cmp_neq_f32_e64 s[0:1], s2, v40
	v_add_f32_e32 v23, v38, v23
	v_add_f32_e32 v22, v22, v23
	v_add_f32_e32 v23, v25, v22
	v_mul_f32_e32 v38, v37, v23
	v_mul_f32_e32 v24, v35, v38
	v_fma_f32 v30, v38, v35, -v24
	v_fmac_f32_e32 v30, v38, v36
	v_sub_f32_e32 v25, v25, v23
	v_add_f32_e32 v35, v22, v25
	v_add_f32_e32 v22, v24, v30
	v_sub_f32_e32 v25, v23, v22
	v_pk_add_f32 v[32:33], v[22:23], v[24:25] neg_lo:[0,1] neg_hi:[0,1]
	v_mov_b32_e32 v31, v22
	v_pk_add_f32 v[22:23], v[32:33], v[30:31] neg_lo:[0,1] neg_hi:[0,1]
	s_nop 0
	v_add_f32_e32 v23, v35, v23
	v_add_f32_e32 v22, v22, v23
	v_add_f32_e32 v23, v39, v38
	v_add_f32_e32 v22, v25, v22
	v_sub_f32_e32 v24, v23, v39
	v_mul_f32_e32 v22, v37, v22
	v_sub_f32_e32 v24, v38, v24
	v_add_f32_e32 v24, v24, v22
	v_add_f32_e32 v30, v23, v24
	v_mul_f32_e32 v31, v30, v30
	v_fmamk_f32 v22, v31, 0x3e9b6dac, v206
	v_fmaak_f32 v179, v31, v22, 0x3f2aaada
	v_cvt_f32_i32_e32 v22, v34
	v_sub_f32_e32 v23, v30, v23
	v_sub_f32_e32 v23, v24, v23
	v_ldexp_f32 v32, v23, 1
	v_mul_f32_e32 v23, v30, v31
	v_ldexp_f32 v25, v30, 1
	v_pk_mul_f32 v[30:31], v[22:23], v[178:179]
	s_nop 0
	v_fma_f32 v24, v22, s69, -v30
	v_fmac_f32_e32 v24, 0xb102e308, v22
	v_pk_add_f32 v[22:23], v[30:31], v[24:25]
	s_nop 0
	v_sub_f32_e32 v25, v23, v25
	v_sub_f32_e32 v25, v31, v25
	v_add_f32_e32 v33, v32, v25
	v_mov_b32_e32 v32, v30
	v_pk_add_f32 v[30:31], v[22:23], v[30:31] neg_lo:[0,1] neg_hi:[0,1]
	v_pk_add_f32 v[34:35], v[22:23], v[32:33]
	v_mov_b32_e32 v25, v22
	v_mov_b32_e32 v31, v35
	v_pk_add_f32 v[36:37], v[24:25], v[30:31] neg_lo:[0,1] neg_hi:[0,1]
	v_pk_add_f32 v[24:25], v[24:25], v[30:31]
	v_mov_b32_e32 v32, v33
	v_pk_add_f32 v[30:31], v[24:25], v[22:23] op_sel:[1,0] op_sel_hi:[0,1] neg_lo:[0,1] neg_hi:[0,1]
	v_pk_add_f32 v[38:39], v[34:35], v[30:31] op_sel_hi:[1,0] neg_lo:[0,1] neg_hi:[0,1]
	v_mov_b32_e32 v34, v35
	v_mov_b32_e32 v35, v25
	v_pk_mov_b32 v[30:31], v[22:23], v[30:31] op_sel:[1,0]
	v_mov_b32_e32 v33, v22
	v_pk_add_f32 v[30:31], v[34:35], v[30:31] neg_lo:[0,1] neg_hi:[0,1]
	v_mov_b32_e32 v38, v36
	v_pk_add_f32 v[22:23], v[32:33], v[30:31] neg_lo:[0,1] neg_hi:[0,1]
	v_mov_b32_e32 v37, v25
	v_pk_add_f32 v[30:31], v[38:39], v[22:23]
	s_nop 0
	v_pk_add_f32 v[32:33], v[30:31], v[30:31] op_sel:[0,1] op_sel_hi:[1,0]
	s_nop 0
	v_pk_add_f32 v[24:25], v[24:25], v[32:33] op_sel:[1,0] op_sel_hi:[0,1]
	v_mov_b32_e32 v31, v24
	v_pk_add_f32 v[34:35], v[30:31], v[36:37] neg_lo:[0,1] neg_hi:[0,1]
	v_mov_b32_e32 v23, v32
	v_sub_f32_e32 v25, v30, v34
	v_pk_add_f32 v[22:23], v[22:23], v[34:35] neg_lo:[0,1] neg_hi:[0,1]
	v_sub_f32_e32 v25, v36, v25
	v_add_f32_e32 v22, v22, v25
	v_add_f32_e32 v22, v22, v23
	v_add_f32_e32 v22, v24, v22
	v_cndmask_b32_e64 v22, v208, v22, s[0:1]
	v_cmp_lt_f32_e64 s[0:1], |v40|, s66
	s_nop 1
	v_cndmask_b32_e64 v22, v22, v40, s[0:1]
	v_sub_f32_e32 v0, v0, v22
	v_lshl_add_u64 v[22:23], v[28:29], 0, v[72:73]
	v_lshlrev_b64 v[22:23], 14, v[22:23]
	v_lshl_add_u64 v[22:23], v[26:27], 0, v[22:23]
	global_store_dword v[22:23], v0, off
	s_or_b64 exec, exec, s[84:85]
	s_and_saveexec_b64 s[84:85], s[12:13]
	s_cbranch_execz .LBB0_568
;     __device__ __forceinline__ void operator()(const f32x4 (&acc)[2][2][4][2], const pg8::Unit& u, int wr, int wc, int fr, int fq) const {
;     ...
;             if (wc == 0) {
; #pragma unroll
;                 for (int ai = 0; ai < 2; ++ai)
; #pragma unroll
;                     for (int m = 0; m < 4; ++m) { const int row = row0 + ai * 128 + m * 16;
; #pragma unroll
;                         for (int n = 0; n < 2; ++n)
; #pragma unroll
;                             for (int j = 0; j < 4; ++j) { const int col = 8 * fq + 4 * n + j;
;                                 if (col < 12) { const float xv = acc[ai][0][m][n][j] * rsqrtf(ssq[row] * (1.f / DM) + EPS) + bfp[col]; LS[((size_t)(row >> 12) * 12 + col) * SEQ + (row & (SEQ - 1))] = fminf(xv, 0.f) - log1pf(expf(-fabsf(xv))); } } }
.LBB0_623:
	global_load_dword v0, v[66:67], off offset:576
	s_waitcnt vmcnt(0) lgkmcnt(0)
	v_fmamk_f32 v0, v0, 0x3a000000, v205
	v_cmp_gt_f32_e64 s[0:1], s68, v0
	v_mul_f32_e32 v22, 0x4b800000, v0
	s_nop 0
	v_cndmask_b32_e64 v0, v0, v22, s[0:1]
	v_rsq_f32_e32 v0, v0
	s_nop 0
	v_mul_f32_e32 v22, 0x45800000, v0
	v_cndmask_b32_e64 v0, v0, v22, s[0:1]
	v_lshl_add_u64 v[22:23], v[64:65], 2, s[60:61]
	global_load_dword v22, v[22:23], off
	s_waitcnt vmcnt(0) lgkmcnt(0)
	v_fmac_f32_e32 v22, v18, v0
	v_mul_f32_e64 v18, |v22|, s88
	v_fma_f32 v23, |v22|, s88, -v18
	v_rndne_f32_e32 v24, v18
	v_fma_f32 v23, |v22|, s89, v23
	v_sub_f32_e32 v18, v18, v24
	v_add_f32_e32 v18, v18, v23
	v_exp_f32_e32 v18, v18
	v_cvt_i32_f32_e32 v23, v24
	v_cmp_ngt_f32_e64 s[0:1], |v22|, s70
	v_min_f32_e32 v0, 0, v22
	v_ldexp_f32 v18, v18, v23
	v_cndmask_b32_e64 v18, 0, v18, s[0:1]
	v_cmp_nlt_f32_e64 s[0:1], |v22|, s90
	s_nop 1
	v_cndmask_b32_e64 v18, v208, v18, s[0:1]
	v_add_f32_e32 v24, 1.0, v18
	v_add_f32_e32 v22, -1.0, v24
	v_sub_f32_e32 v23, v22, v24
	v_add_f32_e32 v23, 1.0, v23
	v_sub_f32_e32 v22, v18, v22
	v_add_f32_e32 v25, v22, v23
	v_frexp_mant_f32_e32 v22, v24
	v_cmp_gt_f32_e64 s[0:1], s3, v22
	v_cvt_f64_f32_e32 v[22:23], v24
	v_frexp_exp_i32_f64_e32 v22, v[22:23]
	v_subbrev_co_u32_e64 v34, s[0:1], 0, v22, s[0:1]
	v_sub_u32_e32 v22, 0, v34
	v_ldexp_f32 v23, v24, v22
	v_add_f32_e32 v24, -1.0, v23
	v_add_f32_e32 v30, 1.0, v23
	v_ldexp_f32 v22, v25, v22
	v_add_f32_e32 v25, 1.0, v24
	v_add_f32_e32 v31, -1.0, v30
	v_sub_f32_e32 v25, v23, v25
	v_sub_f32_e32 v23, v23, v31
	v_add_f32_e32 v25, v22, v25
	v_add_f32_e32 v22, v22, v23
	v_add_f32_e32 v35, v30, v22
	v_rcp_f32_e32 v37, v35
	v_sub_f32_e32 v23, v30, v35
	v_add_f32_e32 v36, v22, v23
	v_add_f32_e32 v23, v24, v25
	v_mul_f32_e32 v39, v23, v37
	v_sub_f32_e32 v22, v24, v23
	v_mul_f32_e32 v24, v35, v39
	v_fma_f32 v30, v39, v35, -v24
	v_fmac_f32_e32 v30, v39, v36
	v_add_f32_e32 v38, v25, v22
	v_add_f32_e32 v22, v24, v30
	v_sub_f32_e32 v25, v23, v22
	v_pk_add_f32 v[32:33], v[22:23], v[24:25] neg_lo:[0,1] neg_hi:[0,1]
	v_mov_b32_e32 v31, v22
	v_pk_add_f32 v[22:23], v[32:33], v[30:31] neg_lo:[0,1] neg_hi:[0,1]
	v_cmp_neq_f32_e64 s[0:1], s2, v18
	v_add_f32_e32 v23, v38, v23
	v_add_f32_e32 v22, v22, v23
	v_add_f32_e32 v23, v25, v22
	v_mul_f32_e32 v38, v37, v23
	v_mul_f32_e32 v24, v35, v38
	v_fma_f32 v30, v38, v35, -v24
	v_fmac_f32_e32 v30, v38, v36
	v_sub_f32_e32 v25, v25, v23
	v_add_f32_e32 v35, v22, v25
	v_add_f32_e32 v22, v24, v30
	v_sub_f32_e32 v25, v23, v22
	v_pk_add_f32 v[32:33], v[22:23], v[24:25] neg_lo:[0,1] neg_hi:[0,1]
	v_mov_b32_e32 v31, v22
	v_pk_add_f32 v[22:23], v[32:33], v[30:31] neg_lo:[0,1] neg_hi:[0,1]
	s_nop 0
	v_add_f32_e32 v23, v35, v23
	v_add_f32_e32 v22, v22, v23
	v_add_f32_e32 v23, v39, v38
	v_add_f32_e32 v22, v25, v22
	v_sub_f32_e32 v24, v23, v39
	v_mul_f32_e32 v22, v37, v22
	v_sub_f32_e32 v24, v38, v24
	v_add_f32_e32 v24, v24, v22
	v_add_f32_e32 v30, v23, v24
	v_mul_f32_e32 v31, v30, v30
	v_fmamk_f32 v22, v31, 0x3e9b6dac, v206
	v_fmaak_f32 v179, v31, v22, 0x3f2aaada
	v_cvt_f32_i32_e32 v22, v34
	v_sub_f32_e32 v23, v30, v23
	v_sub_f32_e32 v23, v24, v23
	v_ldexp_f32 v32, v23, 1
	v_mul_f32_e32 v23, v30, v31
	v_ldexp_f32 v25, v30, 1
	v_pk_mul_f32 v[30:31], v[22:23], v[178:179]
	s_nop 0
	v_fma_f32 v24, v22, s69, -v30
	v_fmac_f32_e32 v24, 0xb102e308, v22
	v_pk_add_f32 v[22:23], v[30:31], v[24:25]
	s_nop 0
	v_sub_f32_e32 v25, v23, v25
	v_sub_f32_e32 v25, v31, v25
	v_add_f32_e32 v33, v32, v25
	v_mov_b32_e32 v32, v30
	v_pk_add_f32 v[30:31], v[22:23], v[30:31] neg_lo:[0,1] neg_hi:[0,1]
	v_pk_add_f32 v[34:35], v[22:23], v[32:33]
	v_mov_b32_e32 v25, v22
	v_mov_b32_e32 v31, v35
	v_pk_add_f32 v[36:37], v[24:25], v[30:31] neg_lo:[0,1] neg_hi:[0,1]
	v_pk_add_f32 v[24:25], v[24:25], v[30:31]
	v_mov_b32_e32 v32, v33
	v_pk_add_f32 v[30:31], v[24:25], v[22:23] op_sel:[1,0] op_sel_hi:[0,1] neg_lo:[0,1] neg_hi:[0,1]
	v_pk_add_f32 v[38:39], v[34:35], v[30:31] op_sel_hi:[1,0] neg_lo:[0,1] neg_hi:[0,1]
	v_mov_b32_e32 v34, v35
	v_mov_b32_e32 v35, v25
	v_pk_mov_b32 v[30:31], v[22:23], v[30:31] op_sel:[1,0]
	v_mov_b32_e32 v33, v22
	v_pk_add_f32 v[30:31], v[34:35], v[30:31] neg_lo:[0,1] neg_hi:[0,1]
	v_mov_b32_e32 v38, v36
	v_pk_add_f32 v[22:23], v[32:33], v[30:31] neg_lo:[0,1] neg_hi:[0,1]
	v_mov_b32_e32 v37, v25
	v_pk_add_f32 v[30:31], v[38:39], v[22:23]
	s_nop 0
	v_pk_add_f32 v[32:33], v[30:31], v[30:31] op_sel:[0,1] op_sel_hi:[1,0]
	s_nop 0
	v_pk_add_f32 v[24:25], v[24:25], v[32:33] op_sel:[1,0] op_sel_hi:[0,1]
	v_mov_b32_e32 v31, v24
	v_pk_add_f32 v[34:35], v[30:31], v[36:37] neg_lo:[0,1] neg_hi:[0,1]
	v_mov_b32_e32 v23, v32
	v_sub_f32_e32 v25, v30, v34
	v_pk_add_f32 v[22:23], v[22:23], v[34:35] neg_lo:[0,1] neg_hi:[0,1]
	v_sub_f32_e32 v25, v36, v25
	v_add_f32_e32 v22, v22, v25
	v_add_f32_e32 v22, v22, v23
	v_add_f32_e32 v22, v24, v22
	v_cndmask_b32_e64 v22, v208, v22, s[0:1]
	v_cmp_lt_f32_e64 s[0:1], |v18|, s66
	s_nop 1
	v_cndmask_b32_e64 v18, v22, v18, s[0:1]
	v_lshl_add_u64 v[22:23], v[28:29], 0, v[64:65]
	v_lshlrev_b64 v[22:23], 14, v[22:23]
	v_sub_f32_e32 v0, v0, v18
	v_lshl_add_u64 v[22:23], v[26:27], 0, v[22:23]
	global_store_dword v[22:23], v0, off
	s_or_b64 exec, exec, s[84:85]
	s_and_saveexec_b64 s[84:85], s[14:15]
	s_cbranch_execz .LBB0_569
;     __device__ __forceinline__ void operator()(const f32x4 (&acc)[2][2][4][2], const pg8::Unit& u, int wr, int wc, int fr, int fq) const {
;     ...
;             if (wc == 0) {
; #pragma unroll
;                 for (int ai = 0; ai < 2; ++ai)
; #pragma unroll
;                     for (int m = 0; m < 4; ++m) { const int row = row0 + ai * 128 + m * 16;
; #pragma unroll
;                         for (int n = 0; n < 2; ++n)
; #pragma unroll
;                             for (int j = 0; j < 4; ++j) { const int col = 8 * fq + 4 * n + j;
;                                 if (col < 12) { const float xv = acc[ai][0][m][n][j] * rsqrtf(ssq[row] * (1.f / DM) + EPS) + bfp[col]; LS[((size_t)(row >> 12) * 12 + col) * SEQ + (row & (SEQ - 1))] = fminf(xv, 0.f) - log1pf(expf(-fabsf(xv))); } } }
.LBB0_624:
	global_load_dword v0, v[66:67], off offset:576
	v_lshl_add_u64 v[22:23], v[74:75], 2, s[60:61]
	s_waitcnt vmcnt(0) lgkmcnt(0)
	v_fmamk_f32 v0, v0, 0x3a000000, v205
	v_cmp_gt_f32_e64 s[0:1], s68, v0
	v_mul_f32_e32 v18, 0x4b800000, v0
	s_nop 0
	v_cndmask_b32_e64 v0, v0, v18, s[0:1]
	v_rsq_f32_e32 v0, v0
	s_nop 0
	v_mul_f32_e32 v18, 0x45800000, v0
	v_cndmask_b32_e64 v0, v0, v18, s[0:1]
	global_load_dword v18, v[22:23], off
	s_waitcnt vmcnt(0) lgkmcnt(0)
	v_fmac_f32_e32 v18, v19, v0
	v_mul_f32_e64 v19, |v18|, s88
	v_fma_f32 v22, |v18|, s88, -v19
	v_rndne_f32_e32 v23, v19
	v_fma_f32 v22, |v18|, s89, v22
	v_sub_f32_e32 v19, v19, v23
	v_add_f32_e32 v19, v19, v22
	v_exp_f32_e32 v19, v19
	v_cvt_i32_f32_e32 v22, v23
	v_cmp_ngt_f32_e64 s[0:1], |v18|, s70
	v_min_f32_e32 v0, 0, v18
	v_ldexp_f32 v19, v19, v22
	v_cndmask_b32_e64 v19, 0, v19, s[0:1]
	v_cmp_nlt_f32_e64 s[0:1], |v18|, s90
	s_nop 1
	v_cndmask_b32_e64 v38, v208, v19, s[0:1]
	v_add_f32_e32 v22, 1.0, v38
	v_add_f32_e32 v18, -1.0, v22
	v_sub_f32_e32 v19, v18, v22
	v_add_f32_e32 v19, 1.0, v19
	v_sub_f32_e32 v18, v38, v18
	v_add_f32_e32 v23, v18, v19
	v_frexp_mant_f32_e32 v18, v22
	v_cmp_gt_f32_e64 s[0:1], s3, v18
	v_cvt_f64_f32_e32 v[18:19], v22
	v_frexp_exp_i32_f64_e32 v18, v[18:19]
	v_subbrev_co_u32_e64 v32, s[0:1], 0, v18, s[0:1]
	v_sub_u32_e32 v18, 0, v32
	v_ldexp_f32 v19, v22, v18
	v_add_f32_e32 v22, -1.0, v19
	v_add_f32_e32 v24, 1.0, v19
	v_ldexp_f32 v18, v23, v18
	v_add_f32_e32 v23, 1.0, v22
	v_add_f32_e32 v25, -1.0, v24
	v_sub_f32_e32 v23, v19, v23
	v_sub_f32_e32 v19, v19, v25
	v_add_f32_e32 v23, v18, v23
	v_add_f32_e32 v18, v18, v19
	v_add_f32_e32 v33, v24, v18
	v_rcp_f32_e32 v35, v33
	v_sub_f32_e32 v19, v24, v33
	v_add_f32_e32 v34, v18, v19
	v_add_f32_e32 v19, v22, v23
	v_mul_f32_e32 v37, v19, v35
	v_sub_f32_e32 v18, v22, v19
	v_mul_f32_e32 v22, v33, v37
	v_fma_f32 v24, v37, v33, -v22
	v_fmac_f32_e32 v24, v37, v34
	v_add_f32_e32 v36, v23, v18
	v_add_f32_e32 v18, v22, v24
	v_sub_f32_e32 v23, v19, v18
	v_pk_add_f32 v[30:31], v[18:19], v[22:23] neg_lo:[0,1] neg_hi:[0,1]
	v_mov_b32_e32 v25, v18
	v_pk_add_f32 v[18:19], v[30:31], v[24:25] neg_lo:[0,1] neg_hi:[0,1]
	v_cmp_neq_f32_e64 s[0:1], s2, v38
	v_add_f32_e32 v19, v36, v19
	v_add_f32_e32 v18, v18, v19
	v_add_f32_e32 v19, v23, v18
	v_mul_f32_e32 v36, v35, v19
	v_mul_f32_e32 v22, v33, v36
	v_fma_f32 v24, v36, v33, -v22
	v_fmac_f32_e32 v24, v36, v34
	v_sub_f32_e32 v23, v23, v19
	v_add_f32_e32 v33, v18, v23
	v_add_f32_e32 v18, v22, v24
	v_sub_f32_e32 v23, v19, v18
	v_pk_add_f32 v[30:31], v[18:19], v[22:23] neg_lo:[0,1] neg_hi:[0,1]
	v_mov_b32_e32 v25, v18
	v_pk_add_f32 v[18:19], v[30:31], v[24:25] neg_lo:[0,1] neg_hi:[0,1]
	s_nop 0
	v_add_f32_e32 v19, v33, v19
	v_add_f32_e32 v18, v18, v19
	v_add_f32_e32 v19, v37, v36
	v_add_f32_e32 v18, v23, v18
	v_sub_f32_e32 v22, v19, v37
	v_mul_f32_e32 v18, v35, v18
	v_sub_f32_e32 v22, v36, v22
	v_add_f32_e32 v22, v22, v18
	v_add_f32_e32 v24, v19, v22
	v_mul_f32_e32 v25, v24, v24
	v_fmamk_f32 v18, v25, 0x3e9b6dac, v206
	v_fmaak_f32 v179, v25, v18, 0x3f2aaada
	v_cvt_f32_i32_e32 v18, v32
	v_sub_f32_e32 v19, v24, v19
	v_sub_f32_e32 v19, v22, v19
	v_ldexp_f32 v30, v19, 1
	v_mul_f32_e32 v19, v24, v25
	v_ldexp_f32 v23, v24, 1
	v_pk_mul_f32 v[24:25], v[18:19], v[178:179]
	s_nop 0
	v_fma_f32 v22, v18, s69, -v24
	v_fmac_f32_e32 v22, 0xb102e308, v18
	v_pk_add_f32 v[18:19], v[24:25], v[22:23]
	s_nop 0
	v_sub_f32_e32 v23, v19, v23
	v_sub_f32_e32 v23, v25, v23
	v_add_f32_e32 v31, v30, v23
	v_mov_b32_e32 v30, v24
	v_pk_add_f32 v[24:25], v[18:19], v[24:25] neg_lo:[0,1] neg_hi:[0,1]
	v_pk_add_f32 v[32:33], v[18:19], v[30:31]
	v_mov_b32_e32 v23, v18
	v_mov_b32_e32 v25, v33
	v_pk_add_f32 v[34:35], v[22:23], v[24:25] neg_lo:[0,1] neg_hi:[0,1]
	v_pk_add_f32 v[22:23], v[22:23], v[24:25]
	v_mov_b32_e32 v30, v31
	v_pk_add_f32 v[24:25], v[22:23], v[18:19] op_sel:[1,0] op_sel_hi:[0,1] neg_lo:[0,1] neg_hi:[0,1]
	v_pk_add_f32 v[36:37], v[32:33], v[24:25] op_sel_hi:[1,0] neg_lo:[0,1] neg_hi:[0,1]
	v_mov_b32_e32 v32, v33
	v_mov_b32_e32 v33, v23
	v_pk_mov_b32 v[24:25], v[18:19], v[24:25] op_sel:[1,0]
	v_mov_b32_e32 v31, v18
	v_pk_add_f32 v[24:25], v[32:33], v[24:25] neg_lo:[0,1] neg_hi:[0,1]
	v_mov_b32_e32 v36, v34
	v_pk_add_f32 v[18:19], v[30:31], v[24:25] neg_lo:[0,1] neg_hi:[0,1]
	v_mov_b32_e32 v35, v23
	v_pk_add_f32 v[24:25], v[36:37], v[18:19]
	s_nop 0
	v_pk_add_f32 v[30:31], v[24:25], v[24:25] op_sel:[0,1] op_sel_hi:[1,0]
	s_nop 0
	v_pk_add_f32 v[22:23], v[22:23], v[30:31] op_sel:[1,0] op_sel_hi:[0,1]
	v_mov_b32_e32 v25, v22
	v_pk_add_f32 v[32:33], v[24:25], v[34:35] neg_lo:[0,1] neg_hi:[0,1]
	v_mov_b32_e32 v19, v30
	v_sub_f32_e32 v23, v24, v32
	v_pk_add_f32 v[18:19], v[18:19], v[32:33] neg_lo:[0,1] neg_hi:[0,1]
	v_sub_f32_e32 v23, v34, v23
	v_add_f32_e32 v18, v18, v23
	v_add_f32_e32 v18, v18, v19
	v_add_f32_e32 v18, v22, v18
	v_cndmask_b32_e64 v18, v208, v18, s[0:1]
	v_cmp_lt_f32_e64 s[0:1], |v38|, s66
	s_nop 1
	v_cndmask_b32_e64 v18, v18, v38, s[0:1]
	v_sub_f32_e32 v0, v0, v18
	v_lshl_add_u64 v[18:19], v[28:29], 0, v[74:75]
	v_lshlrev_b64 v[18:19], 14, v[18:19]
	v_lshl_add_u64 v[18:19], v[26:27], 0, v[18:19]
	global_store_dword v[18:19], v0, off
	s_or_b64 exec, exec, s[84:85]
	s_and_saveexec_b64 s[84:85], s[16:17]
	s_cbranch_execz .LBB0_570
;     __device__ __forceinline__ void operator()(const f32x4 (&acc)[2][2][4][2], const pg8::Unit& u, int wr, int wc, int fr, int fq) const {
;     ...
;             if (wc == 0) {
; #pragma unroll
;                 for (int ai = 0; ai < 2; ++ai)
; #pragma unroll
;                     for (int m = 0; m < 4; ++m) { const int row = row0 + ai * 128 + m * 16;
; #pragma unroll
;                         for (int n = 0; n < 2; ++n)
; #pragma unroll
;                             for (int j = 0; j < 4; ++j) { const int col = 8 * fq + 4 * n + j;
;                                 if (col < 12) { const float xv = acc[ai][0][m][n][j] * rsqrtf(ssq[row] * (1.f / DM) + EPS) + bfp[col]; LS[((size_t)(row >> 12) * 12 + col) * SEQ + (row & (SEQ - 1))] = fminf(xv, 0.f) - log1pf(expf(-fabsf(xv))); } } }
.LBB0_625:
	global_load_dword v0, v[66:67], off offset:576
	s_waitcnt vmcnt(0) lgkmcnt(0)
	v_fmamk_f32 v0, v0, 0x3a000000, v205
	v_cmp_gt_f32_e64 s[0:1], s68, v0
	v_mul_f32_e32 v18, 0x4b800000, v0
	s_nop 0
	v_cndmask_b32_e64 v0, v0, v18, s[0:1]
	v_rsq_f32_e32 v0, v0
	s_nop 0
	v_mul_f32_e32 v18, 0x45800000, v0
	v_cndmask_b32_e64 v0, v0, v18, s[0:1]
	v_lshl_add_u64 v[18:19], v[58:59], 2, s[60:61]
	global_load_dword v18, v[18:19], off
	s_waitcnt vmcnt(0) lgkmcnt(0)
	v_fmac_f32_e32 v18, v20, v0
	v_mul_f32_e64 v19, |v18|, s88
	v_fma_f32 v20, |v18|, s88, -v19
	v_rndne_f32_e32 v22, v19
	v_fma_f32 v20, |v18|, s89, v20
	v_sub_f32_e32 v19, v19, v22
	v_add_f32_e32 v19, v19, v20
	v_exp_f32_e32 v19, v19
	v_cvt_i32_f32_e32 v20, v22
	v_cmp_ngt_f32_e64 s[0:1], |v18|, s70
	v_min_f32_e32 v0, 0, v18
	v_ldexp_f32 v19, v19, v20
	v_cndmask_b32_e64 v19, 0, v19, s[0:1]
	v_cmp_nlt_f32_e64 s[0:1], |v18|, s90
	s_nop 1
	v_cndmask_b32_e64 v20, v208, v19, s[0:1]
	v_add_f32_e32 v22, 1.0, v20
	v_add_f32_e32 v18, -1.0, v22
	v_sub_f32_e32 v19, v18, v22
	v_add_f32_e32 v19, 1.0, v19
	v_sub_f32_e32 v18, v20, v18
	v_add_f32_e32 v23, v18, v19
	v_frexp_mant_f32_e32 v18, v22
	v_cmp_gt_f32_e64 s[0:1], s3, v18
	v_cvt_f64_f32_e32 v[18:19], v22
	v_frexp_exp_i32_f64_e32 v18, v[18:19]
	v_subbrev_co_u32_e64 v32, s[0:1], 0, v18, s[0:1]
	v_sub_u32_e32 v18, 0, v32
	v_ldexp_f32 v19, v22, v18
	v_add_f32_e32 v22, -1.0, v19
	v_add_f32_e32 v24, 1.0, v19
	v_ldexp_f32 v18, v23, v18
	v_add_f32_e32 v23, 1.0, v22
	v_add_f32_e32 v25, -1.0, v24
	v_sub_f32_e32 v23, v19, v23
	v_sub_f32_e32 v19, v19, v25
	v_add_f32_e32 v23, v18, v23
	v_add_f32_e32 v18, v18, v19
	v_add_f32_e32 v33, v24, v18
	v_rcp_f32_e32 v35, v33
	v_sub_f32_e32 v19, v24, v33
	v_add_f32_e32 v34, v18, v19
	v_add_f32_e32 v19, v22, v23
	v_mul_f32_e32 v37, v19, v35
	v_sub_f32_e32 v18, v22, v19
	v_mul_f32_e32 v22, v33, v37
	v_fma_f32 v24, v37, v33, -v22
	v_fmac_f32_e32 v24, v37, v34
	v_add_f32_e32 v36, v23, v18
	v_add_f32_e32 v18, v22, v24
	v_sub_f32_e32 v23, v19, v18
	v_pk_add_f32 v[30:31], v[18:19], v[22:23] neg_lo:[0,1] neg_hi:[0,1]
	v_mov_b32_e32 v25, v18
	v_pk_add_f32 v[18:19], v[30:31], v[24:25] neg_lo:[0,1] neg_hi:[0,1]
	v_cmp_neq_f32_e64 s[0:1], s2, v20
	v_add_f32_e32 v19, v36, v19
	v_add_f32_e32 v18, v18, v19
	v_add_f32_e32 v19, v23, v18
	v_mul_f32_e32 v36, v35, v19
	v_mul_f32_e32 v22, v33, v36
	v_fma_f32 v24, v36, v33, -v22
	v_fmac_f32_e32 v24, v36, v34
	v_sub_f32_e32 v23, v23, v19
	v_add_f32_e32 v33, v18, v23
	v_add_f32_e32 v18, v22, v24
	v_sub_f32_e32 v23, v19, v18
	v_pk_add_f32 v[30:31], v[18:19], v[22:23] neg_lo:[0,1] neg_hi:[0,1]
	v_mov_b32_e32 v25, v18
	v_pk_add_f32 v[18:19], v[30:31], v[24:25] neg_lo:[0,1] neg_hi:[0,1]
	s_nop 0
	v_add_f32_e32 v19, v33, v19
	v_add_f32_e32 v18, v18, v19
	v_add_f32_e32 v19, v37, v36
	v_add_f32_e32 v18, v23, v18
	v_sub_f32_e32 v22, v19, v37
	v_mul_f32_e32 v18, v35, v18
	v_sub_f32_e32 v22, v36, v22
	v_add_f32_e32 v22, v22, v18
	v_add_f32_e32 v24, v19, v22
	v_mul_f32_e32 v25, v24, v24
	v_fmamk_f32 v18, v25, 0x3e9b6dac, v206
	v_fmaak_f32 v179, v25, v18, 0x3f2aaada
	v_cvt_f32_i32_e32 v18, v32
	v_sub_f32_e32 v19, v24, v19
	v_sub_f32_e32 v19, v22, v19
	v_ldexp_f32 v30, v19, 1
	v_mul_f32_e32 v19, v24, v25
	v_ldexp_f32 v23, v24, 1
	v_pk_mul_f32 v[24:25], v[18:19], v[178:179]
	s_nop 0
	v_fma_f32 v22, v18, s69, -v24
	v_fmac_f32_e32 v22, 0xb102e308, v18
	v_pk_add_f32 v[18:19], v[24:25], v[22:23]
	s_nop 0
	v_sub_f32_e32 v23, v19, v23
	v_sub_f32_e32 v23, v25, v23
	v_add_f32_e32 v31, v30, v23
	v_mov_b32_e32 v30, v24
	v_pk_add_f32 v[24:25], v[18:19], v[24:25] neg_lo:[0,1] neg_hi:[0,1]
	v_pk_add_f32 v[32:33], v[18:19], v[30:31]
	v_mov_b32_e32 v23, v18
	v_mov_b32_e32 v25, v33
	v_pk_add_f32 v[34:35], v[22:23], v[24:25] neg_lo:[0,1] neg_hi:[0,1]
	v_pk_add_f32 v[22:23], v[22:23], v[24:25]
	v_mov_b32_e32 v30, v31
	v_pk_add_f32 v[24:25], v[22:23], v[18:19] op_sel:[1,0] op_sel_hi:[0,1] neg_lo:[0,1] neg_hi:[0,1]
	v_pk_add_f32 v[36:37], v[32:33], v[24:25] op_sel_hi:[1,0] neg_lo:[0,1] neg_hi:[0,1]
	v_mov_b32_e32 v32, v33
	v_mov_b32_e32 v33, v23
	v_pk_mov_b32 v[24:25], v[18:19], v[24:25] op_sel:[1,0]
	v_mov_b32_e32 v31, v18
	v_pk_add_f32 v[24:25], v[32:33], v[24:25] neg_lo:[0,1] neg_hi:[0,1]
	v_mov_b32_e32 v36, v34
	v_pk_add_f32 v[18:19], v[30:31], v[24:25] neg_lo:[0,1] neg_hi:[0,1]
	v_mov_b32_e32 v35, v23
	v_pk_add_f32 v[24:25], v[36:37], v[18:19]
	s_nop 0
	v_pk_add_f32 v[30:31], v[24:25], v[24:25] op_sel:[0,1] op_sel_hi:[1,0]
	s_nop 0
	v_pk_add_f32 v[22:23], v[22:23], v[30:31] op_sel:[1,0] op_sel_hi:[0,1]
	v_mov_b32_e32 v25, v22
	v_pk_add_f32 v[32:33], v[24:25], v[34:35] neg_lo:[0,1] neg_hi:[0,1]
	v_mov_b32_e32 v19, v30
	v_sub_f32_e32 v23, v24, v32
	v_pk_add_f32 v[18:19], v[18:19], v[32:33] neg_lo:[0,1] neg_hi:[0,1]
	v_sub_f32_e32 v23, v34, v23
	v_add_f32_e32 v18, v18, v23
	v_add_f32_e32 v18, v18, v19
	v_add_f32_e32 v18, v22, v18
	v_cndmask_b32_e64 v18, v208, v18, s[0:1]
	v_cmp_lt_f32_e64 s[0:1], |v20|, s66
	s_nop 1
	v_cndmask_b32_e64 v18, v18, v20, s[0:1]
	v_sub_f32_e32 v0, v0, v18
	v_lshl_add_u64 v[18:19], v[28:29], 0, v[58:59]
	v_lshlrev_b64 v[18:19], 14, v[18:19]
	v_lshl_add_u64 v[18:19], v[26:27], 0, v[18:19]
	global_store_dword v[18:19], v0, off
	s_or_b64 exec, exec, s[84:85]
	s_and_saveexec_b64 s[84:85], s[18:19]
	s_cbranch_execnz .LBB0_571
	s_branch .LBB0_572
;     __device__ __forceinline__ void operator()(const f32x4 (&acc)[2][2][4][2], const pg8::Unit& u, int wr, int wc, int fr, int fq) const {
;     ...
;             if (wc == 0) {
; #pragma unroll
;                 for (int ai = 0; ai < 2; ++ai)
; #pragma unroll
;                     for (int m = 0; m < 4; ++m) { const int row = row0 + ai * 128 + m * 16;
; #pragma unroll
;                         for (int n = 0; n < 2; ++n)
; #pragma unroll
;                             for (int j = 0; j < 4; ++j) { const int col = 8 * fq + 4 * n + j;
;                                 if (col < 12) { const float xv = acc[ai][0][m][n][j] * rsqrtf(ssq[row] * (1.f / DM) + EPS) + bfp[col]; LS[((size_t)(row >> 12) * 12 + col) * SEQ + (row & (SEQ - 1))] = fminf(xv, 0.f) - log1pf(expf(-fabsf(xv))); } } }
.LBB0_626:
	global_load_dword v0, v[66:67], off offset:640
	s_waitcnt vmcnt(0) lgkmcnt(0)
	v_fmamk_f32 v0, v0, 0x3a000000, v205
	v_cmp_gt_f32_e64 s[0:1], s68, v0
	v_mul_f32_e32 v22, 0x4b800000, v0
	s_nop 0
	v_cndmask_b32_e64 v0, v0, v22, s[0:1]
	v_rsq_f32_e32 v0, v0
	s_nop 0
	v_mul_f32_e32 v22, 0x45800000, v0
	v_cndmask_b32_e64 v0, v0, v22, s[0:1]
	v_lshl_add_u64 v[22:23], v[68:69], 2, s[60:61]
	global_load_dword v22, v[22:23], off
	s_waitcnt vmcnt(0) lgkmcnt(0)
	v_fmac_f32_e32 v22, v14, v0
	v_mul_f32_e64 v14, |v22|, s88
	v_fma_f32 v23, |v22|, s88, -v14
	v_rndne_f32_e32 v24, v14
	v_fma_f32 v23, |v22|, s89, v23
	v_sub_f32_e32 v14, v14, v24
	v_add_f32_e32 v14, v14, v23
	v_exp_f32_e32 v14, v14
	v_cvt_i32_f32_e32 v23, v24
	v_cmp_ngt_f32_e64 s[0:1], |v22|, s70
	v_min_f32_e32 v0, 0, v22
	v_ldexp_f32 v14, v14, v23
	v_cndmask_b32_e64 v14, 0, v14, s[0:1]
	v_cmp_nlt_f32_e64 s[0:1], |v22|, s90
	s_nop 1
	v_cndmask_b32_e64 v14, v208, v14, s[0:1]
	v_add_f32_e32 v24, 1.0, v14
	v_add_f32_e32 v22, -1.0, v24
	v_sub_f32_e32 v23, v22, v24
	v_add_f32_e32 v23, 1.0, v23
	v_sub_f32_e32 v22, v14, v22
	v_add_f32_e32 v25, v22, v23
	v_frexp_mant_f32_e32 v22, v24
	v_cmp_gt_f32_e64 s[0:1], s3, v22
	v_cvt_f64_f32_e32 v[22:23], v24
	v_frexp_exp_i32_f64_e32 v22, v[22:23]
	v_subbrev_co_u32_e64 v30, s[0:1], 0, v22, s[0:1]
	v_sub_u32_e32 v22, 0, v30
	v_ldexp_f32 v23, v24, v22
	v_add_f32_e32 v24, -1.0, v23
	v_add_f32_e32 v26, 1.0, v23
	v_ldexp_f32 v22, v25, v22
	v_add_f32_e32 v25, 1.0, v24
	v_add_f32_e32 v27, -1.0, v26
	v_sub_f32_e32 v25, v23, v25
	v_sub_f32_e32 v23, v23, v27
	v_add_f32_e32 v25, v22, v25
	v_add_f32_e32 v22, v22, v23
	v_add_f32_e32 v31, v26, v22
	v_rcp_f32_e32 v33, v31
	v_sub_f32_e32 v23, v26, v31
	v_add_f32_e32 v32, v22, v23
	v_add_f32_e32 v23, v24, v25
	v_mul_f32_e32 v35, v23, v33
	v_sub_f32_e32 v22, v24, v23
	v_mul_f32_e32 v24, v31, v35
	v_fma_f32 v26, v35, v31, -v24
	v_fmac_f32_e32 v26, v35, v32
	v_add_f32_e32 v34, v25, v22
	v_add_f32_e32 v22, v24, v26
	v_sub_f32_e32 v25, v23, v22
	v_pk_add_f32 v[28:29], v[22:23], v[24:25] neg_lo:[0,1] neg_hi:[0,1]
	v_mov_b32_e32 v27, v22
	v_pk_add_f32 v[22:23], v[28:29], v[26:27] neg_lo:[0,1] neg_hi:[0,1]
	v_cmp_neq_f32_e64 s[0:1], s2, v14
	v_add_f32_e32 v23, v34, v23
	v_add_f32_e32 v22, v22, v23
	v_add_f32_e32 v23, v25, v22
	v_mul_f32_e32 v34, v33, v23
	v_mul_f32_e32 v24, v31, v34
	v_fma_f32 v26, v34, v31, -v24
	v_fmac_f32_e32 v26, v34, v32
	v_sub_f32_e32 v25, v25, v23
	v_add_f32_e32 v31, v22, v25
	v_add_f32_e32 v22, v24, v26
	v_sub_f32_e32 v25, v23, v22
	v_pk_add_f32 v[28:29], v[22:23], v[24:25] neg_lo:[0,1] neg_hi:[0,1]
	v_mov_b32_e32 v27, v22
	v_pk_add_f32 v[22:23], v[28:29], v[26:27] neg_lo:[0,1] neg_hi:[0,1]
	s_nop 0
	v_add_f32_e32 v23, v31, v23
	v_add_f32_e32 v22, v22, v23
	v_add_f32_e32 v23, v35, v34
	v_add_f32_e32 v22, v25, v22
	v_sub_f32_e32 v24, v23, v35
	v_mul_f32_e32 v22, v33, v22
	v_sub_f32_e32 v24, v34, v24
	v_add_f32_e32 v24, v24, v22
	v_add_f32_e32 v26, v23, v24
	v_mul_f32_e32 v27, v26, v26
	v_fmamk_f32 v22, v27, 0x3e9b6dac, v206
	v_fmaak_f32 v179, v27, v22, 0x3f2aaada
	v_cvt_f32_i32_e32 v22, v30
	v_sub_f32_e32 v23, v26, v23
	v_sub_f32_e32 v23, v24, v23
	v_ldexp_f32 v28, v23, 1
	v_mul_f32_e32 v23, v26, v27
	v_ldexp_f32 v25, v26, 1
	v_pk_mul_f32 v[26:27], v[22:23], v[178:179]
	s_nop 0
	v_fma_f32 v24, v22, s69, -v26
	v_fmac_f32_e32 v24, 0xb102e308, v22
	v_pk_add_f32 v[22:23], v[26:27], v[24:25]
	s_nop 0
	v_sub_f32_e32 v25, v23, v25
	v_sub_f32_e32 v25, v27, v25
	v_add_f32_e32 v29, v28, v25
	v_mov_b32_e32 v28, v26
	v_pk_add_f32 v[26:27], v[22:23], v[26:27] neg_lo:[0,1] neg_hi:[0,1]
	v_pk_add_f32 v[30:31], v[22:23], v[28:29]
	v_mov_b32_e32 v25, v22
	v_mov_b32_e32 v27, v31
	v_pk_add_f32 v[32:33], v[24:25], v[26:27] neg_lo:[0,1] neg_hi:[0,1]
	v_pk_add_f32 v[24:25], v[24:25], v[26:27]
	v_mov_b32_e32 v28, v29
	v_pk_add_f32 v[26:27], v[24:25], v[22:23] op_sel:[1,0] op_sel_hi:[0,1] neg_lo:[0,1] neg_hi:[0,1]
	v_pk_add_f32 v[34:35], v[30:31], v[26:27] op_sel_hi:[1,0] neg_lo:[0,1] neg_hi:[0,1]
	v_mov_b32_e32 v30, v31
	v_mov_b32_e32 v31, v25
	v_pk_mov_b32 v[26:27], v[22:23], v[26:27] op_sel:[1,0]
	v_mov_b32_e32 v29, v22
	v_pk_add_f32 v[26:27], v[30:31], v[26:27] neg_lo:[0,1] neg_hi:[0,1]
	v_mov_b32_e32 v34, v32
	v_pk_add_f32 v[22:23], v[28:29], v[26:27] neg_lo:[0,1] neg_hi:[0,1]
	v_mov_b32_e32 v33, v25
	v_pk_add_f32 v[26:27], v[34:35], v[22:23]
	s_nop 0
	v_pk_add_f32 v[28:29], v[26:27], v[26:27] op_sel:[0,1] op_sel_hi:[1,0]
	s_nop 0
	v_pk_add_f32 v[24:25], v[24:25], v[28:29] op_sel:[1,0] op_sel_hi:[0,1]
	v_mov_b32_e32 v27, v24
	v_pk_add_f32 v[30:31], v[26:27], v[32:33] neg_lo:[0,1] neg_hi:[0,1]
	v_mov_b32_e32 v23, v28
	v_sub_f32_e32 v25, v26, v30
	v_pk_add_f32 v[22:23], v[22:23], v[30:31] neg_lo:[0,1] neg_hi:[0,1]
	v_sub_f32_e32 v25, v32, v25
	v_add_f32_e32 v22, v22, v25
	v_add_f32_e32 v22, v22, v23
	v_add_f32_e32 v22, v24, v22
	v_cndmask_b32_e64 v22, v208, v22, s[0:1]
	v_cmp_lt_f32_e64 s[0:1], |v14|, s66
	s_nop 1
	v_cndmask_b32_e64 v14, v22, v14, s[0:1]
	v_lshl_add_u64 v[22:23], v[20:21], 0, v[68:69]
	v_lshlrev_b64 v[22:23], 14, v[22:23]
	v_sub_f32_e32 v0, v0, v14
	v_lshl_add_u64 v[22:23], v[18:19], 0, v[22:23]
	global_store_dword v[22:23], v0, off
	s_or_b64 exec, exec, s[84:85]
	s_and_saveexec_b64 s[84:85], s[6:7]
	s_cbranch_execz .LBB0_574
;     __device__ __forceinline__ void operator()(const f32x4 (&acc)[2][2][4][2], const pg8::Unit& u, int wr, int wc, int fr, int fq) const {
;     ...
;             if (wc == 0) {
; #pragma unroll
;                 for (int ai = 0; ai < 2; ++ai)
; #pragma unroll
;                     for (int m = 0; m < 4; ++m) { const int row = row0 + ai * 128 + m * 16;
; #pragma unroll
;                         for (int n = 0; n < 2; ++n)
; #pragma unroll
;                             for (int j = 0; j < 4; ++j) { const int col = 8 * fq + 4 * n + j;
;                                 if (col < 12) { const float xv = acc[ai][0][m][n][j] * rsqrtf(ssq[row] * (1.f / DM) + EPS) + bfp[col]; LS[((size_t)(row >> 12) * 12 + col) * SEQ + (row & (SEQ - 1))] = fminf(xv, 0.f) - log1pf(expf(-fabsf(xv))); } } }
.LBB0_627:
	global_load_dword v0, v[66:67], off offset:640
	v_lshl_add_u64 v[22:23], v[70:71], 2, s[60:61]
	s_waitcnt vmcnt(0) lgkmcnt(0)
	v_fmamk_f32 v0, v0, 0x3a000000, v205
	v_cmp_gt_f32_e64 s[0:1], s68, v0
	v_mul_f32_e32 v14, 0x4b800000, v0
	s_nop 0
	v_cndmask_b32_e64 v0, v0, v14, s[0:1]
	v_rsq_f32_e32 v0, v0
	s_nop 0
	v_mul_f32_e32 v14, 0x45800000, v0
	v_cndmask_b32_e64 v0, v0, v14, s[0:1]
	global_load_dword v14, v[22:23], off
	s_waitcnt vmcnt(0) lgkmcnt(0)
	v_fmac_f32_e32 v14, v15, v0
	v_mul_f32_e64 v15, |v14|, s88
	v_fma_f32 v22, |v14|, s88, -v15
	v_rndne_f32_e32 v23, v15
	v_fma_f32 v22, |v14|, s89, v22
	v_sub_f32_e32 v15, v15, v23
	v_add_f32_e32 v15, v15, v22
	v_exp_f32_e32 v15, v15
	v_cvt_i32_f32_e32 v22, v23
	v_cmp_ngt_f32_e64 s[0:1], |v14|, s70
	v_min_f32_e32 v0, 0, v14
	v_ldexp_f32 v15, v15, v22
	v_cndmask_b32_e64 v15, 0, v15, s[0:1]
	v_cmp_nlt_f32_e64 s[0:1], |v14|, s90
	s_nop 1
	v_cndmask_b32_e64 v34, v208, v15, s[0:1]
	v_add_f32_e32 v22, 1.0, v34
	v_add_f32_e32 v14, -1.0, v22
	v_sub_f32_e32 v15, v14, v22
	v_add_f32_e32 v15, 1.0, v15
	v_sub_f32_e32 v14, v34, v14
	v_add_f32_e32 v23, v14, v15
	v_frexp_mant_f32_e32 v14, v22
	v_cmp_gt_f32_e64 s[0:1], s3, v14
	v_cvt_f64_f32_e32 v[14:15], v22
	v_frexp_exp_i32_f64_e32 v14, v[14:15]
	v_subbrev_co_u32_e64 v28, s[0:1], 0, v14, s[0:1]
	v_sub_u32_e32 v14, 0, v28
	v_ldexp_f32 v15, v22, v14
	v_add_f32_e32 v22, -1.0, v15
	v_add_f32_e32 v24, 1.0, v15
	v_ldexp_f32 v14, v23, v14
	v_add_f32_e32 v23, 1.0, v22
	v_add_f32_e32 v25, -1.0, v24
	v_sub_f32_e32 v23, v15, v23
	v_sub_f32_e32 v15, v15, v25
	v_add_f32_e32 v23, v14, v23
	v_add_f32_e32 v14, v14, v15
	v_add_f32_e32 v29, v24, v14
	v_rcp_f32_e32 v31, v29
	v_sub_f32_e32 v15, v24, v29
	v_add_f32_e32 v30, v14, v15
	v_add_f32_e32 v15, v22, v23
	v_mul_f32_e32 v33, v15, v31
	v_sub_f32_e32 v14, v22, v15
	v_mul_f32_e32 v22, v29, v33
	v_fma_f32 v24, v33, v29, -v22
	v_fmac_f32_e32 v24, v33, v30
	v_add_f32_e32 v32, v23, v14
	v_add_f32_e32 v14, v22, v24
	v_sub_f32_e32 v23, v15, v14
	v_pk_add_f32 v[26:27], v[14:15], v[22:23] neg_lo:[0,1] neg_hi:[0,1]
	v_mov_b32_e32 v25, v14
	v_pk_add_f32 v[14:15], v[26:27], v[24:25] neg_lo:[0,1] neg_hi:[0,1]
	v_cmp_neq_f32_e64 s[0:1], s2, v34
	v_add_f32_e32 v15, v32, v15
	v_add_f32_e32 v14, v14, v15
	v_add_f32_e32 v15, v23, v14
	v_mul_f32_e32 v32, v31, v15
	v_mul_f32_e32 v22, v29, v32
	v_fma_f32 v24, v32, v29, -v22
	v_fmac_f32_e32 v24, v32, v30
	v_sub_f32_e32 v23, v23, v15
	v_add_f32_e32 v29, v14, v23
	v_add_f32_e32 v14, v22, v24
	v_sub_f32_e32 v23, v15, v14
	v_pk_add_f32 v[26:27], v[14:15], v[22:23] neg_lo:[0,1] neg_hi:[0,1]
	v_mov_b32_e32 v25, v14
	v_pk_add_f32 v[14:15], v[26:27], v[24:25] neg_lo:[0,1] neg_hi:[0,1]
	s_nop 0
	v_add_f32_e32 v15, v29, v15
	v_add_f32_e32 v14, v14, v15
	v_add_f32_e32 v15, v33, v32
	v_add_f32_e32 v14, v23, v14
	v_sub_f32_e32 v22, v15, v33
	v_mul_f32_e32 v14, v31, v14
	v_sub_f32_e32 v22, v32, v22
	v_add_f32_e32 v22, v22, v14
	v_add_f32_e32 v24, v15, v22
	v_mul_f32_e32 v25, v24, v24
	v_fmamk_f32 v14, v25, 0x3e9b6dac, v206
	v_fmaak_f32 v179, v25, v14, 0x3f2aaada
	v_cvt_f32_i32_e32 v14, v28
	v_sub_f32_e32 v15, v24, v15
	v_sub_f32_e32 v15, v22, v15
	v_ldexp_f32 v26, v15, 1
	v_mul_f32_e32 v15, v24, v25
	v_ldexp_f32 v23, v24, 1
	v_pk_mul_f32 v[24:25], v[14:15], v[178:179]
	s_nop 0
	v_fma_f32 v22, v14, s69, -v24
	v_fmac_f32_e32 v22, 0xb102e308, v14
	v_pk_add_f32 v[14:15], v[24:25], v[22:23]
	s_nop 0
	v_sub_f32_e32 v23, v15, v23
	v_sub_f32_e32 v23, v25, v23
	v_add_f32_e32 v27, v26, v23
	v_mov_b32_e32 v26, v24
	v_pk_add_f32 v[24:25], v[14:15], v[24:25] neg_lo:[0,1] neg_hi:[0,1]
	v_pk_add_f32 v[28:29], v[14:15], v[26:27]
	v_mov_b32_e32 v23, v14
	v_mov_b32_e32 v25, v29
	v_pk_add_f32 v[30:31], v[22:23], v[24:25] neg_lo:[0,1] neg_hi:[0,1]
	v_pk_add_f32 v[22:23], v[22:23], v[24:25]
	v_mov_b32_e32 v26, v27
	v_pk_add_f32 v[24:25], v[22:23], v[14:15] op_sel:[1,0] op_sel_hi:[0,1] neg_lo:[0,1] neg_hi:[0,1]
	v_pk_add_f32 v[32:33], v[28:29], v[24:25] op_sel_hi:[1,0] neg_lo:[0,1] neg_hi:[0,1]
	v_mov_b32_e32 v28, v29
	v_mov_b32_e32 v29, v23
	v_pk_mov_b32 v[24:25], v[14:15], v[24:25] op_sel:[1,0]
	v_mov_b32_e32 v27, v14
	v_pk_add_f32 v[24:25], v[28:29], v[24:25] neg_lo:[0,1] neg_hi:[0,1]
	v_mov_b32_e32 v32, v30
	v_pk_add_f32 v[14:15], v[26:27], v[24:25] neg_lo:[0,1] neg_hi:[0,1]
	v_mov_b32_e32 v31, v23
	v_pk_add_f32 v[24:25], v[32:33], v[14:15]
	s_nop 0
	v_pk_add_f32 v[26:27], v[24:25], v[24:25] op_sel:[0,1] op_sel_hi:[1,0]
	s_nop 0
	v_pk_add_f32 v[22:23], v[22:23], v[26:27] op_sel:[1,0] op_sel_hi:[0,1]
	v_mov_b32_e32 v25, v22
	v_pk_add_f32 v[28:29], v[24:25], v[30:31] neg_lo:[0,1] neg_hi:[0,1]
	v_mov_b32_e32 v15, v26
	v_sub_f32_e32 v23, v24, v28
	v_pk_add_f32 v[14:15], v[14:15], v[28:29] neg_lo:[0,1] neg_hi:[0,1]
	v_sub_f32_e32 v23, v30, v23
	v_add_f32_e32 v14, v14, v23
	v_add_f32_e32 v14, v14, v15
	v_add_f32_e32 v14, v22, v14
	v_cndmask_b32_e64 v14, v208, v14, s[0:1]
	v_cmp_lt_f32_e64 s[0:1], |v34|, s66
	s_nop 1
	v_cndmask_b32_e64 v14, v14, v34, s[0:1]
	v_sub_f32_e32 v0, v0, v14
	v_lshl_add_u64 v[14:15], v[20:21], 0, v[70:71]
	v_lshlrev_b64 v[14:15], 14, v[14:15]
	v_lshl_add_u64 v[14:15], v[18:19], 0, v[14:15]
	global_store_dword v[14:15], v0, off
	s_or_b64 exec, exec, s[84:85]
	s_and_saveexec_b64 s[84:85], s[8:9]
	s_cbranch_execz .LBB0_575
;     __device__ __forceinline__ void operator()(const f32x4 (&acc)[2][2][4][2], const pg8::Unit& u, int wr, int wc, int fr, int fq) const {
;     ...
;             if (wc == 0) {
; #pragma unroll
;                 for (int ai = 0; ai < 2; ++ai)
; #pragma unroll
;                     for (int m = 0; m < 4; ++m) { const int row = row0 + ai * 128 + m * 16;
; #pragma unroll
;                         for (int n = 0; n < 2; ++n)
; #pragma unroll
;                             for (int j = 0; j < 4; ++j) { const int col = 8 * fq + 4 * n + j;
;                                 if (col < 12) { const float xv = acc[ai][0][m][n][j] * rsqrtf(ssq[row] * (1.f / DM) + EPS) + bfp[col]; LS[((size_t)(row >> 12) * 12 + col) * SEQ + (row & (SEQ - 1))] = fminf(xv, 0.f) - log1pf(expf(-fabsf(xv))); } } }
.LBB0_628:
	global_load_dword v0, v[66:67], off offset:640
	s_waitcnt vmcnt(0) lgkmcnt(0)
	v_fmamk_f32 v0, v0, 0x3a000000, v205
	v_cmp_gt_f32_e64 s[0:1], s68, v0
	v_mul_f32_e32 v14, 0x4b800000, v0
	s_nop 0
	v_cndmask_b32_e64 v0, v0, v14, s[0:1]
	v_rsq_f32_e32 v0, v0
	s_nop 0
	v_mul_f32_e32 v14, 0x45800000, v0
	v_cndmask_b32_e64 v0, v0, v14, s[0:1]
	v_lshl_add_u64 v[14:15], v[62:63], 2, s[60:61]
	global_load_dword v14, v[14:15], off
	s_waitcnt vmcnt(0) lgkmcnt(0)
	v_fmac_f32_e32 v14, v16, v0
	v_mul_f32_e64 v15, |v14|, s88
	v_fma_f32 v16, |v14|, s88, -v15
	v_rndne_f32_e32 v22, v15
	v_fma_f32 v16, |v14|, s89, v16
	v_sub_f32_e32 v15, v15, v22
	v_add_f32_e32 v15, v15, v16
	v_exp_f32_e32 v15, v15
	v_cvt_i32_f32_e32 v16, v22
	v_cmp_ngt_f32_e64 s[0:1], |v14|, s70
	v_min_f32_e32 v0, 0, v14
	v_ldexp_f32 v15, v15, v16
	v_cndmask_b32_e64 v15, 0, v15, s[0:1]
	v_cmp_nlt_f32_e64 s[0:1], |v14|, s90
	s_nop 1
	v_cndmask_b32_e64 v16, v208, v15, s[0:1]
	v_add_f32_e32 v22, 1.0, v16
	v_add_f32_e32 v14, -1.0, v22
	v_sub_f32_e32 v15, v14, v22
	v_add_f32_e32 v15, 1.0, v15
	v_sub_f32_e32 v14, v16, v14
	v_add_f32_e32 v23, v14, v15
	v_frexp_mant_f32_e32 v14, v22
	v_cmp_gt_f32_e64 s[0:1], s3, v14
	v_cvt_f64_f32_e32 v[14:15], v22
	v_frexp_exp_i32_f64_e32 v14, v[14:15]
	v_subbrev_co_u32_e64 v28, s[0:1], 0, v14, s[0:1]
	v_sub_u32_e32 v14, 0, v28
	v_ldexp_f32 v15, v22, v14
	v_add_f32_e32 v22, -1.0, v15
	v_add_f32_e32 v24, 1.0, v15
	v_ldexp_f32 v14, v23, v14
	v_add_f32_e32 v23, 1.0, v22
	v_add_f32_e32 v25, -1.0, v24
	v_sub_f32_e32 v23, v15, v23
	v_sub_f32_e32 v15, v15, v25
	v_add_f32_e32 v23, v14, v23
	v_add_f32_e32 v14, v14, v15
	v_add_f32_e32 v29, v24, v14
	v_rcp_f32_e32 v31, v29
	v_sub_f32_e32 v15, v24, v29
	v_add_f32_e32 v30, v14, v15
	v_add_f32_e32 v15, v22, v23
	v_mul_f32_e32 v33, v15, v31
	v_sub_f32_e32 v14, v22, v15
	v_mul_f32_e32 v22, v29, v33
	v_fma_f32 v24, v33, v29, -v22
	v_fmac_f32_e32 v24, v33, v30
	v_add_f32_e32 v32, v23, v14
	v_add_f32_e32 v14, v22, v24
	v_sub_f32_e32 v23, v15, v14
	v_pk_add_f32 v[26:27], v[14:15], v[22:23] neg_lo:[0,1] neg_hi:[0,1]
	v_mov_b32_e32 v25, v14
	v_pk_add_f32 v[14:15], v[26:27], v[24:25] neg_lo:[0,1] neg_hi:[0,1]
	v_cmp_neq_f32_e64 s[0:1], s2, v16
	v_add_f32_e32 v15, v32, v15
	v_add_f32_e32 v14, v14, v15
	v_add_f32_e32 v15, v23, v14
	v_mul_f32_e32 v32, v31, v15
	v_mul_f32_e32 v22, v29, v32
	v_fma_f32 v24, v32, v29, -v22
	v_fmac_f32_e32 v24, v32, v30
	v_sub_f32_e32 v23, v23, v15
	v_add_f32_e32 v29, v14, v23
	v_add_f32_e32 v14, v22, v24
	v_sub_f32_e32 v23, v15, v14
	v_pk_add_f32 v[26:27], v[14:15], v[22:23] neg_lo:[0,1] neg_hi:[0,1]
	v_mov_b32_e32 v25, v14
	v_pk_add_f32 v[14:15], v[26:27], v[24:25] neg_lo:[0,1] neg_hi:[0,1]
	s_nop 0
	v_add_f32_e32 v15, v29, v15
	v_add_f32_e32 v14, v14, v15
	v_add_f32_e32 v15, v33, v32
	v_add_f32_e32 v14, v23, v14
	v_sub_f32_e32 v22, v15, v33
	v_mul_f32_e32 v14, v31, v14
	v_sub_f32_e32 v22, v32, v22
	v_add_f32_e32 v22, v22, v14
	v_add_f32_e32 v24, v15, v22
	v_mul_f32_e32 v25, v24, v24
	v_fmamk_f32 v14, v25, 0x3e9b6dac, v206
	v_fmaak_f32 v179, v25, v14, 0x3f2aaada
	v_cvt_f32_i32_e32 v14, v28
	v_sub_f32_e32 v15, v24, v15
	v_sub_f32_e32 v15, v22, v15
	v_ldexp_f32 v26, v15, 1
	v_mul_f32_e32 v15, v24, v25
	v_ldexp_f32 v23, v24, 1
	v_pk_mul_f32 v[24:25], v[14:15], v[178:179]
	s_nop 0
	v_fma_f32 v22, v14, s69, -v24
	v_fmac_f32_e32 v22, 0xb102e308, v14
	v_pk_add_f32 v[14:15], v[24:25], v[22:23]
	s_nop 0
	v_sub_f32_e32 v23, v15, v23
	v_sub_f32_e32 v23, v25, v23
	v_add_f32_e32 v27, v26, v23
	v_mov_b32_e32 v26, v24
	v_pk_add_f32 v[24:25], v[14:15], v[24:25] neg_lo:[0,1] neg_hi:[0,1]
	v_pk_add_f32 v[28:29], v[14:15], v[26:27]
	v_mov_b32_e32 v23, v14
	v_mov_b32_e32 v25, v29
	v_pk_add_f32 v[30:31], v[22:23], v[24:25] neg_lo:[0,1] neg_hi:[0,1]
	v_pk_add_f32 v[22:23], v[22:23], v[24:25]
	v_mov_b32_e32 v26, v27
	v_pk_add_f32 v[24:25], v[22:23], v[14:15] op_sel:[1,0] op_sel_hi:[0,1] neg_lo:[0,1] neg_hi:[0,1]
	v_pk_add_f32 v[32:33], v[28:29], v[24:25] op_sel_hi:[1,0] neg_lo:[0,1] neg_hi:[0,1]
	v_mov_b32_e32 v28, v29
	v_mov_b32_e32 v29, v23
	v_pk_mov_b32 v[24:25], v[14:15], v[24:25] op_sel:[1,0]
	v_mov_b32_e32 v27, v14
	v_pk_add_f32 v[24:25], v[28:29], v[24:25] neg_lo:[0,1] neg_hi:[0,1]
	v_mov_b32_e32 v32, v30
	v_pk_add_f32 v[14:15], v[26:27], v[24:25] neg_lo:[0,1] neg_hi:[0,1]
	v_mov_b32_e32 v31, v23
	v_pk_add_f32 v[24:25], v[32:33], v[14:15]
	s_nop 0
	v_pk_add_f32 v[26:27], v[24:25], v[24:25] op_sel:[0,1] op_sel_hi:[1,0]
	s_nop 0
	v_pk_add_f32 v[22:23], v[22:23], v[26:27] op_sel:[1,0] op_sel_hi:[0,1]
	v_mov_b32_e32 v25, v22
	v_pk_add_f32 v[28:29], v[24:25], v[30:31] neg_lo:[0,1] neg_hi:[0,1]
	v_mov_b32_e32 v15, v26
	v_sub_f32_e32 v23, v24, v28
	v_pk_add_f32 v[14:15], v[14:15], v[28:29] neg_lo:[0,1] neg_hi:[0,1]
	v_sub_f32_e32 v23, v30, v23
	v_add_f32_e32 v14, v14, v23
	v_add_f32_e32 v14, v14, v15
	v_add_f32_e32 v14, v22, v14
	v_cndmask_b32_e64 v14, v208, v14, s[0:1]
	v_cmp_lt_f32_e64 s[0:1], |v16|, s66
	s_nop 1
	v_cndmask_b32_e64 v14, v14, v16, s[0:1]
	v_sub_f32_e32 v0, v0, v14
	v_lshl_add_u64 v[14:15], v[20:21], 0, v[62:63]
	v_lshlrev_b64 v[14:15], 14, v[14:15]
	v_lshl_add_u64 v[14:15], v[18:19], 0, v[14:15]
	global_store_dword v[14:15], v0, off
	s_or_b64 exec, exec, s[84:85]
	s_and_saveexec_b64 s[84:85], s[10:11]
	s_cbranch_execz .LBB0_576
;     __device__ __forceinline__ void operator()(const f32x4 (&acc)[2][2][4][2], const pg8::Unit& u, int wr, int wc, int fr, int fq) const {
;     ...
;             if (wc == 0) {
; #pragma unroll
;                 for (int ai = 0; ai < 2; ++ai)
; #pragma unroll
;                     for (int m = 0; m < 4; ++m) { const int row = row0 + ai * 128 + m * 16;
; #pragma unroll
;                         for (int n = 0; n < 2; ++n)
; #pragma unroll
;                             for (int j = 0; j < 4; ++j) { const int col = 8 * fq + 4 * n + j;
;                                 if (col < 12) { const float xv = acc[ai][0][m][n][j] * rsqrtf(ssq[row] * (1.f / DM) + EPS) + bfp[col]; LS[((size_t)(row >> 12) * 12 + col) * SEQ + (row & (SEQ - 1))] = fminf(xv, 0.f) - log1pf(expf(-fabsf(xv))); } } }
.LBB0_629:
	global_load_dword v0, v[66:67], off offset:640
	s_waitcnt vmcnt(0) lgkmcnt(0)
	v_fmamk_f32 v0, v0, 0x3a000000, v205
	v_cmp_gt_f32_e64 s[0:1], s68, v0
	v_mul_f32_e32 v14, 0x4b800000, v0
	s_nop 0
	v_cndmask_b32_e64 v0, v0, v14, s[0:1]
	v_rsq_f32_e32 v0, v0
	s_nop 0
	v_mul_f32_e32 v14, 0x45800000, v0
	v_cndmask_b32_e64 v0, v0, v14, s[0:1]
	v_lshl_add_u64 v[14:15], v[72:73], 2, s[60:61]
	global_load_dword v14, v[14:15], off
	s_waitcnt vmcnt(0) lgkmcnt(0)
	v_fmac_f32_e32 v14, v17, v0
	v_mul_f32_e64 v15, |v14|, s88
	v_fma_f32 v16, |v14|, s88, -v15
	v_rndne_f32_e32 v17, v15
	v_fma_f32 v16, |v14|, s89, v16
	v_sub_f32_e32 v15, v15, v17
	v_add_f32_e32 v15, v15, v16
	v_exp_f32_e32 v15, v15
	v_cvt_i32_f32_e32 v16, v17
	v_cmp_ngt_f32_e64 s[0:1], |v14|, s70
	v_min_f32_e32 v0, 0, v14
	v_ldexp_f32 v15, v15, v16
	v_cndmask_b32_e64 v15, 0, v15, s[0:1]
	v_cmp_nlt_f32_e64 s[0:1], |v14|, s90
	s_nop 1
	v_cndmask_b32_e64 v32, v208, v15, s[0:1]
	v_add_f32_e32 v16, 1.0, v32
	v_add_f32_e32 v14, -1.0, v16
	v_sub_f32_e32 v15, v14, v16
	v_add_f32_e32 v15, 1.0, v15
	v_sub_f32_e32 v14, v32, v14
	v_add_f32_e32 v17, v14, v15
	v_frexp_mant_f32_e32 v14, v16
	v_cmp_gt_f32_e64 s[0:1], s3, v14
	v_cvt_f64_f32_e32 v[14:15], v16
	v_frexp_exp_i32_f64_e32 v14, v[14:15]
	v_subbrev_co_u32_e64 v26, s[0:1], 0, v14, s[0:1]
	v_sub_u32_e32 v14, 0, v26
	v_ldexp_f32 v15, v16, v14
	v_add_f32_e32 v16, -1.0, v15
	v_add_f32_e32 v22, 1.0, v15
	v_ldexp_f32 v14, v17, v14
	v_add_f32_e32 v17, 1.0, v16
	v_add_f32_e32 v23, -1.0, v22
	v_sub_f32_e32 v17, v15, v17
	v_sub_f32_e32 v15, v15, v23
	v_add_f32_e32 v17, v14, v17
	v_add_f32_e32 v14, v14, v15
	v_add_f32_e32 v27, v22, v14
	v_rcp_f32_e32 v29, v27
	v_sub_f32_e32 v15, v22, v27
	v_add_f32_e32 v28, v14, v15
	v_add_f32_e32 v15, v16, v17
	v_mul_f32_e32 v31, v15, v29
	v_sub_f32_e32 v14, v16, v15
	v_mul_f32_e32 v16, v27, v31
	v_fma_f32 v22, v31, v27, -v16
	v_fmac_f32_e32 v22, v31, v28
	v_add_f32_e32 v30, v17, v14
	v_add_f32_e32 v14, v16, v22
	v_sub_f32_e32 v17, v15, v14
	v_pk_add_f32 v[24:25], v[14:15], v[16:17] neg_lo:[0,1] neg_hi:[0,1]
	v_mov_b32_e32 v23, v14
	v_pk_add_f32 v[14:15], v[24:25], v[22:23] neg_lo:[0,1] neg_hi:[0,1]
	v_cmp_neq_f32_e64 s[0:1], s2, v32
	v_add_f32_e32 v15, v30, v15
	v_add_f32_e32 v14, v14, v15
	v_add_f32_e32 v15, v17, v14
	v_mul_f32_e32 v30, v29, v15
	v_mul_f32_e32 v16, v27, v30
	v_fma_f32 v22, v30, v27, -v16
	v_fmac_f32_e32 v22, v30, v28
	v_sub_f32_e32 v17, v17, v15
	v_add_f32_e32 v27, v14, v17
	v_add_f32_e32 v14, v16, v22
	v_sub_f32_e32 v17, v15, v14
	v_pk_add_f32 v[24:25], v[14:15], v[16:17] neg_lo:[0,1] neg_hi:[0,1]
	v_mov_b32_e32 v23, v14
	v_pk_add_f32 v[14:15], v[24:25], v[22:23] neg_lo:[0,1] neg_hi:[0,1]
	s_nop 0
	v_add_f32_e32 v15, v27, v15
	v_add_f32_e32 v14, v14, v15
	v_add_f32_e32 v15, v31, v30
	v_add_f32_e32 v14, v17, v14
	v_sub_f32_e32 v16, v15, v31
	v_mul_f32_e32 v14, v29, v14
	v_sub_f32_e32 v16, v30, v16
	v_add_f32_e32 v16, v16, v14
	v_add_f32_e32 v22, v15, v16
	v_mul_f32_e32 v23, v22, v22
	v_fmamk_f32 v14, v23, 0x3e9b6dac, v206
	v_fmaak_f32 v179, v23, v14, 0x3f2aaada
	v_cvt_f32_i32_e32 v14, v26
	v_sub_f32_e32 v15, v22, v15
	v_sub_f32_e32 v15, v16, v15
	v_ldexp_f32 v24, v15, 1
	v_mul_f32_e32 v15, v22, v23
	v_ldexp_f32 v17, v22, 1
	v_pk_mul_f32 v[22:23], v[14:15], v[178:179]
	s_nop 0
	v_fma_f32 v16, v14, s69, -v22
	v_fmac_f32_e32 v16, 0xb102e308, v14
	v_pk_add_f32 v[14:15], v[22:23], v[16:17]
	s_nop 0
	v_sub_f32_e32 v17, v15, v17
	v_sub_f32_e32 v17, v23, v17
	v_add_f32_e32 v25, v24, v17
	v_mov_b32_e32 v24, v22
	v_pk_add_f32 v[22:23], v[14:15], v[22:23] neg_lo:[0,1] neg_hi:[0,1]
	v_pk_add_f32 v[26:27], v[14:15], v[24:25]
	v_mov_b32_e32 v17, v14
	v_mov_b32_e32 v23, v27
	v_pk_add_f32 v[28:29], v[16:17], v[22:23] neg_lo:[0,1] neg_hi:[0,1]
	v_pk_add_f32 v[16:17], v[16:17], v[22:23]
	v_mov_b32_e32 v24, v25
	v_pk_add_f32 v[22:23], v[16:17], v[14:15] op_sel:[1,0] op_sel_hi:[0,1] neg_lo:[0,1] neg_hi:[0,1]
	v_pk_add_f32 v[30:31], v[26:27], v[22:23] op_sel_hi:[1,0] neg_lo:[0,1] neg_hi:[0,1]
	v_mov_b32_e32 v26, v27
	v_mov_b32_e32 v27, v17
	v_pk_mov_b32 v[22:23], v[14:15], v[22:23] op_sel:[1,0]
	v_mov_b32_e32 v25, v14
	v_pk_add_f32 v[22:23], v[26:27], v[22:23] neg_lo:[0,1] neg_hi:[0,1]
	v_mov_b32_e32 v30, v28
	v_pk_add_f32 v[14:15], v[24:25], v[22:23] neg_lo:[0,1] neg_hi:[0,1]
	v_mov_b32_e32 v29, v17
	v_pk_add_f32 v[22:23], v[30:31], v[14:15]
	s_nop 0
	v_pk_add_f32 v[24:25], v[22:23], v[22:23] op_sel:[0,1] op_sel_hi:[1,0]
	s_nop 0
	v_pk_add_f32 v[16:17], v[16:17], v[24:25] op_sel:[1,0] op_sel_hi:[0,1]
	v_mov_b32_e32 v23, v16
	v_pk_add_f32 v[26:27], v[22:23], v[28:29] neg_lo:[0,1] neg_hi:[0,1]
	v_mov_b32_e32 v15, v24
	v_sub_f32_e32 v17, v22, v26
	v_pk_add_f32 v[14:15], v[14:15], v[26:27] neg_lo:[0,1] neg_hi:[0,1]
	v_sub_f32_e32 v17, v28, v17
	v_add_f32_e32 v14, v14, v17
	v_add_f32_e32 v14, v14, v15
	v_add_f32_e32 v14, v16, v14
	v_cndmask_b32_e64 v14, v208, v14, s[0:1]
	v_cmp_lt_f32_e64 s[0:1], |v32|, s66
	s_nop 1
	v_cndmask_b32_e64 v14, v14, v32, s[0:1]
	v_sub_f32_e32 v0, v0, v14
	v_lshl_add_u64 v[14:15], v[20:21], 0, v[72:73]
	v_lshlrev_b64 v[14:15], 14, v[14:15]
	v_lshl_add_u64 v[14:15], v[18:19], 0, v[14:15]
	global_store_dword v[14:15], v0, off
	s_or_b64 exec, exec, s[84:85]
	s_and_saveexec_b64 s[84:85], s[12:13]
	s_cbranch_execz .LBB0_577
;     __device__ __forceinline__ void operator()(const f32x4 (&acc)[2][2][4][2], const pg8::Unit& u, int wr, int wc, int fr, int fq) const {
;     ...
;             if (wc == 0) {
; #pragma unroll
;                 for (int ai = 0; ai < 2; ++ai)
; #pragma unroll
;                     for (int m = 0; m < 4; ++m) { const int row = row0 + ai * 128 + m * 16;
; #pragma unroll
;                         for (int n = 0; n < 2; ++n)
; #pragma unroll
;                             for (int j = 0; j < 4; ++j) { const int col = 8 * fq + 4 * n + j;
;                                 if (col < 12) { const float xv = acc[ai][0][m][n][j] * rsqrtf(ssq[row] * (1.f / DM) + EPS) + bfp[col]; LS[((size_t)(row >> 12) * 12 + col) * SEQ + (row & (SEQ - 1))] = fminf(xv, 0.f) - log1pf(expf(-fabsf(xv))); } } }
.LBB0_630:
	global_load_dword v0, v[66:67], off offset:640
	s_waitcnt vmcnt(0) lgkmcnt(0)
	v_fmamk_f32 v0, v0, 0x3a000000, v205
	v_cmp_gt_f32_e64 s[0:1], s68, v0
	v_mul_f32_e32 v14, 0x4b800000, v0
	s_nop 0
	v_cndmask_b32_e64 v0, v0, v14, s[0:1]
	v_rsq_f32_e32 v0, v0
	s_nop 0
	v_mul_f32_e32 v14, 0x45800000, v0
	v_cndmask_b32_e64 v0, v0, v14, s[0:1]
	v_lshl_add_u64 v[14:15], v[64:65], 2, s[60:61]
	global_load_dword v14, v[14:15], off
	s_waitcnt vmcnt(0) lgkmcnt(0)
	v_fmac_f32_e32 v14, v10, v0
	v_mul_f32_e64 v10, |v14|, s88
	v_fma_f32 v15, |v14|, s88, -v10
	v_rndne_f32_e32 v16, v10
	v_fma_f32 v15, |v14|, s89, v15
	v_sub_f32_e32 v10, v10, v16
	v_add_f32_e32 v10, v10, v15
	v_exp_f32_e32 v10, v10
	v_cvt_i32_f32_e32 v15, v16
	v_cmp_ngt_f32_e64 s[0:1], |v14|, s70
	v_min_f32_e32 v0, 0, v14
	v_ldexp_f32 v10, v10, v15
	v_cndmask_b32_e64 v10, 0, v10, s[0:1]
	v_cmp_nlt_f32_e64 s[0:1], |v14|, s90
	s_nop 1
	v_cndmask_b32_e64 v10, v208, v10, s[0:1]
	v_add_f32_e32 v16, 1.0, v10
	v_add_f32_e32 v14, -1.0, v16
	v_sub_f32_e32 v15, v14, v16
	v_add_f32_e32 v15, 1.0, v15
	v_sub_f32_e32 v14, v10, v14
	v_add_f32_e32 v17, v14, v15
	v_frexp_mant_f32_e32 v14, v16
	v_cmp_gt_f32_e64 s[0:1], s3, v14
	v_cvt_f64_f32_e32 v[14:15], v16
	v_frexp_exp_i32_f64_e32 v14, v[14:15]
	v_subbrev_co_u32_e64 v26, s[0:1], 0, v14, s[0:1]
	v_sub_u32_e32 v14, 0, v26
	v_ldexp_f32 v15, v16, v14
	v_add_f32_e32 v16, -1.0, v15
	v_add_f32_e32 v22, 1.0, v15
	v_ldexp_f32 v14, v17, v14
	v_add_f32_e32 v17, 1.0, v16
	v_add_f32_e32 v23, -1.0, v22
	v_sub_f32_e32 v17, v15, v17
	v_sub_f32_e32 v15, v15, v23
	v_add_f32_e32 v17, v14, v17
	v_add_f32_e32 v14, v14, v15
	v_add_f32_e32 v27, v22, v14
	v_rcp_f32_e32 v29, v27
	v_sub_f32_e32 v15, v22, v27
	v_add_f32_e32 v28, v14, v15
	v_add_f32_e32 v15, v16, v17
	v_mul_f32_e32 v31, v15, v29
	v_sub_f32_e32 v14, v16, v15
	v_mul_f32_e32 v16, v27, v31
	v_fma_f32 v22, v31, v27, -v16
	v_fmac_f32_e32 v22, v31, v28
	v_add_f32_e32 v30, v17, v14
	v_add_f32_e32 v14, v16, v22
	v_sub_f32_e32 v17, v15, v14
	v_pk_add_f32 v[24:25], v[14:15], v[16:17] neg_lo:[0,1] neg_hi:[0,1]
	v_mov_b32_e32 v23, v14
	v_pk_add_f32 v[14:15], v[24:25], v[22:23] neg_lo:[0,1] neg_hi:[0,1]
	v_cmp_neq_f32_e64 s[0:1], s2, v10
	v_add_f32_e32 v15, v30, v15
	v_add_f32_e32 v14, v14, v15
	v_add_f32_e32 v15, v17, v14
	v_mul_f32_e32 v30, v29, v15
	v_mul_f32_e32 v16, v27, v30
	v_fma_f32 v22, v30, v27, -v16
	v_fmac_f32_e32 v22, v30, v28
	v_sub_f32_e32 v17, v17, v15
	v_add_f32_e32 v27, v14, v17
	v_add_f32_e32 v14, v16, v22
	v_sub_f32_e32 v17, v15, v14
	v_pk_add_f32 v[24:25], v[14:15], v[16:17] neg_lo:[0,1] neg_hi:[0,1]
	v_mov_b32_e32 v23, v14
	v_pk_add_f32 v[14:15], v[24:25], v[22:23] neg_lo:[0,1] neg_hi:[0,1]
	s_nop 0
	v_add_f32_e32 v15, v27, v15
	v_add_f32_e32 v14, v14, v15
	v_add_f32_e32 v15, v31, v30
	v_add_f32_e32 v14, v17, v14
	v_sub_f32_e32 v16, v15, v31
	v_mul_f32_e32 v14, v29, v14
	v_sub_f32_e32 v16, v30, v16
	v_add_f32_e32 v16, v16, v14
	v_add_f32_e32 v22, v15, v16
	v_mul_f32_e32 v23, v22, v22
	v_fmamk_f32 v14, v23, 0x3e9b6dac, v206
	v_fmaak_f32 v179, v23, v14, 0x3f2aaada
	v_cvt_f32_i32_e32 v14, v26
	v_sub_f32_e32 v15, v22, v15
	v_sub_f32_e32 v15, v16, v15
	v_ldexp_f32 v24, v15, 1
	v_mul_f32_e32 v15, v22, v23
	v_ldexp_f32 v17, v22, 1
	v_pk_mul_f32 v[22:23], v[14:15], v[178:179]
	s_nop 0
	v_fma_f32 v16, v14, s69, -v22
	v_fmac_f32_e32 v16, 0xb102e308, v14
	v_pk_add_f32 v[14:15], v[22:23], v[16:17]
	s_nop 0
	v_sub_f32_e32 v17, v15, v17
	v_sub_f32_e32 v17, v23, v17
	v_add_f32_e32 v25, v24, v17
	v_mov_b32_e32 v24, v22
	v_pk_add_f32 v[22:23], v[14:15], v[22:23] neg_lo:[0,1] neg_hi:[0,1]
	v_pk_add_f32 v[26:27], v[14:15], v[24:25]
	v_mov_b32_e32 v17, v14
	v_mov_b32_e32 v23, v27
	v_pk_add_f32 v[28:29], v[16:17], v[22:23] neg_lo:[0,1] neg_hi:[0,1]
	v_pk_add_f32 v[16:17], v[16:17], v[22:23]
	v_mov_b32_e32 v24, v25
	v_pk_add_f32 v[22:23], v[16:17], v[14:15] op_sel:[1,0] op_sel_hi:[0,1] neg_lo:[0,1] neg_hi:[0,1]
	v_pk_add_f32 v[30:31], v[26:27], v[22:23] op_sel_hi:[1,0] neg_lo:[0,1] neg_hi:[0,1]
	v_mov_b32_e32 v26, v27
	v_mov_b32_e32 v27, v17
	v_pk_mov_b32 v[22:23], v[14:15], v[22:23] op_sel:[1,0]
	v_mov_b32_e32 v25, v14
	v_pk_add_f32 v[22:23], v[26:27], v[22:23] neg_lo:[0,1] neg_hi:[0,1]
	v_mov_b32_e32 v30, v28
	v_pk_add_f32 v[14:15], v[24:25], v[22:23] neg_lo:[0,1] neg_hi:[0,1]
	v_mov_b32_e32 v29, v17
	v_pk_add_f32 v[22:23], v[30:31], v[14:15]
	s_nop 0
	v_pk_add_f32 v[24:25], v[22:23], v[22:23] op_sel:[0,1] op_sel_hi:[1,0]
	s_nop 0
	v_pk_add_f32 v[16:17], v[16:17], v[24:25] op_sel:[1,0] op_sel_hi:[0,1]
	v_mov_b32_e32 v23, v16
	v_pk_add_f32 v[26:27], v[22:23], v[28:29] neg_lo:[0,1] neg_hi:[0,1]
	v_mov_b32_e32 v15, v24
	v_sub_f32_e32 v17, v22, v26
	v_pk_add_f32 v[14:15], v[14:15], v[26:27] neg_lo:[0,1] neg_hi:[0,1]
	v_sub_f32_e32 v17, v28, v17
	v_add_f32_e32 v14, v14, v17
	v_add_f32_e32 v14, v14, v15
	v_add_f32_e32 v14, v16, v14
	v_cndmask_b32_e64 v14, v208, v14, s[0:1]
	v_cmp_lt_f32_e64 s[0:1], |v10|, s66
	s_nop 1
	v_cndmask_b32_e64 v10, v14, v10, s[0:1]
	v_lshl_add_u64 v[14:15], v[20:21], 0, v[64:65]
	v_lshlrev_b64 v[14:15], 14, v[14:15]
	v_sub_f32_e32 v0, v0, v10
	v_lshl_add_u64 v[14:15], v[18:19], 0, v[14:15]
	global_store_dword v[14:15], v0, off
	s_or_b64 exec, exec, s[84:85]
	s_and_saveexec_b64 s[84:85], s[14:15]
	s_cbranch_execz .LBB0_578
;     __device__ __forceinline__ void operator()(const f32x4 (&acc)[2][2][4][2], const pg8::Unit& u, int wr, int wc, int fr, int fq) const {
;     ...
;             if (wc == 0) {
; #pragma unroll
;                 for (int ai = 0; ai < 2; ++ai)
; #pragma unroll
;                     for (int m = 0; m < 4; ++m) { const int row = row0 + ai * 128 + m * 16;
; #pragma unroll
;                         for (int n = 0; n < 2; ++n)
; #pragma unroll
;                             for (int j = 0; j < 4; ++j) { const int col = 8 * fq + 4 * n + j;
;                                 if (col < 12) { const float xv = acc[ai][0][m][n][j] * rsqrtf(ssq[row] * (1.f / DM) + EPS) + bfp[col]; LS[((size_t)(row >> 12) * 12 + col) * SEQ + (row & (SEQ - 1))] = fminf(xv, 0.f) - log1pf(expf(-fabsf(xv))); } } }
.LBB0_631:
	global_load_dword v0, v[66:67], off offset:640
	v_lshl_add_u64 v[14:15], v[74:75], 2, s[60:61]
	s_waitcnt vmcnt(0) lgkmcnt(0)
	v_fmamk_f32 v0, v0, 0x3a000000, v205
	v_cmp_gt_f32_e64 s[0:1], s68, v0
	v_mul_f32_e32 v10, 0x4b800000, v0
	s_nop 0
	v_cndmask_b32_e64 v0, v0, v10, s[0:1]
	v_rsq_f32_e32 v0, v0
	s_nop 0
	v_mul_f32_e32 v10, 0x45800000, v0
	v_cndmask_b32_e64 v0, v0, v10, s[0:1]
	global_load_dword v10, v[14:15], off
	s_waitcnt vmcnt(0) lgkmcnt(0)
	v_fmac_f32_e32 v10, v11, v0
	v_mul_f32_e64 v11, |v10|, s88
	v_fma_f32 v14, |v10|, s88, -v11
	v_rndne_f32_e32 v15, v11
	v_fma_f32 v14, |v10|, s89, v14
	v_sub_f32_e32 v11, v11, v15
	v_add_f32_e32 v11, v11, v14
	v_exp_f32_e32 v11, v11
	v_cvt_i32_f32_e32 v14, v15
	v_cmp_ngt_f32_e64 s[0:1], |v10|, s70
	v_min_f32_e32 v0, 0, v10
	v_ldexp_f32 v11, v11, v14
	v_cndmask_b32_e64 v11, 0, v11, s[0:1]
	v_cmp_nlt_f32_e64 s[0:1], |v10|, s90
	s_nop 1
	v_cndmask_b32_e64 v30, v208, v11, s[0:1]
	v_add_f32_e32 v14, 1.0, v30
	v_add_f32_e32 v10, -1.0, v14
	v_sub_f32_e32 v11, v10, v14
	v_add_f32_e32 v11, 1.0, v11
	v_sub_f32_e32 v10, v30, v10
	v_add_f32_e32 v15, v10, v11
	v_frexp_mant_f32_e32 v10, v14
	v_cmp_gt_f32_e64 s[0:1], s3, v10
	v_cvt_f64_f32_e32 v[10:11], v14
	v_frexp_exp_i32_f64_e32 v10, v[10:11]
	v_subbrev_co_u32_e64 v24, s[0:1], 0, v10, s[0:1]
	v_sub_u32_e32 v10, 0, v24
	v_ldexp_f32 v11, v14, v10
	v_add_f32_e32 v14, -1.0, v11
	v_add_f32_e32 v16, 1.0, v11
	v_ldexp_f32 v10, v15, v10
	v_add_f32_e32 v15, 1.0, v14
	v_add_f32_e32 v17, -1.0, v16
	v_sub_f32_e32 v15, v11, v15
	v_sub_f32_e32 v11, v11, v17
	v_add_f32_e32 v15, v10, v15
	v_add_f32_e32 v10, v10, v11
	v_add_f32_e32 v25, v16, v10
	v_rcp_f32_e32 v27, v25
	v_sub_f32_e32 v11, v16, v25
	v_add_f32_e32 v26, v10, v11
	v_add_f32_e32 v11, v14, v15
	v_mul_f32_e32 v29, v11, v27
	v_sub_f32_e32 v10, v14, v11
	v_mul_f32_e32 v14, v25, v29
	v_fma_f32 v16, v29, v25, -v14
	v_fmac_f32_e32 v16, v29, v26
	v_add_f32_e32 v28, v15, v10
	v_add_f32_e32 v10, v14, v16
	v_sub_f32_e32 v15, v11, v10
	v_pk_add_f32 v[22:23], v[10:11], v[14:15] neg_lo:[0,1] neg_hi:[0,1]
	v_mov_b32_e32 v17, v10
	v_pk_add_f32 v[10:11], v[22:23], v[16:17] neg_lo:[0,1] neg_hi:[0,1]
	v_cmp_neq_f32_e64 s[0:1], s2, v30
	v_add_f32_e32 v11, v28, v11
	v_add_f32_e32 v10, v10, v11
	v_add_f32_e32 v11, v15, v10
	v_mul_f32_e32 v28, v27, v11
	v_mul_f32_e32 v14, v25, v28
	v_fma_f32 v16, v28, v25, -v14
	v_fmac_f32_e32 v16, v28, v26
	v_sub_f32_e32 v15, v15, v11
	v_add_f32_e32 v25, v10, v15
	v_add_f32_e32 v10, v14, v16
	v_sub_f32_e32 v15, v11, v10
	v_pk_add_f32 v[22:23], v[10:11], v[14:15] neg_lo:[0,1] neg_hi:[0,1]
	v_mov_b32_e32 v17, v10
	v_pk_add_f32 v[10:11], v[22:23], v[16:17] neg_lo:[0,1] neg_hi:[0,1]
	s_nop 0
	v_add_f32_e32 v11, v25, v11
	v_add_f32_e32 v10, v10, v11
	v_add_f32_e32 v11, v29, v28
	v_add_f32_e32 v10, v15, v10
	v_sub_f32_e32 v14, v11, v29
	v_mul_f32_e32 v10, v27, v10
	v_sub_f32_e32 v14, v28, v14
	v_add_f32_e32 v14, v14, v10
	v_add_f32_e32 v16, v11, v14
	v_mul_f32_e32 v17, v16, v16
	v_fmamk_f32 v10, v17, 0x3e9b6dac, v206
	v_fmaak_f32 v179, v17, v10, 0x3f2aaada
	v_cvt_f32_i32_e32 v10, v24
	v_sub_f32_e32 v11, v16, v11
	v_sub_f32_e32 v11, v14, v11
	v_ldexp_f32 v22, v11, 1
	v_mul_f32_e32 v11, v16, v17
	v_ldexp_f32 v15, v16, 1
	v_pk_mul_f32 v[16:17], v[10:11], v[178:179]
	s_nop 0
	v_fma_f32 v14, v10, s69, -v16
	v_fmac_f32_e32 v14, 0xb102e308, v10
	v_pk_add_f32 v[10:11], v[16:17], v[14:15]
	s_nop 0
	v_sub_f32_e32 v15, v11, v15
	v_sub_f32_e32 v15, v17, v15
	v_add_f32_e32 v23, v22, v15
	v_mov_b32_e32 v22, v16
	v_pk_add_f32 v[16:17], v[10:11], v[16:17] neg_lo:[0,1] neg_hi:[0,1]
	v_pk_add_f32 v[24:25], v[10:11], v[22:23]
	v_mov_b32_e32 v15, v10
	v_mov_b32_e32 v17, v25
	v_pk_add_f32 v[26:27], v[14:15], v[16:17] neg_lo:[0,1] neg_hi:[0,1]
	v_pk_add_f32 v[14:15], v[14:15], v[16:17]
	v_mov_b32_e32 v22, v23
	v_pk_add_f32 v[16:17], v[14:15], v[10:11] op_sel:[1,0] op_sel_hi:[0,1] neg_lo:[0,1] neg_hi:[0,1]
	v_pk_add_f32 v[28:29], v[24:25], v[16:17] op_sel_hi:[1,0] neg_lo:[0,1] neg_hi:[0,1]
	v_mov_b32_e32 v24, v25
	v_mov_b32_e32 v25, v15
	v_pk_mov_b32 v[16:17], v[10:11], v[16:17] op_sel:[1,0]
	v_mov_b32_e32 v23, v10
	v_pk_add_f32 v[16:17], v[24:25], v[16:17] neg_lo:[0,1] neg_hi:[0,1]
	v_mov_b32_e32 v28, v26
	v_pk_add_f32 v[10:11], v[22:23], v[16:17] neg_lo:[0,1] neg_hi:[0,1]
	v_mov_b32_e32 v27, v15
	v_pk_add_f32 v[16:17], v[28:29], v[10:11]
	s_nop 0
	v_pk_add_f32 v[22:23], v[16:17], v[16:17] op_sel:[0,1] op_sel_hi:[1,0]
	s_nop 0
	v_pk_add_f32 v[14:15], v[14:15], v[22:23] op_sel:[1,0] op_sel_hi:[0,1]
	v_mov_b32_e32 v17, v14
	v_pk_add_f32 v[24:25], v[16:17], v[26:27] neg_lo:[0,1] neg_hi:[0,1]
	v_mov_b32_e32 v11, v22
	v_sub_f32_e32 v15, v16, v24
	v_pk_add_f32 v[10:11], v[10:11], v[24:25] neg_lo:[0,1] neg_hi:[0,1]
	v_sub_f32_e32 v15, v26, v15
	v_add_f32_e32 v10, v10, v15
	v_add_f32_e32 v10, v10, v11
	v_add_f32_e32 v10, v14, v10
	v_cndmask_b32_e64 v10, v208, v10, s[0:1]
	v_cmp_lt_f32_e64 s[0:1], |v30|, s66
	s_nop 1
	v_cndmask_b32_e64 v10, v10, v30, s[0:1]
	v_sub_f32_e32 v0, v0, v10
	v_lshl_add_u64 v[10:11], v[20:21], 0, v[74:75]
	v_lshlrev_b64 v[10:11], 14, v[10:11]
	v_lshl_add_u64 v[10:11], v[18:19], 0, v[10:11]
	global_store_dword v[10:11], v0, off
	s_or_b64 exec, exec, s[84:85]
	s_and_saveexec_b64 s[84:85], s[16:17]
	s_cbranch_execz .LBB0_579
;     __device__ __forceinline__ void operator()(const f32x4 (&acc)[2][2][4][2], const pg8::Unit& u, int wr, int wc, int fr, int fq) const {
;     ...
;             if (wc == 0) {
; #pragma unroll
;                 for (int ai = 0; ai < 2; ++ai)
; #pragma unroll
;                     for (int m = 0; m < 4; ++m) { const int row = row0 + ai * 128 + m * 16;
; #pragma unroll
;                         for (int n = 0; n < 2; ++n)
; #pragma unroll
;                             for (int j = 0; j < 4; ++j) { const int col = 8 * fq + 4 * n + j;
;                                 if (col < 12) { const float xv = acc[ai][0][m][n][j] * rsqrtf(ssq[row] * (1.f / DM) + EPS) + bfp[col]; LS[((size_t)(row >> 12) * 12 + col) * SEQ + (row & (SEQ - 1))] = fminf(xv, 0.f) - log1pf(expf(-fabsf(xv))); } } }
.LBB0_632:
	global_load_dword v0, v[66:67], off offset:640
	s_waitcnt vmcnt(0) lgkmcnt(0)
	v_fmamk_f32 v0, v0, 0x3a000000, v205
	v_cmp_gt_f32_e64 s[0:1], s68, v0
	v_mul_f32_e32 v10, 0x4b800000, v0
	s_nop 0
	v_cndmask_b32_e64 v0, v0, v10, s[0:1]
	v_rsq_f32_e32 v0, v0
	s_nop 0
	v_mul_f32_e32 v10, 0x45800000, v0
	v_cndmask_b32_e64 v0, v0, v10, s[0:1]
	v_lshl_add_u64 v[10:11], v[58:59], 2, s[60:61]
	global_load_dword v10, v[10:11], off
	s_waitcnt vmcnt(0) lgkmcnt(0)
	v_fmac_f32_e32 v10, v12, v0
	v_mul_f32_e64 v11, |v10|, s88
	v_fma_f32 v12, |v10|, s88, -v11
	v_rndne_f32_e32 v14, v11
	v_fma_f32 v12, |v10|, s89, v12
	v_sub_f32_e32 v11, v11, v14
	v_add_f32_e32 v11, v11, v12
	v_exp_f32_e32 v11, v11
	v_cvt_i32_f32_e32 v12, v14
	v_cmp_ngt_f32_e64 s[0:1], |v10|, s70
	v_min_f32_e32 v0, 0, v10
	v_ldexp_f32 v11, v11, v12
	v_cndmask_b32_e64 v11, 0, v11, s[0:1]
	v_cmp_nlt_f32_e64 s[0:1], |v10|, s90
	s_nop 1
	v_cndmask_b32_e64 v12, v208, v11, s[0:1]
	v_add_f32_e32 v14, 1.0, v12
	v_add_f32_e32 v10, -1.0, v14
	v_sub_f32_e32 v11, v10, v14
	v_add_f32_e32 v11, 1.0, v11
	v_sub_f32_e32 v10, v12, v10
	v_add_f32_e32 v15, v10, v11
	v_frexp_mant_f32_e32 v10, v14
	v_cmp_gt_f32_e64 s[0:1], s3, v10
	v_cvt_f64_f32_e32 v[10:11], v14
	v_frexp_exp_i32_f64_e32 v10, v[10:11]
	v_subbrev_co_u32_e64 v24, s[0:1], 0, v10, s[0:1]
	v_sub_u32_e32 v10, 0, v24
	v_ldexp_f32 v11, v14, v10
	v_add_f32_e32 v14, -1.0, v11
	v_add_f32_e32 v16, 1.0, v11
	v_ldexp_f32 v10, v15, v10
	v_add_f32_e32 v15, 1.0, v14
	v_add_f32_e32 v17, -1.0, v16
	v_sub_f32_e32 v15, v11, v15
	v_sub_f32_e32 v11, v11, v17
	v_add_f32_e32 v15, v10, v15
	v_add_f32_e32 v10, v10, v11
	v_add_f32_e32 v25, v16, v10
	v_rcp_f32_e32 v27, v25
	v_sub_f32_e32 v11, v16, v25
	v_add_f32_e32 v26, v10, v11
	v_add_f32_e32 v11, v14, v15
	v_mul_f32_e32 v29, v11, v27
	v_sub_f32_e32 v10, v14, v11
	v_mul_f32_e32 v14, v25, v29
	v_fma_f32 v16, v29, v25, -v14
	v_fmac_f32_e32 v16, v29, v26
	v_add_f32_e32 v28, v15, v10
	v_add_f32_e32 v10, v14, v16
	v_sub_f32_e32 v15, v11, v10
	v_pk_add_f32 v[22:23], v[10:11], v[14:15] neg_lo:[0,1] neg_hi:[0,1]
	v_mov_b32_e32 v17, v10
	v_pk_add_f32 v[10:11], v[22:23], v[16:17] neg_lo:[0,1] neg_hi:[0,1]
	v_cmp_neq_f32_e64 s[0:1], s2, v12
	v_add_f32_e32 v11, v28, v11
	v_add_f32_e32 v10, v10, v11
	v_add_f32_e32 v11, v15, v10
	v_mul_f32_e32 v28, v27, v11
	v_mul_f32_e32 v14, v25, v28
	v_fma_f32 v16, v28, v25, -v14
	v_fmac_f32_e32 v16, v28, v26
	v_sub_f32_e32 v15, v15, v11
	v_add_f32_e32 v25, v10, v15
	v_add_f32_e32 v10, v14, v16
	v_sub_f32_e32 v15, v11, v10
	v_pk_add_f32 v[22:23], v[10:11], v[14:15] neg_lo:[0,1] neg_hi:[0,1]
	v_mov_b32_e32 v17, v10
	v_pk_add_f32 v[10:11], v[22:23], v[16:17] neg_lo:[0,1] neg_hi:[0,1]
	s_nop 0
	v_add_f32_e32 v11, v25, v11
	v_add_f32_e32 v10, v10, v11
	v_add_f32_e32 v11, v29, v28
	v_add_f32_e32 v10, v15, v10
	v_sub_f32_e32 v14, v11, v29
	v_mul_f32_e32 v10, v27, v10
	v_sub_f32_e32 v14, v28, v14
	v_add_f32_e32 v14, v14, v10
	v_add_f32_e32 v16, v11, v14
	v_mul_f32_e32 v17, v16, v16
	v_fmamk_f32 v10, v17, 0x3e9b6dac, v206
	v_fmaak_f32 v179, v17, v10, 0x3f2aaada
	v_cvt_f32_i32_e32 v10, v24
	v_sub_f32_e32 v11, v16, v11
	v_sub_f32_e32 v11, v14, v11
	v_ldexp_f32 v22, v11, 1
	v_mul_f32_e32 v11, v16, v17
	v_ldexp_f32 v15, v16, 1
	v_pk_mul_f32 v[16:17], v[10:11], v[178:179]
	s_nop 0
	v_fma_f32 v14, v10, s69, -v16
	v_fmac_f32_e32 v14, 0xb102e308, v10
	v_pk_add_f32 v[10:11], v[16:17], v[14:15]
	s_nop 0
	v_sub_f32_e32 v15, v11, v15
	v_sub_f32_e32 v15, v17, v15
	v_add_f32_e32 v23, v22, v15
	v_mov_b32_e32 v22, v16
	v_pk_add_f32 v[16:17], v[10:11], v[16:17] neg_lo:[0,1] neg_hi:[0,1]
	v_pk_add_f32 v[24:25], v[10:11], v[22:23]
	v_mov_b32_e32 v15, v10
	v_mov_b32_e32 v17, v25
	v_pk_add_f32 v[26:27], v[14:15], v[16:17] neg_lo:[0,1] neg_hi:[0,1]
	v_pk_add_f32 v[14:15], v[14:15], v[16:17]
	v_mov_b32_e32 v22, v23
	v_pk_add_f32 v[16:17], v[14:15], v[10:11] op_sel:[1,0] op_sel_hi:[0,1] neg_lo:[0,1] neg_hi:[0,1]
	v_pk_add_f32 v[28:29], v[24:25], v[16:17] op_sel_hi:[1,0] neg_lo:[0,1] neg_hi:[0,1]
	v_mov_b32_e32 v24, v25
	v_mov_b32_e32 v25, v15
	v_pk_mov_b32 v[16:17], v[10:11], v[16:17] op_sel:[1,0]
	v_mov_b32_e32 v23, v10
	v_pk_add_f32 v[16:17], v[24:25], v[16:17] neg_lo:[0,1] neg_hi:[0,1]
	v_mov_b32_e32 v28, v26
	v_pk_add_f32 v[10:11], v[22:23], v[16:17] neg_lo:[0,1] neg_hi:[0,1]
	v_mov_b32_e32 v27, v15
	v_pk_add_f32 v[16:17], v[28:29], v[10:11]
	s_nop 0
	v_pk_add_f32 v[22:23], v[16:17], v[16:17] op_sel:[0,1] op_sel_hi:[1,0]
	s_nop 0
	v_pk_add_f32 v[14:15], v[14:15], v[22:23] op_sel:[1,0] op_sel_hi:[0,1]
	v_mov_b32_e32 v17, v14
	v_pk_add_f32 v[24:25], v[16:17], v[26:27] neg_lo:[0,1] neg_hi:[0,1]
	v_mov_b32_e32 v11, v22
	v_sub_f32_e32 v15, v16, v24
	v_pk_add_f32 v[10:11], v[10:11], v[24:25] neg_lo:[0,1] neg_hi:[0,1]
	v_sub_f32_e32 v15, v26, v15
	v_add_f32_e32 v10, v10, v15
	v_add_f32_e32 v10, v10, v11
	v_add_f32_e32 v10, v14, v10
	v_cndmask_b32_e64 v10, v208, v10, s[0:1]
	v_cmp_lt_f32_e64 s[0:1], |v12|, s66
	s_nop 1
	v_cndmask_b32_e64 v10, v10, v12, s[0:1]
	v_sub_f32_e32 v0, v0, v10
	v_lshl_add_u64 v[10:11], v[20:21], 0, v[58:59]
	v_lshlrev_b64 v[10:11], 14, v[10:11]
	v_lshl_add_u64 v[10:11], v[18:19], 0, v[10:11]
	global_store_dword v[10:11], v0, off
	s_or_b64 exec, exec, s[84:85]
	s_and_saveexec_b64 s[84:85], s[18:19]
	s_cbranch_execnz .LBB0_580
	s_branch .LBB0_581
;     __device__ __forceinline__ void operator()(const f32x4 (&acc)[2][2][4][2], const pg8::Unit& u, int wr, int wc, int fr, int fq) const {
;     ...
;                     for (int m = 0; m < 4; ++m) { const int row = row0 + ai * 128 + m * 16;
; #pragma unroll
;                         for (int n = 0; n < 2; ++n)
; #pragma unroll
;                             for (int j = 0; j < 4; ++j) { const int col = 8 * fq + 4 * n + j;
;                                 if (col < 12) { const float xv = acc[ai][0][m][n][j] * rsqrtf(ssq[row] * (1.f / DM) + EPS) + bfp[col]; LS[((size_t)(row >> 12) * 12 + col) * SEQ + (row & (SEQ - 1))] = fminf(xv, 0.f) - log1pf(expf(-fabsf(xv))); } } }
.LBB0_633:
	global_load_dword v0, v[66:67], off offset:704
	s_waitcnt vmcnt(0) lgkmcnt(0)
	v_fmamk_f32 v0, v0, 0x3a000000, v205
	v_cmp_gt_f32_e32 vcc, s68, v0
	v_mul_f32_e32 v14, 0x4b800000, v0
	s_nop 0
	v_cndmask_b32_e32 v0, v0, v14, vcc
	v_rsq_f32_e32 v0, v0
	s_nop 0
	v_mul_f32_e32 v14, 0x45800000, v0
	v_cndmask_b32_e32 v0, v0, v14, vcc
	v_lshl_add_u64 v[14:15], v[68:69], 2, s[60:61]
	global_load_dword v14, v[14:15], off
	s_waitcnt vmcnt(0) lgkmcnt(0)
	v_fmac_f32_e32 v14, v6, v0
	v_mul_f32_e64 v6, |v14|, s88
	v_fma_f32 v15, |v14|, s88, -v6
	v_rndne_f32_e32 v16, v6
	v_fma_f32 v15, |v14|, s89, v15
	v_sub_f32_e32 v6, v6, v16
	v_add_f32_e32 v6, v6, v15
	v_exp_f32_e32 v6, v6
	v_cvt_i32_f32_e32 v15, v16
	v_cmp_ngt_f32_e64 vcc, |v14|, s70
	v_min_f32_e32 v0, 0, v14
	v_ldexp_f32 v6, v6, v15
	v_cndmask_b32_e32 v6, 0, v6, vcc
	v_cmp_nlt_f32_e64 vcc, |v14|, s90
	s_nop 1
	v_cndmask_b32_e32 v6, v208, v6, vcc
	v_add_f32_e32 v16, 1.0, v6
	v_add_f32_e32 v14, -1.0, v16
	v_sub_f32_e32 v15, v14, v16
	v_add_f32_e32 v15, 1.0, v15
	v_sub_f32_e32 v14, v6, v14
	v_add_f32_e32 v17, v14, v15
	v_frexp_mant_f32_e32 v14, v16
	v_cmp_gt_f32_e32 vcc, s3, v14
	v_cvt_f64_f32_e32 v[14:15], v16
	v_frexp_exp_i32_f64_e32 v14, v[14:15]
	v_subbrev_co_u32_e32 v22, vcc, 0, v14, vcc
	v_sub_u32_e32 v14, 0, v22
	v_ldexp_f32 v15, v16, v14
	v_add_f32_e32 v16, -1.0, v15
	v_add_f32_e32 v18, 1.0, v15
	v_ldexp_f32 v14, v17, v14
	v_add_f32_e32 v17, 1.0, v16
	v_add_f32_e32 v19, -1.0, v18
	v_sub_f32_e32 v17, v15, v17
	v_sub_f32_e32 v15, v15, v19
	v_add_f32_e32 v17, v14, v17
	v_add_f32_e32 v14, v14, v15
	v_add_f32_e32 v23, v18, v14
	v_rcp_f32_e32 v25, v23
	v_sub_f32_e32 v15, v18, v23
	v_add_f32_e32 v24, v14, v15
	v_add_f32_e32 v15, v16, v17
	v_mul_f32_e32 v27, v15, v25
	v_sub_f32_e32 v14, v16, v15
	v_mul_f32_e32 v16, v23, v27
	v_fma_f32 v18, v27, v23, -v16
	v_fmac_f32_e32 v18, v27, v24
	v_add_f32_e32 v26, v17, v14
	v_add_f32_e32 v14, v16, v18
	v_sub_f32_e32 v17, v15, v14
	v_pk_add_f32 v[20:21], v[14:15], v[16:17] neg_lo:[0,1] neg_hi:[0,1]
	v_mov_b32_e32 v19, v14
	v_pk_add_f32 v[14:15], v[20:21], v[18:19] neg_lo:[0,1] neg_hi:[0,1]
	v_cmp_neq_f32_e32 vcc, s2, v6
	v_add_f32_e32 v15, v26, v15
	v_add_f32_e32 v14, v14, v15
	v_add_f32_e32 v15, v17, v14
	v_mul_f32_e32 v26, v25, v15
	v_mul_f32_e32 v16, v23, v26
	v_fma_f32 v18, v26, v23, -v16
	v_fmac_f32_e32 v18, v26, v24
	v_sub_f32_e32 v17, v17, v15
	v_add_f32_e32 v23, v14, v17
	v_add_f32_e32 v14, v16, v18
	v_sub_f32_e32 v17, v15, v14
	v_pk_add_f32 v[20:21], v[14:15], v[16:17] neg_lo:[0,1] neg_hi:[0,1]
	v_mov_b32_e32 v19, v14
	v_pk_add_f32 v[14:15], v[20:21], v[18:19] neg_lo:[0,1] neg_hi:[0,1]
	s_nop 0
	v_add_f32_e32 v15, v23, v15
	v_add_f32_e32 v14, v14, v15
	v_add_f32_e32 v15, v27, v26
	v_add_f32_e32 v14, v17, v14
	v_sub_f32_e32 v16, v15, v27
	v_mul_f32_e32 v14, v25, v14
	v_sub_f32_e32 v16, v26, v16
	v_add_f32_e32 v16, v16, v14
	v_add_f32_e32 v18, v15, v16
	v_mul_f32_e32 v19, v18, v18
	v_fmamk_f32 v14, v19, 0x3e9b6dac, v206
	v_fmaak_f32 v179, v19, v14, 0x3f2aaada
	v_cvt_f32_i32_e32 v14, v22
	v_sub_f32_e32 v15, v18, v15
	v_sub_f32_e32 v15, v16, v15
	v_ldexp_f32 v20, v15, 1
	v_mul_f32_e32 v15, v18, v19
	v_ldexp_f32 v17, v18, 1
	v_pk_mul_f32 v[18:19], v[14:15], v[178:179]
	s_nop 0
	v_fma_f32 v16, v14, s69, -v18
	v_fmac_f32_e32 v16, 0xb102e308, v14
	v_pk_add_f32 v[14:15], v[18:19], v[16:17]
	s_nop 0
	v_sub_f32_e32 v17, v15, v17
	v_sub_f32_e32 v17, v19, v17
	v_add_f32_e32 v21, v20, v17
	v_mov_b32_e32 v20, v18
	v_pk_add_f32 v[18:19], v[14:15], v[18:19] neg_lo:[0,1] neg_hi:[0,1]
	v_pk_add_f32 v[22:23], v[14:15], v[20:21]
	v_mov_b32_e32 v17, v14
	v_mov_b32_e32 v19, v23
	v_pk_add_f32 v[24:25], v[16:17], v[18:19] neg_lo:[0,1] neg_hi:[0,1]
	v_pk_add_f32 v[16:17], v[16:17], v[18:19]
	v_mov_b32_e32 v20, v21
	v_pk_add_f32 v[18:19], v[16:17], v[14:15] op_sel:[1,0] op_sel_hi:[0,1] neg_lo:[0,1] neg_hi:[0,1]
	v_pk_add_f32 v[26:27], v[22:23], v[18:19] op_sel_hi:[1,0] neg_lo:[0,1] neg_hi:[0,1]
	v_mov_b32_e32 v22, v23
	v_mov_b32_e32 v23, v17
	v_pk_mov_b32 v[18:19], v[14:15], v[18:19] op_sel:[1,0]
	v_mov_b32_e32 v21, v14
	v_pk_add_f32 v[18:19], v[22:23], v[18:19] neg_lo:[0,1] neg_hi:[0,1]
	v_mov_b32_e32 v26, v24
	v_pk_add_f32 v[14:15], v[20:21], v[18:19] neg_lo:[0,1] neg_hi:[0,1]
	v_mov_b32_e32 v25, v17
	v_pk_add_f32 v[18:19], v[26:27], v[14:15]
	s_nop 0
	v_pk_add_f32 v[20:21], v[18:19], v[18:19] op_sel:[0,1] op_sel_hi:[1,0]
	s_nop 0
	v_pk_add_f32 v[16:17], v[16:17], v[20:21] op_sel:[1,0] op_sel_hi:[0,1]
	v_mov_b32_e32 v19, v16
	v_pk_add_f32 v[22:23], v[18:19], v[24:25] neg_lo:[0,1] neg_hi:[0,1]
	v_mov_b32_e32 v15, v20
	v_sub_f32_e32 v17, v18, v22
	v_pk_add_f32 v[14:15], v[14:15], v[22:23] neg_lo:[0,1] neg_hi:[0,1]
	v_sub_f32_e32 v17, v24, v17
	v_add_f32_e32 v14, v14, v17
	v_add_f32_e32 v14, v14, v15
	v_add_f32_e32 v14, v16, v14
	v_cndmask_b32_e32 v14, v208, v14, vcc
	v_cmp_lt_f32_e64 vcc, |v6|, s66
	s_nop 1
	v_cndmask_b32_e32 v6, v14, v6, vcc
	v_lshl_add_u64 v[14:15], v[12:13], 0, v[68:69]
	v_lshlrev_b64 v[14:15], 14, v[14:15]
	v_sub_f32_e32 v0, v0, v6
	v_lshl_add_u64 v[14:15], v[10:11], 0, v[14:15]
	global_store_dword v[14:15], v0, off
	s_or_b64 exec, exec, s[0:1]
	s_and_saveexec_b64 s[0:1], s[6:7]
	s_cbranch_execz .LBB0_583
;     __device__ __forceinline__ void operator()(const f32x4 (&acc)[2][2][4][2], const pg8::Unit& u, int wr, int wc, int fr, int fq) const {
;     ...
;                     for (int m = 0; m < 4; ++m) { const int row = row0 + ai * 128 + m * 16;
; #pragma unroll
;                         for (int n = 0; n < 2; ++n)
; #pragma unroll
;                             for (int j = 0; j < 4; ++j) { const int col = 8 * fq + 4 * n + j;
;                                 if (col < 12) { const float xv = acc[ai][0][m][n][j] * rsqrtf(ssq[row] * (1.f / DM) + EPS) + bfp[col]; LS[((size_t)(row >> 12) * 12 + col) * SEQ + (row & (SEQ - 1))] = fminf(xv, 0.f) - log1pf(expf(-fabsf(xv))); } } }
.LBB0_634:
	global_load_dword v0, v[66:67], off offset:704
	v_lshl_add_u64 v[14:15], v[70:71], 2, s[60:61]
	s_waitcnt vmcnt(0) lgkmcnt(0)
	v_fmamk_f32 v0, v0, 0x3a000000, v205
	v_cmp_gt_f32_e32 vcc, s68, v0
	v_mul_f32_e32 v6, 0x4b800000, v0
	s_nop 0
	v_cndmask_b32_e32 v0, v0, v6, vcc
	v_rsq_f32_e32 v0, v0
	s_nop 0
	v_mul_f32_e32 v6, 0x45800000, v0
	v_cndmask_b32_e32 v0, v0, v6, vcc
	global_load_dword v6, v[14:15], off
	s_waitcnt vmcnt(0) lgkmcnt(0)
	v_fmac_f32_e32 v6, v7, v0
	v_mul_f32_e64 v7, |v6|, s88
	v_fma_f32 v14, |v6|, s88, -v7
	v_rndne_f32_e32 v15, v7
	v_fma_f32 v14, |v6|, s89, v14
	v_sub_f32_e32 v7, v7, v15
	v_add_f32_e32 v7, v7, v14
	v_exp_f32_e32 v7, v7
	v_cvt_i32_f32_e32 v14, v15
	v_cmp_ngt_f32_e64 vcc, |v6|, s70
	v_min_f32_e32 v0, 0, v6
	v_ldexp_f32 v7, v7, v14
	v_cndmask_b32_e32 v7, 0, v7, vcc
	v_cmp_nlt_f32_e64 vcc, |v6|, s90
	s_nop 1
	v_cndmask_b32_e32 v26, v208, v7, vcc
	v_add_f32_e32 v14, 1.0, v26
	v_add_f32_e32 v6, -1.0, v14
	v_sub_f32_e32 v7, v6, v14
	v_add_f32_e32 v7, 1.0, v7
	v_sub_f32_e32 v6, v26, v6
	v_add_f32_e32 v15, v6, v7
	v_frexp_mant_f32_e32 v6, v14
	v_cmp_gt_f32_e32 vcc, s3, v6
	v_cvt_f64_f32_e32 v[6:7], v14
	v_frexp_exp_i32_f64_e32 v6, v[6:7]
	v_subbrev_co_u32_e32 v20, vcc, 0, v6, vcc
	v_sub_u32_e32 v6, 0, v20
	v_ldexp_f32 v7, v14, v6
	v_add_f32_e32 v14, -1.0, v7
	v_add_f32_e32 v16, 1.0, v7
	v_ldexp_f32 v6, v15, v6
	v_add_f32_e32 v15, 1.0, v14
	v_add_f32_e32 v17, -1.0, v16
	v_sub_f32_e32 v15, v7, v15
	v_sub_f32_e32 v7, v7, v17
	v_add_f32_e32 v15, v6, v15
	v_add_f32_e32 v6, v6, v7
	v_add_f32_e32 v21, v16, v6
	v_rcp_f32_e32 v23, v21
	v_sub_f32_e32 v7, v16, v21
	v_add_f32_e32 v22, v6, v7
	v_add_f32_e32 v7, v14, v15
	v_mul_f32_e32 v25, v7, v23
	v_sub_f32_e32 v6, v14, v7
	v_mul_f32_e32 v14, v21, v25
	v_fma_f32 v16, v25, v21, -v14
	v_fmac_f32_e32 v16, v25, v22
	v_add_f32_e32 v24, v15, v6
	v_add_f32_e32 v6, v14, v16
	v_sub_f32_e32 v15, v7, v6
	v_pk_add_f32 v[18:19], v[6:7], v[14:15] neg_lo:[0,1] neg_hi:[0,1]
	v_mov_b32_e32 v17, v6
	v_pk_add_f32 v[6:7], v[18:19], v[16:17] neg_lo:[0,1] neg_hi:[0,1]
	v_cmp_neq_f32_e32 vcc, s2, v26
	v_add_f32_e32 v7, v24, v7
	v_add_f32_e32 v6, v6, v7
	v_add_f32_e32 v7, v15, v6
	v_mul_f32_e32 v24, v23, v7
	v_mul_f32_e32 v14, v21, v24
	v_fma_f32 v16, v24, v21, -v14
	v_fmac_f32_e32 v16, v24, v22
	v_sub_f32_e32 v15, v15, v7
	v_add_f32_e32 v21, v6, v15
	v_add_f32_e32 v6, v14, v16
	v_sub_f32_e32 v15, v7, v6
	v_pk_add_f32 v[18:19], v[6:7], v[14:15] neg_lo:[0,1] neg_hi:[0,1]
	v_mov_b32_e32 v17, v6
	v_pk_add_f32 v[6:7], v[18:19], v[16:17] neg_lo:[0,1] neg_hi:[0,1]
	s_nop 0
	v_add_f32_e32 v7, v21, v7
	v_add_f32_e32 v6, v6, v7
	v_add_f32_e32 v7, v25, v24
	v_add_f32_e32 v6, v15, v6
	v_sub_f32_e32 v14, v7, v25
	v_mul_f32_e32 v6, v23, v6
	v_sub_f32_e32 v14, v24, v14
	v_add_f32_e32 v14, v14, v6
	v_add_f32_e32 v16, v7, v14
	v_mul_f32_e32 v17, v16, v16
	v_fmamk_f32 v6, v17, 0x3e9b6dac, v206
	v_fmaak_f32 v179, v17, v6, 0x3f2aaada
	v_cvt_f32_i32_e32 v6, v20
	v_sub_f32_e32 v7, v16, v7
	v_sub_f32_e32 v7, v14, v7
	v_ldexp_f32 v18, v7, 1
	v_mul_f32_e32 v7, v16, v17
	v_ldexp_f32 v15, v16, 1
	v_pk_mul_f32 v[16:17], v[6:7], v[178:179]
	s_nop 0
	v_fma_f32 v14, v6, s69, -v16
	v_fmac_f32_e32 v14, 0xb102e308, v6
	v_pk_add_f32 v[6:7], v[16:17], v[14:15]
	s_nop 0
	v_sub_f32_e32 v15, v7, v15
	v_sub_f32_e32 v15, v17, v15
	v_add_f32_e32 v19, v18, v15
	v_mov_b32_e32 v18, v16
	v_pk_add_f32 v[16:17], v[6:7], v[16:17] neg_lo:[0,1] neg_hi:[0,1]
	v_pk_add_f32 v[20:21], v[6:7], v[18:19]
	v_mov_b32_e32 v15, v6
	v_mov_b32_e32 v17, v21
	v_pk_add_f32 v[22:23], v[14:15], v[16:17] neg_lo:[0,1] neg_hi:[0,1]
	v_pk_add_f32 v[14:15], v[14:15], v[16:17]
	v_mov_b32_e32 v18, v19
	v_pk_add_f32 v[16:17], v[14:15], v[6:7] op_sel:[1,0] op_sel_hi:[0,1] neg_lo:[0,1] neg_hi:[0,1]
	v_pk_add_f32 v[24:25], v[20:21], v[16:17] op_sel_hi:[1,0] neg_lo:[0,1] neg_hi:[0,1]
	v_mov_b32_e32 v20, v21
	v_mov_b32_e32 v21, v15
	v_pk_mov_b32 v[16:17], v[6:7], v[16:17] op_sel:[1,0]
	v_mov_b32_e32 v19, v6
	v_pk_add_f32 v[16:17], v[20:21], v[16:17] neg_lo:[0,1] neg_hi:[0,1]
	v_mov_b32_e32 v24, v22
	v_pk_add_f32 v[6:7], v[18:19], v[16:17] neg_lo:[0,1] neg_hi:[0,1]
	v_mov_b32_e32 v23, v15
	v_pk_add_f32 v[16:17], v[24:25], v[6:7]
	s_nop 0
	v_pk_add_f32 v[18:19], v[16:17], v[16:17] op_sel:[0,1] op_sel_hi:[1,0]
	s_nop 0
	v_pk_add_f32 v[14:15], v[14:15], v[18:19] op_sel:[1,0] op_sel_hi:[0,1]
	v_mov_b32_e32 v17, v14
	v_pk_add_f32 v[20:21], v[16:17], v[22:23] neg_lo:[0,1] neg_hi:[0,1]
	v_mov_b32_e32 v7, v18
	v_sub_f32_e32 v15, v16, v20
	v_pk_add_f32 v[6:7], v[6:7], v[20:21] neg_lo:[0,1] neg_hi:[0,1]
	v_sub_f32_e32 v15, v22, v15
	v_add_f32_e32 v6, v6, v15
	v_add_f32_e32 v6, v6, v7
	v_add_f32_e32 v6, v14, v6
	v_cndmask_b32_e32 v6, v208, v6, vcc
	v_cmp_lt_f32_e64 vcc, |v26|, s66
	s_nop 1
	v_cndmask_b32_e32 v6, v6, v26, vcc
	v_sub_f32_e32 v0, v0, v6
	v_lshl_add_u64 v[6:7], v[12:13], 0, v[70:71]
	v_lshlrev_b64 v[6:7], 14, v[6:7]
	v_lshl_add_u64 v[6:7], v[10:11], 0, v[6:7]
	global_store_dword v[6:7], v0, off
	s_or_b64 exec, exec, s[0:1]
	s_and_saveexec_b64 s[0:1], s[8:9]
	s_cbranch_execz .LBB0_584
;     __device__ __forceinline__ void operator()(const f32x4 (&acc)[2][2][4][2], const pg8::Unit& u, int wr, int wc, int fr, int fq) const {
;     ...
;                     for (int m = 0; m < 4; ++m) { const int row = row0 + ai * 128 + m * 16;
; #pragma unroll
;                         for (int n = 0; n < 2; ++n)
; #pragma unroll
;                             for (int j = 0; j < 4; ++j) { const int col = 8 * fq + 4 * n + j;
;                                 if (col < 12) { const float xv = acc[ai][0][m][n][j] * rsqrtf(ssq[row] * (1.f / DM) + EPS) + bfp[col]; LS[((size_t)(row >> 12) * 12 + col) * SEQ + (row & (SEQ - 1))] = fminf(xv, 0.f) - log1pf(expf(-fabsf(xv))); } } }
.LBB0_635:
	global_load_dword v0, v[66:67], off offset:704
	s_waitcnt vmcnt(0) lgkmcnt(0)
	v_fmamk_f32 v0, v0, 0x3a000000, v205
	v_cmp_gt_f32_e32 vcc, s68, v0
	v_mul_f32_e32 v6, 0x4b800000, v0
	s_nop 0
	v_cndmask_b32_e32 v0, v0, v6, vcc
	v_rsq_f32_e32 v0, v0
	s_nop 0
	v_mul_f32_e32 v6, 0x45800000, v0
	v_cndmask_b32_e32 v0, v0, v6, vcc
	v_lshl_add_u64 v[6:7], v[62:63], 2, s[60:61]
	global_load_dword v6, v[6:7], off
	s_waitcnt vmcnt(0) lgkmcnt(0)
	v_fmac_f32_e32 v6, v8, v0
	v_mul_f32_e64 v7, |v6|, s88
	v_fma_f32 v8, |v6|, s88, -v7
	v_rndne_f32_e32 v14, v7
	v_fma_f32 v8, |v6|, s89, v8
	v_sub_f32_e32 v7, v7, v14
	v_add_f32_e32 v7, v7, v8
	v_exp_f32_e32 v7, v7
	v_cvt_i32_f32_e32 v8, v14
	v_cmp_ngt_f32_e64 vcc, |v6|, s70
	v_min_f32_e32 v0, 0, v6
	v_ldexp_f32 v7, v7, v8
	v_cndmask_b32_e32 v7, 0, v7, vcc
	v_cmp_nlt_f32_e64 vcc, |v6|, s90
	s_nop 1
	v_cndmask_b32_e32 v8, v208, v7, vcc
	v_add_f32_e32 v14, 1.0, v8
	v_add_f32_e32 v6, -1.0, v14
	v_sub_f32_e32 v7, v6, v14
	v_add_f32_e32 v7, 1.0, v7
	v_sub_f32_e32 v6, v8, v6
	v_add_f32_e32 v15, v6, v7
	v_frexp_mant_f32_e32 v6, v14
	v_cmp_gt_f32_e32 vcc, s3, v6
	v_cvt_f64_f32_e32 v[6:7], v14
	v_frexp_exp_i32_f64_e32 v6, v[6:7]
	v_subbrev_co_u32_e32 v20, vcc, 0, v6, vcc
	v_sub_u32_e32 v6, 0, v20
	v_ldexp_f32 v7, v14, v6
	v_add_f32_e32 v14, -1.0, v7
	v_add_f32_e32 v16, 1.0, v7
	v_ldexp_f32 v6, v15, v6
	v_add_f32_e32 v15, 1.0, v14
	v_add_f32_e32 v17, -1.0, v16
	v_sub_f32_e32 v15, v7, v15
	v_sub_f32_e32 v7, v7, v17
	v_add_f32_e32 v15, v6, v15
	v_add_f32_e32 v6, v6, v7
	v_add_f32_e32 v21, v16, v6
	v_rcp_f32_e32 v23, v21
	v_sub_f32_e32 v7, v16, v21
	v_add_f32_e32 v22, v6, v7
	v_add_f32_e32 v7, v14, v15
	v_mul_f32_e32 v25, v7, v23
	v_sub_f32_e32 v6, v14, v7
	v_mul_f32_e32 v14, v21, v25
	v_fma_f32 v16, v25, v21, -v14
	v_fmac_f32_e32 v16, v25, v22
	v_add_f32_e32 v24, v15, v6
	v_add_f32_e32 v6, v14, v16
	v_sub_f32_e32 v15, v7, v6
	v_pk_add_f32 v[18:19], v[6:7], v[14:15] neg_lo:[0,1] neg_hi:[0,1]
	v_mov_b32_e32 v17, v6
	v_pk_add_f32 v[6:7], v[18:19], v[16:17] neg_lo:[0,1] neg_hi:[0,1]
	v_cmp_neq_f32_e32 vcc, s2, v8
	v_add_f32_e32 v7, v24, v7
	v_add_f32_e32 v6, v6, v7
	v_add_f32_e32 v7, v15, v6
	v_mul_f32_e32 v24, v23, v7
	v_mul_f32_e32 v14, v21, v24
	v_fma_f32 v16, v24, v21, -v14
	v_fmac_f32_e32 v16, v24, v22
	v_sub_f32_e32 v15, v15, v7
	v_add_f32_e32 v21, v6, v15
	v_add_f32_e32 v6, v14, v16
	v_sub_f32_e32 v15, v7, v6
	v_pk_add_f32 v[18:19], v[6:7], v[14:15] neg_lo:[0,1] neg_hi:[0,1]
	v_mov_b32_e32 v17, v6
	v_pk_add_f32 v[6:7], v[18:19], v[16:17] neg_lo:[0,1] neg_hi:[0,1]
	s_nop 0
	v_add_f32_e32 v7, v21, v7
	v_add_f32_e32 v6, v6, v7
	v_add_f32_e32 v7, v25, v24
	v_add_f32_e32 v6, v15, v6
	v_sub_f32_e32 v14, v7, v25
	v_mul_f32_e32 v6, v23, v6
	v_sub_f32_e32 v14, v24, v14
	v_add_f32_e32 v14, v14, v6
	v_add_f32_e32 v16, v7, v14
	v_mul_f32_e32 v17, v16, v16
	v_fmamk_f32 v6, v17, 0x3e9b6dac, v206
	v_fmaak_f32 v179, v17, v6, 0x3f2aaada
	v_cvt_f32_i32_e32 v6, v20
	v_sub_f32_e32 v7, v16, v7
	v_sub_f32_e32 v7, v14, v7
	v_ldexp_f32 v18, v7, 1
	v_mul_f32_e32 v7, v16, v17
	v_ldexp_f32 v15, v16, 1
	v_pk_mul_f32 v[16:17], v[6:7], v[178:179]
	s_nop 0
	v_fma_f32 v14, v6, s69, -v16
	v_fmac_f32_e32 v14, 0xb102e308, v6
	v_pk_add_f32 v[6:7], v[16:17], v[14:15]
	s_nop 0
	v_sub_f32_e32 v15, v7, v15
	v_sub_f32_e32 v15, v17, v15
	v_add_f32_e32 v19, v18, v15
	v_mov_b32_e32 v18, v16
	v_pk_add_f32 v[16:17], v[6:7], v[16:17] neg_lo:[0,1] neg_hi:[0,1]
	v_pk_add_f32 v[20:21], v[6:7], v[18:19]
	v_mov_b32_e32 v15, v6
	v_mov_b32_e32 v17, v21
	v_pk_add_f32 v[22:23], v[14:15], v[16:17] neg_lo:[0,1] neg_hi:[0,1]
	v_pk_add_f32 v[14:15], v[14:15], v[16:17]
	v_mov_b32_e32 v18, v19
	v_pk_add_f32 v[16:17], v[14:15], v[6:7] op_sel:[1,0] op_sel_hi:[0,1] neg_lo:[0,1] neg_hi:[0,1]
	v_pk_add_f32 v[24:25], v[20:21], v[16:17] op_sel_hi:[1,0] neg_lo:[0,1] neg_hi:[0,1]
	v_mov_b32_e32 v20, v21
	v_mov_b32_e32 v21, v15
	v_pk_mov_b32 v[16:17], v[6:7], v[16:17] op_sel:[1,0]
	v_mov_b32_e32 v19, v6
	v_pk_add_f32 v[16:17], v[20:21], v[16:17] neg_lo:[0,1] neg_hi:[0,1]
	v_mov_b32_e32 v24, v22
	v_pk_add_f32 v[6:7], v[18:19], v[16:17] neg_lo:[0,1] neg_hi:[0,1]
	v_mov_b32_e32 v23, v15
	v_pk_add_f32 v[16:17], v[24:25], v[6:7]
	s_nop 0
	v_pk_add_f32 v[18:19], v[16:17], v[16:17] op_sel:[0,1] op_sel_hi:[1,0]
	s_nop 0
	v_pk_add_f32 v[14:15], v[14:15], v[18:19] op_sel:[1,0] op_sel_hi:[0,1]
	v_mov_b32_e32 v17, v14
	v_pk_add_f32 v[20:21], v[16:17], v[22:23] neg_lo:[0,1] neg_hi:[0,1]
	v_mov_b32_e32 v7, v18
	v_sub_f32_e32 v15, v16, v20
	v_pk_add_f32 v[6:7], v[6:7], v[20:21] neg_lo:[0,1] neg_hi:[0,1]
	v_sub_f32_e32 v15, v22, v15
	v_add_f32_e32 v6, v6, v15
	v_add_f32_e32 v6, v6, v7
	v_add_f32_e32 v6, v14, v6
	v_cndmask_b32_e32 v6, v208, v6, vcc
	v_cmp_lt_f32_e64 vcc, |v8|, s66
	s_nop 1
	v_cndmask_b32_e32 v6, v6, v8, vcc
	v_sub_f32_e32 v0, v0, v6
	v_lshl_add_u64 v[6:7], v[12:13], 0, v[62:63]
	v_lshlrev_b64 v[6:7], 14, v[6:7]
	v_lshl_add_u64 v[6:7], v[10:11], 0, v[6:7]
	global_store_dword v[6:7], v0, off
	s_or_b64 exec, exec, s[0:1]
	s_and_saveexec_b64 s[0:1], s[10:11]
	s_cbranch_execz .LBB0_585
;     __device__ __forceinline__ void operator()(const f32x4 (&acc)[2][2][4][2], const pg8::Unit& u, int wr, int wc, int fr, int fq) const {
;     ...
;                     for (int m = 0; m < 4; ++m) { const int row = row0 + ai * 128 + m * 16;
; #pragma unroll
;                         for (int n = 0; n < 2; ++n)
; #pragma unroll
;                             for (int j = 0; j < 4; ++j) { const int col = 8 * fq + 4 * n + j;
;                                 if (col < 12) { const float xv = acc[ai][0][m][n][j] * rsqrtf(ssq[row] * (1.f / DM) + EPS) + bfp[col]; LS[((size_t)(row >> 12) * 12 + col) * SEQ + (row & (SEQ - 1))] = fminf(xv, 0.f) - log1pf(expf(-fabsf(xv))); } } }
.LBB0_636:
	global_load_dword v0, v[66:67], off offset:704
	s_waitcnt vmcnt(0) lgkmcnt(0)
	v_fmamk_f32 v0, v0, 0x3a000000, v205
	v_cmp_gt_f32_e32 vcc, s68, v0
	v_mul_f32_e32 v6, 0x4b800000, v0
	s_nop 0
	v_cndmask_b32_e32 v0, v0, v6, vcc
	v_rsq_f32_e32 v0, v0
	s_nop 0
	v_mul_f32_e32 v6, 0x45800000, v0
	v_cndmask_b32_e32 v0, v0, v6, vcc
	v_lshl_add_u64 v[6:7], v[72:73], 2, s[60:61]
	global_load_dword v6, v[6:7], off
	s_waitcnt vmcnt(0) lgkmcnt(0)
	v_fmac_f32_e32 v6, v9, v0
	v_mul_f32_e64 v7, |v6|, s88
	v_fma_f32 v8, |v6|, s88, -v7
	v_rndne_f32_e32 v9, v7
	v_fma_f32 v8, |v6|, s89, v8
	v_sub_f32_e32 v7, v7, v9
	v_add_f32_e32 v7, v7, v8
	v_exp_f32_e32 v7, v7
	v_cvt_i32_f32_e32 v8, v9
	v_cmp_ngt_f32_e64 vcc, |v6|, s70
	v_min_f32_e32 v0, 0, v6
	v_ldexp_f32 v7, v7, v8
	v_cndmask_b32_e32 v7, 0, v7, vcc
	v_cmp_nlt_f32_e64 vcc, |v6|, s90
	s_nop 1
	v_cndmask_b32_e32 v24, v208, v7, vcc
	v_add_f32_e32 v8, 1.0, v24
	v_add_f32_e32 v6, -1.0, v8
	v_sub_f32_e32 v7, v6, v8
	v_add_f32_e32 v7, 1.0, v7
	v_sub_f32_e32 v6, v24, v6
	v_add_f32_e32 v9, v6, v7
	v_frexp_mant_f32_e32 v6, v8
	v_cmp_gt_f32_e32 vcc, s3, v6
	v_cvt_f64_f32_e32 v[6:7], v8
	v_frexp_exp_i32_f64_e32 v6, v[6:7]
	v_subbrev_co_u32_e32 v18, vcc, 0, v6, vcc
	v_sub_u32_e32 v6, 0, v18
	v_ldexp_f32 v7, v8, v6
	v_add_f32_e32 v8, -1.0, v7
	v_add_f32_e32 v14, 1.0, v7
	v_ldexp_f32 v6, v9, v6
	v_add_f32_e32 v9, 1.0, v8
	v_add_f32_e32 v15, -1.0, v14
	v_sub_f32_e32 v9, v7, v9
	v_sub_f32_e32 v7, v7, v15
	v_add_f32_e32 v9, v6, v9
	v_add_f32_e32 v6, v6, v7
	v_add_f32_e32 v19, v14, v6
	v_rcp_f32_e32 v21, v19
	v_sub_f32_e32 v7, v14, v19
	v_add_f32_e32 v20, v6, v7
	v_add_f32_e32 v7, v8, v9
	v_mul_f32_e32 v23, v7, v21
	v_sub_f32_e32 v6, v8, v7
	v_mul_f32_e32 v8, v19, v23
	v_fma_f32 v14, v23, v19, -v8
	v_fmac_f32_e32 v14, v23, v20
	v_add_f32_e32 v22, v9, v6
	v_add_f32_e32 v6, v8, v14
	v_sub_f32_e32 v9, v7, v6
	v_pk_add_f32 v[16:17], v[6:7], v[8:9] neg_lo:[0,1] neg_hi:[0,1]
	v_mov_b32_e32 v15, v6
	v_pk_add_f32 v[6:7], v[16:17], v[14:15] neg_lo:[0,1] neg_hi:[0,1]
	v_cmp_neq_f32_e32 vcc, s2, v24
	v_add_f32_e32 v7, v22, v7
	v_add_f32_e32 v6, v6, v7
	v_add_f32_e32 v7, v9, v6
	v_mul_f32_e32 v22, v21, v7
	v_mul_f32_e32 v8, v19, v22
	v_fma_f32 v14, v22, v19, -v8
	v_fmac_f32_e32 v14, v22, v20
	v_sub_f32_e32 v9, v9, v7
	v_add_f32_e32 v19, v6, v9
	v_add_f32_e32 v6, v8, v14
	v_sub_f32_e32 v9, v7, v6
	v_pk_add_f32 v[16:17], v[6:7], v[8:9] neg_lo:[0,1] neg_hi:[0,1]
	v_mov_b32_e32 v15, v6
	v_pk_add_f32 v[6:7], v[16:17], v[14:15] neg_lo:[0,1] neg_hi:[0,1]
	s_nop 0
	v_add_f32_e32 v7, v19, v7
	v_add_f32_e32 v6, v6, v7
	v_add_f32_e32 v7, v23, v22
	v_add_f32_e32 v6, v9, v6
	v_sub_f32_e32 v8, v7, v23
	v_mul_f32_e32 v6, v21, v6
	v_sub_f32_e32 v8, v22, v8
	v_add_f32_e32 v8, v8, v6
	v_add_f32_e32 v14, v7, v8
	v_mul_f32_e32 v15, v14, v14
	v_fmamk_f32 v6, v15, 0x3e9b6dac, v206
	v_fmaak_f32 v179, v15, v6, 0x3f2aaada
	v_cvt_f32_i32_e32 v6, v18
	v_sub_f32_e32 v7, v14, v7
	v_sub_f32_e32 v7, v8, v7
	v_ldexp_f32 v16, v7, 1
	v_mul_f32_e32 v7, v14, v15
	v_ldexp_f32 v9, v14, 1
	v_pk_mul_f32 v[14:15], v[6:7], v[178:179]
	s_nop 0
	v_fma_f32 v8, v6, s69, -v14
	v_fmac_f32_e32 v8, 0xb102e308, v6
	v_pk_add_f32 v[6:7], v[14:15], v[8:9]
	s_nop 0
	v_sub_f32_e32 v9, v7, v9
	v_sub_f32_e32 v9, v15, v9
	v_add_f32_e32 v17, v16, v9
	v_mov_b32_e32 v16, v14
	v_pk_add_f32 v[14:15], v[6:7], v[14:15] neg_lo:[0,1] neg_hi:[0,1]
	v_pk_add_f32 v[18:19], v[6:7], v[16:17]
	v_mov_b32_e32 v9, v6
	v_mov_b32_e32 v15, v19
	v_pk_add_f32 v[20:21], v[8:9], v[14:15] neg_lo:[0,1] neg_hi:[0,1]
	v_pk_add_f32 v[8:9], v[8:9], v[14:15]
	v_mov_b32_e32 v16, v17
	v_pk_add_f32 v[14:15], v[8:9], v[6:7] op_sel:[1,0] op_sel_hi:[0,1] neg_lo:[0,1] neg_hi:[0,1]
	v_pk_add_f32 v[22:23], v[18:19], v[14:15] op_sel_hi:[1,0] neg_lo:[0,1] neg_hi:[0,1]
	v_mov_b32_e32 v18, v19
	v_mov_b32_e32 v19, v9
	v_pk_mov_b32 v[14:15], v[6:7], v[14:15] op_sel:[1,0]
	v_mov_b32_e32 v17, v6
	v_pk_add_f32 v[14:15], v[18:19], v[14:15] neg_lo:[0,1] neg_hi:[0,1]
	v_mov_b32_e32 v22, v20
	v_pk_add_f32 v[6:7], v[16:17], v[14:15] neg_lo:[0,1] neg_hi:[0,1]
	v_mov_b32_e32 v21, v9
	v_pk_add_f32 v[14:15], v[22:23], v[6:7]
	s_nop 0
	v_pk_add_f32 v[16:17], v[14:15], v[14:15] op_sel:[0,1] op_sel_hi:[1,0]
	s_nop 0
	v_pk_add_f32 v[8:9], v[8:9], v[16:17] op_sel:[1,0] op_sel_hi:[0,1]
	v_mov_b32_e32 v15, v8
	v_pk_add_f32 v[18:19], v[14:15], v[20:21] neg_lo:[0,1] neg_hi:[0,1]
	v_mov_b32_e32 v7, v16
	v_sub_f32_e32 v9, v14, v18
	v_pk_add_f32 v[6:7], v[6:7], v[18:19] neg_lo:[0,1] neg_hi:[0,1]
	v_sub_f32_e32 v9, v20, v9
	v_add_f32_e32 v6, v6, v9
	v_add_f32_e32 v6, v6, v7
	v_add_f32_e32 v6, v8, v6
	v_cndmask_b32_e32 v6, v208, v6, vcc
	v_cmp_lt_f32_e64 vcc, |v24|, s66
	s_nop 1
	v_cndmask_b32_e32 v6, v6, v24, vcc
	v_sub_f32_e32 v0, v0, v6
	v_lshl_add_u64 v[6:7], v[12:13], 0, v[72:73]
	v_lshlrev_b64 v[6:7], 14, v[6:7]
	v_lshl_add_u64 v[6:7], v[10:11], 0, v[6:7]
	global_store_dword v[6:7], v0, off
	s_or_b64 exec, exec, s[0:1]
	s_and_saveexec_b64 s[0:1], s[12:13]
	s_cbranch_execz .LBB0_586
;     __device__ __forceinline__ void operator()(const f32x4 (&acc)[2][2][4][2], const pg8::Unit& u, int wr, int wc, int fr, int fq) const {
;     ...
;                     for (int m = 0; m < 4; ++m) { const int row = row0 + ai * 128 + m * 16;
; #pragma unroll
;                         for (int n = 0; n < 2; ++n)
; #pragma unroll
;                             for (int j = 0; j < 4; ++j) { const int col = 8 * fq + 4 * n + j;
;                                 if (col < 12) { const float xv = acc[ai][0][m][n][j] * rsqrtf(ssq[row] * (1.f / DM) + EPS) + bfp[col]; LS[((size_t)(row >> 12) * 12 + col) * SEQ + (row & (SEQ - 1))] = fminf(xv, 0.f) - log1pf(expf(-fabsf(xv))); } } }
.LBB0_637:
	global_load_dword v0, v[66:67], off offset:704
	s_waitcnt vmcnt(0) lgkmcnt(0)
	v_fmamk_f32 v0, v0, 0x3a000000, v205
	v_cmp_gt_f32_e32 vcc, s68, v0
	v_mul_f32_e32 v6, 0x4b800000, v0
	s_nop 0
	v_cndmask_b32_e32 v0, v0, v6, vcc
	v_rsq_f32_e32 v0, v0
	s_nop 0
	v_mul_f32_e32 v6, 0x45800000, v0
	v_cndmask_b32_e32 v0, v0, v6, vcc
	v_lshl_add_u64 v[6:7], v[64:65], 2, s[60:61]
	global_load_dword v6, v[6:7], off
	s_waitcnt vmcnt(0) lgkmcnt(0)
	v_fmac_f32_e32 v6, v2, v0
	v_mul_f32_e64 v2, |v6|, s88
	v_fma_f32 v7, |v6|, s88, -v2
	v_rndne_f32_e32 v8, v2
	v_fma_f32 v7, |v6|, s89, v7
	v_sub_f32_e32 v2, v2, v8
	v_add_f32_e32 v2, v2, v7
	v_exp_f32_e32 v2, v2
	v_cvt_i32_f32_e32 v7, v8
	v_cmp_ngt_f32_e64 vcc, |v6|, s70
	v_min_f32_e32 v0, 0, v6
	v_ldexp_f32 v2, v2, v7
	v_cndmask_b32_e32 v2, 0, v2, vcc
	v_cmp_nlt_f32_e64 vcc, |v6|, s90
	s_nop 1
	v_cndmask_b32_e32 v2, v208, v2, vcc
	v_add_f32_e32 v8, 1.0, v2
	v_add_f32_e32 v6, -1.0, v8
	v_sub_f32_e32 v7, v6, v8
	v_add_f32_e32 v7, 1.0, v7
	v_sub_f32_e32 v6, v2, v6
	v_add_f32_e32 v9, v6, v7
	v_frexp_mant_f32_e32 v6, v8
	v_cmp_gt_f32_e32 vcc, s3, v6
	v_cvt_f64_f32_e32 v[6:7], v8
	v_frexp_exp_i32_f64_e32 v6, v[6:7]
	v_subbrev_co_u32_e32 v18, vcc, 0, v6, vcc
	v_sub_u32_e32 v6, 0, v18
	v_ldexp_f32 v7, v8, v6
	v_add_f32_e32 v8, -1.0, v7
	v_add_f32_e32 v14, 1.0, v7
	v_ldexp_f32 v6, v9, v6
	v_add_f32_e32 v9, 1.0, v8
	v_add_f32_e32 v15, -1.0, v14
	v_sub_f32_e32 v9, v7, v9
	v_sub_f32_e32 v7, v7, v15
	v_add_f32_e32 v9, v6, v9
	v_add_f32_e32 v6, v6, v7
	v_add_f32_e32 v19, v14, v6
	v_rcp_f32_e32 v21, v19
	v_sub_f32_e32 v7, v14, v19
	v_add_f32_e32 v20, v6, v7
	v_add_f32_e32 v7, v8, v9
	v_mul_f32_e32 v23, v7, v21
	v_sub_f32_e32 v6, v8, v7
	v_mul_f32_e32 v8, v19, v23
	v_fma_f32 v14, v23, v19, -v8
	v_fmac_f32_e32 v14, v23, v20
	v_add_f32_e32 v22, v9, v6
	v_add_f32_e32 v6, v8, v14
	v_sub_f32_e32 v9, v7, v6
	v_pk_add_f32 v[16:17], v[6:7], v[8:9] neg_lo:[0,1] neg_hi:[0,1]
	v_mov_b32_e32 v15, v6
	v_pk_add_f32 v[6:7], v[16:17], v[14:15] neg_lo:[0,1] neg_hi:[0,1]
	v_cmp_neq_f32_e32 vcc, s2, v2
	v_add_f32_e32 v7, v22, v7
	v_add_f32_e32 v6, v6, v7
	v_add_f32_e32 v7, v9, v6
	v_mul_f32_e32 v22, v21, v7
	v_mul_f32_e32 v8, v19, v22
	v_fma_f32 v14, v22, v19, -v8
	v_fmac_f32_e32 v14, v22, v20
	v_sub_f32_e32 v9, v9, v7
	v_add_f32_e32 v19, v6, v9
	v_add_f32_e32 v6, v8, v14
	v_sub_f32_e32 v9, v7, v6
	v_pk_add_f32 v[16:17], v[6:7], v[8:9] neg_lo:[0,1] neg_hi:[0,1]
	v_mov_b32_e32 v15, v6
	v_pk_add_f32 v[6:7], v[16:17], v[14:15] neg_lo:[0,1] neg_hi:[0,1]
	s_nop 0
	v_add_f32_e32 v7, v19, v7
	v_add_f32_e32 v6, v6, v7
	v_add_f32_e32 v7, v23, v22
	v_add_f32_e32 v6, v9, v6
	v_sub_f32_e32 v8, v7, v23
	v_mul_f32_e32 v6, v21, v6
	v_sub_f32_e32 v8, v22, v8
	v_add_f32_e32 v8, v8, v6
	v_add_f32_e32 v14, v7, v8
	v_mul_f32_e32 v15, v14, v14
	v_fmamk_f32 v6, v15, 0x3e9b6dac, v206
	v_fmaak_f32 v179, v15, v6, 0x3f2aaada
	v_cvt_f32_i32_e32 v6, v18
	v_sub_f32_e32 v7, v14, v7
	v_sub_f32_e32 v7, v8, v7
	v_ldexp_f32 v16, v7, 1
	v_mul_f32_e32 v7, v14, v15
	v_ldexp_f32 v9, v14, 1
	v_pk_mul_f32 v[14:15], v[6:7], v[178:179]
	s_nop 0
	v_fma_f32 v8, v6, s69, -v14
	v_fmac_f32_e32 v8, 0xb102e308, v6
	v_pk_add_f32 v[6:7], v[14:15], v[8:9]
	s_nop 0
	v_sub_f32_e32 v9, v7, v9
	v_sub_f32_e32 v9, v15, v9
	v_add_f32_e32 v17, v16, v9
	v_mov_b32_e32 v16, v14
	v_pk_add_f32 v[14:15], v[6:7], v[14:15] neg_lo:[0,1] neg_hi:[0,1]
	v_pk_add_f32 v[18:19], v[6:7], v[16:17]
	v_mov_b32_e32 v9, v6
	v_mov_b32_e32 v15, v19
	v_pk_add_f32 v[20:21], v[8:9], v[14:15] neg_lo:[0,1] neg_hi:[0,1]
	v_pk_add_f32 v[8:9], v[8:9], v[14:15]
	v_mov_b32_e32 v16, v17
	v_pk_add_f32 v[14:15], v[8:9], v[6:7] op_sel:[1,0] op_sel_hi:[0,1] neg_lo:[0,1] neg_hi:[0,1]
	v_pk_add_f32 v[22:23], v[18:19], v[14:15] op_sel_hi:[1,0] neg_lo:[0,1] neg_hi:[0,1]
	v_mov_b32_e32 v18, v19
	v_mov_b32_e32 v19, v9
	v_pk_mov_b32 v[14:15], v[6:7], v[14:15] op_sel:[1,0]
	v_mov_b32_e32 v17, v6
	v_pk_add_f32 v[14:15], v[18:19], v[14:15] neg_lo:[0,1] neg_hi:[0,1]
	v_mov_b32_e32 v22, v20
	v_pk_add_f32 v[6:7], v[16:17], v[14:15] neg_lo:[0,1] neg_hi:[0,1]
	v_mov_b32_e32 v21, v9
	v_pk_add_f32 v[14:15], v[22:23], v[6:7]
	s_nop 0
	v_pk_add_f32 v[16:17], v[14:15], v[14:15] op_sel:[0,1] op_sel_hi:[1,0]
	s_nop 0
	v_pk_add_f32 v[8:9], v[8:9], v[16:17] op_sel:[1,0] op_sel_hi:[0,1]
	v_mov_b32_e32 v15, v8
	v_pk_add_f32 v[18:19], v[14:15], v[20:21] neg_lo:[0,1] neg_hi:[0,1]
	v_mov_b32_e32 v7, v16
	v_sub_f32_e32 v9, v14, v18
	v_pk_add_f32 v[6:7], v[6:7], v[18:19] neg_lo:[0,1] neg_hi:[0,1]
	v_sub_f32_e32 v9, v20, v9
	v_add_f32_e32 v6, v6, v9
	v_add_f32_e32 v6, v6, v7
	v_add_f32_e32 v6, v8, v6
	v_cndmask_b32_e32 v6, v208, v6, vcc
	v_cmp_lt_f32_e64 vcc, |v2|, s66
	s_nop 1
	v_cndmask_b32_e32 v2, v6, v2, vcc
	v_lshl_add_u64 v[6:7], v[12:13], 0, v[64:65]
	v_lshlrev_b64 v[6:7], 14, v[6:7]
	v_sub_f32_e32 v0, v0, v2
	v_lshl_add_u64 v[6:7], v[10:11], 0, v[6:7]
	global_store_dword v[6:7], v0, off
	s_or_b64 exec, exec, s[0:1]
	s_and_saveexec_b64 s[0:1], s[14:15]
	s_cbranch_execz .LBB0_587
;     __device__ __forceinline__ void operator()(const f32x4 (&acc)[2][2][4][2], const pg8::Unit& u, int wr, int wc, int fr, int fq) const {
;     ...
;                     for (int m = 0; m < 4; ++m) { const int row = row0 + ai * 128 + m * 16;
; #pragma unroll
;                         for (int n = 0; n < 2; ++n)
; #pragma unroll
;                             for (int j = 0; j < 4; ++j) { const int col = 8 * fq + 4 * n + j;
;                                 if (col < 12) { const float xv = acc[ai][0][m][n][j] * rsqrtf(ssq[row] * (1.f / DM) + EPS) + bfp[col]; LS[((size_t)(row >> 12) * 12 + col) * SEQ + (row & (SEQ - 1))] = fminf(xv, 0.f) - log1pf(expf(-fabsf(xv))); } } }
.LBB0_638:
	global_load_dword v0, v[66:67], off offset:704
	v_lshl_add_u64 v[6:7], v[74:75], 2, s[60:61]
	s_waitcnt vmcnt(0) lgkmcnt(0)
	v_fmamk_f32 v0, v0, 0x3a000000, v205
	v_cmp_gt_f32_e32 vcc, s68, v0
	v_mul_f32_e32 v2, 0x4b800000, v0
	s_nop 0
	v_cndmask_b32_e32 v0, v0, v2, vcc
	v_rsq_f32_e32 v0, v0
	s_nop 0
	v_mul_f32_e32 v2, 0x45800000, v0
	v_cndmask_b32_e32 v0, v0, v2, vcc
	global_load_dword v2, v[6:7], off
	s_waitcnt vmcnt(0) lgkmcnt(0)
	v_fmac_f32_e32 v2, v3, v0
	v_mul_f32_e64 v3, |v2|, s88
	v_fma_f32 v6, |v2|, s88, -v3
	v_rndne_f32_e32 v7, v3
	v_fma_f32 v6, |v2|, s89, v6
	v_sub_f32_e32 v3, v3, v7
	v_add_f32_e32 v3, v3, v6
	v_exp_f32_e32 v3, v3
	v_cvt_i32_f32_e32 v6, v7
	v_cmp_ngt_f32_e64 vcc, |v2|, s70
	v_min_f32_e32 v0, 0, v2
	v_ldexp_f32 v3, v3, v6
	v_cndmask_b32_e32 v3, 0, v3, vcc
	v_cmp_nlt_f32_e64 vcc, |v2|, s90
	s_nop 1
	v_cndmask_b32_e32 v22, v208, v3, vcc
	v_add_f32_e32 v6, 1.0, v22
	v_add_f32_e32 v2, -1.0, v6
	v_sub_f32_e32 v3, v2, v6
	v_add_f32_e32 v3, 1.0, v3
	v_sub_f32_e32 v2, v22, v2
	v_add_f32_e32 v7, v2, v3
	v_frexp_mant_f32_e32 v2, v6
	v_cmp_gt_f32_e32 vcc, s3, v2
	v_cvt_f64_f32_e32 v[2:3], v6
	v_frexp_exp_i32_f64_e32 v2, v[2:3]
	v_subbrev_co_u32_e32 v16, vcc, 0, v2, vcc
	v_sub_u32_e32 v2, 0, v16
	v_ldexp_f32 v3, v6, v2
	v_add_f32_e32 v6, -1.0, v3
	v_add_f32_e32 v8, 1.0, v3
	v_ldexp_f32 v2, v7, v2
	v_add_f32_e32 v7, 1.0, v6
	v_add_f32_e32 v9, -1.0, v8
	v_sub_f32_e32 v7, v3, v7
	v_sub_f32_e32 v3, v3, v9
	v_add_f32_e32 v7, v2, v7
	v_add_f32_e32 v2, v2, v3
	v_add_f32_e32 v17, v8, v2
	v_rcp_f32_e32 v19, v17
	v_sub_f32_e32 v3, v8, v17
	v_add_f32_e32 v18, v2, v3
	v_add_f32_e32 v3, v6, v7
	v_mul_f32_e32 v21, v3, v19
	v_sub_f32_e32 v2, v6, v3
	v_mul_f32_e32 v6, v17, v21
	v_fma_f32 v8, v21, v17, -v6
	v_fmac_f32_e32 v8, v21, v18
	v_add_f32_e32 v20, v7, v2
	v_add_f32_e32 v2, v6, v8
	v_sub_f32_e32 v7, v3, v2
	v_pk_add_f32 v[14:15], v[2:3], v[6:7] neg_lo:[0,1] neg_hi:[0,1]
	v_mov_b32_e32 v9, v2
	v_pk_add_f32 v[2:3], v[14:15], v[8:9] neg_lo:[0,1] neg_hi:[0,1]
	v_cmp_neq_f32_e32 vcc, s2, v22
	v_add_f32_e32 v3, v20, v3
	v_add_f32_e32 v2, v2, v3
	v_add_f32_e32 v3, v7, v2
	v_mul_f32_e32 v20, v19, v3
	v_mul_f32_e32 v6, v17, v20
	v_fma_f32 v8, v20, v17, -v6
	v_fmac_f32_e32 v8, v20, v18
	v_sub_f32_e32 v7, v7, v3
	v_add_f32_e32 v17, v2, v7
	v_add_f32_e32 v2, v6, v8
	v_sub_f32_e32 v7, v3, v2
	v_pk_add_f32 v[14:15], v[2:3], v[6:7] neg_lo:[0,1] neg_hi:[0,1]
	v_mov_b32_e32 v9, v2
	v_pk_add_f32 v[2:3], v[14:15], v[8:9] neg_lo:[0,1] neg_hi:[0,1]
	s_nop 0
	v_add_f32_e32 v3, v17, v3
	v_add_f32_e32 v2, v2, v3
	v_add_f32_e32 v3, v21, v20
	v_add_f32_e32 v2, v7, v2
	v_sub_f32_e32 v6, v3, v21
	v_mul_f32_e32 v2, v19, v2
	v_sub_f32_e32 v6, v20, v6
	v_add_f32_e32 v6, v6, v2
	v_add_f32_e32 v8, v3, v6
	v_mul_f32_e32 v9, v8, v8
	v_fmamk_f32 v2, v9, 0x3e9b6dac, v206
	v_fmaak_f32 v179, v9, v2, 0x3f2aaada
	v_cvt_f32_i32_e32 v2, v16
	v_sub_f32_e32 v3, v8, v3
	v_sub_f32_e32 v3, v6, v3
	v_ldexp_f32 v14, v3, 1
	v_mul_f32_e32 v3, v8, v9
	v_ldexp_f32 v7, v8, 1
	v_pk_mul_f32 v[8:9], v[2:3], v[178:179]
	s_nop 0
	v_fma_f32 v6, v2, s69, -v8
	v_fmac_f32_e32 v6, 0xb102e308, v2
	v_pk_add_f32 v[2:3], v[8:9], v[6:7]
	s_nop 0
	v_sub_f32_e32 v7, v3, v7
	v_sub_f32_e32 v7, v9, v7
	v_add_f32_e32 v15, v14, v7
	v_mov_b32_e32 v14, v8
	v_pk_add_f32 v[8:9], v[2:3], v[8:9] neg_lo:[0,1] neg_hi:[0,1]
	v_pk_add_f32 v[16:17], v[2:3], v[14:15]
	v_mov_b32_e32 v7, v2
	v_mov_b32_e32 v9, v17
	v_pk_add_f32 v[18:19], v[6:7], v[8:9] neg_lo:[0,1] neg_hi:[0,1]
	v_pk_add_f32 v[6:7], v[6:7], v[8:9]
	v_mov_b32_e32 v14, v15
	v_pk_add_f32 v[8:9], v[6:7], v[2:3] op_sel:[1,0] op_sel_hi:[0,1] neg_lo:[0,1] neg_hi:[0,1]
	v_pk_add_f32 v[20:21], v[16:17], v[8:9] op_sel_hi:[1,0] neg_lo:[0,1] neg_hi:[0,1]
	v_mov_b32_e32 v16, v17
	v_mov_b32_e32 v17, v7
	v_pk_mov_b32 v[8:9], v[2:3], v[8:9] op_sel:[1,0]
	v_mov_b32_e32 v15, v2
	v_pk_add_f32 v[8:9], v[16:17], v[8:9] neg_lo:[0,1] neg_hi:[0,1]
	v_mov_b32_e32 v20, v18
	v_pk_add_f32 v[2:3], v[14:15], v[8:9] neg_lo:[0,1] neg_hi:[0,1]
	v_mov_b32_e32 v19, v7
	v_pk_add_f32 v[8:9], v[20:21], v[2:3]
	s_nop 0
	v_pk_add_f32 v[14:15], v[8:9], v[8:9] op_sel:[0,1] op_sel_hi:[1,0]
	s_nop 0
	v_pk_add_f32 v[6:7], v[6:7], v[14:15] op_sel:[1,0] op_sel_hi:[0,1]
	v_mov_b32_e32 v9, v6
	v_pk_add_f32 v[16:17], v[8:9], v[18:19] neg_lo:[0,1] neg_hi:[0,1]
	v_mov_b32_e32 v3, v14
	v_sub_f32_e32 v7, v8, v16
	v_pk_add_f32 v[2:3], v[2:3], v[16:17] neg_lo:[0,1] neg_hi:[0,1]
	v_sub_f32_e32 v7, v18, v7
	v_add_f32_e32 v2, v2, v7
	v_add_f32_e32 v2, v2, v3
	v_add_f32_e32 v2, v6, v2
	v_cndmask_b32_e32 v2, v208, v2, vcc
	v_cmp_lt_f32_e64 vcc, |v22|, s66
	s_nop 1
	v_cndmask_b32_e32 v2, v2, v22, vcc
	v_sub_f32_e32 v0, v0, v2
	v_lshl_add_u64 v[2:3], v[12:13], 0, v[74:75]
	v_lshlrev_b64 v[2:3], 14, v[2:3]
	v_lshl_add_u64 v[2:3], v[10:11], 0, v[2:3]
	global_store_dword v[2:3], v0, off
	s_or_b64 exec, exec, s[0:1]
	s_and_saveexec_b64 s[0:1], s[16:17]
	s_cbranch_execz .LBB0_588
;     __device__ __forceinline__ void operator()(const f32x4 (&acc)[2][2][4][2], const pg8::Unit& u, int wr, int wc, int fr, int fq) const {
;     ...
;                     for (int m = 0; m < 4; ++m) { const int row = row0 + ai * 128 + m * 16;
; #pragma unroll
;                         for (int n = 0; n < 2; ++n)
; #pragma unroll
;                             for (int j = 0; j < 4; ++j) { const int col = 8 * fq + 4 * n + j;
;                                 if (col < 12) { const float xv = acc[ai][0][m][n][j] * rsqrtf(ssq[row] * (1.f / DM) + EPS) + bfp[col]; LS[((size_t)(row >> 12) * 12 + col) * SEQ + (row & (SEQ - 1))] = fminf(xv, 0.f) - log1pf(expf(-fabsf(xv))); } } }
.LBB0_639:
	global_load_dword v0, v[66:67], off offset:704
	s_waitcnt vmcnt(0) lgkmcnt(0)
	v_fmamk_f32 v0, v0, 0x3a000000, v205
	v_cmp_gt_f32_e32 vcc, s68, v0
	v_mul_f32_e32 v2, 0x4b800000, v0
	s_nop 0
	v_cndmask_b32_e32 v0, v0, v2, vcc
	v_rsq_f32_e32 v0, v0
	s_nop 0
	v_mul_f32_e32 v2, 0x45800000, v0
	v_cndmask_b32_e32 v0, v0, v2, vcc
	v_lshl_add_u64 v[2:3], v[58:59], 2, s[60:61]
	global_load_dword v2, v[2:3], off
	s_waitcnt vmcnt(0) lgkmcnt(0)
	v_fmac_f32_e32 v2, v4, v0
	v_mul_f32_e64 v3, |v2|, s88
	v_fma_f32 v4, |v2|, s88, -v3
	v_rndne_f32_e32 v6, v3
	v_fma_f32 v4, |v2|, s89, v4
	v_sub_f32_e32 v3, v3, v6
	v_add_f32_e32 v3, v3, v4
	v_exp_f32_e32 v3, v3
	v_cvt_i32_f32_e32 v4, v6
	v_cmp_ngt_f32_e64 vcc, |v2|, s70
	v_min_f32_e32 v0, 0, v2
	v_ldexp_f32 v3, v3, v4
	v_cndmask_b32_e32 v3, 0, v3, vcc
	v_cmp_nlt_f32_e64 vcc, |v2|, s90
	s_nop 1
	v_cndmask_b32_e32 v4, v208, v3, vcc
	v_add_f32_e32 v6, 1.0, v4
	v_add_f32_e32 v2, -1.0, v6
	v_sub_f32_e32 v3, v2, v6
	v_add_f32_e32 v3, 1.0, v3
	v_sub_f32_e32 v2, v4, v2
	v_add_f32_e32 v7, v2, v3
	v_frexp_mant_f32_e32 v2, v6
	v_cmp_gt_f32_e32 vcc, s3, v2
	v_cvt_f64_f32_e32 v[2:3], v6
	v_frexp_exp_i32_f64_e32 v2, v[2:3]
	v_subbrev_co_u32_e32 v16, vcc, 0, v2, vcc
	v_sub_u32_e32 v2, 0, v16
	v_ldexp_f32 v3, v6, v2
	v_add_f32_e32 v6, -1.0, v3
	v_add_f32_e32 v8, 1.0, v3
	v_ldexp_f32 v2, v7, v2
	v_add_f32_e32 v7, 1.0, v6
	v_add_f32_e32 v9, -1.0, v8
	v_sub_f32_e32 v7, v3, v7
	v_sub_f32_e32 v3, v3, v9
	v_add_f32_e32 v7, v2, v7
	v_add_f32_e32 v2, v2, v3
	v_add_f32_e32 v17, v8, v2
	v_rcp_f32_e32 v19, v17
	v_sub_f32_e32 v3, v8, v17
	v_add_f32_e32 v18, v2, v3
	v_add_f32_e32 v3, v6, v7
	v_mul_f32_e32 v21, v3, v19
	v_sub_f32_e32 v2, v6, v3
	v_mul_f32_e32 v6, v17, v21
	v_fma_f32 v8, v21, v17, -v6
	v_fmac_f32_e32 v8, v21, v18
	v_add_f32_e32 v20, v7, v2
	v_add_f32_e32 v2, v6, v8
	v_sub_f32_e32 v7, v3, v2
	v_pk_add_f32 v[14:15], v[2:3], v[6:7] neg_lo:[0,1] neg_hi:[0,1]
	v_mov_b32_e32 v9, v2
	v_pk_add_f32 v[2:3], v[14:15], v[8:9] neg_lo:[0,1] neg_hi:[0,1]
	v_cmp_neq_f32_e32 vcc, s2, v4
	v_add_f32_e32 v3, v20, v3
	v_add_f32_e32 v2, v2, v3
	v_add_f32_e32 v3, v7, v2
	v_mul_f32_e32 v20, v19, v3
	v_mul_f32_e32 v6, v17, v20
	v_fma_f32 v8, v20, v17, -v6
	v_fmac_f32_e32 v8, v20, v18
	v_sub_f32_e32 v7, v7, v3
	v_add_f32_e32 v17, v2, v7
	v_add_f32_e32 v2, v6, v8
	v_sub_f32_e32 v7, v3, v2
	v_pk_add_f32 v[14:15], v[2:3], v[6:7] neg_lo:[0,1] neg_hi:[0,1]
	v_mov_b32_e32 v9, v2
	v_pk_add_f32 v[2:3], v[14:15], v[8:9] neg_lo:[0,1] neg_hi:[0,1]
	s_nop 0
	v_add_f32_e32 v3, v17, v3
	v_add_f32_e32 v2, v2, v3
	v_add_f32_e32 v3, v21, v20
	v_add_f32_e32 v2, v7, v2
	v_sub_f32_e32 v6, v3, v21
	v_mul_f32_e32 v2, v19, v2
	v_sub_f32_e32 v6, v20, v6
	v_add_f32_e32 v6, v6, v2
	v_add_f32_e32 v8, v3, v6
	v_mul_f32_e32 v9, v8, v8
	v_fmamk_f32 v2, v9, 0x3e9b6dac, v206
	v_fmaak_f32 v179, v9, v2, 0x3f2aaada
	v_cvt_f32_i32_e32 v2, v16
	v_sub_f32_e32 v3, v8, v3
	v_sub_f32_e32 v3, v6, v3
	v_ldexp_f32 v14, v3, 1
	v_mul_f32_e32 v3, v8, v9
	v_ldexp_f32 v7, v8, 1
	v_pk_mul_f32 v[8:9], v[2:3], v[178:179]
	s_nop 0
	v_fma_f32 v6, v2, s69, -v8
	v_fmac_f32_e32 v6, 0xb102e308, v2
	v_pk_add_f32 v[2:3], v[8:9], v[6:7]
	s_nop 0
	v_sub_f32_e32 v7, v3, v7
	v_sub_f32_e32 v7, v9, v7
	v_add_f32_e32 v15, v14, v7
	v_mov_b32_e32 v14, v8
	v_pk_add_f32 v[8:9], v[2:3], v[8:9] neg_lo:[0,1] neg_hi:[0,1]
	v_pk_add_f32 v[16:17], v[2:3], v[14:15]
	v_mov_b32_e32 v7, v2
	v_mov_b32_e32 v9, v17
	v_pk_add_f32 v[18:19], v[6:7], v[8:9] neg_lo:[0,1] neg_hi:[0,1]
	v_pk_add_f32 v[6:7], v[6:7], v[8:9]
	v_mov_b32_e32 v14, v15
	v_pk_add_f32 v[8:9], v[6:7], v[2:3] op_sel:[1,0] op_sel_hi:[0,1] neg_lo:[0,1] neg_hi:[0,1]
	v_pk_add_f32 v[20:21], v[16:17], v[8:9] op_sel_hi:[1,0] neg_lo:[0,1] neg_hi:[0,1]
	v_mov_b32_e32 v16, v17
	v_mov_b32_e32 v17, v7
	v_pk_mov_b32 v[8:9], v[2:3], v[8:9] op_sel:[1,0]
	v_mov_b32_e32 v15, v2
	v_pk_add_f32 v[8:9], v[16:17], v[8:9] neg_lo:[0,1] neg_hi:[0,1]
	v_mov_b32_e32 v20, v18
	v_pk_add_f32 v[2:3], v[14:15], v[8:9] neg_lo:[0,1] neg_hi:[0,1]
	v_mov_b32_e32 v19, v7
	v_pk_add_f32 v[8:9], v[20:21], v[2:3]
	s_nop 0
	v_pk_add_f32 v[14:15], v[8:9], v[8:9] op_sel:[0,1] op_sel_hi:[1,0]
	s_nop 0
	v_pk_add_f32 v[6:7], v[6:7], v[14:15] op_sel:[1,0] op_sel_hi:[0,1]
	v_mov_b32_e32 v9, v6
	v_pk_add_f32 v[16:17], v[8:9], v[18:19] neg_lo:[0,1] neg_hi:[0,1]
	v_mov_b32_e32 v3, v14
	v_sub_f32_e32 v7, v8, v16
	v_pk_add_f32 v[2:3], v[2:3], v[16:17] neg_lo:[0,1] neg_hi:[0,1]
	v_sub_f32_e32 v7, v18, v7
	v_add_f32_e32 v2, v2, v7
	v_add_f32_e32 v2, v2, v3
	v_add_f32_e32 v2, v6, v2
	v_cndmask_b32_e32 v2, v208, v2, vcc
	v_cmp_lt_f32_e64 vcc, |v4|, s66
	s_nop 1
	v_cndmask_b32_e32 v2, v2, v4, vcc
	v_sub_f32_e32 v0, v0, v2
	v_lshl_add_u64 v[2:3], v[12:13], 0, v[58:59]
	v_lshlrev_b64 v[2:3], 14, v[2:3]
	v_lshl_add_u64 v[2:3], v[10:11], 0, v[2:3]
	global_store_dword v[2:3], v0, off
	s_or_b64 exec, exec, s[0:1]
	s_and_saveexec_b64 s[0:1], s[18:19]
	s_cbranch_execnz .LBB0_589
	s_branch .LBB0_590

; #define LAS __attribute__((address_space(3)))
; __device__ __forceinline__ unsigned pk2(float lo, float hi) { const f32x2v v = {lo, hi}; return __builtin_bit_cast(unsigned, __builtin_convertvector(v, bf16x2v)); }
; __device__ __forceinline__ void tr_item(const float* W, int N, bf16_t* WT, int item, int lane, LAS float* scr, int fox, const float* gk) {
;     const int nblk = (N + 31) >> 5, kb = item / nblk, nb = item - kb * nblk, k0 = 64 * kb, n0 = 32 * nb;
;     const int nq = lane & 7, kr = lane >> 3, nc = n0 + 4 * nq;
;     f32x4 wv[8];
; #pragma unroll
;     for (int i = 0; i < 8; ++i) wv[i] = (nc < N) ? *(const f32x4*)(W + (size_t)(k0 + kr + 8 * i) * N + nc) : (f32x4){0.f, 0.f, 0.f, 0.f};
; #pragma unroll
;     for (int i = 0; i < 8; ++i) { const int kk = kr + 8 * i; const float gg = gk ? gk[k0 + kk] : 1.f;
; #pragma unroll
;         for (int e2 = 0; e2 < 4; ++e2) scr[kk * 33 + 4 * nq + e2] = wv[i][e2] * gg; }
;     asm volatile("s_waitcnt lgkmcnt(0)" ::: "memory");
;     const int c = lane & 7;
; #pragma unroll
;     for (int j = 0; j < 4; ++j) { const int nl = (lane >> 3) + 8 * j, n = n0 + nl; const LAS float* s = scr + (8 * c) * 33 + nl;
;         if (n < N) { int nd = n; if (fox) { if (n >= 4620) nd = n - 12; else if (n >= 4608) nd = n - 4608 + 7168; }
;             u32x4 o; o.x = pk2(s[0 * 33], s[1 * 33]); o.y = pk2(s[2 * 33], s[3 * 33]); o.z = pk2(s[4 * 33], s[5 * 33]); o.w = pk2(s[6 * 33], s[7 * 33]);
;             *(u32x4*)(WT + (size_t)nd * DM + k0 + 8 * c) = o; } }
;     asm volatile("s_waitcnt lgkmcnt(0)" ::: "memory");
; __global__ void __launch_bounds__(512) mk_fwd(Params P) {
;     ...
;                 { const int L = r / IK; tr_item(P.w_mem_kv + (size_t)L * DM * 1024, 1024, WKV + (size_t)L * 1024 * DM, r - L * IK, lane, scr, 0, nullptr); }
.LBB0_646:
	s_add_i32 s13, s7, 0x8420
	s_cmpk_gt_i32 s13, 0x15ff
	s_mov_b64 s[0:1], -1
	s_cbranch_scc0 .LBB0_736
	s_cmpk_gt_u32 s13, 0x321f
	s_cbranch_scc0 .LBB0_709
	s_cmpk_gt_u32 s13, 0x4e1f
	s_cbranch_scc0 .LBB0_682
	s_cmpk_gt_u32 s13, 0x641f
	s_cbranch_scc0 .LBB0_655
	s_cmpk_gt_u32 s13, 0x841f
	s_cbranch_scc0 .LBB0_652
	v_readlane_b32 s0, v252, 33
	v_readlane_b32 s1, v252, 34
	s_mov_b32 s15, s1
	s_lshr_b32 s14, s7, 10
	s_lshl_b64 s[0:1], s[14:15], 23
	s_add_u32 s4, s46, s0
	s_addc_u32 s5, s47, s1
	s_mov_b32 s1, s15
	v_writelane_b32 v252, s0, 33
	v_add_u32_e32 v46, v50, v51
	v_add_u32_e32 v47, 0x420, v46
	v_writelane_b32 v252, s1, 34
	s_lshl_b64 s[0:1], s[14:15], 22
	v_readlane_b32 s14, v250, 3
	v_readlane_b32 s15, v250, 4
	s_add_u32 s14, s14, s0
	s_addc_u32 s1, s15, s1
	s_and_b32 s0, s9, 0x3e0
	s_and_b32 s15, s8, 0x7c0
	v_or_b32_e32 v0, s0, v37
	v_or_b32_e32 v4, s15, v34
	v_lshlrev_b32_e32 v0, 2, v0
	v_lshl_add_u64 v[2:3], s[4:5], 0, v[0:1]
	v_lshlrev_b32_e32 v0, 12, v4
	v_lshl_add_u64 v[30:31], v[2:3], 0, v[0:1]
	s_mov_b32 s4, 0x8000
	v_add_co_u32_e32 v6, vcc, s4, v30
	s_mov_b32 s4, 0x10000
	s_nop 0
	v_addc_co_u32_e32 v7, vcc, 0, v31, vcc
	v_add_co_u32_e32 v10, vcc, s4, v30
	s_mov_b32 s4, 0x18000
	s_nop 0
	v_addc_co_u32_e32 v11, vcc, 0, v31, vcc
	v_add_co_u32_e32 v14, vcc, s4, v30
	s_mov_b32 s4, 0x20000
	s_nop 0
	v_addc_co_u32_e32 v15, vcc, 0, v31, vcc
	v_add_co_u32_e32 v18, vcc, s4, v30
	s_mov_b32 s4, 0x28000
	s_nop 0
	v_addc_co_u32_e32 v19, vcc, 0, v31, vcc
	v_add_co_u32_e32 v22, vcc, s4, v30
	global_load_dwordx4 v[2:5], v[30:31], off
	s_nop 0
	global_load_dwordx4 v[6:9], v[6:7], off
	v_addc_co_u32_e32 v23, vcc, 0, v31, vcc
	global_load_dwordx4 v[10:13], v[10:11], off
	s_nop 0
	global_load_dwordx4 v[14:17], v[14:15], off
	s_nop 0
	global_load_dwordx4 v[18:21], v[18:19], off
	s_nop 0
	global_load_dwordx4 v[22:25], v[22:23], off
	s_mov_b32 s4, 0x30000
	v_add_co_u32_e32 v26, vcc, s4, v30
	s_mov_b32 s4, 0x38000
	s_nop 0
	v_addc_co_u32_e32 v27, vcc, 0, v31, vcc
	global_load_dwordx4 v[26:29], v[26:27], off
	v_add_co_u32_e32 v30, vcc, s4, v30
	v_add_u32_e32 v48, 0x428, v46
	s_nop 0
	v_addc_co_u32_e32 v31, vcc, 0, v31, vcc
	global_load_dwordx4 v[30:33], v[30:31], off
	v_add_u32_e32 v49, 0x840, v46
	v_add_u32_e32 v84, 0x848, v46
	v_add_u32_e32 v85, 0xc60, v46
	v_add_u32_e32 v86, 0xc68, v46
	v_add_u32_e32 v87, 0x1080, v46
	v_add_u32_e32 v88, 0x1088, v46
	v_add_u32_e32 v89, 0x14a0, v46
	v_add_u32_e32 v90, 0x14a8, v46
	v_add_u32_e32 v91, 0x18c0, v46
	v_add_u32_e32 v92, 0x18c8, v46
	v_add_u32_e32 v93, 0x1ce0, v46
	v_add_u32_e32 v94, 0x1ce8, v46
	s_lshl_b32 s4, s15, 1
	s_add_u32 s4, s14, s4
	v_or_b32_e32 v95, s0, v34
	s_addc_u32 s5, s1, 0
	v_lshlrev_b32_e32 v0, 1, v36
	s_waitcnt vmcnt(0)
	ds_write2_b32 v46, v2, v3 offset1:1
	ds_write2_b32 v46, v4, v5 offset0:2 offset1:3
	ds_write2_b32 v47, v6, v7 offset1:1
	ds_write2_b32 v48, v8, v9 offset1:1
	ds_write2_b32 v49, v10, v11 offset1:1
	ds_write2_b32 v84, v12, v13 offset1:1
	ds_write2_b32 v85, v14, v15 offset1:1
	ds_write2_b32 v86, v16, v17 offset1:1
	ds_write2_b32 v87, v18, v19 offset1:1
	ds_write2_b32 v88, v20, v21 offset1:1
	ds_write2_b32 v89, v22, v23 offset1:1
	ds_write2_b32 v90, v24, v25 offset1:1
	ds_write2_b32 v91, v26, v27 offset1:1
	ds_write2_b32 v92, v28, v29 offset1:1
	ds_write2_b32 v93, v30, v31 offset1:1
	ds_write2_b32 v94, v32, v33 offset1:1
	s_waitcnt lgkmcnt(0)
	ds_read_b32 v2, v55
	ds_read_b32 v3, v55 offset:132
	ds_read_b32 v4, v55 offset:264
	ds_read_b32 v5, v55 offset:396
	ds_read_b32 v8, v55 offset:528
	ds_read_b32 v9, v55 offset:660
	ds_read_b32 v10, v55 offset:792
	ds_read_b32 v11, v55 offset:924
	v_lshl_add_u64 v[6:7], s[4:5], 0, v[0:1]
	v_lshlrev_b32_e32 v0, 12, v95
	s_waitcnt lgkmcnt(0)
	v_cvt_pk_bf16_f32 v2, v2, v3
	s_waitcnt lgkmcnt(4)
	v_cvt_pk_bf16_f32 v3, v4, v5
	s_waitcnt lgkmcnt(2)
	v_cvt_pk_bf16_f32 v4, v8, v9
	s_waitcnt lgkmcnt(0)
	v_cvt_pk_bf16_f32 v5, v10, v11
	v_lshl_add_u64 v[8:9], v[6:7], 0, v[0:1]
	global_store_dwordx4 v[8:9], v[2:5], off
	ds_read_b32 v0, v55 offset:32
	ds_read_b32 v2, v55 offset:164
	ds_read_b32 v3, v55 offset:296
	ds_read_b32 v4, v55 offset:428
	ds_read_b32 v5, v55 offset:560
	ds_read_b32 v8, v55 offset:692
	ds_read_b32 v9, v55 offset:824
	ds_read_b32 v10, v55 offset:956
	v_or_b32_e32 v11, s0, v52
	s_waitcnt lgkmcnt(0)
	v_cvt_pk_bf16_f32 v2, v0, v2
	v_lshlrev_b32_e32 v0, 12, v11
	v_cvt_pk_bf16_f32 v3, v3, v4
	v_cvt_pk_bf16_f32 v4, v5, v8
	v_cvt_pk_bf16_f32 v5, v9, v10
	v_lshl_add_u64 v[8:9], v[6:7], 0, v[0:1]
	global_store_dwordx4 v[8:9], v[2:5], off
	ds_read_b32 v0, v55 offset:64
	ds_read_b32 v2, v55 offset:196
	ds_read_b32 v3, v55 offset:328
	ds_read_b32 v4, v55 offset:460
	ds_read_b32 v5, v55 offset:592
	ds_read_b32 v8, v55 offset:724
	ds_read_b32 v9, v55 offset:856
	ds_read_b32 v10, v55 offset:988
	v_or_b32_e32 v11, s0, v53
	s_waitcnt lgkmcnt(0)
	v_cvt_pk_bf16_f32 v2, v0, v2
	v_lshlrev_b32_e32 v0, 12, v11
	v_cvt_pk_bf16_f32 v3, v3, v4
	v_cvt_pk_bf16_f32 v4, v5, v8
	v_cvt_pk_bf16_f32 v5, v9, v10
	v_lshl_add_u64 v[8:9], v[6:7], 0, v[0:1]
	global_store_dwordx4 v[8:9], v[2:5], off
	ds_read_b32 v0, v55 offset:96
	ds_read_b32 v2, v55 offset:228
	ds_read_b32 v3, v55 offset:360
	ds_read_b32 v4, v55 offset:492
	ds_read_b32 v5, v55 offset:624
	ds_read_b32 v8, v55 offset:756
	ds_read_b32 v9, v55 offset:888
	ds_read_b32 v10, v55 offset:1020
	v_or_b32_e32 v11, s0, v54
	s_waitcnt lgkmcnt(0)
	v_cvt_pk_bf16_f32 v2, v0, v2
	v_lshlrev_b32_e32 v0, 12, v11
	v_cvt_pk_bf16_f32 v3, v3, v4
	v_cvt_pk_bf16_f32 v4, v5, v8
	v_cvt_pk_bf16_f32 v5, v9, v10
	v_lshl_add_u64 v[6:7], v[6:7], 0, v[0:1]
	global_store_dwordx4 v[6:7], v[2:5], off
	s_waitcnt lgkmcnt(0)
	s_mov_b64 s[0:1], 0
; #define LAS __attribute__((address_space(3)))
; __device__ __forceinline__ unsigned pk2(float lo, float hi) { const f32x2v v = {lo, hi}; return __builtin_bit_cast(unsigned, __builtin_convertvector(v, bf16x2v)); }
; __device__ __forceinline__ void tr_item(const float* W, int N, bf16_t* WT, int item, int lane, LAS float* scr, int fox, const float* gk) {
;     const int nblk = (N + 31) >> 5, kb = item / nblk, nb = item - kb * nblk, k0 = 64 * kb, n0 = 32 * nb;
;     const int nq = lane & 7, kr = lane >> 3, nc = n0 + 4 * nq;
;     f32x4 wv[8];
; #pragma unroll
;     for (int i = 0; i < 8; ++i) wv[i] = (nc < N) ? *(const f32x4*)(W + (size_t)(k0 + kr + 8 * i) * N + nc) : (f32x4){0.f, 0.f, 0.f, 0.f};
; #pragma unroll
;     for (int i = 0; i < 8; ++i) { const int kk = kr + 8 * i; const float gg = gk ? gk[k0 + kk] : 1.f;
; #pragma unroll
;         for (int e2 = 0; e2 < 4; ++e2) scr[kk * 33 + 4 * nq + e2] = wv[i][e2] * gg; }
;     asm volatile("s_waitcnt lgkmcnt(0)" ::: "memory");
;     const int c = lane & 7;
; #pragma unroll
;     for (int j = 0; j < 4; ++j) { const int nl = (lane >> 3) + 8 * j, n = n0 + nl; const LAS float* s = scr + (8 * c) * 33 + nl;
;         if (n < N) { int nd = n; if (fox) { if (n >= 4620) nd = n - 12; else if (n >= 4608) nd = n - 4608 + 7168; }
;             u32x4 o; o.x = pk2(s[0 * 33], s[1 * 33]); o.y = pk2(s[2 * 33], s[3 * 33]); o.z = pk2(s[4 * 33], s[5 * 33]); o.w = pk2(s[6 * 33], s[7 * 33]);
;             *(u32x4*)(WT + (size_t)nd * DM + k0 + 8 * c) = o; } }
;     asm volatile("s_waitcnt lgkmcnt(0)" ::: "memory");
; __global__ void __launch_bounds__(512) mk_fwd(Params P) {
;     ...
;                 if (r < 4 * IO) { const int L = r / IO; tr_item(P.w_out + (size_t)L * DM * DM, DM, WOUT + (size_t)L * DM * DM, r - L * IO, lane, scr, 0, nullptr); continue; } r -= 4 * IO;
.LBB0_652:
	s_andn2_b64 vcc, exec, s[0:1]
	s_cbranch_vccnz .LBB0_654
	v_readlane_b32 s0, v252, 33
	s_add_i32 s14, s7, 0x2000
	v_readlane_b32 s1, v252, 34
	s_mov_b32 s17, s1
	s_and_b32 s16, s14, 0xfffff800
	s_lshl_b64 s[0:1], s[16:17], 13
	v_readlane_b32 s72, v251, 22
	v_readlane_b32 s73, v251, 23
	s_add_u32 s4, s72, s0
	s_addc_u32 s5, s73, s1
	s_mov_b32 s1, s17
	v_writelane_b32 v252, s0, 33
	v_readlane_b32 s15, v250, 1
	v_add_u32_e32 v46, v50, v51
	v_writelane_b32 v252, s1, 34
	s_lshl_b64 s[0:1], s[16:17], 12
	s_add_u32 s15, s15, s0
	v_readlane_b32 s0, v250, 2
	s_addc_u32 s1, s0, s1
	s_add_i32 s0, s9, 0xfff37c00
	s_and_b32 s0, s0, 0x7e0
	s_and_b32 s14, s14, 0x7c0
	v_or_b32_e32 v0, s0, v37
	v_or_b32_e32 v4, s14, v34
	v_lshlrev_b32_e32 v0, 2, v0
	v_lshl_add_u64 v[2:3], s[4:5], 0, v[0:1]
	v_lshlrev_b32_e32 v0, 13, v4
	v_lshl_add_u64 v[30:31], v[2:3], 0, v[0:1]
	s_mov_b32 s4, 0x10000
	v_add_co_u32_e32 v6, vcc, s4, v30
	s_mov_b32 s4, 0x20000
	s_nop 0
	v_addc_co_u32_e32 v7, vcc, 0, v31, vcc
	v_add_co_u32_e32 v10, vcc, s4, v30
	s_mov_b32 s4, 0x30000
	s_nop 0
	v_addc_co_u32_e32 v11, vcc, 0, v31, vcc
	v_add_co_u32_e32 v14, vcc, s4, v30
	s_mov_b32 s4, 0x40000
	s_nop 0
	v_addc_co_u32_e32 v15, vcc, 0, v31, vcc
	v_add_co_u32_e32 v18, vcc, s4, v30
	s_mov_b32 s4, 0x50000
	s_nop 0
	v_addc_co_u32_e32 v19, vcc, 0, v31, vcc
	v_add_co_u32_e32 v22, vcc, s4, v30
	global_load_dwordx4 v[2:5], v[30:31], off
	s_nop 0
	global_load_dwordx4 v[6:9], v[6:7], off
	v_addc_co_u32_e32 v23, vcc, 0, v31, vcc
	global_load_dwordx4 v[10:13], v[10:11], off
	s_nop 0
	global_load_dwordx4 v[14:17], v[14:15], off
	s_nop 0
	global_load_dwordx4 v[18:21], v[18:19], off
	s_nop 0
	global_load_dwordx4 v[22:25], v[22:23], off
	s_mov_b32 s4, 0x60000
	v_add_co_u32_e32 v26, vcc, s4, v30
	s_mov_b32 s4, 0x70000
	s_nop 0
	v_addc_co_u32_e32 v27, vcc, 0, v31, vcc
	global_load_dwordx4 v[26:29], v[26:27], off
	v_add_co_u32_e32 v30, vcc, s4, v30
	v_add_u32_e32 v47, 0x420, v46
	s_nop 0
	v_addc_co_u32_e32 v31, vcc, 0, v31, vcc
	global_load_dwordx4 v[30:33], v[30:31], off
	v_add_u32_e32 v48, 0x428, v46
	v_add_u32_e32 v49, 0x840, v46
	v_add_u32_e32 v84, 0x848, v46
	v_add_u32_e32 v85, 0xc60, v46
	v_add_u32_e32 v86, 0xc68, v46
	v_add_u32_e32 v87, 0x1080, v46
	v_add_u32_e32 v88, 0x1088, v46
	v_add_u32_e32 v89, 0x14a0, v46
	v_add_u32_e32 v90, 0x14a8, v46
	v_add_u32_e32 v91, 0x18c0, v46
	v_add_u32_e32 v92, 0x18c8, v46
	v_add_u32_e32 v93, 0x1ce0, v46
	v_add_u32_e32 v94, 0x1ce8, v46
	s_lshl_b32 s4, s14, 1
	s_add_u32 s4, s15, s4
	v_or_b32_e32 v95, s0, v34
	s_addc_u32 s5, s1, 0
	v_lshlrev_b32_e32 v0, 1, v36
	v_readlane_b32 s74, v251, 24
	v_readlane_b32 s75, v251, 25
	v_readlane_b32 s76, v251, 26
	v_readlane_b32 s77, v251, 27
	v_readlane_b32 s78, v251, 28
	v_readlane_b32 s79, v251, 29
	v_readlane_b32 s80, v251, 30
	v_readlane_b32 s81, v251, 31
	v_readlane_b32 s82, v251, 32
	v_readlane_b32 s83, v251, 33
	v_readlane_b32 s84, v251, 34
	v_readlane_b32 s85, v251, 35
	v_readlane_b32 s86, v251, 36
	v_readlane_b32 s87, v251, 37
	s_waitcnt vmcnt(0)
	ds_write2_b32 v46, v2, v3 offset1:1
	ds_write2_b32 v46, v4, v5 offset0:2 offset1:3
	ds_write2_b32 v47, v6, v7 offset1:1
	ds_write2_b32 v48, v8, v9 offset1:1
	ds_write2_b32 v49, v10, v11 offset1:1
	ds_write2_b32 v84, v12, v13 offset1:1
	ds_write2_b32 v85, v14, v15 offset1:1
	ds_write2_b32 v86, v16, v17 offset1:1
	ds_write2_b32 v87, v18, v19 offset1:1
	ds_write2_b32 v88, v20, v21 offset1:1
	ds_write2_b32 v89, v22, v23 offset1:1
	ds_write2_b32 v90, v24, v25 offset1:1
	ds_write2_b32 v91, v26, v27 offset1:1
	ds_write2_b32 v92, v28, v29 offset1:1
	ds_write2_b32 v93, v30, v31 offset1:1
	ds_write2_b32 v94, v32, v33 offset1:1
	s_waitcnt lgkmcnt(0)
	ds_read_b32 v2, v55
	ds_read_b32 v3, v55 offset:132
	ds_read_b32 v4, v55 offset:264
	ds_read_b32 v5, v55 offset:396
	ds_read_b32 v8, v55 offset:528
	ds_read_b32 v9, v55 offset:660
	ds_read_b32 v10, v55 offset:792
	ds_read_b32 v11, v55 offset:924
	v_lshl_add_u64 v[6:7], s[4:5], 0, v[0:1]
	v_lshlrev_b32_e32 v0, 12, v95
	s_waitcnt lgkmcnt(0)
	v_cvt_pk_bf16_f32 v2, v2, v3
	v_cvt_pk_bf16_f32 v3, v4, v5
	v_cvt_pk_bf16_f32 v4, v8, v9
	v_cvt_pk_bf16_f32 v5, v10, v11
	v_lshl_add_u64 v[8:9], v[6:7], 0, v[0:1]
	global_store_dwordx4 v[8:9], v[2:5], off
	ds_read_b32 v0, v55 offset:32
	ds_read_b32 v2, v55 offset:164
	ds_read_b32 v3, v55 offset:296
	ds_read_b32 v4, v55 offset:428
	ds_read_b32 v5, v55 offset:560
	ds_read_b32 v8, v55 offset:692
	ds_read_b32 v9, v55 offset:824
	ds_read_b32 v10, v55 offset:956
	v_or_b32_e32 v11, s0, v52
	s_waitcnt lgkmcnt(0)
	v_cvt_pk_bf16_f32 v2, v0, v2
	v_lshlrev_b32_e32 v0, 12, v11
	v_cvt_pk_bf16_f32 v3, v3, v4
	v_cvt_pk_bf16_f32 v4, v5, v8
	v_cvt_pk_bf16_f32 v5, v9, v10
	v_lshl_add_u64 v[8:9], v[6:7], 0, v[0:1]
	global_store_dwordx4 v[8:9], v[2:5], off
	ds_read_b32 v0, v55 offset:64
	ds_read_b32 v2, v55 offset:196
	ds_read_b32 v3, v55 offset:328
	ds_read_b32 v4, v55 offset:460
	ds_read_b32 v5, v55 offset:592
	ds_read_b32 v8, v55 offset:724
	ds_read_b32 v9, v55 offset:856
	ds_read_b32 v10, v55 offset:988
	v_or_b32_e32 v11, s0, v53
	s_waitcnt lgkmcnt(0)
	v_cvt_pk_bf16_f32 v2, v0, v2
	v_lshlrev_b32_e32 v0, 12, v11
	v_cvt_pk_bf16_f32 v3, v3, v4
	v_cvt_pk_bf16_f32 v4, v5, v8
	v_cvt_pk_bf16_f32 v5, v9, v10
	v_lshl_add_u64 v[8:9], v[6:7], 0, v[0:1]
	global_store_dwordx4 v[8:9], v[2:5], off
	ds_read_b32 v0, v55 offset:96
	ds_read_b32 v2, v55 offset:228
	ds_read_b32 v3, v55 offset:360
	ds_read_b32 v4, v55 offset:492
	ds_read_b32 v5, v55 offset:624
	ds_read_b32 v8, v55 offset:756
	ds_read_b32 v9, v55 offset:888
	ds_read_b32 v10, v55 offset:1020
	v_or_b32_e32 v11, s0, v54
	s_waitcnt lgkmcnt(0)
	v_cvt_pk_bf16_f32 v2, v0, v2
	v_lshlrev_b32_e32 v0, 12, v11
	v_cvt_pk_bf16_f32 v3, v3, v4
	v_cvt_pk_bf16_f32 v4, v5, v8
	v_cvt_pk_bf16_f32 v5, v9, v10
	v_lshl_add_u64 v[6:7], v[6:7], 0, v[0:1]
	global_store_dwordx4 v[6:7], v[2:5], off
	s_waitcnt lgkmcnt(0)

; #define LAS __attribute__((address_space(3)))
; __device__ __forceinline__ unsigned pk2(float lo, float hi) { const f32x2v v = {lo, hi}; return __builtin_bit_cast(unsigned, __builtin_convertvector(v, bf16x2v)); }
; __device__ __forceinline__ void tr_item(const float* W, int N, bf16_t* WT, int item, int lane, LAS float* scr, int fox, const float* gk) {
;     ...
;     for (int i = 0; i < 8; ++i) { const int kk = kr + 8 * i; const float gg = gk ? gk[k0 + kk] : 1.f;
; #pragma unroll
;         for (int e2 = 0; e2 < 4; ++e2) scr[kk * 33 + 4 * nq + e2] = wv[i][e2] * gg; }
;     asm volatile("s_waitcnt lgkmcnt(0)" ::: "memory");
;     const int c = lane & 7;
; #pragma unroll
;     for (int j = 0; j < 4; ++j) { const int nl = (lane >> 3) + 8 * j, n = n0 + nl; const LAS float* s = scr + (8 * c) * 33 + nl;
;         if (n < N) { int nd = n; if (fox) { if (n >= 4620) nd = n - 12; else if (n >= 4608) nd = n - 4608 + 7168; }
;             u32x4 o; o.x = pk2(s[0 * 33], s[1 * 33]); o.y = pk2(s[2 * 33], s[3 * 33]); o.z = pk2(s[4 * 33], s[5 * 33]); o.w = pk2(s[6 * 33], s[7 * 33]);
;             *(u32x4*)(WT + (size_t)nd * DM + k0 + 8 * c) = o; } }
; __global__ void __launch_bounds__(512) mk_fwd(Params P) {
;     ...
;                 if (r < I0) { tr_item(P.a_w_in, NZ0, (bf16_t*)(ws + WS_WIN0), r, lane, scr, 0, P.norm_g); continue; } r -= I0;
.LBB0_672:
	s_or_b64 exec, exec, s[4:5]
	v_lshlrev_b32_e32 v0, 2, v48
	v_readlane_b32 s0, v252, 16
	v_or_b32_e32 v46, s15, v52
	v_or_b32_e32 v47, s15, v53
	v_or_b32_e32 v48, s15, v54
	v_readlane_b32 s1, v252, 17
	v_lshlrev_b32_e32 v46, 2, v46
	v_lshlrev_b32_e32 v47, 2, v47
	v_lshlrev_b32_e32 v49, 2, v48
	v_or_b32_e32 v48, s15, v56
	v_lshlrev_b32_e32 v85, 2, v48
	global_load_dword v0, v0, s[0:1]
	s_nop 0
	global_load_dword v46, v46, s[0:1]
	s_nop 0
	global_load_dword v48, v47, s[0:1]
	global_load_dword v84, v49, s[0:1]
	global_load_dword v86, v85, s[0:1]
	v_or_b32_e32 v47, s15, v58
	v_lshlrev_b32_e32 v47, 2, v47
	v_or_b32_e32 v49, s15, v59
	v_lshlrev_b32_e32 v49, 2, v49
	global_load_dword v88, v47, s[0:1]
	global_load_dword v90, v49, s[0:1]
	v_or_b32_e32 v47, s15, v60
	v_lshlrev_b32_e32 v47, 2, v47
	global_load_dword v92, v47, s[0:1]
	v_add_u32_e32 v47, v50, v51
	v_add_u32_e32 v49, v50, v57
	v_add_u32_e32 v85, 0x420, v47
	v_add_u32_e32 v87, 0x428, v47
	v_add_u32_e32 v89, 0x840, v47
	v_add_u32_e32 v91, 0x848, v47
	v_add_u32_e32 v93, 0xc60, v47
	v_add_u32_e32 v94, 0xc68, v47
	v_add_u32_e32 v95, 0x420, v49
	v_add_u32_e32 v96, 0x428, v49
	v_add_u32_e32 v97, 0x840, v49
	v_add_u32_e32 v98, 0x848, v49
	v_add_u32_e32 v99, 0xc60, v49
	v_add_u32_e32 v100, 0xc68, v49
	v_readlane_b32 s0, v252, 33
	v_readlane_b32 s1, v252, 34
	s_mov_b32 s5, s1
	s_lshl_b32 s4, s15, 1
	v_writelane_b32 v252, s0, 33
	s_waitcnt vmcnt(0)
	v_pk_mul_f32 v[10:11], v[10:11], v[84:85] op_sel_hi:[1,0]
	v_pk_mul_f32 v[2:3], v[2:3], v[0:1] op_sel_hi:[1,0]
	v_pk_mul_f32 v[4:5], v[4:5], v[0:1] op_sel_hi:[1,0]
	ds_write2_b32 v47, v2, v3 offset1:1
	ds_write2_b32 v47, v4, v5 offset0:2 offset1:3
	v_pk_mul_f32 v[2:3], v[6:7], v[46:47] op_sel_hi:[1,0]
	v_pk_mul_f32 v[4:5], v[8:9], v[46:47] op_sel_hi:[1,0]
	v_pk_mul_f32 v[6:7], v[14:15], v[48:49] op_sel_hi:[1,0]
	v_pk_mul_f32 v[8:9], v[16:17], v[48:49] op_sel_hi:[1,0]
	v_pk_mul_f32 v[12:13], v[12:13], v[84:85] op_sel_hi:[1,0]
	v_pk_mul_f32 v[14:15], v[22:23], v[86:87] op_sel_hi:[1,0]
	v_pk_mul_f32 v[16:17], v[24:25], v[86:87] op_sel_hi:[1,0]
	v_pk_mul_f32 v[18:19], v[18:19], v[88:89] op_sel_hi:[1,0]
	v_pk_mul_f32 v[20:21], v[20:21], v[88:89] op_sel_hi:[1,0]
	v_pk_mul_f32 v[22:23], v[30:31], v[90:91] op_sel_hi:[1,0]
	v_pk_mul_f32 v[24:25], v[32:33], v[90:91] op_sel_hi:[1,0]
	v_pk_mul_f32 v[26:27], v[26:27], v[92:93] op_sel_hi:[1,0]
	v_pk_mul_f32 v[28:29], v[28:29], v[92:93] op_sel_hi:[1,0]
	ds_write2_b32 v85, v2, v3 offset1:1
	ds_write2_b32 v87, v4, v5 offset1:1
	ds_write2_b32 v89, v6, v7 offset1:1
	ds_write2_b32 v91, v8, v9 offset1:1
	ds_write2_b32 v93, v10, v11 offset1:1
	ds_write2_b32 v94, v12, v13 offset1:1
	ds_write2_b32 v49, v14, v15 offset1:1
	ds_write2_b32 v49, v16, v17 offset0:2 offset1:3
	ds_write2_b32 v95, v18, v19 offset1:1
	ds_write2_b32 v96, v20, v21 offset1:1
	ds_write2_b32 v97, v22, v23 offset1:1
	ds_write2_b32 v98, v24, v25 offset1:1
	ds_write2_b32 v99, v26, v27 offset1:1
	ds_write2_b32 v100, v28, v29 offset1:1
	s_waitcnt lgkmcnt(0)
	v_add_u32_e32 v4, s14, v64
	v_lshl_add_u64 v[2:3], v[40:41], 0, s[4:5]
	v_cmp_gt_i32_e32 vcc, s23, v4
	v_writelane_b32 v252, s1, 34
	s_and_saveexec_b64 s[0:1], vcc
	s_cbranch_execz .LBB0_674
	ds_read2_b32 v[6:7], v55 offset1:33
	ds_read2_b32 v[8:9], v55 offset0:66 offset1:99
	ds_read2_b32 v[10:11], v55 offset0:132 offset1:165
	ds_read2_b32 v[12:13], v55 offset0:198 offset1:231
	v_ashrrev_i32_e32 v5, 31, v4
	v_lshlrev_b64 v[4:5], 12, v[4:5]
	s_waitcnt lgkmcnt(0)
	v_cvt_pk_bf16_f32 v6, v6, v7
	v_cvt_pk_bf16_f32 v7, v8, v9
	v_cvt_pk_bf16_f32 v8, v10, v11
	v_cvt_pk_bf16_f32 v9, v12, v13
	v_lshl_add_u64 v[4:5], v[2:3], 0, v[4:5]
	global_store_dwordx4 v[4:5], v[6:9], off
.LBB0_674:
	s_or_b64 exec, exec, s[0:1]
	v_add_u32_e32 v4, s14, v63
	v_cmp_gt_i32_e32 vcc, s23, v4
	s_and_saveexec_b64 s[0:1], vcc
	s_cbranch_execz .LBB0_676
	ds_read2_b32 v[6:7], v55 offset0:8 offset1:41
	ds_read2_b32 v[8:9], v55 offset0:74 offset1:107
	ds_read2_b32 v[10:11], v55 offset0:140 offset1:173
	ds_read2_b32 v[12:13], v55 offset0:206 offset1:239
	v_ashrrev_i32_e32 v5, 31, v4
	v_lshlrev_b64 v[4:5], 12, v[4:5]
	s_waitcnt lgkmcnt(0)
	v_cvt_pk_bf16_f32 v6, v6, v7
	v_cvt_pk_bf16_f32 v7, v8, v9
	v_cvt_pk_bf16_f32 v8, v10, v11
	v_cvt_pk_bf16_f32 v9, v12, v13
	v_lshl_add_u64 v[4:5], v[2:3], 0, v[4:5]
	global_store_dwordx4 v[4:5], v[6:9], off
.LBB0_676:
	s_or_b64 exec, exec, s[0:1]
	v_add_u32_e32 v4, s14, v62
	v_cmp_gt_i32_e32 vcc, s23, v4
	s_and_saveexec_b64 s[0:1], vcc
	s_cbranch_execz .LBB0_678
	ds_read2_b32 v[6:7], v55 offset0:16 offset1:49
	ds_read2_b32 v[8:9], v55 offset0:82 offset1:115
	ds_read2_b32 v[10:11], v55 offset0:148 offset1:181
	ds_read2_b32 v[12:13], v55 offset0:214 offset1:247
	v_ashrrev_i32_e32 v5, 31, v4
	v_lshlrev_b64 v[4:5], 12, v[4:5]
	s_waitcnt lgkmcnt(0)
	v_cvt_pk_bf16_f32 v6, v6, v7
	v_cvt_pk_bf16_f32 v7, v8, v9
	v_cvt_pk_bf16_f32 v8, v10, v11
	v_cvt_pk_bf16_f32 v9, v12, v13
	v_lshl_add_u64 v[4:5], v[2:3], 0, v[4:5]
	global_store_dwordx4 v[4:5], v[6:9], off
.LBB0_678:
	s_or_b64 exec, exec, s[0:1]
	v_add_u32_e32 v4, s14, v61
	v_cmp_gt_i32_e32 vcc, s23, v4
	s_and_saveexec_b64 s[0:1], vcc
	s_cbranch_execz .LBB0_680
	ds_read2_b32 v[6:7], v55 offset0:24 offset1:57
	ds_read2_b32 v[8:9], v55 offset0:90 offset1:123
	ds_read2_b32 v[10:11], v55 offset0:156 offset1:189
	ds_read2_b32 v[12:13], v55 offset0:222 offset1:255
	v_ashrrev_i32_e32 v5, 31, v4
	v_lshlrev_b64 v[4:5], 12, v[4:5]
	s_waitcnt lgkmcnt(0)
	v_cvt_pk_bf16_f32 v6, v6, v7
	v_cvt_pk_bf16_f32 v7, v8, v9
	v_cvt_pk_bf16_f32 v8, v10, v11
	v_cvt_pk_bf16_f32 v9, v12, v13
	v_lshl_add_u64 v[2:3], v[2:3], 0, v[4:5]
	global_store_dwordx4 v[2:3], v[6:9], off

; #define LAS __attribute__((address_space(3)))
; __device__ __forceinline__ unsigned pk2(float lo, float hi) { const f32x2v v = {lo, hi}; return __builtin_bit_cast(unsigned, __builtin_convertvector(v, bf16x2v)); }
; __device__ __forceinline__ void tr_item(const float* W, int N, bf16_t* WT, int item, int lane, LAS float* scr, int fox, const float* gk) {
;     ...
;     for (int i = 0; i < 8; ++i) { const int kk = kr + 8 * i; const float gg = gk ? gk[k0 + kk] : 1.f;
; #pragma unroll
;         for (int e2 = 0; e2 < 4; ++e2) scr[kk * 33 + 4 * nq + e2] = wv[i][e2] * gg; }
;     asm volatile("s_waitcnt lgkmcnt(0)" ::: "memory");
;     const int c = lane & 7;
; #pragma unroll
;     for (int j = 0; j < 4; ++j) { const int nl = (lane >> 3) + 8 * j, n = n0 + nl; const LAS float* s = scr + (8 * c) * 33 + nl;
;         if (n < N) { int nd = n; if (fox) { if (n >= 4620) nd = n - 12; else if (n >= 4608) nd = n - 4608 + 7168; }
;             u32x4 o; o.x = pk2(s[0 * 33], s[1 * 33]); o.y = pk2(s[2 * 33], s[3 * 33]); o.z = pk2(s[4 * 33], s[5 * 33]); o.w = pk2(s[6 * 33], s[7 * 33]);
;             *(u32x4*)(WT + (size_t)nd * DM + k0 + 8 * c) = o; } }
; __global__ void __launch_bounds__(512) mk_fwd(Params P) {
;     ...
;                 if (r < I2) { tr_item(P.c_w_in, NZ2, (bf16_t*)(ws + WS_WIN2), r, lane, scr, 0, P.norm_g + 2 * DM); continue; } r -= I2;
.LBB0_699:
	s_or_b64 exec, exec, s[4:5]
	v_lshlrev_b32_e32 v0, 2, v48
	v_readlane_b32 s0, v252, 18
	v_or_b32_e32 v46, s15, v52
	v_or_b32_e32 v47, s15, v53
	v_or_b32_e32 v48, s15, v54
	v_readlane_b32 s1, v252, 19
	v_lshlrev_b32_e32 v46, 2, v46
	v_lshlrev_b32_e32 v47, 2, v47
	v_lshlrev_b32_e32 v49, 2, v48
	v_or_b32_e32 v48, s15, v56
	v_lshlrev_b32_e32 v85, 2, v48
	global_load_dword v0, v0, s[0:1]
	s_nop 0
	global_load_dword v46, v46, s[0:1]
	s_nop 0
	global_load_dword v48, v47, s[0:1]
	global_load_dword v84, v49, s[0:1]
	global_load_dword v86, v85, s[0:1]
	v_or_b32_e32 v47, s15, v58
	v_lshlrev_b32_e32 v47, 2, v47
	v_or_b32_e32 v49, s15, v59
	v_lshlrev_b32_e32 v49, 2, v49
	global_load_dword v88, v47, s[0:1]
	global_load_dword v90, v49, s[0:1]
	v_or_b32_e32 v47, s15, v60
	v_lshlrev_b32_e32 v47, 2, v47
	global_load_dword v92, v47, s[0:1]
	v_add_u32_e32 v47, v50, v51
	v_add_u32_e32 v49, v50, v57
	v_add_u32_e32 v85, 0x420, v47
	v_add_u32_e32 v87, 0x428, v47
	v_add_u32_e32 v89, 0x840, v47
	v_add_u32_e32 v91, 0x848, v47
	v_add_u32_e32 v93, 0xc60, v47
	v_readlane_b32 s0, v252, 33
	v_add_u32_e32 v94, 0xc68, v47
	v_add_u32_e32 v95, 0x420, v49
	v_add_u32_e32 v96, 0x428, v49
	v_add_u32_e32 v97, 0x840, v49
	v_add_u32_e32 v98, 0x848, v49
	v_add_u32_e32 v99, 0xc60, v49
	v_add_u32_e32 v100, 0xc68, v49
	v_readlane_b32 s1, v252, 34
	s_mov_b32 s5, s1
	v_writelane_b32 v252, s0, 33
	s_lshl_b32 s4, s15, 1
	s_waitcnt vmcnt(0)
	v_pk_mul_f32 v[10:11], v[10:11], v[84:85] op_sel_hi:[1,0]
	v_pk_mul_f32 v[2:3], v[2:3], v[0:1] op_sel_hi:[1,0]
	v_pk_mul_f32 v[4:5], v[4:5], v[0:1] op_sel_hi:[1,0]
	ds_write2_b32 v47, v2, v3 offset1:1
	ds_write2_b32 v47, v4, v5 offset0:2 offset1:3
	v_pk_mul_f32 v[2:3], v[6:7], v[46:47] op_sel_hi:[1,0]
	v_pk_mul_f32 v[4:5], v[8:9], v[46:47] op_sel_hi:[1,0]
	v_pk_mul_f32 v[6:7], v[14:15], v[48:49] op_sel_hi:[1,0]
	v_pk_mul_f32 v[8:9], v[16:17], v[48:49] op_sel_hi:[1,0]
	v_pk_mul_f32 v[12:13], v[12:13], v[84:85] op_sel_hi:[1,0]
	v_pk_mul_f32 v[14:15], v[22:23], v[86:87] op_sel_hi:[1,0]
	v_pk_mul_f32 v[16:17], v[24:25], v[86:87] op_sel_hi:[1,0]
	v_pk_mul_f32 v[18:19], v[18:19], v[88:89] op_sel_hi:[1,0]
	v_pk_mul_f32 v[20:21], v[20:21], v[88:89] op_sel_hi:[1,0]
	v_pk_mul_f32 v[22:23], v[30:31], v[90:91] op_sel_hi:[1,0]
	v_pk_mul_f32 v[24:25], v[32:33], v[90:91] op_sel_hi:[1,0]
	v_pk_mul_f32 v[26:27], v[26:27], v[92:93] op_sel_hi:[1,0]
	v_pk_mul_f32 v[28:29], v[28:29], v[92:93] op_sel_hi:[1,0]
	ds_write2_b32 v85, v2, v3 offset1:1
	ds_write2_b32 v87, v4, v5 offset1:1
	ds_write2_b32 v89, v6, v7 offset1:1
	ds_write2_b32 v91, v8, v9 offset1:1
	ds_write2_b32 v93, v10, v11 offset1:1
	ds_write2_b32 v94, v12, v13 offset1:1
	ds_write2_b32 v49, v14, v15 offset1:1
	ds_write2_b32 v49, v16, v17 offset0:2 offset1:3
	ds_write2_b32 v95, v18, v19 offset1:1
	ds_write2_b32 v96, v20, v21 offset1:1
	ds_write2_b32 v97, v22, v23 offset1:1
	ds_write2_b32 v98, v24, v25 offset1:1
	ds_write2_b32 v99, v26, v27 offset1:1
	ds_write2_b32 v100, v28, v29 offset1:1
	s_waitcnt lgkmcnt(0)
	v_writelane_b32 v252, s1, 34
	v_add_u32_e32 v4, s14, v69
	s_movk_i32 s0, 0x1c00
	v_lshl_add_u64 v[2:3], v[42:43], 0, s[4:5]
	v_cmp_gt_i32_e32 vcc, s0, v4
	s_and_saveexec_b64 s[0:1], vcc
	s_cbranch_execz .LBB0_701
	ds_read2_b32 v[6:7], v55 offset1:33
	ds_read2_b32 v[8:9], v55 offset0:66 offset1:99
	ds_read2_b32 v[10:11], v55 offset0:132 offset1:165
	ds_read2_b32 v[12:13], v55 offset0:198 offset1:231
	v_ashrrev_i32_e32 v5, 31, v4
	v_lshlrev_b64 v[4:5], 12, v[4:5]
	s_waitcnt lgkmcnt(0)
	v_cvt_pk_bf16_f32 v6, v6, v7
	v_cvt_pk_bf16_f32 v7, v8, v9
	v_cvt_pk_bf16_f32 v8, v10, v11
	v_cvt_pk_bf16_f32 v9, v12, v13
	v_lshl_add_u64 v[4:5], v[2:3], 0, v[4:5]
	global_store_dwordx4 v[4:5], v[6:9], off
.LBB0_701:
	s_or_b64 exec, exec, s[0:1]
	v_add_u32_e32 v4, s14, v68
	s_movk_i32 s0, 0x1c00
	v_cmp_gt_i32_e32 vcc, s0, v4
	s_and_saveexec_b64 s[0:1], vcc
	s_cbranch_execz .LBB0_703
	ds_read2_b32 v[6:7], v55 offset0:8 offset1:41
	ds_read2_b32 v[8:9], v55 offset0:74 offset1:107
	ds_read2_b32 v[10:11], v55 offset0:140 offset1:173
	ds_read2_b32 v[12:13], v55 offset0:206 offset1:239
	v_ashrrev_i32_e32 v5, 31, v4
	v_lshlrev_b64 v[4:5], 12, v[4:5]
	s_waitcnt lgkmcnt(0)
	v_cvt_pk_bf16_f32 v6, v6, v7
	v_cvt_pk_bf16_f32 v7, v8, v9
	v_cvt_pk_bf16_f32 v8, v10, v11
	v_cvt_pk_bf16_f32 v9, v12, v13
	v_lshl_add_u64 v[4:5], v[2:3], 0, v[4:5]
	global_store_dwordx4 v[4:5], v[6:9], off
.LBB0_703:
	s_or_b64 exec, exec, s[0:1]
	v_add_u32_e32 v4, s14, v67
	s_movk_i32 s0, 0x1c00
	v_cmp_gt_i32_e32 vcc, s0, v4
	s_and_saveexec_b64 s[0:1], vcc
	s_cbranch_execz .LBB0_705
	ds_read2_b32 v[6:7], v55 offset0:16 offset1:49
	ds_read2_b32 v[8:9], v55 offset0:82 offset1:115
	ds_read2_b32 v[10:11], v55 offset0:148 offset1:181
	ds_read2_b32 v[12:13], v55 offset0:214 offset1:247
	v_ashrrev_i32_e32 v5, 31, v4
	v_lshlrev_b64 v[4:5], 12, v[4:5]
	s_waitcnt lgkmcnt(0)
	v_cvt_pk_bf16_f32 v6, v6, v7
	v_cvt_pk_bf16_f32 v7, v8, v9
	v_cvt_pk_bf16_f32 v8, v10, v11
	v_cvt_pk_bf16_f32 v9, v12, v13
	v_lshl_add_u64 v[4:5], v[2:3], 0, v[4:5]
	global_store_dwordx4 v[4:5], v[6:9], off
.LBB0_705:
	s_or_b64 exec, exec, s[0:1]
	v_add_u32_e32 v4, s14, v66
	s_movk_i32 s0, 0x1c00
	v_cmp_gt_i32_e32 vcc, s0, v4
	s_and_saveexec_b64 s[0:1], vcc
	s_cbranch_execz .LBB0_707
	ds_read2_b32 v[6:7], v55 offset0:24 offset1:57
	ds_read2_b32 v[8:9], v55 offset0:90 offset1:123
	ds_read2_b32 v[10:11], v55 offset0:156 offset1:189
	ds_read2_b32 v[12:13], v55 offset0:222 offset1:255
	v_ashrrev_i32_e32 v5, 31, v4
	v_lshlrev_b64 v[4:5], 12, v[4:5]
	s_waitcnt lgkmcnt(0)
	v_cvt_pk_bf16_f32 v6, v6, v7
	v_cvt_pk_bf16_f32 v7, v8, v9
	v_cvt_pk_bf16_f32 v8, v10, v11
	v_cvt_pk_bf16_f32 v9, v12, v13
	v_lshl_add_u64 v[2:3], v[2:3], 0, v[4:5]
	global_store_dwordx4 v[2:3], v[6:9], off

; #define LAS __attribute__((address_space(3)))
; __device__ __forceinline__ unsigned pk2(float lo, float hi) { const f32x2v v = {lo, hi}; return __builtin_bit_cast(unsigned, __builtin_convertvector(v, bf16x2v)); }
; __device__ __forceinline__ void tr_item(const float* W, int N, bf16_t* WT, int item, int lane, LAS float* scr, int fox, const float* gk) {
;     ...
;     for (int i = 0; i < 8; ++i) { const int kk = kr + 8 * i; const float gg = gk ? gk[k0 + kk] : 1.f;
; #pragma unroll
;         for (int e2 = 0; e2 < 4; ++e2) scr[kk * 33 + 4 * nq + e2] = wv[i][e2] * gg; }
;     asm volatile("s_waitcnt lgkmcnt(0)" ::: "memory");
;     const int c = lane & 7;
; #pragma unroll
;     for (int j = 0; j < 4; ++j) { const int nl = (lane >> 3) + 8 * j, n = n0 + nl; const LAS float* s = scr + (8 * c) * 33 + nl;
;         if (n < N) { int nd = n; if (fox) { if (n >= 4620) nd = n - 12; else if (n >= 4608) nd = n - 4608 + 7168; }
;             u32x4 o; o.x = pk2(s[0 * 33], s[1 * 33]); o.y = pk2(s[2 * 33], s[3 * 33]); o.z = pk2(s[4 * 33], s[5 * 33]); o.w = pk2(s[6 * 33], s[7 * 33]);
;             *(u32x4*)(WT + (size_t)nd * DM + k0 + 8 * c) = o; } }
; __global__ void __launch_bounds__(512) mk_fwd(Params P) {
;     ...
;                 if (r < I1) { tr_item(P.b_w_in, NSRC1, (bf16_t*)(ws + WS_WIN1), r, lane, scr, 1, P.norm_g + DM); continue; } r -= I1;
.LBB0_726:
	s_or_b64 exec, exec, s[4:5]
	v_lshlrev_b32_e32 v0, 2, v48
	v_readlane_b32 s0, v252, 20
	v_or_b32_e32 v46, s15, v52
	v_or_b32_e32 v47, s15, v53
	v_or_b32_e32 v48, s15, v54
	v_readlane_b32 s1, v252, 21
	v_lshlrev_b32_e32 v46, 2, v46
	v_lshlrev_b32_e32 v47, 2, v47
	v_lshlrev_b32_e32 v49, 2, v48
	v_or_b32_e32 v48, s15, v56
	v_lshlrev_b32_e32 v85, 2, v48
	global_load_dword v0, v0, s[0:1]
	s_nop 0
	global_load_dword v46, v46, s[0:1]
	s_nop 0
	global_load_dword v48, v47, s[0:1]
	global_load_dword v84, v49, s[0:1]
	global_load_dword v86, v85, s[0:1]
	v_or_b32_e32 v47, s15, v58
	v_lshlrev_b32_e32 v47, 2, v47
	v_or_b32_e32 v49, s15, v59
	v_lshlrev_b32_e32 v49, 2, v49
	global_load_dword v88, v47, s[0:1]
	global_load_dword v90, v49, s[0:1]
	v_or_b32_e32 v47, s15, v60
	v_lshlrev_b32_e32 v47, 2, v47
	global_load_dword v92, v47, s[0:1]
	v_add_u32_e32 v47, v50, v51
	v_add_u32_e32 v49, v50, v57
	v_add_u32_e32 v85, 0x420, v47
	v_add_u32_e32 v87, 0x428, v47
	v_add_u32_e32 v89, 0x840, v47
	v_add_u32_e32 v91, 0x848, v47
	v_add_u32_e32 v93, 0xc60, v47
	v_readlane_b32 s0, v252, 33
	v_add_u32_e32 v94, 0xc68, v47
	v_add_u32_e32 v95, 0x420, v49
	v_add_u32_e32 v96, 0x428, v49
	v_add_u32_e32 v97, 0x840, v49
	v_add_u32_e32 v98, 0x848, v49
	v_add_u32_e32 v99, 0xc60, v49
	v_add_u32_e32 v100, 0xc68, v49
	v_readlane_b32 s1, v252, 34
	s_mov_b32 s5, s1
	v_writelane_b32 v252, s0, 33
	s_lshl_b32 s4, s15, 1
	s_waitcnt vmcnt(0)
	v_pk_mul_f32 v[2:3], v[2:3], v[46:47] op_sel_hi:[1,0]
	v_pk_mul_f32 v[4:5], v[4:5], v[46:47] op_sel_hi:[1,0]
	v_pk_mul_f32 v[6:7], v[6:7], v[0:1] op_sel_hi:[1,0]
	v_pk_mul_f32 v[8:9], v[8:9], v[0:1] op_sel_hi:[1,0]
	ds_write2_b32 v47, v6, v7 offset1:1
	ds_write2_b32 v47, v8, v9 offset0:2 offset1:3
	v_pk_mul_f32 v[6:7], v[14:15], v[48:49] op_sel_hi:[1,0]
	v_pk_mul_f32 v[8:9], v[16:17], v[48:49] op_sel_hi:[1,0]
	v_pk_mul_f32 v[10:11], v[10:11], v[84:85] op_sel_hi:[1,0]
	v_pk_mul_f32 v[12:13], v[12:13], v[84:85] op_sel_hi:[1,0]
	v_pk_mul_f32 v[14:15], v[22:23], v[86:87] op_sel_hi:[1,0]
	v_pk_mul_f32 v[16:17], v[24:25], v[86:87] op_sel_hi:[1,0]
	v_pk_mul_f32 v[18:19], v[18:19], v[88:89] op_sel_hi:[1,0]
	v_pk_mul_f32 v[20:21], v[20:21], v[88:89] op_sel_hi:[1,0]
	v_pk_mul_f32 v[22:23], v[30:31], v[90:91] op_sel_hi:[1,0]
	v_pk_mul_f32 v[24:25], v[32:33], v[90:91] op_sel_hi:[1,0]
	v_pk_mul_f32 v[26:27], v[26:27], v[92:93] op_sel_hi:[1,0]
	v_pk_mul_f32 v[28:29], v[28:29], v[92:93] op_sel_hi:[1,0]
	ds_write2_b32 v85, v2, v3 offset1:1
	ds_write2_b32 v87, v4, v5 offset1:1
	ds_write2_b32 v89, v6, v7 offset1:1
	ds_write2_b32 v91, v8, v9 offset1:1
	ds_write2_b32 v93, v10, v11 offset1:1
	ds_write2_b32 v94, v12, v13 offset1:1
	ds_write2_b32 v49, v14, v15 offset1:1
	ds_write2_b32 v49, v16, v17 offset0:2 offset1:3
	ds_write2_b32 v95, v18, v19 offset1:1
	ds_write2_b32 v96, v20, v21 offset1:1
	ds_write2_b32 v97, v22, v23 offset1:1
	ds_write2_b32 v98, v24, v25 offset1:1
	ds_write2_b32 v99, v26, v27 offset1:1
	ds_write2_b32 v100, v28, v29 offset1:1
	s_waitcnt lgkmcnt(0)
	v_writelane_b32 v252, s1, 34
	v_add_u32_e32 v0, s14, v80
	s_movk_i32 s0, 0x1c0c
	v_lshl_add_u64 v[2:3], v[44:45], 0, s[4:5]
	v_cmp_gt_i32_e32 vcc, s0, v0
	s_and_saveexec_b64 s[0:1], vcc
	s_cbranch_execz .LBB0_728
	s_movk_i32 s4, 0x11ff
	v_add_u32_e32 v4, s14, v82
	v_cmp_lt_i32_e32 vcc, s4, v0
	s_movk_i32 s4, 0x120b
	v_add_u32_e32 v12, s14, v81
	v_cndmask_b32_e32 v13, v0, v4, vcc
	ds_read2_b32 v[4:5], v55 offset1:33
	ds_read2_b32 v[6:7], v55 offset0:66 offset1:99
	ds_read2_b32 v[8:9], v55 offset0:132 offset1:165
	ds_read2_b32 v[10:11], v55 offset0:198 offset1:231
	v_cmp_lt_i32_e32 vcc, s4, v0
	s_waitcnt lgkmcnt(0)
	v_cvt_pk_bf16_f32 v4, v4, v5
	v_cvt_pk_bf16_f32 v5, v6, v7
	v_cndmask_b32_e32 v12, v13, v12, vcc
	v_ashrrev_i32_e32 v13, 31, v12
	v_cvt_pk_bf16_f32 v6, v8, v9
	v_lshlrev_b64 v[8:9], 12, v[12:13]
	v_cvt_pk_bf16_f32 v7, v10, v11
	v_lshl_add_u64 v[8:9], v[2:3], 0, v[8:9]
	global_store_dwordx4 v[8:9], v[4:7], off
.LBB0_728:
	s_or_b64 exec, exec, s[0:1]
	v_add_u32_e32 v0, s14, v77
	s_movk_i32 s0, 0x1c0c
	v_cmp_gt_i32_e32 vcc, s0, v0
	s_and_saveexec_b64 s[0:1], vcc
	s_cbranch_execz .LBB0_730
	s_movk_i32 s4, 0x11ff
	v_add_u32_e32 v4, s14, v79
	v_cmp_lt_i32_e32 vcc, s4, v0
	s_movk_i32 s4, 0x120b
	v_add_u32_e32 v12, s14, v78
	v_cndmask_b32_e32 v13, v0, v4, vcc
	ds_read2_b32 v[4:5], v55 offset0:8 offset1:41
	ds_read2_b32 v[6:7], v55 offset0:74 offset1:107
	ds_read2_b32 v[8:9], v55 offset0:140 offset1:173
	ds_read2_b32 v[10:11], v55 offset0:206 offset1:239
	v_cmp_lt_i32_e32 vcc, s4, v0
	s_waitcnt lgkmcnt(0)
	v_cvt_pk_bf16_f32 v4, v4, v5
	v_cvt_pk_bf16_f32 v5, v6, v7
	v_cndmask_b32_e32 v12, v13, v12, vcc
	v_ashrrev_i32_e32 v13, 31, v12
	v_cvt_pk_bf16_f32 v6, v8, v9
	v_lshlrev_b64 v[8:9], 12, v[12:13]
	v_cvt_pk_bf16_f32 v7, v10, v11
	v_lshl_add_u64 v[8:9], v[2:3], 0, v[8:9]
	global_store_dwordx4 v[8:9], v[4:7], off
.LBB0_730:
	s_or_b64 exec, exec, s[0:1]
	v_add_u32_e32 v0, s14, v74
	s_movk_i32 s0, 0x1c0c
	v_cmp_gt_i32_e32 vcc, s0, v0
	s_and_saveexec_b64 s[0:1], vcc
	s_cbranch_execz .LBB0_732
	s_movk_i32 s4, 0x11ff
	v_add_u32_e32 v4, s14, v76
	v_cmp_lt_i32_e32 vcc, s4, v0
	s_movk_i32 s4, 0x120b
	v_add_u32_e32 v12, s14, v75
	v_cndmask_b32_e32 v13, v0, v4, vcc
	ds_read2_b32 v[4:5], v55 offset0:16 offset1:49
	ds_read2_b32 v[6:7], v55 offset0:82 offset1:115
	ds_read2_b32 v[8:9], v55 offset0:148 offset1:181
	ds_read2_b32 v[10:11], v55 offset0:214 offset1:247
	v_cmp_lt_i32_e32 vcc, s4, v0
	s_waitcnt lgkmcnt(0)
	v_cvt_pk_bf16_f32 v4, v4, v5
	v_cvt_pk_bf16_f32 v5, v6, v7
	v_cndmask_b32_e32 v12, v13, v12, vcc
	v_ashrrev_i32_e32 v13, 31, v12
	v_cvt_pk_bf16_f32 v6, v8, v9
	v_lshlrev_b64 v[8:9], 12, v[12:13]
	v_cvt_pk_bf16_f32 v7, v10, v11
	v_lshl_add_u64 v[8:9], v[2:3], 0, v[8:9]
	global_store_dwordx4 v[8:9], v[4:7], off
.LBB0_732:
	s_or_b64 exec, exec, s[0:1]
	v_add_u32_e32 v0, s14, v71
	s_movk_i32 s0, 0x1c0c
	v_cmp_gt_i32_e32 vcc, s0, v0
	s_and_saveexec_b64 s[0:1], vcc
	s_cbranch_execz .LBB0_734
	s_movk_i32 s4, 0x11ff
	v_add_u32_e32 v4, s14, v73
	v_cmp_lt_i32_e32 vcc, s4, v0
	s_movk_i32 s4, 0x120b
	v_add_u32_e32 v12, s14, v72
	v_cndmask_b32_e32 v13, v0, v4, vcc
	ds_read2_b32 v[4:5], v55 offset0:24 offset1:57
	ds_read2_b32 v[6:7], v55 offset0:90 offset1:123
	ds_read2_b32 v[8:9], v55 offset0:156 offset1:189
	ds_read2_b32 v[10:11], v55 offset0:222 offset1:255
	v_cmp_lt_i32_e32 vcc, s4, v0
	s_waitcnt lgkmcnt(0)
	v_cvt_pk_bf16_f32 v4, v4, v5
	v_cvt_pk_bf16_f32 v5, v6, v7
	v_cndmask_b32_e32 v12, v13, v12, vcc
	v_ashrrev_i32_e32 v13, 31, v12
	v_cvt_pk_bf16_f32 v6, v8, v9
	v_lshlrev_b64 v[8:9], 12, v[12:13]
	v_cvt_pk_bf16_f32 v7, v10, v11
	v_lshl_add_u64 v[2:3], v[2:3], 0, v[8:9]
	global_store_dwordx4 v[2:3], v[4:7], off

; #define LAS __attribute__((address_space(3)))
; __device__ __forceinline__ unsigned pk2(float lo, float hi) { const f32x2v v = {lo, hi}; return __builtin_bit_cast(unsigned, __builtin_convertvector(v, bf16x2v)); }
; __device__ __forceinline__ void tr_item(const float* W, int N, bf16_t* WT, int item, int lane, LAS float* scr, int fox, const float* gk) {
;     ...
;     for (int i = 0; i < 8; ++i) { const int kk = kr + 8 * i; const float gg = gk ? gk[k0 + kk] : 1.f;
; #pragma unroll
;         for (int e2 = 0; e2 < 4; ++e2) scr[kk * 33 + 4 * nq + e2] = wv[i][e2] * gg; }
;     asm volatile("s_waitcnt lgkmcnt(0)" ::: "memory");
;     const int c = lane & 7;
; #pragma unroll
;     for (int j = 0; j < 4; ++j) { const int nl = (lane >> 3) + 8 * j, n = n0 + nl; const LAS float* s = scr + (8 * c) * 33 + nl;
;         if (n < N) { int nd = n; if (fox) { if (n >= 4620) nd = n - 12; else if (n >= 4608) nd = n - 4608 + 7168; }
;             u32x4 o; o.x = pk2(s[0 * 33], s[1 * 33]); o.y = pk2(s[2 * 33], s[3 * 33]); o.z = pk2(s[4 * 33], s[5 * 33]); o.w = pk2(s[6 * 33], s[7 * 33]);
;             *(u32x4*)(WT + (size_t)nd * DM + k0 + 8 * c) = o; } }
.LBB0_764:
	v_add_u32_e32 v6, 0x840, v14
	ds_write2_b32 v6, v12, v13 offset1:1
	v_add_u32_e32 v6, 0x848, v14
	ds_write2_b32 v6, v10, v11 offset1:1
	v_pk_mul_f32 v[2:3], v[2:3], v[0:1] op_sel_hi:[1,0]
	v_add_u32_e32 v6, 0xc60, v14
	ds_write2_b32 v6, v2, v3 offset1:1
	v_pk_mul_f32 v[2:3], v[4:5], v[0:1] op_sel_hi:[1,0]
	v_add_u32_e32 v0, 0xc68, v14
	ds_write2_b32 v0, v2, v3 offset1:1
	s_waitcnt lgkmcnt(0)
	v_add_u32_e32 v4, s13, v34
	v_lshl_add_u64 v[2:3], s[4:5], 1, v[38:39]
	v_cmp_gt_i32_e32 vcc, s23, v4
	s_and_saveexec_b64 s[0:1], vcc
	s_cbranch_execz .LBB0_766
	ds_read2_b32 v[6:7], v55 offset1:33
	ds_read2_b32 v[8:9], v55 offset0:66 offset1:99
	ds_read2_b32 v[10:11], v55 offset0:132 offset1:165
	ds_read2_b32 v[12:13], v55 offset0:198 offset1:231
	v_ashrrev_i32_e32 v5, 31, v4
	s_waitcnt lgkmcnt(0)
	v_cvt_pk_bf16_f32 v6, v6, v7
	v_cvt_pk_bf16_f32 v7, v8, v9
	v_cvt_pk_bf16_f32 v8, v10, v11
	v_lshlrev_b64 v[10:11], 12, v[4:5]
	v_cvt_pk_bf16_f32 v9, v12, v13
	v_lshl_add_u64 v[10:11], v[2:3], 0, v[10:11]
	global_store_dwordx4 v[10:11], v[6:9], off
.LBB0_766:
	s_or_b64 exec, exec, s[0:1]
	s_nop 0
	v_add_u32_e32 v6, 8, v4
	v_cmp_gt_i32_e32 vcc, s23, v6
	s_and_saveexec_b64 s[0:1], vcc
	s_cbranch_execz .LBB0_768
	ds_read2_b32 v[8:9], v55 offset0:8 offset1:41
	ds_read2_b32 v[10:11], v55 offset0:74 offset1:107
	ds_read2_b32 v[12:13], v55 offset0:140 offset1:173
	ds_read2_b32 v[14:15], v55 offset0:206 offset1:239
	v_ashrrev_i32_e32 v7, 31, v6
	v_lshlrev_b64 v[6:7], 12, v[6:7]
	s_waitcnt lgkmcnt(0)
	v_cvt_pk_bf16_f32 v8, v8, v9
	v_cvt_pk_bf16_f32 v9, v10, v11
	v_cvt_pk_bf16_f32 v10, v12, v13
	v_cvt_pk_bf16_f32 v11, v14, v15
	v_lshl_add_u64 v[6:7], v[2:3], 0, v[6:7]
	global_store_dwordx4 v[6:7], v[8:11], off
.LBB0_768:
	s_or_b64 exec, exec, s[0:1]
	v_add_u32_e32 v6, 16, v4
	v_cmp_gt_i32_e32 vcc, s23, v6
	s_and_saveexec_b64 s[0:1], vcc
	s_cbranch_execz .LBB0_770
	ds_read2_b32 v[8:9], v55 offset0:16 offset1:49
	ds_read2_b32 v[10:11], v55 offset0:82 offset1:115
	ds_read2_b32 v[12:13], v55 offset0:148 offset1:181
	ds_read2_b32 v[14:15], v55 offset0:214 offset1:247
	v_ashrrev_i32_e32 v7, 31, v6
	v_lshlrev_b64 v[6:7], 12, v[6:7]
	s_waitcnt lgkmcnt(0)
	v_cvt_pk_bf16_f32 v8, v8, v9
	v_cvt_pk_bf16_f32 v9, v10, v11
	v_cvt_pk_bf16_f32 v10, v12, v13
	v_cvt_pk_bf16_f32 v11, v14, v15
	v_lshl_add_u64 v[6:7], v[2:3], 0, v[6:7]
	global_store_dwordx4 v[6:7], v[8:11], off
.LBB0_770:
	s_or_b64 exec, exec, s[0:1]
	v_add_u32_e32 v4, 24, v4
	v_cmp_gt_i32_e32 vcc, s23, v4
	s_and_saveexec_b64 s[0:1], vcc
	s_cbranch_execz .LBB0_644
	ds_read2_b32 v[6:7], v55 offset0:24 offset1:57
	ds_read2_b32 v[8:9], v55 offset0:90 offset1:123
	ds_read2_b32 v[10:11], v55 offset0:156 offset1:189
	ds_read2_b32 v[12:13], v55 offset0:222 offset1:255
	v_ashrrev_i32_e32 v5, 31, v4
	v_lshlrev_b64 v[4:5], 12, v[4:5]
	s_waitcnt lgkmcnt(0)
	v_cvt_pk_bf16_f32 v6, v6, v7
	v_cvt_pk_bf16_f32 v7, v8, v9
	v_cvt_pk_bf16_f32 v8, v10, v11
	v_cvt_pk_bf16_f32 v9, v12, v13
	v_lshl_add_u64 v[2:3], v[2:3], 0, v[4:5]
	global_store_dwordx4 v[2:3], v[6:9], off
	s_branch .LBB0_644

; __global__ void __launch_bounds__(512) mk_fwd(Params P) {
;     ...
;             { u32x4* zp = (u32x4*)((bf16_t*)(ws + WS_WIN1) + (size_t)NSRC1 * DM); const int nz = (NZ1 - NSRC1) * DM / 8;
;               for (int i = blockIdx.x * 512 + tid; i < nz; i += G * 512) zp[i] = (u32x4){0u, 0u, 0u, 0u}; }
.LBB0_775:
	v_add_u32_e32 v0, s94, v0
	s_mov_b32 s7, 0xf3ff
	v_cmp_lt_i32_e32 vcc, s7, v0
	global_store_dwordx4 v[2:3], v[228:231], off
	s_or_b64 s[4:5], vcc, s[4:5]
	v_lshl_add_u64 v[2:3], v[2:3], 0, s[30:31]
	s_andn2_b64 exec, exec, s[4:5]
	s_cbranch_execnz .LBB0_775

; __device__ __forceinline__ unsigned pk2(float lo, float hi) { const f32x2v v = {lo, hi}; return __builtin_bit_cast(unsigned, __builtin_convertvector(v, bf16x2v)); }
; __global__ void __launch_bounds__(512) mk_fwd(Params P) {
;     ...
;             { bf16_t* wsb = (bf16_t*)(ws + WS_GT + 65536);
;               for (int i = blockIdx.x * 512 + tid; i < 2 * 12 * 2048; i += G * 512) { const int hd = i >> 11, rem = i & 2047, t = rem >> 4, ch = rem & 15;
;                   const float* src = P.a_w_s + (size_t)hd * 16384 + t * 128 + 8 * ch;
;                   f32x4 a0 = *(const f32x4*)src, a1 = *(const f32x4*)(src + 4);
;                   if (t < 64 && ch >= 8) { a0 = (f32x4){0.f, 0.f, 0.f, 0.f}; a1 = a0; }
;                   u32x4 w; w.x = pk2(a0[0], a0[1]); w.y = pk2(a0[2], a0[3]); w.z = pk2(a1[0], a1[1]); w.w = pk2(a1[2], a1[3]);
;                   *(u32x4*)(wsb + (size_t)hd * 16384 + t * 128 + 8 * ch) = w; } }
.LBB0_778:
	v_ashrrev_i32_e32 v12, 11, v3
	v_ashrrev_i32_e32 v13, 31, v12
	v_bfe_u32 v14, v3, 4, 7
	v_lshlrev_b64 v[4:5], 16, v[12:13]
	v_lshlrev_b32_e32 v0, 9, v14
	v_lshl_add_u64 v[4:5], s[80:81], 0, v[4:5]
	v_lshl_add_u64 v[4:5], v[4:5], 0, v[0:1]
	v_lshlrev_b32_e32 v0, 2, v2
	v_lshl_add_u64 v[8:9], v[4:5], 0, v[0:1]
	global_load_dwordx4 v[4:7], v[8:9], off offset:16
	s_nop 0
	global_load_dwordx4 v[8:11], v[8:9], off
	v_lshlrev_b64 v[12:13], 15, v[12:13]
	v_cmp_gt_u32_e64 s[0:1], 64, v14
	v_lshl_add_u64 v[12:13], s[10:11], 0, v[12:13]
	v_lshlrev_b32_e32 v0, 8, v14
	v_add_u32_e32 v3, s94, v3
	s_mov_b32 s4, 0xbfff
	s_and_b64 s[0:1], s[0:1], vcc
	v_lshl_add_u64 v[12:13], v[12:13], 0, v[0:1]
	v_lshlrev_b32_e32 v0, 1, v2
	v_cmp_lt_i32_e64 s[4:5], s4, v3
	v_lshl_add_u64 v[12:13], v[12:13], 0, v[0:1]
	s_or_b64 s[12:13], s[4:5], s[12:13]
	s_waitcnt vmcnt(0)
	v_cndmask_b32_e64 v0, v7, 0, s[0:1]
	v_cndmask_b32_e64 v7, v6, 0, s[0:1]
	v_cndmask_b32_e64 v6, v5, 0, s[0:1]
	v_cndmask_b32_e64 v14, v4, 0, s[0:1]
	v_cndmask_b32_e64 v5, v11, 0, s[0:1]
	v_cndmask_b32_e64 v10, v10, 0, s[0:1]
	v_cndmask_b32_e64 v4, v9, 0, s[0:1]
	v_cndmask_b32_e64 v8, v8, 0, s[0:1]
	v_cvt_pk_bf16_f32 v4, v8, v4
	v_cvt_pk_bf16_f32 v5, v10, v5
	v_cvt_pk_bf16_f32 v6, v14, v6
	v_cvt_pk_bf16_f32 v7, v7, v0
	global_store_dwordx4 v[12:13], v[4:7], off
	s_andn2_b64 exec, exec, s[12:13]
	s_cbranch_execnz .LBB0_778

; __global__ void __launch_bounds__(512) mk_fwd(Params P) {
;     ...
;             { float* lutg = (float*)(ws + WS_GT + 40960);
;               for (int i = blockIdx.x * 512 + tid; i < 12 * 256; i += G * 512) { const int hd = i >> 8, idx = i & 255; float v = 0.f;
;                   if (idx < 255) { const int rel = idx - 191; const int n = rel < 0 ? -rel : rel; int bkt;
;                       if (n < 8) bkt = n; else { const float nf = (float)n; int lg = 8 + (int)(logf(nf / 8.0f) / 2.772588722239781f * 8.0f); bkt = lg < 15 ? lg : 15; }
;                       if (rel > 0) bkt += 16;
;                       v = P.rel_bias[bkt * 12 + hd] * LOG2E; }
;                   lutg[i] = v; } }
.LBB0_781:
	s_or_b64 exec, exec, s[10:11]
	v_add_u32_e32 v4, s94, v4
	s_movk_i32 s7, 0xbff
	v_cmp_lt_i32_e32 vcc, s7, v4
	global_store_dword v[2:3], v5, off
	s_or_b64 s[4:5], vcc, s[4:5]
	v_lshl_add_u64 v[2:3], v[2:3], 0, s[34:35]
	s_andn2_b64 exec, exec, s[4:5]
	s_cbranch_execz .LBB0_784

; __device__ __forceinline__ unsigned pk2(float lo, float hi) { const f32x2v v = {lo, hi}; return __builtin_bit_cast(unsigned, __builtin_convertvector(v, bf16x2v)); }
; __device__ __forceinline__ void rms_row_to_bf16(const float* xrow, const float* g, bf16_t* orow, int lane) {
;     const f32x4* xr = (const f32x4*)xrow + lane; const f32x4* gr = (const f32x4*)g + lane;
;     f32x4 v[8]; float s = 0.f;
; #pragma unroll
;     for (int j = 0; j < 8; ++j) { v[j] = xr[64 * j]; s += (v[j][0] * v[j][0] + v[j][1] * v[j][1]) + (v[j][2] * v[j][2] + v[j][3] * v[j][3]); }
;     const float rstd = rsqrtf(wave_sum(s) * (1.f / DM) + EPS);
;     u32x2* o8 = (u32x2*)orow + lane;
; #pragma unroll
;     for (int j = 0; j < 8; ++j) { const f32x4 gg = gr[64 * j]; u32x2 w; w.x = pk2(v[j][0] * rstd * gg[0], v[j][1] * rstd * gg[1]); w.y = pk2(v[j][2] * rstd * gg[2], v[j][3] * rstd * gg[3]); o8[64 * j] = w; }
; }
; __global__ void __launch_bounds__(512) mk_fwd(Params P) {
;     ...
;             for (int m = gw; m < NB * NMEM; m += NGW) rms_row_to_bf16(P.mem + (size_t)m * DM, P.mem_norm_g, MEMN + (size_t)m * DM, lane);
.LBB0_786:
	v_add_co_u32_e32 v2, vcc, 0xfffff000, v32
	global_load_dwordx4 v[6:9], v[32:33], off offset:-3072
	global_load_dwordx4 v[14:17], v[32:33], off offset:-2048
	global_load_dwordx4 v[10:13], v[32:33], off offset:-1024
	global_load_dwordx4 v[40:43], v[32:33], off offset:-4096
	v_addc_co_u32_e32 v3, vcc, -1, v33, vcc
	global_load_dwordx4 v[44:47], v[2:3], off offset:-3072
	global_load_dwordx4 v[48:51], v[2:3], off offset:-2048
	global_load_dwordx4 v[52:55], v[2:3], off offset:-1024
	s_nop 0
	global_load_dwordx4 v[2:5], v[32:33], off
	global_load_dwordx4 v[56:59], v[20:21], off
	s_add_i32 s0, s0, s28
	s_cmpk_gt_i32 s0, 0x7ff
	v_lshl_add_u64 v[32:33], v[32:33], 0, s[38:39]
	s_waitcnt vmcnt(0)
	v_mul_f32_e32 v72, v8, v8
	v_pk_mul_f32 v[60:61], v[16:17], v[16:17]
	v_pk_mul_f32 v[62:63], v[14:15], v[14:15]
	v_mul_f32_e32 v0, v11, v11
	v_mul_f32_e32 v64, v13, v13
	v_mul_f32_e32 v66, v41, v41
	v_mul_f32_e32 v68, v43, v43
	v_mul_f32_e32 v73, v9, v9
	v_mul_f32_e32 v74, v4, v4
	v_mul_f32_e32 v75, v5, v5
	v_pk_mov_b32 v[70:71], v[62:63], v[60:61] op_sel:[1,0]
	v_mov_b32_e32 v63, v61
	v_pk_fma_f32 v[60:61], v[10:11], v[10:11], v[0:1] op_sel_hi:[1,1,0]
	v_pk_fma_f32 v[64:65], v[12:13], v[12:13], v[64:65] op_sel_hi:[1,1,0]
	v_pk_fma_f32 v[66:67], v[40:41], v[40:41], v[66:67] op_sel_hi:[1,1,0]
	v_pk_fma_f32 v[68:69], v[42:43], v[42:43], v[68:69] op_sel_hi:[1,1,0]
	v_mov_b32_e32 v61, v74
	v_mov_b32_e32 v65, v75
	v_mov_b32_e32 v67, v72
	v_mov_b32_e32 v69, v73
	v_mov_b32_e32 v72, v45
	v_mov_b32_e32 v73, v49
	v_mov_b32_e32 v76, v47
	v_mov_b32_e32 v77, v51
	v_pk_add_f32 v[62:63], v[70:71], v[62:63]
	v_mov_b32_e32 v70, v44
	v_mov_b32_e32 v71, v48
	v_mov_b32_e32 v74, v46
	v_mov_b32_e32 v75, v50
	v_pk_mul_f32 v[78:79], v[54:55], v[54:55]
	v_pk_mul_f32 v[80:81], v[52:53], v[52:53]
	v_pk_add_f32 v[60:61], v[60:61], v[64:65]
	v_pk_add_f32 v[64:65], v[66:67], v[68:69]
	v_pk_mul_f32 v[66:67], v[72:73], v[72:73]
	v_pk_mul_f32 v[68:69], v[76:77], v[76:77]
	v_pk_mov_b32 v[72:73], v[80:81], v[78:79] op_sel:[1,0]
	v_mov_b32_e32 v81, v79
	v_pk_fma_f32 v[66:67], v[70:71], v[70:71], v[66:67]
	v_pk_fma_f32 v[68:69], v[74:75], v[74:75], v[68:69]
	v_pk_add_f32 v[70:71], v[72:73], v[80:81]
	v_pk_add_f32 v[66:67], v[66:67], v[68:69]
	v_mul_f32_e32 v39, v6, v6
	v_mul_f32_e32 v82, v7, v7
	v_pk_add_f32 v[68:69], v[70:71], v[70:71] op_sel:[0,1] op_sel_hi:[1,0]
	v_pk_add_f32 v[66:67], v[66:67], v[66:67] op_sel:[0,1] op_sel_hi:[1,0]
	v_mov_b32_e32 v69, v82
	v_mov_b32_e32 v67, v39
	v_pk_add_f32 v[66:67], v[66:67], v[68:69]
	v_mul_f32_e32 v83, v2, v2
	v_pk_add_f32 v[64:65], v[66:67], v[64:65]
	v_mul_f32_e32 v84, v3, v3
	v_pk_add_f32 v[62:63], v[62:63], v[62:63] op_sel:[0,1] op_sel_hi:[1,0]
	v_pk_add_f32 v[64:65], v[64:65], v[64:65] op_sel:[0,1] op_sel_hi:[1,0]
	v_mov_b32_e32 v63, v84
	v_mov_b32_e32 v65, v83
	v_pk_add_f32 v[62:63], v[64:65], v[62:63]
	s_nop 0
	v_pk_add_f32 v[60:61], v[62:63], v[60:61]
	s_nop 0
	v_add_f32_e32 v0, v60, v61
	ds_bpermute_b32 v39, v19, v0
	s_waitcnt lgkmcnt(0)
	v_add_f32_e32 v0, v0, v39
	ds_bpermute_b32 v39, v34, v0
	s_waitcnt lgkmcnt(0)
	v_add_f32_e32 v0, v0, v39
	ds_bpermute_b32 v39, v35, v0
	s_waitcnt lgkmcnt(0)
	v_add_f32_e32 v0, v0, v39
	ds_bpermute_b32 v39, v36, v0
	s_waitcnt lgkmcnt(0)
	v_add_f32_e32 v0, v0, v39
	ds_bpermute_b32 v39, v37, v0
	s_waitcnt lgkmcnt(0)
	v_add_f32_e32 v0, v0, v39
	ds_bpermute_b32 v39, v38, v0
	s_waitcnt lgkmcnt(0)
	v_add_f32_e32 v0, v0, v39
	v_fmamk_f32 v0, v0, 0x3a000000, v205
	v_mul_f32_e32 v39, 0x4b800000, v0
	v_cmp_gt_f32_e32 vcc, s68, v0
	s_nop 1
	v_cndmask_b32_e32 v0, v0, v39, vcc
	v_rsq_f32_e32 v0, v0
	s_nop 0
	v_mul_f32_e32 v39, 0x45800000, v0
	v_cndmask_b32_e32 v0, v0, v39, vcc
	v_pk_mul_f32 v[44:45], v[44:45], v[0:1] op_sel_hi:[1,0]
	v_pk_mul_f32 v[46:47], v[46:47], v[0:1] op_sel_hi:[1,0]
	v_pk_mul_f32 v[44:45], v[56:57], v[44:45]
	v_pk_mul_f32 v[46:47], v[58:59], v[46:47]
	v_cvt_pk_bf16_f32 v44, v44, v45
	v_cvt_pk_bf16_f32 v45, v46, v47
	global_store_dwordx2 v[30:31], v[44:45], off
	global_load_dwordx4 v[44:47], v[20:21], off offset:1024
	v_pk_mul_f32 v[48:49], v[48:49], v[0:1] op_sel_hi:[1,0]
	v_pk_mul_f32 v[50:51], v[50:51], v[0:1] op_sel_hi:[1,0]
	v_pk_mul_f32 v[40:41], v[40:41], v[0:1] op_sel_hi:[1,0]
	v_pk_mul_f32 v[42:43], v[42:43], v[0:1] op_sel_hi:[1,0]
	v_pk_mul_f32 v[6:7], v[6:7], v[0:1] op_sel_hi:[1,0]
	v_pk_mul_f32 v[8:9], v[8:9], v[0:1] op_sel_hi:[1,0]
	v_pk_mul_f32 v[14:15], v[14:15], v[0:1] op_sel_hi:[1,0]
	v_pk_mul_f32 v[16:17], v[16:17], v[0:1] op_sel_hi:[1,0]
	v_pk_mul_f32 v[10:11], v[10:11], v[0:1] op_sel_hi:[1,0]
	v_pk_mul_f32 v[12:13], v[12:13], v[0:1] op_sel_hi:[1,0]
	v_pk_mul_f32 v[2:3], v[2:3], v[0:1] op_sel_hi:[1,0]
	v_pk_mul_f32 v[4:5], v[4:5], v[0:1] op_sel_hi:[1,0]
	s_waitcnt vmcnt(0)
	v_pk_mul_f32 v[44:45], v[44:45], v[48:49]
	v_pk_mul_f32 v[46:47], v[46:47], v[50:51]
	v_cvt_pk_bf16_f32 v44, v44, v45
	v_cvt_pk_bf16_f32 v45, v46, v47
	global_store_dwordx2 v[30:31], v[44:45], off offset:512
	global_load_dwordx4 v[44:47], v[20:21], off offset:2048
	v_pk_mul_f32 v[48:49], v[52:53], v[0:1] op_sel_hi:[1,0]
	v_pk_mul_f32 v[50:51], v[54:55], v[0:1] op_sel_hi:[1,0]
	s_waitcnt vmcnt(0)
	v_pk_mul_f32 v[44:45], v[44:45], v[48:49]
	v_pk_mul_f32 v[46:47], v[46:47], v[50:51]
	v_cvt_pk_bf16_f32 v44, v44, v45
	v_cvt_pk_bf16_f32 v45, v46, v47
	global_store_dwordx2 v[30:31], v[44:45], off offset:1024
	global_load_dwordx4 v[44:47], v[20:21], off offset:3072
	s_waitcnt vmcnt(0)
	v_pk_mul_f32 v[40:41], v[44:45], v[40:41]
	v_pk_mul_f32 v[42:43], v[46:47], v[42:43]
	v_cvt_pk_bf16_f32 v40, v40, v41
	v_cvt_pk_bf16_f32 v41, v42, v43
	global_store_dwordx2 v[30:31], v[40:41], off offset:1536
	global_load_dwordx4 v[40:43], v[22:23], off
	s_waitcnt vmcnt(0)
	v_pk_mul_f32 v[6:7], v[40:41], v[6:7]
	v_pk_mul_f32 v[8:9], v[42:43], v[8:9]
	v_cvt_pk_bf16_f32 v6, v6, v7
	v_cvt_pk_bf16_f32 v7, v8, v9
	global_store_dwordx2 v[30:31], v[6:7], off offset:2048
	global_load_dwordx4 v[6:9], v[24:25], off
	s_waitcnt vmcnt(0)
	v_pk_mul_f32 v[6:7], v[14:15], v[6:7]
	v_pk_mul_f32 v[8:9], v[16:17], v[8:9]
	v_cvt_pk_bf16_f32 v6, v6, v7
	v_cvt_pk_bf16_f32 v7, v8, v9
	global_store_dwordx2 v[30:31], v[6:7], off offset:2560
	global_load_dwordx4 v[6:9], v[26:27], off
	s_waitcnt vmcnt(0)
	v_pk_mul_f32 v[6:7], v[10:11], v[6:7]
	v_pk_mul_f32 v[8:9], v[12:13], v[8:9]
	v_cvt_pk_bf16_f32 v6, v6, v7
	v_cvt_pk_bf16_f32 v7, v8, v9
	global_store_dwordx2 v[30:31], v[6:7], off offset:3072
	global_load_dwordx4 v[6:9], v[28:29], off
	s_waitcnt vmcnt(0)
	v_pk_mul_f32 v[2:3], v[2:3], v[6:7]
	v_pk_mul_f32 v[4:5], v[4:5], v[8:9]
	v_cvt_pk_bf16_f32 v2, v2, v3
	v_cvt_pk_bf16_f32 v3, v4, v5
	global_store_dwordx2 v[30:31], v[2:3], off offset:3584
	v_lshl_add_u64 v[30:31], v[30:31], 0, s[54:55]
	s_cbranch_scc0 .LBB0_786

; __device__ __forceinline__ unsigned pk2(float lo, float hi) { const f32x2v v = {lo, hi}; return __builtin_bit_cast(unsigned, __builtin_convertvector(v, bf16x2v)); }
; __device__ __forceinline__ void row_to_bf16_ssq(const float* xrow, bf16_t* orow, float* ssq, int lane) {
;     const f32x4* xr = (const f32x4*)xrow + lane; u32x2* o8 = (u32x2*)orow + lane; float s = 0.f;
; #pragma unroll
;     for (int j = 0; j < 8; ++j) { const f32x4 v = xr[64 * j]; s += (v[0] * v[0] + v[1] * v[1]) + (v[2] * v[2] + v[3] * v[3]);
;         u32x2 w; w.x = pk2(v[0], v[1]); w.y = pk2(v[2], v[3]); o8[64 * j] = w; }
;     s = wave_sum(s);
;     if (lane == 0) *ssq = s;
; }
; __global__ void __launch_bounds__(512) mk_fwd(Params P) {
;     ...
;             for (int m = gw; m < NTOK; m += NGW) row_to_bf16_ssq(P.x + (size_t)m * DM, HB + (size_t)m * DM, SSQ + m, lane);
.LBB0_790:
	v_add_co_u32_e32 v16, vcc, 0xfffff000, v4
	v_lshl_add_u64 v[20:21], s[24:25], 0, v[2:3]
	s_nop 0
	v_addc_co_u32_e32 v17, vcc, -1, v5, vcc
	s_waitcnt lgkmcnt(0)
	global_load_dwordx4 v[12:15], v[16:17], off offset:-3072
	s_mov_b32 s4, 0xb100000
	v_add_co_u32_e32 v48, vcc, s4, v20
	s_waitcnt vmcnt(0)
	v_cvt_pk_bf16_f32 v20, v12, v13
	v_addc_co_u32_e32 v49, vcc, 0, v21, vcc
	v_cvt_pk_bf16_f32 v21, v14, v15
	global_store_dwordx2 v[48:49], v[20:21], off
	global_load_dwordx4 v[20:23], v[16:17], off offset:-2048
	v_mul_f32_e32 v0, v13, v13
	v_mul_f32_e32 v13, v15, v15
	v_fmac_f32_e32 v0, v12, v12
	v_fmac_f32_e32 v13, v14, v14
	v_add_f32_e32 v0, v0, v13
	s_waitcnt vmcnt(0)
	v_cvt_pk_bf16_f32 v24, v20, v21
	v_cvt_pk_bf16_f32 v25, v22, v23
	global_store_dwordx2 v[48:49], v[24:25], off offset:512
	global_load_dwordx4 v[24:27], v[16:17], off offset:-1024
	v_mul_f32_e32 v12, v21, v21
	v_mul_f32_e32 v13, v23, v23
	v_fmac_f32_e32 v12, v20, v20
	v_fmac_f32_e32 v13, v22, v22
	v_add_f32_e32 v12, v12, v13
	v_add_f32_e32 v0, v0, v12
	s_waitcnt vmcnt(0)
	v_cvt_pk_bf16_f32 v16, v24, v25
	v_cvt_pk_bf16_f32 v17, v26, v27
	global_store_dwordx2 v[48:49], v[16:17], off offset:1024
	global_load_dwordx4 v[28:31], v[4:5], off offset:-4096
	v_mul_f32_e32 v12, v25, v25
	v_mul_f32_e32 v13, v27, v27
	v_fmac_f32_e32 v12, v24, v24
	v_fmac_f32_e32 v13, v26, v26
	v_add_f32_e32 v12, v12, v13
	v_add_f32_e32 v0, v0, v12
	s_waitcnt vmcnt(0)
	v_cvt_pk_bf16_f32 v16, v28, v29
	v_cvt_pk_bf16_f32 v17, v30, v31
	global_store_dwordx2 v[48:49], v[16:17], off offset:1536
	global_load_dwordx4 v[32:35], v[4:5], off offset:-3072
	v_mul_f32_e32 v12, v29, v29
	v_mul_f32_e32 v13, v31, v31
	v_fmac_f32_e32 v12, v28, v28
	v_fmac_f32_e32 v13, v30, v30
	v_add_f32_e32 v12, v12, v13
	v_add_f32_e32 v0, v0, v12
	s_waitcnt vmcnt(0)
	v_cvt_pk_bf16_f32 v16, v32, v33
	v_cvt_pk_bf16_f32 v17, v34, v35
	global_store_dwordx2 v[48:49], v[16:17], off offset:2048
	global_load_dwordx4 v[36:39], v[4:5], off offset:-2048
	v_mul_f32_e32 v12, v33, v33
	v_mul_f32_e32 v13, v35, v35
	v_fmac_f32_e32 v12, v32, v32
	v_fmac_f32_e32 v13, v34, v34
	v_add_f32_e32 v12, v12, v13
	v_add_f32_e32 v0, v0, v12
	s_waitcnt vmcnt(0)
	v_cvt_pk_bf16_f32 v16, v36, v37
	v_cvt_pk_bf16_f32 v17, v38, v39
	global_store_dwordx2 v[48:49], v[16:17], off offset:2560
	global_load_dwordx4 v[40:43], v[4:5], off offset:-1024
	v_mul_f32_e32 v12, v37, v37
	v_mul_f32_e32 v13, v39, v39
	v_fmac_f32_e32 v12, v36, v36
	v_fmac_f32_e32 v13, v38, v38
	v_add_f32_e32 v12, v12, v13
	v_add_f32_e32 v0, v0, v12
	s_waitcnt vmcnt(0)
	v_cvt_pk_bf16_f32 v16, v40, v41
	v_cvt_pk_bf16_f32 v17, v42, v43
	global_store_dwordx2 v[48:49], v[16:17], off offset:3072
	global_load_dwordx4 v[44:47], v[4:5], off
	v_mul_f32_e32 v12, v41, v41
	v_mul_f32_e32 v13, v43, v43
	v_fmac_f32_e32 v12, v40, v40
	v_fmac_f32_e32 v13, v42, v42
	v_add_f32_e32 v12, v12, v13
	v_add_f32_e32 v0, v0, v12
	s_waitcnt vmcnt(0)
	v_mul_f32_e32 v12, v45, v45
	v_mul_f32_e32 v13, v47, v47
	v_fmac_f32_e32 v12, v44, v44
	v_fmac_f32_e32 v13, v46, v46
	v_add_f32_e32 v12, v12, v13
	v_add_f32_e32 v0, v0, v12
	ds_bpermute_b32 v12, v6, v0
	v_cvt_pk_bf16_f32 v14, v44, v45
	v_cvt_pk_bf16_f32 v15, v46, v47
	global_store_dwordx2 v[48:49], v[14:15], off offset:3584
	s_waitcnt lgkmcnt(0)
	v_add_f32_e32 v0, v0, v12
	ds_bpermute_b32 v12, v7, v0
	s_waitcnt lgkmcnt(0)
	v_add_f32_e32 v0, v0, v12
	ds_bpermute_b32 v12, v8, v0
	s_waitcnt lgkmcnt(0)
	v_add_f32_e32 v0, v0, v12
	ds_bpermute_b32 v12, v9, v0
	s_waitcnt lgkmcnt(0)
	v_add_f32_e32 v0, v0, v12
	ds_bpermute_b32 v12, v10, v0
	s_waitcnt lgkmcnt(0)
	v_add_f32_e32 v0, v0, v12
	ds_bpermute_b32 v12, v11, v0
	s_and_saveexec_b64 s[4:5], s[0:1]
	s_cbranch_execz .LBB0_789
	s_add_u32 s10, s24, s7
	s_addc_u32 s11, s25, s8
	s_waitcnt lgkmcnt(0)
	v_add_f32_e32 v0, v0, v12
	v_mov_b64_e32 v[12:13], s[10:11]
	global_store_dword v[12:13], v0, off
	s_branch .LBB0_789

; __global__ void __launch_bounds__(512) mk_fwd(Params P) {
;     ...
;             for (int i = blockIdx.x * 512 + tid; i < 3 * NTOK; i += G * 512) SSQ[NTOK + i] = 0.f;
.LBB0_795:
	v_ashrrev_i32_e32 v9, 31, v0
	v_mov_b32_e32 v8, v0
	v_ashrrev_i32_e32 v7, 31, v3
	v_mov_b32_e32 v6, v3
	v_add_u32_e32 v5, -2, v5
	v_lshl_add_u64 v[8:9], v[8:9], 2, s[20:21]
	v_lshl_add_u64 v[6:7], v[6:7], 2, s[20:21]
	v_cmp_eq_u32_e64 s[0:1], 0, v5
	v_add_co_u32_e32 v8, vcc, 0x20000, v8
	s_or_b64 s[8:9], s[0:1], s[8:9]
	s_mov_b64 s[0:1], vcc
	v_add_co_u32_e32 v6, vcc, 0x20000, v6
	v_add_u32_e32 v3, s56, v3
	v_add_u32_e32 v0, s92, v0
	v_addc_co_u32_e64 v9, s[0:1], 0, v9, s[0:1]
	v_addc_co_u32_e32 v7, vcc, 0, v7, vcc
	global_store_dword v[8:9], v1, off
	global_store_dword v[6:7], v1, off
	s_andn2_b64 exec, exec, s[8:9]
	s_cbranch_execnz .LBB0_795
	s_or_b64 exec, exec, s[8:9]
	v_mad_u64_u32 v[18:19], s[0:1], v4, s94, v[18:19]
	v_cmp_ne_u32_e32 vcc, v2, v4
	s_orn2_b64 s[0:1], vcc, exec

; __global__ void __launch_bounds__(512) mk_fwd(Params P) {
;     ...
;             for (int i = blockIdx.x * 512 + tid; i < 3 * NTOK; i += G * 512) SSQ[NTOK + i] = 0.f;
;             if (blockIdx.x == 0) { float* gt = (float*)(ws + WS_GT);
;                 if (tid < 9) { ((unsigned*)(ws + WS_GT))[4096 + 64 * tid] = 0u; ((unsigned*)(ws + WS_GT))[8192 + 64 * tid] = 0u; }
.LBB0_799:
	v_add_u32_e32 v18, s94, v18
	s_mov_b32 s6, 0x17fff
	v_cmp_lt_i32_e32 vcc, s6, v18
	global_store_dword v[2:3], v1, off
	s_or_b64 s[0:1], vcc, s[0:1]
	v_lshl_add_u64 v[2:3], v[2:3], 0, s[34:35]
	s_andn2_b64 exec, exec, s[0:1]
	s_cbranch_execnz .LBB0_799
.LBB0_800:
	s_or_b64 exec, exec, s[4:5]
	v_readlane_b32 s0, v252, 25
	v_readlane_b32 s1, v252, 26
	s_and_b64 vcc, exec, s[0:1]
	s_cbranch_vccz .LBB0_884
	s_add_u32 s4, s24, 0xb000000
	s_addc_u32 s5, s25, 0
	v_cmp_gt_i32_e32 vcc, 9, v180
	s_and_saveexec_b64 s[0:1], vcc
	s_cbranch_execz .LBB0_803
	v_lshlrev_b32_e32 v2, 6, v180
	s_waitcnt lgkmcnt(0)
	v_ashrrev_i32_e32 v3, 31, v2
	v_lshl_add_u64 v[2:3], v[2:3], 2, s[4:5]
	v_add_co_u32_e32 v4, vcc, 0x4000, v2
	s_nop 1
	v_addc_co_u32_e32 v5, vcc, 0, v3, vcc
	v_add_co_u32_e32 v2, vcc, 0x8000, v2
	global_store_dword v[4:5], v1, off
	s_nop 0
	v_addc_co_u32_e32 v3, vcc, 0, v3, vcc
	global_store_dword v[2:3], v1, off

; __global__ void __launch_bounds__(512) mk_fwd(Params P) {
;     ...
;                 for (int i = tid; i < 2064; i += 512) { float v = 0.f;
;                     if (i < 1536) { const int Lq = i / 384, w = (i % 384) / 128, d = i & 127, kd = Lq % 3;
;                         if (w == 2) v = P.mem_q_norm_g[Lq * 128 + d];
;                         else if (kd == 1) v = (w == 0 ? P.b_q_norm_g : P.b_k_norm_g)[d];
;                         else if (kd == 2) v = (w == 0 ? P.c_q_norm_g : P.c_k_norm_g)[d & 63];
;                     } else if (i < 2048) v = P.mem_k_norm_g[i - 1536];
;                     else if (i < 2060) v = P.b_b_f[i - 2048];
;                     gt[i] = v; }
.LBB0_806:
	s_or_b64 exec, exec, s[8:9]
	s_mov_b64 s[8:9], 0x800
	s_waitcnt vmcnt(0)
	global_store_dword v[4:5], v0, off
	v_lshl_add_u64 v[4:5], v[4:5], 0, s[8:9]
	s_movk_i32 s8, 0x60f
	v_add_u32_e32 v0, 0x200, v8
	v_cmp_lt_i32_e32 vcc, s8, v8
	s_or_b64 s[6:7], vcc, s[6:7]
	v_mov_b32_e32 v8, v0
	s_andn2_b64 exec, exec, s[6:7]
	s_cbranch_execz .LBB0_826

; __global__ void __launch_bounds__(512) mk_fwd(Params P) {
;     ...
;                 if (tid < 19) {
;                     float v = 0.f;
;                     if (tid < 16) { const int Lq = tid >> 2, w = tid & 3, kd = Lq % 3;
;                         if (w == 2) { for (int i = 0; i < 128; ++i) v = fmaxf(v, fabsf(P.mem_q_norm_g[Lq * 128 + i])); }
;                         else if (w == 3) { for (int i = 0; i < 128; ++i) v = fmaxf(v, fabsf(P.mem_k_norm_g[Lq * 128 + i])); }
;                         else if (kd == 1) { const float* gsrc = (w == 0) ? P.b_q_norm_g : P.b_k_norm_g; for (int i = 0; i < 128; ++i) v = fmaxf(v, fabsf(gsrc[i])); }
;                         else if (kd == 2) { const float* gsrc = (w == 0) ? P.c_q_norm_g : P.c_k_norm_g; for (int i = 0; i < 64; ++i) v = fmaxf(v, fabsf(gsrc[i])); }
;                     } else if (tid == 16) { for (int i = 0; i < 384; ++i) v = fmaxf(v, P.rel_bias[i]); }
;                     else if (tid == 17) { for (int i = 0; i < 64; ++i) v += P.c_lam[i] * P.c_lam[64 + i]; }
;                     else { for (int i = 0; i < 64; ++i) v += P.c_lam[128 + i] * P.c_lam[192 + i]; }
;                     gt[2080 + tid] = v; } }
.LBB0_882:
	s_or_b64 exec, exec, s[0:1]
	v_ashrrev_i32_e32 v181, 31, v180
	s_waitcnt lgkmcnt(0)
	v_lshl_add_u64 v[2:3], v[180:181], 2, s[4:5]
	v_add_co_u32_e32 v2, vcc, 0x2000, v2
	s_nop 1
	v_addc_co_u32_e32 v3, vcc, 0, v3, vcc
	global_store_dword v[2:3], v0, off offset:128
